# dil loop: dilation-4 bias table copied to a padded layout (1 pad per 4 dwords) so the stride-4 lane reads become stride-5: removes a 4-way LDS bank conflict on 8 of 33 groups
# speedup vs baseline: 1.0006x; 1.0006x over previous
; #define LAS __attribute__((address_space(3)))
; __device__ __forceinline__ void attn_setup(const float* par, int l, LAS unsigned char* lds) {
;     ...
;     LAS float* tl = (LAS float*)(lds + TDIL_OFF);
;     for (int i = tid; i < 6 * TDIL_STRIDE; i += 512) { const int hd = i / TDIL_STRIDE, j = i % TDIL_STRIDE; const int b = j < 1152 ? 0 : (j < 1560 ? 1 : 2), jj = j - (b == 0 ? 0 : (b == 1 ? 1152 : 1560));
;         const int r = (b == 0) ? 1 : (b == 1 ? 4 : 16), f = 16 / r, mm = jj - (64 + 31 * f);
;         tl[i] = (mm >= -64 && mm <= 64) ? (rb[rel_bucket(r * mm) * 10 + 4 + hd] - misc[4 + hd]) * LOG2E : -1e30f; }
; __device__ __forceinline__ void attn_phase(unsigned char* ws, int l, LAS unsigned char* lds, int G) {
;     ...
;     __syncthreads();
;     for (int bu = vb; bu < 1152; bu += G) {
;         const int sh = bu >> 6, rem = bu & 63, T0 = (rem >> 1) * 512, rho = (rem & 1) * 8 + wid;
.Lpt0_done:
	v_cmp_gt_u32_e32 vcc, 0x198, v154
	s_and_saveexec_b64 s[90:91], vcc
	v_lshlrev_b32_e32 v200, 2, v154
	v_add_u32_e32 v200, 93696, v200
	v_lshrrev_b32_e32 v201, 2, v154
	v_add_u32_e32 v201, v201, v154
	v_lshlrev_b32_e32 v201, 2, v201
	v_add_u32_e32 v201, 0x10000, v201
	ds_read_b32 v202, v200 offset:0
	ds_read_b32 v203, v200 offset:7168
	ds_read_b32 v204, v200 offset:14336
	ds_read_b32 v205, v200 offset:21504
	ds_read_b32 v206, v200 offset:28672
	ds_read_b32 v207, v200 offset:35840
	s_waitcnt lgkmcnt(0)
	ds_write_b32 v201, v202 offset:0
	ds_write_b32 v201, v203 offset:1920
	ds_write_b32 v201, v204 offset:3840
	ds_write_b32 v201, v205 offset:5760
	ds_write_b32 v201, v206 offset:7680
	ds_write_b32 v201, v207 offset:9600
	s_mov_b64 exec, s[90:91]
	s_waitcnt lgkmcnt(0)
	s_barrier
	s_lshr_b32 s64, s20, 6
	s_movk_i32 s65, 0x1800
	v_mov_b32_e32 v81, 0
	s_mov_b64 s[52:53], 0x1200
	s_movk_i32 s66, 0x1000
	s_mov_b64 s[54:55], 0x1500
	s_movk_i32 s67, 0x480
	s_movk_i32 s69, 0xbc
	s_movk_i32 s71, 0x4000
	v_mbcnt_hi_u32_b32 v102, -1, v155
	s_branch .LBB0_554

; #define LAS __attribute__((address_space(3)))
; #define GAS __attribute__((address_space(1)))
; __device__ __forceinline__ void dil_unit(LAS unsigned char* lds, bf16_t* proj, int seq, int hd, int T0, int rho) {
;     int tid_ = threadIdx.x; asm volatile("" : "+v"(tid_));
;     const int tid = tid_, lane = tid & 63, r32 = lane & 31, hi = lane >> 5, wid = __builtin_amdgcn_readfirstlane(tid >> 6);
;     bf16_t* base = proj + (size_t)seq * SEQ * NIN;
;     LAS unsigned char* wbuf = lds + wid * 4096;
;     const LAS unsigned char* vp = wbuf + ((lane >> 4) & 1) * 32 + (lane & 3) * 8 + (4 * hi + ((lane & 15) >> 2)) * 64;
;     const int P0 = T0 + rho;
;     bf16x8 qr[4];
; #pragma unroll
;     for (int ks = 0; ks < 4; ++ks) qr[ks] = *(const GAS bf16x8*)(base + (size_t)(P0 + 16 * r32) * NIN + PC_LQ + hd * 64 + 16 * ks + 8 * hi);
;     f32x16 o0 = {}, o1 = {}; float l = 0.f;
;     const bool bound = (T0 < 1024) || (T0 >= 15360);
; __device__ __forceinline__ void attn_phase(unsigned char* ws, int l, LAS unsigned char* lds, int G) {
;     ...
;     for (int bu = vb; bu < 1152; bu += G) {
;         const int sh = bu >> 6, rem = bu & 63, T0 = (rem >> 1) * 512, rho = (rem & 1) * 8 + wid;
;         dil_unit(lds, proj, sh / 6, sh % 6, T0, rho);
.LBB0_554:
	s_lshr_b32 s82, s33, 8
	s_mul_i32 s82, s82, 13
	s_add_i32 s82, s82, s33
	s_ashr_i32 s2, s33, 6
	s_mul_hi_i32 s7, s2, 0x2aaaaaab
	s_lshl_b32 s3, s82, 8
	s_lshr_b32 s8, s7, 31
	s_and_b32 s6, s3, 0x3e00
	s_lshl_b32 s3, s82, 3
	s_add_i32 s7, s7, s8
	s_and_b32 s3, s3, 8
	s_mul_i32 s8, s7, 6
	s_add_i32 s3, s3, s64
	s_sub_i32 s8, s2, s8
	s_mul_hi_i32 s2, s7, 0x6000000
	s_mul_i32 s7, s7, 0x6000000
	v_mov_b32_e32 v2, v154
	s_add_u32 s56, s48, s7
	s_addc_u32 s57, s49, s2
	v_and_b32_e32 v105, 31, v2
	s_add_i32 s76, s3, s6
	v_lshl_add_u32 v3, v105, 4, s76
	v_mov_b64_e32 v[0:1], s[56:57]
	s_lshl_b32 s58, s8, 6
	v_bfe_u32 v106, v2, 5, 1
	v_mad_u64_u32 v[0:1], s[2:3], v3, s65, v[0:1]
	s_ashr_i32 s59, s58, 31
	v_lshl_add_u64 v[0:1], s[58:59], 1, v[0:1]
	v_lshlrev_b32_e32 v80, 4, v106
	v_lshl_add_u64 v[0:1], v[0:1], 0, v[80:81]
	global_load_dwordx4 v[48:51], v[0:1], off offset:1280
	global_load_dwordx4 v[52:55], v[0:1], off offset:1312
	global_load_dwordx4 v[56:59], v[0:1], off offset:1344
	global_load_dwordx4 v[60:63], v[0:1], off offset:1376
	v_readfirstlane_b32 s2, v2
	s_lshl_b32 s2, s2, 6
	s_and_b32 s2, s2, 0xfffff000
	v_lshlrev_b32_e32 v0, 1, v2
	v_lshlrev_b32_e32 v104, 3, v2
	v_lshlrev_b32_e32 v107, 2, v106
	v_lshrrev_b32_e32 v1, 2, v2
	v_and_b32_e32 v103, 63, v2
	v_and_b32_e32 v0, 32, v0
	v_and_b32_e32 v98, 24, v104
	v_and_or_b32 v1, v1, 3, v107
	s_add_i32 s77, s2, 0
	v_lshlrev_b32_e32 v108, 6, v1
	v_lshlrev_b32_e32 v1, 3, v106
	v_add3_u32 v109, s77, v0, v98
	s_addk_i32 s6, 0xc400
	v_lshrrev_b32_e32 v110, 2, v103
	v_lshlrev_b32_e32 v0, 4, v103
	s_mov_b64 s[2:3], -1
	s_cmp_gt_u32 s6, 0xffffc7ff
	v_lshlrev_b32_e32 v100, 1, v98
	s_mul_i32 s6, s8, 0x1c00
	v_lshlrev_b32_e32 v82, 1, v1
	v_or_b32_e32 v111, 16, v110
	v_add_u32_e32 v112, s77, v0
	s_cbranch_scc0 .LBB0_558
	s_movk_i32 s100, 0x1800
	s_add_i32 s101, s6, 0x15c00
	s_lshl_b32 s90, s58, 1
	s_add_u32 s82, s56, s90
	s_addc_u32 s83, s57, 0
	s_add_u32 s82, s82, 0x1200
	s_addc_u32 s83, s83, 0
	s_sub_i32 s90, s76, 64
	s_mul_i32 s90, s90, 0x1800
	s_add_u32 s84, s82, s90
	s_addc_u32 s85, s83, 0
	s_sub_i32 s90, s76, 256
	s_mul_i32 s90, s90, 0x1800
	s_add_u32 s86, s82, s90
	s_addc_u32 s87, s83, 0
	s_sub_i32 s90, s76, 1024
	s_mul_i32 s90, s90, 0x1800
	s_add_u32 s88, s82, s90
	s_addc_u32 s89, s83, 0
	v_lshlrev_b32_e32 v153, 1, v98
	v_mad_u32_u24 v80, v105, s100, v82
	v_mad_u32_u24 v100, v110, s100, v153
	v_add_u32_e32 v149, 0x18000, v100
	v_lshlrev_b32_e32 v83, 2, v105
	v_mad_u32_u24 v83, v83, s100, v82
	v_lshlrev_b32_e32 v101, 2, v110
	v_mad_u32_u24 v101, v101, s100, v153
	v_add_u32_e32 v150, 0x60000, v101
	v_lshlrev_b32_e32 v99, 4, v105
	v_mad_u32_u24 v99, v99, s100, v82
	v_lshlrev_b32_e32 v148, 4, v110
	v_mad_u32_u24 v148, v148, s100, v153
	v_add_u32_e32 v151, 0x180000, v148
	v_lshrrev_b32_e32 v249, 3, v103
	v_and_b32_e32 v250, 7, v103
	v_lshlrev_b32_e32 v250, 4, v250
	v_add_u32_e32 v235, 0, v249
	v_mad_u32_u24 v235, v235, s100, v250
	v_add_u32_e32 v236, 8, v249
	v_mad_u32_u24 v236, v236, s100, v250
	v_add_u32_e32 v237, 16, v249
	v_mad_u32_u24 v237, v237, s100, v250
	v_add_u32_e32 v238, 24, v249
	v_mad_u32_u24 v238, v238, s100, v250
	v_add_u32_e32 v239, 0, v249
	v_lshlrev_b32_e32 v239, 2, v239
	v_mad_u32_u24 v239, v239, s100, v250
	v_add_u32_e32 v240, 8, v249
	v_lshlrev_b32_e32 v240, 2, v240
	v_mad_u32_u24 v240, v240, s100, v250
	v_add_u32_e32 v241, 16, v249
	v_lshlrev_b32_e32 v241, 2, v241
	v_mad_u32_u24 v241, v241, s100, v250
	v_add_u32_e32 v242, 24, v249
	v_lshlrev_b32_e32 v242, 2, v242
	v_mad_u32_u24 v242, v242, s100, v250
	v_add_u32_e32 v243, 0, v249
	v_lshlrev_b32_e32 v243, 4, v243
	v_mad_u32_u24 v243, v243, s100, v250
	v_add_u32_e32 v244, 8, v249
	v_lshlrev_b32_e32 v244, 4, v244
	v_mad_u32_u24 v244, v244, s100, v250
	v_add_u32_e32 v245, 16, v249
	v_lshlrev_b32_e32 v245, 4, v245
	v_mad_u32_u24 v245, v245, s100, v250
	v_add_u32_e32 v246, 24, v249
	v_lshlrev_b32_e32 v246, 4, v246
	v_mad_u32_u24 v246, v246, s100, v250
	v_and_b32_e32 v247, 7, v249
	v_lshlrev_b32_e32 v247, 4, v247
	v_xor_b32_e32 v247, v247, v112
	v_and_b32_e32 v153, 7, v105
	v_or_b32_e32 v248, 0, v106
	v_xor_b32_e32 v248, v248, v153
	v_lshlrev_b32_e32 v248, 4, v248
	v_lshl_add_u32 v248, v105, 7, v248
	v_add_u32_e32 v248, s77, v248
	v_or_b32_e32 v249, 2, v106
	v_xor_b32_e32 v249, v249, v153
	v_lshlrev_b32_e32 v249, 4, v249
	v_lshl_add_u32 v249, v105, 7, v249
	v_add_u32_e32 v249, s77, v249
	v_or_b32_e32 v250, 4, v106
	v_xor_b32_e32 v250, v250, v153
	v_lshlrev_b32_e32 v250, 4, v250
	v_lshl_add_u32 v250, v105, 7, v250
	v_add_u32_e32 v250, s77, v250
	v_or_b32_e32 v251, 6, v106
	v_xor_b32_e32 v251, v251, v153
	v_lshlrev_b32_e32 v251, 4, v251
	v_lshl_add_u32 v251, v105, 7, v251
	v_add_u32_e32 v251, s77, v251
	v_lshlrev_b32_e32 v153, 1, v98
	v_mul_u32_u24_e32 v228, 17, v105
	v_sub_u32_e32 v228, v107, v228
	s_mul_i32 s90, s58, 153
	s_lshr_b32 s90, s90, 1
	s_add_i32 s90, s90, 34876
	v_lshl_add_u32 v228, v228, 2, s90
	v_mul_u32_u24_e32 v229, 5, v105
	v_sub_u32_e32 v229, v107, v229
	v_add_u32_e32 v229, v229, v106
	s_mul_i32 s90, s58, 30
	s_add_i32 s90, s90, 66156
	v_lshl_add_u32 v229, v229, 2, s90
	v_sub_u32_e32 v230, v107, v105
	s_add_i32 s90, s101, 6364
	v_lshl_add_u32 v230, v230, 2, s90
	v_add_u32_e32 v231, v109, v108
	v_mov_b64_e32 v[232:233], 0
	v_mov_b64_e32 v[0:1], 0
	v_mov_b64_e32 v[2:3], 0
	v_mov_b64_e32 v[4:5], 0
	v_mov_b64_e32 v[6:7], 0
	v_mov_b64_e32 v[8:9], 0
	v_mov_b64_e32 v[10:11], 0
	v_mov_b64_e32 v[12:13], 0
	v_mov_b64_e32 v[14:15], 0
	v_mov_b64_e32 v[16:17], 0
	v_mov_b64_e32 v[18:19], 0
	v_mov_b64_e32 v[20:21], 0
	v_mov_b64_e32 v[22:23], 0
	v_mov_b64_e32 v[24:25], 0
	v_mov_b64_e32 v[26:27], 0
	v_mov_b64_e32 v[28:29], 0
	v_mov_b64_e32 v[30:31], 0
	global_load_dwordx4 v[116:119], v235, s[84:85]
	global_load_dwordx4 v[120:123], v236, s[84:85]
	global_load_dwordx4 v[124:127], v237, s[84:85]
	global_load_dwordx4 v[128:131], v238, s[84:85]
	global_load_dwordx4 v[132:135], v100, s[84:85] offset:768
	global_load_dwordx4 v[136:139], v149, s[84:85] offset:768
	global_load_dwordx4 v[140:143], v100, s[84:85] offset:832
	global_load_dwordx4 v[144:147], v149, s[84:85] offset:832
	s_add_u32 s84, s84, 0x30000
	s_addc_u32 s85, s85, 0
	global_load_dwordx4 v[156:159], v235, s[84:85]
	global_load_dwordx4 v[160:163], v236, s[84:85]
	global_load_dwordx4 v[164:167], v237, s[84:85]
	global_load_dwordx4 v[168:171], v238, s[84:85]
	global_load_dwordx4 v[172:175], v100, s[84:85] offset:768
	global_load_dwordx4 v[176:179], v149, s[84:85] offset:768
	global_load_dwordx4 v[180:183], v100, s[84:85] offset:832
	global_load_dwordx4 v[184:187], v149, s[84:85] offset:832
	s_add_u32 s84, s84, 0x30000
	s_addc_u32 s85, s85, 0
	global_load_dwordx4 v[188:191], v235, s[84:85]
	global_load_dwordx4 v[192:195], v236, s[84:85]
	global_load_dwordx4 v[196:199], v237, s[84:85]
	global_load_dwordx4 v[200:203], v238, s[84:85]
	global_load_dwordx4 v[204:207], v100, s[84:85] offset:768
	global_load_dwordx4 v[208:211], v149, s[84:85] offset:768
	global_load_dwordx4 v[212:215], v100, s[84:85] offset:832
	global_load_dwordx4 v[216:219], v149, s[84:85] offset:832
	s_add_u32 s84, s84, 0x30000
	s_addc_u32 s85, s85, 0
	s_waitcnt vmcnt(16)
	ds_write_b128 v247, v[116:119]
	ds_write_b128 v247, v[120:123] offset:1024
	ds_write_b128 v247, v[124:127] offset:2048
	ds_write_b128 v247, v[128:131] offset:3072
	ds_read_b128 v[116:119], v248
	ds_read_b128 v[120:123], v249
	ds_read_b128 v[124:127], v250
	ds_read_b128 v[128:131], v251
	ds_write_b128 v112, v[132:135]
	ds_write_b128 v112, v[136:139] offset:1024
	ds_write_b128 v112, v[140:143] offset:2048
	ds_write_b128 v112, v[144:147] offset:3072
	v_mov_b32_e32 v115, v228
	ds_read2_b32 v[32:33], v115 offset0:0 offset1:1
	ds_read2_b32 v[34:35], v115 offset0:2 offset1:3
	ds_read2_b32 v[36:37], v115 offset0:8 offset1:9
	ds_read2_b32 v[38:39], v115 offset0:10 offset1:11
	ds_read2_b32 v[40:41], v115 offset0:17 offset1:18
	ds_read2_b32 v[42:43], v115 offset0:19 offset1:20
	ds_read2_b32 v[44:45], v115 offset0:25 offset1:26
	ds_read2_b32 v[46:47], v115 offset0:27 offset1:28
	s_waitcnt lgkmcnt(0)
	v_mfma_f32_32x32x16_bf16 v[32:47], v[116:119], v[48:51], v[32:47]
	ds_read_b64_tr_b16 v[72:73], v231
	ds_read_b64_tr_b16 v[74:75], v231 offset:512
	ds_read_b64_tr_b16 v[76:77], v231 offset:2048
	ds_read_b64_tr_b16 v[78:79], v231 offset:2560
	ds_read_b64_tr_b16 v[220:221], v231 offset:1024
	ds_read_b64_tr_b16 v[222:223], v231 offset:1536
	ds_read_b64_tr_b16 v[224:225], v231 offset:3072
	ds_read_b64_tr_b16 v[226:227], v231 offset:3584
	s_waitcnt vmcnt(8)
	ds_write_b128 v247, v[156:159]
	ds_write_b128 v247, v[160:163] offset:1024
	ds_write_b128 v247, v[164:167] offset:2048
	ds_write_b128 v247, v[168:171] offset:3072
	ds_read_b128 v[156:159], v248
	ds_read_b128 v[160:163], v249
	ds_read_b128 v[164:167], v250
	ds_read_b128 v[168:171], v251
	ds_write_b128 v112, v[172:175]
	ds_write_b128 v112, v[176:179] offset:1024
	ds_write_b128 v112, v[180:183] offset:2048
	ds_write_b128 v112, v[184:187] offset:3072
	v_mfma_f32_32x32x16_bf16 v[32:47], v[120:123], v[52:55], v[32:47]
	v_mfma_f32_32x32x16_bf16 v[32:47], v[124:127], v[56:59], v[32:47]
	v_mfma_f32_32x32x16_bf16 v[32:47], v[128:131], v[60:63], v[32:47]
	s_nop 11
	v_exp_f32_e32 v32, v32
	v_exp_f32_e32 v33, v33
	v_exp_f32_e32 v34, v34
	v_exp_f32_e32 v35, v35
	v_exp_f32_e32 v36, v36
	v_exp_f32_e32 v37, v37
	v_exp_f32_e32 v38, v38
	v_exp_f32_e32 v39, v39
	v_exp_f32_e32 v40, v40
	v_exp_f32_e32 v41, v41
	v_exp_f32_e32 v42, v42
	v_exp_f32_e32 v43, v43
	v_exp_f32_e32 v44, v44
	v_exp_f32_e32 v45, v45
	v_exp_f32_e32 v46, v46
	v_exp_f32_e32 v47, v47
	v_cvt_pk_bf16_f32 v64, v32, v33
	v_cvt_pk_bf16_f32 v65, v34, v35
	v_cvt_pk_bf16_f32 v66, v36, v37
	v_cvt_pk_bf16_f32 v67, v38, v39
	v_cvt_pk_bf16_f32 v68, v40, v41
	v_cvt_pk_bf16_f32 v69, v42, v43
	v_cvt_pk_bf16_f32 v70, v44, v45
	v_cvt_pk_bf16_f32 v71, v46, v47
	v_pk_add_f32 v[232:233], v[232:233], v[32:33]
	v_pk_add_f32 v[232:233], v[232:233], v[34:35]
	v_pk_add_f32 v[232:233], v[232:233], v[36:37]
	v_pk_add_f32 v[232:233], v[232:233], v[38:39]
	v_pk_add_f32 v[232:233], v[232:233], v[40:41]
	v_pk_add_f32 v[232:233], v[232:233], v[42:43]
	v_pk_add_f32 v[232:233], v[232:233], v[44:45]
	v_pk_add_f32 v[232:233], v[232:233], v[46:47]
	s_waitcnt lgkmcnt(12)
	v_mfma_f32_32x32x16_bf16 v[0:15], v[64:67], v[72:75], v[0:15]
	v_mfma_f32_32x32x16_bf16 v[16:31], v[64:67], v[76:79], v[16:31]
	v_mfma_f32_32x32x16_bf16 v[0:15], v[68:71], v[220:223], v[0:15]
	v_mfma_f32_32x32x16_bf16 v[16:31], v[68:71], v[224:227], v[16:31]
	global_load_dwordx4 v[116:119], v235, s[84:85]
	global_load_dwordx4 v[120:123], v236, s[84:85]
	global_load_dwordx4 v[124:127], v237, s[84:85]
	global_load_dwordx4 v[128:131], v238, s[84:85]
	global_load_dwordx4 v[132:135], v100, s[84:85] offset:768
	global_load_dwordx4 v[136:139], v149, s[84:85] offset:768
	global_load_dwordx4 v[140:143], v100, s[84:85] offset:832
	global_load_dwordx4 v[144:147], v149, s[84:85] offset:832
	s_add_u32 s84, s84, 0x30000
	s_addc_u32 s85, s85, 0
	ds_read2_b32 v[32:33], v115 offset0:34 offset1:35
	ds_read2_b32 v[34:35], v115 offset0:36 offset1:37
	ds_read2_b32 v[36:37], v115 offset0:42 offset1:43
	ds_read2_b32 v[38:39], v115 offset0:44 offset1:45
	ds_read2_b32 v[40:41], v115 offset0:51 offset1:52
	ds_read2_b32 v[42:43], v115 offset0:53 offset1:54
	ds_read2_b32 v[44:45], v115 offset0:59 offset1:60
	ds_read2_b32 v[46:47], v115 offset0:61 offset1:62
	s_waitcnt lgkmcnt(0)
	v_mfma_f32_32x32x16_bf16 v[32:47], v[156:159], v[48:51], v[32:47]
	ds_read_b64_tr_b16 v[72:73], v231
	ds_read_b64_tr_b16 v[74:75], v231 offset:512
	ds_read_b64_tr_b16 v[76:77], v231 offset:2048
	ds_read_b64_tr_b16 v[78:79], v231 offset:2560
	ds_read_b64_tr_b16 v[220:221], v231 offset:1024
	ds_read_b64_tr_b16 v[222:223], v231 offset:1536
	ds_read_b64_tr_b16 v[224:225], v231 offset:3072
	ds_read_b64_tr_b16 v[226:227], v231 offset:3584
	s_waitcnt vmcnt(8)
	ds_write_b128 v247, v[188:191]
	ds_write_b128 v247, v[192:195] offset:1024
	ds_write_b128 v247, v[196:199] offset:2048
	ds_write_b128 v247, v[200:203] offset:3072
	ds_read_b128 v[188:191], v248
	ds_read_b128 v[192:195], v249
	ds_read_b128 v[196:199], v250
	ds_read_b128 v[200:203], v251
	ds_write_b128 v112, v[204:207]
	ds_write_b128 v112, v[208:211] offset:1024
	ds_write_b128 v112, v[212:215] offset:2048
	ds_write_b128 v112, v[216:219] offset:3072
	v_mfma_f32_32x32x16_bf16 v[32:47], v[160:163], v[52:55], v[32:47]
	v_mfma_f32_32x32x16_bf16 v[32:47], v[164:167], v[56:59], v[32:47]
	v_mfma_f32_32x32x16_bf16 v[32:47], v[168:171], v[60:63], v[32:47]
	s_nop 11
	v_exp_f32_e32 v32, v32
	v_exp_f32_e32 v33, v33
	v_exp_f32_e32 v34, v34
	v_exp_f32_e32 v35, v35
	v_exp_f32_e32 v36, v36
	v_exp_f32_e32 v37, v37
	v_exp_f32_e32 v38, v38
	v_exp_f32_e32 v39, v39
	v_exp_f32_e32 v40, v40
	v_exp_f32_e32 v41, v41
	v_exp_f32_e32 v42, v42
	v_exp_f32_e32 v43, v43
	v_exp_f32_e32 v44, v44
	v_exp_f32_e32 v45, v45
	v_exp_f32_e32 v46, v46
	v_exp_f32_e32 v47, v47
	v_cvt_pk_bf16_f32 v64, v32, v33
	v_cvt_pk_bf16_f32 v65, v34, v35
	v_cvt_pk_bf16_f32 v66, v36, v37
	v_cvt_pk_bf16_f32 v67, v38, v39
	v_cvt_pk_bf16_f32 v68, v40, v41
	v_cvt_pk_bf16_f32 v69, v42, v43
	v_cvt_pk_bf16_f32 v70, v44, v45
	v_cvt_pk_bf16_f32 v71, v46, v47
	v_pk_add_f32 v[232:233], v[232:233], v[32:33]
	v_pk_add_f32 v[232:233], v[232:233], v[34:35]
	v_pk_add_f32 v[232:233], v[232:233], v[36:37]
	v_pk_add_f32 v[232:233], v[232:233], v[38:39]
	v_pk_add_f32 v[232:233], v[232:233], v[40:41]
	v_pk_add_f32 v[232:233], v[232:233], v[42:43]
	v_pk_add_f32 v[232:233], v[232:233], v[44:45]
	v_pk_add_f32 v[232:233], v[232:233], v[46:47]
	s_waitcnt lgkmcnt(12)
	v_mfma_f32_32x32x16_bf16 v[0:15], v[64:67], v[72:75], v[0:15]
	v_mfma_f32_32x32x16_bf16 v[16:31], v[64:67], v[76:79], v[16:31]
	v_mfma_f32_32x32x16_bf16 v[0:15], v[68:71], v[220:223], v[0:15]
	v_mfma_f32_32x32x16_bf16 v[16:31], v[68:71], v[224:227], v[16:31]
	global_load_dwordx4 v[156:159], v235, s[84:85]
	global_load_dwordx4 v[160:163], v236, s[84:85]
	global_load_dwordx4 v[164:167], v237, s[84:85]
	global_load_dwordx4 v[168:171], v238, s[84:85]
	global_load_dwordx4 v[172:175], v100, s[84:85] offset:768
	global_load_dwordx4 v[176:179], v149, s[84:85] offset:768
	global_load_dwordx4 v[180:183], v100, s[84:85] offset:832
	global_load_dwordx4 v[184:187], v149, s[84:85] offset:832
	s_add_u32 s84, s84, 0x30000
	s_addc_u32 s85, s85, 0
	ds_read2_b32 v[32:33], v115 offset0:68 offset1:69
	ds_read2_b32 v[34:35], v115 offset0:70 offset1:71
	ds_read2_b32 v[36:37], v115 offset0:76 offset1:77
	ds_read2_b32 v[38:39], v115 offset0:78 offset1:79
	ds_read2_b32 v[40:41], v115 offset0:85 offset1:86
	ds_read2_b32 v[42:43], v115 offset0:87 offset1:88
	ds_read2_b32 v[44:45], v115 offset0:93 offset1:94
	ds_read2_b32 v[46:47], v115 offset0:95 offset1:96
	s_waitcnt lgkmcnt(0)
	v_mfma_f32_32x32x16_bf16 v[32:47], v[188:191], v[48:51], v[32:47]
	ds_read_b64_tr_b16 v[72:73], v231
	ds_read_b64_tr_b16 v[74:75], v231 offset:512
	ds_read_b64_tr_b16 v[76:77], v231 offset:2048
	ds_read_b64_tr_b16 v[78:79], v231 offset:2560
	ds_read_b64_tr_b16 v[220:221], v231 offset:1024
	ds_read_b64_tr_b16 v[222:223], v231 offset:1536
	ds_read_b64_tr_b16 v[224:225], v231 offset:3072
	ds_read_b64_tr_b16 v[226:227], v231 offset:3584
	s_waitcnt vmcnt(8)
	ds_write_b128 v247, v[116:119]
	ds_write_b128 v247, v[120:123] offset:1024
	ds_write_b128 v247, v[124:127] offset:2048
	ds_write_b128 v247, v[128:131] offset:3072
	ds_read_b128 v[116:119], v248
	ds_read_b128 v[120:123], v249
	ds_read_b128 v[124:127], v250
	ds_read_b128 v[128:131], v251
	ds_write_b128 v112, v[132:135]
	ds_write_b128 v112, v[136:139] offset:1024
	ds_write_b128 v112, v[140:143] offset:2048
	ds_write_b128 v112, v[144:147] offset:3072
	v_mfma_f32_32x32x16_bf16 v[32:47], v[192:195], v[52:55], v[32:47]
	v_mfma_f32_32x32x16_bf16 v[32:47], v[196:199], v[56:59], v[32:47]
	v_mfma_f32_32x32x16_bf16 v[32:47], v[200:203], v[60:63], v[32:47]
	s_nop 11
	v_exp_f32_e32 v32, v32
	v_exp_f32_e32 v33, v33
	v_exp_f32_e32 v34, v34
	v_exp_f32_e32 v35, v35
	v_exp_f32_e32 v36, v36
	v_exp_f32_e32 v37, v37
	v_exp_f32_e32 v38, v38
	v_exp_f32_e32 v39, v39
	v_exp_f32_e32 v40, v40
	v_exp_f32_e32 v41, v41
	v_exp_f32_e32 v42, v42
	v_exp_f32_e32 v43, v43
	v_exp_f32_e32 v44, v44
	v_exp_f32_e32 v45, v45
	v_exp_f32_e32 v46, v46
	v_exp_f32_e32 v47, v47
	v_cvt_pk_bf16_f32 v64, v32, v33
	v_cvt_pk_bf16_f32 v65, v34, v35
	v_cvt_pk_bf16_f32 v66, v36, v37
	v_cvt_pk_bf16_f32 v67, v38, v39
	v_cvt_pk_bf16_f32 v68, v40, v41
	v_cvt_pk_bf16_f32 v69, v42, v43
	v_cvt_pk_bf16_f32 v70, v44, v45
	v_cvt_pk_bf16_f32 v71, v46, v47
	v_pk_add_f32 v[232:233], v[232:233], v[32:33]
	v_pk_add_f32 v[232:233], v[232:233], v[34:35]
	v_pk_add_f32 v[232:233], v[232:233], v[36:37]
	v_pk_add_f32 v[232:233], v[232:233], v[38:39]
	v_pk_add_f32 v[232:233], v[232:233], v[40:41]
	v_pk_add_f32 v[232:233], v[232:233], v[42:43]
	v_pk_add_f32 v[232:233], v[232:233], v[44:45]
	v_pk_add_f32 v[232:233], v[232:233], v[46:47]
	s_waitcnt lgkmcnt(12)
	v_mfma_f32_32x32x16_bf16 v[0:15], v[64:67], v[72:75], v[0:15]
	v_mfma_f32_32x32x16_bf16 v[16:31], v[64:67], v[76:79], v[16:31]
	v_mfma_f32_32x32x16_bf16 v[0:15], v[68:71], v[220:223], v[0:15]
	v_mfma_f32_32x32x16_bf16 v[16:31], v[68:71], v[224:227], v[16:31]
	global_load_dwordx4 v[188:191], v235, s[84:85]
	global_load_dwordx4 v[192:195], v236, s[84:85]
	global_load_dwordx4 v[196:199], v237, s[84:85]
	global_load_dwordx4 v[200:203], v238, s[84:85]
	global_load_dwordx4 v[204:207], v100, s[84:85] offset:768
	global_load_dwordx4 v[208:211], v149, s[84:85] offset:768
	global_load_dwordx4 v[212:215], v100, s[84:85] offset:832
	global_load_dwordx4 v[216:219], v149, s[84:85] offset:832
	s_add_u32 s84, s84, 0x30000
	s_addc_u32 s85, s85, 0
	ds_read2_b32 v[32:33], v115 offset0:102 offset1:103
	ds_read2_b32 v[34:35], v115 offset0:104 offset1:105
	ds_read2_b32 v[36:37], v115 offset0:110 offset1:111
	ds_read2_b32 v[38:39], v115 offset0:112 offset1:113
	ds_read2_b32 v[40:41], v115 offset0:119 offset1:120
	ds_read2_b32 v[42:43], v115 offset0:121 offset1:122
	ds_read2_b32 v[44:45], v115 offset0:127 offset1:128
	ds_read2_b32 v[46:47], v115 offset0:129 offset1:130
	s_waitcnt lgkmcnt(0)
	v_mfma_f32_32x32x16_bf16 v[32:47], v[116:119], v[48:51], v[32:47]
	ds_read_b64_tr_b16 v[72:73], v231
	ds_read_b64_tr_b16 v[74:75], v231 offset:512
	ds_read_b64_tr_b16 v[76:77], v231 offset:2048
	ds_read_b64_tr_b16 v[78:79], v231 offset:2560
	ds_read_b64_tr_b16 v[220:221], v231 offset:1024
	ds_read_b64_tr_b16 v[222:223], v231 offset:1536
	ds_read_b64_tr_b16 v[224:225], v231 offset:3072
	ds_read_b64_tr_b16 v[226:227], v231 offset:3584
	s_waitcnt vmcnt(8)
	ds_write_b128 v247, v[156:159]
	ds_write_b128 v247, v[160:163] offset:1024
	ds_write_b128 v247, v[164:167] offset:2048
	ds_write_b128 v247, v[168:171] offset:3072
	ds_read_b128 v[156:159], v248
	ds_read_b128 v[160:163], v249
	ds_read_b128 v[164:167], v250
	ds_read_b128 v[168:171], v251
	ds_write_b128 v112, v[172:175]
	ds_write_b128 v112, v[176:179] offset:1024
	ds_write_b128 v112, v[180:183] offset:2048
	ds_write_b128 v112, v[184:187] offset:3072
	v_mfma_f32_32x32x16_bf16 v[32:47], v[120:123], v[52:55], v[32:47]
	v_mfma_f32_32x32x16_bf16 v[32:47], v[124:127], v[56:59], v[32:47]
	v_mfma_f32_32x32x16_bf16 v[32:47], v[128:131], v[60:63], v[32:47]
	s_nop 11
	v_exp_f32_e32 v32, v32
	v_exp_f32_e32 v33, v33
	v_exp_f32_e32 v34, v34
	v_exp_f32_e32 v35, v35
	v_exp_f32_e32 v36, v36
	v_exp_f32_e32 v37, v37
	v_exp_f32_e32 v38, v38
	v_exp_f32_e32 v39, v39
	v_exp_f32_e32 v40, v40
	v_exp_f32_e32 v41, v41
	v_exp_f32_e32 v42, v42
	v_exp_f32_e32 v43, v43
	v_exp_f32_e32 v44, v44
	v_exp_f32_e32 v45, v45
	v_exp_f32_e32 v46, v46
	v_exp_f32_e32 v47, v47
	v_cvt_pk_bf16_f32 v64, v32, v33
	v_cvt_pk_bf16_f32 v65, v34, v35
	v_cvt_pk_bf16_f32 v66, v36, v37
	v_cvt_pk_bf16_f32 v67, v38, v39
	v_cvt_pk_bf16_f32 v68, v40, v41
	v_cvt_pk_bf16_f32 v69, v42, v43
	v_cvt_pk_bf16_f32 v70, v44, v45
	v_cvt_pk_bf16_f32 v71, v46, v47
	v_pk_add_f32 v[232:233], v[232:233], v[32:33]
	v_pk_add_f32 v[232:233], v[232:233], v[34:35]
	v_pk_add_f32 v[232:233], v[232:233], v[36:37]
	v_pk_add_f32 v[232:233], v[232:233], v[38:39]
	v_pk_add_f32 v[232:233], v[232:233], v[40:41]
	v_pk_add_f32 v[232:233], v[232:233], v[42:43]
	v_pk_add_f32 v[232:233], v[232:233], v[44:45]
	v_pk_add_f32 v[232:233], v[232:233], v[46:47]
	s_waitcnt lgkmcnt(12)
	v_mfma_f32_32x32x16_bf16 v[0:15], v[64:67], v[72:75], v[0:15]
	v_mfma_f32_32x32x16_bf16 v[16:31], v[64:67], v[76:79], v[16:31]
	v_mfma_f32_32x32x16_bf16 v[0:15], v[68:71], v[220:223], v[0:15]
	v_mfma_f32_32x32x16_bf16 v[16:31], v[68:71], v[224:227], v[16:31]
	global_load_dwordx4 v[116:119], v235, s[84:85]
	global_load_dwordx4 v[120:123], v236, s[84:85]
	global_load_dwordx4 v[124:127], v237, s[84:85]
	global_load_dwordx4 v[128:131], v238, s[84:85]
	global_load_dwordx4 v[132:135], v100, s[84:85] offset:768
	global_load_dwordx4 v[136:139], v149, s[84:85] offset:768
	global_load_dwordx4 v[140:143], v100, s[84:85] offset:832
	global_load_dwordx4 v[144:147], v149, s[84:85] offset:832
	s_add_u32 s84, s84, 0x30000
	s_addc_u32 s85, s85, 0
	ds_read2_b32 v[32:33], v115 offset0:136 offset1:137
	ds_read2_b32 v[34:35], v115 offset0:138 offset1:139
	ds_read2_b32 v[36:37], v115 offset0:144 offset1:145
	ds_read2_b32 v[38:39], v115 offset0:146 offset1:147
	ds_read2_b32 v[40:41], v115 offset0:153 offset1:154
	ds_read2_b32 v[42:43], v115 offset0:155 offset1:156
	ds_read2_b32 v[44:45], v115 offset0:161 offset1:162
	ds_read2_b32 v[46:47], v115 offset0:163 offset1:164
	s_waitcnt lgkmcnt(0)
	v_mfma_f32_32x32x16_bf16 v[32:47], v[156:159], v[48:51], v[32:47]
	ds_read_b64_tr_b16 v[72:73], v231
	ds_read_b64_tr_b16 v[74:75], v231 offset:512
	ds_read_b64_tr_b16 v[76:77], v231 offset:2048
	ds_read_b64_tr_b16 v[78:79], v231 offset:2560
	ds_read_b64_tr_b16 v[220:221], v231 offset:1024
	ds_read_b64_tr_b16 v[222:223], v231 offset:1536
	ds_read_b64_tr_b16 v[224:225], v231 offset:3072
	ds_read_b64_tr_b16 v[226:227], v231 offset:3584
	s_waitcnt vmcnt(8)
	ds_write_b128 v247, v[188:191]
	ds_write_b128 v247, v[192:195] offset:1024
	ds_write_b128 v247, v[196:199] offset:2048
	ds_write_b128 v247, v[200:203] offset:3072
	ds_read_b128 v[188:191], v248
	ds_read_b128 v[192:195], v249
	ds_read_b128 v[196:199], v250
	ds_read_b128 v[200:203], v251
	ds_write_b128 v112, v[204:207]
	ds_write_b128 v112, v[208:211] offset:1024
	ds_write_b128 v112, v[212:215] offset:2048
	ds_write_b128 v112, v[216:219] offset:3072
	v_mfma_f32_32x32x16_bf16 v[32:47], v[160:163], v[52:55], v[32:47]
	v_mfma_f32_32x32x16_bf16 v[32:47], v[164:167], v[56:59], v[32:47]
	v_mfma_f32_32x32x16_bf16 v[32:47], v[168:171], v[60:63], v[32:47]
	s_nop 11
	v_exp_f32_e32 v32, v32
	v_exp_f32_e32 v33, v33
	v_exp_f32_e32 v34, v34
	v_exp_f32_e32 v35, v35
	v_exp_f32_e32 v36, v36
	v_exp_f32_e32 v37, v37
	v_exp_f32_e32 v38, v38
	v_exp_f32_e32 v39, v39
	v_exp_f32_e32 v40, v40
	v_exp_f32_e32 v41, v41
	v_exp_f32_e32 v42, v42
	v_exp_f32_e32 v43, v43
	v_exp_f32_e32 v44, v44
	v_exp_f32_e32 v45, v45
	v_exp_f32_e32 v46, v46
	v_exp_f32_e32 v47, v47
	v_cvt_pk_bf16_f32 v64, v32, v33
	v_cvt_pk_bf16_f32 v65, v34, v35
	v_cvt_pk_bf16_f32 v66, v36, v37
	v_cvt_pk_bf16_f32 v67, v38, v39
	v_cvt_pk_bf16_f32 v68, v40, v41
	v_cvt_pk_bf16_f32 v69, v42, v43
	v_cvt_pk_bf16_f32 v70, v44, v45
	v_cvt_pk_bf16_f32 v71, v46, v47
	v_pk_add_f32 v[232:233], v[232:233], v[32:33]
	v_pk_add_f32 v[232:233], v[232:233], v[34:35]
	v_pk_add_f32 v[232:233], v[232:233], v[36:37]
	v_pk_add_f32 v[232:233], v[232:233], v[38:39]
	v_pk_add_f32 v[232:233], v[232:233], v[40:41]
	v_pk_add_f32 v[232:233], v[232:233], v[42:43]
	v_pk_add_f32 v[232:233], v[232:233], v[44:45]
	v_pk_add_f32 v[232:233], v[232:233], v[46:47]
	s_waitcnt lgkmcnt(12)
	v_mfma_f32_32x32x16_bf16 v[0:15], v[64:67], v[72:75], v[0:15]
	v_mfma_f32_32x32x16_bf16 v[16:31], v[64:67], v[76:79], v[16:31]
	v_mfma_f32_32x32x16_bf16 v[0:15], v[68:71], v[220:223], v[0:15]
	v_mfma_f32_32x32x16_bf16 v[16:31], v[68:71], v[224:227], v[16:31]
	global_load_dwordx4 v[156:159], v235, s[84:85]
	global_load_dwordx4 v[160:163], v236, s[84:85]
	global_load_dwordx4 v[164:167], v237, s[84:85]
	global_load_dwordx4 v[168:171], v238, s[84:85]
	global_load_dwordx4 v[172:175], v100, s[84:85] offset:768
	global_load_dwordx4 v[176:179], v149, s[84:85] offset:768
	global_load_dwordx4 v[180:183], v100, s[84:85] offset:832
	global_load_dwordx4 v[184:187], v149, s[84:85] offset:832
	s_add_u32 s84, s84, 0x30000
	s_addc_u32 s85, s85, 0
	ds_read2_b32 v[32:33], v115 offset0:170 offset1:171
	ds_read2_b32 v[34:35], v115 offset0:172 offset1:173
	ds_read2_b32 v[36:37], v115 offset0:178 offset1:179
	ds_read2_b32 v[38:39], v115 offset0:180 offset1:181
	ds_read2_b32 v[40:41], v115 offset0:187 offset1:188
	ds_read2_b32 v[42:43], v115 offset0:189 offset1:190
	ds_read2_b32 v[44:45], v115 offset0:195 offset1:196
	ds_read2_b32 v[46:47], v115 offset0:197 offset1:198
	s_waitcnt lgkmcnt(0)
	v_mfma_f32_32x32x16_bf16 v[32:47], v[188:191], v[48:51], v[32:47]
	ds_read_b64_tr_b16 v[72:73], v231
	ds_read_b64_tr_b16 v[74:75], v231 offset:512
	ds_read_b64_tr_b16 v[76:77], v231 offset:2048
	ds_read_b64_tr_b16 v[78:79], v231 offset:2560
	ds_read_b64_tr_b16 v[220:221], v231 offset:1024
	ds_read_b64_tr_b16 v[222:223], v231 offset:1536
	ds_read_b64_tr_b16 v[224:225], v231 offset:3072
	ds_read_b64_tr_b16 v[226:227], v231 offset:3584
	s_waitcnt vmcnt(8)
	ds_write_b128 v247, v[116:119]
	ds_write_b128 v247, v[120:123] offset:1024
	ds_write_b128 v247, v[124:127] offset:2048
	ds_write_b128 v247, v[128:131] offset:3072
	ds_read_b128 v[116:119], v248
	ds_read_b128 v[120:123], v249
	ds_read_b128 v[124:127], v250
	ds_read_b128 v[128:131], v251
	ds_write_b128 v112, v[132:135]
	ds_write_b128 v112, v[136:139] offset:1024
	ds_write_b128 v112, v[140:143] offset:2048
	ds_write_b128 v112, v[144:147] offset:3072
	v_mfma_f32_32x32x16_bf16 v[32:47], v[192:195], v[52:55], v[32:47]
	v_mfma_f32_32x32x16_bf16 v[32:47], v[196:199], v[56:59], v[32:47]
	v_mfma_f32_32x32x16_bf16 v[32:47], v[200:203], v[60:63], v[32:47]
	s_nop 11
	v_exp_f32_e32 v32, v32
	v_exp_f32_e32 v33, v33
	v_exp_f32_e32 v34, v34
	v_exp_f32_e32 v35, v35
	v_exp_f32_e32 v36, v36
	v_exp_f32_e32 v37, v37
	v_exp_f32_e32 v38, v38
	v_exp_f32_e32 v39, v39
	v_exp_f32_e32 v40, v40
	v_exp_f32_e32 v41, v41
	v_exp_f32_e32 v42, v42
	v_exp_f32_e32 v43, v43
	v_exp_f32_e32 v44, v44
	v_exp_f32_e32 v45, v45
	v_exp_f32_e32 v46, v46
	v_exp_f32_e32 v47, v47
	v_cvt_pk_bf16_f32 v64, v32, v33
	v_cvt_pk_bf16_f32 v65, v34, v35
	v_cvt_pk_bf16_f32 v66, v36, v37
	v_cvt_pk_bf16_f32 v67, v38, v39
	v_cvt_pk_bf16_f32 v68, v40, v41
	v_cvt_pk_bf16_f32 v69, v42, v43
	v_cvt_pk_bf16_f32 v70, v44, v45
	v_cvt_pk_bf16_f32 v71, v46, v47
	v_pk_add_f32 v[232:233], v[232:233], v[32:33]
	v_pk_add_f32 v[232:233], v[232:233], v[34:35]
	v_pk_add_f32 v[232:233], v[232:233], v[36:37]
	v_pk_add_f32 v[232:233], v[232:233], v[38:39]
	v_pk_add_f32 v[232:233], v[232:233], v[40:41]
	v_pk_add_f32 v[232:233], v[232:233], v[42:43]
	v_pk_add_f32 v[232:233], v[232:233], v[44:45]
	v_pk_add_f32 v[232:233], v[232:233], v[46:47]
	s_waitcnt lgkmcnt(12)
	v_mfma_f32_32x32x16_bf16 v[0:15], v[64:67], v[72:75], v[0:15]
	v_mfma_f32_32x32x16_bf16 v[16:31], v[64:67], v[76:79], v[16:31]
	v_mfma_f32_32x32x16_bf16 v[0:15], v[68:71], v[220:223], v[0:15]
	v_mfma_f32_32x32x16_bf16 v[16:31], v[68:71], v[224:227], v[16:31]
	global_load_dwordx4 v[188:191], v235, s[84:85]
	global_load_dwordx4 v[192:195], v236, s[84:85]
	global_load_dwordx4 v[196:199], v237, s[84:85]
	global_load_dwordx4 v[200:203], v238, s[84:85]
	global_load_dwordx4 v[204:207], v100, s[84:85] offset:768
	global_load_dwordx4 v[208:211], v149, s[84:85] offset:768
	global_load_dwordx4 v[212:215], v100, s[84:85] offset:832
	global_load_dwordx4 v[216:219], v149, s[84:85] offset:832
	s_add_u32 s84, s84, 0x30000
	s_addc_u32 s85, s85, 0
	ds_read2_b32 v[32:33], v115 offset0:204 offset1:205
	ds_read2_b32 v[34:35], v115 offset0:206 offset1:207
	ds_read2_b32 v[36:37], v115 offset0:212 offset1:213
	ds_read2_b32 v[38:39], v115 offset0:214 offset1:215
	ds_read2_b32 v[40:41], v115 offset0:221 offset1:222
	ds_read2_b32 v[42:43], v115 offset0:223 offset1:224
	ds_read2_b32 v[44:45], v115 offset0:229 offset1:230
	ds_read2_b32 v[46:47], v115 offset0:231 offset1:232
	s_waitcnt lgkmcnt(0)
	v_mfma_f32_32x32x16_bf16 v[32:47], v[116:119], v[48:51], v[32:47]
	ds_read_b64_tr_b16 v[72:73], v231
	ds_read_b64_tr_b16 v[74:75], v231 offset:512
	ds_read_b64_tr_b16 v[76:77], v231 offset:2048
	ds_read_b64_tr_b16 v[78:79], v231 offset:2560
	ds_read_b64_tr_b16 v[220:221], v231 offset:1024
	ds_read_b64_tr_b16 v[222:223], v231 offset:1536
	ds_read_b64_tr_b16 v[224:225], v231 offset:3072
	ds_read_b64_tr_b16 v[226:227], v231 offset:3584
	s_waitcnt vmcnt(8)
	ds_write_b128 v247, v[156:159]
	ds_write_b128 v247, v[160:163] offset:1024
	ds_write_b128 v247, v[164:167] offset:2048
	ds_write_b128 v247, v[168:171] offset:3072
	ds_read_b128 v[156:159], v248
	ds_read_b128 v[160:163], v249
	ds_read_b128 v[164:167], v250
	ds_read_b128 v[168:171], v251
	ds_write_b128 v112, v[172:175]
	ds_write_b128 v112, v[176:179] offset:1024
	ds_write_b128 v112, v[180:183] offset:2048
	ds_write_b128 v112, v[184:187] offset:3072
	v_mfma_f32_32x32x16_bf16 v[32:47], v[120:123], v[52:55], v[32:47]
	v_mfma_f32_32x32x16_bf16 v[32:47], v[124:127], v[56:59], v[32:47]
	v_mfma_f32_32x32x16_bf16 v[32:47], v[128:131], v[60:63], v[32:47]
	s_nop 11
	v_exp_f32_e32 v32, v32
	v_exp_f32_e32 v33, v33
	v_exp_f32_e32 v34, v34
	v_exp_f32_e32 v35, v35
	v_exp_f32_e32 v36, v36
	v_exp_f32_e32 v37, v37
	v_exp_f32_e32 v38, v38
	v_exp_f32_e32 v39, v39
	v_exp_f32_e32 v40, v40
	v_exp_f32_e32 v41, v41
	v_exp_f32_e32 v42, v42
	v_exp_f32_e32 v43, v43
	v_exp_f32_e32 v44, v44
	v_exp_f32_e32 v45, v45
	v_exp_f32_e32 v46, v46
	v_exp_f32_e32 v47, v47
	v_cvt_pk_bf16_f32 v64, v32, v33
	v_cvt_pk_bf16_f32 v65, v34, v35
	v_cvt_pk_bf16_f32 v66, v36, v37
	v_cvt_pk_bf16_f32 v67, v38, v39
	v_cvt_pk_bf16_f32 v68, v40, v41
	v_cvt_pk_bf16_f32 v69, v42, v43
	v_cvt_pk_bf16_f32 v70, v44, v45
	v_cvt_pk_bf16_f32 v71, v46, v47
	v_pk_add_f32 v[232:233], v[232:233], v[32:33]
	v_pk_add_f32 v[232:233], v[232:233], v[34:35]
	v_pk_add_f32 v[232:233], v[232:233], v[36:37]
	v_pk_add_f32 v[232:233], v[232:233], v[38:39]
	v_pk_add_f32 v[232:233], v[232:233], v[40:41]
	v_pk_add_f32 v[232:233], v[232:233], v[42:43]
	v_pk_add_f32 v[232:233], v[232:233], v[44:45]
	v_pk_add_f32 v[232:233], v[232:233], v[46:47]
	s_waitcnt lgkmcnt(12)
	v_mfma_f32_32x32x16_bf16 v[0:15], v[64:67], v[72:75], v[0:15]
	v_mfma_f32_32x32x16_bf16 v[16:31], v[64:67], v[76:79], v[16:31]
	v_mfma_f32_32x32x16_bf16 v[0:15], v[68:71], v[220:223], v[0:15]
	v_mfma_f32_32x32x16_bf16 v[16:31], v[68:71], v[224:227], v[16:31]
	global_load_dwordx4 v[116:119], v235, s[84:85]
	global_load_dwordx4 v[120:123], v236, s[84:85]
	global_load_dwordx4 v[124:127], v237, s[84:85]
	global_load_dwordx4 v[128:131], v238, s[84:85]
	global_load_dwordx4 v[132:135], v100, s[84:85] offset:768
	global_load_dwordx4 v[136:139], v149, s[84:85] offset:768
	global_load_dwordx4 v[140:143], v100, s[84:85] offset:832
	global_load_dwordx4 v[144:147], v149, s[84:85] offset:832
	s_add_u32 s84, s84, 0x30000
	s_addc_u32 s85, s85, 0
	v_add_u32_e32 v115, 952, v115
	ds_read2_b32 v[32:33], v115 offset0:0 offset1:1
	ds_read2_b32 v[34:35], v115 offset0:2 offset1:3
	ds_read2_b32 v[36:37], v115 offset0:8 offset1:9
	ds_read2_b32 v[38:39], v115 offset0:10 offset1:11
	ds_read2_b32 v[40:41], v115 offset0:17 offset1:18
	ds_read2_b32 v[42:43], v115 offset0:19 offset1:20
	ds_read2_b32 v[44:45], v115 offset0:25 offset1:26
	ds_read2_b32 v[46:47], v115 offset0:27 offset1:28
	s_waitcnt lgkmcnt(0)
	v_mfma_f32_32x32x16_bf16 v[32:47], v[156:159], v[48:51], v[32:47]
	ds_read_b64_tr_b16 v[72:73], v231
	ds_read_b64_tr_b16 v[74:75], v231 offset:512
	ds_read_b64_tr_b16 v[76:77], v231 offset:2048
	ds_read_b64_tr_b16 v[78:79], v231 offset:2560
	ds_read_b64_tr_b16 v[220:221], v231 offset:1024
	ds_read_b64_tr_b16 v[222:223], v231 offset:1536
	ds_read_b64_tr_b16 v[224:225], v231 offset:3072
	ds_read_b64_tr_b16 v[226:227], v231 offset:3584
	s_waitcnt vmcnt(8)
	ds_write_b128 v247, v[188:191]
	ds_write_b128 v247, v[192:195] offset:1024
	ds_write_b128 v247, v[196:199] offset:2048
	ds_write_b128 v247, v[200:203] offset:3072
	ds_read_b128 v[188:191], v248
	ds_read_b128 v[192:195], v249
	ds_read_b128 v[196:199], v250
	ds_read_b128 v[200:203], v251
	ds_write_b128 v112, v[204:207]
	ds_write_b128 v112, v[208:211] offset:1024
	ds_write_b128 v112, v[212:215] offset:2048
	ds_write_b128 v112, v[216:219] offset:3072
	v_mfma_f32_32x32x16_bf16 v[32:47], v[160:163], v[52:55], v[32:47]
	v_mfma_f32_32x32x16_bf16 v[32:47], v[164:167], v[56:59], v[32:47]
	v_mfma_f32_32x32x16_bf16 v[32:47], v[168:171], v[60:63], v[32:47]
	s_nop 11
	v_exp_f32_e32 v32, v32
	v_exp_f32_e32 v33, v33
	v_exp_f32_e32 v34, v34
	v_exp_f32_e32 v35, v35
	v_exp_f32_e32 v36, v36
	v_exp_f32_e32 v37, v37
	v_exp_f32_e32 v38, v38
	v_exp_f32_e32 v39, v39
	v_exp_f32_e32 v40, v40
	v_exp_f32_e32 v41, v41
	v_exp_f32_e32 v42, v42
	v_exp_f32_e32 v43, v43
	v_exp_f32_e32 v44, v44
	v_exp_f32_e32 v45, v45
	v_exp_f32_e32 v46, v46
	v_exp_f32_e32 v47, v47
	v_cvt_pk_bf16_f32 v64, v32, v33
	v_cvt_pk_bf16_f32 v65, v34, v35
	v_cvt_pk_bf16_f32 v66, v36, v37
	v_cvt_pk_bf16_f32 v67, v38, v39
	v_cvt_pk_bf16_f32 v68, v40, v41
	v_cvt_pk_bf16_f32 v69, v42, v43
	v_cvt_pk_bf16_f32 v70, v44, v45
	v_cvt_pk_bf16_f32 v71, v46, v47
	v_pk_add_f32 v[232:233], v[232:233], v[32:33]
	v_pk_add_f32 v[232:233], v[232:233], v[34:35]
	v_pk_add_f32 v[232:233], v[232:233], v[36:37]
	v_pk_add_f32 v[232:233], v[232:233], v[38:39]
	v_pk_add_f32 v[232:233], v[232:233], v[40:41]
	v_pk_add_f32 v[232:233], v[232:233], v[42:43]
	v_pk_add_f32 v[232:233], v[232:233], v[44:45]
	v_pk_add_f32 v[232:233], v[232:233], v[46:47]
	s_waitcnt lgkmcnt(12)
	v_mfma_f32_32x32x16_bf16 v[0:15], v[64:67], v[72:75], v[0:15]
	v_mfma_f32_32x32x16_bf16 v[16:31], v[64:67], v[76:79], v[16:31]
	v_mfma_f32_32x32x16_bf16 v[0:15], v[68:71], v[220:223], v[0:15]
	v_mfma_f32_32x32x16_bf16 v[16:31], v[68:71], v[224:227], v[16:31]
	global_load_dwordx4 v[156:159], v235, s[84:85]
	global_load_dwordx4 v[160:163], v236, s[84:85]
	global_load_dwordx4 v[164:167], v237, s[84:85]
	global_load_dwordx4 v[168:171], v238, s[84:85]
	global_load_dwordx4 v[172:175], v100, s[84:85] offset:768
	global_load_dwordx4 v[176:179], v149, s[84:85] offset:768
	global_load_dwordx4 v[180:183], v100, s[84:85] offset:832
	global_load_dwordx4 v[184:187], v149, s[84:85] offset:832
	s_add_u32 s84, s84, 0x30000
	s_addc_u32 s85, s85, 0
	ds_read2_b32 v[32:33], v115 offset0:34 offset1:35
	ds_read2_b32 v[34:35], v115 offset0:36 offset1:37
	ds_read2_b32 v[36:37], v115 offset0:42 offset1:43
	ds_read2_b32 v[38:39], v115 offset0:44 offset1:45
	ds_read2_b32 v[40:41], v115 offset0:51 offset1:52
	ds_read2_b32 v[42:43], v115 offset0:53 offset1:54
	ds_read2_b32 v[44:45], v115 offset0:59 offset1:60
	ds_read2_b32 v[46:47], v115 offset0:61 offset1:62
	s_waitcnt lgkmcnt(0)
	v_mfma_f32_32x32x16_bf16 v[32:47], v[188:191], v[48:51], v[32:47]
	ds_read_b64_tr_b16 v[72:73], v231
	ds_read_b64_tr_b16 v[74:75], v231 offset:512
	ds_read_b64_tr_b16 v[76:77], v231 offset:2048
	ds_read_b64_tr_b16 v[78:79], v231 offset:2560
	ds_read_b64_tr_b16 v[220:221], v231 offset:1024
	ds_read_b64_tr_b16 v[222:223], v231 offset:1536
	ds_read_b64_tr_b16 v[224:225], v231 offset:3072
	ds_read_b64_tr_b16 v[226:227], v231 offset:3584
	s_waitcnt vmcnt(8)
	ds_write_b128 v247, v[116:119]
	ds_write_b128 v247, v[120:123] offset:1024
	ds_write_b128 v247, v[124:127] offset:2048
	ds_write_b128 v247, v[128:131] offset:3072
	ds_read_b128 v[116:119], v248
	ds_read_b128 v[120:123], v249
	ds_read_b128 v[124:127], v250
	ds_read_b128 v[128:131], v251
	ds_write_b128 v112, v[132:135]
	ds_write_b128 v112, v[136:139] offset:1024
	ds_write_b128 v112, v[140:143] offset:2048
	ds_write_b128 v112, v[144:147] offset:3072
	v_mfma_f32_32x32x16_bf16 v[32:47], v[192:195], v[52:55], v[32:47]
	v_mfma_f32_32x32x16_bf16 v[32:47], v[196:199], v[56:59], v[32:47]
	v_mfma_f32_32x32x16_bf16 v[32:47], v[200:203], v[60:63], v[32:47]
	s_nop 11
	v_exp_f32_e32 v32, v32
	v_exp_f32_e32 v33, v33
	v_exp_f32_e32 v34, v34
	v_exp_f32_e32 v35, v35
	v_exp_f32_e32 v36, v36
	v_exp_f32_e32 v37, v37
	v_exp_f32_e32 v38, v38
	v_exp_f32_e32 v39, v39
	v_exp_f32_e32 v40, v40
	v_exp_f32_e32 v41, v41
	v_exp_f32_e32 v42, v42
	v_exp_f32_e32 v43, v43
	v_exp_f32_e32 v44, v44
	v_exp_f32_e32 v45, v45
	v_exp_f32_e32 v46, v46
	v_exp_f32_e32 v47, v47
	v_cvt_pk_bf16_f32 v64, v32, v33
	v_cvt_pk_bf16_f32 v65, v34, v35
	v_cvt_pk_bf16_f32 v66, v36, v37
	v_cvt_pk_bf16_f32 v67, v38, v39
	v_cvt_pk_bf16_f32 v68, v40, v41
	v_cvt_pk_bf16_f32 v69, v42, v43
	v_cvt_pk_bf16_f32 v70, v44, v45
	v_cvt_pk_bf16_f32 v71, v46, v47
	v_pk_add_f32 v[232:233], v[232:233], v[32:33]
	v_pk_add_f32 v[232:233], v[232:233], v[34:35]
	v_pk_add_f32 v[232:233], v[232:233], v[36:37]
	v_pk_add_f32 v[232:233], v[232:233], v[38:39]
	v_pk_add_f32 v[232:233], v[232:233], v[40:41]
	v_pk_add_f32 v[232:233], v[232:233], v[42:43]
	v_pk_add_f32 v[232:233], v[232:233], v[44:45]
	v_pk_add_f32 v[232:233], v[232:233], v[46:47]
	s_waitcnt lgkmcnt(12)
	v_mfma_f32_32x32x16_bf16 v[0:15], v[64:67], v[72:75], v[0:15]
	v_mfma_f32_32x32x16_bf16 v[16:31], v[64:67], v[76:79], v[16:31]
	v_mfma_f32_32x32x16_bf16 v[0:15], v[68:71], v[220:223], v[0:15]
	v_mfma_f32_32x32x16_bf16 v[16:31], v[68:71], v[224:227], v[16:31]
	global_load_dwordx4 v[188:191], v235, s[84:85]
	global_load_dwordx4 v[192:195], v236, s[84:85]
	global_load_dwordx4 v[196:199], v237, s[84:85]
	global_load_dwordx4 v[200:203], v238, s[84:85]
	global_load_dwordx4 v[204:207], v100, s[84:85] offset:768
	global_load_dwordx4 v[208:211], v149, s[84:85] offset:768
	global_load_dwordx4 v[212:215], v100, s[84:85] offset:832
	global_load_dwordx4 v[216:219], v149, s[84:85] offset:832
	s_add_u32 s84, s84, 0x30000
	s_addc_u32 s85, s85, 0
	ds_read2_b32 v[32:33], v115 offset0:68 offset1:69
	ds_read2_b32 v[34:35], v115 offset0:70 offset1:71
	ds_read2_b32 v[36:37], v115 offset0:76 offset1:77
	ds_read2_b32 v[38:39], v115 offset0:78 offset1:79
	ds_read2_b32 v[40:41], v115 offset0:85 offset1:86
	ds_read2_b32 v[42:43], v115 offset0:87 offset1:88
	ds_read2_b32 v[44:45], v115 offset0:93 offset1:94
	ds_read2_b32 v[46:47], v115 offset0:95 offset1:96
	s_waitcnt lgkmcnt(0)
	v_mfma_f32_32x32x16_bf16 v[32:47], v[116:119], v[48:51], v[32:47]
	ds_read_b64_tr_b16 v[72:73], v231
	ds_read_b64_tr_b16 v[74:75], v231 offset:512
	ds_read_b64_tr_b16 v[76:77], v231 offset:2048
	ds_read_b64_tr_b16 v[78:79], v231 offset:2560
	ds_read_b64_tr_b16 v[220:221], v231 offset:1024
	ds_read_b64_tr_b16 v[222:223], v231 offset:1536
	ds_read_b64_tr_b16 v[224:225], v231 offset:3072
	ds_read_b64_tr_b16 v[226:227], v231 offset:3584
	s_waitcnt vmcnt(8)
	ds_write_b128 v247, v[156:159]
	ds_write_b128 v247, v[160:163] offset:1024
	ds_write_b128 v247, v[164:167] offset:2048
	ds_write_b128 v247, v[168:171] offset:3072
	ds_read_b128 v[156:159], v248
	ds_read_b128 v[160:163], v249
	ds_read_b128 v[164:167], v250
	ds_read_b128 v[168:171], v251
	ds_write_b128 v112, v[172:175]
	ds_write_b128 v112, v[176:179] offset:1024
	ds_write_b128 v112, v[180:183] offset:2048
	ds_write_b128 v112, v[184:187] offset:3072
	v_mfma_f32_32x32x16_bf16 v[32:47], v[120:123], v[52:55], v[32:47]
	v_mfma_f32_32x32x16_bf16 v[32:47], v[124:127], v[56:59], v[32:47]
	v_mfma_f32_32x32x16_bf16 v[32:47], v[128:131], v[60:63], v[32:47]
	s_nop 11
	v_exp_f32_e32 v32, v32
	v_exp_f32_e32 v33, v33
	v_exp_f32_e32 v34, v34
	v_exp_f32_e32 v35, v35
	v_exp_f32_e32 v36, v36
	v_exp_f32_e32 v37, v37
	v_exp_f32_e32 v38, v38
	v_exp_f32_e32 v39, v39
	v_exp_f32_e32 v40, v40
	v_exp_f32_e32 v41, v41
	v_exp_f32_e32 v42, v42
	v_exp_f32_e32 v43, v43
	v_exp_f32_e32 v44, v44
	v_exp_f32_e32 v45, v45
	v_exp_f32_e32 v46, v46
	v_exp_f32_e32 v47, v47
	v_cvt_pk_bf16_f32 v64, v32, v33
	v_cvt_pk_bf16_f32 v65, v34, v35
	v_cvt_pk_bf16_f32 v66, v36, v37
	v_cvt_pk_bf16_f32 v67, v38, v39
	v_cvt_pk_bf16_f32 v68, v40, v41
	v_cvt_pk_bf16_f32 v69, v42, v43
	v_cvt_pk_bf16_f32 v70, v44, v45
	v_cvt_pk_bf16_f32 v71, v46, v47
	v_pk_add_f32 v[232:233], v[232:233], v[32:33]
	v_pk_add_f32 v[232:233], v[232:233], v[34:35]
	v_pk_add_f32 v[232:233], v[232:233], v[36:37]
	v_pk_add_f32 v[232:233], v[232:233], v[38:39]
	v_pk_add_f32 v[232:233], v[232:233], v[40:41]
	v_pk_add_f32 v[232:233], v[232:233], v[42:43]
	v_pk_add_f32 v[232:233], v[232:233], v[44:45]
	v_pk_add_f32 v[232:233], v[232:233], v[46:47]
	s_waitcnt lgkmcnt(12)
	v_mfma_f32_32x32x16_bf16 v[0:15], v[64:67], v[72:75], v[0:15]
	v_mfma_f32_32x32x16_bf16 v[16:31], v[64:67], v[76:79], v[16:31]
	v_mfma_f32_32x32x16_bf16 v[0:15], v[68:71], v[220:223], v[0:15]
	v_mfma_f32_32x32x16_bf16 v[16:31], v[68:71], v[224:227], v[16:31]
	global_load_dwordx4 v[116:119], v235, s[84:85]
	global_load_dwordx4 v[120:123], v236, s[84:85]
	global_load_dwordx4 v[124:127], v237, s[84:85]
	global_load_dwordx4 v[128:131], v238, s[84:85]
	global_load_dwordx4 v[132:135], v100, s[84:85] offset:768
	global_load_dwordx4 v[136:139], v149, s[84:85] offset:768
	global_load_dwordx4 v[140:143], v100, s[84:85] offset:832
	global_load_dwordx4 v[144:147], v149, s[84:85] offset:832
	s_add_u32 s84, s84, 0x30000
	s_addc_u32 s85, s85, 0
	ds_read2_b32 v[32:33], v115 offset0:102 offset1:103
	ds_read2_b32 v[34:35], v115 offset0:104 offset1:105
	ds_read2_b32 v[36:37], v115 offset0:110 offset1:111
	ds_read2_b32 v[38:39], v115 offset0:112 offset1:113
	ds_read2_b32 v[40:41], v115 offset0:119 offset1:120
	ds_read2_b32 v[42:43], v115 offset0:121 offset1:122
	ds_read2_b32 v[44:45], v115 offset0:127 offset1:128
	ds_read2_b32 v[46:47], v115 offset0:129 offset1:130
	s_waitcnt lgkmcnt(0)
	v_mfma_f32_32x32x16_bf16 v[32:47], v[156:159], v[48:51], v[32:47]
	ds_read_b64_tr_b16 v[72:73], v231
	ds_read_b64_tr_b16 v[74:75], v231 offset:512
	ds_read_b64_tr_b16 v[76:77], v231 offset:2048
	ds_read_b64_tr_b16 v[78:79], v231 offset:2560
	ds_read_b64_tr_b16 v[220:221], v231 offset:1024
	ds_read_b64_tr_b16 v[222:223], v231 offset:1536
	ds_read_b64_tr_b16 v[224:225], v231 offset:3072
	ds_read_b64_tr_b16 v[226:227], v231 offset:3584
	s_waitcnt vmcnt(8)
	ds_write_b128 v247, v[188:191]
	ds_write_b128 v247, v[192:195] offset:1024
	ds_write_b128 v247, v[196:199] offset:2048
	ds_write_b128 v247, v[200:203] offset:3072
	ds_read_b128 v[188:191], v248
	ds_read_b128 v[192:195], v249
	ds_read_b128 v[196:199], v250
	ds_read_b128 v[200:203], v251
	ds_write_b128 v112, v[204:207]
	ds_write_b128 v112, v[208:211] offset:1024
	ds_write_b128 v112, v[212:215] offset:2048
	ds_write_b128 v112, v[216:219] offset:3072
	v_mfma_f32_32x32x16_bf16 v[32:47], v[160:163], v[52:55], v[32:47]
	v_mfma_f32_32x32x16_bf16 v[32:47], v[164:167], v[56:59], v[32:47]
	v_mfma_f32_32x32x16_bf16 v[32:47], v[168:171], v[60:63], v[32:47]
	s_nop 11
	v_exp_f32_e32 v32, v32
	v_exp_f32_e32 v33, v33
	v_exp_f32_e32 v34, v34
	v_exp_f32_e32 v35, v35
	v_exp_f32_e32 v36, v36
	v_exp_f32_e32 v37, v37
	v_exp_f32_e32 v38, v38
	v_exp_f32_e32 v39, v39
	v_exp_f32_e32 v40, v40
	v_exp_f32_e32 v41, v41
	v_exp_f32_e32 v42, v42
	v_exp_f32_e32 v43, v43
	v_exp_f32_e32 v44, v44
	v_exp_f32_e32 v45, v45
	v_exp_f32_e32 v46, v46
	v_exp_f32_e32 v47, v47
	v_cvt_pk_bf16_f32 v64, v32, v33
	v_cvt_pk_bf16_f32 v65, v34, v35
	v_cvt_pk_bf16_f32 v66, v36, v37
	v_cvt_pk_bf16_f32 v67, v38, v39
	v_cvt_pk_bf16_f32 v68, v40, v41
	v_cvt_pk_bf16_f32 v69, v42, v43
	v_cvt_pk_bf16_f32 v70, v44, v45
	v_cvt_pk_bf16_f32 v71, v46, v47
	v_pk_add_f32 v[232:233], v[232:233], v[32:33]
	v_pk_add_f32 v[232:233], v[232:233], v[34:35]
	v_pk_add_f32 v[232:233], v[232:233], v[36:37]
	v_pk_add_f32 v[232:233], v[232:233], v[38:39]
	v_pk_add_f32 v[232:233], v[232:233], v[40:41]
	v_pk_add_f32 v[232:233], v[232:233], v[42:43]
	v_pk_add_f32 v[232:233], v[232:233], v[44:45]
	v_pk_add_f32 v[232:233], v[232:233], v[46:47]
	s_waitcnt lgkmcnt(12)
	v_mfma_f32_32x32x16_bf16 v[0:15], v[64:67], v[72:75], v[0:15]
	v_mfma_f32_32x32x16_bf16 v[16:31], v[64:67], v[76:79], v[16:31]
	v_mfma_f32_32x32x16_bf16 v[0:15], v[68:71], v[220:223], v[0:15]
	v_mfma_f32_32x32x16_bf16 v[16:31], v[68:71], v[224:227], v[16:31]
	global_load_dwordx4 v[156:159], v235, s[84:85]
	global_load_dwordx4 v[160:163], v236, s[84:85]
	global_load_dwordx4 v[164:167], v237, s[84:85]
	global_load_dwordx4 v[168:171], v238, s[84:85]
	global_load_dwordx4 v[172:175], v100, s[84:85] offset:768
	global_load_dwordx4 v[176:179], v149, s[84:85] offset:768
	global_load_dwordx4 v[180:183], v100, s[84:85] offset:832
	global_load_dwordx4 v[184:187], v149, s[84:85] offset:832
	s_add_u32 s84, s84, 0x30000
	s_addc_u32 s85, s85, 0
	ds_read2_b32 v[32:33], v115 offset0:136 offset1:137
	ds_read2_b32 v[34:35], v115 offset0:138 offset1:139
	ds_read2_b32 v[36:37], v115 offset0:144 offset1:145
	ds_read2_b32 v[38:39], v115 offset0:146 offset1:147
	ds_read2_b32 v[40:41], v115 offset0:153 offset1:154
	ds_read2_b32 v[42:43], v115 offset0:155 offset1:156
	ds_read2_b32 v[44:45], v115 offset0:161 offset1:162
	ds_read2_b32 v[46:47], v115 offset0:163 offset1:164
	s_waitcnt lgkmcnt(0)
	v_mfma_f32_32x32x16_bf16 v[32:47], v[188:191], v[48:51], v[32:47]
	ds_read_b64_tr_b16 v[72:73], v231
	ds_read_b64_tr_b16 v[74:75], v231 offset:512
	ds_read_b64_tr_b16 v[76:77], v231 offset:2048
	ds_read_b64_tr_b16 v[78:79], v231 offset:2560
	ds_read_b64_tr_b16 v[220:221], v231 offset:1024
	ds_read_b64_tr_b16 v[222:223], v231 offset:1536
	ds_read_b64_tr_b16 v[224:225], v231 offset:3072
	ds_read_b64_tr_b16 v[226:227], v231 offset:3584
	s_waitcnt vmcnt(8)
	ds_write_b128 v247, v[116:119]
	ds_write_b128 v247, v[120:123] offset:1024
	ds_write_b128 v247, v[124:127] offset:2048
	ds_write_b128 v247, v[128:131] offset:3072
	ds_read_b128 v[116:119], v248
	ds_read_b128 v[120:123], v249
	ds_read_b128 v[124:127], v250
	ds_read_b128 v[128:131], v251
	ds_write_b128 v112, v[132:135]
	ds_write_b128 v112, v[136:139] offset:1024
	ds_write_b128 v112, v[140:143] offset:2048
	ds_write_b128 v112, v[144:147] offset:3072
	v_mfma_f32_32x32x16_bf16 v[32:47], v[192:195], v[52:55], v[32:47]
	v_mfma_f32_32x32x16_bf16 v[32:47], v[196:199], v[56:59], v[32:47]
	v_mfma_f32_32x32x16_bf16 v[32:47], v[200:203], v[60:63], v[32:47]
	s_nop 11
	v_exp_f32_e32 v32, v32
	v_exp_f32_e32 v33, v33
	v_exp_f32_e32 v34, v34
	v_exp_f32_e32 v35, v35
	v_exp_f32_e32 v36, v36
	v_exp_f32_e32 v37, v37
	v_exp_f32_e32 v38, v38
	v_exp_f32_e32 v39, v39
	v_exp_f32_e32 v40, v40
	v_exp_f32_e32 v41, v41
	v_exp_f32_e32 v42, v42
	v_exp_f32_e32 v43, v43
	v_exp_f32_e32 v44, v44
	v_exp_f32_e32 v45, v45
	v_exp_f32_e32 v46, v46
	v_exp_f32_e32 v47, v47
	v_cvt_pk_bf16_f32 v64, v32, v33
	v_cvt_pk_bf16_f32 v65, v34, v35
	v_cvt_pk_bf16_f32 v66, v36, v37
	v_cvt_pk_bf16_f32 v67, v38, v39
	v_cvt_pk_bf16_f32 v68, v40, v41
	v_cvt_pk_bf16_f32 v69, v42, v43
	v_cvt_pk_bf16_f32 v70, v44, v45
	v_cvt_pk_bf16_f32 v71, v46, v47
	v_pk_add_f32 v[232:233], v[232:233], v[32:33]
	v_pk_add_f32 v[232:233], v[232:233], v[34:35]
	v_pk_add_f32 v[232:233], v[232:233], v[36:37]
	v_pk_add_f32 v[232:233], v[232:233], v[38:39]
	v_pk_add_f32 v[232:233], v[232:233], v[40:41]
	v_pk_add_f32 v[232:233], v[232:233], v[42:43]
	v_pk_add_f32 v[232:233], v[232:233], v[44:45]
	v_pk_add_f32 v[232:233], v[232:233], v[46:47]
	s_waitcnt lgkmcnt(12)
	v_mfma_f32_32x32x16_bf16 v[0:15], v[64:67], v[72:75], v[0:15]
	v_mfma_f32_32x32x16_bf16 v[16:31], v[64:67], v[76:79], v[16:31]
	v_mfma_f32_32x32x16_bf16 v[0:15], v[68:71], v[220:223], v[0:15]
	v_mfma_f32_32x32x16_bf16 v[16:31], v[68:71], v[224:227], v[16:31]
	global_load_dwordx4 v[188:191], v235, s[84:85]
	global_load_dwordx4 v[192:195], v236, s[84:85]
	global_load_dwordx4 v[196:199], v237, s[84:85]
	global_load_dwordx4 v[200:203], v238, s[84:85]
	global_load_dwordx4 v[204:207], v100, s[84:85] offset:768
	global_load_dwordx4 v[208:211], v149, s[84:85] offset:768
	global_load_dwordx4 v[212:215], v100, s[84:85] offset:832
	global_load_dwordx4 v[216:219], v149, s[84:85] offset:832
	s_add_u32 s84, s84, 0x30000
	s_addc_u32 s85, s85, 0
	ds_read2_b32 v[32:33], v115 offset0:170 offset1:171
	ds_read2_b32 v[34:35], v115 offset0:172 offset1:173
	ds_read2_b32 v[36:37], v115 offset0:178 offset1:179
	ds_read2_b32 v[38:39], v115 offset0:180 offset1:181
	ds_read2_b32 v[40:41], v115 offset0:187 offset1:188
	ds_read2_b32 v[42:43], v115 offset0:189 offset1:190
	ds_read2_b32 v[44:45], v115 offset0:195 offset1:196
	ds_read2_b32 v[46:47], v115 offset0:197 offset1:198
	s_waitcnt lgkmcnt(0)
	v_mfma_f32_32x32x16_bf16 v[32:47], v[116:119], v[48:51], v[32:47]
	ds_read_b64_tr_b16 v[72:73], v231
	ds_read_b64_tr_b16 v[74:75], v231 offset:512
	ds_read_b64_tr_b16 v[76:77], v231 offset:2048
	ds_read_b64_tr_b16 v[78:79], v231 offset:2560
	ds_read_b64_tr_b16 v[220:221], v231 offset:1024
	ds_read_b64_tr_b16 v[222:223], v231 offset:1536
	ds_read_b64_tr_b16 v[224:225], v231 offset:3072
	ds_read_b64_tr_b16 v[226:227], v231 offset:3584
	s_waitcnt vmcnt(8)
	ds_write_b128 v247, v[156:159]
	ds_write_b128 v247, v[160:163] offset:1024
	ds_write_b128 v247, v[164:167] offset:2048
	ds_write_b128 v247, v[168:171] offset:3072
	ds_read_b128 v[156:159], v248
	ds_read_b128 v[160:163], v249
	ds_read_b128 v[164:167], v250
	ds_read_b128 v[168:171], v251
	ds_write_b128 v112, v[172:175]
	ds_write_b128 v112, v[176:179] offset:1024
	ds_write_b128 v112, v[180:183] offset:2048
	ds_write_b128 v112, v[184:187] offset:3072
	v_mfma_f32_32x32x16_bf16 v[32:47], v[120:123], v[52:55], v[32:47]
	v_mfma_f32_32x32x16_bf16 v[32:47], v[124:127], v[56:59], v[32:47]
	v_mfma_f32_32x32x16_bf16 v[32:47], v[128:131], v[60:63], v[32:47]
	s_nop 11
	v_exp_f32_e32 v32, v32
	v_exp_f32_e32 v33, v33
	v_exp_f32_e32 v34, v34
	v_exp_f32_e32 v35, v35
	v_exp_f32_e32 v36, v36
	v_exp_f32_e32 v37, v37
	v_exp_f32_e32 v38, v38
	v_exp_f32_e32 v39, v39
	v_exp_f32_e32 v40, v40
	v_exp_f32_e32 v41, v41
	v_exp_f32_e32 v42, v42
	v_exp_f32_e32 v43, v43
	v_exp_f32_e32 v44, v44
	v_exp_f32_e32 v45, v45
	v_exp_f32_e32 v46, v46
	v_exp_f32_e32 v47, v47
	v_cvt_pk_bf16_f32 v64, v32, v33
	v_cvt_pk_bf16_f32 v65, v34, v35
	v_cvt_pk_bf16_f32 v66, v36, v37
	v_cvt_pk_bf16_f32 v67, v38, v39
	v_cvt_pk_bf16_f32 v68, v40, v41
	v_cvt_pk_bf16_f32 v69, v42, v43
	v_cvt_pk_bf16_f32 v70, v44, v45
	v_cvt_pk_bf16_f32 v71, v46, v47
	v_pk_add_f32 v[232:233], v[232:233], v[32:33]
	v_pk_add_f32 v[232:233], v[232:233], v[34:35]
	v_pk_add_f32 v[232:233], v[232:233], v[36:37]
	v_pk_add_f32 v[232:233], v[232:233], v[38:39]
	v_pk_add_f32 v[232:233], v[232:233], v[40:41]
	v_pk_add_f32 v[232:233], v[232:233], v[42:43]
	v_pk_add_f32 v[232:233], v[232:233], v[44:45]
	v_pk_add_f32 v[232:233], v[232:233], v[46:47]
	s_waitcnt lgkmcnt(12)
	v_mfma_f32_32x32x16_bf16 v[0:15], v[64:67], v[72:75], v[0:15]
	v_mfma_f32_32x32x16_bf16 v[16:31], v[64:67], v[76:79], v[16:31]
	v_mfma_f32_32x32x16_bf16 v[0:15], v[68:71], v[220:223], v[0:15]
	v_mfma_f32_32x32x16_bf16 v[16:31], v[68:71], v[224:227], v[16:31]
	global_load_dwordx4 v[116:119], v235, s[84:85]
	global_load_dwordx4 v[120:123], v236, s[84:85]
	global_load_dwordx4 v[124:127], v237, s[84:85]
	global_load_dwordx4 v[128:131], v238, s[84:85]
	global_load_dwordx4 v[132:135], v100, s[84:85] offset:768
	global_load_dwordx4 v[136:139], v149, s[84:85] offset:768
	global_load_dwordx4 v[140:143], v100, s[84:85] offset:832
	global_load_dwordx4 v[144:147], v149, s[84:85] offset:832
	s_add_u32 s84, s84, 0x30000
	s_addc_u32 s85, s85, 0
	ds_read2_b32 v[32:33], v115 offset0:204 offset1:205
	ds_read2_b32 v[34:35], v115 offset0:206 offset1:207
	ds_read2_b32 v[36:37], v115 offset0:212 offset1:213
	ds_read2_b32 v[38:39], v115 offset0:214 offset1:215
	ds_read2_b32 v[40:41], v115 offset0:221 offset1:222
	ds_read2_b32 v[42:43], v115 offset0:223 offset1:224
	ds_read2_b32 v[44:45], v115 offset0:229 offset1:230
	ds_read2_b32 v[46:47], v115 offset0:231 offset1:232
	s_waitcnt lgkmcnt(0)
	v_mfma_f32_32x32x16_bf16 v[32:47], v[156:159], v[48:51], v[32:47]
	ds_read_b64_tr_b16 v[72:73], v231
	ds_read_b64_tr_b16 v[74:75], v231 offset:512
	ds_read_b64_tr_b16 v[76:77], v231 offset:2048
	ds_read_b64_tr_b16 v[78:79], v231 offset:2560
	ds_read_b64_tr_b16 v[220:221], v231 offset:1024
	ds_read_b64_tr_b16 v[222:223], v231 offset:1536
	ds_read_b64_tr_b16 v[224:225], v231 offset:3072
	ds_read_b64_tr_b16 v[226:227], v231 offset:3584
	s_waitcnt vmcnt(8)
	ds_write_b128 v247, v[188:191]
	ds_write_b128 v247, v[192:195] offset:1024
	ds_write_b128 v247, v[196:199] offset:2048
	ds_write_b128 v247, v[200:203] offset:3072
	ds_read_b128 v[188:191], v248
	ds_read_b128 v[192:195], v249
	ds_read_b128 v[196:199], v250
	ds_read_b128 v[200:203], v251
	ds_write_b128 v112, v[204:207]
	ds_write_b128 v112, v[208:211] offset:1024
	ds_write_b128 v112, v[212:215] offset:2048
	ds_write_b128 v112, v[216:219] offset:3072
	v_mfma_f32_32x32x16_bf16 v[32:47], v[160:163], v[52:55], v[32:47]
	v_mfma_f32_32x32x16_bf16 v[32:47], v[164:167], v[56:59], v[32:47]
	v_mfma_f32_32x32x16_bf16 v[32:47], v[168:171], v[60:63], v[32:47]
	s_nop 11
	v_exp_f32_e32 v32, v32
	v_exp_f32_e32 v33, v33
	v_exp_f32_e32 v34, v34
	v_exp_f32_e32 v35, v35
	v_exp_f32_e32 v36, v36
	v_exp_f32_e32 v37, v37
	v_exp_f32_e32 v38, v38
	v_exp_f32_e32 v39, v39
	v_exp_f32_e32 v40, v40
	v_exp_f32_e32 v41, v41
	v_exp_f32_e32 v42, v42
	v_exp_f32_e32 v43, v43
	v_exp_f32_e32 v44, v44
	v_exp_f32_e32 v45, v45
	v_exp_f32_e32 v46, v46
	v_exp_f32_e32 v47, v47
	v_cvt_pk_bf16_f32 v64, v32, v33
	v_cvt_pk_bf16_f32 v65, v34, v35
	v_cvt_pk_bf16_f32 v66, v36, v37
	v_cvt_pk_bf16_f32 v67, v38, v39
	v_cvt_pk_bf16_f32 v68, v40, v41
	v_cvt_pk_bf16_f32 v69, v42, v43
	v_cvt_pk_bf16_f32 v70, v44, v45
	v_cvt_pk_bf16_f32 v71, v46, v47
	v_pk_add_f32 v[232:233], v[232:233], v[32:33]
	v_pk_add_f32 v[232:233], v[232:233], v[34:35]
	v_pk_add_f32 v[232:233], v[232:233], v[36:37]
	v_pk_add_f32 v[232:233], v[232:233], v[38:39]
	v_pk_add_f32 v[232:233], v[232:233], v[40:41]
	v_pk_add_f32 v[232:233], v[232:233], v[42:43]
	v_pk_add_f32 v[232:233], v[232:233], v[44:45]
	v_pk_add_f32 v[232:233], v[232:233], v[46:47]
	s_waitcnt lgkmcnt(12)
	v_mfma_f32_32x32x16_bf16 v[0:15], v[64:67], v[72:75], v[0:15]
	v_mfma_f32_32x32x16_bf16 v[16:31], v[64:67], v[76:79], v[16:31]
	v_mfma_f32_32x32x16_bf16 v[0:15], v[68:71], v[220:223], v[0:15]
	v_mfma_f32_32x32x16_bf16 v[16:31], v[68:71], v[224:227], v[16:31]
	global_load_dwordx4 v[156:159], v235, s[84:85]
	global_load_dwordx4 v[160:163], v236, s[84:85]
	global_load_dwordx4 v[164:167], v237, s[84:85]
	global_load_dwordx4 v[168:171], v238, s[84:85]
	global_load_dwordx4 v[172:175], v100, s[84:85] offset:768
	global_load_dwordx4 v[176:179], v149, s[84:85] offset:768
	global_load_dwordx4 v[180:183], v100, s[84:85] offset:832
	global_load_dwordx4 v[184:187], v149, s[84:85] offset:832
	s_add_u32 s84, s84, 0x30000
	s_addc_u32 s85, s85, 0
	v_add_u32_e32 v115, 952, v115
	ds_read2_b32 v[32:33], v115 offset0:0 offset1:1
	ds_read2_b32 v[34:35], v115 offset0:2 offset1:3
	ds_read2_b32 v[36:37], v115 offset0:8 offset1:9
	ds_read2_b32 v[38:39], v115 offset0:10 offset1:11
	ds_read2_b32 v[40:41], v115 offset0:17 offset1:18
	ds_read2_b32 v[42:43], v115 offset0:19 offset1:20
	ds_read2_b32 v[44:45], v115 offset0:25 offset1:26
	ds_read2_b32 v[46:47], v115 offset0:27 offset1:28
	s_waitcnt lgkmcnt(0)
	v_mfma_f32_32x32x16_bf16 v[32:47], v[188:191], v[48:51], v[32:47]
	ds_read_b64_tr_b16 v[72:73], v231
	ds_read_b64_tr_b16 v[74:75], v231 offset:512
	ds_read_b64_tr_b16 v[76:77], v231 offset:2048
	ds_read_b64_tr_b16 v[78:79], v231 offset:2560
	ds_read_b64_tr_b16 v[220:221], v231 offset:1024
	ds_read_b64_tr_b16 v[222:223], v231 offset:1536
	ds_read_b64_tr_b16 v[224:225], v231 offset:3072
	ds_read_b64_tr_b16 v[226:227], v231 offset:3584
	s_waitcnt vmcnt(8)
	ds_write_b128 v247, v[116:119]
	ds_write_b128 v247, v[120:123] offset:1024
	ds_write_b128 v247, v[124:127] offset:2048
	ds_write_b128 v247, v[128:131] offset:3072
	ds_read_b128 v[116:119], v248
	ds_read_b128 v[120:123], v249
	ds_read_b128 v[124:127], v250
	ds_read_b128 v[128:131], v251
	ds_write_b128 v112, v[132:135]
	ds_write_b128 v112, v[136:139] offset:1024
	ds_write_b128 v112, v[140:143] offset:2048
	ds_write_b128 v112, v[144:147] offset:3072
	v_mfma_f32_32x32x16_bf16 v[32:47], v[192:195], v[52:55], v[32:47]
	v_mfma_f32_32x32x16_bf16 v[32:47], v[196:199], v[56:59], v[32:47]
	v_mfma_f32_32x32x16_bf16 v[32:47], v[200:203], v[60:63], v[32:47]
	s_nop 11
	v_exp_f32_e32 v32, v32
	v_exp_f32_e32 v33, v33
	v_exp_f32_e32 v34, v34
	v_exp_f32_e32 v35, v35
	v_exp_f32_e32 v36, v36
	v_exp_f32_e32 v37, v37
	v_exp_f32_e32 v38, v38
	v_exp_f32_e32 v39, v39
	v_exp_f32_e32 v40, v40
	v_exp_f32_e32 v41, v41
	v_exp_f32_e32 v42, v42
	v_exp_f32_e32 v43, v43
	v_exp_f32_e32 v44, v44
	v_exp_f32_e32 v45, v45
	v_exp_f32_e32 v46, v46
	v_exp_f32_e32 v47, v47
	v_cvt_pk_bf16_f32 v64, v32, v33
	v_cvt_pk_bf16_f32 v65, v34, v35
	v_cvt_pk_bf16_f32 v66, v36, v37
	v_cvt_pk_bf16_f32 v67, v38, v39
	v_cvt_pk_bf16_f32 v68, v40, v41
	v_cvt_pk_bf16_f32 v69, v42, v43
	v_cvt_pk_bf16_f32 v70, v44, v45
	v_cvt_pk_bf16_f32 v71, v46, v47
	v_pk_add_f32 v[232:233], v[232:233], v[32:33]
	v_pk_add_f32 v[232:233], v[232:233], v[34:35]
	v_pk_add_f32 v[232:233], v[232:233], v[36:37]
	v_pk_add_f32 v[232:233], v[232:233], v[38:39]
	v_pk_add_f32 v[232:233], v[232:233], v[40:41]
	v_pk_add_f32 v[232:233], v[232:233], v[42:43]
	v_pk_add_f32 v[232:233], v[232:233], v[44:45]
	v_pk_add_f32 v[232:233], v[232:233], v[46:47]
	s_waitcnt lgkmcnt(12)
	v_mfma_f32_32x32x16_bf16 v[0:15], v[64:67], v[72:75], v[0:15]
	v_mfma_f32_32x32x16_bf16 v[16:31], v[64:67], v[76:79], v[16:31]
	v_mfma_f32_32x32x16_bf16 v[0:15], v[68:71], v[220:223], v[0:15]
	v_mfma_f32_32x32x16_bf16 v[16:31], v[68:71], v[224:227], v[16:31]
	global_load_dwordx4 v[188:191], v235, s[84:85]
	global_load_dwordx4 v[192:195], v236, s[84:85]
	global_load_dwordx4 v[196:199], v237, s[84:85]
	global_load_dwordx4 v[200:203], v238, s[84:85]
	global_load_dwordx4 v[204:207], v100, s[84:85] offset:768
	global_load_dwordx4 v[208:211], v149, s[84:85] offset:768
	global_load_dwordx4 v[212:215], v100, s[84:85] offset:832
	global_load_dwordx4 v[216:219], v149, s[84:85] offset:832
	s_add_u32 s84, s84, 0x30000
	s_addc_u32 s85, s85, 0
	ds_read2_b32 v[32:33], v115 offset0:34 offset1:35
	ds_read2_b32 v[34:35], v115 offset0:36 offset1:37
	ds_read2_b32 v[36:37], v115 offset0:42 offset1:43
	ds_read2_b32 v[38:39], v115 offset0:44 offset1:45
	ds_read2_b32 v[40:41], v115 offset0:51 offset1:52
	ds_read2_b32 v[42:43], v115 offset0:53 offset1:54
	ds_read2_b32 v[44:45], v115 offset0:59 offset1:60
	ds_read2_b32 v[46:47], v115 offset0:61 offset1:62
	s_waitcnt lgkmcnt(0)
	v_mfma_f32_32x32x16_bf16 v[32:47], v[116:119], v[48:51], v[32:47]
	ds_read_b64_tr_b16 v[72:73], v231
	ds_read_b64_tr_b16 v[74:75], v231 offset:512
	ds_read_b64_tr_b16 v[76:77], v231 offset:2048
	ds_read_b64_tr_b16 v[78:79], v231 offset:2560
	ds_read_b64_tr_b16 v[220:221], v231 offset:1024
	ds_read_b64_tr_b16 v[222:223], v231 offset:1536
	ds_read_b64_tr_b16 v[224:225], v231 offset:3072
	ds_read_b64_tr_b16 v[226:227], v231 offset:3584
	s_waitcnt vmcnt(8)
	ds_write_b128 v247, v[156:159]
	ds_write_b128 v247, v[160:163] offset:1024
	ds_write_b128 v247, v[164:167] offset:2048
	ds_write_b128 v247, v[168:171] offset:3072
	ds_read_b128 v[156:159], v248
	ds_read_b128 v[160:163], v249
	ds_read_b128 v[164:167], v250
	ds_read_b128 v[168:171], v251
	ds_write_b128 v112, v[172:175]
	ds_write_b128 v112, v[176:179] offset:1024
	ds_write_b128 v112, v[180:183] offset:2048
	ds_write_b128 v112, v[184:187] offset:3072
	v_mfma_f32_32x32x16_bf16 v[32:47], v[120:123], v[52:55], v[32:47]
	v_mfma_f32_32x32x16_bf16 v[32:47], v[124:127], v[56:59], v[32:47]
	v_mfma_f32_32x32x16_bf16 v[32:47], v[128:131], v[60:63], v[32:47]
	s_nop 11
	v_exp_f32_e32 v32, v32
	v_exp_f32_e32 v33, v33
	v_exp_f32_e32 v34, v34
	v_exp_f32_e32 v35, v35
	v_exp_f32_e32 v36, v36
	v_exp_f32_e32 v37, v37
	v_exp_f32_e32 v38, v38
	v_exp_f32_e32 v39, v39
	v_exp_f32_e32 v40, v40
	v_exp_f32_e32 v41, v41
	v_exp_f32_e32 v42, v42
	v_exp_f32_e32 v43, v43
	v_exp_f32_e32 v44, v44
	v_exp_f32_e32 v45, v45
	v_exp_f32_e32 v46, v46
	v_exp_f32_e32 v47, v47
	v_cvt_pk_bf16_f32 v64, v32, v33
	v_cvt_pk_bf16_f32 v65, v34, v35
	v_cvt_pk_bf16_f32 v66, v36, v37
	v_cvt_pk_bf16_f32 v67, v38, v39
	v_cvt_pk_bf16_f32 v68, v40, v41
	v_cvt_pk_bf16_f32 v69, v42, v43
	v_cvt_pk_bf16_f32 v70, v44, v45
	v_cvt_pk_bf16_f32 v71, v46, v47
	v_pk_add_f32 v[232:233], v[232:233], v[32:33]
	v_pk_add_f32 v[232:233], v[232:233], v[34:35]
	v_pk_add_f32 v[232:233], v[232:233], v[36:37]
	v_pk_add_f32 v[232:233], v[232:233], v[38:39]
	v_pk_add_f32 v[232:233], v[232:233], v[40:41]
	v_pk_add_f32 v[232:233], v[232:233], v[42:43]
	v_pk_add_f32 v[232:233], v[232:233], v[44:45]
	v_pk_add_f32 v[232:233], v[232:233], v[46:47]
	s_waitcnt lgkmcnt(12)
	v_mfma_f32_32x32x16_bf16 v[0:15], v[64:67], v[72:75], v[0:15]
	v_mfma_f32_32x32x16_bf16 v[16:31], v[64:67], v[76:79], v[16:31]
	v_mfma_f32_32x32x16_bf16 v[0:15], v[68:71], v[220:223], v[0:15]
	v_mfma_f32_32x32x16_bf16 v[16:31], v[68:71], v[224:227], v[16:31]
	global_load_dwordx4 v[116:119], v235, s[84:85]
	global_load_dwordx4 v[120:123], v236, s[84:85]
	global_load_dwordx4 v[124:127], v237, s[84:85]
	global_load_dwordx4 v[128:131], v238, s[84:85]
	global_load_dwordx4 v[132:135], v100, s[84:85] offset:768
	global_load_dwordx4 v[136:139], v149, s[84:85] offset:768
	global_load_dwordx4 v[140:143], v100, s[84:85] offset:832
	global_load_dwordx4 v[144:147], v149, s[84:85] offset:832
	s_add_u32 s84, s84, 0x30000
	s_addc_u32 s85, s85, 0
	ds_read2_b32 v[32:33], v115 offset0:68 offset1:69
	ds_read2_b32 v[34:35], v115 offset0:70 offset1:71
	ds_read2_b32 v[36:37], v115 offset0:76 offset1:77
	ds_read2_b32 v[38:39], v115 offset0:78 offset1:79
	ds_read2_b32 v[40:41], v115 offset0:85 offset1:86
	ds_read2_b32 v[42:43], v115 offset0:87 offset1:88
	ds_read2_b32 v[44:45], v115 offset0:93 offset1:94
	ds_read2_b32 v[46:47], v115 offset0:95 offset1:96
	s_waitcnt lgkmcnt(0)
	v_mfma_f32_32x32x16_bf16 v[32:47], v[156:159], v[48:51], v[32:47]
	ds_read_b64_tr_b16 v[72:73], v231
	ds_read_b64_tr_b16 v[74:75], v231 offset:512
	ds_read_b64_tr_b16 v[76:77], v231 offset:2048
	ds_read_b64_tr_b16 v[78:79], v231 offset:2560
	ds_read_b64_tr_b16 v[220:221], v231 offset:1024
	ds_read_b64_tr_b16 v[222:223], v231 offset:1536
	ds_read_b64_tr_b16 v[224:225], v231 offset:3072
	ds_read_b64_tr_b16 v[226:227], v231 offset:3584
	s_waitcnt vmcnt(8)
	ds_write_b128 v247, v[188:191]
	ds_write_b128 v247, v[192:195] offset:1024
	ds_write_b128 v247, v[196:199] offset:2048
	ds_write_b128 v247, v[200:203] offset:3072
	ds_read_b128 v[188:191], v248
	ds_read_b128 v[192:195], v249
	ds_read_b128 v[196:199], v250
	ds_read_b128 v[200:203], v251
	ds_write_b128 v112, v[204:207]
	ds_write_b128 v112, v[208:211] offset:1024
	ds_write_b128 v112, v[212:215] offset:2048
	ds_write_b128 v112, v[216:219] offset:3072
	v_mfma_f32_32x32x16_bf16 v[32:47], v[160:163], v[52:55], v[32:47]
	v_mfma_f32_32x32x16_bf16 v[32:47], v[164:167], v[56:59], v[32:47]
	v_mfma_f32_32x32x16_bf16 v[32:47], v[168:171], v[60:63], v[32:47]
	s_nop 11
	v_exp_f32_e32 v32, v32
	v_exp_f32_e32 v33, v33
	v_exp_f32_e32 v34, v34
	v_exp_f32_e32 v35, v35
	v_exp_f32_e32 v36, v36
	v_exp_f32_e32 v37, v37
	v_exp_f32_e32 v38, v38
	v_exp_f32_e32 v39, v39
	v_exp_f32_e32 v40, v40
	v_exp_f32_e32 v41, v41
	v_exp_f32_e32 v42, v42
	v_exp_f32_e32 v43, v43
	v_exp_f32_e32 v44, v44
	v_exp_f32_e32 v45, v45
	v_exp_f32_e32 v46, v46
	v_exp_f32_e32 v47, v47
	v_cvt_pk_bf16_f32 v64, v32, v33
	v_cvt_pk_bf16_f32 v65, v34, v35
	v_cvt_pk_bf16_f32 v66, v36, v37
	v_cvt_pk_bf16_f32 v67, v38, v39
	v_cvt_pk_bf16_f32 v68, v40, v41
	v_cvt_pk_bf16_f32 v69, v42, v43
	v_cvt_pk_bf16_f32 v70, v44, v45
	v_cvt_pk_bf16_f32 v71, v46, v47
	v_pk_add_f32 v[232:233], v[232:233], v[32:33]
	v_pk_add_f32 v[232:233], v[232:233], v[34:35]
	v_pk_add_f32 v[232:233], v[232:233], v[36:37]
	v_pk_add_f32 v[232:233], v[232:233], v[38:39]
	v_pk_add_f32 v[232:233], v[232:233], v[40:41]
	v_pk_add_f32 v[232:233], v[232:233], v[42:43]
	v_pk_add_f32 v[232:233], v[232:233], v[44:45]
	v_pk_add_f32 v[232:233], v[232:233], v[46:47]
	s_waitcnt lgkmcnt(12)
	v_mfma_f32_32x32x16_bf16 v[0:15], v[64:67], v[72:75], v[0:15]
	v_mfma_f32_32x32x16_bf16 v[16:31], v[64:67], v[76:79], v[16:31]
	v_mfma_f32_32x32x16_bf16 v[0:15], v[68:71], v[220:223], v[0:15]
	v_mfma_f32_32x32x16_bf16 v[16:31], v[68:71], v[224:227], v[16:31]
	global_load_dwordx4 v[156:159], v235, s[84:85]
	global_load_dwordx4 v[160:163], v236, s[84:85]
	global_load_dwordx4 v[164:167], v237, s[84:85]
	global_load_dwordx4 v[168:171], v238, s[84:85]
	global_load_dwordx4 v[172:175], v100, s[84:85] offset:768
	global_load_dwordx4 v[176:179], v149, s[84:85] offset:768
	global_load_dwordx4 v[180:183], v100, s[84:85] offset:832
	global_load_dwordx4 v[184:187], v149, s[84:85] offset:832
	ds_read2_b32 v[32:33], v115 offset0:102 offset1:103
	ds_read2_b32 v[34:35], v115 offset0:104 offset1:105
	ds_read2_b32 v[36:37], v115 offset0:110 offset1:111
	ds_read2_b32 v[38:39], v115 offset0:112 offset1:113
	ds_read2_b32 v[40:41], v115 offset0:119 offset1:120
	ds_read2_b32 v[42:43], v115 offset0:121 offset1:122
	ds_read2_b32 v[44:45], v115 offset0:127 offset1:128
	ds_read2_b32 v[46:47], v115 offset0:129 offset1:130
	s_waitcnt lgkmcnt(0)
	v_mfma_f32_32x32x16_bf16 v[32:47], v[188:191], v[48:51], v[32:47]
	ds_read_b64_tr_b16 v[72:73], v231
	ds_read_b64_tr_b16 v[74:75], v231 offset:512
	ds_read_b64_tr_b16 v[76:77], v231 offset:2048
	ds_read_b64_tr_b16 v[78:79], v231 offset:2560
	ds_read_b64_tr_b16 v[220:221], v231 offset:1024
	ds_read_b64_tr_b16 v[222:223], v231 offset:1536
	ds_read_b64_tr_b16 v[224:225], v231 offset:3072
	ds_read_b64_tr_b16 v[226:227], v231 offset:3584
	s_waitcnt vmcnt(8)
	ds_write_b128 v247, v[116:119]
	ds_write_b128 v247, v[120:123] offset:1024
	ds_write_b128 v247, v[124:127] offset:2048
	ds_write_b128 v247, v[128:131] offset:3072
	ds_read_b128 v[116:119], v248
	ds_read_b128 v[120:123], v249
	ds_read_b128 v[124:127], v250
	ds_read_b128 v[128:131], v251
	ds_write_b128 v112, v[132:135]
	ds_write_b128 v112, v[136:139] offset:1024
	ds_write_b128 v112, v[140:143] offset:2048
	ds_write_b128 v112, v[144:147] offset:3072
	v_mfma_f32_32x32x16_bf16 v[32:47], v[192:195], v[52:55], v[32:47]
	v_mfma_f32_32x32x16_bf16 v[32:47], v[196:199], v[56:59], v[32:47]
	v_mfma_f32_32x32x16_bf16 v[32:47], v[200:203], v[60:63], v[32:47]
	s_nop 11
	v_exp_f32_e32 v32, v32
	v_exp_f32_e32 v33, v33
	v_exp_f32_e32 v34, v34
	v_exp_f32_e32 v35, v35
	v_exp_f32_e32 v36, v36
	v_exp_f32_e32 v37, v37
	v_exp_f32_e32 v38, v38
	v_exp_f32_e32 v39, v39
	v_exp_f32_e32 v40, v40
	v_exp_f32_e32 v41, v41
	v_exp_f32_e32 v42, v42
	v_exp_f32_e32 v43, v43
	v_exp_f32_e32 v44, v44
	v_exp_f32_e32 v45, v45
	v_exp_f32_e32 v46, v46
	v_exp_f32_e32 v47, v47
	v_cvt_pk_bf16_f32 v64, v32, v33
	v_cvt_pk_bf16_f32 v65, v34, v35
	v_cvt_pk_bf16_f32 v66, v36, v37
	v_cvt_pk_bf16_f32 v67, v38, v39
	v_cvt_pk_bf16_f32 v68, v40, v41
	v_cvt_pk_bf16_f32 v69, v42, v43
	v_cvt_pk_bf16_f32 v70, v44, v45
	v_cvt_pk_bf16_f32 v71, v46, v47
	v_pk_add_f32 v[232:233], v[232:233], v[32:33]
	v_pk_add_f32 v[232:233], v[232:233], v[34:35]
	v_pk_add_f32 v[232:233], v[232:233], v[36:37]
	v_pk_add_f32 v[232:233], v[232:233], v[38:39]
	v_pk_add_f32 v[232:233], v[232:233], v[40:41]
	v_pk_add_f32 v[232:233], v[232:233], v[42:43]
	v_pk_add_f32 v[232:233], v[232:233], v[44:45]
	v_pk_add_f32 v[232:233], v[232:233], v[46:47]
	s_waitcnt lgkmcnt(12)
	v_mfma_f32_32x32x16_bf16 v[0:15], v[64:67], v[72:75], v[0:15]
	v_mfma_f32_32x32x16_bf16 v[16:31], v[64:67], v[76:79], v[16:31]
	v_mfma_f32_32x32x16_bf16 v[0:15], v[68:71], v[220:223], v[0:15]
	v_mfma_f32_32x32x16_bf16 v[16:31], v[68:71], v[224:227], v[16:31]
	global_load_dwordx4 v[188:191], v239, s[86:87]
	global_load_dwordx4 v[192:195], v240, s[86:87]
	global_load_dwordx4 v[196:199], v241, s[86:87]
	global_load_dwordx4 v[200:203], v242, s[86:87]
	global_load_dwordx4 v[204:207], v101, s[86:87] offset:768
	global_load_dwordx4 v[208:211], v150, s[86:87] offset:768
	global_load_dwordx4 v[212:215], v101, s[86:87] offset:832
	global_load_dwordx4 v[216:219], v150, s[86:87] offset:832
	s_add_u32 s86, s86, 0xc0000
	s_addc_u32 s87, s87, 0
	ds_read2_b32 v[32:33], v115 offset0:136 offset1:137
	ds_read2_b32 v[34:35], v115 offset0:138 offset1:139
	ds_read2_b32 v[36:37], v115 offset0:144 offset1:145
	ds_read2_b32 v[38:39], v115 offset0:146 offset1:147
	ds_read2_b32 v[40:41], v115 offset0:153 offset1:154
	ds_read2_b32 v[42:43], v115 offset0:155 offset1:156
	ds_read2_b32 v[44:45], v115 offset0:161 offset1:162
	ds_read2_b32 v[46:47], v115 offset0:163 offset1:164
	s_waitcnt lgkmcnt(0)
	v_mfma_f32_32x32x16_bf16 v[32:47], v[116:119], v[48:51], v[32:47]
	ds_read_b64_tr_b16 v[72:73], v231
	ds_read_b64_tr_b16 v[74:75], v231 offset:512
	ds_read_b64_tr_b16 v[76:77], v231 offset:2048
	ds_read_b64_tr_b16 v[78:79], v231 offset:2560
	ds_read_b64_tr_b16 v[220:221], v231 offset:1024
	ds_read_b64_tr_b16 v[222:223], v231 offset:1536
	ds_read_b64_tr_b16 v[224:225], v231 offset:3072
	ds_read_b64_tr_b16 v[226:227], v231 offset:3584
	s_waitcnt vmcnt(8)
	ds_write_b128 v247, v[156:159]
	ds_write_b128 v247, v[160:163] offset:1024
	ds_write_b128 v247, v[164:167] offset:2048
	ds_write_b128 v247, v[168:171] offset:3072
	ds_read_b128 v[156:159], v248
	ds_read_b128 v[160:163], v249
	ds_read_b128 v[164:167], v250
	ds_read_b128 v[168:171], v251
	ds_write_b128 v112, v[172:175]
	ds_write_b128 v112, v[176:179] offset:1024
	ds_write_b128 v112, v[180:183] offset:2048
	ds_write_b128 v112, v[184:187] offset:3072
	v_mfma_f32_32x32x16_bf16 v[32:47], v[120:123], v[52:55], v[32:47]
	v_mfma_f32_32x32x16_bf16 v[32:47], v[124:127], v[56:59], v[32:47]
	v_mfma_f32_32x32x16_bf16 v[32:47], v[128:131], v[60:63], v[32:47]
	s_nop 11
	v_exp_f32_e32 v32, v32
	v_exp_f32_e32 v33, v33
	v_exp_f32_e32 v34, v34
	v_exp_f32_e32 v35, v35
	v_exp_f32_e32 v36, v36
	v_exp_f32_e32 v37, v37
	v_exp_f32_e32 v38, v38
	v_exp_f32_e32 v39, v39
	v_exp_f32_e32 v40, v40
	v_exp_f32_e32 v41, v41
	v_exp_f32_e32 v42, v42
	v_exp_f32_e32 v43, v43
	v_exp_f32_e32 v44, v44
	v_exp_f32_e32 v45, v45
	v_exp_f32_e32 v46, v46
	v_exp_f32_e32 v47, v47
	v_cvt_pk_bf16_f32 v64, v32, v33
	v_cvt_pk_bf16_f32 v65, v34, v35
	v_cvt_pk_bf16_f32 v66, v36, v37
	v_cvt_pk_bf16_f32 v67, v38, v39
	v_cvt_pk_bf16_f32 v68, v40, v41
	v_cvt_pk_bf16_f32 v69, v42, v43
	v_cvt_pk_bf16_f32 v70, v44, v45
	v_cvt_pk_bf16_f32 v71, v46, v47
	v_pk_add_f32 v[232:233], v[232:233], v[32:33]
	v_pk_add_f32 v[232:233], v[232:233], v[34:35]
	v_pk_add_f32 v[232:233], v[232:233], v[36:37]
	v_pk_add_f32 v[232:233], v[232:233], v[38:39]
	v_pk_add_f32 v[232:233], v[232:233], v[40:41]
	v_pk_add_f32 v[232:233], v[232:233], v[42:43]
	v_pk_add_f32 v[232:233], v[232:233], v[44:45]
	v_pk_add_f32 v[232:233], v[232:233], v[46:47]
	s_waitcnt lgkmcnt(12)
	v_mfma_f32_32x32x16_bf16 v[0:15], v[64:67], v[72:75], v[0:15]
	v_mfma_f32_32x32x16_bf16 v[16:31], v[64:67], v[76:79], v[16:31]
	v_mfma_f32_32x32x16_bf16 v[0:15], v[68:71], v[220:223], v[0:15]
	v_mfma_f32_32x32x16_bf16 v[16:31], v[68:71], v[224:227], v[16:31]
	global_load_dwordx4 v[116:119], v239, s[86:87]
	global_load_dwordx4 v[120:123], v240, s[86:87]
	global_load_dwordx4 v[124:127], v241, s[86:87]
	global_load_dwordx4 v[128:131], v242, s[86:87]
	global_load_dwordx4 v[132:135], v101, s[86:87] offset:768
	global_load_dwordx4 v[136:139], v150, s[86:87] offset:768
	global_load_dwordx4 v[140:143], v101, s[86:87] offset:832
	global_load_dwordx4 v[144:147], v150, s[86:87] offset:832
	s_add_u32 s86, s86, 0xc0000
	s_addc_u32 s87, s87, 0
	ds_read2_b32 v[32:33], v115 offset0:170 offset1:171
	ds_read2_b32 v[34:35], v115 offset0:172 offset1:173
	ds_read2_b32 v[36:37], v115 offset0:178 offset1:179
	ds_read2_b32 v[38:39], v115 offset0:180 offset1:181
	ds_read2_b32 v[40:41], v115 offset0:187 offset1:188
	ds_read2_b32 v[42:43], v115 offset0:189 offset1:190
	ds_read2_b32 v[44:45], v115 offset0:195 offset1:196
	ds_read2_b32 v[46:47], v115 offset0:197 offset1:198
	s_waitcnt lgkmcnt(0)
	v_mfma_f32_32x32x16_bf16 v[32:47], v[156:159], v[48:51], v[32:47]
	ds_read_b64_tr_b16 v[72:73], v231
	ds_read_b64_tr_b16 v[74:75], v231 offset:512
	ds_read_b64_tr_b16 v[76:77], v231 offset:2048
	ds_read_b64_tr_b16 v[78:79], v231 offset:2560
	ds_read_b64_tr_b16 v[220:221], v231 offset:1024
	ds_read_b64_tr_b16 v[222:223], v231 offset:1536
	ds_read_b64_tr_b16 v[224:225], v231 offset:3072
	ds_read_b64_tr_b16 v[226:227], v231 offset:3584
	s_waitcnt vmcnt(8)
	ds_write_b128 v247, v[188:191]
	ds_write_b128 v247, v[192:195] offset:1024
	ds_write_b128 v247, v[196:199] offset:2048
	ds_write_b128 v247, v[200:203] offset:3072
	ds_read_b128 v[188:191], v248
	ds_read_b128 v[192:195], v249
	ds_read_b128 v[196:199], v250
	ds_read_b128 v[200:203], v251
	ds_write_b128 v112, v[204:207]
	ds_write_b128 v112, v[208:211] offset:1024
	ds_write_b128 v112, v[212:215] offset:2048
	ds_write_b128 v112, v[216:219] offset:3072
	v_mfma_f32_32x32x16_bf16 v[32:47], v[160:163], v[52:55], v[32:47]
	v_mfma_f32_32x32x16_bf16 v[32:47], v[164:167], v[56:59], v[32:47]
	v_mfma_f32_32x32x16_bf16 v[32:47], v[168:171], v[60:63], v[32:47]
	s_nop 11
	v_exp_f32_e32 v32, v32
	v_exp_f32_e32 v33, v33
	v_exp_f32_e32 v34, v34
	v_exp_f32_e32 v35, v35
	v_exp_f32_e32 v36, v36
	v_exp_f32_e32 v37, v37
	v_exp_f32_e32 v38, v38
	v_exp_f32_e32 v39, v39
	v_exp_f32_e32 v40, v40
	v_exp_f32_e32 v41, v41
	v_exp_f32_e32 v42, v42
	v_exp_f32_e32 v43, v43
	v_exp_f32_e32 v44, v44
	v_exp_f32_e32 v45, v45
	v_exp_f32_e32 v46, v46
	v_exp_f32_e32 v47, v47
	v_cvt_pk_bf16_f32 v64, v32, v33
	v_cvt_pk_bf16_f32 v65, v34, v35
	v_cvt_pk_bf16_f32 v66, v36, v37
	v_cvt_pk_bf16_f32 v67, v38, v39
	v_cvt_pk_bf16_f32 v68, v40, v41
	v_cvt_pk_bf16_f32 v69, v42, v43
	v_cvt_pk_bf16_f32 v70, v44, v45
	v_cvt_pk_bf16_f32 v71, v46, v47
	v_pk_add_f32 v[232:233], v[232:233], v[32:33]
	v_pk_add_f32 v[232:233], v[232:233], v[34:35]
	v_pk_add_f32 v[232:233], v[232:233], v[36:37]
	v_pk_add_f32 v[232:233], v[232:233], v[38:39]
	v_pk_add_f32 v[232:233], v[232:233], v[40:41]
	v_pk_add_f32 v[232:233], v[232:233], v[42:43]
	v_pk_add_f32 v[232:233], v[232:233], v[44:45]
	v_pk_add_f32 v[232:233], v[232:233], v[46:47]
	s_waitcnt lgkmcnt(12)
	v_mfma_f32_32x32x16_bf16 v[0:15], v[64:67], v[72:75], v[0:15]
	v_mfma_f32_32x32x16_bf16 v[16:31], v[64:67], v[76:79], v[16:31]
	v_mfma_f32_32x32x16_bf16 v[0:15], v[68:71], v[220:223], v[0:15]
	v_mfma_f32_32x32x16_bf16 v[16:31], v[68:71], v[224:227], v[16:31]
	global_load_dwordx4 v[156:159], v239, s[86:87]
	global_load_dwordx4 v[160:163], v240, s[86:87]
	global_load_dwordx4 v[164:167], v241, s[86:87]
	global_load_dwordx4 v[168:171], v242, s[86:87]
	global_load_dwordx4 v[172:175], v101, s[86:87] offset:768
	global_load_dwordx4 v[176:179], v150, s[86:87] offset:768
	global_load_dwordx4 v[180:183], v101, s[86:87] offset:832
	global_load_dwordx4 v[184:187], v150, s[86:87] offset:832
	s_add_u32 s86, s86, 0xc0000
	s_addc_u32 s87, s87, 0
	v_mov_b32_e32 v115, v229
	ds_read2_b32 v[32:33], v115 offset0:0 offset1:1
	ds_read2_b32 v[34:35], v115 offset0:2 offset1:3
	ds_read2_b32 v[36:37], v115 offset0:10 offset1:11
	ds_read2_b32 v[38:39], v115 offset0:12 offset1:13
	ds_read2_b32 v[40:41], v115 offset0:20 offset1:21
	ds_read2_b32 v[42:43], v115 offset0:22 offset1:23
	ds_read2_b32 v[44:45], v115 offset0:30 offset1:31
	ds_read2_b32 v[46:47], v115 offset0:32 offset1:33
	s_waitcnt lgkmcnt(0)
	v_mfma_f32_32x32x16_bf16 v[32:47], v[188:191], v[48:51], v[32:47]
	ds_read_b64_tr_b16 v[72:73], v231
	ds_read_b64_tr_b16 v[74:75], v231 offset:512
	ds_read_b64_tr_b16 v[76:77], v231 offset:2048
	ds_read_b64_tr_b16 v[78:79], v231 offset:2560
	ds_read_b64_tr_b16 v[220:221], v231 offset:1024
	ds_read_b64_tr_b16 v[222:223], v231 offset:1536
	ds_read_b64_tr_b16 v[224:225], v231 offset:3072
	ds_read_b64_tr_b16 v[226:227], v231 offset:3584
	s_waitcnt vmcnt(8)
	ds_write_b128 v247, v[116:119]
	ds_write_b128 v247, v[120:123] offset:1024
	ds_write_b128 v247, v[124:127] offset:2048
	ds_write_b128 v247, v[128:131] offset:3072
	ds_read_b128 v[116:119], v248
	ds_read_b128 v[120:123], v249
	ds_read_b128 v[124:127], v250
	ds_read_b128 v[128:131], v251
	ds_write_b128 v112, v[132:135]
	ds_write_b128 v112, v[136:139] offset:1024
	ds_write_b128 v112, v[140:143] offset:2048
	ds_write_b128 v112, v[144:147] offset:3072
	v_mfma_f32_32x32x16_bf16 v[32:47], v[192:195], v[52:55], v[32:47]
	v_mfma_f32_32x32x16_bf16 v[32:47], v[196:199], v[56:59], v[32:47]
	v_mfma_f32_32x32x16_bf16 v[32:47], v[200:203], v[60:63], v[32:47]
	s_nop 11
	v_exp_f32_e32 v32, v32
	v_exp_f32_e32 v33, v33
	v_exp_f32_e32 v34, v34
	v_exp_f32_e32 v35, v35
	v_exp_f32_e32 v36, v36
	v_exp_f32_e32 v37, v37
	v_exp_f32_e32 v38, v38
	v_exp_f32_e32 v39, v39
	v_exp_f32_e32 v40, v40
	v_exp_f32_e32 v41, v41
	v_exp_f32_e32 v42, v42
	v_exp_f32_e32 v43, v43
	v_exp_f32_e32 v44, v44
	v_exp_f32_e32 v45, v45
	v_exp_f32_e32 v46, v46
	v_exp_f32_e32 v47, v47
	v_cvt_pk_bf16_f32 v64, v32, v33
	v_cvt_pk_bf16_f32 v65, v34, v35
	v_cvt_pk_bf16_f32 v66, v36, v37
	v_cvt_pk_bf16_f32 v67, v38, v39
	v_cvt_pk_bf16_f32 v68, v40, v41
	v_cvt_pk_bf16_f32 v69, v42, v43
	v_cvt_pk_bf16_f32 v70, v44, v45
	v_cvt_pk_bf16_f32 v71, v46, v47
	v_pk_add_f32 v[232:233], v[232:233], v[32:33]
	v_pk_add_f32 v[232:233], v[232:233], v[34:35]
	v_pk_add_f32 v[232:233], v[232:233], v[36:37]
	v_pk_add_f32 v[232:233], v[232:233], v[38:39]
	v_pk_add_f32 v[232:233], v[232:233], v[40:41]
	v_pk_add_f32 v[232:233], v[232:233], v[42:43]
	v_pk_add_f32 v[232:233], v[232:233], v[44:45]
	v_pk_add_f32 v[232:233], v[232:233], v[46:47]
	s_waitcnt lgkmcnt(12)
	v_mfma_f32_32x32x16_bf16 v[0:15], v[64:67], v[72:75], v[0:15]
	v_mfma_f32_32x32x16_bf16 v[16:31], v[64:67], v[76:79], v[16:31]
	v_mfma_f32_32x32x16_bf16 v[0:15], v[68:71], v[220:223], v[0:15]
	v_mfma_f32_32x32x16_bf16 v[16:31], v[68:71], v[224:227], v[16:31]
	global_load_dwordx4 v[188:191], v239, s[86:87]
	global_load_dwordx4 v[192:195], v240, s[86:87]
	global_load_dwordx4 v[196:199], v241, s[86:87]
	global_load_dwordx4 v[200:203], v242, s[86:87]
	global_load_dwordx4 v[204:207], v101, s[86:87] offset:768
	global_load_dwordx4 v[208:211], v150, s[86:87] offset:768
	global_load_dwordx4 v[212:215], v101, s[86:87] offset:832
	global_load_dwordx4 v[216:219], v150, s[86:87] offset:832
	s_add_u32 s86, s86, 0xc0000
	s_addc_u32 s87, s87, 0
	ds_read2_b32 v[32:33], v115 offset0:40 offset1:41
	ds_read2_b32 v[34:35], v115 offset0:42 offset1:43
	ds_read2_b32 v[36:37], v115 offset0:50 offset1:51
	ds_read2_b32 v[38:39], v115 offset0:52 offset1:53
	ds_read2_b32 v[40:41], v115 offset0:60 offset1:61
	ds_read2_b32 v[42:43], v115 offset0:62 offset1:63
	ds_read2_b32 v[44:45], v115 offset0:70 offset1:71
	ds_read2_b32 v[46:47], v115 offset0:72 offset1:73
	s_waitcnt lgkmcnt(0)
	v_mfma_f32_32x32x16_bf16 v[32:47], v[116:119], v[48:51], v[32:47]
	ds_read_b64_tr_b16 v[72:73], v231
	ds_read_b64_tr_b16 v[74:75], v231 offset:512
	ds_read_b64_tr_b16 v[76:77], v231 offset:2048
	ds_read_b64_tr_b16 v[78:79], v231 offset:2560
	ds_read_b64_tr_b16 v[220:221], v231 offset:1024
	ds_read_b64_tr_b16 v[222:223], v231 offset:1536
	ds_read_b64_tr_b16 v[224:225], v231 offset:3072
	ds_read_b64_tr_b16 v[226:227], v231 offset:3584
	s_waitcnt vmcnt(8)
	ds_write_b128 v247, v[156:159]
	ds_write_b128 v247, v[160:163] offset:1024
	ds_write_b128 v247, v[164:167] offset:2048
	ds_write_b128 v247, v[168:171] offset:3072
	ds_read_b128 v[156:159], v248
	ds_read_b128 v[160:163], v249
	ds_read_b128 v[164:167], v250
	ds_read_b128 v[168:171], v251
	ds_write_b128 v112, v[172:175]
	ds_write_b128 v112, v[176:179] offset:1024
	ds_write_b128 v112, v[180:183] offset:2048
	ds_write_b128 v112, v[184:187] offset:3072
	v_mfma_f32_32x32x16_bf16 v[32:47], v[120:123], v[52:55], v[32:47]
	v_mfma_f32_32x32x16_bf16 v[32:47], v[124:127], v[56:59], v[32:47]
	v_mfma_f32_32x32x16_bf16 v[32:47], v[128:131], v[60:63], v[32:47]
	s_nop 11
	v_exp_f32_e32 v32, v32
	v_exp_f32_e32 v33, v33
	v_exp_f32_e32 v34, v34
	v_exp_f32_e32 v35, v35
	v_exp_f32_e32 v36, v36
	v_exp_f32_e32 v37, v37
	v_exp_f32_e32 v38, v38
	v_exp_f32_e32 v39, v39
	v_exp_f32_e32 v40, v40
	v_exp_f32_e32 v41, v41
	v_exp_f32_e32 v42, v42
	v_exp_f32_e32 v43, v43
	v_exp_f32_e32 v44, v44
	v_exp_f32_e32 v45, v45
	v_exp_f32_e32 v46, v46
	v_exp_f32_e32 v47, v47
	v_cvt_pk_bf16_f32 v64, v32, v33
	v_cvt_pk_bf16_f32 v65, v34, v35
	v_cvt_pk_bf16_f32 v66, v36, v37
	v_cvt_pk_bf16_f32 v67, v38, v39
	v_cvt_pk_bf16_f32 v68, v40, v41
	v_cvt_pk_bf16_f32 v69, v42, v43
	v_cvt_pk_bf16_f32 v70, v44, v45
	v_cvt_pk_bf16_f32 v71, v46, v47
	v_pk_add_f32 v[232:233], v[232:233], v[32:33]
	v_pk_add_f32 v[232:233], v[232:233], v[34:35]
	v_pk_add_f32 v[232:233], v[232:233], v[36:37]
	v_pk_add_f32 v[232:233], v[232:233], v[38:39]
	v_pk_add_f32 v[232:233], v[232:233], v[40:41]
	v_pk_add_f32 v[232:233], v[232:233], v[42:43]
	v_pk_add_f32 v[232:233], v[232:233], v[44:45]
	v_pk_add_f32 v[232:233], v[232:233], v[46:47]
	s_waitcnt lgkmcnt(12)
	v_mfma_f32_32x32x16_bf16 v[0:15], v[64:67], v[72:75], v[0:15]
	v_mfma_f32_32x32x16_bf16 v[16:31], v[64:67], v[76:79], v[16:31]
	v_mfma_f32_32x32x16_bf16 v[0:15], v[68:71], v[220:223], v[0:15]
	v_mfma_f32_32x32x16_bf16 v[16:31], v[68:71], v[224:227], v[16:31]
	global_load_dwordx4 v[116:119], v239, s[86:87]
	global_load_dwordx4 v[120:123], v240, s[86:87]
	global_load_dwordx4 v[124:127], v241, s[86:87]
	global_load_dwordx4 v[128:131], v242, s[86:87]
	global_load_dwordx4 v[132:135], v101, s[86:87] offset:768
	global_load_dwordx4 v[136:139], v150, s[86:87] offset:768
	global_load_dwordx4 v[140:143], v101, s[86:87] offset:832
	global_load_dwordx4 v[144:147], v150, s[86:87] offset:832
	s_add_u32 s86, s86, 0xc0000
	s_addc_u32 s87, s87, 0
	ds_read2_b32 v[32:33], v115 offset0:80 offset1:81
	ds_read2_b32 v[34:35], v115 offset0:82 offset1:83
	ds_read2_b32 v[36:37], v115 offset0:90 offset1:91
	ds_read2_b32 v[38:39], v115 offset0:92 offset1:93
	ds_read2_b32 v[40:41], v115 offset0:100 offset1:101
	ds_read2_b32 v[42:43], v115 offset0:102 offset1:103
	ds_read2_b32 v[44:45], v115 offset0:110 offset1:111
	ds_read2_b32 v[46:47], v115 offset0:112 offset1:113
	s_waitcnt lgkmcnt(0)
	v_mfma_f32_32x32x16_bf16 v[32:47], v[156:159], v[48:51], v[32:47]
	ds_read_b64_tr_b16 v[72:73], v231
	ds_read_b64_tr_b16 v[74:75], v231 offset:512
	ds_read_b64_tr_b16 v[76:77], v231 offset:2048
	ds_read_b64_tr_b16 v[78:79], v231 offset:2560
	ds_read_b64_tr_b16 v[220:221], v231 offset:1024
	ds_read_b64_tr_b16 v[222:223], v231 offset:1536
	ds_read_b64_tr_b16 v[224:225], v231 offset:3072
	ds_read_b64_tr_b16 v[226:227], v231 offset:3584
	s_waitcnt vmcnt(8)
	ds_write_b128 v247, v[188:191]
	ds_write_b128 v247, v[192:195] offset:1024
	ds_write_b128 v247, v[196:199] offset:2048
	ds_write_b128 v247, v[200:203] offset:3072
	ds_read_b128 v[188:191], v248
	ds_read_b128 v[192:195], v249
	ds_read_b128 v[196:199], v250
	ds_read_b128 v[200:203], v251
	ds_write_b128 v112, v[204:207]
	ds_write_b128 v112, v[208:211] offset:1024
	ds_write_b128 v112, v[212:215] offset:2048
	ds_write_b128 v112, v[216:219] offset:3072
	v_mfma_f32_32x32x16_bf16 v[32:47], v[160:163], v[52:55], v[32:47]
	v_mfma_f32_32x32x16_bf16 v[32:47], v[164:167], v[56:59], v[32:47]
	v_mfma_f32_32x32x16_bf16 v[32:47], v[168:171], v[60:63], v[32:47]
	s_nop 11
	v_exp_f32_e32 v32, v32
	v_exp_f32_e32 v33, v33
	v_exp_f32_e32 v34, v34
	v_exp_f32_e32 v35, v35
	v_exp_f32_e32 v36, v36
	v_exp_f32_e32 v37, v37
	v_exp_f32_e32 v38, v38
	v_exp_f32_e32 v39, v39
	v_exp_f32_e32 v40, v40
	v_exp_f32_e32 v41, v41
	v_exp_f32_e32 v42, v42
	v_exp_f32_e32 v43, v43
	v_exp_f32_e32 v44, v44
	v_exp_f32_e32 v45, v45
	v_exp_f32_e32 v46, v46
	v_exp_f32_e32 v47, v47
	v_cvt_pk_bf16_f32 v64, v32, v33
	v_cvt_pk_bf16_f32 v65, v34, v35
	v_cvt_pk_bf16_f32 v66, v36, v37
	v_cvt_pk_bf16_f32 v67, v38, v39
	v_cvt_pk_bf16_f32 v68, v40, v41
	v_cvt_pk_bf16_f32 v69, v42, v43
	v_cvt_pk_bf16_f32 v70, v44, v45
	v_cvt_pk_bf16_f32 v71, v46, v47
	v_pk_add_f32 v[232:233], v[232:233], v[32:33]
	v_pk_add_f32 v[232:233], v[232:233], v[34:35]
	v_pk_add_f32 v[232:233], v[232:233], v[36:37]
	v_pk_add_f32 v[232:233], v[232:233], v[38:39]
	v_pk_add_f32 v[232:233], v[232:233], v[40:41]
	v_pk_add_f32 v[232:233], v[232:233], v[42:43]
	v_pk_add_f32 v[232:233], v[232:233], v[44:45]
	v_pk_add_f32 v[232:233], v[232:233], v[46:47]
	s_waitcnt lgkmcnt(12)
	v_mfma_f32_32x32x16_bf16 v[0:15], v[64:67], v[72:75], v[0:15]
	v_mfma_f32_32x32x16_bf16 v[16:31], v[64:67], v[76:79], v[16:31]
	v_mfma_f32_32x32x16_bf16 v[0:15], v[68:71], v[220:223], v[0:15]
	v_mfma_f32_32x32x16_bf16 v[16:31], v[68:71], v[224:227], v[16:31]
	global_load_dwordx4 v[156:159], v239, s[86:87]
	global_load_dwordx4 v[160:163], v240, s[86:87]
	global_load_dwordx4 v[164:167], v241, s[86:87]
	global_load_dwordx4 v[168:171], v242, s[86:87]
	global_load_dwordx4 v[172:175], v101, s[86:87] offset:768
	global_load_dwordx4 v[176:179], v150, s[86:87] offset:768
	global_load_dwordx4 v[180:183], v101, s[86:87] offset:832
	global_load_dwordx4 v[184:187], v150, s[86:87] offset:832
	s_add_u32 s86, s86, 0xc0000
	s_addc_u32 s87, s87, 0
	ds_read2_b32 v[32:33], v115 offset0:120 offset1:121
	ds_read2_b32 v[34:35], v115 offset0:122 offset1:123
	ds_read2_b32 v[36:37], v115 offset0:130 offset1:131
	ds_read2_b32 v[38:39], v115 offset0:132 offset1:133
	ds_read2_b32 v[40:41], v115 offset0:140 offset1:141
	ds_read2_b32 v[42:43], v115 offset0:142 offset1:143
	ds_read2_b32 v[44:45], v115 offset0:150 offset1:151
	ds_read2_b32 v[46:47], v115 offset0:152 offset1:153
	s_waitcnt lgkmcnt(0)
	v_mfma_f32_32x32x16_bf16 v[32:47], v[188:191], v[48:51], v[32:47]
	ds_read_b64_tr_b16 v[72:73], v231
	ds_read_b64_tr_b16 v[74:75], v231 offset:512
	ds_read_b64_tr_b16 v[76:77], v231 offset:2048
	ds_read_b64_tr_b16 v[78:79], v231 offset:2560
	ds_read_b64_tr_b16 v[220:221], v231 offset:1024
	ds_read_b64_tr_b16 v[222:223], v231 offset:1536
	ds_read_b64_tr_b16 v[224:225], v231 offset:3072
	ds_read_b64_tr_b16 v[226:227], v231 offset:3584
	s_waitcnt vmcnt(8)
	ds_write_b128 v247, v[116:119]
	ds_write_b128 v247, v[120:123] offset:1024
	ds_write_b128 v247, v[124:127] offset:2048
	ds_write_b128 v247, v[128:131] offset:3072
	ds_read_b128 v[116:119], v248
	ds_read_b128 v[120:123], v249
	ds_read_b128 v[124:127], v250
	ds_read_b128 v[128:131], v251
	ds_write_b128 v112, v[132:135]
	ds_write_b128 v112, v[136:139] offset:1024
	ds_write_b128 v112, v[140:143] offset:2048
	ds_write_b128 v112, v[144:147] offset:3072
	v_mfma_f32_32x32x16_bf16 v[32:47], v[192:195], v[52:55], v[32:47]
	v_mfma_f32_32x32x16_bf16 v[32:47], v[196:199], v[56:59], v[32:47]
	v_mfma_f32_32x32x16_bf16 v[32:47], v[200:203], v[60:63], v[32:47]
	s_nop 11
	v_exp_f32_e32 v32, v32
	v_exp_f32_e32 v33, v33
	v_exp_f32_e32 v34, v34
	v_exp_f32_e32 v35, v35
	v_exp_f32_e32 v36, v36
	v_exp_f32_e32 v37, v37
	v_exp_f32_e32 v38, v38
	v_exp_f32_e32 v39, v39
	v_exp_f32_e32 v40, v40
	v_exp_f32_e32 v41, v41
	v_exp_f32_e32 v42, v42
	v_exp_f32_e32 v43, v43
	v_exp_f32_e32 v44, v44
	v_exp_f32_e32 v45, v45
	v_exp_f32_e32 v46, v46
	v_exp_f32_e32 v47, v47
	v_cvt_pk_bf16_f32 v64, v32, v33
	v_cvt_pk_bf16_f32 v65, v34, v35
	v_cvt_pk_bf16_f32 v66, v36, v37
	v_cvt_pk_bf16_f32 v67, v38, v39
	v_cvt_pk_bf16_f32 v68, v40, v41
	v_cvt_pk_bf16_f32 v69, v42, v43
	v_cvt_pk_bf16_f32 v70, v44, v45
	v_cvt_pk_bf16_f32 v71, v46, v47
	v_pk_add_f32 v[232:233], v[232:233], v[32:33]
	v_pk_add_f32 v[232:233], v[232:233], v[34:35]
	v_pk_add_f32 v[232:233], v[232:233], v[36:37]
	v_pk_add_f32 v[232:233], v[232:233], v[38:39]
	v_pk_add_f32 v[232:233], v[232:233], v[40:41]
	v_pk_add_f32 v[232:233], v[232:233], v[42:43]
	v_pk_add_f32 v[232:233], v[232:233], v[44:45]
	v_pk_add_f32 v[232:233], v[232:233], v[46:47]
	s_waitcnt lgkmcnt(12)
	v_mfma_f32_32x32x16_bf16 v[0:15], v[64:67], v[72:75], v[0:15]
	v_mfma_f32_32x32x16_bf16 v[16:31], v[64:67], v[76:79], v[16:31]
	v_mfma_f32_32x32x16_bf16 v[0:15], v[68:71], v[220:223], v[0:15]
	v_mfma_f32_32x32x16_bf16 v[16:31], v[68:71], v[224:227], v[16:31]
	global_load_dwordx4 v[188:191], v239, s[86:87]
	global_load_dwordx4 v[192:195], v240, s[86:87]
	global_load_dwordx4 v[196:199], v241, s[86:87]
	global_load_dwordx4 v[200:203], v242, s[86:87]
	global_load_dwordx4 v[204:207], v101, s[86:87] offset:768
	global_load_dwordx4 v[208:211], v150, s[86:87] offset:768
	global_load_dwordx4 v[212:215], v101, s[86:87] offset:832
	global_load_dwordx4 v[216:219], v150, s[86:87] offset:832
	s_add_u32 s86, s86, 0xc0000
	s_addc_u32 s87, s87, 0
	v_add_u32_e32 v115, 640, v115
	ds_read2_b32 v[32:33], v115 offset0:0 offset1:1
	ds_read2_b32 v[34:35], v115 offset0:2 offset1:3
	ds_read2_b32 v[36:37], v115 offset0:10 offset1:11
	ds_read2_b32 v[38:39], v115 offset0:12 offset1:13
	ds_read2_b32 v[40:41], v115 offset0:20 offset1:21
	ds_read2_b32 v[42:43], v115 offset0:22 offset1:23
	ds_read2_b32 v[44:45], v115 offset0:30 offset1:31
	ds_read2_b32 v[46:47], v115 offset0:32 offset1:33
	s_waitcnt lgkmcnt(0)
	v_mfma_f32_32x32x16_bf16 v[32:47], v[116:119], v[48:51], v[32:47]
	ds_read_b64_tr_b16 v[72:73], v231
	ds_read_b64_tr_b16 v[74:75], v231 offset:512
	ds_read_b64_tr_b16 v[76:77], v231 offset:2048
	ds_read_b64_tr_b16 v[78:79], v231 offset:2560
	ds_read_b64_tr_b16 v[220:221], v231 offset:1024
	ds_read_b64_tr_b16 v[222:223], v231 offset:1536
	ds_read_b64_tr_b16 v[224:225], v231 offset:3072
	ds_read_b64_tr_b16 v[226:227], v231 offset:3584
	s_waitcnt vmcnt(8)
	ds_write_b128 v247, v[156:159]
	ds_write_b128 v247, v[160:163] offset:1024
	ds_write_b128 v247, v[164:167] offset:2048
	ds_write_b128 v247, v[168:171] offset:3072
	ds_read_b128 v[156:159], v248
	ds_read_b128 v[160:163], v249
	ds_read_b128 v[164:167], v250
	ds_read_b128 v[168:171], v251
	ds_write_b128 v112, v[172:175]
	ds_write_b128 v112, v[176:179] offset:1024
	ds_write_b128 v112, v[180:183] offset:2048
	ds_write_b128 v112, v[184:187] offset:3072
	v_mfma_f32_32x32x16_bf16 v[32:47], v[120:123], v[52:55], v[32:47]
	v_mfma_f32_32x32x16_bf16 v[32:47], v[124:127], v[56:59], v[32:47]
	v_mfma_f32_32x32x16_bf16 v[32:47], v[128:131], v[60:63], v[32:47]
	s_nop 11
	v_exp_f32_e32 v32, v32
	v_exp_f32_e32 v33, v33
	v_exp_f32_e32 v34, v34
	v_exp_f32_e32 v35, v35
	v_exp_f32_e32 v36, v36
	v_exp_f32_e32 v37, v37
	v_exp_f32_e32 v38, v38
	v_exp_f32_e32 v39, v39
	v_exp_f32_e32 v40, v40
	v_exp_f32_e32 v41, v41
	v_exp_f32_e32 v42, v42
	v_exp_f32_e32 v43, v43
	v_exp_f32_e32 v44, v44
	v_exp_f32_e32 v45, v45
	v_exp_f32_e32 v46, v46
	v_exp_f32_e32 v47, v47
	v_cvt_pk_bf16_f32 v64, v32, v33
	v_cvt_pk_bf16_f32 v65, v34, v35
	v_cvt_pk_bf16_f32 v66, v36, v37
	v_cvt_pk_bf16_f32 v67, v38, v39
	v_cvt_pk_bf16_f32 v68, v40, v41
	v_cvt_pk_bf16_f32 v69, v42, v43
	v_cvt_pk_bf16_f32 v70, v44, v45
	v_cvt_pk_bf16_f32 v71, v46, v47
	v_pk_add_f32 v[232:233], v[232:233], v[32:33]
	v_pk_add_f32 v[232:233], v[232:233], v[34:35]
	v_pk_add_f32 v[232:233], v[232:233], v[36:37]
	v_pk_add_f32 v[232:233], v[232:233], v[38:39]
	v_pk_add_f32 v[232:233], v[232:233], v[40:41]
	v_pk_add_f32 v[232:233], v[232:233], v[42:43]
	v_pk_add_f32 v[232:233], v[232:233], v[44:45]
	v_pk_add_f32 v[232:233], v[232:233], v[46:47]
	s_waitcnt lgkmcnt(12)
	v_mfma_f32_32x32x16_bf16 v[0:15], v[64:67], v[72:75], v[0:15]
	v_mfma_f32_32x32x16_bf16 v[16:31], v[64:67], v[76:79], v[16:31]
	v_mfma_f32_32x32x16_bf16 v[0:15], v[68:71], v[220:223], v[0:15]
	v_mfma_f32_32x32x16_bf16 v[16:31], v[68:71], v[224:227], v[16:31]
	global_load_dwordx4 v[116:119], v239, s[86:87]
	global_load_dwordx4 v[120:123], v240, s[86:87]
	global_load_dwordx4 v[124:127], v241, s[86:87]
	global_load_dwordx4 v[128:131], v242, s[86:87]
	global_load_dwordx4 v[132:135], v101, s[86:87] offset:768
	global_load_dwordx4 v[136:139], v150, s[86:87] offset:768
	global_load_dwordx4 v[140:143], v101, s[86:87] offset:832
	global_load_dwordx4 v[144:147], v150, s[86:87] offset:832
	ds_read2_b32 v[32:33], v115 offset0:40 offset1:41
	ds_read2_b32 v[34:35], v115 offset0:42 offset1:43
	ds_read2_b32 v[36:37], v115 offset0:50 offset1:51
	ds_read2_b32 v[38:39], v115 offset0:52 offset1:53
	ds_read2_b32 v[40:41], v115 offset0:60 offset1:61
	ds_read2_b32 v[42:43], v115 offset0:62 offset1:63
	ds_read2_b32 v[44:45], v115 offset0:70 offset1:71
	ds_read2_b32 v[46:47], v115 offset0:72 offset1:73
	s_waitcnt lgkmcnt(0)
	v_mfma_f32_32x32x16_bf16 v[32:47], v[156:159], v[48:51], v[32:47]
	ds_read_b64_tr_b16 v[72:73], v231
	ds_read_b64_tr_b16 v[74:75], v231 offset:512
	ds_read_b64_tr_b16 v[76:77], v231 offset:2048
	ds_read_b64_tr_b16 v[78:79], v231 offset:2560
	ds_read_b64_tr_b16 v[220:221], v231 offset:1024
	ds_read_b64_tr_b16 v[222:223], v231 offset:1536
	ds_read_b64_tr_b16 v[224:225], v231 offset:3072
	ds_read_b64_tr_b16 v[226:227], v231 offset:3584
	s_waitcnt vmcnt(8)
	ds_write_b128 v247, v[188:191]
	ds_write_b128 v247, v[192:195] offset:1024
	ds_write_b128 v247, v[196:199] offset:2048
	ds_write_b128 v247, v[200:203] offset:3072
	ds_read_b128 v[188:191], v248
	ds_read_b128 v[192:195], v249
	ds_read_b128 v[196:199], v250
	ds_read_b128 v[200:203], v251
	ds_write_b128 v112, v[204:207]
	ds_write_b128 v112, v[208:211] offset:1024
	ds_write_b128 v112, v[212:215] offset:2048
	ds_write_b128 v112, v[216:219] offset:3072
	v_mfma_f32_32x32x16_bf16 v[32:47], v[160:163], v[52:55], v[32:47]
	v_mfma_f32_32x32x16_bf16 v[32:47], v[164:167], v[56:59], v[32:47]
	v_mfma_f32_32x32x16_bf16 v[32:47], v[168:171], v[60:63], v[32:47]
	s_nop 11
	v_exp_f32_e32 v32, v32
	v_exp_f32_e32 v33, v33
	v_exp_f32_e32 v34, v34
	v_exp_f32_e32 v35, v35
	v_exp_f32_e32 v36, v36
	v_exp_f32_e32 v37, v37
	v_exp_f32_e32 v38, v38
	v_exp_f32_e32 v39, v39
	v_exp_f32_e32 v40, v40
	v_exp_f32_e32 v41, v41
	v_exp_f32_e32 v42, v42
	v_exp_f32_e32 v43, v43
	v_exp_f32_e32 v44, v44
	v_exp_f32_e32 v45, v45
	v_exp_f32_e32 v46, v46
	v_exp_f32_e32 v47, v47
	v_cvt_pk_bf16_f32 v64, v32, v33
	v_cvt_pk_bf16_f32 v65, v34, v35
	v_cvt_pk_bf16_f32 v66, v36, v37
	v_cvt_pk_bf16_f32 v67, v38, v39
	v_cvt_pk_bf16_f32 v68, v40, v41
	v_cvt_pk_bf16_f32 v69, v42, v43
	v_cvt_pk_bf16_f32 v70, v44, v45
	v_cvt_pk_bf16_f32 v71, v46, v47
	v_pk_add_f32 v[232:233], v[232:233], v[32:33]
	v_pk_add_f32 v[232:233], v[232:233], v[34:35]
	v_pk_add_f32 v[232:233], v[232:233], v[36:37]
	v_pk_add_f32 v[232:233], v[232:233], v[38:39]
	v_pk_add_f32 v[232:233], v[232:233], v[40:41]
	v_pk_add_f32 v[232:233], v[232:233], v[42:43]
	v_pk_add_f32 v[232:233], v[232:233], v[44:45]
	v_pk_add_f32 v[232:233], v[232:233], v[46:47]
	s_waitcnt lgkmcnt(12)
	v_mfma_f32_32x32x16_bf16 v[0:15], v[64:67], v[72:75], v[0:15]
	v_mfma_f32_32x32x16_bf16 v[16:31], v[64:67], v[76:79], v[16:31]
	v_mfma_f32_32x32x16_bf16 v[0:15], v[68:71], v[220:223], v[0:15]
	v_mfma_f32_32x32x16_bf16 v[16:31], v[68:71], v[224:227], v[16:31]
	global_load_dwordx4 v[156:159], v243, s[88:89]
	global_load_dwordx4 v[160:163], v244, s[88:89]
	global_load_dwordx4 v[164:167], v245, s[88:89]
	global_load_dwordx4 v[168:171], v246, s[88:89]
	global_load_dwordx4 v[172:175], v148, s[88:89] offset:768
	global_load_dwordx4 v[176:179], v151, s[88:89] offset:768
	global_load_dwordx4 v[180:183], v148, s[88:89] offset:832
	global_load_dwordx4 v[184:187], v151, s[88:89] offset:832
	s_add_u32 s88, s88, 0x300000
	s_addc_u32 s89, s89, 0
	ds_read2_b32 v[32:33], v115 offset0:80 offset1:81
	ds_read2_b32 v[34:35], v115 offset0:82 offset1:83
	ds_read2_b32 v[36:37], v115 offset0:90 offset1:91
	ds_read2_b32 v[38:39], v115 offset0:92 offset1:93
	ds_read2_b32 v[40:41], v115 offset0:100 offset1:101
	ds_read2_b32 v[42:43], v115 offset0:102 offset1:103
	ds_read2_b32 v[44:45], v115 offset0:110 offset1:111
	ds_read2_b32 v[46:47], v115 offset0:112 offset1:113
	s_waitcnt lgkmcnt(0)
	v_mfma_f32_32x32x16_bf16 v[32:47], v[188:191], v[48:51], v[32:47]
	ds_read_b64_tr_b16 v[72:73], v231
	ds_read_b64_tr_b16 v[74:75], v231 offset:512
	ds_read_b64_tr_b16 v[76:77], v231 offset:2048
	ds_read_b64_tr_b16 v[78:79], v231 offset:2560
	ds_read_b64_tr_b16 v[220:221], v231 offset:1024
	ds_read_b64_tr_b16 v[222:223], v231 offset:1536
	ds_read_b64_tr_b16 v[224:225], v231 offset:3072
	ds_read_b64_tr_b16 v[226:227], v231 offset:3584
	s_waitcnt vmcnt(8)
	ds_write_b128 v247, v[116:119]
	ds_write_b128 v247, v[120:123] offset:1024
	ds_write_b128 v247, v[124:127] offset:2048
	ds_write_b128 v247, v[128:131] offset:3072
	ds_read_b128 v[116:119], v248
	ds_read_b128 v[120:123], v249
	ds_read_b128 v[124:127], v250
	ds_read_b128 v[128:131], v251
	ds_write_b128 v112, v[132:135]
	ds_write_b128 v112, v[136:139] offset:1024
	ds_write_b128 v112, v[140:143] offset:2048
	ds_write_b128 v112, v[144:147] offset:3072
	v_mfma_f32_32x32x16_bf16 v[32:47], v[192:195], v[52:55], v[32:47]
	v_mfma_f32_32x32x16_bf16 v[32:47], v[196:199], v[56:59], v[32:47]
	v_mfma_f32_32x32x16_bf16 v[32:47], v[200:203], v[60:63], v[32:47]
	s_nop 11
	v_exp_f32_e32 v32, v32
	v_exp_f32_e32 v33, v33
	v_exp_f32_e32 v34, v34
	v_exp_f32_e32 v35, v35
	v_exp_f32_e32 v36, v36
	v_exp_f32_e32 v37, v37
	v_exp_f32_e32 v38, v38
	v_exp_f32_e32 v39, v39
	v_exp_f32_e32 v40, v40
	v_exp_f32_e32 v41, v41
	v_exp_f32_e32 v42, v42
	v_exp_f32_e32 v43, v43
	v_exp_f32_e32 v44, v44
	v_exp_f32_e32 v45, v45
	v_exp_f32_e32 v46, v46
	v_exp_f32_e32 v47, v47
	v_cvt_pk_bf16_f32 v64, v32, v33
	v_cvt_pk_bf16_f32 v65, v34, v35
	v_cvt_pk_bf16_f32 v66, v36, v37
	v_cvt_pk_bf16_f32 v67, v38, v39
	v_cvt_pk_bf16_f32 v68, v40, v41
	v_cvt_pk_bf16_f32 v69, v42, v43
	v_cvt_pk_bf16_f32 v70, v44, v45
	v_cvt_pk_bf16_f32 v71, v46, v47
	v_pk_add_f32 v[232:233], v[232:233], v[32:33]
	v_pk_add_f32 v[232:233], v[232:233], v[34:35]
	v_pk_add_f32 v[232:233], v[232:233], v[36:37]
	v_pk_add_f32 v[232:233], v[232:233], v[38:39]
	v_pk_add_f32 v[232:233], v[232:233], v[40:41]
	v_pk_add_f32 v[232:233], v[232:233], v[42:43]
	v_pk_add_f32 v[232:233], v[232:233], v[44:45]
	v_pk_add_f32 v[232:233], v[232:233], v[46:47]
	s_waitcnt lgkmcnt(12)
	v_mfma_f32_32x32x16_bf16 v[0:15], v[64:67], v[72:75], v[0:15]
	v_mfma_f32_32x32x16_bf16 v[16:31], v[64:67], v[76:79], v[16:31]
	v_mfma_f32_32x32x16_bf16 v[0:15], v[68:71], v[220:223], v[0:15]
	v_mfma_f32_32x32x16_bf16 v[16:31], v[68:71], v[224:227], v[16:31]
	global_load_dwordx4 v[188:191], v243, s[88:89]
	global_load_dwordx4 v[192:195], v244, s[88:89]
	global_load_dwordx4 v[196:199], v245, s[88:89]
	global_load_dwordx4 v[200:203], v246, s[88:89]
	global_load_dwordx4 v[204:207], v148, s[88:89] offset:768
	global_load_dwordx4 v[208:211], v151, s[88:89] offset:768
	global_load_dwordx4 v[212:215], v148, s[88:89] offset:832
	global_load_dwordx4 v[216:219], v151, s[88:89] offset:832
	s_add_u32 s88, s88, 0x300000
	s_addc_u32 s89, s89, 0
	ds_read2_b32 v[32:33], v115 offset0:120 offset1:121
	ds_read2_b32 v[34:35], v115 offset0:122 offset1:123
	ds_read2_b32 v[36:37], v115 offset0:130 offset1:131
	ds_read2_b32 v[38:39], v115 offset0:132 offset1:133
	ds_read2_b32 v[40:41], v115 offset0:140 offset1:141
	ds_read2_b32 v[42:43], v115 offset0:142 offset1:143
	ds_read2_b32 v[44:45], v115 offset0:150 offset1:151
	ds_read2_b32 v[46:47], v115 offset0:152 offset1:153
	s_waitcnt lgkmcnt(0)
	v_mfma_f32_32x32x16_bf16 v[32:47], v[116:119], v[48:51], v[32:47]
	ds_read_b64_tr_b16 v[72:73], v231
	ds_read_b64_tr_b16 v[74:75], v231 offset:512
	ds_read_b64_tr_b16 v[76:77], v231 offset:2048
	ds_read_b64_tr_b16 v[78:79], v231 offset:2560
	ds_read_b64_tr_b16 v[220:221], v231 offset:1024
	ds_read_b64_tr_b16 v[222:223], v231 offset:1536
	ds_read_b64_tr_b16 v[224:225], v231 offset:3072
	ds_read_b64_tr_b16 v[226:227], v231 offset:3584
	s_waitcnt vmcnt(8)
	ds_write_b128 v247, v[156:159]
	ds_write_b128 v247, v[160:163] offset:1024
	ds_write_b128 v247, v[164:167] offset:2048
	ds_write_b128 v247, v[168:171] offset:3072
	ds_read_b128 v[156:159], v248
	ds_read_b128 v[160:163], v249
	ds_read_b128 v[164:167], v250
	ds_read_b128 v[168:171], v251
	ds_write_b128 v112, v[172:175]
	ds_write_b128 v112, v[176:179] offset:1024
	ds_write_b128 v112, v[180:183] offset:2048
	ds_write_b128 v112, v[184:187] offset:3072
	v_mfma_f32_32x32x16_bf16 v[32:47], v[120:123], v[52:55], v[32:47]
	v_mfma_f32_32x32x16_bf16 v[32:47], v[124:127], v[56:59], v[32:47]
	v_mfma_f32_32x32x16_bf16 v[32:47], v[128:131], v[60:63], v[32:47]
	s_nop 11
	v_exp_f32_e32 v32, v32
	v_exp_f32_e32 v33, v33
	v_exp_f32_e32 v34, v34
	v_exp_f32_e32 v35, v35
	v_exp_f32_e32 v36, v36
	v_exp_f32_e32 v37, v37
	v_exp_f32_e32 v38, v38
	v_exp_f32_e32 v39, v39
	v_exp_f32_e32 v40, v40
	v_exp_f32_e32 v41, v41
	v_exp_f32_e32 v42, v42
	v_exp_f32_e32 v43, v43
	v_exp_f32_e32 v44, v44
	v_exp_f32_e32 v45, v45
	v_exp_f32_e32 v46, v46
	v_exp_f32_e32 v47, v47
	v_cvt_pk_bf16_f32 v64, v32, v33
	v_cvt_pk_bf16_f32 v65, v34, v35
	v_cvt_pk_bf16_f32 v66, v36, v37
	v_cvt_pk_bf16_f32 v67, v38, v39
	v_cvt_pk_bf16_f32 v68, v40, v41
	v_cvt_pk_bf16_f32 v69, v42, v43
	v_cvt_pk_bf16_f32 v70, v44, v45
	v_cvt_pk_bf16_f32 v71, v46, v47
	v_pk_add_f32 v[232:233], v[232:233], v[32:33]
	v_pk_add_f32 v[232:233], v[232:233], v[34:35]
	v_pk_add_f32 v[232:233], v[232:233], v[36:37]
	v_pk_add_f32 v[232:233], v[232:233], v[38:39]
	v_pk_add_f32 v[232:233], v[232:233], v[40:41]
	v_pk_add_f32 v[232:233], v[232:233], v[42:43]
	v_pk_add_f32 v[232:233], v[232:233], v[44:45]
	v_pk_add_f32 v[232:233], v[232:233], v[46:47]
	s_waitcnt lgkmcnt(12)
	v_mfma_f32_32x32x16_bf16 v[0:15], v[64:67], v[72:75], v[0:15]
	v_mfma_f32_32x32x16_bf16 v[16:31], v[64:67], v[76:79], v[16:31]
	v_mfma_f32_32x32x16_bf16 v[0:15], v[68:71], v[220:223], v[0:15]
	v_mfma_f32_32x32x16_bf16 v[16:31], v[68:71], v[224:227], v[16:31]
	global_load_dwordx4 v[116:119], v243, s[88:89]
	global_load_dwordx4 v[120:123], v244, s[88:89]
	global_load_dwordx4 v[124:127], v245, s[88:89]
	global_load_dwordx4 v[128:131], v246, s[88:89]
	global_load_dwordx4 v[132:135], v148, s[88:89] offset:768
	global_load_dwordx4 v[136:139], v151, s[88:89] offset:768
	global_load_dwordx4 v[140:143], v148, s[88:89] offset:832
	global_load_dwordx4 v[144:147], v151, s[88:89] offset:832
	s_add_u32 s88, s88, 0x300000
	s_addc_u32 s89, s89, 0
	v_mov_b32_e32 v115, v230
	ds_read2_b32 v[32:33], v115 offset0:0 offset1:1
	ds_read2_b32 v[34:35], v115 offset0:2 offset1:3
	ds_read2_b32 v[36:37], v115 offset0:8 offset1:9
	ds_read2_b32 v[38:39], v115 offset0:10 offset1:11
	ds_read2_b32 v[40:41], v115 offset0:16 offset1:17
	ds_read2_b32 v[42:43], v115 offset0:18 offset1:19
	ds_read2_b32 v[44:45], v115 offset0:24 offset1:25
	ds_read2_b32 v[46:47], v115 offset0:26 offset1:27
	s_waitcnt lgkmcnt(0)
	v_mfma_f32_32x32x16_bf16 v[32:47], v[156:159], v[48:51], v[32:47]
	ds_read_b64_tr_b16 v[72:73], v231
	ds_read_b64_tr_b16 v[74:75], v231 offset:512
	ds_read_b64_tr_b16 v[76:77], v231 offset:2048
	ds_read_b64_tr_b16 v[78:79], v231 offset:2560
	ds_read_b64_tr_b16 v[220:221], v231 offset:1024
	ds_read_b64_tr_b16 v[222:223], v231 offset:1536
	ds_read_b64_tr_b16 v[224:225], v231 offset:3072
	ds_read_b64_tr_b16 v[226:227], v231 offset:3584
	s_waitcnt vmcnt(8)
	ds_write_b128 v247, v[188:191]
	ds_write_b128 v247, v[192:195] offset:1024
	ds_write_b128 v247, v[196:199] offset:2048
	ds_write_b128 v247, v[200:203] offset:3072
	ds_read_b128 v[188:191], v248
	ds_read_b128 v[192:195], v249
	ds_read_b128 v[196:199], v250
	ds_read_b128 v[200:203], v251
	ds_write_b128 v112, v[204:207]
	ds_write_b128 v112, v[208:211] offset:1024
	ds_write_b128 v112, v[212:215] offset:2048
	ds_write_b128 v112, v[216:219] offset:3072
	v_mfma_f32_32x32x16_bf16 v[32:47], v[160:163], v[52:55], v[32:47]
	v_mfma_f32_32x32x16_bf16 v[32:47], v[164:167], v[56:59], v[32:47]
	v_mfma_f32_32x32x16_bf16 v[32:47], v[168:171], v[60:63], v[32:47]
	s_nop 11
	v_exp_f32_e32 v32, v32
	v_exp_f32_e32 v33, v33
	v_exp_f32_e32 v34, v34
	v_exp_f32_e32 v35, v35
	v_exp_f32_e32 v36, v36
	v_exp_f32_e32 v37, v37
	v_exp_f32_e32 v38, v38
	v_exp_f32_e32 v39, v39
	v_exp_f32_e32 v40, v40
	v_exp_f32_e32 v41, v41
	v_exp_f32_e32 v42, v42
	v_exp_f32_e32 v43, v43
	v_exp_f32_e32 v44, v44
	v_exp_f32_e32 v45, v45
	v_exp_f32_e32 v46, v46
	v_exp_f32_e32 v47, v47
	v_cvt_pk_bf16_f32 v64, v32, v33
	v_cvt_pk_bf16_f32 v65, v34, v35
	v_cvt_pk_bf16_f32 v66, v36, v37
	v_cvt_pk_bf16_f32 v67, v38, v39
	v_cvt_pk_bf16_f32 v68, v40, v41
	v_cvt_pk_bf16_f32 v69, v42, v43
	v_cvt_pk_bf16_f32 v70, v44, v45
	v_cvt_pk_bf16_f32 v71, v46, v47
	v_pk_add_f32 v[232:233], v[232:233], v[32:33]
	v_pk_add_f32 v[232:233], v[232:233], v[34:35]
	v_pk_add_f32 v[232:233], v[232:233], v[36:37]
	v_pk_add_f32 v[232:233], v[232:233], v[38:39]
	v_pk_add_f32 v[232:233], v[232:233], v[40:41]
	v_pk_add_f32 v[232:233], v[232:233], v[42:43]
	v_pk_add_f32 v[232:233], v[232:233], v[44:45]
	v_pk_add_f32 v[232:233], v[232:233], v[46:47]
	s_waitcnt lgkmcnt(12)
	v_mfma_f32_32x32x16_bf16 v[0:15], v[64:67], v[72:75], v[0:15]
	v_mfma_f32_32x32x16_bf16 v[16:31], v[64:67], v[76:79], v[16:31]
	v_mfma_f32_32x32x16_bf16 v[0:15], v[68:71], v[220:223], v[0:15]
	v_mfma_f32_32x32x16_bf16 v[16:31], v[68:71], v[224:227], v[16:31]
	global_load_dwordx4 v[156:159], v243, s[88:89]
	global_load_dwordx4 v[160:163], v244, s[88:89]
	global_load_dwordx4 v[164:167], v245, s[88:89]
	global_load_dwordx4 v[168:171], v246, s[88:89]
	global_load_dwordx4 v[172:175], v148, s[88:89] offset:768
	global_load_dwordx4 v[176:179], v151, s[88:89] offset:768
	global_load_dwordx4 v[180:183], v148, s[88:89] offset:832
	global_load_dwordx4 v[184:187], v151, s[88:89] offset:832
	s_add_u32 s88, s88, 0x300000
	s_addc_u32 s89, s89, 0
	ds_read2_b32 v[32:33], v115 offset0:32 offset1:33
	ds_read2_b32 v[34:35], v115 offset0:34 offset1:35
	ds_read2_b32 v[36:37], v115 offset0:40 offset1:41
	ds_read2_b32 v[38:39], v115 offset0:42 offset1:43
	ds_read2_b32 v[40:41], v115 offset0:48 offset1:49
	ds_read2_b32 v[42:43], v115 offset0:50 offset1:51
	ds_read2_b32 v[44:45], v115 offset0:56 offset1:57
	ds_read2_b32 v[46:47], v115 offset0:58 offset1:59
	s_waitcnt lgkmcnt(0)
	v_mfma_f32_32x32x16_bf16 v[32:47], v[188:191], v[48:51], v[32:47]
	ds_read_b64_tr_b16 v[72:73], v231
	ds_read_b64_tr_b16 v[74:75], v231 offset:512
	ds_read_b64_tr_b16 v[76:77], v231 offset:2048
	ds_read_b64_tr_b16 v[78:79], v231 offset:2560
	ds_read_b64_tr_b16 v[220:221], v231 offset:1024
	ds_read_b64_tr_b16 v[222:223], v231 offset:1536
	ds_read_b64_tr_b16 v[224:225], v231 offset:3072
	ds_read_b64_tr_b16 v[226:227], v231 offset:3584
	s_waitcnt vmcnt(8)
	ds_write_b128 v247, v[116:119]
	ds_write_b128 v247, v[120:123] offset:1024
	ds_write_b128 v247, v[124:127] offset:2048
	ds_write_b128 v247, v[128:131] offset:3072
	ds_read_b128 v[116:119], v248
	ds_read_b128 v[120:123], v249
	ds_read_b128 v[124:127], v250
	ds_read_b128 v[128:131], v251
	ds_write_b128 v112, v[132:135]
	ds_write_b128 v112, v[136:139] offset:1024
	ds_write_b128 v112, v[140:143] offset:2048
	ds_write_b128 v112, v[144:147] offset:3072
	v_mfma_f32_32x32x16_bf16 v[32:47], v[192:195], v[52:55], v[32:47]
	v_mfma_f32_32x32x16_bf16 v[32:47], v[196:199], v[56:59], v[32:47]
	v_mfma_f32_32x32x16_bf16 v[32:47], v[200:203], v[60:63], v[32:47]
	s_nop 11
	v_exp_f32_e32 v32, v32
	v_exp_f32_e32 v33, v33
	v_exp_f32_e32 v34, v34
	v_exp_f32_e32 v35, v35
	v_exp_f32_e32 v36, v36
	v_exp_f32_e32 v37, v37
	v_exp_f32_e32 v38, v38
	v_exp_f32_e32 v39, v39
	v_exp_f32_e32 v40, v40
	v_exp_f32_e32 v41, v41
	v_exp_f32_e32 v42, v42
	v_exp_f32_e32 v43, v43
	v_exp_f32_e32 v44, v44
	v_exp_f32_e32 v45, v45
	v_exp_f32_e32 v46, v46
	v_exp_f32_e32 v47, v47
	v_cvt_pk_bf16_f32 v64, v32, v33
	v_cvt_pk_bf16_f32 v65, v34, v35
	v_cvt_pk_bf16_f32 v66, v36, v37
	v_cvt_pk_bf16_f32 v67, v38, v39
	v_cvt_pk_bf16_f32 v68, v40, v41
	v_cvt_pk_bf16_f32 v69, v42, v43
	v_cvt_pk_bf16_f32 v70, v44, v45
	v_cvt_pk_bf16_f32 v71, v46, v47
	v_pk_add_f32 v[232:233], v[232:233], v[32:33]
	v_pk_add_f32 v[232:233], v[232:233], v[34:35]
	v_pk_add_f32 v[232:233], v[232:233], v[36:37]
	v_pk_add_f32 v[232:233], v[232:233], v[38:39]
	v_pk_add_f32 v[232:233], v[232:233], v[40:41]
	v_pk_add_f32 v[232:233], v[232:233], v[42:43]
	v_pk_add_f32 v[232:233], v[232:233], v[44:45]
	v_pk_add_f32 v[232:233], v[232:233], v[46:47]
	s_waitcnt lgkmcnt(12)
	v_mfma_f32_32x32x16_bf16 v[0:15], v[64:67], v[72:75], v[0:15]
	v_mfma_f32_32x32x16_bf16 v[16:31], v[64:67], v[76:79], v[16:31]
	v_mfma_f32_32x32x16_bf16 v[0:15], v[68:71], v[220:223], v[0:15]
	v_mfma_f32_32x32x16_bf16 v[16:31], v[68:71], v[224:227], v[16:31]
	global_load_dwordx4 v[188:191], v243, s[88:89]
	global_load_dwordx4 v[192:195], v244, s[88:89]
	global_load_dwordx4 v[196:199], v245, s[88:89]
	global_load_dwordx4 v[200:203], v246, s[88:89]
	global_load_dwordx4 v[204:207], v148, s[88:89] offset:768
	global_load_dwordx4 v[208:211], v151, s[88:89] offset:768
	global_load_dwordx4 v[212:215], v148, s[88:89] offset:832
	global_load_dwordx4 v[216:219], v151, s[88:89] offset:832
	ds_read2_b32 v[32:33], v115 offset0:64 offset1:65
	ds_read2_b32 v[34:35], v115 offset0:66 offset1:67
	ds_read2_b32 v[36:37], v115 offset0:72 offset1:73
	ds_read2_b32 v[38:39], v115 offset0:74 offset1:75
	ds_read2_b32 v[40:41], v115 offset0:80 offset1:81
	ds_read2_b32 v[42:43], v115 offset0:82 offset1:83
	ds_read2_b32 v[44:45], v115 offset0:88 offset1:89
	ds_read2_b32 v[46:47], v115 offset0:90 offset1:91
	s_waitcnt lgkmcnt(0)
	v_mfma_f32_32x32x16_bf16 v[32:47], v[116:119], v[48:51], v[32:47]
	ds_read_b64_tr_b16 v[72:73], v231
	ds_read_b64_tr_b16 v[74:75], v231 offset:512
	ds_read_b64_tr_b16 v[76:77], v231 offset:2048
	ds_read_b64_tr_b16 v[78:79], v231 offset:2560
	ds_read_b64_tr_b16 v[220:221], v231 offset:1024
	ds_read_b64_tr_b16 v[222:223], v231 offset:1536
	ds_read_b64_tr_b16 v[224:225], v231 offset:3072
	ds_read_b64_tr_b16 v[226:227], v231 offset:3584
	s_waitcnt vmcnt(8)
	ds_write_b128 v247, v[156:159]
	ds_write_b128 v247, v[160:163] offset:1024
	ds_write_b128 v247, v[164:167] offset:2048
	ds_write_b128 v247, v[168:171] offset:3072
	ds_read_b128 v[156:159], v248
	ds_read_b128 v[160:163], v249
	ds_read_b128 v[164:167], v250
	ds_read_b128 v[168:171], v251
	ds_write_b128 v112, v[172:175]
	ds_write_b128 v112, v[176:179] offset:1024
	ds_write_b128 v112, v[180:183] offset:2048
	ds_write_b128 v112, v[184:187] offset:3072
	v_mfma_f32_32x32x16_bf16 v[32:47], v[120:123], v[52:55], v[32:47]
	v_mfma_f32_32x32x16_bf16 v[32:47], v[124:127], v[56:59], v[32:47]
	v_mfma_f32_32x32x16_bf16 v[32:47], v[128:131], v[60:63], v[32:47]
	s_nop 11
	v_exp_f32_e32 v32, v32
	v_exp_f32_e32 v33, v33
	v_exp_f32_e32 v34, v34
	v_exp_f32_e32 v35, v35
	v_exp_f32_e32 v36, v36
	v_exp_f32_e32 v37, v37
	v_exp_f32_e32 v38, v38
	v_exp_f32_e32 v39, v39
	v_exp_f32_e32 v40, v40
	v_exp_f32_e32 v41, v41
	v_exp_f32_e32 v42, v42
	v_exp_f32_e32 v43, v43
	v_exp_f32_e32 v44, v44
	v_exp_f32_e32 v45, v45
	v_exp_f32_e32 v46, v46
	v_exp_f32_e32 v47, v47
	v_cvt_pk_bf16_f32 v64, v32, v33
	v_cvt_pk_bf16_f32 v65, v34, v35
	v_cvt_pk_bf16_f32 v66, v36, v37
	v_cvt_pk_bf16_f32 v67, v38, v39
	v_cvt_pk_bf16_f32 v68, v40, v41
	v_cvt_pk_bf16_f32 v69, v42, v43
	v_cvt_pk_bf16_f32 v70, v44, v45
	v_cvt_pk_bf16_f32 v71, v46, v47
	v_pk_add_f32 v[232:233], v[232:233], v[32:33]
	v_pk_add_f32 v[232:233], v[232:233], v[34:35]
	v_pk_add_f32 v[232:233], v[232:233], v[36:37]
	v_pk_add_f32 v[232:233], v[232:233], v[38:39]
	v_pk_add_f32 v[232:233], v[232:233], v[40:41]
	v_pk_add_f32 v[232:233], v[232:233], v[42:43]
	v_pk_add_f32 v[232:233], v[232:233], v[44:45]
	v_pk_add_f32 v[232:233], v[232:233], v[46:47]
	s_waitcnt lgkmcnt(12)
	v_mfma_f32_32x32x16_bf16 v[0:15], v[64:67], v[72:75], v[0:15]
	v_mfma_f32_32x32x16_bf16 v[16:31], v[64:67], v[76:79], v[16:31]
	v_mfma_f32_32x32x16_bf16 v[0:15], v[68:71], v[220:223], v[0:15]
	v_mfma_f32_32x32x16_bf16 v[16:31], v[68:71], v[224:227], v[16:31]
	ds_read2_b32 v[32:33], v115 offset0:96 offset1:97
	ds_read2_b32 v[34:35], v115 offset0:98 offset1:99
	ds_read2_b32 v[36:37], v115 offset0:104 offset1:105
	ds_read2_b32 v[38:39], v115 offset0:106 offset1:107
	ds_read2_b32 v[40:41], v115 offset0:112 offset1:113
	ds_read2_b32 v[42:43], v115 offset0:114 offset1:115
	ds_read2_b32 v[44:45], v115 offset0:120 offset1:121
	ds_read2_b32 v[46:47], v115 offset0:122 offset1:123
	s_waitcnt lgkmcnt(0)
	v_mfma_f32_32x32x16_bf16 v[32:47], v[156:159], v[48:51], v[32:47]
	ds_read_b64_tr_b16 v[72:73], v231
	ds_read_b64_tr_b16 v[74:75], v231 offset:512
	ds_read_b64_tr_b16 v[76:77], v231 offset:2048
	ds_read_b64_tr_b16 v[78:79], v231 offset:2560
	ds_read_b64_tr_b16 v[220:221], v231 offset:1024
	ds_read_b64_tr_b16 v[222:223], v231 offset:1536
	ds_read_b64_tr_b16 v[224:225], v231 offset:3072
	ds_read_b64_tr_b16 v[226:227], v231 offset:3584
	s_waitcnt vmcnt(0)
	ds_write_b128 v247, v[188:191]
	ds_write_b128 v247, v[192:195] offset:1024
	ds_write_b128 v247, v[196:199] offset:2048
	ds_write_b128 v247, v[200:203] offset:3072
	ds_read_b128 v[188:191], v248
	ds_read_b128 v[192:195], v249
	ds_read_b128 v[196:199], v250
	ds_read_b128 v[200:203], v251
	ds_write_b128 v112, v[204:207]
	ds_write_b128 v112, v[208:211] offset:1024
	ds_write_b128 v112, v[212:215] offset:2048
	ds_write_b128 v112, v[216:219] offset:3072
	v_mfma_f32_32x32x16_bf16 v[32:47], v[160:163], v[52:55], v[32:47]
	v_mfma_f32_32x32x16_bf16 v[32:47], v[164:167], v[56:59], v[32:47]
	v_mfma_f32_32x32x16_bf16 v[32:47], v[168:171], v[60:63], v[32:47]
	s_nop 11
	v_exp_f32_e32 v32, v32
	v_exp_f32_e32 v33, v33
	v_exp_f32_e32 v34, v34
	v_exp_f32_e32 v35, v35
	v_exp_f32_e32 v36, v36
	v_exp_f32_e32 v37, v37
	v_exp_f32_e32 v38, v38
	v_exp_f32_e32 v39, v39
	v_exp_f32_e32 v40, v40
	v_exp_f32_e32 v41, v41
	v_exp_f32_e32 v42, v42
	v_exp_f32_e32 v43, v43
	v_exp_f32_e32 v44, v44
	v_exp_f32_e32 v45, v45
	v_exp_f32_e32 v46, v46
	v_exp_f32_e32 v47, v47
	v_cvt_pk_bf16_f32 v64, v32, v33
	v_cvt_pk_bf16_f32 v65, v34, v35
	v_cvt_pk_bf16_f32 v66, v36, v37
	v_cvt_pk_bf16_f32 v67, v38, v39
	v_cvt_pk_bf16_f32 v68, v40, v41
	v_cvt_pk_bf16_f32 v69, v42, v43
	v_cvt_pk_bf16_f32 v70, v44, v45
	v_cvt_pk_bf16_f32 v71, v46, v47
	v_pk_add_f32 v[232:233], v[232:233], v[32:33]
	v_pk_add_f32 v[232:233], v[232:233], v[34:35]
	v_pk_add_f32 v[232:233], v[232:233], v[36:37]
	v_pk_add_f32 v[232:233], v[232:233], v[38:39]
	v_pk_add_f32 v[232:233], v[232:233], v[40:41]
	v_pk_add_f32 v[232:233], v[232:233], v[42:43]
	v_pk_add_f32 v[232:233], v[232:233], v[44:45]
	v_pk_add_f32 v[232:233], v[232:233], v[46:47]
	s_waitcnt lgkmcnt(12)
	v_mfma_f32_32x32x16_bf16 v[0:15], v[64:67], v[72:75], v[0:15]
	v_mfma_f32_32x32x16_bf16 v[16:31], v[64:67], v[76:79], v[16:31]
	v_mfma_f32_32x32x16_bf16 v[0:15], v[68:71], v[220:223], v[0:15]
	v_mfma_f32_32x32x16_bf16 v[16:31], v[68:71], v[224:227], v[16:31]
	ds_read2_b32 v[32:33], v115 offset0:128 offset1:129
	ds_read2_b32 v[34:35], v115 offset0:130 offset1:131
	ds_read2_b32 v[36:37], v115 offset0:136 offset1:137
	ds_read2_b32 v[38:39], v115 offset0:138 offset1:139
	ds_read2_b32 v[40:41], v115 offset0:144 offset1:145
	ds_read2_b32 v[42:43], v115 offset0:146 offset1:147
	ds_read2_b32 v[44:45], v115 offset0:152 offset1:153
	ds_read2_b32 v[46:47], v115 offset0:154 offset1:155
	s_waitcnt lgkmcnt(0)
; #define LAS __attribute__((address_space(3)))
; #define GAS __attribute__((address_space(1)))
; __device__ __forceinline__ void dil_unit(LAS unsigned char* lds, bf16_t* proj, int seq, int hd, int T0, int rho) {
;     int tid_ = threadIdx.x; asm volatile("" : "+v"(tid_));
;     const int tid = tid_, lane = tid & 63, r32 = lane & 31, hi = lane >> 5, wid = __builtin_amdgcn_readfirstlane(tid >> 6);
;     bf16_t* base = proj + (size_t)seq * SEQ * NIN;
;     LAS unsigned char* wbuf = lds + wid * 4096;
;     const LAS unsigned char* vp = wbuf + ((lane >> 4) & 1) * 32 + (lane & 3) * 8 + (4 * hi + ((lane & 15) >> 2)) * 64;
;     const int P0 = T0 + rho;
;     bf16x8 qr[4];
; #pragma unroll
;     for (int ks = 0; ks < 4; ++ks) qr[ks] = *(const GAS bf16x8*)(base + (size_t)(P0 + 16 * r32) * NIN + PC_LQ + hd * 64 + 16 * ks + 8 * hi);
;     f32x16 o0 = {}, o1 = {}; float l = 0.f;
;     const bool bound = (T0 < 1024) || (T0 >= 15360);
	v_mfma_f32_32x32x16_bf16 v[32:47], v[188:191], v[48:51], v[32:47]
	ds_read_b64_tr_b16 v[72:73], v231
	ds_read_b64_tr_b16 v[74:75], v231 offset:512
	ds_read_b64_tr_b16 v[76:77], v231 offset:2048
	ds_read_b64_tr_b16 v[78:79], v231 offset:2560
	ds_read_b64_tr_b16 v[220:221], v231 offset:1024
	ds_read_b64_tr_b16 v[222:223], v231 offset:1536
	ds_read_b64_tr_b16 v[224:225], v231 offset:3072
	ds_read_b64_tr_b16 v[226:227], v231 offset:3584
	v_mfma_f32_32x32x16_bf16 v[32:47], v[192:195], v[52:55], v[32:47]
	v_mfma_f32_32x32x16_bf16 v[32:47], v[196:199], v[56:59], v[32:47]
	v_mfma_f32_32x32x16_bf16 v[32:47], v[200:203], v[60:63], v[32:47]
	s_nop 11
	v_exp_f32_e32 v32, v32
	v_exp_f32_e32 v33, v33
	v_exp_f32_e32 v34, v34
	v_exp_f32_e32 v35, v35
	v_exp_f32_e32 v36, v36
	v_exp_f32_e32 v37, v37
	v_exp_f32_e32 v38, v38
	v_exp_f32_e32 v39, v39
	v_exp_f32_e32 v40, v40
	v_exp_f32_e32 v41, v41
	v_exp_f32_e32 v42, v42
	v_exp_f32_e32 v43, v43
	v_exp_f32_e32 v44, v44
	v_exp_f32_e32 v45, v45
	v_exp_f32_e32 v46, v46
	v_exp_f32_e32 v47, v47
	v_cvt_pk_bf16_f32 v64, v32, v33
	v_cvt_pk_bf16_f32 v65, v34, v35
	v_cvt_pk_bf16_f32 v66, v36, v37
	v_cvt_pk_bf16_f32 v67, v38, v39
	v_cvt_pk_bf16_f32 v68, v40, v41
	v_cvt_pk_bf16_f32 v69, v42, v43
	v_cvt_pk_bf16_f32 v70, v44, v45
	v_cvt_pk_bf16_f32 v71, v46, v47
	v_pk_add_f32 v[232:233], v[232:233], v[32:33]
	v_pk_add_f32 v[232:233], v[232:233], v[34:35]
	v_pk_add_f32 v[232:233], v[232:233], v[36:37]
	v_pk_add_f32 v[232:233], v[232:233], v[38:39]
	v_pk_add_f32 v[232:233], v[232:233], v[40:41]
	v_pk_add_f32 v[232:233], v[232:233], v[42:43]
	v_pk_add_f32 v[232:233], v[232:233], v[44:45]
	v_pk_add_f32 v[232:233], v[232:233], v[46:47]
	s_waitcnt lgkmcnt(0)
	v_mfma_f32_32x32x16_bf16 v[0:15], v[64:67], v[72:75], v[0:15]
	v_mfma_f32_32x32x16_bf16 v[16:31], v[64:67], v[76:79], v[16:31]
	v_mfma_f32_32x32x16_bf16 v[0:15], v[68:71], v[220:223], v[0:15]
	v_mfma_f32_32x32x16_bf16 v[16:31], v[68:71], v[224:227], v[16:31]
	v_add_f32_e32 v113, v232, v233
	v_or_b32_e32 v114, 1, v107
	v_or_b32_e32 v97, 2, v107
	v_or_b32_e32 v96, 3, v107
	v_or_b32_e32 v95, 8, v107
	v_or_b32_e32 v94, 9, v107
	v_or_b32_e32 v93, 10, v107
	v_or_b32_e32 v92, 11, v107
	v_or_b32_e32 v91, 16, v107
	v_or_b32_e32 v90, 17, v107
	v_or_b32_e32 v89, 18, v107
	v_or_b32_e32 v88, 19, v107
	v_or_b32_e32 v87, 24, v107
	v_or_b32_e32 v86, 25, v107
	v_or_b32_e32 v85, 26, v107
	v_or_b32_e32 v84, 27, v107
	s_nop 11
	s_branch .LBB0_553
.LBB0_558:
	s_movk_i32 s100, 0x1800
	s_add_i32 s101, s6, 0x15c00
	s_lshl_b32 s90, s58, 1
	s_add_u32 s82, s56, s90
	s_addc_u32 s83, s57, 0
	s_add_u32 s82, s82, 0x1200
	s_addc_u32 s83, s83, 0
	s_sub_i32 s90, s76, 64
	s_mul_i32 s90, s90, 0x1800
	s_add_u32 s84, s82, s90
	s_addc_u32 s85, s83, 0
	s_sub_i32 s90, s76, 256
	s_mul_i32 s90, s90, 0x1800
	s_add_u32 s86, s82, s90
	s_addc_u32 s87, s83, 0
	s_sub_i32 s90, s76, 1024
	s_mul_i32 s90, s90, 0x1800
	s_add_u32 s88, s82, s90
	s_addc_u32 s89, s83, 0
	v_lshlrev_b32_e32 v153, 1, v98
	v_mad_u32_u24 v80, v105, s100, v82
	v_mad_u32_u24 v100, v110, s100, v153
	v_add_u32_e32 v149, 0x18000, v100
	v_lshlrev_b32_e32 v83, 2, v105
	v_mad_u32_u24 v83, v83, s100, v82
	v_lshlrev_b32_e32 v101, 2, v110
	v_mad_u32_u24 v101, v101, s100, v153
	v_add_u32_e32 v150, 0x60000, v101
	v_lshlrev_b32_e32 v99, 4, v105
	v_mad_u32_u24 v99, v99, s100, v82
	v_lshlrev_b32_e32 v148, 4, v110
	v_mad_u32_u24 v148, v148, s100, v153
	v_add_u32_e32 v151, 0x180000, v148
	v_lshrrev_b32_e32 v249, 3, v103
	v_and_b32_e32 v250, 7, v103
	v_lshlrev_b32_e32 v250, 4, v250
	v_add_u32_e32 v235, 0, v249
	v_add_u32_e32 v236, 8, v249
	v_add_u32_e32 v237, 16, v249
	v_add_u32_e32 v238, 24, v249
	v_add_u32_e32 v239, 0, v249
	v_lshlrev_b32_e32 v239, 2, v239
	v_add_u32_e32 v240, 8, v249
	v_lshlrev_b32_e32 v240, 2, v240
	v_add_u32_e32 v241, 16, v249
	v_lshlrev_b32_e32 v241, 2, v241
	v_add_u32_e32 v242, 24, v249
	v_lshlrev_b32_e32 v242, 2, v242
	v_add_u32_e32 v243, 0, v249
	v_lshlrev_b32_e32 v243, 4, v243
	v_add_u32_e32 v244, 8, v249
	v_lshlrev_b32_e32 v244, 4, v244
	v_add_u32_e32 v245, 16, v249
	v_lshlrev_b32_e32 v245, 4, v245
	v_add_u32_e32 v246, 24, v249
	v_lshlrev_b32_e32 v246, 4, v246
	v_mov_b32_e32 v252, v250
	v_mov_b32_e32 v100, v110
	v_add_u32_e32 v149, 16, v100
	v_lshlrev_b32_e32 v101, 2, v110
	v_add_u32_e32 v150, 64, v101
	v_lshlrev_b32_e32 v148, 4, v110
	v_add_u32_e32 v151, 256, v148
	s_mov_b32 s98, 0x4000
	s_mov_b32 s99, 0x3fff
	v_and_b32_e32 v247, 7, v249
	v_lshlrev_b32_e32 v247, 4, v247
	v_xor_b32_e32 v247, v247, v112
	v_and_b32_e32 v153, 7, v105
	v_or_b32_e32 v248, 0, v106
	v_xor_b32_e32 v248, v248, v153
	v_lshlrev_b32_e32 v248, 4, v248
	v_lshl_add_u32 v248, v105, 7, v248
	v_add_u32_e32 v248, s77, v248
	v_or_b32_e32 v249, 2, v106
	v_xor_b32_e32 v249, v249, v153
	v_lshlrev_b32_e32 v249, 4, v249
	v_lshl_add_u32 v249, v105, 7, v249
	v_add_u32_e32 v249, s77, v249
	v_or_b32_e32 v250, 4, v106
	v_xor_b32_e32 v250, v250, v153
	v_lshlrev_b32_e32 v250, 4, v250
	v_lshl_add_u32 v250, v105, 7, v250
	v_add_u32_e32 v250, s77, v250
	v_or_b32_e32 v251, 6, v106
	v_xor_b32_e32 v251, v251, v153
	v_lshlrev_b32_e32 v251, 4, v251
	v_lshl_add_u32 v251, v105, 7, v251
	v_add_u32_e32 v251, s77, v251
	v_lshlrev_b32_e32 v153, 1, v98
	v_mul_u32_u24_e32 v228, 17, v105
	v_sub_u32_e32 v228, v107, v228
	s_mul_i32 s90, s58, 153
	s_lshr_b32 s90, s90, 1
	s_add_i32 s90, s90, 34876
	v_lshl_add_u32 v228, v228, 2, s90
	v_mul_u32_u24_e32 v229, 5, v105
	v_sub_u32_e32 v229, v107, v229
	v_add_u32_e32 v229, v229, v106
	s_mul_i32 s90, s58, 30
	s_add_i32 s90, s90, 66156
	v_lshl_add_u32 v229, v229, 2, s90
	v_sub_u32_e32 v230, v107, v105
	s_add_i32 s90, s101, 6364
	v_lshl_add_u32 v230, v230, 2, s90
; __device__ __forceinline__ void dil_unit(LAS unsigned char* lds, bf16_t* proj, int seq, int hd, int T0, int rho) {
;     ...
;     f32x16 o0 = {}, o1 = {}; float l = 0.f;
;     const bool bound = (T0 < 1024) || (T0 >= 15360);
	v_add_u32_e32 v231, v109, v108
	v_mov_b64_e32 v[232:233], 0
	v_mov_b64_e32 v[0:1], 0
	v_mov_b64_e32 v[2:3], 0
	v_mov_b64_e32 v[4:5], 0
	v_mov_b64_e32 v[6:7], 0
	v_mov_b64_e32 v[8:9], 0
	v_mov_b64_e32 v[10:11], 0
	v_mov_b64_e32 v[12:13], 0
	v_mov_b64_e32 v[14:15], 0
	v_mov_b64_e32 v[16:17], 0
	v_mov_b64_e32 v[18:19], 0
	v_mov_b64_e32 v[20:21], 0
	v_mov_b64_e32 v[22:23], 0
	v_mov_b64_e32 v[24:25], 0
	v_mov_b64_e32 v[26:27], 0
	v_mov_b64_e32 v[28:29], 0
	v_mov_b64_e32 v[30:31], 0
	s_add_i32 s90, s76, -64
	v_add_u32_e32 v80, s90, v235
	v_add_u32_e32 v83, s90, v236
	v_add_u32_e32 v99, s90, v237
	v_add_u32_e32 v253, s90, v238
	v_add_u32_e32 v254, s90, v100
	v_add_u32_e32 v255, s90, v149
	v_med3_i32 v80, v80, 0, s99
	v_med3_i32 v83, v83, 0, s99
	v_med3_i32 v99, v99, 0, s99
	v_med3_i32 v253, v253, 0, s99
	v_med3_i32 v254, v254, 0, s99
	v_med3_i32 v255, v255, 0, s99
	v_mad_u32_u24 v80, v80, s100, v252
	v_mad_u32_u24 v83, v83, s100, v252
	v_mad_u32_u24 v99, v99, s100, v252
	v_mad_u32_u24 v253, v253, s100, v252
	v_mad_u32_u24 v254, v254, s100, v153
	v_mad_u32_u24 v255, v255, s100, v153
	global_load_dwordx4 v[116:119], v80, s[82:83]
	global_load_dwordx4 v[120:123], v83, s[82:83]
	global_load_dwordx4 v[124:127], v99, s[82:83]
	global_load_dwordx4 v[128:131], v253, s[82:83]
	global_load_dwordx4 v[132:135], v254, s[82:83] offset:768
	global_load_dwordx4 v[136:139], v255, s[82:83] offset:768
	global_load_dwordx4 v[140:143], v254, s[82:83] offset:832
	global_load_dwordx4 v[144:147], v255, s[82:83] offset:832
	s_add_i32 s90, s76, -32
	v_add_u32_e32 v80, s90, v235
	v_add_u32_e32 v83, s90, v236
	v_add_u32_e32 v99, s90, v237
	v_add_u32_e32 v253, s90, v238
	v_add_u32_e32 v254, s90, v100
	v_add_u32_e32 v255, s90, v149
	v_med3_i32 v80, v80, 0, s99
	v_med3_i32 v83, v83, 0, s99
	v_med3_i32 v99, v99, 0, s99
	v_med3_i32 v253, v253, 0, s99
	v_med3_i32 v254, v254, 0, s99
	v_med3_i32 v255, v255, 0, s99
	v_mad_u32_u24 v80, v80, s100, v252
	v_mad_u32_u24 v83, v83, s100, v252
	v_mad_u32_u24 v99, v99, s100, v252
	v_mad_u32_u24 v253, v253, s100, v252
	v_mad_u32_u24 v254, v254, s100, v153
	v_mad_u32_u24 v255, v255, s100, v153
	global_load_dwordx4 v[156:159], v80, s[82:83]
	global_load_dwordx4 v[160:163], v83, s[82:83]
	global_load_dwordx4 v[164:167], v99, s[82:83]
	global_load_dwordx4 v[168:171], v253, s[82:83]
	global_load_dwordx4 v[172:175], v254, s[82:83] offset:768
	global_load_dwordx4 v[176:179], v255, s[82:83] offset:768
	global_load_dwordx4 v[180:183], v254, s[82:83] offset:832
	global_load_dwordx4 v[184:187], v255, s[82:83] offset:832
	s_add_i32 s90, s76, 0
	v_add_u32_e32 v80, s90, v235
	v_add_u32_e32 v83, s90, v236
	v_add_u32_e32 v99, s90, v237
	v_add_u32_e32 v253, s90, v238
	v_add_u32_e32 v254, s90, v100
	v_add_u32_e32 v255, s90, v149
	v_med3_i32 v80, v80, 0, s99
	v_med3_i32 v83, v83, 0, s99
	v_med3_i32 v99, v99, 0, s99
	v_med3_i32 v253, v253, 0, s99
	v_med3_i32 v254, v254, 0, s99
	v_med3_i32 v255, v255, 0, s99
	v_mad_u32_u24 v80, v80, s100, v252
	v_mad_u32_u24 v83, v83, s100, v252
	v_mad_u32_u24 v99, v99, s100, v252
	v_mad_u32_u24 v253, v253, s100, v252
	v_mad_u32_u24 v254, v254, s100, v153
	v_mad_u32_u24 v255, v255, s100, v153
	global_load_dwordx4 v[188:191], v80, s[82:83]
	global_load_dwordx4 v[192:195], v83, s[82:83]
	global_load_dwordx4 v[196:199], v99, s[82:83]
	global_load_dwordx4 v[200:203], v253, s[82:83]
	global_load_dwordx4 v[204:207], v254, s[82:83] offset:768
	global_load_dwordx4 v[208:211], v255, s[82:83] offset:768
	global_load_dwordx4 v[212:215], v254, s[82:83] offset:832
	global_load_dwordx4 v[216:219], v255, s[82:83] offset:832
	s_waitcnt vmcnt(16)
	ds_write_b128 v247, v[116:119]
	ds_write_b128 v247, v[120:123] offset:1024
	ds_write_b128 v247, v[124:127] offset:2048
	ds_write_b128 v247, v[128:131] offset:3072
	ds_read_b128 v[116:119], v248
	ds_read_b128 v[120:123], v249
	ds_read_b128 v[124:127], v250
	ds_read_b128 v[128:131], v251
	ds_write_b128 v112, v[132:135]
	ds_write_b128 v112, v[136:139] offset:1024
	ds_write_b128 v112, v[140:143] offset:2048
	ds_write_b128 v112, v[144:147] offset:3072
	v_mov_b32_e32 v115, v228
	ds_read2_b32 v[32:33], v115 offset0:0 offset1:1
	ds_read2_b32 v[34:35], v115 offset0:2 offset1:3
	ds_read2_b32 v[36:37], v115 offset0:8 offset1:9
	ds_read2_b32 v[38:39], v115 offset0:10 offset1:11
	ds_read2_b32 v[40:41], v115 offset0:17 offset1:18
	ds_read2_b32 v[42:43], v115 offset0:19 offset1:20
	ds_read2_b32 v[44:45], v115 offset0:25 offset1:26
	ds_read2_b32 v[46:47], v115 offset0:27 offset1:28
	s_waitcnt lgkmcnt(0)
	v_mfma_f32_32x32x16_bf16 v[32:47], v[116:119], v[48:51], v[32:47]
	ds_read_b64_tr_b16 v[72:73], v231
	ds_read_b64_tr_b16 v[74:75], v231 offset:512
	ds_read_b64_tr_b16 v[76:77], v231 offset:2048
	ds_read_b64_tr_b16 v[78:79], v231 offset:2560
	ds_read_b64_tr_b16 v[220:221], v231 offset:1024
	ds_read_b64_tr_b16 v[222:223], v231 offset:1536
	ds_read_b64_tr_b16 v[224:225], v231 offset:3072
	ds_read_b64_tr_b16 v[226:227], v231 offset:3584
	s_waitcnt vmcnt(8)
	ds_write_b128 v247, v[156:159]
	ds_write_b128 v247, v[160:163] offset:1024
	ds_write_b128 v247, v[164:167] offset:2048
	ds_write_b128 v247, v[168:171] offset:3072
	ds_read_b128 v[156:159], v248
	ds_read_b128 v[160:163], v249
	ds_read_b128 v[164:167], v250
	ds_read_b128 v[168:171], v251
	ds_write_b128 v112, v[172:175]
	ds_write_b128 v112, v[176:179] offset:1024
	ds_write_b128 v112, v[180:183] offset:2048
	ds_write_b128 v112, v[184:187] offset:3072
	v_mfma_f32_32x32x16_bf16 v[32:47], v[120:123], v[52:55], v[32:47]
	v_mfma_f32_32x32x16_bf16 v[32:47], v[124:127], v[56:59], v[32:47]
	v_mfma_f32_32x32x16_bf16 v[32:47], v[128:131], v[60:63], v[32:47]
	s_nop 11
	v_exp_f32_e32 v32, v32
	v_exp_f32_e32 v33, v33
	v_exp_f32_e32 v34, v34
	v_exp_f32_e32 v35, v35
	v_exp_f32_e32 v36, v36
	v_exp_f32_e32 v37, v37
	v_exp_f32_e32 v38, v38
	v_exp_f32_e32 v39, v39
	v_exp_f32_e32 v40, v40
	v_exp_f32_e32 v41, v41
	v_exp_f32_e32 v42, v42
	v_exp_f32_e32 v43, v43
	v_exp_f32_e32 v44, v44
	v_exp_f32_e32 v45, v45
	v_exp_f32_e32 v46, v46
	v_exp_f32_e32 v47, v47
	s_add_i32 s90, s76, -64
	v_add_u32_e32 v84, s90, v107
	v_add_u32_e32 v85, 0, v84
	v_add_u32_e32 v86, 1, v84
	v_add_u32_e32 v87, 2, v84
	v_add_u32_e32 v88, 3, v84
	v_cmp_gt_u32_e64 s[30:31], s98, v85
	v_cmp_gt_u32_e64 s[36:37], s98, v86
	v_cmp_gt_u32_e64 s[78:79], s98, v87
	v_cmp_gt_u32_e64 s[50:51], s98, v88
	v_cndmask_b32_e64 v32, 0, v32, s[30:31]
	v_add_u32_e32 v85, 8, v84
	v_cmp_gt_u32_e64 s[30:31], s98, v85
	v_cndmask_b32_e64 v33, 0, v33, s[36:37]
	v_add_u32_e32 v86, 9, v84
	v_cmp_gt_u32_e64 s[36:37], s98, v86
	v_cndmask_b32_e64 v34, 0, v34, s[78:79]
	v_add_u32_e32 v87, 10, v84
	v_cmp_gt_u32_e64 s[78:79], s98, v87
	v_cndmask_b32_e64 v35, 0, v35, s[50:51]
	v_add_u32_e32 v88, 11, v84
	v_cmp_gt_u32_e64 s[50:51], s98, v88
	v_cndmask_b32_e64 v36, 0, v36, s[30:31]
	v_add_u32_e32 v85, 16, v84
	v_cmp_gt_u32_e64 s[30:31], s98, v85
	v_cndmask_b32_e64 v37, 0, v37, s[36:37]
	v_add_u32_e32 v86, 17, v84
	v_cmp_gt_u32_e64 s[36:37], s98, v86
	v_cndmask_b32_e64 v38, 0, v38, s[78:79]
	v_add_u32_e32 v87, 18, v84
	v_cmp_gt_u32_e64 s[78:79], s98, v87
	v_cndmask_b32_e64 v39, 0, v39, s[50:51]
	v_add_u32_e32 v88, 19, v84
	v_cmp_gt_u32_e64 s[50:51], s98, v88
	v_cndmask_b32_e64 v40, 0, v40, s[30:31]
	v_add_u32_e32 v85, 24, v84
	v_cmp_gt_u32_e64 s[30:31], s98, v85
	v_cndmask_b32_e64 v41, 0, v41, s[36:37]
	v_add_u32_e32 v86, 25, v84
	v_cmp_gt_u32_e64 s[36:37], s98, v86
	v_cndmask_b32_e64 v42, 0, v42, s[78:79]
	v_add_u32_e32 v87, 26, v84
	v_cmp_gt_u32_e64 s[78:79], s98, v87
	v_cndmask_b32_e64 v43, 0, v43, s[50:51]
	v_add_u32_e32 v88, 27, v84
	v_cmp_gt_u32_e64 s[50:51], s98, v88
	v_nop
	v_cndmask_b32_e64 v44, 0, v44, s[30:31]
	v_cndmask_b32_e64 v45, 0, v45, s[36:37]
	v_cndmask_b32_e64 v46, 0, v46, s[78:79]
	v_cndmask_b32_e64 v47, 0, v47, s[50:51]
	v_cvt_pk_bf16_f32 v64, v32, v33
	v_cvt_pk_bf16_f32 v65, v34, v35
	v_cvt_pk_bf16_f32 v66, v36, v37
	v_cvt_pk_bf16_f32 v67, v38, v39
	v_cvt_pk_bf16_f32 v68, v40, v41
	v_cvt_pk_bf16_f32 v69, v42, v43
	v_cvt_pk_bf16_f32 v70, v44, v45
	v_cvt_pk_bf16_f32 v71, v46, v47
	v_pk_add_f32 v[232:233], v[232:233], v[32:33]
	v_pk_add_f32 v[232:233], v[232:233], v[34:35]
	v_pk_add_f32 v[232:233], v[232:233], v[36:37]
	v_pk_add_f32 v[232:233], v[232:233], v[38:39]
	v_pk_add_f32 v[232:233], v[232:233], v[40:41]
	v_pk_add_f32 v[232:233], v[232:233], v[42:43]
	v_pk_add_f32 v[232:233], v[232:233], v[44:45]
	v_pk_add_f32 v[232:233], v[232:233], v[46:47]
	s_waitcnt lgkmcnt(12)
	v_mfma_f32_32x32x16_bf16 v[0:15], v[64:67], v[72:75], v[0:15]
	v_mfma_f32_32x32x16_bf16 v[16:31], v[64:67], v[76:79], v[16:31]
	v_mfma_f32_32x32x16_bf16 v[0:15], v[68:71], v[220:223], v[0:15]
	v_mfma_f32_32x32x16_bf16 v[16:31], v[68:71], v[224:227], v[16:31]
	s_add_i32 s90, s76, 32
	v_add_u32_e32 v80, s90, v235
	v_add_u32_e32 v83, s90, v236
	v_add_u32_e32 v99, s90, v237
	v_add_u32_e32 v253, s90, v238
	v_add_u32_e32 v254, s90, v100
	v_add_u32_e32 v255, s90, v149
	v_med3_i32 v80, v80, 0, s99
	v_med3_i32 v83, v83, 0, s99
	v_med3_i32 v99, v99, 0, s99
	v_med3_i32 v253, v253, 0, s99
	v_med3_i32 v254, v254, 0, s99
	v_med3_i32 v255, v255, 0, s99
	v_mad_u32_u24 v80, v80, s100, v252
	v_mad_u32_u24 v83, v83, s100, v252
	v_mad_u32_u24 v99, v99, s100, v252
	v_mad_u32_u24 v253, v253, s100, v252
	v_mad_u32_u24 v254, v254, s100, v153
	v_mad_u32_u24 v255, v255, s100, v153
	global_load_dwordx4 v[116:119], v80, s[82:83]
	global_load_dwordx4 v[120:123], v83, s[82:83]
	global_load_dwordx4 v[124:127], v99, s[82:83]
	global_load_dwordx4 v[128:131], v253, s[82:83]
	global_load_dwordx4 v[132:135], v254, s[82:83] offset:768
	global_load_dwordx4 v[136:139], v255, s[82:83] offset:768
	global_load_dwordx4 v[140:143], v254, s[82:83] offset:832
	global_load_dwordx4 v[144:147], v255, s[82:83] offset:832
	ds_read2_b32 v[32:33], v115 offset0:34 offset1:35
	ds_read2_b32 v[34:35], v115 offset0:36 offset1:37
	ds_read2_b32 v[36:37], v115 offset0:42 offset1:43
	ds_read2_b32 v[38:39], v115 offset0:44 offset1:45
	ds_read2_b32 v[40:41], v115 offset0:51 offset1:52
	ds_read2_b32 v[42:43], v115 offset0:53 offset1:54
	ds_read2_b32 v[44:45], v115 offset0:59 offset1:60
	ds_read2_b32 v[46:47], v115 offset0:61 offset1:62
	s_waitcnt lgkmcnt(0)
	v_mfma_f32_32x32x16_bf16 v[32:47], v[156:159], v[48:51], v[32:47]
	ds_read_b64_tr_b16 v[72:73], v231
	ds_read_b64_tr_b16 v[74:75], v231 offset:512
	ds_read_b64_tr_b16 v[76:77], v231 offset:2048
	ds_read_b64_tr_b16 v[78:79], v231 offset:2560
	ds_read_b64_tr_b16 v[220:221], v231 offset:1024
	ds_read_b64_tr_b16 v[222:223], v231 offset:1536
	ds_read_b64_tr_b16 v[224:225], v231 offset:3072
	ds_read_b64_tr_b16 v[226:227], v231 offset:3584
	s_waitcnt vmcnt(8)
	ds_write_b128 v247, v[188:191]
	ds_write_b128 v247, v[192:195] offset:1024
	ds_write_b128 v247, v[196:199] offset:2048
	ds_write_b128 v247, v[200:203] offset:3072
	ds_read_b128 v[188:191], v248
	ds_read_b128 v[192:195], v249
	ds_read_b128 v[196:199], v250
	ds_read_b128 v[200:203], v251
	ds_write_b128 v112, v[204:207]
	ds_write_b128 v112, v[208:211] offset:1024
	ds_write_b128 v112, v[212:215] offset:2048
	ds_write_b128 v112, v[216:219] offset:3072
	v_mfma_f32_32x32x16_bf16 v[32:47], v[160:163], v[52:55], v[32:47]
	v_mfma_f32_32x32x16_bf16 v[32:47], v[164:167], v[56:59], v[32:47]
	v_mfma_f32_32x32x16_bf16 v[32:47], v[168:171], v[60:63], v[32:47]
	s_nop 11
	v_exp_f32_e32 v32, v32
	v_exp_f32_e32 v33, v33
	v_exp_f32_e32 v34, v34
	v_exp_f32_e32 v35, v35
	v_exp_f32_e32 v36, v36
	v_exp_f32_e32 v37, v37
	v_exp_f32_e32 v38, v38
	v_exp_f32_e32 v39, v39
	v_exp_f32_e32 v40, v40
	v_exp_f32_e32 v41, v41
	v_exp_f32_e32 v42, v42
	v_exp_f32_e32 v43, v43
	v_exp_f32_e32 v44, v44
	v_exp_f32_e32 v45, v45
	v_exp_f32_e32 v46, v46
	v_exp_f32_e32 v47, v47
	s_add_i32 s90, s76, -32
	v_add_u32_e32 v84, s90, v107
	v_add_u32_e32 v85, 0, v84
	v_add_u32_e32 v86, 1, v84
	v_add_u32_e32 v87, 2, v84
	v_add_u32_e32 v88, 3, v84
	v_cmp_gt_u32_e64 s[30:31], s98, v85
	v_cmp_gt_u32_e64 s[36:37], s98, v86
	v_cmp_gt_u32_e64 s[78:79], s98, v87
	v_cmp_gt_u32_e64 s[50:51], s98, v88
	v_cndmask_b32_e64 v32, 0, v32, s[30:31]
	v_add_u32_e32 v85, 8, v84
	v_cmp_gt_u32_e64 s[30:31], s98, v85
	v_cndmask_b32_e64 v33, 0, v33, s[36:37]
	v_add_u32_e32 v86, 9, v84
	v_cmp_gt_u32_e64 s[36:37], s98, v86
	v_cndmask_b32_e64 v34, 0, v34, s[78:79]
	v_add_u32_e32 v87, 10, v84
	v_cmp_gt_u32_e64 s[78:79], s98, v87
	v_cndmask_b32_e64 v35, 0, v35, s[50:51]
	v_add_u32_e32 v88, 11, v84
	v_cmp_gt_u32_e64 s[50:51], s98, v88
	v_cndmask_b32_e64 v36, 0, v36, s[30:31]
	v_add_u32_e32 v85, 16, v84
	v_cmp_gt_u32_e64 s[30:31], s98, v85
	v_cndmask_b32_e64 v37, 0, v37, s[36:37]
	v_add_u32_e32 v86, 17, v84
	v_cmp_gt_u32_e64 s[36:37], s98, v86
	v_cndmask_b32_e64 v38, 0, v38, s[78:79]
	v_add_u32_e32 v87, 18, v84
	v_cmp_gt_u32_e64 s[78:79], s98, v87
	v_cndmask_b32_e64 v39, 0, v39, s[50:51]
	v_add_u32_e32 v88, 19, v84
	v_cmp_gt_u32_e64 s[50:51], s98, v88
	v_cndmask_b32_e64 v40, 0, v40, s[30:31]
	v_add_u32_e32 v85, 24, v84
	v_cmp_gt_u32_e64 s[30:31], s98, v85
	v_cndmask_b32_e64 v41, 0, v41, s[36:37]
	v_add_u32_e32 v86, 25, v84
	v_cmp_gt_u32_e64 s[36:37], s98, v86
	v_cndmask_b32_e64 v42, 0, v42, s[78:79]
	v_add_u32_e32 v87, 26, v84
	v_cmp_gt_u32_e64 s[78:79], s98, v87
	v_cndmask_b32_e64 v43, 0, v43, s[50:51]
	v_add_u32_e32 v88, 27, v84
	v_cmp_gt_u32_e64 s[50:51], s98, v88
	v_nop
	v_cndmask_b32_e64 v44, 0, v44, s[30:31]
	v_cndmask_b32_e64 v45, 0, v45, s[36:37]
	v_cndmask_b32_e64 v46, 0, v46, s[78:79]
	v_cndmask_b32_e64 v47, 0, v47, s[50:51]
	v_cvt_pk_bf16_f32 v64, v32, v33
	v_cvt_pk_bf16_f32 v65, v34, v35
	v_cvt_pk_bf16_f32 v66, v36, v37
	v_cvt_pk_bf16_f32 v67, v38, v39
	v_cvt_pk_bf16_f32 v68, v40, v41
	v_cvt_pk_bf16_f32 v69, v42, v43
	v_cvt_pk_bf16_f32 v70, v44, v45
	v_cvt_pk_bf16_f32 v71, v46, v47
	v_pk_add_f32 v[232:233], v[232:233], v[32:33]
	v_pk_add_f32 v[232:233], v[232:233], v[34:35]
	v_pk_add_f32 v[232:233], v[232:233], v[36:37]
	v_pk_add_f32 v[232:233], v[232:233], v[38:39]
	v_pk_add_f32 v[232:233], v[232:233], v[40:41]
	v_pk_add_f32 v[232:233], v[232:233], v[42:43]
	v_pk_add_f32 v[232:233], v[232:233], v[44:45]
	v_pk_add_f32 v[232:233], v[232:233], v[46:47]
	s_waitcnt lgkmcnt(12)
	v_mfma_f32_32x32x16_bf16 v[0:15], v[64:67], v[72:75], v[0:15]
	v_mfma_f32_32x32x16_bf16 v[16:31], v[64:67], v[76:79], v[16:31]
	v_mfma_f32_32x32x16_bf16 v[0:15], v[68:71], v[220:223], v[0:15]
	v_mfma_f32_32x32x16_bf16 v[16:31], v[68:71], v[224:227], v[16:31]
	s_add_i32 s90, s76, 64
	v_add_u32_e32 v80, s90, v235
	v_add_u32_e32 v83, s90, v236
	v_add_u32_e32 v99, s90, v237
	v_add_u32_e32 v253, s90, v238
	v_add_u32_e32 v254, s90, v100
	v_add_u32_e32 v255, s90, v149
	v_med3_i32 v80, v80, 0, s99
	v_med3_i32 v83, v83, 0, s99
	v_med3_i32 v99, v99, 0, s99
	v_med3_i32 v253, v253, 0, s99
	v_med3_i32 v254, v254, 0, s99
	v_med3_i32 v255, v255, 0, s99
	v_mad_u32_u24 v80, v80, s100, v252
	v_mad_u32_u24 v83, v83, s100, v252
	v_mad_u32_u24 v99, v99, s100, v252
	v_mad_u32_u24 v253, v253, s100, v252
	v_mad_u32_u24 v254, v254, s100, v153
	v_mad_u32_u24 v255, v255, s100, v153
	global_load_dwordx4 v[156:159], v80, s[82:83]
	global_load_dwordx4 v[160:163], v83, s[82:83]
	global_load_dwordx4 v[164:167], v99, s[82:83]
	global_load_dwordx4 v[168:171], v253, s[82:83]
	global_load_dwordx4 v[172:175], v254, s[82:83] offset:768
	global_load_dwordx4 v[176:179], v255, s[82:83] offset:768
	global_load_dwordx4 v[180:183], v254, s[82:83] offset:832
	global_load_dwordx4 v[184:187], v255, s[82:83] offset:832
	ds_read2_b32 v[32:33], v115 offset0:68 offset1:69
	ds_read2_b32 v[34:35], v115 offset0:70 offset1:71
	ds_read2_b32 v[36:37], v115 offset0:76 offset1:77
	ds_read2_b32 v[38:39], v115 offset0:78 offset1:79
	ds_read2_b32 v[40:41], v115 offset0:85 offset1:86
	ds_read2_b32 v[42:43], v115 offset0:87 offset1:88
	ds_read2_b32 v[44:45], v115 offset0:93 offset1:94
	ds_read2_b32 v[46:47], v115 offset0:95 offset1:96
	s_waitcnt lgkmcnt(0)
	v_mfma_f32_32x32x16_bf16 v[32:47], v[188:191], v[48:51], v[32:47]
	ds_read_b64_tr_b16 v[72:73], v231
	ds_read_b64_tr_b16 v[74:75], v231 offset:512
	ds_read_b64_tr_b16 v[76:77], v231 offset:2048
	ds_read_b64_tr_b16 v[78:79], v231 offset:2560
	ds_read_b64_tr_b16 v[220:221], v231 offset:1024
	ds_read_b64_tr_b16 v[222:223], v231 offset:1536
	ds_read_b64_tr_b16 v[224:225], v231 offset:3072
	ds_read_b64_tr_b16 v[226:227], v231 offset:3584
	s_waitcnt vmcnt(8)
	ds_write_b128 v247, v[116:119]
	ds_write_b128 v247, v[120:123] offset:1024
	ds_write_b128 v247, v[124:127] offset:2048
	ds_write_b128 v247, v[128:131] offset:3072
	ds_read_b128 v[116:119], v248
	ds_read_b128 v[120:123], v249
	ds_read_b128 v[124:127], v250
	ds_read_b128 v[128:131], v251
	ds_write_b128 v112, v[132:135]
	ds_write_b128 v112, v[136:139] offset:1024
	ds_write_b128 v112, v[140:143] offset:2048
	ds_write_b128 v112, v[144:147] offset:3072
	v_mfma_f32_32x32x16_bf16 v[32:47], v[192:195], v[52:55], v[32:47]
	v_mfma_f32_32x32x16_bf16 v[32:47], v[196:199], v[56:59], v[32:47]
	v_mfma_f32_32x32x16_bf16 v[32:47], v[200:203], v[60:63], v[32:47]
	s_nop 11
	v_exp_f32_e32 v32, v32
	v_exp_f32_e32 v33, v33
	v_exp_f32_e32 v34, v34
	v_exp_f32_e32 v35, v35
	v_exp_f32_e32 v36, v36
	v_exp_f32_e32 v37, v37
	v_exp_f32_e32 v38, v38
	v_exp_f32_e32 v39, v39
	v_exp_f32_e32 v40, v40
	v_exp_f32_e32 v41, v41
	v_exp_f32_e32 v42, v42
	v_exp_f32_e32 v43, v43
	v_exp_f32_e32 v44, v44
	v_exp_f32_e32 v45, v45
	v_exp_f32_e32 v46, v46
	v_exp_f32_e32 v47, v47
	s_add_i32 s90, s76, 0
	v_add_u32_e32 v84, s90, v107
	v_add_u32_e32 v85, 0, v84
	v_add_u32_e32 v86, 1, v84
	v_add_u32_e32 v87, 2, v84
	v_add_u32_e32 v88, 3, v84
	v_cmp_gt_u32_e64 s[30:31], s98, v85
	v_cmp_gt_u32_e64 s[36:37], s98, v86
	v_cmp_gt_u32_e64 s[78:79], s98, v87
	v_cmp_gt_u32_e64 s[50:51], s98, v88
	v_cndmask_b32_e64 v32, 0, v32, s[30:31]
	v_add_u32_e32 v85, 8, v84
	v_cmp_gt_u32_e64 s[30:31], s98, v85
	v_cndmask_b32_e64 v33, 0, v33, s[36:37]
	v_add_u32_e32 v86, 9, v84
	v_cmp_gt_u32_e64 s[36:37], s98, v86
	v_cndmask_b32_e64 v34, 0, v34, s[78:79]
	v_add_u32_e32 v87, 10, v84
	v_cmp_gt_u32_e64 s[78:79], s98, v87
	v_cndmask_b32_e64 v35, 0, v35, s[50:51]
	v_add_u32_e32 v88, 11, v84
	v_cmp_gt_u32_e64 s[50:51], s98, v88
	v_cndmask_b32_e64 v36, 0, v36, s[30:31]
	v_add_u32_e32 v85, 16, v84
	v_cmp_gt_u32_e64 s[30:31], s98, v85
	v_cndmask_b32_e64 v37, 0, v37, s[36:37]
	v_add_u32_e32 v86, 17, v84
	v_cmp_gt_u32_e64 s[36:37], s98, v86
	v_cndmask_b32_e64 v38, 0, v38, s[78:79]
	v_add_u32_e32 v87, 18, v84
	v_cmp_gt_u32_e64 s[78:79], s98, v87
	v_cndmask_b32_e64 v39, 0, v39, s[50:51]
	v_add_u32_e32 v88, 19, v84
	v_cmp_gt_u32_e64 s[50:51], s98, v88
	v_cndmask_b32_e64 v40, 0, v40, s[30:31]
	v_add_u32_e32 v85, 24, v84
	v_cmp_gt_u32_e64 s[30:31], s98, v85
	v_cndmask_b32_e64 v41, 0, v41, s[36:37]
	v_add_u32_e32 v86, 25, v84
	v_cmp_gt_u32_e64 s[36:37], s98, v86
	v_cndmask_b32_e64 v42, 0, v42, s[78:79]
	v_add_u32_e32 v87, 26, v84
	v_cmp_gt_u32_e64 s[78:79], s98, v87
	v_cndmask_b32_e64 v43, 0, v43, s[50:51]
	v_add_u32_e32 v88, 27, v84
	v_cmp_gt_u32_e64 s[50:51], s98, v88
	v_nop
	v_cndmask_b32_e64 v44, 0, v44, s[30:31]
	v_cndmask_b32_e64 v45, 0, v45, s[36:37]
	v_cndmask_b32_e64 v46, 0, v46, s[78:79]
	v_cndmask_b32_e64 v47, 0, v47, s[50:51]
	v_cvt_pk_bf16_f32 v64, v32, v33
	v_cvt_pk_bf16_f32 v65, v34, v35
	v_cvt_pk_bf16_f32 v66, v36, v37
	v_cvt_pk_bf16_f32 v67, v38, v39
	v_cvt_pk_bf16_f32 v68, v40, v41
	v_cvt_pk_bf16_f32 v69, v42, v43
	v_cvt_pk_bf16_f32 v70, v44, v45
	v_cvt_pk_bf16_f32 v71, v46, v47
	v_pk_add_f32 v[232:233], v[232:233], v[32:33]
	v_pk_add_f32 v[232:233], v[232:233], v[34:35]
	v_pk_add_f32 v[232:233], v[232:233], v[36:37]
	v_pk_add_f32 v[232:233], v[232:233], v[38:39]
	v_pk_add_f32 v[232:233], v[232:233], v[40:41]
	v_pk_add_f32 v[232:233], v[232:233], v[42:43]
	v_pk_add_f32 v[232:233], v[232:233], v[44:45]
	v_pk_add_f32 v[232:233], v[232:233], v[46:47]
	s_waitcnt lgkmcnt(12)
	v_mfma_f32_32x32x16_bf16 v[0:15], v[64:67], v[72:75], v[0:15]
	v_mfma_f32_32x32x16_bf16 v[16:31], v[64:67], v[76:79], v[16:31]
	v_mfma_f32_32x32x16_bf16 v[0:15], v[68:71], v[220:223], v[0:15]
	v_mfma_f32_32x32x16_bf16 v[16:31], v[68:71], v[224:227], v[16:31]
	s_add_i32 s90, s76, 96
	v_add_u32_e32 v80, s90, v235
	v_add_u32_e32 v83, s90, v236
	v_add_u32_e32 v99, s90, v237
	v_add_u32_e32 v253, s90, v238
	v_add_u32_e32 v254, s90, v100
	v_add_u32_e32 v255, s90, v149
	v_med3_i32 v80, v80, 0, s99
	v_med3_i32 v83, v83, 0, s99
	v_med3_i32 v99, v99, 0, s99
	v_med3_i32 v253, v253, 0, s99
	v_med3_i32 v254, v254, 0, s99
	v_med3_i32 v255, v255, 0, s99
	v_mad_u32_u24 v80, v80, s100, v252
	v_mad_u32_u24 v83, v83, s100, v252
	v_mad_u32_u24 v99, v99, s100, v252
	v_mad_u32_u24 v253, v253, s100, v252
	v_mad_u32_u24 v254, v254, s100, v153
	v_mad_u32_u24 v255, v255, s100, v153
	global_load_dwordx4 v[188:191], v80, s[82:83]
	global_load_dwordx4 v[192:195], v83, s[82:83]
	global_load_dwordx4 v[196:199], v99, s[82:83]
	global_load_dwordx4 v[200:203], v253, s[82:83]
	global_load_dwordx4 v[204:207], v254, s[82:83] offset:768
	global_load_dwordx4 v[208:211], v255, s[82:83] offset:768
	global_load_dwordx4 v[212:215], v254, s[82:83] offset:832
	global_load_dwordx4 v[216:219], v255, s[82:83] offset:832
	ds_read2_b32 v[32:33], v115 offset0:102 offset1:103
	ds_read2_b32 v[34:35], v115 offset0:104 offset1:105
	ds_read2_b32 v[36:37], v115 offset0:110 offset1:111
	ds_read2_b32 v[38:39], v115 offset0:112 offset1:113
	ds_read2_b32 v[40:41], v115 offset0:119 offset1:120
	ds_read2_b32 v[42:43], v115 offset0:121 offset1:122
	ds_read2_b32 v[44:45], v115 offset0:127 offset1:128
	ds_read2_b32 v[46:47], v115 offset0:129 offset1:130
	s_waitcnt lgkmcnt(0)
	v_mfma_f32_32x32x16_bf16 v[32:47], v[116:119], v[48:51], v[32:47]
	ds_read_b64_tr_b16 v[72:73], v231
	ds_read_b64_tr_b16 v[74:75], v231 offset:512
	ds_read_b64_tr_b16 v[76:77], v231 offset:2048
	ds_read_b64_tr_b16 v[78:79], v231 offset:2560
	ds_read_b64_tr_b16 v[220:221], v231 offset:1024
	ds_read_b64_tr_b16 v[222:223], v231 offset:1536
	ds_read_b64_tr_b16 v[224:225], v231 offset:3072
	ds_read_b64_tr_b16 v[226:227], v231 offset:3584
	s_waitcnt vmcnt(8)
	ds_write_b128 v247, v[156:159]
	ds_write_b128 v247, v[160:163] offset:1024
	ds_write_b128 v247, v[164:167] offset:2048
	ds_write_b128 v247, v[168:171] offset:3072
	ds_read_b128 v[156:159], v248
	ds_read_b128 v[160:163], v249
	ds_read_b128 v[164:167], v250
	ds_read_b128 v[168:171], v251
	ds_write_b128 v112, v[172:175]
	ds_write_b128 v112, v[176:179] offset:1024
	ds_write_b128 v112, v[180:183] offset:2048
	ds_write_b128 v112, v[184:187] offset:3072
	v_mfma_f32_32x32x16_bf16 v[32:47], v[120:123], v[52:55], v[32:47]
	v_mfma_f32_32x32x16_bf16 v[32:47], v[124:127], v[56:59], v[32:47]
	v_mfma_f32_32x32x16_bf16 v[32:47], v[128:131], v[60:63], v[32:47]
	s_nop 11
	v_exp_f32_e32 v32, v32
	v_exp_f32_e32 v33, v33
	v_exp_f32_e32 v34, v34
	v_exp_f32_e32 v35, v35
	v_exp_f32_e32 v36, v36
	v_exp_f32_e32 v37, v37
	v_exp_f32_e32 v38, v38
	v_exp_f32_e32 v39, v39
	v_exp_f32_e32 v40, v40
	v_exp_f32_e32 v41, v41
	v_exp_f32_e32 v42, v42
	v_exp_f32_e32 v43, v43
	v_exp_f32_e32 v44, v44
	v_exp_f32_e32 v45, v45
	v_exp_f32_e32 v46, v46
	v_exp_f32_e32 v47, v47
	s_add_i32 s90, s76, 32
	v_add_u32_e32 v84, s90, v107
	v_add_u32_e32 v85, 0, v84
	v_add_u32_e32 v86, 1, v84
	v_add_u32_e32 v87, 2, v84
	v_add_u32_e32 v88, 3, v84
	v_cmp_gt_u32_e64 s[30:31], s98, v85
	v_cmp_gt_u32_e64 s[36:37], s98, v86
	v_cmp_gt_u32_e64 s[78:79], s98, v87
	v_cmp_gt_u32_e64 s[50:51], s98, v88
	v_cndmask_b32_e64 v32, 0, v32, s[30:31]
	v_add_u32_e32 v85, 8, v84
	v_cmp_gt_u32_e64 s[30:31], s98, v85
	v_cndmask_b32_e64 v33, 0, v33, s[36:37]
	v_add_u32_e32 v86, 9, v84
	v_cmp_gt_u32_e64 s[36:37], s98, v86
	v_cndmask_b32_e64 v34, 0, v34, s[78:79]
	v_add_u32_e32 v87, 10, v84
	v_cmp_gt_u32_e64 s[78:79], s98, v87
	v_cndmask_b32_e64 v35, 0, v35, s[50:51]
	v_add_u32_e32 v88, 11, v84
	v_cmp_gt_u32_e64 s[50:51], s98, v88
	v_cndmask_b32_e64 v36, 0, v36, s[30:31]
	v_add_u32_e32 v85, 16, v84
	v_cmp_gt_u32_e64 s[30:31], s98, v85
	v_cndmask_b32_e64 v37, 0, v37, s[36:37]
	v_add_u32_e32 v86, 17, v84
	v_cmp_gt_u32_e64 s[36:37], s98, v86
	v_cndmask_b32_e64 v38, 0, v38, s[78:79]
	v_add_u32_e32 v87, 18, v84
	v_cmp_gt_u32_e64 s[78:79], s98, v87
	v_cndmask_b32_e64 v39, 0, v39, s[50:51]
	v_add_u32_e32 v88, 19, v84
	v_cmp_gt_u32_e64 s[50:51], s98, v88
	v_cndmask_b32_e64 v40, 0, v40, s[30:31]
	v_add_u32_e32 v85, 24, v84
	v_cmp_gt_u32_e64 s[30:31], s98, v85
	v_cndmask_b32_e64 v41, 0, v41, s[36:37]
	v_add_u32_e32 v86, 25, v84
	v_cmp_gt_u32_e64 s[36:37], s98, v86
	v_cndmask_b32_e64 v42, 0, v42, s[78:79]
	v_add_u32_e32 v87, 26, v84
	v_cmp_gt_u32_e64 s[78:79], s98, v87
	v_cndmask_b32_e64 v43, 0, v43, s[50:51]
	v_add_u32_e32 v88, 27, v84
	v_cmp_gt_u32_e64 s[50:51], s98, v88
	v_nop
	v_cndmask_b32_e64 v44, 0, v44, s[30:31]
	v_cndmask_b32_e64 v45, 0, v45, s[36:37]
	v_cndmask_b32_e64 v46, 0, v46, s[78:79]
	v_cndmask_b32_e64 v47, 0, v47, s[50:51]
	v_cvt_pk_bf16_f32 v64, v32, v33
	v_cvt_pk_bf16_f32 v65, v34, v35
	v_cvt_pk_bf16_f32 v66, v36, v37
	v_cvt_pk_bf16_f32 v67, v38, v39
	v_cvt_pk_bf16_f32 v68, v40, v41
	v_cvt_pk_bf16_f32 v69, v42, v43
	v_cvt_pk_bf16_f32 v70, v44, v45
	v_cvt_pk_bf16_f32 v71, v46, v47
	v_pk_add_f32 v[232:233], v[232:233], v[32:33]
	v_pk_add_f32 v[232:233], v[232:233], v[34:35]
	v_pk_add_f32 v[232:233], v[232:233], v[36:37]
	v_pk_add_f32 v[232:233], v[232:233], v[38:39]
	v_pk_add_f32 v[232:233], v[232:233], v[40:41]
	v_pk_add_f32 v[232:233], v[232:233], v[42:43]
	v_pk_add_f32 v[232:233], v[232:233], v[44:45]
	v_pk_add_f32 v[232:233], v[232:233], v[46:47]
	s_waitcnt lgkmcnt(12)
	v_mfma_f32_32x32x16_bf16 v[0:15], v[64:67], v[72:75], v[0:15]
	v_mfma_f32_32x32x16_bf16 v[16:31], v[64:67], v[76:79], v[16:31]
	v_mfma_f32_32x32x16_bf16 v[0:15], v[68:71], v[220:223], v[0:15]
	v_mfma_f32_32x32x16_bf16 v[16:31], v[68:71], v[224:227], v[16:31]
	s_add_i32 s90, s76, 128
	v_add_u32_e32 v80, s90, v235
	v_add_u32_e32 v83, s90, v236
	v_add_u32_e32 v99, s90, v237
	v_add_u32_e32 v253, s90, v238
	v_add_u32_e32 v254, s90, v100
	v_add_u32_e32 v255, s90, v149
	v_med3_i32 v80, v80, 0, s99
	v_med3_i32 v83, v83, 0, s99
	v_med3_i32 v99, v99, 0, s99
	v_med3_i32 v253, v253, 0, s99
	v_med3_i32 v254, v254, 0, s99
	v_med3_i32 v255, v255, 0, s99
	v_mad_u32_u24 v80, v80, s100, v252
	v_mad_u32_u24 v83, v83, s100, v252
	v_mad_u32_u24 v99, v99, s100, v252
	v_mad_u32_u24 v253, v253, s100, v252
	v_mad_u32_u24 v254, v254, s100, v153
	v_mad_u32_u24 v255, v255, s100, v153
	global_load_dwordx4 v[116:119], v80, s[82:83]
	global_load_dwordx4 v[120:123], v83, s[82:83]
	global_load_dwordx4 v[124:127], v99, s[82:83]
	global_load_dwordx4 v[128:131], v253, s[82:83]
	global_load_dwordx4 v[132:135], v254, s[82:83] offset:768
	global_load_dwordx4 v[136:139], v255, s[82:83] offset:768
	global_load_dwordx4 v[140:143], v254, s[82:83] offset:832
	global_load_dwordx4 v[144:147], v255, s[82:83] offset:832
	ds_read2_b32 v[32:33], v115 offset0:136 offset1:137
	ds_read2_b32 v[34:35], v115 offset0:138 offset1:139
	ds_read2_b32 v[36:37], v115 offset0:144 offset1:145
	ds_read2_b32 v[38:39], v115 offset0:146 offset1:147
	ds_read2_b32 v[40:41], v115 offset0:153 offset1:154
	ds_read2_b32 v[42:43], v115 offset0:155 offset1:156
	ds_read2_b32 v[44:45], v115 offset0:161 offset1:162
	ds_read2_b32 v[46:47], v115 offset0:163 offset1:164
	s_waitcnt lgkmcnt(0)
	v_mfma_f32_32x32x16_bf16 v[32:47], v[156:159], v[48:51], v[32:47]
	ds_read_b64_tr_b16 v[72:73], v231
	ds_read_b64_tr_b16 v[74:75], v231 offset:512
	ds_read_b64_tr_b16 v[76:77], v231 offset:2048
	ds_read_b64_tr_b16 v[78:79], v231 offset:2560
	ds_read_b64_tr_b16 v[220:221], v231 offset:1024
	ds_read_b64_tr_b16 v[222:223], v231 offset:1536
	ds_read_b64_tr_b16 v[224:225], v231 offset:3072
	ds_read_b64_tr_b16 v[226:227], v231 offset:3584
	s_waitcnt vmcnt(8)
	ds_write_b128 v247, v[188:191]
	ds_write_b128 v247, v[192:195] offset:1024
	ds_write_b128 v247, v[196:199] offset:2048
	ds_write_b128 v247, v[200:203] offset:3072
	ds_read_b128 v[188:191], v248
	ds_read_b128 v[192:195], v249
	ds_read_b128 v[196:199], v250
	ds_read_b128 v[200:203], v251
	ds_write_b128 v112, v[204:207]
	ds_write_b128 v112, v[208:211] offset:1024
	ds_write_b128 v112, v[212:215] offset:2048
	ds_write_b128 v112, v[216:219] offset:3072
	v_mfma_f32_32x32x16_bf16 v[32:47], v[160:163], v[52:55], v[32:47]
	v_mfma_f32_32x32x16_bf16 v[32:47], v[164:167], v[56:59], v[32:47]
	v_mfma_f32_32x32x16_bf16 v[32:47], v[168:171], v[60:63], v[32:47]
	s_nop 11
	v_exp_f32_e32 v32, v32
	v_exp_f32_e32 v33, v33
	v_exp_f32_e32 v34, v34
	v_exp_f32_e32 v35, v35
	v_exp_f32_e32 v36, v36
	v_exp_f32_e32 v37, v37
	v_exp_f32_e32 v38, v38
	v_exp_f32_e32 v39, v39
	v_exp_f32_e32 v40, v40
	v_exp_f32_e32 v41, v41
	v_exp_f32_e32 v42, v42
	v_exp_f32_e32 v43, v43
	v_exp_f32_e32 v44, v44
	v_exp_f32_e32 v45, v45
	v_exp_f32_e32 v46, v46
	v_exp_f32_e32 v47, v47
	s_add_i32 s90, s76, 64
	v_add_u32_e32 v84, s90, v107
	v_add_u32_e32 v85, 0, v84
	v_add_u32_e32 v86, 1, v84
	v_add_u32_e32 v87, 2, v84
	v_add_u32_e32 v88, 3, v84
	v_cmp_gt_u32_e64 s[30:31], s98, v85
	v_cmp_gt_u32_e64 s[36:37], s98, v86
	v_cmp_gt_u32_e64 s[78:79], s98, v87
	v_cmp_gt_u32_e64 s[50:51], s98, v88
	v_cndmask_b32_e64 v32, 0, v32, s[30:31]
	v_add_u32_e32 v85, 8, v84
	v_cmp_gt_u32_e64 s[30:31], s98, v85
	v_cndmask_b32_e64 v33, 0, v33, s[36:37]
	v_add_u32_e32 v86, 9, v84
	v_cmp_gt_u32_e64 s[36:37], s98, v86
	v_cndmask_b32_e64 v34, 0, v34, s[78:79]
	v_add_u32_e32 v87, 10, v84
	v_cmp_gt_u32_e64 s[78:79], s98, v87
	v_cndmask_b32_e64 v35, 0, v35, s[50:51]
	v_add_u32_e32 v88, 11, v84
	v_cmp_gt_u32_e64 s[50:51], s98, v88
	v_cndmask_b32_e64 v36, 0, v36, s[30:31]
	v_add_u32_e32 v85, 16, v84
	v_cmp_gt_u32_e64 s[30:31], s98, v85
	v_cndmask_b32_e64 v37, 0, v37, s[36:37]
	v_add_u32_e32 v86, 17, v84
	v_cmp_gt_u32_e64 s[36:37], s98, v86
	v_cndmask_b32_e64 v38, 0, v38, s[78:79]
	v_add_u32_e32 v87, 18, v84
	v_cmp_gt_u32_e64 s[78:79], s98, v87
	v_cndmask_b32_e64 v39, 0, v39, s[50:51]
	v_add_u32_e32 v88, 19, v84
	v_cmp_gt_u32_e64 s[50:51], s98, v88
	v_cndmask_b32_e64 v40, 0, v40, s[30:31]
	v_add_u32_e32 v85, 24, v84
	v_cmp_gt_u32_e64 s[30:31], s98, v85
	v_cndmask_b32_e64 v41, 0, v41, s[36:37]
	v_add_u32_e32 v86, 25, v84
	v_cmp_gt_u32_e64 s[36:37], s98, v86
	v_cndmask_b32_e64 v42, 0, v42, s[78:79]
	v_add_u32_e32 v87, 26, v84
	v_cmp_gt_u32_e64 s[78:79], s98, v87
	v_cndmask_b32_e64 v43, 0, v43, s[50:51]
	v_add_u32_e32 v88, 27, v84
	v_cmp_gt_u32_e64 s[50:51], s98, v88
	v_nop
	v_cndmask_b32_e64 v44, 0, v44, s[30:31]
	v_cndmask_b32_e64 v45, 0, v45, s[36:37]
	v_cndmask_b32_e64 v46, 0, v46, s[78:79]
	v_cndmask_b32_e64 v47, 0, v47, s[50:51]
	v_cvt_pk_bf16_f32 v64, v32, v33
	v_cvt_pk_bf16_f32 v65, v34, v35
	v_cvt_pk_bf16_f32 v66, v36, v37
	v_cvt_pk_bf16_f32 v67, v38, v39
	v_cvt_pk_bf16_f32 v68, v40, v41
	v_cvt_pk_bf16_f32 v69, v42, v43
	v_cvt_pk_bf16_f32 v70, v44, v45
	v_cvt_pk_bf16_f32 v71, v46, v47
	v_pk_add_f32 v[232:233], v[232:233], v[32:33]
	v_pk_add_f32 v[232:233], v[232:233], v[34:35]
	v_pk_add_f32 v[232:233], v[232:233], v[36:37]
	v_pk_add_f32 v[232:233], v[232:233], v[38:39]
	v_pk_add_f32 v[232:233], v[232:233], v[40:41]
	v_pk_add_f32 v[232:233], v[232:233], v[42:43]
	v_pk_add_f32 v[232:233], v[232:233], v[44:45]
	v_pk_add_f32 v[232:233], v[232:233], v[46:47]
	s_waitcnt lgkmcnt(12)
	v_mfma_f32_32x32x16_bf16 v[0:15], v[64:67], v[72:75], v[0:15]
	v_mfma_f32_32x32x16_bf16 v[16:31], v[64:67], v[76:79], v[16:31]
	v_mfma_f32_32x32x16_bf16 v[0:15], v[68:71], v[220:223], v[0:15]
	v_mfma_f32_32x32x16_bf16 v[16:31], v[68:71], v[224:227], v[16:31]
	s_add_i32 s90, s76, 160
	v_add_u32_e32 v80, s90, v235
	v_add_u32_e32 v83, s90, v236
	v_add_u32_e32 v99, s90, v237
	v_add_u32_e32 v253, s90, v238
	v_add_u32_e32 v254, s90, v100
	v_add_u32_e32 v255, s90, v149
	v_med3_i32 v80, v80, 0, s99
	v_med3_i32 v83, v83, 0, s99
	v_med3_i32 v99, v99, 0, s99
	v_med3_i32 v253, v253, 0, s99
	v_med3_i32 v254, v254, 0, s99
	v_med3_i32 v255, v255, 0, s99
	v_mad_u32_u24 v80, v80, s100, v252
	v_mad_u32_u24 v83, v83, s100, v252
	v_mad_u32_u24 v99, v99, s100, v252
	v_mad_u32_u24 v253, v253, s100, v252
	v_mad_u32_u24 v254, v254, s100, v153
	v_mad_u32_u24 v255, v255, s100, v153
	global_load_dwordx4 v[156:159], v80, s[82:83]
	global_load_dwordx4 v[160:163], v83, s[82:83]
	global_load_dwordx4 v[164:167], v99, s[82:83]
	global_load_dwordx4 v[168:171], v253, s[82:83]
	global_load_dwordx4 v[172:175], v254, s[82:83] offset:768
	global_load_dwordx4 v[176:179], v255, s[82:83] offset:768
	global_load_dwordx4 v[180:183], v254, s[82:83] offset:832
	global_load_dwordx4 v[184:187], v255, s[82:83] offset:832
	ds_read2_b32 v[32:33], v115 offset0:170 offset1:171
	ds_read2_b32 v[34:35], v115 offset0:172 offset1:173
	ds_read2_b32 v[36:37], v115 offset0:178 offset1:179
	ds_read2_b32 v[38:39], v115 offset0:180 offset1:181
	ds_read2_b32 v[40:41], v115 offset0:187 offset1:188
	ds_read2_b32 v[42:43], v115 offset0:189 offset1:190
	ds_read2_b32 v[44:45], v115 offset0:195 offset1:196
	ds_read2_b32 v[46:47], v115 offset0:197 offset1:198
	s_waitcnt lgkmcnt(0)
	v_mfma_f32_32x32x16_bf16 v[32:47], v[188:191], v[48:51], v[32:47]
	ds_read_b64_tr_b16 v[72:73], v231
	ds_read_b64_tr_b16 v[74:75], v231 offset:512
	ds_read_b64_tr_b16 v[76:77], v231 offset:2048
	ds_read_b64_tr_b16 v[78:79], v231 offset:2560
	ds_read_b64_tr_b16 v[220:221], v231 offset:1024
	ds_read_b64_tr_b16 v[222:223], v231 offset:1536
	ds_read_b64_tr_b16 v[224:225], v231 offset:3072
	ds_read_b64_tr_b16 v[226:227], v231 offset:3584
	s_waitcnt vmcnt(8)
	ds_write_b128 v247, v[116:119]
	ds_write_b128 v247, v[120:123] offset:1024
	ds_write_b128 v247, v[124:127] offset:2048
	ds_write_b128 v247, v[128:131] offset:3072
	ds_read_b128 v[116:119], v248
	ds_read_b128 v[120:123], v249
	ds_read_b128 v[124:127], v250
	ds_read_b128 v[128:131], v251
	ds_write_b128 v112, v[132:135]
	ds_write_b128 v112, v[136:139] offset:1024
	ds_write_b128 v112, v[140:143] offset:2048
	ds_write_b128 v112, v[144:147] offset:3072
	v_mfma_f32_32x32x16_bf16 v[32:47], v[192:195], v[52:55], v[32:47]
	v_mfma_f32_32x32x16_bf16 v[32:47], v[196:199], v[56:59], v[32:47]
	v_mfma_f32_32x32x16_bf16 v[32:47], v[200:203], v[60:63], v[32:47]
	s_nop 11
	v_exp_f32_e32 v32, v32
	v_exp_f32_e32 v33, v33
	v_exp_f32_e32 v34, v34
	v_exp_f32_e32 v35, v35
	v_exp_f32_e32 v36, v36
	v_exp_f32_e32 v37, v37
	v_exp_f32_e32 v38, v38
	v_exp_f32_e32 v39, v39
	v_exp_f32_e32 v40, v40
	v_exp_f32_e32 v41, v41
	v_exp_f32_e32 v42, v42
	v_exp_f32_e32 v43, v43
	v_exp_f32_e32 v44, v44
	v_exp_f32_e32 v45, v45
	v_exp_f32_e32 v46, v46
	v_exp_f32_e32 v47, v47
	s_add_i32 s90, s76, 96
	v_add_u32_e32 v84, s90, v107
	v_add_u32_e32 v85, 0, v84
	v_add_u32_e32 v86, 1, v84
	v_add_u32_e32 v87, 2, v84
	v_add_u32_e32 v88, 3, v84
	v_cmp_gt_u32_e64 s[30:31], s98, v85
	v_cmp_gt_u32_e64 s[36:37], s98, v86
	v_cmp_gt_u32_e64 s[78:79], s98, v87
	v_cmp_gt_u32_e64 s[50:51], s98, v88
	v_cndmask_b32_e64 v32, 0, v32, s[30:31]
	v_add_u32_e32 v85, 8, v84
	v_cmp_gt_u32_e64 s[30:31], s98, v85
	v_cndmask_b32_e64 v33, 0, v33, s[36:37]
	v_add_u32_e32 v86, 9, v84
	v_cmp_gt_u32_e64 s[36:37], s98, v86
	v_cndmask_b32_e64 v34, 0, v34, s[78:79]
	v_add_u32_e32 v87, 10, v84
	v_cmp_gt_u32_e64 s[78:79], s98, v87
	v_cndmask_b32_e64 v35, 0, v35, s[50:51]
	v_add_u32_e32 v88, 11, v84
	v_cmp_gt_u32_e64 s[50:51], s98, v88
	v_cndmask_b32_e64 v36, 0, v36, s[30:31]
	v_add_u32_e32 v85, 16, v84
	v_cmp_gt_u32_e64 s[30:31], s98, v85
	v_cndmask_b32_e64 v37, 0, v37, s[36:37]
	v_add_u32_e32 v86, 17, v84
	v_cmp_gt_u32_e64 s[36:37], s98, v86
	v_cndmask_b32_e64 v38, 0, v38, s[78:79]
	v_add_u32_e32 v87, 18, v84
	v_cmp_gt_u32_e64 s[78:79], s98, v87
	v_cndmask_b32_e64 v39, 0, v39, s[50:51]
	v_add_u32_e32 v88, 19, v84
	v_cmp_gt_u32_e64 s[50:51], s98, v88
	v_cndmask_b32_e64 v40, 0, v40, s[30:31]
	v_add_u32_e32 v85, 24, v84
	v_cmp_gt_u32_e64 s[30:31], s98, v85
	v_cndmask_b32_e64 v41, 0, v41, s[36:37]
	v_add_u32_e32 v86, 25, v84
	v_cmp_gt_u32_e64 s[36:37], s98, v86
	v_cndmask_b32_e64 v42, 0, v42, s[78:79]
	v_add_u32_e32 v87, 26, v84
	v_cmp_gt_u32_e64 s[78:79], s98, v87
	v_cndmask_b32_e64 v43, 0, v43, s[50:51]
	v_add_u32_e32 v88, 27, v84
	v_cmp_gt_u32_e64 s[50:51], s98, v88
	v_nop
	v_cndmask_b32_e64 v44, 0, v44, s[30:31]
	v_cndmask_b32_e64 v45, 0, v45, s[36:37]
	v_cndmask_b32_e64 v46, 0, v46, s[78:79]
	v_cndmask_b32_e64 v47, 0, v47, s[50:51]
	v_cvt_pk_bf16_f32 v64, v32, v33
	v_cvt_pk_bf16_f32 v65, v34, v35
	v_cvt_pk_bf16_f32 v66, v36, v37
	v_cvt_pk_bf16_f32 v67, v38, v39
	v_cvt_pk_bf16_f32 v68, v40, v41
	v_cvt_pk_bf16_f32 v69, v42, v43
	v_cvt_pk_bf16_f32 v70, v44, v45
	v_cvt_pk_bf16_f32 v71, v46, v47
	v_pk_add_f32 v[232:233], v[232:233], v[32:33]
	v_pk_add_f32 v[232:233], v[232:233], v[34:35]
	v_pk_add_f32 v[232:233], v[232:233], v[36:37]
	v_pk_add_f32 v[232:233], v[232:233], v[38:39]
	v_pk_add_f32 v[232:233], v[232:233], v[40:41]
	v_pk_add_f32 v[232:233], v[232:233], v[42:43]
	v_pk_add_f32 v[232:233], v[232:233], v[44:45]
	v_pk_add_f32 v[232:233], v[232:233], v[46:47]
	s_waitcnt lgkmcnt(12)
	v_mfma_f32_32x32x16_bf16 v[0:15], v[64:67], v[72:75], v[0:15]
	v_mfma_f32_32x32x16_bf16 v[16:31], v[64:67], v[76:79], v[16:31]
	v_mfma_f32_32x32x16_bf16 v[0:15], v[68:71], v[220:223], v[0:15]
	v_mfma_f32_32x32x16_bf16 v[16:31], v[68:71], v[224:227], v[16:31]
	s_add_i32 s90, s76, 192
	v_add_u32_e32 v80, s90, v235
	v_add_u32_e32 v83, s90, v236
	v_add_u32_e32 v99, s90, v237
	v_add_u32_e32 v253, s90, v238
	v_add_u32_e32 v254, s90, v100
	v_add_u32_e32 v255, s90, v149
	v_med3_i32 v80, v80, 0, s99
	v_med3_i32 v83, v83, 0, s99
	v_med3_i32 v99, v99, 0, s99
	v_med3_i32 v253, v253, 0, s99
	v_med3_i32 v254, v254, 0, s99
	v_med3_i32 v255, v255, 0, s99
	v_mad_u32_u24 v80, v80, s100, v252
	v_mad_u32_u24 v83, v83, s100, v252
	v_mad_u32_u24 v99, v99, s100, v252
	v_mad_u32_u24 v253, v253, s100, v252
	v_mad_u32_u24 v254, v254, s100, v153
	v_mad_u32_u24 v255, v255, s100, v153
	global_load_dwordx4 v[188:191], v80, s[82:83]
	global_load_dwordx4 v[192:195], v83, s[82:83]
	global_load_dwordx4 v[196:199], v99, s[82:83]
	global_load_dwordx4 v[200:203], v253, s[82:83]
	global_load_dwordx4 v[204:207], v254, s[82:83] offset:768
	global_load_dwordx4 v[208:211], v255, s[82:83] offset:768
	global_load_dwordx4 v[212:215], v254, s[82:83] offset:832
	global_load_dwordx4 v[216:219], v255, s[82:83] offset:832
	ds_read2_b32 v[32:33], v115 offset0:204 offset1:205
	ds_read2_b32 v[34:35], v115 offset0:206 offset1:207
	ds_read2_b32 v[36:37], v115 offset0:212 offset1:213
	ds_read2_b32 v[38:39], v115 offset0:214 offset1:215
	ds_read2_b32 v[40:41], v115 offset0:221 offset1:222
	ds_read2_b32 v[42:43], v115 offset0:223 offset1:224
	ds_read2_b32 v[44:45], v115 offset0:229 offset1:230
	ds_read2_b32 v[46:47], v115 offset0:231 offset1:232
	s_waitcnt lgkmcnt(0)
	v_mfma_f32_32x32x16_bf16 v[32:47], v[116:119], v[48:51], v[32:47]
	ds_read_b64_tr_b16 v[72:73], v231
	ds_read_b64_tr_b16 v[74:75], v231 offset:512
	ds_read_b64_tr_b16 v[76:77], v231 offset:2048
	ds_read_b64_tr_b16 v[78:79], v231 offset:2560
	ds_read_b64_tr_b16 v[220:221], v231 offset:1024
	ds_read_b64_tr_b16 v[222:223], v231 offset:1536
	ds_read_b64_tr_b16 v[224:225], v231 offset:3072
	ds_read_b64_tr_b16 v[226:227], v231 offset:3584
	s_waitcnt vmcnt(8)
	ds_write_b128 v247, v[156:159]
	ds_write_b128 v247, v[160:163] offset:1024
	ds_write_b128 v247, v[164:167] offset:2048
	ds_write_b128 v247, v[168:171] offset:3072
	ds_read_b128 v[156:159], v248
	ds_read_b128 v[160:163], v249
	ds_read_b128 v[164:167], v250
	ds_read_b128 v[168:171], v251
	ds_write_b128 v112, v[172:175]
	ds_write_b128 v112, v[176:179] offset:1024
	ds_write_b128 v112, v[180:183] offset:2048
	ds_write_b128 v112, v[184:187] offset:3072
	v_mfma_f32_32x32x16_bf16 v[32:47], v[120:123], v[52:55], v[32:47]
	v_mfma_f32_32x32x16_bf16 v[32:47], v[124:127], v[56:59], v[32:47]
	v_mfma_f32_32x32x16_bf16 v[32:47], v[128:131], v[60:63], v[32:47]
	s_nop 11
	v_exp_f32_e32 v32, v32
	v_exp_f32_e32 v33, v33
	v_exp_f32_e32 v34, v34
	v_exp_f32_e32 v35, v35
	v_exp_f32_e32 v36, v36
	v_exp_f32_e32 v37, v37
	v_exp_f32_e32 v38, v38
	v_exp_f32_e32 v39, v39
	v_exp_f32_e32 v40, v40
	v_exp_f32_e32 v41, v41
	v_exp_f32_e32 v42, v42
	v_exp_f32_e32 v43, v43
	v_exp_f32_e32 v44, v44
	v_exp_f32_e32 v45, v45
	v_exp_f32_e32 v46, v46
	v_exp_f32_e32 v47, v47
	s_add_i32 s90, s76, 128
	v_add_u32_e32 v84, s90, v107
	v_add_u32_e32 v85, 0, v84
	v_add_u32_e32 v86, 1, v84
	v_add_u32_e32 v87, 2, v84
	v_add_u32_e32 v88, 3, v84
	v_cmp_gt_u32_e64 s[30:31], s98, v85
	v_cmp_gt_u32_e64 s[36:37], s98, v86
	v_cmp_gt_u32_e64 s[78:79], s98, v87
	v_cmp_gt_u32_e64 s[50:51], s98, v88
	v_cndmask_b32_e64 v32, 0, v32, s[30:31]
	v_add_u32_e32 v85, 8, v84
	v_cmp_gt_u32_e64 s[30:31], s98, v85
	v_cndmask_b32_e64 v33, 0, v33, s[36:37]
	v_add_u32_e32 v86, 9, v84
	v_cmp_gt_u32_e64 s[36:37], s98, v86
	v_cndmask_b32_e64 v34, 0, v34, s[78:79]
	v_add_u32_e32 v87, 10, v84
	v_cmp_gt_u32_e64 s[78:79], s98, v87
	v_cndmask_b32_e64 v35, 0, v35, s[50:51]
	v_add_u32_e32 v88, 11, v84
	v_cmp_gt_u32_e64 s[50:51], s98, v88
	v_cndmask_b32_e64 v36, 0, v36, s[30:31]
	v_add_u32_e32 v85, 16, v84
	v_cmp_gt_u32_e64 s[30:31], s98, v85
	v_cndmask_b32_e64 v37, 0, v37, s[36:37]
	v_add_u32_e32 v86, 17, v84
	v_cmp_gt_u32_e64 s[36:37], s98, v86
	v_cndmask_b32_e64 v38, 0, v38, s[78:79]
	v_add_u32_e32 v87, 18, v84
	v_cmp_gt_u32_e64 s[78:79], s98, v87
	v_cndmask_b32_e64 v39, 0, v39, s[50:51]
	v_add_u32_e32 v88, 19, v84
	v_cmp_gt_u32_e64 s[50:51], s98, v88
	v_cndmask_b32_e64 v40, 0, v40, s[30:31]
	v_add_u32_e32 v85, 24, v84
	v_cmp_gt_u32_e64 s[30:31], s98, v85
	v_cndmask_b32_e64 v41, 0, v41, s[36:37]
	v_add_u32_e32 v86, 25, v84
	v_cmp_gt_u32_e64 s[36:37], s98, v86
	v_cndmask_b32_e64 v42, 0, v42, s[78:79]
	v_add_u32_e32 v87, 26, v84
	v_cmp_gt_u32_e64 s[78:79], s98, v87
	v_cndmask_b32_e64 v43, 0, v43, s[50:51]
	v_add_u32_e32 v88, 27, v84
	v_cmp_gt_u32_e64 s[50:51], s98, v88
	v_nop
	v_cndmask_b32_e64 v44, 0, v44, s[30:31]
	v_cndmask_b32_e64 v45, 0, v45, s[36:37]
	v_cndmask_b32_e64 v46, 0, v46, s[78:79]
	v_cndmask_b32_e64 v47, 0, v47, s[50:51]
	v_cvt_pk_bf16_f32 v64, v32, v33
	v_cvt_pk_bf16_f32 v65, v34, v35
	v_cvt_pk_bf16_f32 v66, v36, v37
	v_cvt_pk_bf16_f32 v67, v38, v39
	v_cvt_pk_bf16_f32 v68, v40, v41
	v_cvt_pk_bf16_f32 v69, v42, v43
	v_cvt_pk_bf16_f32 v70, v44, v45
	v_cvt_pk_bf16_f32 v71, v46, v47
	v_pk_add_f32 v[232:233], v[232:233], v[32:33]
	v_pk_add_f32 v[232:233], v[232:233], v[34:35]
	v_pk_add_f32 v[232:233], v[232:233], v[36:37]
	v_pk_add_f32 v[232:233], v[232:233], v[38:39]
	v_pk_add_f32 v[232:233], v[232:233], v[40:41]
	v_pk_add_f32 v[232:233], v[232:233], v[42:43]
	v_pk_add_f32 v[232:233], v[232:233], v[44:45]
	v_pk_add_f32 v[232:233], v[232:233], v[46:47]
	s_waitcnt lgkmcnt(12)
	v_mfma_f32_32x32x16_bf16 v[0:15], v[64:67], v[72:75], v[0:15]
	v_mfma_f32_32x32x16_bf16 v[16:31], v[64:67], v[76:79], v[16:31]
	v_mfma_f32_32x32x16_bf16 v[0:15], v[68:71], v[220:223], v[0:15]
	v_mfma_f32_32x32x16_bf16 v[16:31], v[68:71], v[224:227], v[16:31]
	s_add_i32 s90, s76, 224
	v_add_u32_e32 v80, s90, v235
	v_add_u32_e32 v83, s90, v236
	v_add_u32_e32 v99, s90, v237
	v_add_u32_e32 v253, s90, v238
	v_add_u32_e32 v254, s90, v100
	v_add_u32_e32 v255, s90, v149
	v_med3_i32 v80, v80, 0, s99
	v_med3_i32 v83, v83, 0, s99
	v_med3_i32 v99, v99, 0, s99
	v_med3_i32 v253, v253, 0, s99
	v_med3_i32 v254, v254, 0, s99
	v_med3_i32 v255, v255, 0, s99
	v_mad_u32_u24 v80, v80, s100, v252
	v_mad_u32_u24 v83, v83, s100, v252
	v_mad_u32_u24 v99, v99, s100, v252
	v_mad_u32_u24 v253, v253, s100, v252
	v_mad_u32_u24 v254, v254, s100, v153
	v_mad_u32_u24 v255, v255, s100, v153
	global_load_dwordx4 v[116:119], v80, s[82:83]
	global_load_dwordx4 v[120:123], v83, s[82:83]
	global_load_dwordx4 v[124:127], v99, s[82:83]
	global_load_dwordx4 v[128:131], v253, s[82:83]
	global_load_dwordx4 v[132:135], v254, s[82:83] offset:768
	global_load_dwordx4 v[136:139], v255, s[82:83] offset:768
	global_load_dwordx4 v[140:143], v254, s[82:83] offset:832
	global_load_dwordx4 v[144:147], v255, s[82:83] offset:832
	v_add_u32_e32 v115, 952, v115
	ds_read2_b32 v[32:33], v115 offset0:0 offset1:1
	ds_read2_b32 v[34:35], v115 offset0:2 offset1:3
	ds_read2_b32 v[36:37], v115 offset0:8 offset1:9
	ds_read2_b32 v[38:39], v115 offset0:10 offset1:11
	ds_read2_b32 v[40:41], v115 offset0:17 offset1:18
	ds_read2_b32 v[42:43], v115 offset0:19 offset1:20
	ds_read2_b32 v[44:45], v115 offset0:25 offset1:26
	ds_read2_b32 v[46:47], v115 offset0:27 offset1:28
	s_waitcnt lgkmcnt(0)
	v_mfma_f32_32x32x16_bf16 v[32:47], v[156:159], v[48:51], v[32:47]
	ds_read_b64_tr_b16 v[72:73], v231
	ds_read_b64_tr_b16 v[74:75], v231 offset:512
	ds_read_b64_tr_b16 v[76:77], v231 offset:2048
	ds_read_b64_tr_b16 v[78:79], v231 offset:2560
	ds_read_b64_tr_b16 v[220:221], v231 offset:1024
	ds_read_b64_tr_b16 v[222:223], v231 offset:1536
	ds_read_b64_tr_b16 v[224:225], v231 offset:3072
	ds_read_b64_tr_b16 v[226:227], v231 offset:3584
	s_waitcnt vmcnt(8)
	ds_write_b128 v247, v[188:191]
	ds_write_b128 v247, v[192:195] offset:1024
	ds_write_b128 v247, v[196:199] offset:2048
	ds_write_b128 v247, v[200:203] offset:3072
	ds_read_b128 v[188:191], v248
	ds_read_b128 v[192:195], v249
	ds_read_b128 v[196:199], v250
	ds_read_b128 v[200:203], v251
	ds_write_b128 v112, v[204:207]
	ds_write_b128 v112, v[208:211] offset:1024
	ds_write_b128 v112, v[212:215] offset:2048
	ds_write_b128 v112, v[216:219] offset:3072
	v_mfma_f32_32x32x16_bf16 v[32:47], v[160:163], v[52:55], v[32:47]
	v_mfma_f32_32x32x16_bf16 v[32:47], v[164:167], v[56:59], v[32:47]
	v_mfma_f32_32x32x16_bf16 v[32:47], v[168:171], v[60:63], v[32:47]
	s_nop 11
	v_exp_f32_e32 v32, v32
	v_exp_f32_e32 v33, v33
	v_exp_f32_e32 v34, v34
	v_exp_f32_e32 v35, v35
	v_exp_f32_e32 v36, v36
	v_exp_f32_e32 v37, v37
	v_exp_f32_e32 v38, v38
	v_exp_f32_e32 v39, v39
	v_exp_f32_e32 v40, v40
	v_exp_f32_e32 v41, v41
	v_exp_f32_e32 v42, v42
	v_exp_f32_e32 v43, v43
	v_exp_f32_e32 v44, v44
	v_exp_f32_e32 v45, v45
	v_exp_f32_e32 v46, v46
	v_exp_f32_e32 v47, v47
	s_add_i32 s90, s76, 160
	v_add_u32_e32 v84, s90, v107
	v_add_u32_e32 v85, 0, v84
	v_add_u32_e32 v86, 1, v84
	v_add_u32_e32 v87, 2, v84
	v_add_u32_e32 v88, 3, v84
	v_cmp_gt_u32_e64 s[30:31], s98, v85
	v_cmp_gt_u32_e64 s[36:37], s98, v86
	v_cmp_gt_u32_e64 s[78:79], s98, v87
	v_cmp_gt_u32_e64 s[50:51], s98, v88
	v_cndmask_b32_e64 v32, 0, v32, s[30:31]
	v_add_u32_e32 v85, 8, v84
	v_cmp_gt_u32_e64 s[30:31], s98, v85
	v_cndmask_b32_e64 v33, 0, v33, s[36:37]
	v_add_u32_e32 v86, 9, v84
	v_cmp_gt_u32_e64 s[36:37], s98, v86
	v_cndmask_b32_e64 v34, 0, v34, s[78:79]
	v_add_u32_e32 v87, 10, v84
	v_cmp_gt_u32_e64 s[78:79], s98, v87
	v_cndmask_b32_e64 v35, 0, v35, s[50:51]
	v_add_u32_e32 v88, 11, v84
	v_cmp_gt_u32_e64 s[50:51], s98, v88
	v_cndmask_b32_e64 v36, 0, v36, s[30:31]
	v_add_u32_e32 v85, 16, v84
	v_cmp_gt_u32_e64 s[30:31], s98, v85
	v_cndmask_b32_e64 v37, 0, v37, s[36:37]
	v_add_u32_e32 v86, 17, v84
	v_cmp_gt_u32_e64 s[36:37], s98, v86
	v_cndmask_b32_e64 v38, 0, v38, s[78:79]
	v_add_u32_e32 v87, 18, v84
	v_cmp_gt_u32_e64 s[78:79], s98, v87
	v_cndmask_b32_e64 v39, 0, v39, s[50:51]
	v_add_u32_e32 v88, 19, v84
	v_cmp_gt_u32_e64 s[50:51], s98, v88
	v_cndmask_b32_e64 v40, 0, v40, s[30:31]
	v_add_u32_e32 v85, 24, v84
	v_cmp_gt_u32_e64 s[30:31], s98, v85
	v_cndmask_b32_e64 v41, 0, v41, s[36:37]
	v_add_u32_e32 v86, 25, v84
	v_cmp_gt_u32_e64 s[36:37], s98, v86
	v_cndmask_b32_e64 v42, 0, v42, s[78:79]
	v_add_u32_e32 v87, 26, v84
	v_cmp_gt_u32_e64 s[78:79], s98, v87
	v_cndmask_b32_e64 v43, 0, v43, s[50:51]
	v_add_u32_e32 v88, 27, v84
	v_cmp_gt_u32_e64 s[50:51], s98, v88
	v_nop
	v_cndmask_b32_e64 v44, 0, v44, s[30:31]
	v_cndmask_b32_e64 v45, 0, v45, s[36:37]
	v_cndmask_b32_e64 v46, 0, v46, s[78:79]
	v_cndmask_b32_e64 v47, 0, v47, s[50:51]
	v_cvt_pk_bf16_f32 v64, v32, v33
	v_cvt_pk_bf16_f32 v65, v34, v35
	v_cvt_pk_bf16_f32 v66, v36, v37
	v_cvt_pk_bf16_f32 v67, v38, v39
	v_cvt_pk_bf16_f32 v68, v40, v41
	v_cvt_pk_bf16_f32 v69, v42, v43
	v_cvt_pk_bf16_f32 v70, v44, v45
	v_cvt_pk_bf16_f32 v71, v46, v47
	v_pk_add_f32 v[232:233], v[232:233], v[32:33]
	v_pk_add_f32 v[232:233], v[232:233], v[34:35]
	v_pk_add_f32 v[232:233], v[232:233], v[36:37]
	v_pk_add_f32 v[232:233], v[232:233], v[38:39]
	v_pk_add_f32 v[232:233], v[232:233], v[40:41]
	v_pk_add_f32 v[232:233], v[232:233], v[42:43]
	v_pk_add_f32 v[232:233], v[232:233], v[44:45]
	v_pk_add_f32 v[232:233], v[232:233], v[46:47]
	s_waitcnt lgkmcnt(12)
	v_mfma_f32_32x32x16_bf16 v[0:15], v[64:67], v[72:75], v[0:15]
	v_mfma_f32_32x32x16_bf16 v[16:31], v[64:67], v[76:79], v[16:31]
	v_mfma_f32_32x32x16_bf16 v[0:15], v[68:71], v[220:223], v[0:15]
	v_mfma_f32_32x32x16_bf16 v[16:31], v[68:71], v[224:227], v[16:31]
	s_add_i32 s90, s76, 256
	v_add_u32_e32 v80, s90, v235
	v_add_u32_e32 v83, s90, v236
	v_add_u32_e32 v99, s90, v237
	v_add_u32_e32 v253, s90, v238
	v_add_u32_e32 v254, s90, v100
	v_add_u32_e32 v255, s90, v149
	v_med3_i32 v80, v80, 0, s99
	v_med3_i32 v83, v83, 0, s99
	v_med3_i32 v99, v99, 0, s99
	v_med3_i32 v253, v253, 0, s99
	v_med3_i32 v254, v254, 0, s99
	v_med3_i32 v255, v255, 0, s99
	v_mad_u32_u24 v80, v80, s100, v252
	v_mad_u32_u24 v83, v83, s100, v252
	v_mad_u32_u24 v99, v99, s100, v252
	v_mad_u32_u24 v253, v253, s100, v252
	v_mad_u32_u24 v254, v254, s100, v153
	v_mad_u32_u24 v255, v255, s100, v153
	global_load_dwordx4 v[156:159], v80, s[82:83]
	global_load_dwordx4 v[160:163], v83, s[82:83]
	global_load_dwordx4 v[164:167], v99, s[82:83]
	global_load_dwordx4 v[168:171], v253, s[82:83]
	global_load_dwordx4 v[172:175], v254, s[82:83] offset:768
	global_load_dwordx4 v[176:179], v255, s[82:83] offset:768
	global_load_dwordx4 v[180:183], v254, s[82:83] offset:832
	global_load_dwordx4 v[184:187], v255, s[82:83] offset:832
	ds_read2_b32 v[32:33], v115 offset0:34 offset1:35
	ds_read2_b32 v[34:35], v115 offset0:36 offset1:37
	ds_read2_b32 v[36:37], v115 offset0:42 offset1:43
	ds_read2_b32 v[38:39], v115 offset0:44 offset1:45
	ds_read2_b32 v[40:41], v115 offset0:51 offset1:52
	ds_read2_b32 v[42:43], v115 offset0:53 offset1:54
	ds_read2_b32 v[44:45], v115 offset0:59 offset1:60
	ds_read2_b32 v[46:47], v115 offset0:61 offset1:62
	s_waitcnt lgkmcnt(0)
	v_mfma_f32_32x32x16_bf16 v[32:47], v[188:191], v[48:51], v[32:47]
	ds_read_b64_tr_b16 v[72:73], v231
	ds_read_b64_tr_b16 v[74:75], v231 offset:512
	ds_read_b64_tr_b16 v[76:77], v231 offset:2048
	ds_read_b64_tr_b16 v[78:79], v231 offset:2560
	ds_read_b64_tr_b16 v[220:221], v231 offset:1024
	ds_read_b64_tr_b16 v[222:223], v231 offset:1536
	ds_read_b64_tr_b16 v[224:225], v231 offset:3072
	ds_read_b64_tr_b16 v[226:227], v231 offset:3584
	s_waitcnt vmcnt(8)
	ds_write_b128 v247, v[116:119]
	ds_write_b128 v247, v[120:123] offset:1024
	ds_write_b128 v247, v[124:127] offset:2048
	ds_write_b128 v247, v[128:131] offset:3072
	ds_read_b128 v[116:119], v248
	ds_read_b128 v[120:123], v249
	ds_read_b128 v[124:127], v250
	ds_read_b128 v[128:131], v251
	ds_write_b128 v112, v[132:135]
	ds_write_b128 v112, v[136:139] offset:1024
	ds_write_b128 v112, v[140:143] offset:2048
	ds_write_b128 v112, v[144:147] offset:3072
	v_mfma_f32_32x32x16_bf16 v[32:47], v[192:195], v[52:55], v[32:47]
	v_mfma_f32_32x32x16_bf16 v[32:47], v[196:199], v[56:59], v[32:47]
	v_mfma_f32_32x32x16_bf16 v[32:47], v[200:203], v[60:63], v[32:47]
	s_nop 11
	v_exp_f32_e32 v32, v32
	v_exp_f32_e32 v33, v33
	v_exp_f32_e32 v34, v34
	v_exp_f32_e32 v35, v35
	v_exp_f32_e32 v36, v36
	v_exp_f32_e32 v37, v37
	v_exp_f32_e32 v38, v38
	v_exp_f32_e32 v39, v39
	v_exp_f32_e32 v40, v40
	v_exp_f32_e32 v41, v41
	v_exp_f32_e32 v42, v42
	v_exp_f32_e32 v43, v43
	v_exp_f32_e32 v44, v44
	v_exp_f32_e32 v45, v45
	v_exp_f32_e32 v46, v46
	v_exp_f32_e32 v47, v47
	s_add_i32 s90, s76, 192
	v_add_u32_e32 v84, s90, v107
	v_add_u32_e32 v85, 0, v84
	v_add_u32_e32 v86, 1, v84
	v_add_u32_e32 v87, 2, v84
	v_add_u32_e32 v88, 3, v84
	v_cmp_gt_u32_e64 s[30:31], s98, v85
	v_cmp_gt_u32_e64 s[36:37], s98, v86
	v_cmp_gt_u32_e64 s[78:79], s98, v87
	v_cmp_gt_u32_e64 s[50:51], s98, v88
	v_cndmask_b32_e64 v32, 0, v32, s[30:31]
	v_add_u32_e32 v85, 8, v84
	v_cmp_gt_u32_e64 s[30:31], s98, v85
	v_cndmask_b32_e64 v33, 0, v33, s[36:37]
	v_add_u32_e32 v86, 9, v84
	v_cmp_gt_u32_e64 s[36:37], s98, v86
	v_cndmask_b32_e64 v34, 0, v34, s[78:79]
	v_add_u32_e32 v87, 10, v84
	v_cmp_gt_u32_e64 s[78:79], s98, v87
	v_cndmask_b32_e64 v35, 0, v35, s[50:51]
	v_add_u32_e32 v88, 11, v84
	v_cmp_gt_u32_e64 s[50:51], s98, v88
	v_cndmask_b32_e64 v36, 0, v36, s[30:31]
	v_add_u32_e32 v85, 16, v84
	v_cmp_gt_u32_e64 s[30:31], s98, v85
	v_cndmask_b32_e64 v37, 0, v37, s[36:37]
	v_add_u32_e32 v86, 17, v84
	v_cmp_gt_u32_e64 s[36:37], s98, v86
	v_cndmask_b32_e64 v38, 0, v38, s[78:79]
	v_add_u32_e32 v87, 18, v84
	v_cmp_gt_u32_e64 s[78:79], s98, v87
	v_cndmask_b32_e64 v39, 0, v39, s[50:51]
	v_add_u32_e32 v88, 19, v84
	v_cmp_gt_u32_e64 s[50:51], s98, v88
	v_cndmask_b32_e64 v40, 0, v40, s[30:31]
	v_add_u32_e32 v85, 24, v84
	v_cmp_gt_u32_e64 s[30:31], s98, v85
	v_cndmask_b32_e64 v41, 0, v41, s[36:37]
	v_add_u32_e32 v86, 25, v84
	v_cmp_gt_u32_e64 s[36:37], s98, v86
	v_cndmask_b32_e64 v42, 0, v42, s[78:79]
	v_add_u32_e32 v87, 26, v84
	v_cmp_gt_u32_e64 s[78:79], s98, v87
	v_cndmask_b32_e64 v43, 0, v43, s[50:51]
	v_add_u32_e32 v88, 27, v84
	v_cmp_gt_u32_e64 s[50:51], s98, v88
	v_nop
	v_cndmask_b32_e64 v44, 0, v44, s[30:31]
	v_cndmask_b32_e64 v45, 0, v45, s[36:37]
	v_cndmask_b32_e64 v46, 0, v46, s[78:79]
	v_cndmask_b32_e64 v47, 0, v47, s[50:51]
	v_cvt_pk_bf16_f32 v64, v32, v33
	v_cvt_pk_bf16_f32 v65, v34, v35
	v_cvt_pk_bf16_f32 v66, v36, v37
	v_cvt_pk_bf16_f32 v67, v38, v39
	v_cvt_pk_bf16_f32 v68, v40, v41
	v_cvt_pk_bf16_f32 v69, v42, v43
	v_cvt_pk_bf16_f32 v70, v44, v45
	v_cvt_pk_bf16_f32 v71, v46, v47
	v_pk_add_f32 v[232:233], v[232:233], v[32:33]
	v_pk_add_f32 v[232:233], v[232:233], v[34:35]
	v_pk_add_f32 v[232:233], v[232:233], v[36:37]
	v_pk_add_f32 v[232:233], v[232:233], v[38:39]
	v_pk_add_f32 v[232:233], v[232:233], v[40:41]
	v_pk_add_f32 v[232:233], v[232:233], v[42:43]
	v_pk_add_f32 v[232:233], v[232:233], v[44:45]
	v_pk_add_f32 v[232:233], v[232:233], v[46:47]
	s_waitcnt lgkmcnt(12)
	v_mfma_f32_32x32x16_bf16 v[0:15], v[64:67], v[72:75], v[0:15]
	v_mfma_f32_32x32x16_bf16 v[16:31], v[64:67], v[76:79], v[16:31]
	v_mfma_f32_32x32x16_bf16 v[0:15], v[68:71], v[220:223], v[0:15]
	v_mfma_f32_32x32x16_bf16 v[16:31], v[68:71], v[224:227], v[16:31]
	s_add_i32 s90, s76, 288
	v_add_u32_e32 v80, s90, v235
	v_add_u32_e32 v83, s90, v236
	v_add_u32_e32 v99, s90, v237
	v_add_u32_e32 v253, s90, v238
	v_add_u32_e32 v254, s90, v100
	v_add_u32_e32 v255, s90, v149
	v_med3_i32 v80, v80, 0, s99
	v_med3_i32 v83, v83, 0, s99
	v_med3_i32 v99, v99, 0, s99
	v_med3_i32 v253, v253, 0, s99
	v_med3_i32 v254, v254, 0, s99
	v_med3_i32 v255, v255, 0, s99
	v_mad_u32_u24 v80, v80, s100, v252
	v_mad_u32_u24 v83, v83, s100, v252
	v_mad_u32_u24 v99, v99, s100, v252
	v_mad_u32_u24 v253, v253, s100, v252
	v_mad_u32_u24 v254, v254, s100, v153
	v_mad_u32_u24 v255, v255, s100, v153
	global_load_dwordx4 v[188:191], v80, s[82:83]
	global_load_dwordx4 v[192:195], v83, s[82:83]
	global_load_dwordx4 v[196:199], v99, s[82:83]
	global_load_dwordx4 v[200:203], v253, s[82:83]
	global_load_dwordx4 v[204:207], v254, s[82:83] offset:768
	global_load_dwordx4 v[208:211], v255, s[82:83] offset:768
	global_load_dwordx4 v[212:215], v254, s[82:83] offset:832
	global_load_dwordx4 v[216:219], v255, s[82:83] offset:832
	ds_read2_b32 v[32:33], v115 offset0:68 offset1:69
	ds_read2_b32 v[34:35], v115 offset0:70 offset1:71
	ds_read2_b32 v[36:37], v115 offset0:76 offset1:77
	ds_read2_b32 v[38:39], v115 offset0:78 offset1:79
	ds_read2_b32 v[40:41], v115 offset0:85 offset1:86
	ds_read2_b32 v[42:43], v115 offset0:87 offset1:88
	ds_read2_b32 v[44:45], v115 offset0:93 offset1:94
	ds_read2_b32 v[46:47], v115 offset0:95 offset1:96
	s_waitcnt lgkmcnt(0)
	v_mfma_f32_32x32x16_bf16 v[32:47], v[116:119], v[48:51], v[32:47]
	ds_read_b64_tr_b16 v[72:73], v231
	ds_read_b64_tr_b16 v[74:75], v231 offset:512
	ds_read_b64_tr_b16 v[76:77], v231 offset:2048
	ds_read_b64_tr_b16 v[78:79], v231 offset:2560
	ds_read_b64_tr_b16 v[220:221], v231 offset:1024
	ds_read_b64_tr_b16 v[222:223], v231 offset:1536
	ds_read_b64_tr_b16 v[224:225], v231 offset:3072
	ds_read_b64_tr_b16 v[226:227], v231 offset:3584
	s_waitcnt vmcnt(8)
	ds_write_b128 v247, v[156:159]
	ds_write_b128 v247, v[160:163] offset:1024
	ds_write_b128 v247, v[164:167] offset:2048
	ds_write_b128 v247, v[168:171] offset:3072
	ds_read_b128 v[156:159], v248
	ds_read_b128 v[160:163], v249
	ds_read_b128 v[164:167], v250
	ds_read_b128 v[168:171], v251
	ds_write_b128 v112, v[172:175]
	ds_write_b128 v112, v[176:179] offset:1024
	ds_write_b128 v112, v[180:183] offset:2048
	ds_write_b128 v112, v[184:187] offset:3072
	v_mfma_f32_32x32x16_bf16 v[32:47], v[120:123], v[52:55], v[32:47]
	v_mfma_f32_32x32x16_bf16 v[32:47], v[124:127], v[56:59], v[32:47]
	v_mfma_f32_32x32x16_bf16 v[32:47], v[128:131], v[60:63], v[32:47]
	s_nop 11
	v_exp_f32_e32 v32, v32
	v_exp_f32_e32 v33, v33
	v_exp_f32_e32 v34, v34
	v_exp_f32_e32 v35, v35
	v_exp_f32_e32 v36, v36
	v_exp_f32_e32 v37, v37
	v_exp_f32_e32 v38, v38
	v_exp_f32_e32 v39, v39
	v_exp_f32_e32 v40, v40
	v_exp_f32_e32 v41, v41
	v_exp_f32_e32 v42, v42
	v_exp_f32_e32 v43, v43
	v_exp_f32_e32 v44, v44
	v_exp_f32_e32 v45, v45
	v_exp_f32_e32 v46, v46
	v_exp_f32_e32 v47, v47
	s_add_i32 s90, s76, 224
	v_add_u32_e32 v84, s90, v107
	v_add_u32_e32 v85, 0, v84
	v_add_u32_e32 v86, 1, v84
	v_add_u32_e32 v87, 2, v84
	v_add_u32_e32 v88, 3, v84
	v_cmp_gt_u32_e64 s[30:31], s98, v85
	v_cmp_gt_u32_e64 s[36:37], s98, v86
	v_cmp_gt_u32_e64 s[78:79], s98, v87
	v_cmp_gt_u32_e64 s[50:51], s98, v88
	v_cndmask_b32_e64 v32, 0, v32, s[30:31]
	v_add_u32_e32 v85, 8, v84
	v_cmp_gt_u32_e64 s[30:31], s98, v85
	v_cndmask_b32_e64 v33, 0, v33, s[36:37]
	v_add_u32_e32 v86, 9, v84
	v_cmp_gt_u32_e64 s[36:37], s98, v86
	v_cndmask_b32_e64 v34, 0, v34, s[78:79]
	v_add_u32_e32 v87, 10, v84
	v_cmp_gt_u32_e64 s[78:79], s98, v87
	v_cndmask_b32_e64 v35, 0, v35, s[50:51]
	v_add_u32_e32 v88, 11, v84
	v_cmp_gt_u32_e64 s[50:51], s98, v88
	v_cndmask_b32_e64 v36, 0, v36, s[30:31]
	v_add_u32_e32 v85, 16, v84
	v_cmp_gt_u32_e64 s[30:31], s98, v85
	v_cndmask_b32_e64 v37, 0, v37, s[36:37]
	v_add_u32_e32 v86, 17, v84
	v_cmp_gt_u32_e64 s[36:37], s98, v86
	v_cndmask_b32_e64 v38, 0, v38, s[78:79]
	v_add_u32_e32 v87, 18, v84
	v_cmp_gt_u32_e64 s[78:79], s98, v87
	v_cndmask_b32_e64 v39, 0, v39, s[50:51]
	v_add_u32_e32 v88, 19, v84
	v_cmp_gt_u32_e64 s[50:51], s98, v88
	v_cndmask_b32_e64 v40, 0, v40, s[30:31]
	v_add_u32_e32 v85, 24, v84
	v_cmp_gt_u32_e64 s[30:31], s98, v85
	v_cndmask_b32_e64 v41, 0, v41, s[36:37]
	v_add_u32_e32 v86, 25, v84
	v_cmp_gt_u32_e64 s[36:37], s98, v86
	v_cndmask_b32_e64 v42, 0, v42, s[78:79]
	v_add_u32_e32 v87, 26, v84
	v_cmp_gt_u32_e64 s[78:79], s98, v87
	v_cndmask_b32_e64 v43, 0, v43, s[50:51]
	v_add_u32_e32 v88, 27, v84
	v_cmp_gt_u32_e64 s[50:51], s98, v88
	v_nop
	v_cndmask_b32_e64 v44, 0, v44, s[30:31]
	v_cndmask_b32_e64 v45, 0, v45, s[36:37]
	v_cndmask_b32_e64 v46, 0, v46, s[78:79]
	v_cndmask_b32_e64 v47, 0, v47, s[50:51]
	v_cvt_pk_bf16_f32 v64, v32, v33
	v_cvt_pk_bf16_f32 v65, v34, v35
	v_cvt_pk_bf16_f32 v66, v36, v37
	v_cvt_pk_bf16_f32 v67, v38, v39
	v_cvt_pk_bf16_f32 v68, v40, v41
	v_cvt_pk_bf16_f32 v69, v42, v43
	v_cvt_pk_bf16_f32 v70, v44, v45
	v_cvt_pk_bf16_f32 v71, v46, v47
	v_pk_add_f32 v[232:233], v[232:233], v[32:33]
	v_pk_add_f32 v[232:233], v[232:233], v[34:35]
	v_pk_add_f32 v[232:233], v[232:233], v[36:37]
	v_pk_add_f32 v[232:233], v[232:233], v[38:39]
	v_pk_add_f32 v[232:233], v[232:233], v[40:41]
	v_pk_add_f32 v[232:233], v[232:233], v[42:43]
	v_pk_add_f32 v[232:233], v[232:233], v[44:45]
	v_pk_add_f32 v[232:233], v[232:233], v[46:47]
	s_waitcnt lgkmcnt(12)
	v_mfma_f32_32x32x16_bf16 v[0:15], v[64:67], v[72:75], v[0:15]
	v_mfma_f32_32x32x16_bf16 v[16:31], v[64:67], v[76:79], v[16:31]
	v_mfma_f32_32x32x16_bf16 v[0:15], v[68:71], v[220:223], v[0:15]
	v_mfma_f32_32x32x16_bf16 v[16:31], v[68:71], v[224:227], v[16:31]
	s_add_i32 s90, s76, 320
	v_add_u32_e32 v80, s90, v235
	v_add_u32_e32 v83, s90, v236
	v_add_u32_e32 v99, s90, v237
	v_add_u32_e32 v253, s90, v238
	v_add_u32_e32 v254, s90, v100
	v_add_u32_e32 v255, s90, v149
	v_med3_i32 v80, v80, 0, s99
	v_med3_i32 v83, v83, 0, s99
	v_med3_i32 v99, v99, 0, s99
	v_med3_i32 v253, v253, 0, s99
	v_med3_i32 v254, v254, 0, s99
	v_med3_i32 v255, v255, 0, s99
	v_mad_u32_u24 v80, v80, s100, v252
	v_mad_u32_u24 v83, v83, s100, v252
	v_mad_u32_u24 v99, v99, s100, v252
	v_mad_u32_u24 v253, v253, s100, v252
	v_mad_u32_u24 v254, v254, s100, v153
	v_mad_u32_u24 v255, v255, s100, v153
	global_load_dwordx4 v[116:119], v80, s[82:83]
	global_load_dwordx4 v[120:123], v83, s[82:83]
	global_load_dwordx4 v[124:127], v99, s[82:83]
	global_load_dwordx4 v[128:131], v253, s[82:83]
	global_load_dwordx4 v[132:135], v254, s[82:83] offset:768
	global_load_dwordx4 v[136:139], v255, s[82:83] offset:768
	global_load_dwordx4 v[140:143], v254, s[82:83] offset:832
	global_load_dwordx4 v[144:147], v255, s[82:83] offset:832
	ds_read2_b32 v[32:33], v115 offset0:102 offset1:103
	ds_read2_b32 v[34:35], v115 offset0:104 offset1:105
	ds_read2_b32 v[36:37], v115 offset0:110 offset1:111
	ds_read2_b32 v[38:39], v115 offset0:112 offset1:113
	ds_read2_b32 v[40:41], v115 offset0:119 offset1:120
	ds_read2_b32 v[42:43], v115 offset0:121 offset1:122
	ds_read2_b32 v[44:45], v115 offset0:127 offset1:128
	ds_read2_b32 v[46:47], v115 offset0:129 offset1:130
	s_waitcnt lgkmcnt(0)
	v_mfma_f32_32x32x16_bf16 v[32:47], v[156:159], v[48:51], v[32:47]
	ds_read_b64_tr_b16 v[72:73], v231
	ds_read_b64_tr_b16 v[74:75], v231 offset:512
	ds_read_b64_tr_b16 v[76:77], v231 offset:2048
	ds_read_b64_tr_b16 v[78:79], v231 offset:2560
	ds_read_b64_tr_b16 v[220:221], v231 offset:1024
	ds_read_b64_tr_b16 v[222:223], v231 offset:1536
	ds_read_b64_tr_b16 v[224:225], v231 offset:3072
	ds_read_b64_tr_b16 v[226:227], v231 offset:3584
	s_waitcnt vmcnt(8)
	ds_write_b128 v247, v[188:191]
	ds_write_b128 v247, v[192:195] offset:1024
	ds_write_b128 v247, v[196:199] offset:2048
	ds_write_b128 v247, v[200:203] offset:3072
	ds_read_b128 v[188:191], v248
	ds_read_b128 v[192:195], v249
	ds_read_b128 v[196:199], v250
	ds_read_b128 v[200:203], v251
	ds_write_b128 v112, v[204:207]
	ds_write_b128 v112, v[208:211] offset:1024
	ds_write_b128 v112, v[212:215] offset:2048
	ds_write_b128 v112, v[216:219] offset:3072
	v_mfma_f32_32x32x16_bf16 v[32:47], v[160:163], v[52:55], v[32:47]
	v_mfma_f32_32x32x16_bf16 v[32:47], v[164:167], v[56:59], v[32:47]
	v_mfma_f32_32x32x16_bf16 v[32:47], v[168:171], v[60:63], v[32:47]
	s_nop 11
	v_exp_f32_e32 v32, v32
	v_exp_f32_e32 v33, v33
	v_exp_f32_e32 v34, v34
	v_exp_f32_e32 v35, v35
	v_exp_f32_e32 v36, v36
	v_exp_f32_e32 v37, v37
	v_exp_f32_e32 v38, v38
	v_exp_f32_e32 v39, v39
	v_exp_f32_e32 v40, v40
	v_exp_f32_e32 v41, v41
	v_exp_f32_e32 v42, v42
	v_exp_f32_e32 v43, v43
	v_exp_f32_e32 v44, v44
	v_exp_f32_e32 v45, v45
	v_exp_f32_e32 v46, v46
	v_exp_f32_e32 v47, v47
	s_add_i32 s90, s76, 256
	v_add_u32_e32 v84, s90, v107
	v_add_u32_e32 v85, 0, v84
	v_add_u32_e32 v86, 1, v84
	v_add_u32_e32 v87, 2, v84
	v_add_u32_e32 v88, 3, v84
	v_cmp_gt_u32_e64 s[30:31], s98, v85
	v_cmp_gt_u32_e64 s[36:37], s98, v86
	v_cmp_gt_u32_e64 s[78:79], s98, v87
	v_cmp_gt_u32_e64 s[50:51], s98, v88
	v_cndmask_b32_e64 v32, 0, v32, s[30:31]
	v_add_u32_e32 v85, 8, v84
	v_cmp_gt_u32_e64 s[30:31], s98, v85
	v_cndmask_b32_e64 v33, 0, v33, s[36:37]
	v_add_u32_e32 v86, 9, v84
	v_cmp_gt_u32_e64 s[36:37], s98, v86
	v_cndmask_b32_e64 v34, 0, v34, s[78:79]
	v_add_u32_e32 v87, 10, v84
	v_cmp_gt_u32_e64 s[78:79], s98, v87
	v_cndmask_b32_e64 v35, 0, v35, s[50:51]
	v_add_u32_e32 v88, 11, v84
	v_cmp_gt_u32_e64 s[50:51], s98, v88
	v_cndmask_b32_e64 v36, 0, v36, s[30:31]
	v_add_u32_e32 v85, 16, v84
	v_cmp_gt_u32_e64 s[30:31], s98, v85
	v_cndmask_b32_e64 v37, 0, v37, s[36:37]
	v_add_u32_e32 v86, 17, v84
	v_cmp_gt_u32_e64 s[36:37], s98, v86
	v_cndmask_b32_e64 v38, 0, v38, s[78:79]
	v_add_u32_e32 v87, 18, v84
	v_cmp_gt_u32_e64 s[78:79], s98, v87
	v_cndmask_b32_e64 v39, 0, v39, s[50:51]
	v_add_u32_e32 v88, 19, v84
	v_cmp_gt_u32_e64 s[50:51], s98, v88
	v_cndmask_b32_e64 v40, 0, v40, s[30:31]
	v_add_u32_e32 v85, 24, v84
	v_cmp_gt_u32_e64 s[30:31], s98, v85
	v_cndmask_b32_e64 v41, 0, v41, s[36:37]
	v_add_u32_e32 v86, 25, v84
	v_cmp_gt_u32_e64 s[36:37], s98, v86
	v_cndmask_b32_e64 v42, 0, v42, s[78:79]
	v_add_u32_e32 v87, 26, v84
	v_cmp_gt_u32_e64 s[78:79], s98, v87
	v_cndmask_b32_e64 v43, 0, v43, s[50:51]
	v_add_u32_e32 v88, 27, v84
	v_cmp_gt_u32_e64 s[50:51], s98, v88
	v_nop
	v_cndmask_b32_e64 v44, 0, v44, s[30:31]
	v_cndmask_b32_e64 v45, 0, v45, s[36:37]
	v_cndmask_b32_e64 v46, 0, v46, s[78:79]
	v_cndmask_b32_e64 v47, 0, v47, s[50:51]
	v_cvt_pk_bf16_f32 v64, v32, v33
	v_cvt_pk_bf16_f32 v65, v34, v35
	v_cvt_pk_bf16_f32 v66, v36, v37
	v_cvt_pk_bf16_f32 v67, v38, v39
	v_cvt_pk_bf16_f32 v68, v40, v41
	v_cvt_pk_bf16_f32 v69, v42, v43
	v_cvt_pk_bf16_f32 v70, v44, v45
	v_cvt_pk_bf16_f32 v71, v46, v47
	v_pk_add_f32 v[232:233], v[232:233], v[32:33]
	v_pk_add_f32 v[232:233], v[232:233], v[34:35]
	v_pk_add_f32 v[232:233], v[232:233], v[36:37]
	v_pk_add_f32 v[232:233], v[232:233], v[38:39]
	v_pk_add_f32 v[232:233], v[232:233], v[40:41]
	v_pk_add_f32 v[232:233], v[232:233], v[42:43]
	v_pk_add_f32 v[232:233], v[232:233], v[44:45]
	v_pk_add_f32 v[232:233], v[232:233], v[46:47]
	s_waitcnt lgkmcnt(12)
	v_mfma_f32_32x32x16_bf16 v[0:15], v[64:67], v[72:75], v[0:15]
	v_mfma_f32_32x32x16_bf16 v[16:31], v[64:67], v[76:79], v[16:31]
	v_mfma_f32_32x32x16_bf16 v[0:15], v[68:71], v[220:223], v[0:15]
	v_mfma_f32_32x32x16_bf16 v[16:31], v[68:71], v[224:227], v[16:31]
	s_add_i32 s90, s76, 352
	v_add_u32_e32 v80, s90, v235
	v_add_u32_e32 v83, s90, v236
	v_add_u32_e32 v99, s90, v237
	v_add_u32_e32 v253, s90, v238
	v_add_u32_e32 v254, s90, v100
	v_add_u32_e32 v255, s90, v149
	v_med3_i32 v80, v80, 0, s99
	v_med3_i32 v83, v83, 0, s99
	v_med3_i32 v99, v99, 0, s99
	v_med3_i32 v253, v253, 0, s99
	v_med3_i32 v254, v254, 0, s99
	v_med3_i32 v255, v255, 0, s99
	v_mad_u32_u24 v80, v80, s100, v252
	v_mad_u32_u24 v83, v83, s100, v252
	v_mad_u32_u24 v99, v99, s100, v252
	v_mad_u32_u24 v253, v253, s100, v252
	v_mad_u32_u24 v254, v254, s100, v153
	v_mad_u32_u24 v255, v255, s100, v153
	global_load_dwordx4 v[156:159], v80, s[82:83]
	global_load_dwordx4 v[160:163], v83, s[82:83]
	global_load_dwordx4 v[164:167], v99, s[82:83]
	global_load_dwordx4 v[168:171], v253, s[82:83]
	global_load_dwordx4 v[172:175], v254, s[82:83] offset:768
	global_load_dwordx4 v[176:179], v255, s[82:83] offset:768
	global_load_dwordx4 v[180:183], v254, s[82:83] offset:832
	global_load_dwordx4 v[184:187], v255, s[82:83] offset:832
	ds_read2_b32 v[32:33], v115 offset0:136 offset1:137
	ds_read2_b32 v[34:35], v115 offset0:138 offset1:139
	ds_read2_b32 v[36:37], v115 offset0:144 offset1:145
	ds_read2_b32 v[38:39], v115 offset0:146 offset1:147
	ds_read2_b32 v[40:41], v115 offset0:153 offset1:154
	ds_read2_b32 v[42:43], v115 offset0:155 offset1:156
	ds_read2_b32 v[44:45], v115 offset0:161 offset1:162
	ds_read2_b32 v[46:47], v115 offset0:163 offset1:164
	s_waitcnt lgkmcnt(0)
	v_mfma_f32_32x32x16_bf16 v[32:47], v[188:191], v[48:51], v[32:47]
	ds_read_b64_tr_b16 v[72:73], v231
	ds_read_b64_tr_b16 v[74:75], v231 offset:512
	ds_read_b64_tr_b16 v[76:77], v231 offset:2048
	ds_read_b64_tr_b16 v[78:79], v231 offset:2560
	ds_read_b64_tr_b16 v[220:221], v231 offset:1024
	ds_read_b64_tr_b16 v[222:223], v231 offset:1536
	ds_read_b64_tr_b16 v[224:225], v231 offset:3072
	ds_read_b64_tr_b16 v[226:227], v231 offset:3584
	s_waitcnt vmcnt(8)
	ds_write_b128 v247, v[116:119]
	ds_write_b128 v247, v[120:123] offset:1024
	ds_write_b128 v247, v[124:127] offset:2048
	ds_write_b128 v247, v[128:131] offset:3072
	ds_read_b128 v[116:119], v248
	ds_read_b128 v[120:123], v249
	ds_read_b128 v[124:127], v250
	ds_read_b128 v[128:131], v251
	ds_write_b128 v112, v[132:135]
	ds_write_b128 v112, v[136:139] offset:1024
	ds_write_b128 v112, v[140:143] offset:2048
	ds_write_b128 v112, v[144:147] offset:3072
	v_mfma_f32_32x32x16_bf16 v[32:47], v[192:195], v[52:55], v[32:47]
	v_mfma_f32_32x32x16_bf16 v[32:47], v[196:199], v[56:59], v[32:47]
	v_mfma_f32_32x32x16_bf16 v[32:47], v[200:203], v[60:63], v[32:47]
	s_nop 11
	v_exp_f32_e32 v32, v32
	v_exp_f32_e32 v33, v33
	v_exp_f32_e32 v34, v34
	v_exp_f32_e32 v35, v35
	v_exp_f32_e32 v36, v36
	v_exp_f32_e32 v37, v37
	v_exp_f32_e32 v38, v38
	v_exp_f32_e32 v39, v39
	v_exp_f32_e32 v40, v40
	v_exp_f32_e32 v41, v41
	v_exp_f32_e32 v42, v42
	v_exp_f32_e32 v43, v43
	v_exp_f32_e32 v44, v44
	v_exp_f32_e32 v45, v45
	v_exp_f32_e32 v46, v46
	v_exp_f32_e32 v47, v47
	s_add_i32 s90, s76, 288
	v_add_u32_e32 v84, s90, v107
	v_add_u32_e32 v85, 0, v84
	v_add_u32_e32 v86, 1, v84
	v_add_u32_e32 v87, 2, v84
	v_add_u32_e32 v88, 3, v84
	v_cmp_gt_u32_e64 s[30:31], s98, v85
	v_cmp_gt_u32_e64 s[36:37], s98, v86
	v_cmp_gt_u32_e64 s[78:79], s98, v87
	v_cmp_gt_u32_e64 s[50:51], s98, v88
	v_cndmask_b32_e64 v32, 0, v32, s[30:31]
	v_add_u32_e32 v85, 8, v84
	v_cmp_gt_u32_e64 s[30:31], s98, v85
	v_cndmask_b32_e64 v33, 0, v33, s[36:37]
	v_add_u32_e32 v86, 9, v84
	v_cmp_gt_u32_e64 s[36:37], s98, v86
	v_cndmask_b32_e64 v34, 0, v34, s[78:79]
	v_add_u32_e32 v87, 10, v84
	v_cmp_gt_u32_e64 s[78:79], s98, v87
	v_cndmask_b32_e64 v35, 0, v35, s[50:51]
	v_add_u32_e32 v88, 11, v84
	v_cmp_gt_u32_e64 s[50:51], s98, v88
	v_cndmask_b32_e64 v36, 0, v36, s[30:31]
	v_add_u32_e32 v85, 16, v84
	v_cmp_gt_u32_e64 s[30:31], s98, v85
	v_cndmask_b32_e64 v37, 0, v37, s[36:37]
	v_add_u32_e32 v86, 17, v84
	v_cmp_gt_u32_e64 s[36:37], s98, v86
	v_cndmask_b32_e64 v38, 0, v38, s[78:79]
	v_add_u32_e32 v87, 18, v84
	v_cmp_gt_u32_e64 s[78:79], s98, v87
	v_cndmask_b32_e64 v39, 0, v39, s[50:51]
	v_add_u32_e32 v88, 19, v84
	v_cmp_gt_u32_e64 s[50:51], s98, v88
	v_cndmask_b32_e64 v40, 0, v40, s[30:31]
	v_add_u32_e32 v85, 24, v84
	v_cmp_gt_u32_e64 s[30:31], s98, v85
	v_cndmask_b32_e64 v41, 0, v41, s[36:37]
	v_add_u32_e32 v86, 25, v84
	v_cmp_gt_u32_e64 s[36:37], s98, v86
	v_cndmask_b32_e64 v42, 0, v42, s[78:79]
	v_add_u32_e32 v87, 26, v84
	v_cmp_gt_u32_e64 s[78:79], s98, v87
	v_cndmask_b32_e64 v43, 0, v43, s[50:51]
	v_add_u32_e32 v88, 27, v84
	v_cmp_gt_u32_e64 s[50:51], s98, v88
	v_nop
	v_cndmask_b32_e64 v44, 0, v44, s[30:31]
	v_cndmask_b32_e64 v45, 0, v45, s[36:37]
	v_cndmask_b32_e64 v46, 0, v46, s[78:79]
	v_cndmask_b32_e64 v47, 0, v47, s[50:51]
	v_cvt_pk_bf16_f32 v64, v32, v33
	v_cvt_pk_bf16_f32 v65, v34, v35
	v_cvt_pk_bf16_f32 v66, v36, v37
	v_cvt_pk_bf16_f32 v67, v38, v39
	v_cvt_pk_bf16_f32 v68, v40, v41
	v_cvt_pk_bf16_f32 v69, v42, v43
	v_cvt_pk_bf16_f32 v70, v44, v45
	v_cvt_pk_bf16_f32 v71, v46, v47
	v_pk_add_f32 v[232:233], v[232:233], v[32:33]
	v_pk_add_f32 v[232:233], v[232:233], v[34:35]
	v_pk_add_f32 v[232:233], v[232:233], v[36:37]
	v_pk_add_f32 v[232:233], v[232:233], v[38:39]
	v_pk_add_f32 v[232:233], v[232:233], v[40:41]
	v_pk_add_f32 v[232:233], v[232:233], v[42:43]
	v_pk_add_f32 v[232:233], v[232:233], v[44:45]
	v_pk_add_f32 v[232:233], v[232:233], v[46:47]
	s_waitcnt lgkmcnt(12)
	v_mfma_f32_32x32x16_bf16 v[0:15], v[64:67], v[72:75], v[0:15]
	v_mfma_f32_32x32x16_bf16 v[16:31], v[64:67], v[76:79], v[16:31]
	v_mfma_f32_32x32x16_bf16 v[0:15], v[68:71], v[220:223], v[0:15]
	v_mfma_f32_32x32x16_bf16 v[16:31], v[68:71], v[224:227], v[16:31]
	s_add_i32 s90, s76, 384
	v_add_u32_e32 v80, s90, v235
	v_add_u32_e32 v83, s90, v236
	v_add_u32_e32 v99, s90, v237
	v_add_u32_e32 v253, s90, v238
	v_add_u32_e32 v254, s90, v100
	v_add_u32_e32 v255, s90, v149
	v_med3_i32 v80, v80, 0, s99
	v_med3_i32 v83, v83, 0, s99
	v_med3_i32 v99, v99, 0, s99
	v_med3_i32 v253, v253, 0, s99
	v_med3_i32 v254, v254, 0, s99
	v_med3_i32 v255, v255, 0, s99
	v_mad_u32_u24 v80, v80, s100, v252
	v_mad_u32_u24 v83, v83, s100, v252
	v_mad_u32_u24 v99, v99, s100, v252
	v_mad_u32_u24 v253, v253, s100, v252
	v_mad_u32_u24 v254, v254, s100, v153
	v_mad_u32_u24 v255, v255, s100, v153
	global_load_dwordx4 v[188:191], v80, s[82:83]
	global_load_dwordx4 v[192:195], v83, s[82:83]
	global_load_dwordx4 v[196:199], v99, s[82:83]
	global_load_dwordx4 v[200:203], v253, s[82:83]
	global_load_dwordx4 v[204:207], v254, s[82:83] offset:768
	global_load_dwordx4 v[208:211], v255, s[82:83] offset:768
	global_load_dwordx4 v[212:215], v254, s[82:83] offset:832
	global_load_dwordx4 v[216:219], v255, s[82:83] offset:832
	ds_read2_b32 v[32:33], v115 offset0:170 offset1:171
	ds_read2_b32 v[34:35], v115 offset0:172 offset1:173
	ds_read2_b32 v[36:37], v115 offset0:178 offset1:179
	ds_read2_b32 v[38:39], v115 offset0:180 offset1:181
	ds_read2_b32 v[40:41], v115 offset0:187 offset1:188
	ds_read2_b32 v[42:43], v115 offset0:189 offset1:190
	ds_read2_b32 v[44:45], v115 offset0:195 offset1:196
	ds_read2_b32 v[46:47], v115 offset0:197 offset1:198
	s_waitcnt lgkmcnt(0)
	v_mfma_f32_32x32x16_bf16 v[32:47], v[116:119], v[48:51], v[32:47]
	ds_read_b64_tr_b16 v[72:73], v231
	ds_read_b64_tr_b16 v[74:75], v231 offset:512
	ds_read_b64_tr_b16 v[76:77], v231 offset:2048
	ds_read_b64_tr_b16 v[78:79], v231 offset:2560
	ds_read_b64_tr_b16 v[220:221], v231 offset:1024
	ds_read_b64_tr_b16 v[222:223], v231 offset:1536
	ds_read_b64_tr_b16 v[224:225], v231 offset:3072
	ds_read_b64_tr_b16 v[226:227], v231 offset:3584
	s_waitcnt vmcnt(8)
	ds_write_b128 v247, v[156:159]
	ds_write_b128 v247, v[160:163] offset:1024
	ds_write_b128 v247, v[164:167] offset:2048
	ds_write_b128 v247, v[168:171] offset:3072
	ds_read_b128 v[156:159], v248
	ds_read_b128 v[160:163], v249
	ds_read_b128 v[164:167], v250
	ds_read_b128 v[168:171], v251
	ds_write_b128 v112, v[172:175]
	ds_write_b128 v112, v[176:179] offset:1024
	ds_write_b128 v112, v[180:183] offset:2048
	ds_write_b128 v112, v[184:187] offset:3072
	v_mfma_f32_32x32x16_bf16 v[32:47], v[120:123], v[52:55], v[32:47]
	v_mfma_f32_32x32x16_bf16 v[32:47], v[124:127], v[56:59], v[32:47]
	v_mfma_f32_32x32x16_bf16 v[32:47], v[128:131], v[60:63], v[32:47]
	s_nop 11
	v_exp_f32_e32 v32, v32
	v_exp_f32_e32 v33, v33
	v_exp_f32_e32 v34, v34
	v_exp_f32_e32 v35, v35
	v_exp_f32_e32 v36, v36
	v_exp_f32_e32 v37, v37
	v_exp_f32_e32 v38, v38
	v_exp_f32_e32 v39, v39
	v_exp_f32_e32 v40, v40
	v_exp_f32_e32 v41, v41
	v_exp_f32_e32 v42, v42
	v_exp_f32_e32 v43, v43
	v_exp_f32_e32 v44, v44
	v_exp_f32_e32 v45, v45
	v_exp_f32_e32 v46, v46
	v_exp_f32_e32 v47, v47
	s_add_i32 s90, s76, 320
	v_add_u32_e32 v84, s90, v107
	v_add_u32_e32 v85, 0, v84
	v_add_u32_e32 v86, 1, v84
	v_add_u32_e32 v87, 2, v84
	v_add_u32_e32 v88, 3, v84
	v_cmp_gt_u32_e64 s[30:31], s98, v85
	v_cmp_gt_u32_e64 s[36:37], s98, v86
	v_cmp_gt_u32_e64 s[78:79], s98, v87
	v_cmp_gt_u32_e64 s[50:51], s98, v88
	v_cndmask_b32_e64 v32, 0, v32, s[30:31]
	v_add_u32_e32 v85, 8, v84
	v_cmp_gt_u32_e64 s[30:31], s98, v85
	v_cndmask_b32_e64 v33, 0, v33, s[36:37]
	v_add_u32_e32 v86, 9, v84
	v_cmp_gt_u32_e64 s[36:37], s98, v86
	v_cndmask_b32_e64 v34, 0, v34, s[78:79]
	v_add_u32_e32 v87, 10, v84
	v_cmp_gt_u32_e64 s[78:79], s98, v87
	v_cndmask_b32_e64 v35, 0, v35, s[50:51]
	v_add_u32_e32 v88, 11, v84
	v_cmp_gt_u32_e64 s[50:51], s98, v88
	v_cndmask_b32_e64 v36, 0, v36, s[30:31]
	v_add_u32_e32 v85, 16, v84
	v_cmp_gt_u32_e64 s[30:31], s98, v85
	v_cndmask_b32_e64 v37, 0, v37, s[36:37]
	v_add_u32_e32 v86, 17, v84
	v_cmp_gt_u32_e64 s[36:37], s98, v86
	v_cndmask_b32_e64 v38, 0, v38, s[78:79]
	v_add_u32_e32 v87, 18, v84
	v_cmp_gt_u32_e64 s[78:79], s98, v87
	v_cndmask_b32_e64 v39, 0, v39, s[50:51]
	v_add_u32_e32 v88, 19, v84
	v_cmp_gt_u32_e64 s[50:51], s98, v88
	v_cndmask_b32_e64 v40, 0, v40, s[30:31]
	v_add_u32_e32 v85, 24, v84
	v_cmp_gt_u32_e64 s[30:31], s98, v85
	v_cndmask_b32_e64 v41, 0, v41, s[36:37]
	v_add_u32_e32 v86, 25, v84
	v_cmp_gt_u32_e64 s[36:37], s98, v86
	v_cndmask_b32_e64 v42, 0, v42, s[78:79]
	v_add_u32_e32 v87, 26, v84
	v_cmp_gt_u32_e64 s[78:79], s98, v87
	v_cndmask_b32_e64 v43, 0, v43, s[50:51]
	v_add_u32_e32 v88, 27, v84
	v_cmp_gt_u32_e64 s[50:51], s98, v88
	v_nop
	v_cndmask_b32_e64 v44, 0, v44, s[30:31]
	v_cndmask_b32_e64 v45, 0, v45, s[36:37]
	v_cndmask_b32_e64 v46, 0, v46, s[78:79]
	v_cndmask_b32_e64 v47, 0, v47, s[50:51]
	v_cvt_pk_bf16_f32 v64, v32, v33
	v_cvt_pk_bf16_f32 v65, v34, v35
	v_cvt_pk_bf16_f32 v66, v36, v37
	v_cvt_pk_bf16_f32 v67, v38, v39
	v_cvt_pk_bf16_f32 v68, v40, v41
	v_cvt_pk_bf16_f32 v69, v42, v43
	v_cvt_pk_bf16_f32 v70, v44, v45
	v_cvt_pk_bf16_f32 v71, v46, v47
	v_pk_add_f32 v[232:233], v[232:233], v[32:33]
	v_pk_add_f32 v[232:233], v[232:233], v[34:35]
	v_pk_add_f32 v[232:233], v[232:233], v[36:37]
	v_pk_add_f32 v[232:233], v[232:233], v[38:39]
	v_pk_add_f32 v[232:233], v[232:233], v[40:41]
	v_pk_add_f32 v[232:233], v[232:233], v[42:43]
	v_pk_add_f32 v[232:233], v[232:233], v[44:45]
	v_pk_add_f32 v[232:233], v[232:233], v[46:47]
	s_waitcnt lgkmcnt(12)
	v_mfma_f32_32x32x16_bf16 v[0:15], v[64:67], v[72:75], v[0:15]
	v_mfma_f32_32x32x16_bf16 v[16:31], v[64:67], v[76:79], v[16:31]
	v_mfma_f32_32x32x16_bf16 v[0:15], v[68:71], v[220:223], v[0:15]
	v_mfma_f32_32x32x16_bf16 v[16:31], v[68:71], v[224:227], v[16:31]
	s_add_i32 s90, s76, 416
	v_add_u32_e32 v80, s90, v235
	v_add_u32_e32 v83, s90, v236
	v_add_u32_e32 v99, s90, v237
	v_add_u32_e32 v253, s90, v238
	v_add_u32_e32 v254, s90, v100
	v_add_u32_e32 v255, s90, v149
	v_med3_i32 v80, v80, 0, s99
	v_med3_i32 v83, v83, 0, s99
	v_med3_i32 v99, v99, 0, s99
	v_med3_i32 v253, v253, 0, s99
	v_med3_i32 v254, v254, 0, s99
	v_med3_i32 v255, v255, 0, s99
	v_mad_u32_u24 v80, v80, s100, v252
	v_mad_u32_u24 v83, v83, s100, v252
	v_mad_u32_u24 v99, v99, s100, v252
	v_mad_u32_u24 v253, v253, s100, v252
	v_mad_u32_u24 v254, v254, s100, v153
	v_mad_u32_u24 v255, v255, s100, v153
	global_load_dwordx4 v[116:119], v80, s[82:83]
	global_load_dwordx4 v[120:123], v83, s[82:83]
	global_load_dwordx4 v[124:127], v99, s[82:83]
	global_load_dwordx4 v[128:131], v253, s[82:83]
	global_load_dwordx4 v[132:135], v254, s[82:83] offset:768
	global_load_dwordx4 v[136:139], v255, s[82:83] offset:768
	global_load_dwordx4 v[140:143], v254, s[82:83] offset:832
	global_load_dwordx4 v[144:147], v255, s[82:83] offset:832
	ds_read2_b32 v[32:33], v115 offset0:204 offset1:205
	ds_read2_b32 v[34:35], v115 offset0:206 offset1:207
	ds_read2_b32 v[36:37], v115 offset0:212 offset1:213
	ds_read2_b32 v[38:39], v115 offset0:214 offset1:215
	ds_read2_b32 v[40:41], v115 offset0:221 offset1:222
	ds_read2_b32 v[42:43], v115 offset0:223 offset1:224
	ds_read2_b32 v[44:45], v115 offset0:229 offset1:230
	ds_read2_b32 v[46:47], v115 offset0:231 offset1:232
	s_waitcnt lgkmcnt(0)
	v_mfma_f32_32x32x16_bf16 v[32:47], v[156:159], v[48:51], v[32:47]
	ds_read_b64_tr_b16 v[72:73], v231
	ds_read_b64_tr_b16 v[74:75], v231 offset:512
	ds_read_b64_tr_b16 v[76:77], v231 offset:2048
	ds_read_b64_tr_b16 v[78:79], v231 offset:2560
	ds_read_b64_tr_b16 v[220:221], v231 offset:1024
	ds_read_b64_tr_b16 v[222:223], v231 offset:1536
	ds_read_b64_tr_b16 v[224:225], v231 offset:3072
	ds_read_b64_tr_b16 v[226:227], v231 offset:3584
	s_waitcnt vmcnt(8)
	ds_write_b128 v247, v[188:191]
	ds_write_b128 v247, v[192:195] offset:1024
	ds_write_b128 v247, v[196:199] offset:2048
	ds_write_b128 v247, v[200:203] offset:3072
	ds_read_b128 v[188:191], v248
	ds_read_b128 v[192:195], v249
	ds_read_b128 v[196:199], v250
	ds_read_b128 v[200:203], v251
	ds_write_b128 v112, v[204:207]
	ds_write_b128 v112, v[208:211] offset:1024
	ds_write_b128 v112, v[212:215] offset:2048
	ds_write_b128 v112, v[216:219] offset:3072
	v_mfma_f32_32x32x16_bf16 v[32:47], v[160:163], v[52:55], v[32:47]
	v_mfma_f32_32x32x16_bf16 v[32:47], v[164:167], v[56:59], v[32:47]
	v_mfma_f32_32x32x16_bf16 v[32:47], v[168:171], v[60:63], v[32:47]
	s_nop 11
	v_exp_f32_e32 v32, v32
	v_exp_f32_e32 v33, v33
	v_exp_f32_e32 v34, v34
	v_exp_f32_e32 v35, v35
	v_exp_f32_e32 v36, v36
	v_exp_f32_e32 v37, v37
	v_exp_f32_e32 v38, v38
	v_exp_f32_e32 v39, v39
	v_exp_f32_e32 v40, v40
	v_exp_f32_e32 v41, v41
	v_exp_f32_e32 v42, v42
	v_exp_f32_e32 v43, v43
	v_exp_f32_e32 v44, v44
	v_exp_f32_e32 v45, v45
	v_exp_f32_e32 v46, v46
	v_exp_f32_e32 v47, v47
	s_add_i32 s90, s76, 352
	v_add_u32_e32 v84, s90, v107
	v_add_u32_e32 v85, 0, v84
	v_add_u32_e32 v86, 1, v84
	v_add_u32_e32 v87, 2, v84
	v_add_u32_e32 v88, 3, v84
	v_cmp_gt_u32_e64 s[30:31], s98, v85
	v_cmp_gt_u32_e64 s[36:37], s98, v86
	v_cmp_gt_u32_e64 s[78:79], s98, v87
	v_cmp_gt_u32_e64 s[50:51], s98, v88
	v_cndmask_b32_e64 v32, 0, v32, s[30:31]
	v_add_u32_e32 v85, 8, v84
	v_cmp_gt_u32_e64 s[30:31], s98, v85
	v_cndmask_b32_e64 v33, 0, v33, s[36:37]
	v_add_u32_e32 v86, 9, v84
	v_cmp_gt_u32_e64 s[36:37], s98, v86
	v_cndmask_b32_e64 v34, 0, v34, s[78:79]
	v_add_u32_e32 v87, 10, v84
	v_cmp_gt_u32_e64 s[78:79], s98, v87
	v_cndmask_b32_e64 v35, 0, v35, s[50:51]
	v_add_u32_e32 v88, 11, v84
	v_cmp_gt_u32_e64 s[50:51], s98, v88
	v_cndmask_b32_e64 v36, 0, v36, s[30:31]
	v_add_u32_e32 v85, 16, v84
	v_cmp_gt_u32_e64 s[30:31], s98, v85
	v_cndmask_b32_e64 v37, 0, v37, s[36:37]
	v_add_u32_e32 v86, 17, v84
	v_cmp_gt_u32_e64 s[36:37], s98, v86
	v_cndmask_b32_e64 v38, 0, v38, s[78:79]
	v_add_u32_e32 v87, 18, v84
	v_cmp_gt_u32_e64 s[78:79], s98, v87
	v_cndmask_b32_e64 v39, 0, v39, s[50:51]
	v_add_u32_e32 v88, 19, v84
	v_cmp_gt_u32_e64 s[50:51], s98, v88
	v_cndmask_b32_e64 v40, 0, v40, s[30:31]
	v_add_u32_e32 v85, 24, v84
	v_cmp_gt_u32_e64 s[30:31], s98, v85
	v_cndmask_b32_e64 v41, 0, v41, s[36:37]
	v_add_u32_e32 v86, 25, v84
	v_cmp_gt_u32_e64 s[36:37], s98, v86
	v_cndmask_b32_e64 v42, 0, v42, s[78:79]
	v_add_u32_e32 v87, 26, v84
	v_cmp_gt_u32_e64 s[78:79], s98, v87
	v_cndmask_b32_e64 v43, 0, v43, s[50:51]
	v_add_u32_e32 v88, 27, v84
	v_cmp_gt_u32_e64 s[50:51], s98, v88
	v_nop
	v_cndmask_b32_e64 v44, 0, v44, s[30:31]
	v_cndmask_b32_e64 v45, 0, v45, s[36:37]
	v_cndmask_b32_e64 v46, 0, v46, s[78:79]
	v_cndmask_b32_e64 v47, 0, v47, s[50:51]
	v_cvt_pk_bf16_f32 v64, v32, v33
	v_cvt_pk_bf16_f32 v65, v34, v35
	v_cvt_pk_bf16_f32 v66, v36, v37
	v_cvt_pk_bf16_f32 v67, v38, v39
	v_cvt_pk_bf16_f32 v68, v40, v41
	v_cvt_pk_bf16_f32 v69, v42, v43
	v_cvt_pk_bf16_f32 v70, v44, v45
	v_cvt_pk_bf16_f32 v71, v46, v47
	v_pk_add_f32 v[232:233], v[232:233], v[32:33]
	v_pk_add_f32 v[232:233], v[232:233], v[34:35]
	v_pk_add_f32 v[232:233], v[232:233], v[36:37]
	v_pk_add_f32 v[232:233], v[232:233], v[38:39]
	v_pk_add_f32 v[232:233], v[232:233], v[40:41]
	v_pk_add_f32 v[232:233], v[232:233], v[42:43]
	v_pk_add_f32 v[232:233], v[232:233], v[44:45]
	v_pk_add_f32 v[232:233], v[232:233], v[46:47]
	s_waitcnt lgkmcnt(12)
	v_mfma_f32_32x32x16_bf16 v[0:15], v[64:67], v[72:75], v[0:15]
	v_mfma_f32_32x32x16_bf16 v[16:31], v[64:67], v[76:79], v[16:31]
	v_mfma_f32_32x32x16_bf16 v[0:15], v[68:71], v[220:223], v[0:15]
	v_mfma_f32_32x32x16_bf16 v[16:31], v[68:71], v[224:227], v[16:31]
	s_add_i32 s90, s76, 448
	v_add_u32_e32 v80, s90, v235
	v_add_u32_e32 v83, s90, v236
	v_add_u32_e32 v99, s90, v237
	v_add_u32_e32 v253, s90, v238
	v_add_u32_e32 v254, s90, v100
	v_add_u32_e32 v255, s90, v149
	v_med3_i32 v80, v80, 0, s99
	v_med3_i32 v83, v83, 0, s99
	v_med3_i32 v99, v99, 0, s99
	v_med3_i32 v253, v253, 0, s99
	v_med3_i32 v254, v254, 0, s99
	v_med3_i32 v255, v255, 0, s99
	v_mad_u32_u24 v80, v80, s100, v252
	v_mad_u32_u24 v83, v83, s100, v252
	v_mad_u32_u24 v99, v99, s100, v252
	v_mad_u32_u24 v253, v253, s100, v252
	v_mad_u32_u24 v254, v254, s100, v153
	v_mad_u32_u24 v255, v255, s100, v153
	global_load_dwordx4 v[156:159], v80, s[82:83]
	global_load_dwordx4 v[160:163], v83, s[82:83]
	global_load_dwordx4 v[164:167], v99, s[82:83]
	global_load_dwordx4 v[168:171], v253, s[82:83]
	global_load_dwordx4 v[172:175], v254, s[82:83] offset:768
	global_load_dwordx4 v[176:179], v255, s[82:83] offset:768
	global_load_dwordx4 v[180:183], v254, s[82:83] offset:832
	global_load_dwordx4 v[184:187], v255, s[82:83] offset:832
	v_add_u32_e32 v115, 952, v115
	ds_read2_b32 v[32:33], v115 offset0:0 offset1:1
	ds_read2_b32 v[34:35], v115 offset0:2 offset1:3
	ds_read2_b32 v[36:37], v115 offset0:8 offset1:9
	ds_read2_b32 v[38:39], v115 offset0:10 offset1:11
	ds_read2_b32 v[40:41], v115 offset0:17 offset1:18
	ds_read2_b32 v[42:43], v115 offset0:19 offset1:20
	ds_read2_b32 v[44:45], v115 offset0:25 offset1:26
	ds_read2_b32 v[46:47], v115 offset0:27 offset1:28
	s_waitcnt lgkmcnt(0)
	v_mfma_f32_32x32x16_bf16 v[32:47], v[188:191], v[48:51], v[32:47]
	ds_read_b64_tr_b16 v[72:73], v231
	ds_read_b64_tr_b16 v[74:75], v231 offset:512
	ds_read_b64_tr_b16 v[76:77], v231 offset:2048
	ds_read_b64_tr_b16 v[78:79], v231 offset:2560
	ds_read_b64_tr_b16 v[220:221], v231 offset:1024
	ds_read_b64_tr_b16 v[222:223], v231 offset:1536
	ds_read_b64_tr_b16 v[224:225], v231 offset:3072
	ds_read_b64_tr_b16 v[226:227], v231 offset:3584
	s_waitcnt vmcnt(8)
	ds_write_b128 v247, v[116:119]
	ds_write_b128 v247, v[120:123] offset:1024
	ds_write_b128 v247, v[124:127] offset:2048
	ds_write_b128 v247, v[128:131] offset:3072
	ds_read_b128 v[116:119], v248
	ds_read_b128 v[120:123], v249
	ds_read_b128 v[124:127], v250
	ds_read_b128 v[128:131], v251
	ds_write_b128 v112, v[132:135]
	ds_write_b128 v112, v[136:139] offset:1024
	ds_write_b128 v112, v[140:143] offset:2048
	ds_write_b128 v112, v[144:147] offset:3072
	v_mfma_f32_32x32x16_bf16 v[32:47], v[192:195], v[52:55], v[32:47]
	v_mfma_f32_32x32x16_bf16 v[32:47], v[196:199], v[56:59], v[32:47]
	v_mfma_f32_32x32x16_bf16 v[32:47], v[200:203], v[60:63], v[32:47]
	s_nop 11
	v_exp_f32_e32 v32, v32
	v_exp_f32_e32 v33, v33
	v_exp_f32_e32 v34, v34
	v_exp_f32_e32 v35, v35
	v_exp_f32_e32 v36, v36
	v_exp_f32_e32 v37, v37
	v_exp_f32_e32 v38, v38
	v_exp_f32_e32 v39, v39
	v_exp_f32_e32 v40, v40
	v_exp_f32_e32 v41, v41
	v_exp_f32_e32 v42, v42
	v_exp_f32_e32 v43, v43
	v_exp_f32_e32 v44, v44
	v_exp_f32_e32 v45, v45
	v_exp_f32_e32 v46, v46
	v_exp_f32_e32 v47, v47
	s_add_i32 s90, s76, 384
	v_add_u32_e32 v84, s90, v107
	v_add_u32_e32 v85, 0, v84
	v_add_u32_e32 v86, 1, v84
	v_add_u32_e32 v87, 2, v84
	v_add_u32_e32 v88, 3, v84
	v_cmp_gt_u32_e64 s[30:31], s98, v85
	v_cmp_gt_u32_e64 s[36:37], s98, v86
	v_cmp_gt_u32_e64 s[78:79], s98, v87
	v_cmp_gt_u32_e64 s[50:51], s98, v88
	v_cndmask_b32_e64 v32, 0, v32, s[30:31]
	v_add_u32_e32 v85, 8, v84
	v_cmp_gt_u32_e64 s[30:31], s98, v85
	v_cndmask_b32_e64 v33, 0, v33, s[36:37]
	v_add_u32_e32 v86, 9, v84
	v_cmp_gt_u32_e64 s[36:37], s98, v86
	v_cndmask_b32_e64 v34, 0, v34, s[78:79]
	v_add_u32_e32 v87, 10, v84
	v_cmp_gt_u32_e64 s[78:79], s98, v87
	v_cndmask_b32_e64 v35, 0, v35, s[50:51]
	v_add_u32_e32 v88, 11, v84
	v_cmp_gt_u32_e64 s[50:51], s98, v88
	v_cndmask_b32_e64 v36, 0, v36, s[30:31]
	v_add_u32_e32 v85, 16, v84
	v_cmp_gt_u32_e64 s[30:31], s98, v85
	v_cndmask_b32_e64 v37, 0, v37, s[36:37]
	v_add_u32_e32 v86, 17, v84
	v_cmp_gt_u32_e64 s[36:37], s98, v86
	v_cndmask_b32_e64 v38, 0, v38, s[78:79]
	v_add_u32_e32 v87, 18, v84
	v_cmp_gt_u32_e64 s[78:79], s98, v87
	v_cndmask_b32_e64 v39, 0, v39, s[50:51]
	v_add_u32_e32 v88, 19, v84
	v_cmp_gt_u32_e64 s[50:51], s98, v88
	v_cndmask_b32_e64 v40, 0, v40, s[30:31]
	v_add_u32_e32 v85, 24, v84
	v_cmp_gt_u32_e64 s[30:31], s98, v85
	v_cndmask_b32_e64 v41, 0, v41, s[36:37]
	v_add_u32_e32 v86, 25, v84
	v_cmp_gt_u32_e64 s[36:37], s98, v86
	v_cndmask_b32_e64 v42, 0, v42, s[78:79]
	v_add_u32_e32 v87, 26, v84
	v_cmp_gt_u32_e64 s[78:79], s98, v87
	v_cndmask_b32_e64 v43, 0, v43, s[50:51]
	v_add_u32_e32 v88, 27, v84
	v_cmp_gt_u32_e64 s[50:51], s98, v88
	v_nop
	v_cndmask_b32_e64 v44, 0, v44, s[30:31]
	v_cndmask_b32_e64 v45, 0, v45, s[36:37]
	v_cndmask_b32_e64 v46, 0, v46, s[78:79]
	v_cndmask_b32_e64 v47, 0, v47, s[50:51]
	v_cvt_pk_bf16_f32 v64, v32, v33
	v_cvt_pk_bf16_f32 v65, v34, v35
	v_cvt_pk_bf16_f32 v66, v36, v37
	v_cvt_pk_bf16_f32 v67, v38, v39
	v_cvt_pk_bf16_f32 v68, v40, v41
	v_cvt_pk_bf16_f32 v69, v42, v43
	v_cvt_pk_bf16_f32 v70, v44, v45
	v_cvt_pk_bf16_f32 v71, v46, v47
	v_pk_add_f32 v[232:233], v[232:233], v[32:33]
	v_pk_add_f32 v[232:233], v[232:233], v[34:35]
	v_pk_add_f32 v[232:233], v[232:233], v[36:37]
	v_pk_add_f32 v[232:233], v[232:233], v[38:39]
	v_pk_add_f32 v[232:233], v[232:233], v[40:41]
	v_pk_add_f32 v[232:233], v[232:233], v[42:43]
	v_pk_add_f32 v[232:233], v[232:233], v[44:45]
	v_pk_add_f32 v[232:233], v[232:233], v[46:47]
	s_waitcnt lgkmcnt(12)
	v_mfma_f32_32x32x16_bf16 v[0:15], v[64:67], v[72:75], v[0:15]
	v_mfma_f32_32x32x16_bf16 v[16:31], v[64:67], v[76:79], v[16:31]
	v_mfma_f32_32x32x16_bf16 v[0:15], v[68:71], v[220:223], v[0:15]
	v_mfma_f32_32x32x16_bf16 v[16:31], v[68:71], v[224:227], v[16:31]
	s_add_i32 s90, s76, 480
	v_add_u32_e32 v80, s90, v235
	v_add_u32_e32 v83, s90, v236
	v_add_u32_e32 v99, s90, v237
	v_add_u32_e32 v253, s90, v238
	v_add_u32_e32 v254, s90, v100
	v_add_u32_e32 v255, s90, v149
	v_med3_i32 v80, v80, 0, s99
	v_med3_i32 v83, v83, 0, s99
	v_med3_i32 v99, v99, 0, s99
	v_med3_i32 v253, v253, 0, s99
	v_med3_i32 v254, v254, 0, s99
	v_med3_i32 v255, v255, 0, s99
	v_mad_u32_u24 v80, v80, s100, v252
	v_mad_u32_u24 v83, v83, s100, v252
	v_mad_u32_u24 v99, v99, s100, v252
	v_mad_u32_u24 v253, v253, s100, v252
	v_mad_u32_u24 v254, v254, s100, v153
	v_mad_u32_u24 v255, v255, s100, v153
	global_load_dwordx4 v[188:191], v80, s[82:83]
	global_load_dwordx4 v[192:195], v83, s[82:83]
	global_load_dwordx4 v[196:199], v99, s[82:83]
	global_load_dwordx4 v[200:203], v253, s[82:83]
	global_load_dwordx4 v[204:207], v254, s[82:83] offset:768
	global_load_dwordx4 v[208:211], v255, s[82:83] offset:768
	global_load_dwordx4 v[212:215], v254, s[82:83] offset:832
	global_load_dwordx4 v[216:219], v255, s[82:83] offset:832
	ds_read2_b32 v[32:33], v115 offset0:34 offset1:35
	ds_read2_b32 v[34:35], v115 offset0:36 offset1:37
	ds_read2_b32 v[36:37], v115 offset0:42 offset1:43
	ds_read2_b32 v[38:39], v115 offset0:44 offset1:45
	ds_read2_b32 v[40:41], v115 offset0:51 offset1:52
	ds_read2_b32 v[42:43], v115 offset0:53 offset1:54
	ds_read2_b32 v[44:45], v115 offset0:59 offset1:60
	ds_read2_b32 v[46:47], v115 offset0:61 offset1:62
	s_waitcnt lgkmcnt(0)
	v_mfma_f32_32x32x16_bf16 v[32:47], v[116:119], v[48:51], v[32:47]
	ds_read_b64_tr_b16 v[72:73], v231
	ds_read_b64_tr_b16 v[74:75], v231 offset:512
	ds_read_b64_tr_b16 v[76:77], v231 offset:2048
	ds_read_b64_tr_b16 v[78:79], v231 offset:2560
	ds_read_b64_tr_b16 v[220:221], v231 offset:1024
	ds_read_b64_tr_b16 v[222:223], v231 offset:1536
	ds_read_b64_tr_b16 v[224:225], v231 offset:3072
	ds_read_b64_tr_b16 v[226:227], v231 offset:3584
	s_waitcnt vmcnt(8)
	ds_write_b128 v247, v[156:159]
	ds_write_b128 v247, v[160:163] offset:1024
	ds_write_b128 v247, v[164:167] offset:2048
	ds_write_b128 v247, v[168:171] offset:3072
	ds_read_b128 v[156:159], v248
	ds_read_b128 v[160:163], v249
	ds_read_b128 v[164:167], v250
	ds_read_b128 v[168:171], v251
	ds_write_b128 v112, v[172:175]
	ds_write_b128 v112, v[176:179] offset:1024
	ds_write_b128 v112, v[180:183] offset:2048
	ds_write_b128 v112, v[184:187] offset:3072
	v_mfma_f32_32x32x16_bf16 v[32:47], v[120:123], v[52:55], v[32:47]
	v_mfma_f32_32x32x16_bf16 v[32:47], v[124:127], v[56:59], v[32:47]
	v_mfma_f32_32x32x16_bf16 v[32:47], v[128:131], v[60:63], v[32:47]
	s_nop 11
	v_exp_f32_e32 v32, v32
	v_exp_f32_e32 v33, v33
	v_exp_f32_e32 v34, v34
	v_exp_f32_e32 v35, v35
	v_exp_f32_e32 v36, v36
	v_exp_f32_e32 v37, v37
	v_exp_f32_e32 v38, v38
	v_exp_f32_e32 v39, v39
	v_exp_f32_e32 v40, v40
	v_exp_f32_e32 v41, v41
	v_exp_f32_e32 v42, v42
	v_exp_f32_e32 v43, v43
	v_exp_f32_e32 v44, v44
	v_exp_f32_e32 v45, v45
	v_exp_f32_e32 v46, v46
	v_exp_f32_e32 v47, v47
	s_add_i32 s90, s76, 416
	v_add_u32_e32 v84, s90, v107
	v_add_u32_e32 v85, 0, v84
	v_add_u32_e32 v86, 1, v84
	v_add_u32_e32 v87, 2, v84
	v_add_u32_e32 v88, 3, v84
	v_cmp_gt_u32_e64 s[30:31], s98, v85
	v_cmp_gt_u32_e64 s[36:37], s98, v86
	v_cmp_gt_u32_e64 s[78:79], s98, v87
	v_cmp_gt_u32_e64 s[50:51], s98, v88
	v_cndmask_b32_e64 v32, 0, v32, s[30:31]
	v_add_u32_e32 v85, 8, v84
	v_cmp_gt_u32_e64 s[30:31], s98, v85
	v_cndmask_b32_e64 v33, 0, v33, s[36:37]
	v_add_u32_e32 v86, 9, v84
	v_cmp_gt_u32_e64 s[36:37], s98, v86
	v_cndmask_b32_e64 v34, 0, v34, s[78:79]
	v_add_u32_e32 v87, 10, v84
	v_cmp_gt_u32_e64 s[78:79], s98, v87
	v_cndmask_b32_e64 v35, 0, v35, s[50:51]
	v_add_u32_e32 v88, 11, v84
	v_cmp_gt_u32_e64 s[50:51], s98, v88
	v_cndmask_b32_e64 v36, 0, v36, s[30:31]
	v_add_u32_e32 v85, 16, v84
	v_cmp_gt_u32_e64 s[30:31], s98, v85
	v_cndmask_b32_e64 v37, 0, v37, s[36:37]
	v_add_u32_e32 v86, 17, v84
	v_cmp_gt_u32_e64 s[36:37], s98, v86
	v_cndmask_b32_e64 v38, 0, v38, s[78:79]
	v_add_u32_e32 v87, 18, v84
	v_cmp_gt_u32_e64 s[78:79], s98, v87
	v_cndmask_b32_e64 v39, 0, v39, s[50:51]
	v_add_u32_e32 v88, 19, v84
	v_cmp_gt_u32_e64 s[50:51], s98, v88
	v_cndmask_b32_e64 v40, 0, v40, s[30:31]
	v_add_u32_e32 v85, 24, v84
	v_cmp_gt_u32_e64 s[30:31], s98, v85
	v_cndmask_b32_e64 v41, 0, v41, s[36:37]
	v_add_u32_e32 v86, 25, v84
	v_cmp_gt_u32_e64 s[36:37], s98, v86
	v_cndmask_b32_e64 v42, 0, v42, s[78:79]
	v_add_u32_e32 v87, 26, v84
	v_cmp_gt_u32_e64 s[78:79], s98, v87
	v_cndmask_b32_e64 v43, 0, v43, s[50:51]
	v_add_u32_e32 v88, 27, v84
	v_cmp_gt_u32_e64 s[50:51], s98, v88
	v_nop
	v_cndmask_b32_e64 v44, 0, v44, s[30:31]
	v_cndmask_b32_e64 v45, 0, v45, s[36:37]
	v_cndmask_b32_e64 v46, 0, v46, s[78:79]
	v_cndmask_b32_e64 v47, 0, v47, s[50:51]
	v_cvt_pk_bf16_f32 v64, v32, v33
	v_cvt_pk_bf16_f32 v65, v34, v35
	v_cvt_pk_bf16_f32 v66, v36, v37
	v_cvt_pk_bf16_f32 v67, v38, v39
	v_cvt_pk_bf16_f32 v68, v40, v41
	v_cvt_pk_bf16_f32 v69, v42, v43
	v_cvt_pk_bf16_f32 v70, v44, v45
	v_cvt_pk_bf16_f32 v71, v46, v47
	v_pk_add_f32 v[232:233], v[232:233], v[32:33]
	v_pk_add_f32 v[232:233], v[232:233], v[34:35]
	v_pk_add_f32 v[232:233], v[232:233], v[36:37]
	v_pk_add_f32 v[232:233], v[232:233], v[38:39]
	v_pk_add_f32 v[232:233], v[232:233], v[40:41]
	v_pk_add_f32 v[232:233], v[232:233], v[42:43]
	v_pk_add_f32 v[232:233], v[232:233], v[44:45]
	v_pk_add_f32 v[232:233], v[232:233], v[46:47]
	s_waitcnt lgkmcnt(12)
	v_mfma_f32_32x32x16_bf16 v[0:15], v[64:67], v[72:75], v[0:15]
	v_mfma_f32_32x32x16_bf16 v[16:31], v[64:67], v[76:79], v[16:31]
	v_mfma_f32_32x32x16_bf16 v[0:15], v[68:71], v[220:223], v[0:15]
	v_mfma_f32_32x32x16_bf16 v[16:31], v[68:71], v[224:227], v[16:31]
	s_add_i32 s90, s76, 512
	v_add_u32_e32 v80, s90, v235
	v_add_u32_e32 v83, s90, v236
	v_add_u32_e32 v99, s90, v237
	v_add_u32_e32 v253, s90, v238
	v_add_u32_e32 v254, s90, v100
	v_add_u32_e32 v255, s90, v149
	v_med3_i32 v80, v80, 0, s99
	v_med3_i32 v83, v83, 0, s99
	v_med3_i32 v99, v99, 0, s99
	v_med3_i32 v253, v253, 0, s99
	v_med3_i32 v254, v254, 0, s99
	v_med3_i32 v255, v255, 0, s99
	v_mad_u32_u24 v80, v80, s100, v252
	v_mad_u32_u24 v83, v83, s100, v252
	v_mad_u32_u24 v99, v99, s100, v252
	v_mad_u32_u24 v253, v253, s100, v252
	v_mad_u32_u24 v254, v254, s100, v153
	v_mad_u32_u24 v255, v255, s100, v153
	global_load_dwordx4 v[116:119], v80, s[82:83]
	global_load_dwordx4 v[120:123], v83, s[82:83]
	global_load_dwordx4 v[124:127], v99, s[82:83]
	global_load_dwordx4 v[128:131], v253, s[82:83]
	global_load_dwordx4 v[132:135], v254, s[82:83] offset:768
	global_load_dwordx4 v[136:139], v255, s[82:83] offset:768
	global_load_dwordx4 v[140:143], v254, s[82:83] offset:832
	global_load_dwordx4 v[144:147], v255, s[82:83] offset:832
	ds_read2_b32 v[32:33], v115 offset0:68 offset1:69
	ds_read2_b32 v[34:35], v115 offset0:70 offset1:71
	ds_read2_b32 v[36:37], v115 offset0:76 offset1:77
	ds_read2_b32 v[38:39], v115 offset0:78 offset1:79
	ds_read2_b32 v[40:41], v115 offset0:85 offset1:86
	ds_read2_b32 v[42:43], v115 offset0:87 offset1:88
	ds_read2_b32 v[44:45], v115 offset0:93 offset1:94
	ds_read2_b32 v[46:47], v115 offset0:95 offset1:96
	s_waitcnt lgkmcnt(0)
	v_mfma_f32_32x32x16_bf16 v[32:47], v[156:159], v[48:51], v[32:47]
	ds_read_b64_tr_b16 v[72:73], v231
	ds_read_b64_tr_b16 v[74:75], v231 offset:512
	ds_read_b64_tr_b16 v[76:77], v231 offset:2048
	ds_read_b64_tr_b16 v[78:79], v231 offset:2560
	ds_read_b64_tr_b16 v[220:221], v231 offset:1024
	ds_read_b64_tr_b16 v[222:223], v231 offset:1536
	ds_read_b64_tr_b16 v[224:225], v231 offset:3072
	ds_read_b64_tr_b16 v[226:227], v231 offset:3584
	s_waitcnt vmcnt(8)
	ds_write_b128 v247, v[188:191]
	ds_write_b128 v247, v[192:195] offset:1024
	ds_write_b128 v247, v[196:199] offset:2048
	ds_write_b128 v247, v[200:203] offset:3072
	ds_read_b128 v[188:191], v248
	ds_read_b128 v[192:195], v249
	ds_read_b128 v[196:199], v250
	ds_read_b128 v[200:203], v251
	ds_write_b128 v112, v[204:207]
	ds_write_b128 v112, v[208:211] offset:1024
	ds_write_b128 v112, v[212:215] offset:2048
	ds_write_b128 v112, v[216:219] offset:3072
	v_mfma_f32_32x32x16_bf16 v[32:47], v[160:163], v[52:55], v[32:47]
	v_mfma_f32_32x32x16_bf16 v[32:47], v[164:167], v[56:59], v[32:47]
	v_mfma_f32_32x32x16_bf16 v[32:47], v[168:171], v[60:63], v[32:47]
	s_nop 11
	v_exp_f32_e32 v32, v32
	v_exp_f32_e32 v33, v33
	v_exp_f32_e32 v34, v34
	v_exp_f32_e32 v35, v35
	v_exp_f32_e32 v36, v36
	v_exp_f32_e32 v37, v37
	v_exp_f32_e32 v38, v38
	v_exp_f32_e32 v39, v39
	v_exp_f32_e32 v40, v40
	v_exp_f32_e32 v41, v41
	v_exp_f32_e32 v42, v42
	v_exp_f32_e32 v43, v43
	v_exp_f32_e32 v44, v44
	v_exp_f32_e32 v45, v45
	v_exp_f32_e32 v46, v46
	v_exp_f32_e32 v47, v47
	s_add_i32 s90, s76, 448
	v_add_u32_e32 v84, s90, v107
	v_add_u32_e32 v85, 0, v84
	v_add_u32_e32 v86, 1, v84
	v_add_u32_e32 v87, 2, v84
	v_add_u32_e32 v88, 3, v84
	v_cmp_gt_u32_e64 s[30:31], s98, v85
	v_cmp_gt_u32_e64 s[36:37], s98, v86
	v_cmp_gt_u32_e64 s[78:79], s98, v87
	v_cmp_gt_u32_e64 s[50:51], s98, v88
	v_cndmask_b32_e64 v32, 0, v32, s[30:31]
	v_add_u32_e32 v85, 8, v84
	v_cmp_gt_u32_e64 s[30:31], s98, v85
	v_cndmask_b32_e64 v33, 0, v33, s[36:37]
	v_add_u32_e32 v86, 9, v84
	v_cmp_gt_u32_e64 s[36:37], s98, v86
	v_cndmask_b32_e64 v34, 0, v34, s[78:79]
	v_add_u32_e32 v87, 10, v84
	v_cmp_gt_u32_e64 s[78:79], s98, v87
	v_cndmask_b32_e64 v35, 0, v35, s[50:51]
	v_add_u32_e32 v88, 11, v84
	v_cmp_gt_u32_e64 s[50:51], s98, v88
	v_cndmask_b32_e64 v36, 0, v36, s[30:31]
	v_add_u32_e32 v85, 16, v84
	v_cmp_gt_u32_e64 s[30:31], s98, v85
	v_cndmask_b32_e64 v37, 0, v37, s[36:37]
	v_add_u32_e32 v86, 17, v84
	v_cmp_gt_u32_e64 s[36:37], s98, v86
	v_cndmask_b32_e64 v38, 0, v38, s[78:79]
	v_add_u32_e32 v87, 18, v84
	v_cmp_gt_u32_e64 s[78:79], s98, v87
	v_cndmask_b32_e64 v39, 0, v39, s[50:51]
	v_add_u32_e32 v88, 19, v84
	v_cmp_gt_u32_e64 s[50:51], s98, v88
	v_cndmask_b32_e64 v40, 0, v40, s[30:31]
	v_add_u32_e32 v85, 24, v84
	v_cmp_gt_u32_e64 s[30:31], s98, v85
	v_cndmask_b32_e64 v41, 0, v41, s[36:37]
	v_add_u32_e32 v86, 25, v84
	v_cmp_gt_u32_e64 s[36:37], s98, v86
	v_cndmask_b32_e64 v42, 0, v42, s[78:79]
	v_add_u32_e32 v87, 26, v84
	v_cmp_gt_u32_e64 s[78:79], s98, v87
	v_cndmask_b32_e64 v43, 0, v43, s[50:51]
	v_add_u32_e32 v88, 27, v84
	v_cmp_gt_u32_e64 s[50:51], s98, v88
	v_nop
	v_cndmask_b32_e64 v44, 0, v44, s[30:31]
	v_cndmask_b32_e64 v45, 0, v45, s[36:37]
	v_cndmask_b32_e64 v46, 0, v46, s[78:79]
	v_cndmask_b32_e64 v47, 0, v47, s[50:51]
	v_cvt_pk_bf16_f32 v64, v32, v33
	v_cvt_pk_bf16_f32 v65, v34, v35
	v_cvt_pk_bf16_f32 v66, v36, v37
	v_cvt_pk_bf16_f32 v67, v38, v39
	v_cvt_pk_bf16_f32 v68, v40, v41
	v_cvt_pk_bf16_f32 v69, v42, v43
	v_cvt_pk_bf16_f32 v70, v44, v45
	v_cvt_pk_bf16_f32 v71, v46, v47
	v_pk_add_f32 v[232:233], v[232:233], v[32:33]
	v_pk_add_f32 v[232:233], v[232:233], v[34:35]
	v_pk_add_f32 v[232:233], v[232:233], v[36:37]
	v_pk_add_f32 v[232:233], v[232:233], v[38:39]
	v_pk_add_f32 v[232:233], v[232:233], v[40:41]
	v_pk_add_f32 v[232:233], v[232:233], v[42:43]
	v_pk_add_f32 v[232:233], v[232:233], v[44:45]
	v_pk_add_f32 v[232:233], v[232:233], v[46:47]
	s_waitcnt lgkmcnt(12)
	v_mfma_f32_32x32x16_bf16 v[0:15], v[64:67], v[72:75], v[0:15]
	v_mfma_f32_32x32x16_bf16 v[16:31], v[64:67], v[76:79], v[16:31]
	v_mfma_f32_32x32x16_bf16 v[0:15], v[68:71], v[220:223], v[0:15]
	v_mfma_f32_32x32x16_bf16 v[16:31], v[68:71], v[224:227], v[16:31]
	s_add_i32 s90, s76, 544
	v_add_u32_e32 v80, s90, v235
	v_add_u32_e32 v83, s90, v236
	v_add_u32_e32 v99, s90, v237
	v_add_u32_e32 v253, s90, v238
	v_add_u32_e32 v254, s90, v100
	v_add_u32_e32 v255, s90, v149
	v_med3_i32 v80, v80, 0, s99
	v_med3_i32 v83, v83, 0, s99
	v_med3_i32 v99, v99, 0, s99
	v_med3_i32 v253, v253, 0, s99
	v_med3_i32 v254, v254, 0, s99
	v_med3_i32 v255, v255, 0, s99
	v_mad_u32_u24 v80, v80, s100, v252
	v_mad_u32_u24 v83, v83, s100, v252
	v_mad_u32_u24 v99, v99, s100, v252
	v_mad_u32_u24 v253, v253, s100, v252
	v_mad_u32_u24 v254, v254, s100, v153
	v_mad_u32_u24 v255, v255, s100, v153
	global_load_dwordx4 v[156:159], v80, s[82:83]
	global_load_dwordx4 v[160:163], v83, s[82:83]
	global_load_dwordx4 v[164:167], v99, s[82:83]
	global_load_dwordx4 v[168:171], v253, s[82:83]
	global_load_dwordx4 v[172:175], v254, s[82:83] offset:768
	global_load_dwordx4 v[176:179], v255, s[82:83] offset:768
	global_load_dwordx4 v[180:183], v254, s[82:83] offset:832
	global_load_dwordx4 v[184:187], v255, s[82:83] offset:832
	ds_read2_b32 v[32:33], v115 offset0:102 offset1:103
	ds_read2_b32 v[34:35], v115 offset0:104 offset1:105
	ds_read2_b32 v[36:37], v115 offset0:110 offset1:111
	ds_read2_b32 v[38:39], v115 offset0:112 offset1:113
	ds_read2_b32 v[40:41], v115 offset0:119 offset1:120
	ds_read2_b32 v[42:43], v115 offset0:121 offset1:122
	ds_read2_b32 v[44:45], v115 offset0:127 offset1:128
	ds_read2_b32 v[46:47], v115 offset0:129 offset1:130
	s_waitcnt lgkmcnt(0)
	v_mfma_f32_32x32x16_bf16 v[32:47], v[188:191], v[48:51], v[32:47]
	ds_read_b64_tr_b16 v[72:73], v231
	ds_read_b64_tr_b16 v[74:75], v231 offset:512
	ds_read_b64_tr_b16 v[76:77], v231 offset:2048
	ds_read_b64_tr_b16 v[78:79], v231 offset:2560
	ds_read_b64_tr_b16 v[220:221], v231 offset:1024
	ds_read_b64_tr_b16 v[222:223], v231 offset:1536
	ds_read_b64_tr_b16 v[224:225], v231 offset:3072
	ds_read_b64_tr_b16 v[226:227], v231 offset:3584
	s_waitcnt vmcnt(8)
	ds_write_b128 v247, v[116:119]
	ds_write_b128 v247, v[120:123] offset:1024
	ds_write_b128 v247, v[124:127] offset:2048
	ds_write_b128 v247, v[128:131] offset:3072
	ds_read_b128 v[116:119], v248
	ds_read_b128 v[120:123], v249
	ds_read_b128 v[124:127], v250
	ds_read_b128 v[128:131], v251
	ds_write_b128 v112, v[132:135]
	ds_write_b128 v112, v[136:139] offset:1024
	ds_write_b128 v112, v[140:143] offset:2048
	ds_write_b128 v112, v[144:147] offset:3072
	v_mfma_f32_32x32x16_bf16 v[32:47], v[192:195], v[52:55], v[32:47]
	v_mfma_f32_32x32x16_bf16 v[32:47], v[196:199], v[56:59], v[32:47]
	v_mfma_f32_32x32x16_bf16 v[32:47], v[200:203], v[60:63], v[32:47]
	s_nop 11
	v_exp_f32_e32 v32, v32
	v_exp_f32_e32 v33, v33
	v_exp_f32_e32 v34, v34
	v_exp_f32_e32 v35, v35
	v_exp_f32_e32 v36, v36
	v_exp_f32_e32 v37, v37
	v_exp_f32_e32 v38, v38
	v_exp_f32_e32 v39, v39
	v_exp_f32_e32 v40, v40
	v_exp_f32_e32 v41, v41
	v_exp_f32_e32 v42, v42
	v_exp_f32_e32 v43, v43
	v_exp_f32_e32 v44, v44
	v_exp_f32_e32 v45, v45
	v_exp_f32_e32 v46, v46
	v_exp_f32_e32 v47, v47
	s_add_i32 s90, s76, 480
	v_add_u32_e32 v84, s90, v107
	v_add_u32_e32 v85, 0, v84
	v_add_u32_e32 v86, 1, v84
	v_add_u32_e32 v87, 2, v84
	v_add_u32_e32 v88, 3, v84
	v_cmp_gt_u32_e64 s[30:31], s98, v85
	v_cmp_gt_u32_e64 s[36:37], s98, v86
	v_cmp_gt_u32_e64 s[78:79], s98, v87
	v_cmp_gt_u32_e64 s[50:51], s98, v88
	v_cndmask_b32_e64 v32, 0, v32, s[30:31]
	v_add_u32_e32 v85, 8, v84
	v_cmp_gt_u32_e64 s[30:31], s98, v85
	v_cndmask_b32_e64 v33, 0, v33, s[36:37]
	v_add_u32_e32 v86, 9, v84
	v_cmp_gt_u32_e64 s[36:37], s98, v86
	v_cndmask_b32_e64 v34, 0, v34, s[78:79]
	v_add_u32_e32 v87, 10, v84
	v_cmp_gt_u32_e64 s[78:79], s98, v87
	v_cndmask_b32_e64 v35, 0, v35, s[50:51]
	v_add_u32_e32 v88, 11, v84
	v_cmp_gt_u32_e64 s[50:51], s98, v88
	v_cndmask_b32_e64 v36, 0, v36, s[30:31]
	v_add_u32_e32 v85, 16, v84
	v_cmp_gt_u32_e64 s[30:31], s98, v85
	v_cndmask_b32_e64 v37, 0, v37, s[36:37]
	v_add_u32_e32 v86, 17, v84
	v_cmp_gt_u32_e64 s[36:37], s98, v86
	v_cndmask_b32_e64 v38, 0, v38, s[78:79]
	v_add_u32_e32 v87, 18, v84
	v_cmp_gt_u32_e64 s[78:79], s98, v87
	v_cndmask_b32_e64 v39, 0, v39, s[50:51]
	v_add_u32_e32 v88, 19, v84
	v_cmp_gt_u32_e64 s[50:51], s98, v88
	v_cndmask_b32_e64 v40, 0, v40, s[30:31]
	v_add_u32_e32 v85, 24, v84
	v_cmp_gt_u32_e64 s[30:31], s98, v85
	v_cndmask_b32_e64 v41, 0, v41, s[36:37]
	v_add_u32_e32 v86, 25, v84
	v_cmp_gt_u32_e64 s[36:37], s98, v86
	v_cndmask_b32_e64 v42, 0, v42, s[78:79]
	v_add_u32_e32 v87, 26, v84
	v_cmp_gt_u32_e64 s[78:79], s98, v87
	v_cndmask_b32_e64 v43, 0, v43, s[50:51]
	v_add_u32_e32 v88, 27, v84
	v_cmp_gt_u32_e64 s[50:51], s98, v88
	v_nop
	v_cndmask_b32_e64 v44, 0, v44, s[30:31]
	v_cndmask_b32_e64 v45, 0, v45, s[36:37]
	v_cndmask_b32_e64 v46, 0, v46, s[78:79]
	v_cndmask_b32_e64 v47, 0, v47, s[50:51]
	v_cvt_pk_bf16_f32 v64, v32, v33
	v_cvt_pk_bf16_f32 v65, v34, v35
	v_cvt_pk_bf16_f32 v66, v36, v37
	v_cvt_pk_bf16_f32 v67, v38, v39
	v_cvt_pk_bf16_f32 v68, v40, v41
	v_cvt_pk_bf16_f32 v69, v42, v43
	v_cvt_pk_bf16_f32 v70, v44, v45
	v_cvt_pk_bf16_f32 v71, v46, v47
	v_pk_add_f32 v[232:233], v[232:233], v[32:33]
	v_pk_add_f32 v[232:233], v[232:233], v[34:35]
	v_pk_add_f32 v[232:233], v[232:233], v[36:37]
	v_pk_add_f32 v[232:233], v[232:233], v[38:39]
	v_pk_add_f32 v[232:233], v[232:233], v[40:41]
	v_pk_add_f32 v[232:233], v[232:233], v[42:43]
	v_pk_add_f32 v[232:233], v[232:233], v[44:45]
	v_pk_add_f32 v[232:233], v[232:233], v[46:47]
	s_waitcnt lgkmcnt(12)
	v_mfma_f32_32x32x16_bf16 v[0:15], v[64:67], v[72:75], v[0:15]
	v_mfma_f32_32x32x16_bf16 v[16:31], v[64:67], v[76:79], v[16:31]
	v_mfma_f32_32x32x16_bf16 v[0:15], v[68:71], v[220:223], v[0:15]
	v_mfma_f32_32x32x16_bf16 v[16:31], v[68:71], v[224:227], v[16:31]
	s_add_i32 s90, s76, -256
	v_add_u32_e32 v80, s90, v239
	v_add_u32_e32 v83, s90, v240
	v_add_u32_e32 v99, s90, v241
	v_add_u32_e32 v253, s90, v242
	v_add_u32_e32 v254, s90, v101
	v_add_u32_e32 v255, s90, v150
	v_med3_i32 v80, v80, 0, s99
	v_med3_i32 v83, v83, 0, s99
	v_med3_i32 v99, v99, 0, s99
	v_med3_i32 v253, v253, 0, s99
	v_med3_i32 v254, v254, 0, s99
	v_med3_i32 v255, v255, 0, s99
	v_mad_u32_u24 v80, v80, s100, v252
	v_mad_u32_u24 v83, v83, s100, v252
	v_mad_u32_u24 v99, v99, s100, v252
	v_mad_u32_u24 v253, v253, s100, v252
	v_mad_u32_u24 v254, v254, s100, v153
	v_mad_u32_u24 v255, v255, s100, v153
	global_load_dwordx4 v[188:191], v80, s[82:83]
	global_load_dwordx4 v[192:195], v83, s[82:83]
	global_load_dwordx4 v[196:199], v99, s[82:83]
	global_load_dwordx4 v[200:203], v253, s[82:83]
	global_load_dwordx4 v[204:207], v254, s[82:83] offset:768
	global_load_dwordx4 v[208:211], v255, s[82:83] offset:768
	global_load_dwordx4 v[212:215], v254, s[82:83] offset:832
	global_load_dwordx4 v[216:219], v255, s[82:83] offset:832
	ds_read2_b32 v[32:33], v115 offset0:136 offset1:137
	ds_read2_b32 v[34:35], v115 offset0:138 offset1:139
	ds_read2_b32 v[36:37], v115 offset0:144 offset1:145
	ds_read2_b32 v[38:39], v115 offset0:146 offset1:147
	ds_read2_b32 v[40:41], v115 offset0:153 offset1:154
	ds_read2_b32 v[42:43], v115 offset0:155 offset1:156
	ds_read2_b32 v[44:45], v115 offset0:161 offset1:162
	ds_read2_b32 v[46:47], v115 offset0:163 offset1:164
	s_waitcnt lgkmcnt(0)
	v_mfma_f32_32x32x16_bf16 v[32:47], v[116:119], v[48:51], v[32:47]
	ds_read_b64_tr_b16 v[72:73], v231
	ds_read_b64_tr_b16 v[74:75], v231 offset:512
	ds_read_b64_tr_b16 v[76:77], v231 offset:2048
	ds_read_b64_tr_b16 v[78:79], v231 offset:2560
	ds_read_b64_tr_b16 v[220:221], v231 offset:1024
	ds_read_b64_tr_b16 v[222:223], v231 offset:1536
	ds_read_b64_tr_b16 v[224:225], v231 offset:3072
	ds_read_b64_tr_b16 v[226:227], v231 offset:3584
	s_waitcnt vmcnt(8)
	ds_write_b128 v247, v[156:159]
	ds_write_b128 v247, v[160:163] offset:1024
	ds_write_b128 v247, v[164:167] offset:2048
	ds_write_b128 v247, v[168:171] offset:3072
	ds_read_b128 v[156:159], v248
	ds_read_b128 v[160:163], v249
	ds_read_b128 v[164:167], v250
	ds_read_b128 v[168:171], v251
	ds_write_b128 v112, v[172:175]
	ds_write_b128 v112, v[176:179] offset:1024
	ds_write_b128 v112, v[180:183] offset:2048
	ds_write_b128 v112, v[184:187] offset:3072
	v_mfma_f32_32x32x16_bf16 v[32:47], v[120:123], v[52:55], v[32:47]
	v_mfma_f32_32x32x16_bf16 v[32:47], v[124:127], v[56:59], v[32:47]
	v_mfma_f32_32x32x16_bf16 v[32:47], v[128:131], v[60:63], v[32:47]
	s_nop 11
	v_exp_f32_e32 v32, v32
	v_exp_f32_e32 v33, v33
	v_exp_f32_e32 v34, v34
	v_exp_f32_e32 v35, v35
	v_exp_f32_e32 v36, v36
	v_exp_f32_e32 v37, v37
	v_exp_f32_e32 v38, v38
	v_exp_f32_e32 v39, v39
	v_exp_f32_e32 v40, v40
	v_exp_f32_e32 v41, v41
	v_exp_f32_e32 v42, v42
	v_exp_f32_e32 v43, v43
	v_exp_f32_e32 v44, v44
	v_exp_f32_e32 v45, v45
	v_exp_f32_e32 v46, v46
	v_exp_f32_e32 v47, v47
	s_add_i32 s90, s76, 512
	v_add_u32_e32 v84, s90, v107
	v_add_u32_e32 v85, 0, v84
	v_add_u32_e32 v86, 1, v84
	v_add_u32_e32 v87, 2, v84
	v_add_u32_e32 v88, 3, v84
	v_cmp_gt_u32_e64 s[30:31], s98, v85
	v_cmp_gt_u32_e64 s[36:37], s98, v86
	v_cmp_gt_u32_e64 s[78:79], s98, v87
	v_cmp_gt_u32_e64 s[50:51], s98, v88
	v_cndmask_b32_e64 v32, 0, v32, s[30:31]
	v_add_u32_e32 v85, 8, v84
	v_cmp_gt_u32_e64 s[30:31], s98, v85
	v_cndmask_b32_e64 v33, 0, v33, s[36:37]
	v_add_u32_e32 v86, 9, v84
	v_cmp_gt_u32_e64 s[36:37], s98, v86
	v_cndmask_b32_e64 v34, 0, v34, s[78:79]
	v_add_u32_e32 v87, 10, v84
	v_cmp_gt_u32_e64 s[78:79], s98, v87
	v_cndmask_b32_e64 v35, 0, v35, s[50:51]
	v_add_u32_e32 v88, 11, v84
	v_cmp_gt_u32_e64 s[50:51], s98, v88
	v_cndmask_b32_e64 v36, 0, v36, s[30:31]
	v_add_u32_e32 v85, 16, v84
	v_cmp_gt_u32_e64 s[30:31], s98, v85
	v_cndmask_b32_e64 v37, 0, v37, s[36:37]
	v_add_u32_e32 v86, 17, v84
	v_cmp_gt_u32_e64 s[36:37], s98, v86
	v_cndmask_b32_e64 v38, 0, v38, s[78:79]
	v_add_u32_e32 v87, 18, v84
	v_cmp_gt_u32_e64 s[78:79], s98, v87
	v_cndmask_b32_e64 v39, 0, v39, s[50:51]
	v_add_u32_e32 v88, 19, v84
	v_cmp_gt_u32_e64 s[50:51], s98, v88
	v_cndmask_b32_e64 v40, 0, v40, s[30:31]
	v_add_u32_e32 v85, 24, v84
	v_cmp_gt_u32_e64 s[30:31], s98, v85
	v_cndmask_b32_e64 v41, 0, v41, s[36:37]
	v_add_u32_e32 v86, 25, v84
	v_cmp_gt_u32_e64 s[36:37], s98, v86
	v_cndmask_b32_e64 v42, 0, v42, s[78:79]
	v_add_u32_e32 v87, 26, v84
	v_cmp_gt_u32_e64 s[78:79], s98, v87
	v_cndmask_b32_e64 v43, 0, v43, s[50:51]
	v_add_u32_e32 v88, 27, v84
	v_cmp_gt_u32_e64 s[50:51], s98, v88
	v_nop
	v_cndmask_b32_e64 v44, 0, v44, s[30:31]
	v_cndmask_b32_e64 v45, 0, v45, s[36:37]
	v_cndmask_b32_e64 v46, 0, v46, s[78:79]
	v_cndmask_b32_e64 v47, 0, v47, s[50:51]
	v_cvt_pk_bf16_f32 v64, v32, v33
	v_cvt_pk_bf16_f32 v65, v34, v35
	v_cvt_pk_bf16_f32 v66, v36, v37
	v_cvt_pk_bf16_f32 v67, v38, v39
	v_cvt_pk_bf16_f32 v68, v40, v41
	v_cvt_pk_bf16_f32 v69, v42, v43
	v_cvt_pk_bf16_f32 v70, v44, v45
	v_cvt_pk_bf16_f32 v71, v46, v47
	v_pk_add_f32 v[232:233], v[232:233], v[32:33]
	v_pk_add_f32 v[232:233], v[232:233], v[34:35]
	v_pk_add_f32 v[232:233], v[232:233], v[36:37]
	v_pk_add_f32 v[232:233], v[232:233], v[38:39]
	v_pk_add_f32 v[232:233], v[232:233], v[40:41]
	v_pk_add_f32 v[232:233], v[232:233], v[42:43]
	v_pk_add_f32 v[232:233], v[232:233], v[44:45]
	v_pk_add_f32 v[232:233], v[232:233], v[46:47]
	s_waitcnt lgkmcnt(12)
	v_mfma_f32_32x32x16_bf16 v[0:15], v[64:67], v[72:75], v[0:15]
	v_mfma_f32_32x32x16_bf16 v[16:31], v[64:67], v[76:79], v[16:31]
	v_mfma_f32_32x32x16_bf16 v[0:15], v[68:71], v[220:223], v[0:15]
	v_mfma_f32_32x32x16_bf16 v[16:31], v[68:71], v[224:227], v[16:31]
	s_add_i32 s90, s76, -128
	v_add_u32_e32 v80, s90, v239
	v_add_u32_e32 v83, s90, v240
	v_add_u32_e32 v99, s90, v241
	v_add_u32_e32 v253, s90, v242
	v_add_u32_e32 v254, s90, v101
	v_add_u32_e32 v255, s90, v150
	v_med3_i32 v80, v80, 0, s99
	v_med3_i32 v83, v83, 0, s99
	v_med3_i32 v99, v99, 0, s99
	v_med3_i32 v253, v253, 0, s99
	v_med3_i32 v254, v254, 0, s99
	v_med3_i32 v255, v255, 0, s99
	v_mad_u32_u24 v80, v80, s100, v252
	v_mad_u32_u24 v83, v83, s100, v252
	v_mad_u32_u24 v99, v99, s100, v252
	v_mad_u32_u24 v253, v253, s100, v252
	v_mad_u32_u24 v254, v254, s100, v153
	v_mad_u32_u24 v255, v255, s100, v153
	global_load_dwordx4 v[116:119], v80, s[82:83]
	global_load_dwordx4 v[120:123], v83, s[82:83]
	global_load_dwordx4 v[124:127], v99, s[82:83]
	global_load_dwordx4 v[128:131], v253, s[82:83]
	global_load_dwordx4 v[132:135], v254, s[82:83] offset:768
	global_load_dwordx4 v[136:139], v255, s[82:83] offset:768
	global_load_dwordx4 v[140:143], v254, s[82:83] offset:832
	global_load_dwordx4 v[144:147], v255, s[82:83] offset:832
	ds_read2_b32 v[32:33], v115 offset0:170 offset1:171
	ds_read2_b32 v[34:35], v115 offset0:172 offset1:173
	ds_read2_b32 v[36:37], v115 offset0:178 offset1:179
	ds_read2_b32 v[38:39], v115 offset0:180 offset1:181
	ds_read2_b32 v[40:41], v115 offset0:187 offset1:188
	ds_read2_b32 v[42:43], v115 offset0:189 offset1:190
	ds_read2_b32 v[44:45], v115 offset0:195 offset1:196
	ds_read2_b32 v[46:47], v115 offset0:197 offset1:198
	s_waitcnt lgkmcnt(0)
	v_mfma_f32_32x32x16_bf16 v[32:47], v[156:159], v[48:51], v[32:47]
	ds_read_b64_tr_b16 v[72:73], v231
	ds_read_b64_tr_b16 v[74:75], v231 offset:512
	ds_read_b64_tr_b16 v[76:77], v231 offset:2048
	ds_read_b64_tr_b16 v[78:79], v231 offset:2560
	ds_read_b64_tr_b16 v[220:221], v231 offset:1024
	ds_read_b64_tr_b16 v[222:223], v231 offset:1536
	ds_read_b64_tr_b16 v[224:225], v231 offset:3072
	ds_read_b64_tr_b16 v[226:227], v231 offset:3584
	s_waitcnt vmcnt(8)
	ds_write_b128 v247, v[188:191]
	ds_write_b128 v247, v[192:195] offset:1024
	ds_write_b128 v247, v[196:199] offset:2048
	ds_write_b128 v247, v[200:203] offset:3072
	ds_read_b128 v[188:191], v248
	ds_read_b128 v[192:195], v249
	ds_read_b128 v[196:199], v250
	ds_read_b128 v[200:203], v251
	ds_write_b128 v112, v[204:207]
	ds_write_b128 v112, v[208:211] offset:1024
	ds_write_b128 v112, v[212:215] offset:2048
	ds_write_b128 v112, v[216:219] offset:3072
	v_mfma_f32_32x32x16_bf16 v[32:47], v[160:163], v[52:55], v[32:47]
	v_mfma_f32_32x32x16_bf16 v[32:47], v[164:167], v[56:59], v[32:47]
	v_mfma_f32_32x32x16_bf16 v[32:47], v[168:171], v[60:63], v[32:47]
	s_nop 11
	v_exp_f32_e32 v32, v32
	v_exp_f32_e32 v33, v33
	v_exp_f32_e32 v34, v34
	v_exp_f32_e32 v35, v35
	v_exp_f32_e32 v36, v36
	v_exp_f32_e32 v37, v37
	v_exp_f32_e32 v38, v38
	v_exp_f32_e32 v39, v39
	v_exp_f32_e32 v40, v40
	v_exp_f32_e32 v41, v41
	v_exp_f32_e32 v42, v42
	v_exp_f32_e32 v43, v43
	v_exp_f32_e32 v44, v44
	v_exp_f32_e32 v45, v45
	v_exp_f32_e32 v46, v46
	v_exp_f32_e32 v47, v47
	s_add_i32 s90, s76, 544
	v_add_u32_e32 v84, s90, v107
	v_add_u32_e32 v85, 0, v84
	v_add_u32_e32 v86, 1, v84
	v_add_u32_e32 v87, 2, v84
	v_add_u32_e32 v88, 3, v84
	v_cmp_gt_u32_e64 s[30:31], s98, v85
	v_cmp_gt_u32_e64 s[36:37], s98, v86
	v_cmp_gt_u32_e64 s[78:79], s98, v87
	v_cmp_gt_u32_e64 s[50:51], s98, v88
	v_cndmask_b32_e64 v32, 0, v32, s[30:31]
	v_add_u32_e32 v85, 8, v84
	v_cmp_gt_u32_e64 s[30:31], s98, v85
	v_cndmask_b32_e64 v33, 0, v33, s[36:37]
	v_add_u32_e32 v86, 9, v84
	v_cmp_gt_u32_e64 s[36:37], s98, v86
	v_cndmask_b32_e64 v34, 0, v34, s[78:79]
	v_add_u32_e32 v87, 10, v84
	v_cmp_gt_u32_e64 s[78:79], s98, v87
	v_cndmask_b32_e64 v35, 0, v35, s[50:51]
	v_add_u32_e32 v88, 11, v84
	v_cmp_gt_u32_e64 s[50:51], s98, v88
	v_cndmask_b32_e64 v36, 0, v36, s[30:31]
	v_add_u32_e32 v85, 16, v84
	v_cmp_gt_u32_e64 s[30:31], s98, v85
	v_cndmask_b32_e64 v37, 0, v37, s[36:37]
	v_add_u32_e32 v86, 17, v84
	v_cmp_gt_u32_e64 s[36:37], s98, v86
	v_cndmask_b32_e64 v38, 0, v38, s[78:79]
	v_add_u32_e32 v87, 18, v84
	v_cmp_gt_u32_e64 s[78:79], s98, v87
	v_cndmask_b32_e64 v39, 0, v39, s[50:51]
	v_add_u32_e32 v88, 19, v84
	v_cmp_gt_u32_e64 s[50:51], s98, v88
	v_cndmask_b32_e64 v40, 0, v40, s[30:31]
	v_add_u32_e32 v85, 24, v84
	v_cmp_gt_u32_e64 s[30:31], s98, v85
	v_cndmask_b32_e64 v41, 0, v41, s[36:37]
	v_add_u32_e32 v86, 25, v84
	v_cmp_gt_u32_e64 s[36:37], s98, v86
	v_cndmask_b32_e64 v42, 0, v42, s[78:79]
	v_add_u32_e32 v87, 26, v84
	v_cmp_gt_u32_e64 s[78:79], s98, v87
	v_cndmask_b32_e64 v43, 0, v43, s[50:51]
	v_add_u32_e32 v88, 27, v84
	v_cmp_gt_u32_e64 s[50:51], s98, v88
	v_nop
	v_cndmask_b32_e64 v44, 0, v44, s[30:31]
	v_cndmask_b32_e64 v45, 0, v45, s[36:37]
	v_cndmask_b32_e64 v46, 0, v46, s[78:79]
	v_cndmask_b32_e64 v47, 0, v47, s[50:51]
	v_cvt_pk_bf16_f32 v64, v32, v33
	v_cvt_pk_bf16_f32 v65, v34, v35
	v_cvt_pk_bf16_f32 v66, v36, v37
	v_cvt_pk_bf16_f32 v67, v38, v39
	v_cvt_pk_bf16_f32 v68, v40, v41
	v_cvt_pk_bf16_f32 v69, v42, v43
	v_cvt_pk_bf16_f32 v70, v44, v45
	v_cvt_pk_bf16_f32 v71, v46, v47
	v_pk_add_f32 v[232:233], v[232:233], v[32:33]
	v_pk_add_f32 v[232:233], v[232:233], v[34:35]
	v_pk_add_f32 v[232:233], v[232:233], v[36:37]
	v_pk_add_f32 v[232:233], v[232:233], v[38:39]
	v_pk_add_f32 v[232:233], v[232:233], v[40:41]
	v_pk_add_f32 v[232:233], v[232:233], v[42:43]
	v_pk_add_f32 v[232:233], v[232:233], v[44:45]
	v_pk_add_f32 v[232:233], v[232:233], v[46:47]
	s_waitcnt lgkmcnt(12)
	v_mfma_f32_32x32x16_bf16 v[0:15], v[64:67], v[72:75], v[0:15]
	v_mfma_f32_32x32x16_bf16 v[16:31], v[64:67], v[76:79], v[16:31]
	v_mfma_f32_32x32x16_bf16 v[0:15], v[68:71], v[220:223], v[0:15]
	v_mfma_f32_32x32x16_bf16 v[16:31], v[68:71], v[224:227], v[16:31]
	s_add_i32 s90, s76, 0
	v_add_u32_e32 v80, s90, v239
	v_add_u32_e32 v83, s90, v240
	v_add_u32_e32 v99, s90, v241
	v_add_u32_e32 v253, s90, v242
	v_add_u32_e32 v254, s90, v101
	v_add_u32_e32 v255, s90, v150
	v_med3_i32 v80, v80, 0, s99
	v_med3_i32 v83, v83, 0, s99
	v_med3_i32 v99, v99, 0, s99
	v_med3_i32 v253, v253, 0, s99
	v_med3_i32 v254, v254, 0, s99
	v_med3_i32 v255, v255, 0, s99
	v_mad_u32_u24 v80, v80, s100, v252
	v_mad_u32_u24 v83, v83, s100, v252
	v_mad_u32_u24 v99, v99, s100, v252
	v_mad_u32_u24 v253, v253, s100, v252
	v_mad_u32_u24 v254, v254, s100, v153
	v_mad_u32_u24 v255, v255, s100, v153
	global_load_dwordx4 v[156:159], v80, s[82:83]
	global_load_dwordx4 v[160:163], v83, s[82:83]
	global_load_dwordx4 v[164:167], v99, s[82:83]
	global_load_dwordx4 v[168:171], v253, s[82:83]
	global_load_dwordx4 v[172:175], v254, s[82:83] offset:768
	global_load_dwordx4 v[176:179], v255, s[82:83] offset:768
	global_load_dwordx4 v[180:183], v254, s[82:83] offset:832
	global_load_dwordx4 v[184:187], v255, s[82:83] offset:832
	v_mov_b32_e32 v115, v229
	ds_read2_b32 v[32:33], v115 offset0:0 offset1:1
	ds_read2_b32 v[34:35], v115 offset0:2 offset1:3
	ds_read2_b32 v[36:37], v115 offset0:10 offset1:11
	ds_read2_b32 v[38:39], v115 offset0:12 offset1:13
	ds_read2_b32 v[40:41], v115 offset0:20 offset1:21
	ds_read2_b32 v[42:43], v115 offset0:22 offset1:23
	ds_read2_b32 v[44:45], v115 offset0:30 offset1:31
	ds_read2_b32 v[46:47], v115 offset0:32 offset1:33
	s_waitcnt lgkmcnt(0)
	v_mfma_f32_32x32x16_bf16 v[32:47], v[188:191], v[48:51], v[32:47]
	ds_read_b64_tr_b16 v[72:73], v231
	ds_read_b64_tr_b16 v[74:75], v231 offset:512
	ds_read_b64_tr_b16 v[76:77], v231 offset:2048
	ds_read_b64_tr_b16 v[78:79], v231 offset:2560
	ds_read_b64_tr_b16 v[220:221], v231 offset:1024
	ds_read_b64_tr_b16 v[222:223], v231 offset:1536
	ds_read_b64_tr_b16 v[224:225], v231 offset:3072
	ds_read_b64_tr_b16 v[226:227], v231 offset:3584
	s_waitcnt vmcnt(8)
	ds_write_b128 v247, v[116:119]
	ds_write_b128 v247, v[120:123] offset:1024
	ds_write_b128 v247, v[124:127] offset:2048
	ds_write_b128 v247, v[128:131] offset:3072
	ds_read_b128 v[116:119], v248
	ds_read_b128 v[120:123], v249
	ds_read_b128 v[124:127], v250
	ds_read_b128 v[128:131], v251
	ds_write_b128 v112, v[132:135]
	ds_write_b128 v112, v[136:139] offset:1024
	ds_write_b128 v112, v[140:143] offset:2048
	ds_write_b128 v112, v[144:147] offset:3072
	v_mfma_f32_32x32x16_bf16 v[32:47], v[192:195], v[52:55], v[32:47]
	v_mfma_f32_32x32x16_bf16 v[32:47], v[196:199], v[56:59], v[32:47]
	v_mfma_f32_32x32x16_bf16 v[32:47], v[200:203], v[60:63], v[32:47]
	s_nop 11
	v_exp_f32_e32 v32, v32
	v_exp_f32_e32 v33, v33
	v_exp_f32_e32 v34, v34
	v_exp_f32_e32 v35, v35
	v_exp_f32_e32 v36, v36
	v_exp_f32_e32 v37, v37
	v_exp_f32_e32 v38, v38
	v_exp_f32_e32 v39, v39
	v_exp_f32_e32 v40, v40
	v_exp_f32_e32 v41, v41
	v_exp_f32_e32 v42, v42
	v_exp_f32_e32 v43, v43
	v_exp_f32_e32 v44, v44
	v_exp_f32_e32 v45, v45
	v_exp_f32_e32 v46, v46
	v_exp_f32_e32 v47, v47
	s_add_i32 s90, s76, -256
	v_lshlrev_b32_e32 v84, 2, v107
	v_add_u32_e32 v84, s90, v84
	v_add_u32_e32 v85, 0, v84
	v_add_u32_e32 v86, 4, v84
	v_add_u32_e32 v87, 8, v84
	v_add_u32_e32 v88, 12, v84
	v_cmp_gt_u32_e64 s[30:31], s98, v85
	v_cmp_gt_u32_e64 s[36:37], s98, v86
	v_cmp_gt_u32_e64 s[78:79], s98, v87
	v_cmp_gt_u32_e64 s[50:51], s98, v88
	v_cndmask_b32_e64 v32, 0, v32, s[30:31]
	v_add_u32_e32 v85, 32, v84
	v_cmp_gt_u32_e64 s[30:31], s98, v85
	v_cndmask_b32_e64 v33, 0, v33, s[36:37]
	v_add_u32_e32 v86, 36, v84
	v_cmp_gt_u32_e64 s[36:37], s98, v86
	v_cndmask_b32_e64 v34, 0, v34, s[78:79]
	v_add_u32_e32 v87, 40, v84
	v_cmp_gt_u32_e64 s[78:79], s98, v87
	v_cndmask_b32_e64 v35, 0, v35, s[50:51]
	v_add_u32_e32 v88, 44, v84
	v_cmp_gt_u32_e64 s[50:51], s98, v88
	v_cndmask_b32_e64 v36, 0, v36, s[30:31]
	v_add_u32_e32 v85, 64, v84
	v_cmp_gt_u32_e64 s[30:31], s98, v85
	v_cndmask_b32_e64 v37, 0, v37, s[36:37]
	v_add_u32_e32 v86, 68, v84
	v_cmp_gt_u32_e64 s[36:37], s98, v86
	v_cndmask_b32_e64 v38, 0, v38, s[78:79]
	v_add_u32_e32 v87, 72, v84
	v_cmp_gt_u32_e64 s[78:79], s98, v87
	v_cndmask_b32_e64 v39, 0, v39, s[50:51]
	v_add_u32_e32 v88, 76, v84
	v_cmp_gt_u32_e64 s[50:51], s98, v88
	v_cndmask_b32_e64 v40, 0, v40, s[30:31]
	v_add_u32_e32 v85, 96, v84
	v_cmp_gt_u32_e64 s[30:31], s98, v85
	v_cndmask_b32_e64 v41, 0, v41, s[36:37]
	v_add_u32_e32 v86, 100, v84
	v_cmp_gt_u32_e64 s[36:37], s98, v86
	v_cndmask_b32_e64 v42, 0, v42, s[78:79]
	v_add_u32_e32 v87, 104, v84
	v_cmp_gt_u32_e64 s[78:79], s98, v87
	v_cndmask_b32_e64 v43, 0, v43, s[50:51]
	v_add_u32_e32 v88, 108, v84
	v_cmp_gt_u32_e64 s[50:51], s98, v88
	v_nop
	v_cndmask_b32_e64 v44, 0, v44, s[30:31]
	v_cndmask_b32_e64 v45, 0, v45, s[36:37]
	v_cndmask_b32_e64 v46, 0, v46, s[78:79]
	v_cndmask_b32_e64 v47, 0, v47, s[50:51]
	v_cvt_pk_bf16_f32 v64, v32, v33
	v_cvt_pk_bf16_f32 v65, v34, v35
	v_cvt_pk_bf16_f32 v66, v36, v37
	v_cvt_pk_bf16_f32 v67, v38, v39
	v_cvt_pk_bf16_f32 v68, v40, v41
	v_cvt_pk_bf16_f32 v69, v42, v43
	v_cvt_pk_bf16_f32 v70, v44, v45
	v_cvt_pk_bf16_f32 v71, v46, v47
	v_pk_add_f32 v[232:233], v[232:233], v[32:33]
	v_pk_add_f32 v[232:233], v[232:233], v[34:35]
	v_pk_add_f32 v[232:233], v[232:233], v[36:37]
	v_pk_add_f32 v[232:233], v[232:233], v[38:39]
	v_pk_add_f32 v[232:233], v[232:233], v[40:41]
	v_pk_add_f32 v[232:233], v[232:233], v[42:43]
	v_pk_add_f32 v[232:233], v[232:233], v[44:45]
	v_pk_add_f32 v[232:233], v[232:233], v[46:47]
	s_waitcnt lgkmcnt(12)
	v_mfma_f32_32x32x16_bf16 v[0:15], v[64:67], v[72:75], v[0:15]
	v_mfma_f32_32x32x16_bf16 v[16:31], v[64:67], v[76:79], v[16:31]
	v_mfma_f32_32x32x16_bf16 v[0:15], v[68:71], v[220:223], v[0:15]
	v_mfma_f32_32x32x16_bf16 v[16:31], v[68:71], v[224:227], v[16:31]
	s_add_i32 s90, s76, 128
	v_add_u32_e32 v80, s90, v239
	v_add_u32_e32 v83, s90, v240
	v_add_u32_e32 v99, s90, v241
	v_add_u32_e32 v253, s90, v242
	v_add_u32_e32 v254, s90, v101
	v_add_u32_e32 v255, s90, v150
	v_med3_i32 v80, v80, 0, s99
	v_med3_i32 v83, v83, 0, s99
	v_med3_i32 v99, v99, 0, s99
	v_med3_i32 v253, v253, 0, s99
	v_med3_i32 v254, v254, 0, s99
	v_med3_i32 v255, v255, 0, s99
	v_mad_u32_u24 v80, v80, s100, v252
	v_mad_u32_u24 v83, v83, s100, v252
	v_mad_u32_u24 v99, v99, s100, v252
	v_mad_u32_u24 v253, v253, s100, v252
	v_mad_u32_u24 v254, v254, s100, v153
	v_mad_u32_u24 v255, v255, s100, v153
	global_load_dwordx4 v[188:191], v80, s[82:83]
	global_load_dwordx4 v[192:195], v83, s[82:83]
	global_load_dwordx4 v[196:199], v99, s[82:83]
	global_load_dwordx4 v[200:203], v253, s[82:83]
	global_load_dwordx4 v[204:207], v254, s[82:83] offset:768
	global_load_dwordx4 v[208:211], v255, s[82:83] offset:768
	global_load_dwordx4 v[212:215], v254, s[82:83] offset:832
	global_load_dwordx4 v[216:219], v255, s[82:83] offset:832
	ds_read2_b32 v[32:33], v115 offset0:40 offset1:41
	ds_read2_b32 v[34:35], v115 offset0:42 offset1:43
	ds_read2_b32 v[36:37], v115 offset0:50 offset1:51
	ds_read2_b32 v[38:39], v115 offset0:52 offset1:53
	ds_read2_b32 v[40:41], v115 offset0:60 offset1:61
	ds_read2_b32 v[42:43], v115 offset0:62 offset1:63
	ds_read2_b32 v[44:45], v115 offset0:70 offset1:71
	ds_read2_b32 v[46:47], v115 offset0:72 offset1:73
	s_waitcnt lgkmcnt(0)
	v_mfma_f32_32x32x16_bf16 v[32:47], v[116:119], v[48:51], v[32:47]
	ds_read_b64_tr_b16 v[72:73], v231
	ds_read_b64_tr_b16 v[74:75], v231 offset:512
	ds_read_b64_tr_b16 v[76:77], v231 offset:2048
	ds_read_b64_tr_b16 v[78:79], v231 offset:2560
	ds_read_b64_tr_b16 v[220:221], v231 offset:1024
	ds_read_b64_tr_b16 v[222:223], v231 offset:1536
	ds_read_b64_tr_b16 v[224:225], v231 offset:3072
	ds_read_b64_tr_b16 v[226:227], v231 offset:3584
	s_waitcnt vmcnt(8)
	ds_write_b128 v247, v[156:159]
	ds_write_b128 v247, v[160:163] offset:1024
	ds_write_b128 v247, v[164:167] offset:2048
	ds_write_b128 v247, v[168:171] offset:3072
	ds_read_b128 v[156:159], v248
	ds_read_b128 v[160:163], v249
	ds_read_b128 v[164:167], v250
	ds_read_b128 v[168:171], v251
	ds_write_b128 v112, v[172:175]
	ds_write_b128 v112, v[176:179] offset:1024
	ds_write_b128 v112, v[180:183] offset:2048
	ds_write_b128 v112, v[184:187] offset:3072
	v_mfma_f32_32x32x16_bf16 v[32:47], v[120:123], v[52:55], v[32:47]
	v_mfma_f32_32x32x16_bf16 v[32:47], v[124:127], v[56:59], v[32:47]
	v_mfma_f32_32x32x16_bf16 v[32:47], v[128:131], v[60:63], v[32:47]
	s_nop 11
	v_exp_f32_e32 v32, v32
	v_exp_f32_e32 v33, v33
	v_exp_f32_e32 v34, v34
	v_exp_f32_e32 v35, v35
	v_exp_f32_e32 v36, v36
	v_exp_f32_e32 v37, v37
	v_exp_f32_e32 v38, v38
	v_exp_f32_e32 v39, v39
	v_exp_f32_e32 v40, v40
	v_exp_f32_e32 v41, v41
	v_exp_f32_e32 v42, v42
	v_exp_f32_e32 v43, v43
	v_exp_f32_e32 v44, v44
	v_exp_f32_e32 v45, v45
	v_exp_f32_e32 v46, v46
	v_exp_f32_e32 v47, v47
	s_add_i32 s90, s76, -128
	v_lshlrev_b32_e32 v84, 2, v107
	v_add_u32_e32 v84, s90, v84
	v_add_u32_e32 v85, 0, v84
	v_add_u32_e32 v86, 4, v84
	v_add_u32_e32 v87, 8, v84
	v_add_u32_e32 v88, 12, v84
	v_cmp_gt_u32_e64 s[30:31], s98, v85
	v_cmp_gt_u32_e64 s[36:37], s98, v86
	v_cmp_gt_u32_e64 s[78:79], s98, v87
	v_cmp_gt_u32_e64 s[50:51], s98, v88
	v_cndmask_b32_e64 v32, 0, v32, s[30:31]
	v_add_u32_e32 v85, 32, v84
	v_cmp_gt_u32_e64 s[30:31], s98, v85
	v_cndmask_b32_e64 v33, 0, v33, s[36:37]
	v_add_u32_e32 v86, 36, v84
	v_cmp_gt_u32_e64 s[36:37], s98, v86
	v_cndmask_b32_e64 v34, 0, v34, s[78:79]
	v_add_u32_e32 v87, 40, v84
	v_cmp_gt_u32_e64 s[78:79], s98, v87
	v_cndmask_b32_e64 v35, 0, v35, s[50:51]
	v_add_u32_e32 v88, 44, v84
	v_cmp_gt_u32_e64 s[50:51], s98, v88
	v_cndmask_b32_e64 v36, 0, v36, s[30:31]
	v_add_u32_e32 v85, 64, v84
	v_cmp_gt_u32_e64 s[30:31], s98, v85
	v_cndmask_b32_e64 v37, 0, v37, s[36:37]
	v_add_u32_e32 v86, 68, v84
	v_cmp_gt_u32_e64 s[36:37], s98, v86
	v_cndmask_b32_e64 v38, 0, v38, s[78:79]
	v_add_u32_e32 v87, 72, v84
	v_cmp_gt_u32_e64 s[78:79], s98, v87
	v_cndmask_b32_e64 v39, 0, v39, s[50:51]
	v_add_u32_e32 v88, 76, v84
	v_cmp_gt_u32_e64 s[50:51], s98, v88
	v_cndmask_b32_e64 v40, 0, v40, s[30:31]
	v_add_u32_e32 v85, 96, v84
	v_cmp_gt_u32_e64 s[30:31], s98, v85
	v_cndmask_b32_e64 v41, 0, v41, s[36:37]
	v_add_u32_e32 v86, 100, v84
	v_cmp_gt_u32_e64 s[36:37], s98, v86
	v_cndmask_b32_e64 v42, 0, v42, s[78:79]
	v_add_u32_e32 v87, 104, v84
	v_cmp_gt_u32_e64 s[78:79], s98, v87
	v_cndmask_b32_e64 v43, 0, v43, s[50:51]
	v_add_u32_e32 v88, 108, v84
	v_cmp_gt_u32_e64 s[50:51], s98, v88
	v_nop
	v_cndmask_b32_e64 v44, 0, v44, s[30:31]
	v_cndmask_b32_e64 v45, 0, v45, s[36:37]
	v_cndmask_b32_e64 v46, 0, v46, s[78:79]
	v_cndmask_b32_e64 v47, 0, v47, s[50:51]
	v_cvt_pk_bf16_f32 v64, v32, v33
	v_cvt_pk_bf16_f32 v65, v34, v35
	v_cvt_pk_bf16_f32 v66, v36, v37
	v_cvt_pk_bf16_f32 v67, v38, v39
	v_cvt_pk_bf16_f32 v68, v40, v41
	v_cvt_pk_bf16_f32 v69, v42, v43
	v_cvt_pk_bf16_f32 v70, v44, v45
	v_cvt_pk_bf16_f32 v71, v46, v47
	v_pk_add_f32 v[232:233], v[232:233], v[32:33]
	v_pk_add_f32 v[232:233], v[232:233], v[34:35]
	v_pk_add_f32 v[232:233], v[232:233], v[36:37]
	v_pk_add_f32 v[232:233], v[232:233], v[38:39]
	v_pk_add_f32 v[232:233], v[232:233], v[40:41]
	v_pk_add_f32 v[232:233], v[232:233], v[42:43]
	v_pk_add_f32 v[232:233], v[232:233], v[44:45]
	v_pk_add_f32 v[232:233], v[232:233], v[46:47]
	s_waitcnt lgkmcnt(12)
	v_mfma_f32_32x32x16_bf16 v[0:15], v[64:67], v[72:75], v[0:15]
	v_mfma_f32_32x32x16_bf16 v[16:31], v[64:67], v[76:79], v[16:31]
	v_mfma_f32_32x32x16_bf16 v[0:15], v[68:71], v[220:223], v[0:15]
	v_mfma_f32_32x32x16_bf16 v[16:31], v[68:71], v[224:227], v[16:31]
	s_add_i32 s90, s76, 256
	v_add_u32_e32 v80, s90, v239
	v_add_u32_e32 v83, s90, v240
	v_add_u32_e32 v99, s90, v241
	v_add_u32_e32 v253, s90, v242
	v_add_u32_e32 v254, s90, v101
	v_add_u32_e32 v255, s90, v150
	v_med3_i32 v80, v80, 0, s99
	v_med3_i32 v83, v83, 0, s99
	v_med3_i32 v99, v99, 0, s99
	v_med3_i32 v253, v253, 0, s99
	v_med3_i32 v254, v254, 0, s99
	v_med3_i32 v255, v255, 0, s99
	v_mad_u32_u24 v80, v80, s100, v252
	v_mad_u32_u24 v83, v83, s100, v252
	v_mad_u32_u24 v99, v99, s100, v252
	v_mad_u32_u24 v253, v253, s100, v252
	v_mad_u32_u24 v254, v254, s100, v153
	v_mad_u32_u24 v255, v255, s100, v153
	global_load_dwordx4 v[116:119], v80, s[82:83]
	global_load_dwordx4 v[120:123], v83, s[82:83]
	global_load_dwordx4 v[124:127], v99, s[82:83]
	global_load_dwordx4 v[128:131], v253, s[82:83]
	global_load_dwordx4 v[132:135], v254, s[82:83] offset:768
	global_load_dwordx4 v[136:139], v255, s[82:83] offset:768
	global_load_dwordx4 v[140:143], v254, s[82:83] offset:832
	global_load_dwordx4 v[144:147], v255, s[82:83] offset:832
	ds_read2_b32 v[32:33], v115 offset0:80 offset1:81
	ds_read2_b32 v[34:35], v115 offset0:82 offset1:83
	ds_read2_b32 v[36:37], v115 offset0:90 offset1:91
	ds_read2_b32 v[38:39], v115 offset0:92 offset1:93
	ds_read2_b32 v[40:41], v115 offset0:100 offset1:101
	ds_read2_b32 v[42:43], v115 offset0:102 offset1:103
	ds_read2_b32 v[44:45], v115 offset0:110 offset1:111
	ds_read2_b32 v[46:47], v115 offset0:112 offset1:113
	s_waitcnt lgkmcnt(0)
	v_mfma_f32_32x32x16_bf16 v[32:47], v[156:159], v[48:51], v[32:47]
	ds_read_b64_tr_b16 v[72:73], v231
	ds_read_b64_tr_b16 v[74:75], v231 offset:512
	ds_read_b64_tr_b16 v[76:77], v231 offset:2048
	ds_read_b64_tr_b16 v[78:79], v231 offset:2560
	ds_read_b64_tr_b16 v[220:221], v231 offset:1024
	ds_read_b64_tr_b16 v[222:223], v231 offset:1536
	ds_read_b64_tr_b16 v[224:225], v231 offset:3072
	ds_read_b64_tr_b16 v[226:227], v231 offset:3584
	s_waitcnt vmcnt(8)
	ds_write_b128 v247, v[188:191]
	ds_write_b128 v247, v[192:195] offset:1024
	ds_write_b128 v247, v[196:199] offset:2048
	ds_write_b128 v247, v[200:203] offset:3072
	ds_read_b128 v[188:191], v248
	ds_read_b128 v[192:195], v249
	ds_read_b128 v[196:199], v250
	ds_read_b128 v[200:203], v251
	ds_write_b128 v112, v[204:207]
	ds_write_b128 v112, v[208:211] offset:1024
	ds_write_b128 v112, v[212:215] offset:2048
	ds_write_b128 v112, v[216:219] offset:3072
	v_mfma_f32_32x32x16_bf16 v[32:47], v[160:163], v[52:55], v[32:47]
	v_mfma_f32_32x32x16_bf16 v[32:47], v[164:167], v[56:59], v[32:47]
	v_mfma_f32_32x32x16_bf16 v[32:47], v[168:171], v[60:63], v[32:47]
	s_nop 11
	v_exp_f32_e32 v32, v32
	v_exp_f32_e32 v33, v33
	v_exp_f32_e32 v34, v34
	v_exp_f32_e32 v35, v35
	v_exp_f32_e32 v36, v36
	v_exp_f32_e32 v37, v37
	v_exp_f32_e32 v38, v38
	v_exp_f32_e32 v39, v39
	v_exp_f32_e32 v40, v40
	v_exp_f32_e32 v41, v41
	v_exp_f32_e32 v42, v42
	v_exp_f32_e32 v43, v43
	v_exp_f32_e32 v44, v44
	v_exp_f32_e32 v45, v45
	v_exp_f32_e32 v46, v46
	v_exp_f32_e32 v47, v47
	s_add_i32 s90, s76, 0
	v_lshlrev_b32_e32 v84, 2, v107
	v_add_u32_e32 v84, s90, v84
	v_add_u32_e32 v85, 0, v84
	v_add_u32_e32 v86, 4, v84
	v_add_u32_e32 v87, 8, v84
	v_add_u32_e32 v88, 12, v84
	v_cmp_gt_u32_e64 s[30:31], s98, v85
	v_cmp_gt_u32_e64 s[36:37], s98, v86
	v_cmp_gt_u32_e64 s[78:79], s98, v87
	v_cmp_gt_u32_e64 s[50:51], s98, v88
	v_cndmask_b32_e64 v32, 0, v32, s[30:31]
	v_add_u32_e32 v85, 32, v84
	v_cmp_gt_u32_e64 s[30:31], s98, v85
	v_cndmask_b32_e64 v33, 0, v33, s[36:37]
	v_add_u32_e32 v86, 36, v84
	v_cmp_gt_u32_e64 s[36:37], s98, v86
	v_cndmask_b32_e64 v34, 0, v34, s[78:79]
	v_add_u32_e32 v87, 40, v84
	v_cmp_gt_u32_e64 s[78:79], s98, v87
	v_cndmask_b32_e64 v35, 0, v35, s[50:51]
	v_add_u32_e32 v88, 44, v84
	v_cmp_gt_u32_e64 s[50:51], s98, v88
	v_cndmask_b32_e64 v36, 0, v36, s[30:31]
	v_add_u32_e32 v85, 64, v84
	v_cmp_gt_u32_e64 s[30:31], s98, v85
	v_cndmask_b32_e64 v37, 0, v37, s[36:37]
	v_add_u32_e32 v86, 68, v84
	v_cmp_gt_u32_e64 s[36:37], s98, v86
	v_cndmask_b32_e64 v38, 0, v38, s[78:79]
	v_add_u32_e32 v87, 72, v84
	v_cmp_gt_u32_e64 s[78:79], s98, v87
	v_cndmask_b32_e64 v39, 0, v39, s[50:51]
	v_add_u32_e32 v88, 76, v84
	v_cmp_gt_u32_e64 s[50:51], s98, v88
	v_cndmask_b32_e64 v40, 0, v40, s[30:31]
	v_add_u32_e32 v85, 96, v84
	v_cmp_gt_u32_e64 s[30:31], s98, v85
	v_cndmask_b32_e64 v41, 0, v41, s[36:37]
	v_add_u32_e32 v86, 100, v84
	v_cmp_gt_u32_e64 s[36:37], s98, v86
	v_cndmask_b32_e64 v42, 0, v42, s[78:79]
	v_add_u32_e32 v87, 104, v84
	v_cmp_gt_u32_e64 s[78:79], s98, v87
	v_cndmask_b32_e64 v43, 0, v43, s[50:51]
	v_add_u32_e32 v88, 108, v84
	v_cmp_gt_u32_e64 s[50:51], s98, v88
	v_nop
	v_cndmask_b32_e64 v44, 0, v44, s[30:31]
	v_cndmask_b32_e64 v45, 0, v45, s[36:37]
	v_cndmask_b32_e64 v46, 0, v46, s[78:79]
	v_cndmask_b32_e64 v47, 0, v47, s[50:51]
	v_cvt_pk_bf16_f32 v64, v32, v33
	v_cvt_pk_bf16_f32 v65, v34, v35
	v_cvt_pk_bf16_f32 v66, v36, v37
	v_cvt_pk_bf16_f32 v67, v38, v39
	v_cvt_pk_bf16_f32 v68, v40, v41
	v_cvt_pk_bf16_f32 v69, v42, v43
	v_cvt_pk_bf16_f32 v70, v44, v45
	v_cvt_pk_bf16_f32 v71, v46, v47
	v_pk_add_f32 v[232:233], v[232:233], v[32:33]
	v_pk_add_f32 v[232:233], v[232:233], v[34:35]
	v_pk_add_f32 v[232:233], v[232:233], v[36:37]
	v_pk_add_f32 v[232:233], v[232:233], v[38:39]
	v_pk_add_f32 v[232:233], v[232:233], v[40:41]
	v_pk_add_f32 v[232:233], v[232:233], v[42:43]
	v_pk_add_f32 v[232:233], v[232:233], v[44:45]
	v_pk_add_f32 v[232:233], v[232:233], v[46:47]
	s_waitcnt lgkmcnt(12)
	v_mfma_f32_32x32x16_bf16 v[0:15], v[64:67], v[72:75], v[0:15]
	v_mfma_f32_32x32x16_bf16 v[16:31], v[64:67], v[76:79], v[16:31]
	v_mfma_f32_32x32x16_bf16 v[0:15], v[68:71], v[220:223], v[0:15]
	v_mfma_f32_32x32x16_bf16 v[16:31], v[68:71], v[224:227], v[16:31]
	s_add_i32 s90, s76, 384
	v_add_u32_e32 v80, s90, v239
	v_add_u32_e32 v83, s90, v240
	v_add_u32_e32 v99, s90, v241
	v_add_u32_e32 v253, s90, v242
	v_add_u32_e32 v254, s90, v101
	v_add_u32_e32 v255, s90, v150
	v_med3_i32 v80, v80, 0, s99
	v_med3_i32 v83, v83, 0, s99
	v_med3_i32 v99, v99, 0, s99
	v_med3_i32 v253, v253, 0, s99
	v_med3_i32 v254, v254, 0, s99
	v_med3_i32 v255, v255, 0, s99
	v_mad_u32_u24 v80, v80, s100, v252
	v_mad_u32_u24 v83, v83, s100, v252
	v_mad_u32_u24 v99, v99, s100, v252
	v_mad_u32_u24 v253, v253, s100, v252
	v_mad_u32_u24 v254, v254, s100, v153
	v_mad_u32_u24 v255, v255, s100, v153
	global_load_dwordx4 v[156:159], v80, s[82:83]
	global_load_dwordx4 v[160:163], v83, s[82:83]
	global_load_dwordx4 v[164:167], v99, s[82:83]
	global_load_dwordx4 v[168:171], v253, s[82:83]
	global_load_dwordx4 v[172:175], v254, s[82:83] offset:768
	global_load_dwordx4 v[176:179], v255, s[82:83] offset:768
	global_load_dwordx4 v[180:183], v254, s[82:83] offset:832
	global_load_dwordx4 v[184:187], v255, s[82:83] offset:832
	ds_read2_b32 v[32:33], v115 offset0:120 offset1:121
	ds_read2_b32 v[34:35], v115 offset0:122 offset1:123
	ds_read2_b32 v[36:37], v115 offset0:130 offset1:131
	ds_read2_b32 v[38:39], v115 offset0:132 offset1:133
	ds_read2_b32 v[40:41], v115 offset0:140 offset1:141
	ds_read2_b32 v[42:43], v115 offset0:142 offset1:143
	ds_read2_b32 v[44:45], v115 offset0:150 offset1:151
	ds_read2_b32 v[46:47], v115 offset0:152 offset1:153
	s_waitcnt lgkmcnt(0)
	v_mfma_f32_32x32x16_bf16 v[32:47], v[188:191], v[48:51], v[32:47]
	ds_read_b64_tr_b16 v[72:73], v231
	ds_read_b64_tr_b16 v[74:75], v231 offset:512
	ds_read_b64_tr_b16 v[76:77], v231 offset:2048
	ds_read_b64_tr_b16 v[78:79], v231 offset:2560
	ds_read_b64_tr_b16 v[220:221], v231 offset:1024
	ds_read_b64_tr_b16 v[222:223], v231 offset:1536
	ds_read_b64_tr_b16 v[224:225], v231 offset:3072
	ds_read_b64_tr_b16 v[226:227], v231 offset:3584
	s_waitcnt vmcnt(8)
	ds_write_b128 v247, v[116:119]
	ds_write_b128 v247, v[120:123] offset:1024
	ds_write_b128 v247, v[124:127] offset:2048
	ds_write_b128 v247, v[128:131] offset:3072
	ds_read_b128 v[116:119], v248
	ds_read_b128 v[120:123], v249
	ds_read_b128 v[124:127], v250
	ds_read_b128 v[128:131], v251
	ds_write_b128 v112, v[132:135]
	ds_write_b128 v112, v[136:139] offset:1024
	ds_write_b128 v112, v[140:143] offset:2048
	ds_write_b128 v112, v[144:147] offset:3072
	v_mfma_f32_32x32x16_bf16 v[32:47], v[192:195], v[52:55], v[32:47]
	v_mfma_f32_32x32x16_bf16 v[32:47], v[196:199], v[56:59], v[32:47]
	v_mfma_f32_32x32x16_bf16 v[32:47], v[200:203], v[60:63], v[32:47]
	s_nop 11
	v_exp_f32_e32 v32, v32
	v_exp_f32_e32 v33, v33
	v_exp_f32_e32 v34, v34
	v_exp_f32_e32 v35, v35
	v_exp_f32_e32 v36, v36
	v_exp_f32_e32 v37, v37
	v_exp_f32_e32 v38, v38
	v_exp_f32_e32 v39, v39
	v_exp_f32_e32 v40, v40
	v_exp_f32_e32 v41, v41
	v_exp_f32_e32 v42, v42
	v_exp_f32_e32 v43, v43
	v_exp_f32_e32 v44, v44
	v_exp_f32_e32 v45, v45
	v_exp_f32_e32 v46, v46
	v_exp_f32_e32 v47, v47
	s_add_i32 s90, s76, 128
	v_lshlrev_b32_e32 v84, 2, v107
	v_add_u32_e32 v84, s90, v84
	v_add_u32_e32 v85, 0, v84
	v_add_u32_e32 v86, 4, v84
	v_add_u32_e32 v87, 8, v84
	v_add_u32_e32 v88, 12, v84
	v_cmp_gt_u32_e64 s[30:31], s98, v85
	v_cmp_gt_u32_e64 s[36:37], s98, v86
	v_cmp_gt_u32_e64 s[78:79], s98, v87
	v_cmp_gt_u32_e64 s[50:51], s98, v88
	v_cndmask_b32_e64 v32, 0, v32, s[30:31]
	v_add_u32_e32 v85, 32, v84
	v_cmp_gt_u32_e64 s[30:31], s98, v85
	v_cndmask_b32_e64 v33, 0, v33, s[36:37]
	v_add_u32_e32 v86, 36, v84
	v_cmp_gt_u32_e64 s[36:37], s98, v86
	v_cndmask_b32_e64 v34, 0, v34, s[78:79]
	v_add_u32_e32 v87, 40, v84
	v_cmp_gt_u32_e64 s[78:79], s98, v87
	v_cndmask_b32_e64 v35, 0, v35, s[50:51]
	v_add_u32_e32 v88, 44, v84
	v_cmp_gt_u32_e64 s[50:51], s98, v88
	v_cndmask_b32_e64 v36, 0, v36, s[30:31]
	v_add_u32_e32 v85, 64, v84
	v_cmp_gt_u32_e64 s[30:31], s98, v85
	v_cndmask_b32_e64 v37, 0, v37, s[36:37]
	v_add_u32_e32 v86, 68, v84
	v_cmp_gt_u32_e64 s[36:37], s98, v86
	v_cndmask_b32_e64 v38, 0, v38, s[78:79]
	v_add_u32_e32 v87, 72, v84
	v_cmp_gt_u32_e64 s[78:79], s98, v87
	v_cndmask_b32_e64 v39, 0, v39, s[50:51]
	v_add_u32_e32 v88, 76, v84
	v_cmp_gt_u32_e64 s[50:51], s98, v88
	v_cndmask_b32_e64 v40, 0, v40, s[30:31]
	v_add_u32_e32 v85, 96, v84
	v_cmp_gt_u32_e64 s[30:31], s98, v85
	v_cndmask_b32_e64 v41, 0, v41, s[36:37]
	v_add_u32_e32 v86, 100, v84
	v_cmp_gt_u32_e64 s[36:37], s98, v86
	v_cndmask_b32_e64 v42, 0, v42, s[78:79]
	v_add_u32_e32 v87, 104, v84
	v_cmp_gt_u32_e64 s[78:79], s98, v87
	v_cndmask_b32_e64 v43, 0, v43, s[50:51]
	v_add_u32_e32 v88, 108, v84
	v_cmp_gt_u32_e64 s[50:51], s98, v88
	v_nop
	v_cndmask_b32_e64 v44, 0, v44, s[30:31]
	v_cndmask_b32_e64 v45, 0, v45, s[36:37]
	v_cndmask_b32_e64 v46, 0, v46, s[78:79]
	v_cndmask_b32_e64 v47, 0, v47, s[50:51]
	v_cvt_pk_bf16_f32 v64, v32, v33
	v_cvt_pk_bf16_f32 v65, v34, v35
	v_cvt_pk_bf16_f32 v66, v36, v37
	v_cvt_pk_bf16_f32 v67, v38, v39
	v_cvt_pk_bf16_f32 v68, v40, v41
	v_cvt_pk_bf16_f32 v69, v42, v43
	v_cvt_pk_bf16_f32 v70, v44, v45
	v_cvt_pk_bf16_f32 v71, v46, v47
	v_pk_add_f32 v[232:233], v[232:233], v[32:33]
	v_pk_add_f32 v[232:233], v[232:233], v[34:35]
	v_pk_add_f32 v[232:233], v[232:233], v[36:37]
	v_pk_add_f32 v[232:233], v[232:233], v[38:39]
	v_pk_add_f32 v[232:233], v[232:233], v[40:41]
	v_pk_add_f32 v[232:233], v[232:233], v[42:43]
	v_pk_add_f32 v[232:233], v[232:233], v[44:45]
	v_pk_add_f32 v[232:233], v[232:233], v[46:47]
	s_waitcnt lgkmcnt(12)
	v_mfma_f32_32x32x16_bf16 v[0:15], v[64:67], v[72:75], v[0:15]
	v_mfma_f32_32x32x16_bf16 v[16:31], v[64:67], v[76:79], v[16:31]
	v_mfma_f32_32x32x16_bf16 v[0:15], v[68:71], v[220:223], v[0:15]
	v_mfma_f32_32x32x16_bf16 v[16:31], v[68:71], v[224:227], v[16:31]
	s_add_i32 s90, s76, 512
	v_add_u32_e32 v80, s90, v239
	v_add_u32_e32 v83, s90, v240
	v_add_u32_e32 v99, s90, v241
	v_add_u32_e32 v253, s90, v242
	v_add_u32_e32 v254, s90, v101
	v_add_u32_e32 v255, s90, v150
	v_med3_i32 v80, v80, 0, s99
	v_med3_i32 v83, v83, 0, s99
	v_med3_i32 v99, v99, 0, s99
	v_med3_i32 v253, v253, 0, s99
	v_med3_i32 v254, v254, 0, s99
	v_med3_i32 v255, v255, 0, s99
	v_mad_u32_u24 v80, v80, s100, v252
	v_mad_u32_u24 v83, v83, s100, v252
	v_mad_u32_u24 v99, v99, s100, v252
	v_mad_u32_u24 v253, v253, s100, v252
	v_mad_u32_u24 v254, v254, s100, v153
	v_mad_u32_u24 v255, v255, s100, v153
	global_load_dwordx4 v[188:191], v80, s[82:83]
	global_load_dwordx4 v[192:195], v83, s[82:83]
	global_load_dwordx4 v[196:199], v99, s[82:83]
	global_load_dwordx4 v[200:203], v253, s[82:83]
	global_load_dwordx4 v[204:207], v254, s[82:83] offset:768
	global_load_dwordx4 v[208:211], v255, s[82:83] offset:768
	global_load_dwordx4 v[212:215], v254, s[82:83] offset:832
	global_load_dwordx4 v[216:219], v255, s[82:83] offset:832
	v_add_u32_e32 v115, 640, v115
	ds_read2_b32 v[32:33], v115 offset0:0 offset1:1
	ds_read2_b32 v[34:35], v115 offset0:2 offset1:3
	ds_read2_b32 v[36:37], v115 offset0:10 offset1:11
	ds_read2_b32 v[38:39], v115 offset0:12 offset1:13
	ds_read2_b32 v[40:41], v115 offset0:20 offset1:21
	ds_read2_b32 v[42:43], v115 offset0:22 offset1:23
	ds_read2_b32 v[44:45], v115 offset0:30 offset1:31
	ds_read2_b32 v[46:47], v115 offset0:32 offset1:33
	s_waitcnt lgkmcnt(0)
	v_mfma_f32_32x32x16_bf16 v[32:47], v[116:119], v[48:51], v[32:47]
	ds_read_b64_tr_b16 v[72:73], v231
	ds_read_b64_tr_b16 v[74:75], v231 offset:512
	ds_read_b64_tr_b16 v[76:77], v231 offset:2048
	ds_read_b64_tr_b16 v[78:79], v231 offset:2560
	ds_read_b64_tr_b16 v[220:221], v231 offset:1024
	ds_read_b64_tr_b16 v[222:223], v231 offset:1536
	ds_read_b64_tr_b16 v[224:225], v231 offset:3072
	ds_read_b64_tr_b16 v[226:227], v231 offset:3584
	s_waitcnt vmcnt(8)
	ds_write_b128 v247, v[156:159]
	ds_write_b128 v247, v[160:163] offset:1024
	ds_write_b128 v247, v[164:167] offset:2048
	ds_write_b128 v247, v[168:171] offset:3072
	ds_read_b128 v[156:159], v248
	ds_read_b128 v[160:163], v249
	ds_read_b128 v[164:167], v250
	ds_read_b128 v[168:171], v251
	ds_write_b128 v112, v[172:175]
	ds_write_b128 v112, v[176:179] offset:1024
	ds_write_b128 v112, v[180:183] offset:2048
	ds_write_b128 v112, v[184:187] offset:3072
	v_mfma_f32_32x32x16_bf16 v[32:47], v[120:123], v[52:55], v[32:47]
	v_mfma_f32_32x32x16_bf16 v[32:47], v[124:127], v[56:59], v[32:47]
	v_mfma_f32_32x32x16_bf16 v[32:47], v[128:131], v[60:63], v[32:47]
	s_nop 11
	v_exp_f32_e32 v32, v32
	v_exp_f32_e32 v33, v33
	v_exp_f32_e32 v34, v34
	v_exp_f32_e32 v35, v35
	v_exp_f32_e32 v36, v36
	v_exp_f32_e32 v37, v37
	v_exp_f32_e32 v38, v38
	v_exp_f32_e32 v39, v39
	v_exp_f32_e32 v40, v40
	v_exp_f32_e32 v41, v41
	v_exp_f32_e32 v42, v42
	v_exp_f32_e32 v43, v43
	v_exp_f32_e32 v44, v44
	v_exp_f32_e32 v45, v45
	v_exp_f32_e32 v46, v46
	v_exp_f32_e32 v47, v47
	s_add_i32 s90, s76, 256
	v_lshlrev_b32_e32 v84, 2, v107
	v_add_u32_e32 v84, s90, v84
	v_add_u32_e32 v85, 0, v84
	v_add_u32_e32 v86, 4, v84
	v_add_u32_e32 v87, 8, v84
	v_add_u32_e32 v88, 12, v84
	v_cmp_gt_u32_e64 s[30:31], s98, v85
	v_cmp_gt_u32_e64 s[36:37], s98, v86
	v_cmp_gt_u32_e64 s[78:79], s98, v87
	v_cmp_gt_u32_e64 s[50:51], s98, v88
	v_cndmask_b32_e64 v32, 0, v32, s[30:31]
	v_add_u32_e32 v85, 32, v84
	v_cmp_gt_u32_e64 s[30:31], s98, v85
	v_cndmask_b32_e64 v33, 0, v33, s[36:37]
	v_add_u32_e32 v86, 36, v84
	v_cmp_gt_u32_e64 s[36:37], s98, v86
	v_cndmask_b32_e64 v34, 0, v34, s[78:79]
	v_add_u32_e32 v87, 40, v84
	v_cmp_gt_u32_e64 s[78:79], s98, v87
	v_cndmask_b32_e64 v35, 0, v35, s[50:51]
	v_add_u32_e32 v88, 44, v84
	v_cmp_gt_u32_e64 s[50:51], s98, v88
	v_cndmask_b32_e64 v36, 0, v36, s[30:31]
	v_add_u32_e32 v85, 64, v84
	v_cmp_gt_u32_e64 s[30:31], s98, v85
	v_cndmask_b32_e64 v37, 0, v37, s[36:37]
	v_add_u32_e32 v86, 68, v84
	v_cmp_gt_u32_e64 s[36:37], s98, v86
	v_cndmask_b32_e64 v38, 0, v38, s[78:79]
	v_add_u32_e32 v87, 72, v84
	v_cmp_gt_u32_e64 s[78:79], s98, v87
	v_cndmask_b32_e64 v39, 0, v39, s[50:51]
	v_add_u32_e32 v88, 76, v84
	v_cmp_gt_u32_e64 s[50:51], s98, v88
	v_cndmask_b32_e64 v40, 0, v40, s[30:31]
	v_add_u32_e32 v85, 96, v84
	v_cmp_gt_u32_e64 s[30:31], s98, v85
	v_cndmask_b32_e64 v41, 0, v41, s[36:37]
	v_add_u32_e32 v86, 100, v84
	v_cmp_gt_u32_e64 s[36:37], s98, v86
	v_cndmask_b32_e64 v42, 0, v42, s[78:79]
	v_add_u32_e32 v87, 104, v84
	v_cmp_gt_u32_e64 s[78:79], s98, v87
	v_cndmask_b32_e64 v43, 0, v43, s[50:51]
	v_add_u32_e32 v88, 108, v84
	v_cmp_gt_u32_e64 s[50:51], s98, v88
	v_nop
	v_cndmask_b32_e64 v44, 0, v44, s[30:31]
	v_cndmask_b32_e64 v45, 0, v45, s[36:37]
	v_cndmask_b32_e64 v46, 0, v46, s[78:79]
	v_cndmask_b32_e64 v47, 0, v47, s[50:51]
	v_cvt_pk_bf16_f32 v64, v32, v33
	v_cvt_pk_bf16_f32 v65, v34, v35
	v_cvt_pk_bf16_f32 v66, v36, v37
	v_cvt_pk_bf16_f32 v67, v38, v39
	v_cvt_pk_bf16_f32 v68, v40, v41
	v_cvt_pk_bf16_f32 v69, v42, v43
	v_cvt_pk_bf16_f32 v70, v44, v45
	v_cvt_pk_bf16_f32 v71, v46, v47
	v_pk_add_f32 v[232:233], v[232:233], v[32:33]
	v_pk_add_f32 v[232:233], v[232:233], v[34:35]
	v_pk_add_f32 v[232:233], v[232:233], v[36:37]
	v_pk_add_f32 v[232:233], v[232:233], v[38:39]
	v_pk_add_f32 v[232:233], v[232:233], v[40:41]
	v_pk_add_f32 v[232:233], v[232:233], v[42:43]
	v_pk_add_f32 v[232:233], v[232:233], v[44:45]
	v_pk_add_f32 v[232:233], v[232:233], v[46:47]
	s_waitcnt lgkmcnt(12)
	v_mfma_f32_32x32x16_bf16 v[0:15], v[64:67], v[72:75], v[0:15]
	v_mfma_f32_32x32x16_bf16 v[16:31], v[64:67], v[76:79], v[16:31]
	v_mfma_f32_32x32x16_bf16 v[0:15], v[68:71], v[220:223], v[0:15]
	v_mfma_f32_32x32x16_bf16 v[16:31], v[68:71], v[224:227], v[16:31]
	s_add_i32 s90, s76, 640
	v_add_u32_e32 v80, s90, v239
	v_add_u32_e32 v83, s90, v240
	v_add_u32_e32 v99, s90, v241
	v_add_u32_e32 v253, s90, v242
	v_add_u32_e32 v254, s90, v101
	v_add_u32_e32 v255, s90, v150
	v_med3_i32 v80, v80, 0, s99
	v_med3_i32 v83, v83, 0, s99
	v_med3_i32 v99, v99, 0, s99
	v_med3_i32 v253, v253, 0, s99
	v_med3_i32 v254, v254, 0, s99
	v_med3_i32 v255, v255, 0, s99
	v_mad_u32_u24 v80, v80, s100, v252
	v_mad_u32_u24 v83, v83, s100, v252
	v_mad_u32_u24 v99, v99, s100, v252
	v_mad_u32_u24 v253, v253, s100, v252
	v_mad_u32_u24 v254, v254, s100, v153
	v_mad_u32_u24 v255, v255, s100, v153
	global_load_dwordx4 v[116:119], v80, s[82:83]
	global_load_dwordx4 v[120:123], v83, s[82:83]
	global_load_dwordx4 v[124:127], v99, s[82:83]
	global_load_dwordx4 v[128:131], v253, s[82:83]
	global_load_dwordx4 v[132:135], v254, s[82:83] offset:768
	global_load_dwordx4 v[136:139], v255, s[82:83] offset:768
	global_load_dwordx4 v[140:143], v254, s[82:83] offset:832
	global_load_dwordx4 v[144:147], v255, s[82:83] offset:832
	ds_read2_b32 v[32:33], v115 offset0:40 offset1:41
	ds_read2_b32 v[34:35], v115 offset0:42 offset1:43
	ds_read2_b32 v[36:37], v115 offset0:50 offset1:51
	ds_read2_b32 v[38:39], v115 offset0:52 offset1:53
	ds_read2_b32 v[40:41], v115 offset0:60 offset1:61
	ds_read2_b32 v[42:43], v115 offset0:62 offset1:63
	ds_read2_b32 v[44:45], v115 offset0:70 offset1:71
	ds_read2_b32 v[46:47], v115 offset0:72 offset1:73
	s_waitcnt lgkmcnt(0)
	v_mfma_f32_32x32x16_bf16 v[32:47], v[156:159], v[48:51], v[32:47]
	ds_read_b64_tr_b16 v[72:73], v231
	ds_read_b64_tr_b16 v[74:75], v231 offset:512
	ds_read_b64_tr_b16 v[76:77], v231 offset:2048
	ds_read_b64_tr_b16 v[78:79], v231 offset:2560
	ds_read_b64_tr_b16 v[220:221], v231 offset:1024
	ds_read_b64_tr_b16 v[222:223], v231 offset:1536
	ds_read_b64_tr_b16 v[224:225], v231 offset:3072
	ds_read_b64_tr_b16 v[226:227], v231 offset:3584
	s_waitcnt vmcnt(8)
	ds_write_b128 v247, v[188:191]
	ds_write_b128 v247, v[192:195] offset:1024
	ds_write_b128 v247, v[196:199] offset:2048
	ds_write_b128 v247, v[200:203] offset:3072
	ds_read_b128 v[188:191], v248
	ds_read_b128 v[192:195], v249
	ds_read_b128 v[196:199], v250
	ds_read_b128 v[200:203], v251
	ds_write_b128 v112, v[204:207]
	ds_write_b128 v112, v[208:211] offset:1024
	ds_write_b128 v112, v[212:215] offset:2048
	ds_write_b128 v112, v[216:219] offset:3072
	v_mfma_f32_32x32x16_bf16 v[32:47], v[160:163], v[52:55], v[32:47]
	v_mfma_f32_32x32x16_bf16 v[32:47], v[164:167], v[56:59], v[32:47]
	v_mfma_f32_32x32x16_bf16 v[32:47], v[168:171], v[60:63], v[32:47]
	s_nop 11
	v_exp_f32_e32 v32, v32
	v_exp_f32_e32 v33, v33
	v_exp_f32_e32 v34, v34
	v_exp_f32_e32 v35, v35
	v_exp_f32_e32 v36, v36
	v_exp_f32_e32 v37, v37
	v_exp_f32_e32 v38, v38
	v_exp_f32_e32 v39, v39
	v_exp_f32_e32 v40, v40
	v_exp_f32_e32 v41, v41
	v_exp_f32_e32 v42, v42
	v_exp_f32_e32 v43, v43
	v_exp_f32_e32 v44, v44
	v_exp_f32_e32 v45, v45
	v_exp_f32_e32 v46, v46
	v_exp_f32_e32 v47, v47
	s_add_i32 s90, s76, 384
	v_lshlrev_b32_e32 v84, 2, v107
	v_add_u32_e32 v84, s90, v84
	v_add_u32_e32 v85, 0, v84
	v_add_u32_e32 v86, 4, v84
	v_add_u32_e32 v87, 8, v84
	v_add_u32_e32 v88, 12, v84
	v_cmp_gt_u32_e64 s[30:31], s98, v85
	v_cmp_gt_u32_e64 s[36:37], s98, v86
	v_cmp_gt_u32_e64 s[78:79], s98, v87
	v_cmp_gt_u32_e64 s[50:51], s98, v88
	v_cndmask_b32_e64 v32, 0, v32, s[30:31]
	v_add_u32_e32 v85, 32, v84
	v_cmp_gt_u32_e64 s[30:31], s98, v85
	v_cndmask_b32_e64 v33, 0, v33, s[36:37]
	v_add_u32_e32 v86, 36, v84
	v_cmp_gt_u32_e64 s[36:37], s98, v86
	v_cndmask_b32_e64 v34, 0, v34, s[78:79]
	v_add_u32_e32 v87, 40, v84
	v_cmp_gt_u32_e64 s[78:79], s98, v87
	v_cndmask_b32_e64 v35, 0, v35, s[50:51]
	v_add_u32_e32 v88, 44, v84
	v_cmp_gt_u32_e64 s[50:51], s98, v88
	v_cndmask_b32_e64 v36, 0, v36, s[30:31]
	v_add_u32_e32 v85, 64, v84
	v_cmp_gt_u32_e64 s[30:31], s98, v85
	v_cndmask_b32_e64 v37, 0, v37, s[36:37]
	v_add_u32_e32 v86, 68, v84
	v_cmp_gt_u32_e64 s[36:37], s98, v86
	v_cndmask_b32_e64 v38, 0, v38, s[78:79]
	v_add_u32_e32 v87, 72, v84
	v_cmp_gt_u32_e64 s[78:79], s98, v87
	v_cndmask_b32_e64 v39, 0, v39, s[50:51]
	v_add_u32_e32 v88, 76, v84
	v_cmp_gt_u32_e64 s[50:51], s98, v88
	v_cndmask_b32_e64 v40, 0, v40, s[30:31]
	v_add_u32_e32 v85, 96, v84
	v_cmp_gt_u32_e64 s[30:31], s98, v85
	v_cndmask_b32_e64 v41, 0, v41, s[36:37]
	v_add_u32_e32 v86, 100, v84
	v_cmp_gt_u32_e64 s[36:37], s98, v86
	v_cndmask_b32_e64 v42, 0, v42, s[78:79]
	v_add_u32_e32 v87, 104, v84
	v_cmp_gt_u32_e64 s[78:79], s98, v87
	v_cndmask_b32_e64 v43, 0, v43, s[50:51]
	v_add_u32_e32 v88, 108, v84
	v_cmp_gt_u32_e64 s[50:51], s98, v88
	v_nop
	v_cndmask_b32_e64 v44, 0, v44, s[30:31]
	v_cndmask_b32_e64 v45, 0, v45, s[36:37]
	v_cndmask_b32_e64 v46, 0, v46, s[78:79]
	v_cndmask_b32_e64 v47, 0, v47, s[50:51]
	v_cvt_pk_bf16_f32 v64, v32, v33
	v_cvt_pk_bf16_f32 v65, v34, v35
	v_cvt_pk_bf16_f32 v66, v36, v37
	v_cvt_pk_bf16_f32 v67, v38, v39
	v_cvt_pk_bf16_f32 v68, v40, v41
	v_cvt_pk_bf16_f32 v69, v42, v43
	v_cvt_pk_bf16_f32 v70, v44, v45
	v_cvt_pk_bf16_f32 v71, v46, v47
	v_pk_add_f32 v[232:233], v[232:233], v[32:33]
	v_pk_add_f32 v[232:233], v[232:233], v[34:35]
	v_pk_add_f32 v[232:233], v[232:233], v[36:37]
	v_pk_add_f32 v[232:233], v[232:233], v[38:39]
	v_pk_add_f32 v[232:233], v[232:233], v[40:41]
	v_pk_add_f32 v[232:233], v[232:233], v[42:43]
	v_pk_add_f32 v[232:233], v[232:233], v[44:45]
	v_pk_add_f32 v[232:233], v[232:233], v[46:47]
	s_waitcnt lgkmcnt(12)
	v_mfma_f32_32x32x16_bf16 v[0:15], v[64:67], v[72:75], v[0:15]
	v_mfma_f32_32x32x16_bf16 v[16:31], v[64:67], v[76:79], v[16:31]
	v_mfma_f32_32x32x16_bf16 v[0:15], v[68:71], v[220:223], v[0:15]
	v_mfma_f32_32x32x16_bf16 v[16:31], v[68:71], v[224:227], v[16:31]
	s_add_i32 s90, s76, -1024
	v_add_u32_e32 v80, s90, v243
	v_add_u32_e32 v83, s90, v244
	v_add_u32_e32 v99, s90, v245
	v_add_u32_e32 v253, s90, v246
	v_add_u32_e32 v254, s90, v148
	v_add_u32_e32 v255, s90, v151
	v_med3_i32 v80, v80, 0, s99
	v_med3_i32 v83, v83, 0, s99
	v_med3_i32 v99, v99, 0, s99
	v_med3_i32 v253, v253, 0, s99
	v_med3_i32 v254, v254, 0, s99
	v_med3_i32 v255, v255, 0, s99
	v_mad_u32_u24 v80, v80, s100, v252
	v_mad_u32_u24 v83, v83, s100, v252
	v_mad_u32_u24 v99, v99, s100, v252
	v_mad_u32_u24 v253, v253, s100, v252
	v_mad_u32_u24 v254, v254, s100, v153
	v_mad_u32_u24 v255, v255, s100, v153
	global_load_dwordx4 v[156:159], v80, s[82:83]
	global_load_dwordx4 v[160:163], v83, s[82:83]
	global_load_dwordx4 v[164:167], v99, s[82:83]
	global_load_dwordx4 v[168:171], v253, s[82:83]
	global_load_dwordx4 v[172:175], v254, s[82:83] offset:768
	global_load_dwordx4 v[176:179], v255, s[82:83] offset:768
	global_load_dwordx4 v[180:183], v254, s[82:83] offset:832
	global_load_dwordx4 v[184:187], v255, s[82:83] offset:832
	ds_read2_b32 v[32:33], v115 offset0:80 offset1:81
	ds_read2_b32 v[34:35], v115 offset0:82 offset1:83
	ds_read2_b32 v[36:37], v115 offset0:90 offset1:91
	ds_read2_b32 v[38:39], v115 offset0:92 offset1:93
	ds_read2_b32 v[40:41], v115 offset0:100 offset1:101
	ds_read2_b32 v[42:43], v115 offset0:102 offset1:103
	ds_read2_b32 v[44:45], v115 offset0:110 offset1:111
	ds_read2_b32 v[46:47], v115 offset0:112 offset1:113
	s_waitcnt lgkmcnt(0)
	v_mfma_f32_32x32x16_bf16 v[32:47], v[188:191], v[48:51], v[32:47]
	ds_read_b64_tr_b16 v[72:73], v231
	ds_read_b64_tr_b16 v[74:75], v231 offset:512
	ds_read_b64_tr_b16 v[76:77], v231 offset:2048
	ds_read_b64_tr_b16 v[78:79], v231 offset:2560
	ds_read_b64_tr_b16 v[220:221], v231 offset:1024
	ds_read_b64_tr_b16 v[222:223], v231 offset:1536
	ds_read_b64_tr_b16 v[224:225], v231 offset:3072
	ds_read_b64_tr_b16 v[226:227], v231 offset:3584
	s_waitcnt vmcnt(8)
	ds_write_b128 v247, v[116:119]
	ds_write_b128 v247, v[120:123] offset:1024
	ds_write_b128 v247, v[124:127] offset:2048
	ds_write_b128 v247, v[128:131] offset:3072
	ds_read_b128 v[116:119], v248
	ds_read_b128 v[120:123], v249
	ds_read_b128 v[124:127], v250
	ds_read_b128 v[128:131], v251
	ds_write_b128 v112, v[132:135]
	ds_write_b128 v112, v[136:139] offset:1024
	ds_write_b128 v112, v[140:143] offset:2048
	ds_write_b128 v112, v[144:147] offset:3072
	v_mfma_f32_32x32x16_bf16 v[32:47], v[192:195], v[52:55], v[32:47]
	v_mfma_f32_32x32x16_bf16 v[32:47], v[196:199], v[56:59], v[32:47]
	v_mfma_f32_32x32x16_bf16 v[32:47], v[200:203], v[60:63], v[32:47]
	s_nop 11
	v_exp_f32_e32 v32, v32
	v_exp_f32_e32 v33, v33
	v_exp_f32_e32 v34, v34
	v_exp_f32_e32 v35, v35
	v_exp_f32_e32 v36, v36
	v_exp_f32_e32 v37, v37
	v_exp_f32_e32 v38, v38
	v_exp_f32_e32 v39, v39
	v_exp_f32_e32 v40, v40
	v_exp_f32_e32 v41, v41
	v_exp_f32_e32 v42, v42
	v_exp_f32_e32 v43, v43
	v_exp_f32_e32 v44, v44
	v_exp_f32_e32 v45, v45
	v_exp_f32_e32 v46, v46
	v_exp_f32_e32 v47, v47
	s_add_i32 s90, s76, 512
	v_lshlrev_b32_e32 v84, 2, v107
	v_add_u32_e32 v84, s90, v84
	v_add_u32_e32 v85, 0, v84
	v_add_u32_e32 v86, 4, v84
	v_add_u32_e32 v87, 8, v84
	v_add_u32_e32 v88, 12, v84
	v_cmp_gt_u32_e64 s[30:31], s98, v85
	v_cmp_gt_u32_e64 s[36:37], s98, v86
	v_cmp_gt_u32_e64 s[78:79], s98, v87
	v_cmp_gt_u32_e64 s[50:51], s98, v88
	v_cndmask_b32_e64 v32, 0, v32, s[30:31]
	v_add_u32_e32 v85, 32, v84
	v_cmp_gt_u32_e64 s[30:31], s98, v85
	v_cndmask_b32_e64 v33, 0, v33, s[36:37]
	v_add_u32_e32 v86, 36, v84
	v_cmp_gt_u32_e64 s[36:37], s98, v86
	v_cndmask_b32_e64 v34, 0, v34, s[78:79]
	v_add_u32_e32 v87, 40, v84
	v_cmp_gt_u32_e64 s[78:79], s98, v87
	v_cndmask_b32_e64 v35, 0, v35, s[50:51]
	v_add_u32_e32 v88, 44, v84
	v_cmp_gt_u32_e64 s[50:51], s98, v88
	v_cndmask_b32_e64 v36, 0, v36, s[30:31]
	v_add_u32_e32 v85, 64, v84
	v_cmp_gt_u32_e64 s[30:31], s98, v85
	v_cndmask_b32_e64 v37, 0, v37, s[36:37]
	v_add_u32_e32 v86, 68, v84
	v_cmp_gt_u32_e64 s[36:37], s98, v86
	v_cndmask_b32_e64 v38, 0, v38, s[78:79]
	v_add_u32_e32 v87, 72, v84
	v_cmp_gt_u32_e64 s[78:79], s98, v87
	v_cndmask_b32_e64 v39, 0, v39, s[50:51]
	v_add_u32_e32 v88, 76, v84
	v_cmp_gt_u32_e64 s[50:51], s98, v88
	v_cndmask_b32_e64 v40, 0, v40, s[30:31]
	v_add_u32_e32 v85, 96, v84
	v_cmp_gt_u32_e64 s[30:31], s98, v85
	v_cndmask_b32_e64 v41, 0, v41, s[36:37]
	v_add_u32_e32 v86, 100, v84
	v_cmp_gt_u32_e64 s[36:37], s98, v86
	v_cndmask_b32_e64 v42, 0, v42, s[78:79]
	v_add_u32_e32 v87, 104, v84
	v_cmp_gt_u32_e64 s[78:79], s98, v87
	v_cndmask_b32_e64 v43, 0, v43, s[50:51]
	v_add_u32_e32 v88, 108, v84
	v_cmp_gt_u32_e64 s[50:51], s98, v88
	v_nop
	v_cndmask_b32_e64 v44, 0, v44, s[30:31]
	v_cndmask_b32_e64 v45, 0, v45, s[36:37]
	v_cndmask_b32_e64 v46, 0, v46, s[78:79]
	v_cndmask_b32_e64 v47, 0, v47, s[50:51]
	v_cvt_pk_bf16_f32 v64, v32, v33
	v_cvt_pk_bf16_f32 v65, v34, v35
	v_cvt_pk_bf16_f32 v66, v36, v37
	v_cvt_pk_bf16_f32 v67, v38, v39
	v_cvt_pk_bf16_f32 v68, v40, v41
	v_cvt_pk_bf16_f32 v69, v42, v43
	v_cvt_pk_bf16_f32 v70, v44, v45
	v_cvt_pk_bf16_f32 v71, v46, v47
	v_pk_add_f32 v[232:233], v[232:233], v[32:33]
	v_pk_add_f32 v[232:233], v[232:233], v[34:35]
	v_pk_add_f32 v[232:233], v[232:233], v[36:37]
	v_pk_add_f32 v[232:233], v[232:233], v[38:39]
	v_pk_add_f32 v[232:233], v[232:233], v[40:41]
	v_pk_add_f32 v[232:233], v[232:233], v[42:43]
	v_pk_add_f32 v[232:233], v[232:233], v[44:45]
	v_pk_add_f32 v[232:233], v[232:233], v[46:47]
	s_waitcnt lgkmcnt(12)
	v_mfma_f32_32x32x16_bf16 v[0:15], v[64:67], v[72:75], v[0:15]
	v_mfma_f32_32x32x16_bf16 v[16:31], v[64:67], v[76:79], v[16:31]
	v_mfma_f32_32x32x16_bf16 v[0:15], v[68:71], v[220:223], v[0:15]
	v_mfma_f32_32x32x16_bf16 v[16:31], v[68:71], v[224:227], v[16:31]
	s_add_i32 s90, s76, -512
	v_add_u32_e32 v80, s90, v243
	v_add_u32_e32 v83, s90, v244
	v_add_u32_e32 v99, s90, v245
	v_add_u32_e32 v253, s90, v246
	v_add_u32_e32 v254, s90, v148
	v_add_u32_e32 v255, s90, v151
	v_med3_i32 v80, v80, 0, s99
	v_med3_i32 v83, v83, 0, s99
	v_med3_i32 v99, v99, 0, s99
	v_med3_i32 v253, v253, 0, s99
	v_med3_i32 v254, v254, 0, s99
	v_med3_i32 v255, v255, 0, s99
	v_mad_u32_u24 v80, v80, s100, v252
	v_mad_u32_u24 v83, v83, s100, v252
	v_mad_u32_u24 v99, v99, s100, v252
	v_mad_u32_u24 v253, v253, s100, v252
	v_mad_u32_u24 v254, v254, s100, v153
	v_mad_u32_u24 v255, v255, s100, v153
	global_load_dwordx4 v[188:191], v80, s[82:83]
	global_load_dwordx4 v[192:195], v83, s[82:83]
	global_load_dwordx4 v[196:199], v99, s[82:83]
	global_load_dwordx4 v[200:203], v253, s[82:83]
	global_load_dwordx4 v[204:207], v254, s[82:83] offset:768
	global_load_dwordx4 v[208:211], v255, s[82:83] offset:768
	global_load_dwordx4 v[212:215], v254, s[82:83] offset:832
	global_load_dwordx4 v[216:219], v255, s[82:83] offset:832
	ds_read2_b32 v[32:33], v115 offset0:120 offset1:121
	ds_read2_b32 v[34:35], v115 offset0:122 offset1:123
	ds_read2_b32 v[36:37], v115 offset0:130 offset1:131
	ds_read2_b32 v[38:39], v115 offset0:132 offset1:133
	ds_read2_b32 v[40:41], v115 offset0:140 offset1:141
	ds_read2_b32 v[42:43], v115 offset0:142 offset1:143
	ds_read2_b32 v[44:45], v115 offset0:150 offset1:151
	ds_read2_b32 v[46:47], v115 offset0:152 offset1:153
	s_waitcnt lgkmcnt(0)
	v_mfma_f32_32x32x16_bf16 v[32:47], v[116:119], v[48:51], v[32:47]
	ds_read_b64_tr_b16 v[72:73], v231
	ds_read_b64_tr_b16 v[74:75], v231 offset:512
	ds_read_b64_tr_b16 v[76:77], v231 offset:2048
	ds_read_b64_tr_b16 v[78:79], v231 offset:2560
	ds_read_b64_tr_b16 v[220:221], v231 offset:1024
	ds_read_b64_tr_b16 v[222:223], v231 offset:1536
	ds_read_b64_tr_b16 v[224:225], v231 offset:3072
	ds_read_b64_tr_b16 v[226:227], v231 offset:3584
	s_waitcnt vmcnt(8)
	ds_write_b128 v247, v[156:159]
	ds_write_b128 v247, v[160:163] offset:1024
	ds_write_b128 v247, v[164:167] offset:2048
	ds_write_b128 v247, v[168:171] offset:3072
	ds_read_b128 v[156:159], v248
	ds_read_b128 v[160:163], v249
	ds_read_b128 v[164:167], v250
	ds_read_b128 v[168:171], v251
	ds_write_b128 v112, v[172:175]
	ds_write_b128 v112, v[176:179] offset:1024
	ds_write_b128 v112, v[180:183] offset:2048
	ds_write_b128 v112, v[184:187] offset:3072
	v_mfma_f32_32x32x16_bf16 v[32:47], v[120:123], v[52:55], v[32:47]
	v_mfma_f32_32x32x16_bf16 v[32:47], v[124:127], v[56:59], v[32:47]
	v_mfma_f32_32x32x16_bf16 v[32:47], v[128:131], v[60:63], v[32:47]
	s_nop 11
	v_exp_f32_e32 v32, v32
	v_exp_f32_e32 v33, v33
	v_exp_f32_e32 v34, v34
	v_exp_f32_e32 v35, v35
	v_exp_f32_e32 v36, v36
	v_exp_f32_e32 v37, v37
	v_exp_f32_e32 v38, v38
	v_exp_f32_e32 v39, v39
	v_exp_f32_e32 v40, v40
	v_exp_f32_e32 v41, v41
	v_exp_f32_e32 v42, v42
	v_exp_f32_e32 v43, v43
	v_exp_f32_e32 v44, v44
	v_exp_f32_e32 v45, v45
	v_exp_f32_e32 v46, v46
	v_exp_f32_e32 v47, v47
	s_add_i32 s90, s76, 640
	v_lshlrev_b32_e32 v84, 2, v107
	v_add_u32_e32 v84, s90, v84
	v_add_u32_e32 v85, 0, v84
	v_add_u32_e32 v86, 4, v84
	v_add_u32_e32 v87, 8, v84
	v_add_u32_e32 v88, 12, v84
	v_cmp_gt_u32_e64 s[30:31], s98, v85
	v_cmp_gt_u32_e64 s[36:37], s98, v86
	v_cmp_gt_u32_e64 s[78:79], s98, v87
	v_cmp_gt_u32_e64 s[50:51], s98, v88
	v_cndmask_b32_e64 v32, 0, v32, s[30:31]
	v_add_u32_e32 v85, 32, v84
	v_cmp_gt_u32_e64 s[30:31], s98, v85
	v_cndmask_b32_e64 v33, 0, v33, s[36:37]
	v_add_u32_e32 v86, 36, v84
	v_cmp_gt_u32_e64 s[36:37], s98, v86
	v_cndmask_b32_e64 v34, 0, v34, s[78:79]
	v_add_u32_e32 v87, 40, v84
	v_cmp_gt_u32_e64 s[78:79], s98, v87
	v_cndmask_b32_e64 v35, 0, v35, s[50:51]
	v_add_u32_e32 v88, 44, v84
	v_cmp_gt_u32_e64 s[50:51], s98, v88
	v_cndmask_b32_e64 v36, 0, v36, s[30:31]
	v_add_u32_e32 v85, 64, v84
	v_cmp_gt_u32_e64 s[30:31], s98, v85
	v_cndmask_b32_e64 v37, 0, v37, s[36:37]
	v_add_u32_e32 v86, 68, v84
	v_cmp_gt_u32_e64 s[36:37], s98, v86
	v_cndmask_b32_e64 v38, 0, v38, s[78:79]
	v_add_u32_e32 v87, 72, v84
	v_cmp_gt_u32_e64 s[78:79], s98, v87
	v_cndmask_b32_e64 v39, 0, v39, s[50:51]
	v_add_u32_e32 v88, 76, v84
	v_cmp_gt_u32_e64 s[50:51], s98, v88
	v_cndmask_b32_e64 v40, 0, v40, s[30:31]
	v_add_u32_e32 v85, 96, v84
	v_cmp_gt_u32_e64 s[30:31], s98, v85
	v_cndmask_b32_e64 v41, 0, v41, s[36:37]
	v_add_u32_e32 v86, 100, v84
	v_cmp_gt_u32_e64 s[36:37], s98, v86
	v_cndmask_b32_e64 v42, 0, v42, s[78:79]
	v_add_u32_e32 v87, 104, v84
	v_cmp_gt_u32_e64 s[78:79], s98, v87
	v_cndmask_b32_e64 v43, 0, v43, s[50:51]
	v_add_u32_e32 v88, 108, v84
	v_cmp_gt_u32_e64 s[50:51], s98, v88
	v_nop
	v_cndmask_b32_e64 v44, 0, v44, s[30:31]
	v_cndmask_b32_e64 v45, 0, v45, s[36:37]
	v_cndmask_b32_e64 v46, 0, v46, s[78:79]
	v_cndmask_b32_e64 v47, 0, v47, s[50:51]
	v_cvt_pk_bf16_f32 v64, v32, v33
	v_cvt_pk_bf16_f32 v65, v34, v35
	v_cvt_pk_bf16_f32 v66, v36, v37
	v_cvt_pk_bf16_f32 v67, v38, v39
	v_cvt_pk_bf16_f32 v68, v40, v41
	v_cvt_pk_bf16_f32 v69, v42, v43
	v_cvt_pk_bf16_f32 v70, v44, v45
	v_cvt_pk_bf16_f32 v71, v46, v47
	v_pk_add_f32 v[232:233], v[232:233], v[32:33]
	v_pk_add_f32 v[232:233], v[232:233], v[34:35]
	v_pk_add_f32 v[232:233], v[232:233], v[36:37]
	v_pk_add_f32 v[232:233], v[232:233], v[38:39]
	v_pk_add_f32 v[232:233], v[232:233], v[40:41]
	v_pk_add_f32 v[232:233], v[232:233], v[42:43]
	v_pk_add_f32 v[232:233], v[232:233], v[44:45]
	v_pk_add_f32 v[232:233], v[232:233], v[46:47]
	s_waitcnt lgkmcnt(12)
	v_mfma_f32_32x32x16_bf16 v[0:15], v[64:67], v[72:75], v[0:15]
	v_mfma_f32_32x32x16_bf16 v[16:31], v[64:67], v[76:79], v[16:31]
	v_mfma_f32_32x32x16_bf16 v[0:15], v[68:71], v[220:223], v[0:15]
	v_mfma_f32_32x32x16_bf16 v[16:31], v[68:71], v[224:227], v[16:31]
	s_add_i32 s90, s76, 0
	v_add_u32_e32 v80, s90, v243
	v_add_u32_e32 v83, s90, v244
	v_add_u32_e32 v99, s90, v245
	v_add_u32_e32 v253, s90, v246
	v_add_u32_e32 v254, s90, v148
	v_add_u32_e32 v255, s90, v151
	v_med3_i32 v80, v80, 0, s99
	v_med3_i32 v83, v83, 0, s99
	v_med3_i32 v99, v99, 0, s99
	v_med3_i32 v253, v253, 0, s99
	v_med3_i32 v254, v254, 0, s99
	v_med3_i32 v255, v255, 0, s99
	v_mad_u32_u24 v80, v80, s100, v252
	v_mad_u32_u24 v83, v83, s100, v252
	v_mad_u32_u24 v99, v99, s100, v252
	v_mad_u32_u24 v253, v253, s100, v252
	v_mad_u32_u24 v254, v254, s100, v153
	v_mad_u32_u24 v255, v255, s100, v153
	global_load_dwordx4 v[116:119], v80, s[82:83]
	global_load_dwordx4 v[120:123], v83, s[82:83]
	global_load_dwordx4 v[124:127], v99, s[82:83]
	global_load_dwordx4 v[128:131], v253, s[82:83]
	global_load_dwordx4 v[132:135], v254, s[82:83] offset:768
	global_load_dwordx4 v[136:139], v255, s[82:83] offset:768
	global_load_dwordx4 v[140:143], v254, s[82:83] offset:832
	global_load_dwordx4 v[144:147], v255, s[82:83] offset:832
	v_mov_b32_e32 v115, v230
	ds_read2_b32 v[32:33], v115 offset0:0 offset1:1
	ds_read2_b32 v[34:35], v115 offset0:2 offset1:3
	ds_read2_b32 v[36:37], v115 offset0:8 offset1:9
	ds_read2_b32 v[38:39], v115 offset0:10 offset1:11
	ds_read2_b32 v[40:41], v115 offset0:16 offset1:17
	ds_read2_b32 v[42:43], v115 offset0:18 offset1:19
	ds_read2_b32 v[44:45], v115 offset0:24 offset1:25
	ds_read2_b32 v[46:47], v115 offset0:26 offset1:27
	s_waitcnt lgkmcnt(0)
	v_mfma_f32_32x32x16_bf16 v[32:47], v[156:159], v[48:51], v[32:47]
	ds_read_b64_tr_b16 v[72:73], v231
	ds_read_b64_tr_b16 v[74:75], v231 offset:512
	ds_read_b64_tr_b16 v[76:77], v231 offset:2048
	ds_read_b64_tr_b16 v[78:79], v231 offset:2560
	ds_read_b64_tr_b16 v[220:221], v231 offset:1024
	ds_read_b64_tr_b16 v[222:223], v231 offset:1536
	ds_read_b64_tr_b16 v[224:225], v231 offset:3072
	ds_read_b64_tr_b16 v[226:227], v231 offset:3584
	s_waitcnt vmcnt(8)
	ds_write_b128 v247, v[188:191]
	ds_write_b128 v247, v[192:195] offset:1024
	ds_write_b128 v247, v[196:199] offset:2048
	ds_write_b128 v247, v[200:203] offset:3072
	ds_read_b128 v[188:191], v248
	ds_read_b128 v[192:195], v249
	ds_read_b128 v[196:199], v250
	ds_read_b128 v[200:203], v251
	ds_write_b128 v112, v[204:207]
	ds_write_b128 v112, v[208:211] offset:1024
	ds_write_b128 v112, v[212:215] offset:2048
	ds_write_b128 v112, v[216:219] offset:3072
	v_mfma_f32_32x32x16_bf16 v[32:47], v[160:163], v[52:55], v[32:47]
	v_mfma_f32_32x32x16_bf16 v[32:47], v[164:167], v[56:59], v[32:47]
	v_mfma_f32_32x32x16_bf16 v[32:47], v[168:171], v[60:63], v[32:47]
	s_nop 11
	v_exp_f32_e32 v32, v32
	v_exp_f32_e32 v33, v33
	v_exp_f32_e32 v34, v34
	v_exp_f32_e32 v35, v35
	v_exp_f32_e32 v36, v36
	v_exp_f32_e32 v37, v37
	v_exp_f32_e32 v38, v38
	v_exp_f32_e32 v39, v39
	v_exp_f32_e32 v40, v40
	v_exp_f32_e32 v41, v41
	v_exp_f32_e32 v42, v42
	v_exp_f32_e32 v43, v43
	v_exp_f32_e32 v44, v44
	v_exp_f32_e32 v45, v45
	v_exp_f32_e32 v46, v46
	v_exp_f32_e32 v47, v47
	s_add_i32 s90, s76, -1024
	v_lshlrev_b32_e32 v84, 4, v107
	v_add_u32_e32 v84, s90, v84
	v_add_u32_e32 v85, 0, v84
	v_add_u32_e32 v86, 16, v84
	v_add_u32_e32 v87, 32, v84
	v_add_u32_e32 v88, 48, v84
	v_cmp_gt_u32_e64 s[30:31], s98, v85
	v_cmp_gt_u32_e64 s[36:37], s98, v86
	v_cmp_gt_u32_e64 s[78:79], s98, v87
	v_cmp_gt_u32_e64 s[50:51], s98, v88
	v_cndmask_b32_e64 v32, 0, v32, s[30:31]
	v_add_u32_e32 v85, 128, v84
	v_cmp_gt_u32_e64 s[30:31], s98, v85
	v_cndmask_b32_e64 v33, 0, v33, s[36:37]
	v_add_u32_e32 v86, 144, v84
	v_cmp_gt_u32_e64 s[36:37], s98, v86
	v_cndmask_b32_e64 v34, 0, v34, s[78:79]
	v_add_u32_e32 v87, 160, v84
	v_cmp_gt_u32_e64 s[78:79], s98, v87
	v_cndmask_b32_e64 v35, 0, v35, s[50:51]
	v_add_u32_e32 v88, 176, v84
	v_cmp_gt_u32_e64 s[50:51], s98, v88
	v_cndmask_b32_e64 v36, 0, v36, s[30:31]
	v_add_u32_e32 v85, 256, v84
	v_cmp_gt_u32_e64 s[30:31], s98, v85
	v_cndmask_b32_e64 v37, 0, v37, s[36:37]
	v_add_u32_e32 v86, 272, v84
	v_cmp_gt_u32_e64 s[36:37], s98, v86
	v_cndmask_b32_e64 v38, 0, v38, s[78:79]
	v_add_u32_e32 v87, 288, v84
	v_cmp_gt_u32_e64 s[78:79], s98, v87
	v_cndmask_b32_e64 v39, 0, v39, s[50:51]
	v_add_u32_e32 v88, 304, v84
	v_cmp_gt_u32_e64 s[50:51], s98, v88
	v_cndmask_b32_e64 v40, 0, v40, s[30:31]
	v_add_u32_e32 v85, 384, v84
	v_cmp_gt_u32_e64 s[30:31], s98, v85
	v_cndmask_b32_e64 v41, 0, v41, s[36:37]
	v_add_u32_e32 v86, 400, v84
	v_cmp_gt_u32_e64 s[36:37], s98, v86
	v_cndmask_b32_e64 v42, 0, v42, s[78:79]
	v_add_u32_e32 v87, 416, v84
	v_cmp_gt_u32_e64 s[78:79], s98, v87
	v_cndmask_b32_e64 v43, 0, v43, s[50:51]
	v_add_u32_e32 v88, 432, v84
	v_cmp_gt_u32_e64 s[50:51], s98, v88
	v_nop
	v_cndmask_b32_e64 v44, 0, v44, s[30:31]
	v_cndmask_b32_e64 v45, 0, v45, s[36:37]
	v_cndmask_b32_e64 v46, 0, v46, s[78:79]
	v_cndmask_b32_e64 v47, 0, v47, s[50:51]
	v_cvt_pk_bf16_f32 v64, v32, v33
	v_cvt_pk_bf16_f32 v65, v34, v35
	v_cvt_pk_bf16_f32 v66, v36, v37
	v_cvt_pk_bf16_f32 v67, v38, v39
	v_cvt_pk_bf16_f32 v68, v40, v41
	v_cvt_pk_bf16_f32 v69, v42, v43
	v_cvt_pk_bf16_f32 v70, v44, v45
	v_cvt_pk_bf16_f32 v71, v46, v47
	v_pk_add_f32 v[232:233], v[232:233], v[32:33]
	v_pk_add_f32 v[232:233], v[232:233], v[34:35]
	v_pk_add_f32 v[232:233], v[232:233], v[36:37]
	v_pk_add_f32 v[232:233], v[232:233], v[38:39]
	v_pk_add_f32 v[232:233], v[232:233], v[40:41]
	v_pk_add_f32 v[232:233], v[232:233], v[42:43]
	v_pk_add_f32 v[232:233], v[232:233], v[44:45]
	v_pk_add_f32 v[232:233], v[232:233], v[46:47]
	s_waitcnt lgkmcnt(12)
	v_mfma_f32_32x32x16_bf16 v[0:15], v[64:67], v[72:75], v[0:15]
	v_mfma_f32_32x32x16_bf16 v[16:31], v[64:67], v[76:79], v[16:31]
	v_mfma_f32_32x32x16_bf16 v[0:15], v[68:71], v[220:223], v[0:15]
	v_mfma_f32_32x32x16_bf16 v[16:31], v[68:71], v[224:227], v[16:31]
	s_add_i32 s90, s76, 512
	v_add_u32_e32 v80, s90, v243
	v_add_u32_e32 v83, s90, v244
	v_add_u32_e32 v99, s90, v245
	v_add_u32_e32 v253, s90, v246
	v_add_u32_e32 v254, s90, v148
	v_add_u32_e32 v255, s90, v151
	v_med3_i32 v80, v80, 0, s99
	v_med3_i32 v83, v83, 0, s99
	v_med3_i32 v99, v99, 0, s99
	v_med3_i32 v253, v253, 0, s99
	v_med3_i32 v254, v254, 0, s99
	v_med3_i32 v255, v255, 0, s99
	v_mad_u32_u24 v80, v80, s100, v252
	v_mad_u32_u24 v83, v83, s100, v252
	v_mad_u32_u24 v99, v99, s100, v252
	v_mad_u32_u24 v253, v253, s100, v252
	v_mad_u32_u24 v254, v254, s100, v153
	v_mad_u32_u24 v255, v255, s100, v153
	global_load_dwordx4 v[156:159], v80, s[82:83]
	global_load_dwordx4 v[160:163], v83, s[82:83]
	global_load_dwordx4 v[164:167], v99, s[82:83]
	global_load_dwordx4 v[168:171], v253, s[82:83]
	global_load_dwordx4 v[172:175], v254, s[82:83] offset:768
	global_load_dwordx4 v[176:179], v255, s[82:83] offset:768
	global_load_dwordx4 v[180:183], v254, s[82:83] offset:832
	global_load_dwordx4 v[184:187], v255, s[82:83] offset:832
	ds_read2_b32 v[32:33], v115 offset0:32 offset1:33
	ds_read2_b32 v[34:35], v115 offset0:34 offset1:35
	ds_read2_b32 v[36:37], v115 offset0:40 offset1:41
	ds_read2_b32 v[38:39], v115 offset0:42 offset1:43
	ds_read2_b32 v[40:41], v115 offset0:48 offset1:49
	ds_read2_b32 v[42:43], v115 offset0:50 offset1:51
	ds_read2_b32 v[44:45], v115 offset0:56 offset1:57
	ds_read2_b32 v[46:47], v115 offset0:58 offset1:59
	s_waitcnt lgkmcnt(0)
	v_mfma_f32_32x32x16_bf16 v[32:47], v[188:191], v[48:51], v[32:47]
	ds_read_b64_tr_b16 v[72:73], v231
	ds_read_b64_tr_b16 v[74:75], v231 offset:512
	ds_read_b64_tr_b16 v[76:77], v231 offset:2048
	ds_read_b64_tr_b16 v[78:79], v231 offset:2560
	ds_read_b64_tr_b16 v[220:221], v231 offset:1024
	ds_read_b64_tr_b16 v[222:223], v231 offset:1536
	ds_read_b64_tr_b16 v[224:225], v231 offset:3072
	ds_read_b64_tr_b16 v[226:227], v231 offset:3584
	s_waitcnt vmcnt(8)
	ds_write_b128 v247, v[116:119]
	ds_write_b128 v247, v[120:123] offset:1024
	ds_write_b128 v247, v[124:127] offset:2048
	ds_write_b128 v247, v[128:131] offset:3072
	ds_read_b128 v[116:119], v248
	ds_read_b128 v[120:123], v249
	ds_read_b128 v[124:127], v250
	ds_read_b128 v[128:131], v251
	ds_write_b128 v112, v[132:135]
	ds_write_b128 v112, v[136:139] offset:1024
	ds_write_b128 v112, v[140:143] offset:2048
	ds_write_b128 v112, v[144:147] offset:3072
	v_mfma_f32_32x32x16_bf16 v[32:47], v[192:195], v[52:55], v[32:47]
	v_mfma_f32_32x32x16_bf16 v[32:47], v[196:199], v[56:59], v[32:47]
	v_mfma_f32_32x32x16_bf16 v[32:47], v[200:203], v[60:63], v[32:47]
	s_nop 11
	v_exp_f32_e32 v32, v32
	v_exp_f32_e32 v33, v33
	v_exp_f32_e32 v34, v34
	v_exp_f32_e32 v35, v35
	v_exp_f32_e32 v36, v36
	v_exp_f32_e32 v37, v37
	v_exp_f32_e32 v38, v38
	v_exp_f32_e32 v39, v39
	v_exp_f32_e32 v40, v40
	v_exp_f32_e32 v41, v41
	v_exp_f32_e32 v42, v42
	v_exp_f32_e32 v43, v43
	v_exp_f32_e32 v44, v44
	v_exp_f32_e32 v45, v45
	v_exp_f32_e32 v46, v46
	v_exp_f32_e32 v47, v47
	s_add_i32 s90, s76, -512
	v_lshlrev_b32_e32 v84, 4, v107
	v_add_u32_e32 v84, s90, v84
	v_add_u32_e32 v85, 0, v84
	v_add_u32_e32 v86, 16, v84
	v_add_u32_e32 v87, 32, v84
	v_add_u32_e32 v88, 48, v84
	v_cmp_gt_u32_e64 s[30:31], s98, v85
	v_cmp_gt_u32_e64 s[36:37], s98, v86
	v_cmp_gt_u32_e64 s[78:79], s98, v87
	v_cmp_gt_u32_e64 s[50:51], s98, v88
	v_cndmask_b32_e64 v32, 0, v32, s[30:31]
	v_add_u32_e32 v85, 128, v84
	v_cmp_gt_u32_e64 s[30:31], s98, v85
	v_cndmask_b32_e64 v33, 0, v33, s[36:37]
	v_add_u32_e32 v86, 144, v84
	v_cmp_gt_u32_e64 s[36:37], s98, v86
	v_cndmask_b32_e64 v34, 0, v34, s[78:79]
	v_add_u32_e32 v87, 160, v84
	v_cmp_gt_u32_e64 s[78:79], s98, v87
	v_cndmask_b32_e64 v35, 0, v35, s[50:51]
	v_add_u32_e32 v88, 176, v84
	v_cmp_gt_u32_e64 s[50:51], s98, v88
	v_cndmask_b32_e64 v36, 0, v36, s[30:31]
	v_add_u32_e32 v85, 256, v84
	v_cmp_gt_u32_e64 s[30:31], s98, v85
	v_cndmask_b32_e64 v37, 0, v37, s[36:37]
	v_add_u32_e32 v86, 272, v84
	v_cmp_gt_u32_e64 s[36:37], s98, v86
	v_cndmask_b32_e64 v38, 0, v38, s[78:79]
	v_add_u32_e32 v87, 288, v84
	v_cmp_gt_u32_e64 s[78:79], s98, v87
	v_cndmask_b32_e64 v39, 0, v39, s[50:51]
	v_add_u32_e32 v88, 304, v84
	v_cmp_gt_u32_e64 s[50:51], s98, v88
	v_cndmask_b32_e64 v40, 0, v40, s[30:31]
	v_add_u32_e32 v85, 384, v84
	v_cmp_gt_u32_e64 s[30:31], s98, v85
	v_cndmask_b32_e64 v41, 0, v41, s[36:37]
	v_add_u32_e32 v86, 400, v84
	v_cmp_gt_u32_e64 s[36:37], s98, v86
	v_cndmask_b32_e64 v42, 0, v42, s[78:79]
	v_add_u32_e32 v87, 416, v84
	v_cmp_gt_u32_e64 s[78:79], s98, v87
	v_cndmask_b32_e64 v43, 0, v43, s[50:51]
	v_add_u32_e32 v88, 432, v84
	v_cmp_gt_u32_e64 s[50:51], s98, v88
	v_nop
	v_cndmask_b32_e64 v44, 0, v44, s[30:31]
	v_cndmask_b32_e64 v45, 0, v45, s[36:37]
	v_cndmask_b32_e64 v46, 0, v46, s[78:79]
	v_cndmask_b32_e64 v47, 0, v47, s[50:51]
	v_cvt_pk_bf16_f32 v64, v32, v33
	v_cvt_pk_bf16_f32 v65, v34, v35
	v_cvt_pk_bf16_f32 v66, v36, v37
	v_cvt_pk_bf16_f32 v67, v38, v39
	v_cvt_pk_bf16_f32 v68, v40, v41
	v_cvt_pk_bf16_f32 v69, v42, v43
	v_cvt_pk_bf16_f32 v70, v44, v45
	v_cvt_pk_bf16_f32 v71, v46, v47
	v_pk_add_f32 v[232:233], v[232:233], v[32:33]
	v_pk_add_f32 v[232:233], v[232:233], v[34:35]
	v_pk_add_f32 v[232:233], v[232:233], v[36:37]
	v_pk_add_f32 v[232:233], v[232:233], v[38:39]
	v_pk_add_f32 v[232:233], v[232:233], v[40:41]
	v_pk_add_f32 v[232:233], v[232:233], v[42:43]
	v_pk_add_f32 v[232:233], v[232:233], v[44:45]
	v_pk_add_f32 v[232:233], v[232:233], v[46:47]
	s_waitcnt lgkmcnt(12)
	v_mfma_f32_32x32x16_bf16 v[0:15], v[64:67], v[72:75], v[0:15]
	v_mfma_f32_32x32x16_bf16 v[16:31], v[64:67], v[76:79], v[16:31]
	v_mfma_f32_32x32x16_bf16 v[0:15], v[68:71], v[220:223], v[0:15]
	v_mfma_f32_32x32x16_bf16 v[16:31], v[68:71], v[224:227], v[16:31]
	s_add_i32 s90, s76, 1024
	v_add_u32_e32 v80, s90, v243
	v_add_u32_e32 v83, s90, v244
	v_add_u32_e32 v99, s90, v245
	v_add_u32_e32 v253, s90, v246
	v_add_u32_e32 v254, s90, v148
	v_add_u32_e32 v255, s90, v151
	v_med3_i32 v80, v80, 0, s99
	v_med3_i32 v83, v83, 0, s99
	v_med3_i32 v99, v99, 0, s99
	v_med3_i32 v253, v253, 0, s99
	v_med3_i32 v254, v254, 0, s99
	v_med3_i32 v255, v255, 0, s99
	v_mad_u32_u24 v80, v80, s100, v252
	v_mad_u32_u24 v83, v83, s100, v252
	v_mad_u32_u24 v99, v99, s100, v252
	v_mad_u32_u24 v253, v253, s100, v252
	v_mad_u32_u24 v254, v254, s100, v153
	v_mad_u32_u24 v255, v255, s100, v153
	global_load_dwordx4 v[188:191], v80, s[82:83]
	global_load_dwordx4 v[192:195], v83, s[82:83]
	global_load_dwordx4 v[196:199], v99, s[82:83]
	global_load_dwordx4 v[200:203], v253, s[82:83]
	global_load_dwordx4 v[204:207], v254, s[82:83] offset:768
	global_load_dwordx4 v[208:211], v255, s[82:83] offset:768
	global_load_dwordx4 v[212:215], v254, s[82:83] offset:832
	global_load_dwordx4 v[216:219], v255, s[82:83] offset:832
	ds_read2_b32 v[32:33], v115 offset0:64 offset1:65
	ds_read2_b32 v[34:35], v115 offset0:66 offset1:67
	ds_read2_b32 v[36:37], v115 offset0:72 offset1:73
	ds_read2_b32 v[38:39], v115 offset0:74 offset1:75
	ds_read2_b32 v[40:41], v115 offset0:80 offset1:81
	ds_read2_b32 v[42:43], v115 offset0:82 offset1:83
	ds_read2_b32 v[44:45], v115 offset0:88 offset1:89
	ds_read2_b32 v[46:47], v115 offset0:90 offset1:91
	s_waitcnt lgkmcnt(0)
	v_mfma_f32_32x32x16_bf16 v[32:47], v[116:119], v[48:51], v[32:47]
	ds_read_b64_tr_b16 v[72:73], v231
	ds_read_b64_tr_b16 v[74:75], v231 offset:512
	ds_read_b64_tr_b16 v[76:77], v231 offset:2048
	ds_read_b64_tr_b16 v[78:79], v231 offset:2560
	ds_read_b64_tr_b16 v[220:221], v231 offset:1024
	ds_read_b64_tr_b16 v[222:223], v231 offset:1536
	ds_read_b64_tr_b16 v[224:225], v231 offset:3072
	ds_read_b64_tr_b16 v[226:227], v231 offset:3584
	s_waitcnt vmcnt(8)
	ds_write_b128 v247, v[156:159]
	ds_write_b128 v247, v[160:163] offset:1024
	ds_write_b128 v247, v[164:167] offset:2048
	ds_write_b128 v247, v[168:171] offset:3072
	ds_read_b128 v[156:159], v248
	ds_read_b128 v[160:163], v249
	ds_read_b128 v[164:167], v250
	ds_read_b128 v[168:171], v251
	ds_write_b128 v112, v[172:175]
	ds_write_b128 v112, v[176:179] offset:1024
	ds_write_b128 v112, v[180:183] offset:2048
	ds_write_b128 v112, v[184:187] offset:3072
	v_mfma_f32_32x32x16_bf16 v[32:47], v[120:123], v[52:55], v[32:47]
	v_mfma_f32_32x32x16_bf16 v[32:47], v[124:127], v[56:59], v[32:47]
	v_mfma_f32_32x32x16_bf16 v[32:47], v[128:131], v[60:63], v[32:47]
	s_nop 11
	v_exp_f32_e32 v32, v32
	v_exp_f32_e32 v33, v33
	v_exp_f32_e32 v34, v34
	v_exp_f32_e32 v35, v35
	v_exp_f32_e32 v36, v36
	v_exp_f32_e32 v37, v37
	v_exp_f32_e32 v38, v38
	v_exp_f32_e32 v39, v39
	v_exp_f32_e32 v40, v40
	v_exp_f32_e32 v41, v41
	v_exp_f32_e32 v42, v42
	v_exp_f32_e32 v43, v43
	v_exp_f32_e32 v44, v44
	v_exp_f32_e32 v45, v45
	v_exp_f32_e32 v46, v46
	v_exp_f32_e32 v47, v47
	s_add_i32 s90, s76, 0
	v_lshlrev_b32_e32 v84, 4, v107
	v_add_u32_e32 v84, s90, v84
	v_add_u32_e32 v85, 0, v84
	v_add_u32_e32 v86, 16, v84
	v_add_u32_e32 v87, 32, v84
	v_add_u32_e32 v88, 48, v84
	v_cmp_gt_u32_e64 s[30:31], s98, v85
	v_cmp_gt_u32_e64 s[36:37], s98, v86
	v_cmp_gt_u32_e64 s[78:79], s98, v87
	v_cmp_gt_u32_e64 s[50:51], s98, v88
	v_cndmask_b32_e64 v32, 0, v32, s[30:31]
	v_add_u32_e32 v85, 128, v84
	v_cmp_gt_u32_e64 s[30:31], s98, v85
	v_cndmask_b32_e64 v33, 0, v33, s[36:37]
	v_add_u32_e32 v86, 144, v84
	v_cmp_gt_u32_e64 s[36:37], s98, v86
	v_cndmask_b32_e64 v34, 0, v34, s[78:79]
	v_add_u32_e32 v87, 160, v84
	v_cmp_gt_u32_e64 s[78:79], s98, v87
	v_cndmask_b32_e64 v35, 0, v35, s[50:51]
	v_add_u32_e32 v88, 176, v84
	v_cmp_gt_u32_e64 s[50:51], s98, v88
	v_cndmask_b32_e64 v36, 0, v36, s[30:31]
	v_add_u32_e32 v85, 256, v84
	v_cmp_gt_u32_e64 s[30:31], s98, v85
	v_cndmask_b32_e64 v37, 0, v37, s[36:37]
	v_add_u32_e32 v86, 272, v84
	v_cmp_gt_u32_e64 s[36:37], s98, v86
	v_cndmask_b32_e64 v38, 0, v38, s[78:79]
	v_add_u32_e32 v87, 288, v84
	v_cmp_gt_u32_e64 s[78:79], s98, v87
	v_cndmask_b32_e64 v39, 0, v39, s[50:51]
	v_add_u32_e32 v88, 304, v84
	v_cmp_gt_u32_e64 s[50:51], s98, v88
	v_cndmask_b32_e64 v40, 0, v40, s[30:31]
	v_add_u32_e32 v85, 384, v84
	v_cmp_gt_u32_e64 s[30:31], s98, v85
	v_cndmask_b32_e64 v41, 0, v41, s[36:37]
	v_add_u32_e32 v86, 400, v84
	v_cmp_gt_u32_e64 s[36:37], s98, v86
	v_cndmask_b32_e64 v42, 0, v42, s[78:79]
	v_add_u32_e32 v87, 416, v84
	v_cmp_gt_u32_e64 s[78:79], s98, v87
	v_cndmask_b32_e64 v43, 0, v43, s[50:51]
	v_add_u32_e32 v88, 432, v84
	v_cmp_gt_u32_e64 s[50:51], s98, v88
	v_nop
	v_cndmask_b32_e64 v44, 0, v44, s[30:31]
	v_cndmask_b32_e64 v45, 0, v45, s[36:37]
	v_cndmask_b32_e64 v46, 0, v46, s[78:79]
	v_cndmask_b32_e64 v47, 0, v47, s[50:51]
	v_cvt_pk_bf16_f32 v64, v32, v33
	v_cvt_pk_bf16_f32 v65, v34, v35
	v_cvt_pk_bf16_f32 v66, v36, v37
	v_cvt_pk_bf16_f32 v67, v38, v39
	v_cvt_pk_bf16_f32 v68, v40, v41
	v_cvt_pk_bf16_f32 v69, v42, v43
	v_cvt_pk_bf16_f32 v70, v44, v45
	v_cvt_pk_bf16_f32 v71, v46, v47
	v_pk_add_f32 v[232:233], v[232:233], v[32:33]
	v_pk_add_f32 v[232:233], v[232:233], v[34:35]
	v_pk_add_f32 v[232:233], v[232:233], v[36:37]
	v_pk_add_f32 v[232:233], v[232:233], v[38:39]
	v_pk_add_f32 v[232:233], v[232:233], v[40:41]
	v_pk_add_f32 v[232:233], v[232:233], v[42:43]
	v_pk_add_f32 v[232:233], v[232:233], v[44:45]
	v_pk_add_f32 v[232:233], v[232:233], v[46:47]
	s_waitcnt lgkmcnt(12)
	v_mfma_f32_32x32x16_bf16 v[0:15], v[64:67], v[72:75], v[0:15]
	v_mfma_f32_32x32x16_bf16 v[16:31], v[64:67], v[76:79], v[16:31]
	v_mfma_f32_32x32x16_bf16 v[0:15], v[68:71], v[220:223], v[0:15]
	v_mfma_f32_32x32x16_bf16 v[16:31], v[68:71], v[224:227], v[16:31]
	ds_read2_b32 v[32:33], v115 offset0:96 offset1:97
	ds_read2_b32 v[34:35], v115 offset0:98 offset1:99
	ds_read2_b32 v[36:37], v115 offset0:104 offset1:105
	ds_read2_b32 v[38:39], v115 offset0:106 offset1:107
	ds_read2_b32 v[40:41], v115 offset0:112 offset1:113
	ds_read2_b32 v[42:43], v115 offset0:114 offset1:115
	ds_read2_b32 v[44:45], v115 offset0:120 offset1:121
	ds_read2_b32 v[46:47], v115 offset0:122 offset1:123
	s_waitcnt lgkmcnt(0)
	v_mfma_f32_32x32x16_bf16 v[32:47], v[156:159], v[48:51], v[32:47]
	ds_read_b64_tr_b16 v[72:73], v231
	ds_read_b64_tr_b16 v[74:75], v231 offset:512
	ds_read_b64_tr_b16 v[76:77], v231 offset:2048
	ds_read_b64_tr_b16 v[78:79], v231 offset:2560
	ds_read_b64_tr_b16 v[220:221], v231 offset:1024
	ds_read_b64_tr_b16 v[222:223], v231 offset:1536
	ds_read_b64_tr_b16 v[224:225], v231 offset:3072
	ds_read_b64_tr_b16 v[226:227], v231 offset:3584
	s_waitcnt vmcnt(0)
	ds_write_b128 v247, v[188:191]
	ds_write_b128 v247, v[192:195] offset:1024
	ds_write_b128 v247, v[196:199] offset:2048
	ds_write_b128 v247, v[200:203] offset:3072
	ds_read_b128 v[188:191], v248
	ds_read_b128 v[192:195], v249
	ds_read_b128 v[196:199], v250
	ds_read_b128 v[200:203], v251
	ds_write_b128 v112, v[204:207]
	ds_write_b128 v112, v[208:211] offset:1024
	ds_write_b128 v112, v[212:215] offset:2048
	ds_write_b128 v112, v[216:219] offset:3072
	v_mfma_f32_32x32x16_bf16 v[32:47], v[160:163], v[52:55], v[32:47]
	v_mfma_f32_32x32x16_bf16 v[32:47], v[164:167], v[56:59], v[32:47]
	v_mfma_f32_32x32x16_bf16 v[32:47], v[168:171], v[60:63], v[32:47]
	s_nop 11
	v_exp_f32_e32 v32, v32
	v_exp_f32_e32 v33, v33
	v_exp_f32_e32 v34, v34
	v_exp_f32_e32 v35, v35
	v_exp_f32_e32 v36, v36
	v_exp_f32_e32 v37, v37
	v_exp_f32_e32 v38, v38
	v_exp_f32_e32 v39, v39
	v_exp_f32_e32 v40, v40
	v_exp_f32_e32 v41, v41
	v_exp_f32_e32 v42, v42
	v_exp_f32_e32 v43, v43
	v_exp_f32_e32 v44, v44
	v_exp_f32_e32 v45, v45
	v_exp_f32_e32 v46, v46
	v_exp_f32_e32 v47, v47
	s_add_i32 s90, s76, 512
	v_lshlrev_b32_e32 v84, 4, v107
	v_add_u32_e32 v84, s90, v84
	v_add_u32_e32 v85, 0, v84
	v_add_u32_e32 v86, 16, v84
	v_add_u32_e32 v87, 32, v84
	v_add_u32_e32 v88, 48, v84
	v_cmp_gt_u32_e64 s[30:31], s98, v85
	v_cmp_gt_u32_e64 s[36:37], s98, v86
	v_cmp_gt_u32_e64 s[78:79], s98, v87
	v_cmp_gt_u32_e64 s[50:51], s98, v88
	v_cndmask_b32_e64 v32, 0, v32, s[30:31]
	v_add_u32_e32 v85, 128, v84
	v_cmp_gt_u32_e64 s[30:31], s98, v85
	v_cndmask_b32_e64 v33, 0, v33, s[36:37]
	v_add_u32_e32 v86, 144, v84
	v_cmp_gt_u32_e64 s[36:37], s98, v86
	v_cndmask_b32_e64 v34, 0, v34, s[78:79]
	v_add_u32_e32 v87, 160, v84
	v_cmp_gt_u32_e64 s[78:79], s98, v87
	v_cndmask_b32_e64 v35, 0, v35, s[50:51]
	v_add_u32_e32 v88, 176, v84
	v_cmp_gt_u32_e64 s[50:51], s98, v88
	v_cndmask_b32_e64 v36, 0, v36, s[30:31]
	v_add_u32_e32 v85, 256, v84
	v_cmp_gt_u32_e64 s[30:31], s98, v85
	v_cndmask_b32_e64 v37, 0, v37, s[36:37]
	v_add_u32_e32 v86, 272, v84
	v_cmp_gt_u32_e64 s[36:37], s98, v86
	v_cndmask_b32_e64 v38, 0, v38, s[78:79]
	v_add_u32_e32 v87, 288, v84
	v_cmp_gt_u32_e64 s[78:79], s98, v87
	v_cndmask_b32_e64 v39, 0, v39, s[50:51]
	v_add_u32_e32 v88, 304, v84
	v_cmp_gt_u32_e64 s[50:51], s98, v88
	v_cndmask_b32_e64 v40, 0, v40, s[30:31]
	v_add_u32_e32 v85, 384, v84
	v_cmp_gt_u32_e64 s[30:31], s98, v85
	v_cndmask_b32_e64 v41, 0, v41, s[36:37]
	v_add_u32_e32 v86, 400, v84
	v_cmp_gt_u32_e64 s[36:37], s98, v86
	v_cndmask_b32_e64 v42, 0, v42, s[78:79]
	v_add_u32_e32 v87, 416, v84
	v_cmp_gt_u32_e64 s[78:79], s98, v87
	v_cndmask_b32_e64 v43, 0, v43, s[50:51]
	v_add_u32_e32 v88, 432, v84
	v_cmp_gt_u32_e64 s[50:51], s98, v88
	v_nop
	v_cndmask_b32_e64 v44, 0, v44, s[30:31]
	v_cndmask_b32_e64 v45, 0, v45, s[36:37]
	v_cndmask_b32_e64 v46, 0, v46, s[78:79]
	v_cndmask_b32_e64 v47, 0, v47, s[50:51]
	v_cvt_pk_bf16_f32 v64, v32, v33
	v_cvt_pk_bf16_f32 v65, v34, v35
	v_cvt_pk_bf16_f32 v66, v36, v37
	v_cvt_pk_bf16_f32 v67, v38, v39
	v_cvt_pk_bf16_f32 v68, v40, v41
	v_cvt_pk_bf16_f32 v69, v42, v43
	v_cvt_pk_bf16_f32 v70, v44, v45
	v_cvt_pk_bf16_f32 v71, v46, v47
	v_pk_add_f32 v[232:233], v[232:233], v[32:33]
	v_pk_add_f32 v[232:233], v[232:233], v[34:35]
	v_pk_add_f32 v[232:233], v[232:233], v[36:37]
	v_pk_add_f32 v[232:233], v[232:233], v[38:39]
	v_pk_add_f32 v[232:233], v[232:233], v[40:41]
	v_pk_add_f32 v[232:233], v[232:233], v[42:43]
	v_pk_add_f32 v[232:233], v[232:233], v[44:45]
	v_pk_add_f32 v[232:233], v[232:233], v[46:47]
	s_waitcnt lgkmcnt(12)
	v_mfma_f32_32x32x16_bf16 v[0:15], v[64:67], v[72:75], v[0:15]
	v_mfma_f32_32x32x16_bf16 v[16:31], v[64:67], v[76:79], v[16:31]
	v_mfma_f32_32x32x16_bf16 v[0:15], v[68:71], v[220:223], v[0:15]
	v_mfma_f32_32x32x16_bf16 v[16:31], v[68:71], v[224:227], v[16:31]
	ds_read2_b32 v[32:33], v115 offset0:128 offset1:129
	ds_read2_b32 v[34:35], v115 offset0:130 offset1:131
	ds_read2_b32 v[36:37], v115 offset0:136 offset1:137
	ds_read2_b32 v[38:39], v115 offset0:138 offset1:139
	ds_read2_b32 v[40:41], v115 offset0:144 offset1:145
	ds_read2_b32 v[42:43], v115 offset0:146 offset1:147
	ds_read2_b32 v[44:45], v115 offset0:152 offset1:153
	ds_read2_b32 v[46:47], v115 offset0:154 offset1:155
	s_waitcnt lgkmcnt(0)
; __device__ __forceinline__ int crow(int r, int hi) { return (r & 3) + 8 * (r >> 2) + 4 * hi; }
; __device__ __forceinline__ void dil_unit(LAS unsigned char* lds, bf16_t* proj, int seq, int hd, int T0, int rho) {
;     ...
;     l += __shfl_xor(l, 32);
; #pragma unroll
;     for (int rr = 0; rr < 16; ++rr) {
;         const int j = crow(rr, hi);
;         const float il = __builtin_amdgcn_rcpf(__shfl(l, j));
	v_mfma_f32_32x32x16_bf16 v[32:47], v[188:191], v[48:51], v[32:47]
	ds_read_b64_tr_b16 v[72:73], v231
	ds_read_b64_tr_b16 v[74:75], v231 offset:512
	ds_read_b64_tr_b16 v[76:77], v231 offset:2048
	ds_read_b64_tr_b16 v[78:79], v231 offset:2560
	ds_read_b64_tr_b16 v[220:221], v231 offset:1024
	ds_read_b64_tr_b16 v[222:223], v231 offset:1536
	ds_read_b64_tr_b16 v[224:225], v231 offset:3072
	ds_read_b64_tr_b16 v[226:227], v231 offset:3584
	v_mfma_f32_32x32x16_bf16 v[32:47], v[192:195], v[52:55], v[32:47]
	v_mfma_f32_32x32x16_bf16 v[32:47], v[196:199], v[56:59], v[32:47]
	v_mfma_f32_32x32x16_bf16 v[32:47], v[200:203], v[60:63], v[32:47]
	s_nop 11
	v_exp_f32_e32 v32, v32
	v_exp_f32_e32 v33, v33
	v_exp_f32_e32 v34, v34
	v_exp_f32_e32 v35, v35
	v_exp_f32_e32 v36, v36
	v_exp_f32_e32 v37, v37
	v_exp_f32_e32 v38, v38
	v_exp_f32_e32 v39, v39
	v_exp_f32_e32 v40, v40
	v_exp_f32_e32 v41, v41
	v_exp_f32_e32 v42, v42
	v_exp_f32_e32 v43, v43
	v_exp_f32_e32 v44, v44
	v_exp_f32_e32 v45, v45
	v_exp_f32_e32 v46, v46
	v_exp_f32_e32 v47, v47
	s_add_i32 s90, s76, 1024
	v_lshlrev_b32_e32 v84, 4, v107
	v_add_u32_e32 v84, s90, v84
	v_add_u32_e32 v85, 0, v84
	v_add_u32_e32 v86, 16, v84
	v_add_u32_e32 v87, 32, v84
	v_add_u32_e32 v88, 48, v84
	v_cmp_gt_u32_e64 s[30:31], s98, v85
	v_cmp_gt_u32_e64 s[36:37], s98, v86
	v_cmp_gt_u32_e64 s[78:79], s98, v87
	v_cmp_gt_u32_e64 s[50:51], s98, v88
	v_cndmask_b32_e64 v32, 0, v32, s[30:31]
	v_add_u32_e32 v85, 128, v84
	v_cmp_gt_u32_e64 s[30:31], s98, v85
	v_cndmask_b32_e64 v33, 0, v33, s[36:37]
	v_add_u32_e32 v86, 144, v84
	v_cmp_gt_u32_e64 s[36:37], s98, v86
	v_cndmask_b32_e64 v34, 0, v34, s[78:79]
	v_add_u32_e32 v87, 160, v84
	v_cmp_gt_u32_e64 s[78:79], s98, v87
	v_cndmask_b32_e64 v35, 0, v35, s[50:51]
	v_add_u32_e32 v88, 176, v84
	v_cmp_gt_u32_e64 s[50:51], s98, v88
	v_cndmask_b32_e64 v36, 0, v36, s[30:31]
	v_add_u32_e32 v85, 256, v84
	v_cmp_gt_u32_e64 s[30:31], s98, v85
	v_cndmask_b32_e64 v37, 0, v37, s[36:37]
	v_add_u32_e32 v86, 272, v84
	v_cmp_gt_u32_e64 s[36:37], s98, v86
	v_cndmask_b32_e64 v38, 0, v38, s[78:79]
	v_add_u32_e32 v87, 288, v84
	v_cmp_gt_u32_e64 s[78:79], s98, v87
	v_cndmask_b32_e64 v39, 0, v39, s[50:51]
	v_add_u32_e32 v88, 304, v84
	v_cmp_gt_u32_e64 s[50:51], s98, v88
	v_cndmask_b32_e64 v40, 0, v40, s[30:31]
	v_add_u32_e32 v85, 384, v84
	v_cmp_gt_u32_e64 s[30:31], s98, v85
	v_cndmask_b32_e64 v41, 0, v41, s[36:37]
	v_add_u32_e32 v86, 400, v84
	v_cmp_gt_u32_e64 s[36:37], s98, v86
	v_cndmask_b32_e64 v42, 0, v42, s[78:79]
	v_add_u32_e32 v87, 416, v84
	v_cmp_gt_u32_e64 s[78:79], s98, v87
	v_cndmask_b32_e64 v43, 0, v43, s[50:51]
	v_add_u32_e32 v88, 432, v84
	v_cmp_gt_u32_e64 s[50:51], s98, v88
	v_nop
	v_cndmask_b32_e64 v44, 0, v44, s[30:31]
	v_cndmask_b32_e64 v45, 0, v45, s[36:37]
	v_cndmask_b32_e64 v46, 0, v46, s[78:79]
	v_cndmask_b32_e64 v47, 0, v47, s[50:51]
	v_cvt_pk_bf16_f32 v64, v32, v33
	v_cvt_pk_bf16_f32 v65, v34, v35
	v_cvt_pk_bf16_f32 v66, v36, v37
	v_cvt_pk_bf16_f32 v67, v38, v39
	v_cvt_pk_bf16_f32 v68, v40, v41
	v_cvt_pk_bf16_f32 v69, v42, v43
	v_cvt_pk_bf16_f32 v70, v44, v45
	v_cvt_pk_bf16_f32 v71, v46, v47
	v_pk_add_f32 v[232:233], v[232:233], v[32:33]
	v_pk_add_f32 v[232:233], v[232:233], v[34:35]
	v_pk_add_f32 v[232:233], v[232:233], v[36:37]
	v_pk_add_f32 v[232:233], v[232:233], v[38:39]
	v_pk_add_f32 v[232:233], v[232:233], v[40:41]
	v_pk_add_f32 v[232:233], v[232:233], v[42:43]
	v_pk_add_f32 v[232:233], v[232:233], v[44:45]
	v_pk_add_f32 v[232:233], v[232:233], v[46:47]
	s_waitcnt lgkmcnt(0)
	v_mfma_f32_32x32x16_bf16 v[0:15], v[64:67], v[72:75], v[0:15]
	v_mfma_f32_32x32x16_bf16 v[16:31], v[64:67], v[76:79], v[16:31]
	v_mfma_f32_32x32x16_bf16 v[0:15], v[68:71], v[220:223], v[0:15]
	v_mfma_f32_32x32x16_bf16 v[16:31], v[68:71], v[224:227], v[16:31]
	v_add_f32_e32 v113, v232, v233
	v_or_b32_e32 v114, 1, v107
	v_or_b32_e32 v97, 2, v107
	v_or_b32_e32 v96, 3, v107
	v_or_b32_e32 v95, 8, v107
	v_or_b32_e32 v94, 9, v107
	v_or_b32_e32 v93, 10, v107
	v_or_b32_e32 v92, 11, v107
	v_or_b32_e32 v91, 16, v107
	v_or_b32_e32 v90, 17, v107
	v_or_b32_e32 v89, 18, v107
	v_or_b32_e32 v88, 19, v107
	v_or_b32_e32 v87, 24, v107
	v_or_b32_e32 v86, 25, v107
	v_or_b32_e32 v85, 26, v107
	v_or_b32_e32 v84, 27, v107
	s_nop 11
	s_branch .LBB0_553

; __device__ __forceinline__ void attn_setup(const float* par, int l, LAS unsigned char* lds) {
;     ...
;     for (int i = tid; i < 6 * TDIL_STRIDE; i += 512) { const int hd = i / TDIL_STRIDE, j = i % TDIL_STRIDE; const int b = j < 1152 ? 0 : (j < 1560 ? 1 : 2), jj = j - (b == 0 ? 0 : (b == 1 ? 1152 : 1560));
;         const int r = (b == 0) ? 1 : (b == 1 ? 4 : 16), f = 16 / r, mm = jj - (64 + 31 * f);
;         tl[i] = (mm >= -64 && mm <= 64) ? (rb[rel_bucket(r * mm) * 10 + 4 + hd] - misc[4 + hd]) * LOG2E : -1e30f; }
; __device__ __forceinline__ void attn_phase(unsigned char* ws, int l, LAS unsigned char* lds, int G) {
;     ...
;     __syncthreads();
;     for (int bu = vb; bu < 1152; bu += G) {
;         const int sh = bu >> 6, rem = bu & 63, T0 = (rem >> 1) * 512, rho = (rem & 1) * 8 + wid;
;         dil_unit(lds, proj, sh / 6, sh % 6, T0, rho);
.Lpt1_done:
	v_cmp_gt_u32_e32 vcc, 0x198, v154
	s_and_saveexec_b64 s[90:91], vcc
	v_lshlrev_b32_e32 v200, 2, v154
	v_add_u32_e32 v200, 93696, v200
	v_lshrrev_b32_e32 v201, 2, v154
	v_add_u32_e32 v201, v201, v154
	v_lshlrev_b32_e32 v201, 2, v201
	v_add_u32_e32 v201, 0x10000, v201
	ds_read_b32 v202, v200 offset:0
	ds_read_b32 v203, v200 offset:7168
	ds_read_b32 v204, v200 offset:14336
	ds_read_b32 v205, v200 offset:21504
	ds_read_b32 v206, v200 offset:28672
	ds_read_b32 v207, v200 offset:35840
	s_waitcnt lgkmcnt(0)
	ds_write_b32 v201, v202 offset:0
	ds_write_b32 v201, v203 offset:1920
	ds_write_b32 v201, v204 offset:3840
	ds_write_b32 v201, v205 offset:5760
	ds_write_b32 v201, v206 offset:7680
	ds_write_b32 v201, v207 offset:9600
	s_mov_b64 exec, s[90:91]
	s_waitcnt lgkmcnt(0)
	s_barrier
	s_lshr_b32 s61, s22, 6
	s_movk_i32 s62, 0x1800
	v_mov_b32_e32 v81, 0
	s_mov_b64 s[46:47], 0x1200
	s_movk_i32 s63, 0x1000
	s_mov_b64 s[48:49], 0x1500
	s_movk_i32 s64, 0x480
	s_movk_i32 s65, 0xbc
	s_movk_i32 s66, 0x4000
	v_mbcnt_hi_u32_b32 v102, -1, v155
	s_branch .LBB0_1266

; #define LAS __attribute__((address_space(3)))
; #define GAS __attribute__((address_space(1)))
; __device__ __forceinline__ void dil_unit(LAS unsigned char* lds, bf16_t* proj, int seq, int hd, int T0, int rho) {
;     int tid_ = threadIdx.x; asm volatile("" : "+v"(tid_));
;     const int tid = tid_, lane = tid & 63, r32 = lane & 31, hi = lane >> 5, wid = __builtin_amdgcn_readfirstlane(tid >> 6);
;     bf16_t* base = proj + (size_t)seq * SEQ * NIN;
;     LAS unsigned char* wbuf = lds + wid * 4096;
;     const LAS unsigned char* vp = wbuf + ((lane >> 4) & 1) * 32 + (lane & 3) * 8 + (4 * hi + ((lane & 15) >> 2)) * 64;
;     const int P0 = T0 + rho;
;     bf16x8 qr[4];
; #pragma unroll
;     for (int ks = 0; ks < 4; ++ks) qr[ks] = *(const GAS bf16x8*)(base + (size_t)(P0 + 16 * r32) * NIN + PC_LQ + hd * 64 + 16 * ks + 8 * hi);
;     f32x16 o0 = {}, o1 = {}; float l = 0.f;
;     const bool bound = (T0 < 1024) || (T0 >= 15360);
.LBB0_1266:
	s_lshr_b32 s82, s60, 8
	s_mul_i32 s82, s82, 13
	s_add_i32 s82, s82, s60
	s_ashr_i32 s4, s60, 6
	s_mul_hi_i32 s9, s4, 0x2aaaaaab
	s_lshl_b32 s5, s82, 8
	s_lshr_b32 s10, s9, 31
	s_and_b32 s8, s5, 0x3e00
	s_lshl_b32 s5, s82, 3
	s_add_i32 s9, s9, s10
	s_and_b32 s5, s5, 8
	s_mul_i32 s10, s9, 6
	s_add_i32 s5, s5, s61
	s_sub_i32 s10, s4, s10
	s_mul_hi_i32 s4, s9, 0x6000000
	s_mul_i32 s9, s9, 0x6000000
	v_mov_b32_e32 v2, v154
	s_add_u32 s52, s44, s9
	s_addc_u32 s53, s45, s4
	v_and_b32_e32 v105, 31, v2
	s_add_i32 s67, s5, s8
	v_lshl_add_u32 v3, v105, 4, s67
	v_mov_b64_e32 v[0:1], s[52:53]
	s_lshl_b32 s54, s10, 6
	v_bfe_u32 v106, v2, 5, 1
	v_mad_u64_u32 v[0:1], s[4:5], v3, s62, v[0:1]
	s_ashr_i32 s55, s54, 31
	v_lshl_add_u64 v[0:1], s[54:55], 1, v[0:1]
	v_lshlrev_b32_e32 v80, 4, v106
	v_lshl_add_u64 v[0:1], v[0:1], 0, v[80:81]
	global_load_dwordx4 v[48:51], v[0:1], off offset:1280
	global_load_dwordx4 v[52:55], v[0:1], off offset:1312
	global_load_dwordx4 v[56:59], v[0:1], off offset:1344
	global_load_dwordx4 v[60:63], v[0:1], off offset:1376
	v_readfirstlane_b32 s4, v2
	s_lshl_b32 s4, s4, 6
	s_and_b32 s4, s4, 0xfffff000
	v_lshlrev_b32_e32 v0, 1, v2
	v_lshlrev_b32_e32 v104, 3, v2
	v_lshlrev_b32_e32 v107, 2, v106
	v_lshrrev_b32_e32 v1, 2, v2
	v_and_b32_e32 v103, 63, v2
	v_and_b32_e32 v0, 32, v0
	v_and_b32_e32 v98, 24, v104
	v_and_or_b32 v1, v1, 3, v107
	s_add_i32 s69, s4, 0
	v_lshlrev_b32_e32 v108, 6, v1
	v_lshlrev_b32_e32 v1, 3, v106
	v_add3_u32 v109, s69, v0, v98
	s_addk_i32 s8, 0xc400
	v_lshrrev_b32_e32 v110, 2, v103
	v_lshlrev_b32_e32 v0, 4, v103
	s_mov_b64 s[4:5], -1
	s_cmp_gt_u32 s8, 0xffffc7ff
	v_lshlrev_b32_e32 v100, 1, v98
	s_mul_i32 s8, s10, 0x1c00
	v_lshlrev_b32_e32 v82, 1, v1
	v_or_b32_e32 v111, 16, v110
	v_add_u32_e32 v112, s69, v0
	s_cbranch_scc0 .LBB0_1270
	s_movk_i32 s100, 0x1800
	s_add_i32 s101, s8, 0x15c00
	s_lshl_b32 s90, s54, 1
	s_add_u32 s82, s52, s90
	s_addc_u32 s83, s53, 0
	s_add_u32 s82, s82, 0x1200
	s_addc_u32 s83, s83, 0
	s_sub_i32 s90, s67, 64
	s_mul_i32 s90, s90, 0x1800
	s_add_u32 s84, s82, s90
	s_addc_u32 s85, s83, 0
	s_sub_i32 s90, s67, 256
	s_mul_i32 s90, s90, 0x1800
	s_add_u32 s86, s82, s90
	s_addc_u32 s87, s83, 0
	s_sub_i32 s90, s67, 1024
	s_mul_i32 s90, s90, 0x1800
	s_add_u32 s88, s82, s90
	s_addc_u32 s89, s83, 0
	v_lshlrev_b32_e32 v153, 1, v98
	v_mad_u32_u24 v80, v105, s100, v82
	v_mad_u32_u24 v100, v110, s100, v153
	v_add_u32_e32 v149, 0x18000, v100
	v_lshlrev_b32_e32 v83, 2, v105
	v_mad_u32_u24 v83, v83, s100, v82
	v_lshlrev_b32_e32 v101, 2, v110
	v_mad_u32_u24 v101, v101, s100, v153
	v_add_u32_e32 v150, 0x60000, v101
	v_lshlrev_b32_e32 v99, 4, v105
	v_mad_u32_u24 v99, v99, s100, v82
	v_lshlrev_b32_e32 v148, 4, v110
	v_mad_u32_u24 v148, v148, s100, v153
	v_add_u32_e32 v151, 0x180000, v148
	v_lshrrev_b32_e32 v249, 3, v103
	v_and_b32_e32 v250, 7, v103
	v_lshlrev_b32_e32 v250, 4, v250
	v_add_u32_e32 v235, 0, v249
	v_mad_u32_u24 v235, v235, s100, v250
	v_add_u32_e32 v236, 8, v249
	v_mad_u32_u24 v236, v236, s100, v250
	v_add_u32_e32 v237, 16, v249
	v_mad_u32_u24 v237, v237, s100, v250
	v_add_u32_e32 v238, 24, v249
	v_mad_u32_u24 v238, v238, s100, v250
	v_add_u32_e32 v239, 0, v249
	v_lshlrev_b32_e32 v239, 2, v239
	v_mad_u32_u24 v239, v239, s100, v250
	v_add_u32_e32 v240, 8, v249
	v_lshlrev_b32_e32 v240, 2, v240
	v_mad_u32_u24 v240, v240, s100, v250
	v_add_u32_e32 v241, 16, v249
	v_lshlrev_b32_e32 v241, 2, v241
	v_mad_u32_u24 v241, v241, s100, v250
	v_add_u32_e32 v242, 24, v249
	v_lshlrev_b32_e32 v242, 2, v242
	v_mad_u32_u24 v242, v242, s100, v250
	v_add_u32_e32 v243, 0, v249
	v_lshlrev_b32_e32 v243, 4, v243
	v_mad_u32_u24 v243, v243, s100, v250
	v_add_u32_e32 v244, 8, v249
	v_lshlrev_b32_e32 v244, 4, v244
	v_mad_u32_u24 v244, v244, s100, v250
	v_add_u32_e32 v245, 16, v249
	v_lshlrev_b32_e32 v245, 4, v245
	v_mad_u32_u24 v245, v245, s100, v250
	v_add_u32_e32 v246, 24, v249
	v_lshlrev_b32_e32 v246, 4, v246
	v_mad_u32_u24 v246, v246, s100, v250
	v_and_b32_e32 v247, 7, v249
	v_lshlrev_b32_e32 v247, 4, v247
	v_xor_b32_e32 v247, v247, v112
	v_and_b32_e32 v153, 7, v105
	v_or_b32_e32 v248, 0, v106
	v_xor_b32_e32 v248, v248, v153
	v_lshlrev_b32_e32 v248, 4, v248
	v_lshl_add_u32 v248, v105, 7, v248
	v_add_u32_e32 v248, s69, v248
	v_or_b32_e32 v249, 2, v106
	v_xor_b32_e32 v249, v249, v153
	v_lshlrev_b32_e32 v249, 4, v249
	v_lshl_add_u32 v249, v105, 7, v249
	v_add_u32_e32 v249, s69, v249
	v_or_b32_e32 v250, 4, v106
	v_xor_b32_e32 v250, v250, v153
	v_lshlrev_b32_e32 v250, 4, v250
	v_lshl_add_u32 v250, v105, 7, v250
	v_add_u32_e32 v250, s69, v250
	v_or_b32_e32 v251, 6, v106
	v_xor_b32_e32 v251, v251, v153
	v_lshlrev_b32_e32 v251, 4, v251
	v_lshl_add_u32 v251, v105, 7, v251
	v_add_u32_e32 v251, s69, v251
	v_lshlrev_b32_e32 v153, 1, v98
	v_mul_u32_u24_e32 v228, 17, v105
	v_sub_u32_e32 v228, v107, v228
	s_mul_i32 s90, s54, 153
	s_lshr_b32 s90, s90, 1
	s_add_i32 s90, s90, 34876
	v_lshl_add_u32 v228, v228, 2, s90
	v_mul_u32_u24_e32 v229, 5, v105
	v_sub_u32_e32 v229, v107, v229
	v_add_u32_e32 v229, v229, v106
	s_mul_i32 s90, s54, 30
	s_add_i32 s90, s90, 66156
	v_lshl_add_u32 v229, v229, 2, s90
	v_sub_u32_e32 v230, v107, v105
	s_add_i32 s90, s101, 6364
	v_lshl_add_u32 v230, v230, 2, s90
	v_add_u32_e32 v231, v109, v108
	v_mov_b64_e32 v[232:233], 0
	v_mov_b64_e32 v[0:1], 0
	v_mov_b64_e32 v[2:3], 0
	v_mov_b64_e32 v[4:5], 0
	v_mov_b64_e32 v[6:7], 0
	v_mov_b64_e32 v[8:9], 0
	v_mov_b64_e32 v[10:11], 0
	v_mov_b64_e32 v[12:13], 0
	v_mov_b64_e32 v[14:15], 0
	v_mov_b64_e32 v[16:17], 0
	v_mov_b64_e32 v[18:19], 0
	v_mov_b64_e32 v[20:21], 0
	v_mov_b64_e32 v[22:23], 0
	v_mov_b64_e32 v[24:25], 0
	v_mov_b64_e32 v[26:27], 0
	v_mov_b64_e32 v[28:29], 0
	v_mov_b64_e32 v[30:31], 0
	global_load_dwordx4 v[116:119], v235, s[84:85]
	global_load_dwordx4 v[120:123], v236, s[84:85]
	global_load_dwordx4 v[124:127], v237, s[84:85]
	global_load_dwordx4 v[128:131], v238, s[84:85]
	global_load_dwordx4 v[132:135], v100, s[84:85] offset:768
	global_load_dwordx4 v[136:139], v149, s[84:85] offset:768
	global_load_dwordx4 v[140:143], v100, s[84:85] offset:832
	global_load_dwordx4 v[144:147], v149, s[84:85] offset:832
	s_add_u32 s84, s84, 0x30000
	s_addc_u32 s85, s85, 0
	global_load_dwordx4 v[156:159], v235, s[84:85]
	global_load_dwordx4 v[160:163], v236, s[84:85]
	global_load_dwordx4 v[164:167], v237, s[84:85]
	global_load_dwordx4 v[168:171], v238, s[84:85]
	global_load_dwordx4 v[172:175], v100, s[84:85] offset:768
	global_load_dwordx4 v[176:179], v149, s[84:85] offset:768
	global_load_dwordx4 v[180:183], v100, s[84:85] offset:832
	global_load_dwordx4 v[184:187], v149, s[84:85] offset:832
	s_add_u32 s84, s84, 0x30000
	s_addc_u32 s85, s85, 0
	global_load_dwordx4 v[188:191], v235, s[84:85]
	global_load_dwordx4 v[192:195], v236, s[84:85]
	global_load_dwordx4 v[196:199], v237, s[84:85]
	global_load_dwordx4 v[200:203], v238, s[84:85]
	global_load_dwordx4 v[204:207], v100, s[84:85] offset:768
	global_load_dwordx4 v[208:211], v149, s[84:85] offset:768
	global_load_dwordx4 v[212:215], v100, s[84:85] offset:832
	global_load_dwordx4 v[216:219], v149, s[84:85] offset:832
	s_add_u32 s84, s84, 0x30000
	s_addc_u32 s85, s85, 0
	s_waitcnt vmcnt(16)
	ds_write_b128 v247, v[116:119]
	ds_write_b128 v247, v[120:123] offset:1024
	ds_write_b128 v247, v[124:127] offset:2048
	ds_write_b128 v247, v[128:131] offset:3072
	ds_read_b128 v[116:119], v248
	ds_read_b128 v[120:123], v249
	ds_read_b128 v[124:127], v250
	ds_read_b128 v[128:131], v251
	ds_write_b128 v112, v[132:135]
	ds_write_b128 v112, v[136:139] offset:1024
	ds_write_b128 v112, v[140:143] offset:2048
	ds_write_b128 v112, v[144:147] offset:3072
	v_mov_b32_e32 v115, v228
	ds_read2_b32 v[32:33], v115 offset0:0 offset1:1
	ds_read2_b32 v[34:35], v115 offset0:2 offset1:3
	ds_read2_b32 v[36:37], v115 offset0:8 offset1:9
	ds_read2_b32 v[38:39], v115 offset0:10 offset1:11
	ds_read2_b32 v[40:41], v115 offset0:17 offset1:18
	ds_read2_b32 v[42:43], v115 offset0:19 offset1:20
	ds_read2_b32 v[44:45], v115 offset0:25 offset1:26
	ds_read2_b32 v[46:47], v115 offset0:27 offset1:28
	s_waitcnt lgkmcnt(0)
	v_mfma_f32_32x32x16_bf16 v[32:47], v[116:119], v[48:51], v[32:47]
	ds_read_b64_tr_b16 v[72:73], v231
	ds_read_b64_tr_b16 v[74:75], v231 offset:512
	ds_read_b64_tr_b16 v[76:77], v231 offset:2048
	ds_read_b64_tr_b16 v[78:79], v231 offset:2560
	ds_read_b64_tr_b16 v[220:221], v231 offset:1024
	ds_read_b64_tr_b16 v[222:223], v231 offset:1536
	ds_read_b64_tr_b16 v[224:225], v231 offset:3072
	ds_read_b64_tr_b16 v[226:227], v231 offset:3584
	s_waitcnt vmcnt(8)
	ds_write_b128 v247, v[156:159]
	ds_write_b128 v247, v[160:163] offset:1024
	ds_write_b128 v247, v[164:167] offset:2048
	ds_write_b128 v247, v[168:171] offset:3072
	ds_read_b128 v[156:159], v248
	ds_read_b128 v[160:163], v249
	ds_read_b128 v[164:167], v250
	ds_read_b128 v[168:171], v251
	ds_write_b128 v112, v[172:175]
	ds_write_b128 v112, v[176:179] offset:1024
	ds_write_b128 v112, v[180:183] offset:2048
	ds_write_b128 v112, v[184:187] offset:3072
	v_mfma_f32_32x32x16_bf16 v[32:47], v[120:123], v[52:55], v[32:47]
	v_mfma_f32_32x32x16_bf16 v[32:47], v[124:127], v[56:59], v[32:47]
	v_mfma_f32_32x32x16_bf16 v[32:47], v[128:131], v[60:63], v[32:47]
	s_nop 11
	v_exp_f32_e32 v32, v32
	v_exp_f32_e32 v33, v33
	v_exp_f32_e32 v34, v34
	v_exp_f32_e32 v35, v35
	v_exp_f32_e32 v36, v36
	v_exp_f32_e32 v37, v37
	v_exp_f32_e32 v38, v38
	v_exp_f32_e32 v39, v39
	v_exp_f32_e32 v40, v40
	v_exp_f32_e32 v41, v41
	v_exp_f32_e32 v42, v42
	v_exp_f32_e32 v43, v43
	v_exp_f32_e32 v44, v44
	v_exp_f32_e32 v45, v45
	v_exp_f32_e32 v46, v46
	v_exp_f32_e32 v47, v47
	v_cvt_pk_bf16_f32 v64, v32, v33
	v_cvt_pk_bf16_f32 v65, v34, v35
	v_cvt_pk_bf16_f32 v66, v36, v37
	v_cvt_pk_bf16_f32 v67, v38, v39
	v_cvt_pk_bf16_f32 v68, v40, v41
	v_cvt_pk_bf16_f32 v69, v42, v43
	v_cvt_pk_bf16_f32 v70, v44, v45
	v_cvt_pk_bf16_f32 v71, v46, v47
	v_pk_add_f32 v[232:233], v[232:233], v[32:33]
	v_pk_add_f32 v[232:233], v[232:233], v[34:35]
	v_pk_add_f32 v[232:233], v[232:233], v[36:37]
	v_pk_add_f32 v[232:233], v[232:233], v[38:39]
	v_pk_add_f32 v[232:233], v[232:233], v[40:41]
	v_pk_add_f32 v[232:233], v[232:233], v[42:43]
	v_pk_add_f32 v[232:233], v[232:233], v[44:45]
	v_pk_add_f32 v[232:233], v[232:233], v[46:47]
	s_waitcnt lgkmcnt(12)
	v_mfma_f32_32x32x16_bf16 v[0:15], v[64:67], v[72:75], v[0:15]
	v_mfma_f32_32x32x16_bf16 v[16:31], v[64:67], v[76:79], v[16:31]
	v_mfma_f32_32x32x16_bf16 v[0:15], v[68:71], v[220:223], v[0:15]
	v_mfma_f32_32x32x16_bf16 v[16:31], v[68:71], v[224:227], v[16:31]
	global_load_dwordx4 v[116:119], v235, s[84:85]
	global_load_dwordx4 v[120:123], v236, s[84:85]
	global_load_dwordx4 v[124:127], v237, s[84:85]
	global_load_dwordx4 v[128:131], v238, s[84:85]
	global_load_dwordx4 v[132:135], v100, s[84:85] offset:768
	global_load_dwordx4 v[136:139], v149, s[84:85] offset:768
	global_load_dwordx4 v[140:143], v100, s[84:85] offset:832
	global_load_dwordx4 v[144:147], v149, s[84:85] offset:832
	s_add_u32 s84, s84, 0x30000
	s_addc_u32 s85, s85, 0
	ds_read2_b32 v[32:33], v115 offset0:34 offset1:35
	ds_read2_b32 v[34:35], v115 offset0:36 offset1:37
	ds_read2_b32 v[36:37], v115 offset0:42 offset1:43
	ds_read2_b32 v[38:39], v115 offset0:44 offset1:45
	ds_read2_b32 v[40:41], v115 offset0:51 offset1:52
	ds_read2_b32 v[42:43], v115 offset0:53 offset1:54
	ds_read2_b32 v[44:45], v115 offset0:59 offset1:60
	ds_read2_b32 v[46:47], v115 offset0:61 offset1:62
	s_waitcnt lgkmcnt(0)
	v_mfma_f32_32x32x16_bf16 v[32:47], v[156:159], v[48:51], v[32:47]
	ds_read_b64_tr_b16 v[72:73], v231
	ds_read_b64_tr_b16 v[74:75], v231 offset:512
	ds_read_b64_tr_b16 v[76:77], v231 offset:2048
	ds_read_b64_tr_b16 v[78:79], v231 offset:2560
	ds_read_b64_tr_b16 v[220:221], v231 offset:1024
	ds_read_b64_tr_b16 v[222:223], v231 offset:1536
	ds_read_b64_tr_b16 v[224:225], v231 offset:3072
	ds_read_b64_tr_b16 v[226:227], v231 offset:3584
	s_waitcnt vmcnt(8)
	ds_write_b128 v247, v[188:191]
	ds_write_b128 v247, v[192:195] offset:1024
	ds_write_b128 v247, v[196:199] offset:2048
	ds_write_b128 v247, v[200:203] offset:3072
	ds_read_b128 v[188:191], v248
	ds_read_b128 v[192:195], v249
	ds_read_b128 v[196:199], v250
	ds_read_b128 v[200:203], v251
	ds_write_b128 v112, v[204:207]
	ds_write_b128 v112, v[208:211] offset:1024
	ds_write_b128 v112, v[212:215] offset:2048
	ds_write_b128 v112, v[216:219] offset:3072
	v_mfma_f32_32x32x16_bf16 v[32:47], v[160:163], v[52:55], v[32:47]
	v_mfma_f32_32x32x16_bf16 v[32:47], v[164:167], v[56:59], v[32:47]
	v_mfma_f32_32x32x16_bf16 v[32:47], v[168:171], v[60:63], v[32:47]
	s_nop 11
	v_exp_f32_e32 v32, v32
	v_exp_f32_e32 v33, v33
	v_exp_f32_e32 v34, v34
	v_exp_f32_e32 v35, v35
	v_exp_f32_e32 v36, v36
	v_exp_f32_e32 v37, v37
	v_exp_f32_e32 v38, v38
	v_exp_f32_e32 v39, v39
	v_exp_f32_e32 v40, v40
	v_exp_f32_e32 v41, v41
	v_exp_f32_e32 v42, v42
	v_exp_f32_e32 v43, v43
	v_exp_f32_e32 v44, v44
	v_exp_f32_e32 v45, v45
	v_exp_f32_e32 v46, v46
	v_exp_f32_e32 v47, v47
	v_cvt_pk_bf16_f32 v64, v32, v33
	v_cvt_pk_bf16_f32 v65, v34, v35
	v_cvt_pk_bf16_f32 v66, v36, v37
	v_cvt_pk_bf16_f32 v67, v38, v39
	v_cvt_pk_bf16_f32 v68, v40, v41
	v_cvt_pk_bf16_f32 v69, v42, v43
	v_cvt_pk_bf16_f32 v70, v44, v45
	v_cvt_pk_bf16_f32 v71, v46, v47
	v_pk_add_f32 v[232:233], v[232:233], v[32:33]
	v_pk_add_f32 v[232:233], v[232:233], v[34:35]
	v_pk_add_f32 v[232:233], v[232:233], v[36:37]
	v_pk_add_f32 v[232:233], v[232:233], v[38:39]
	v_pk_add_f32 v[232:233], v[232:233], v[40:41]
	v_pk_add_f32 v[232:233], v[232:233], v[42:43]
	v_pk_add_f32 v[232:233], v[232:233], v[44:45]
	v_pk_add_f32 v[232:233], v[232:233], v[46:47]
	s_waitcnt lgkmcnt(12)
	v_mfma_f32_32x32x16_bf16 v[0:15], v[64:67], v[72:75], v[0:15]
	v_mfma_f32_32x32x16_bf16 v[16:31], v[64:67], v[76:79], v[16:31]
	v_mfma_f32_32x32x16_bf16 v[0:15], v[68:71], v[220:223], v[0:15]
	v_mfma_f32_32x32x16_bf16 v[16:31], v[68:71], v[224:227], v[16:31]
	global_load_dwordx4 v[156:159], v235, s[84:85]
	global_load_dwordx4 v[160:163], v236, s[84:85]
	global_load_dwordx4 v[164:167], v237, s[84:85]
	global_load_dwordx4 v[168:171], v238, s[84:85]
	global_load_dwordx4 v[172:175], v100, s[84:85] offset:768
	global_load_dwordx4 v[176:179], v149, s[84:85] offset:768
	global_load_dwordx4 v[180:183], v100, s[84:85] offset:832
	global_load_dwordx4 v[184:187], v149, s[84:85] offset:832
	s_add_u32 s84, s84, 0x30000
	s_addc_u32 s85, s85, 0
	ds_read2_b32 v[32:33], v115 offset0:68 offset1:69
	ds_read2_b32 v[34:35], v115 offset0:70 offset1:71
	ds_read2_b32 v[36:37], v115 offset0:76 offset1:77
	ds_read2_b32 v[38:39], v115 offset0:78 offset1:79
	ds_read2_b32 v[40:41], v115 offset0:85 offset1:86
	ds_read2_b32 v[42:43], v115 offset0:87 offset1:88
	ds_read2_b32 v[44:45], v115 offset0:93 offset1:94
	ds_read2_b32 v[46:47], v115 offset0:95 offset1:96
	s_waitcnt lgkmcnt(0)
	v_mfma_f32_32x32x16_bf16 v[32:47], v[188:191], v[48:51], v[32:47]
	ds_read_b64_tr_b16 v[72:73], v231
	ds_read_b64_tr_b16 v[74:75], v231 offset:512
	ds_read_b64_tr_b16 v[76:77], v231 offset:2048
	ds_read_b64_tr_b16 v[78:79], v231 offset:2560
	ds_read_b64_tr_b16 v[220:221], v231 offset:1024
	ds_read_b64_tr_b16 v[222:223], v231 offset:1536
	ds_read_b64_tr_b16 v[224:225], v231 offset:3072
	ds_read_b64_tr_b16 v[226:227], v231 offset:3584
	s_waitcnt vmcnt(8)
	ds_write_b128 v247, v[116:119]
	ds_write_b128 v247, v[120:123] offset:1024
	ds_write_b128 v247, v[124:127] offset:2048
	ds_write_b128 v247, v[128:131] offset:3072
	ds_read_b128 v[116:119], v248
	ds_read_b128 v[120:123], v249
	ds_read_b128 v[124:127], v250
	ds_read_b128 v[128:131], v251
	ds_write_b128 v112, v[132:135]
	ds_write_b128 v112, v[136:139] offset:1024
	ds_write_b128 v112, v[140:143] offset:2048
	ds_write_b128 v112, v[144:147] offset:3072
	v_mfma_f32_32x32x16_bf16 v[32:47], v[192:195], v[52:55], v[32:47]
	v_mfma_f32_32x32x16_bf16 v[32:47], v[196:199], v[56:59], v[32:47]
	v_mfma_f32_32x32x16_bf16 v[32:47], v[200:203], v[60:63], v[32:47]
	s_nop 11
	v_exp_f32_e32 v32, v32
	v_exp_f32_e32 v33, v33
	v_exp_f32_e32 v34, v34
	v_exp_f32_e32 v35, v35
	v_exp_f32_e32 v36, v36
	v_exp_f32_e32 v37, v37
	v_exp_f32_e32 v38, v38
	v_exp_f32_e32 v39, v39
	v_exp_f32_e32 v40, v40
	v_exp_f32_e32 v41, v41
	v_exp_f32_e32 v42, v42
	v_exp_f32_e32 v43, v43
	v_exp_f32_e32 v44, v44
	v_exp_f32_e32 v45, v45
	v_exp_f32_e32 v46, v46
	v_exp_f32_e32 v47, v47
	v_cvt_pk_bf16_f32 v64, v32, v33
	v_cvt_pk_bf16_f32 v65, v34, v35
	v_cvt_pk_bf16_f32 v66, v36, v37
	v_cvt_pk_bf16_f32 v67, v38, v39
	v_cvt_pk_bf16_f32 v68, v40, v41
	v_cvt_pk_bf16_f32 v69, v42, v43
	v_cvt_pk_bf16_f32 v70, v44, v45
	v_cvt_pk_bf16_f32 v71, v46, v47
	v_pk_add_f32 v[232:233], v[232:233], v[32:33]
	v_pk_add_f32 v[232:233], v[232:233], v[34:35]
	v_pk_add_f32 v[232:233], v[232:233], v[36:37]
	v_pk_add_f32 v[232:233], v[232:233], v[38:39]
	v_pk_add_f32 v[232:233], v[232:233], v[40:41]
	v_pk_add_f32 v[232:233], v[232:233], v[42:43]
	v_pk_add_f32 v[232:233], v[232:233], v[44:45]
	v_pk_add_f32 v[232:233], v[232:233], v[46:47]
	s_waitcnt lgkmcnt(12)
	v_mfma_f32_32x32x16_bf16 v[0:15], v[64:67], v[72:75], v[0:15]
	v_mfma_f32_32x32x16_bf16 v[16:31], v[64:67], v[76:79], v[16:31]
	v_mfma_f32_32x32x16_bf16 v[0:15], v[68:71], v[220:223], v[0:15]
	v_mfma_f32_32x32x16_bf16 v[16:31], v[68:71], v[224:227], v[16:31]
	global_load_dwordx4 v[188:191], v235, s[84:85]
	global_load_dwordx4 v[192:195], v236, s[84:85]
	global_load_dwordx4 v[196:199], v237, s[84:85]
	global_load_dwordx4 v[200:203], v238, s[84:85]
	global_load_dwordx4 v[204:207], v100, s[84:85] offset:768
	global_load_dwordx4 v[208:211], v149, s[84:85] offset:768
	global_load_dwordx4 v[212:215], v100, s[84:85] offset:832
	global_load_dwordx4 v[216:219], v149, s[84:85] offset:832
	s_add_u32 s84, s84, 0x30000
	s_addc_u32 s85, s85, 0
	ds_read2_b32 v[32:33], v115 offset0:102 offset1:103
	ds_read2_b32 v[34:35], v115 offset0:104 offset1:105
	ds_read2_b32 v[36:37], v115 offset0:110 offset1:111
	ds_read2_b32 v[38:39], v115 offset0:112 offset1:113
	ds_read2_b32 v[40:41], v115 offset0:119 offset1:120
	ds_read2_b32 v[42:43], v115 offset0:121 offset1:122
	ds_read2_b32 v[44:45], v115 offset0:127 offset1:128
	ds_read2_b32 v[46:47], v115 offset0:129 offset1:130
	s_waitcnt lgkmcnt(0)
	v_mfma_f32_32x32x16_bf16 v[32:47], v[116:119], v[48:51], v[32:47]
	ds_read_b64_tr_b16 v[72:73], v231
	ds_read_b64_tr_b16 v[74:75], v231 offset:512
	ds_read_b64_tr_b16 v[76:77], v231 offset:2048
	ds_read_b64_tr_b16 v[78:79], v231 offset:2560
	ds_read_b64_tr_b16 v[220:221], v231 offset:1024
	ds_read_b64_tr_b16 v[222:223], v231 offset:1536
	ds_read_b64_tr_b16 v[224:225], v231 offset:3072
	ds_read_b64_tr_b16 v[226:227], v231 offset:3584
	s_waitcnt vmcnt(8)
	ds_write_b128 v247, v[156:159]
	ds_write_b128 v247, v[160:163] offset:1024
	ds_write_b128 v247, v[164:167] offset:2048
	ds_write_b128 v247, v[168:171] offset:3072
	ds_read_b128 v[156:159], v248
	ds_read_b128 v[160:163], v249
	ds_read_b128 v[164:167], v250
	ds_read_b128 v[168:171], v251
	ds_write_b128 v112, v[172:175]
	ds_write_b128 v112, v[176:179] offset:1024
	ds_write_b128 v112, v[180:183] offset:2048
	ds_write_b128 v112, v[184:187] offset:3072
	v_mfma_f32_32x32x16_bf16 v[32:47], v[120:123], v[52:55], v[32:47]
	v_mfma_f32_32x32x16_bf16 v[32:47], v[124:127], v[56:59], v[32:47]
	v_mfma_f32_32x32x16_bf16 v[32:47], v[128:131], v[60:63], v[32:47]
	s_nop 11
	v_exp_f32_e32 v32, v32
	v_exp_f32_e32 v33, v33
	v_exp_f32_e32 v34, v34
	v_exp_f32_e32 v35, v35
	v_exp_f32_e32 v36, v36
	v_exp_f32_e32 v37, v37
	v_exp_f32_e32 v38, v38
	v_exp_f32_e32 v39, v39
	v_exp_f32_e32 v40, v40
	v_exp_f32_e32 v41, v41
	v_exp_f32_e32 v42, v42
	v_exp_f32_e32 v43, v43
	v_exp_f32_e32 v44, v44
	v_exp_f32_e32 v45, v45
	v_exp_f32_e32 v46, v46
	v_exp_f32_e32 v47, v47
	v_cvt_pk_bf16_f32 v64, v32, v33
	v_cvt_pk_bf16_f32 v65, v34, v35
	v_cvt_pk_bf16_f32 v66, v36, v37
	v_cvt_pk_bf16_f32 v67, v38, v39
	v_cvt_pk_bf16_f32 v68, v40, v41
	v_cvt_pk_bf16_f32 v69, v42, v43
	v_cvt_pk_bf16_f32 v70, v44, v45
	v_cvt_pk_bf16_f32 v71, v46, v47
	v_pk_add_f32 v[232:233], v[232:233], v[32:33]
	v_pk_add_f32 v[232:233], v[232:233], v[34:35]
	v_pk_add_f32 v[232:233], v[232:233], v[36:37]
	v_pk_add_f32 v[232:233], v[232:233], v[38:39]
	v_pk_add_f32 v[232:233], v[232:233], v[40:41]
	v_pk_add_f32 v[232:233], v[232:233], v[42:43]
	v_pk_add_f32 v[232:233], v[232:233], v[44:45]
	v_pk_add_f32 v[232:233], v[232:233], v[46:47]
	s_waitcnt lgkmcnt(12)
	v_mfma_f32_32x32x16_bf16 v[0:15], v[64:67], v[72:75], v[0:15]
	v_mfma_f32_32x32x16_bf16 v[16:31], v[64:67], v[76:79], v[16:31]
	v_mfma_f32_32x32x16_bf16 v[0:15], v[68:71], v[220:223], v[0:15]
	v_mfma_f32_32x32x16_bf16 v[16:31], v[68:71], v[224:227], v[16:31]
	global_load_dwordx4 v[116:119], v235, s[84:85]
	global_load_dwordx4 v[120:123], v236, s[84:85]
	global_load_dwordx4 v[124:127], v237, s[84:85]
	global_load_dwordx4 v[128:131], v238, s[84:85]
	global_load_dwordx4 v[132:135], v100, s[84:85] offset:768
	global_load_dwordx4 v[136:139], v149, s[84:85] offset:768
	global_load_dwordx4 v[140:143], v100, s[84:85] offset:832
	global_load_dwordx4 v[144:147], v149, s[84:85] offset:832
	s_add_u32 s84, s84, 0x30000
	s_addc_u32 s85, s85, 0
	ds_read2_b32 v[32:33], v115 offset0:136 offset1:137
	ds_read2_b32 v[34:35], v115 offset0:138 offset1:139
	ds_read2_b32 v[36:37], v115 offset0:144 offset1:145
	ds_read2_b32 v[38:39], v115 offset0:146 offset1:147
	ds_read2_b32 v[40:41], v115 offset0:153 offset1:154
	ds_read2_b32 v[42:43], v115 offset0:155 offset1:156
	ds_read2_b32 v[44:45], v115 offset0:161 offset1:162
	ds_read2_b32 v[46:47], v115 offset0:163 offset1:164
	s_waitcnt lgkmcnt(0)
	v_mfma_f32_32x32x16_bf16 v[32:47], v[156:159], v[48:51], v[32:47]
	ds_read_b64_tr_b16 v[72:73], v231
	ds_read_b64_tr_b16 v[74:75], v231 offset:512
	ds_read_b64_tr_b16 v[76:77], v231 offset:2048
	ds_read_b64_tr_b16 v[78:79], v231 offset:2560
	ds_read_b64_tr_b16 v[220:221], v231 offset:1024
	ds_read_b64_tr_b16 v[222:223], v231 offset:1536
	ds_read_b64_tr_b16 v[224:225], v231 offset:3072
	ds_read_b64_tr_b16 v[226:227], v231 offset:3584
	s_waitcnt vmcnt(8)
	ds_write_b128 v247, v[188:191]
	ds_write_b128 v247, v[192:195] offset:1024
	ds_write_b128 v247, v[196:199] offset:2048
	ds_write_b128 v247, v[200:203] offset:3072
	ds_read_b128 v[188:191], v248
	ds_read_b128 v[192:195], v249
	ds_read_b128 v[196:199], v250
	ds_read_b128 v[200:203], v251
	ds_write_b128 v112, v[204:207]
	ds_write_b128 v112, v[208:211] offset:1024
	ds_write_b128 v112, v[212:215] offset:2048
	ds_write_b128 v112, v[216:219] offset:3072
	v_mfma_f32_32x32x16_bf16 v[32:47], v[160:163], v[52:55], v[32:47]
	v_mfma_f32_32x32x16_bf16 v[32:47], v[164:167], v[56:59], v[32:47]
	v_mfma_f32_32x32x16_bf16 v[32:47], v[168:171], v[60:63], v[32:47]
	s_nop 11
	v_exp_f32_e32 v32, v32
	v_exp_f32_e32 v33, v33
	v_exp_f32_e32 v34, v34
	v_exp_f32_e32 v35, v35
	v_exp_f32_e32 v36, v36
	v_exp_f32_e32 v37, v37
	v_exp_f32_e32 v38, v38
	v_exp_f32_e32 v39, v39
	v_exp_f32_e32 v40, v40
	v_exp_f32_e32 v41, v41
	v_exp_f32_e32 v42, v42
	v_exp_f32_e32 v43, v43
	v_exp_f32_e32 v44, v44
	v_exp_f32_e32 v45, v45
	v_exp_f32_e32 v46, v46
	v_exp_f32_e32 v47, v47
	v_cvt_pk_bf16_f32 v64, v32, v33
	v_cvt_pk_bf16_f32 v65, v34, v35
	v_cvt_pk_bf16_f32 v66, v36, v37
	v_cvt_pk_bf16_f32 v67, v38, v39
	v_cvt_pk_bf16_f32 v68, v40, v41
	v_cvt_pk_bf16_f32 v69, v42, v43
	v_cvt_pk_bf16_f32 v70, v44, v45
	v_cvt_pk_bf16_f32 v71, v46, v47
	v_pk_add_f32 v[232:233], v[232:233], v[32:33]
	v_pk_add_f32 v[232:233], v[232:233], v[34:35]
	v_pk_add_f32 v[232:233], v[232:233], v[36:37]
	v_pk_add_f32 v[232:233], v[232:233], v[38:39]
	v_pk_add_f32 v[232:233], v[232:233], v[40:41]
	v_pk_add_f32 v[232:233], v[232:233], v[42:43]
	v_pk_add_f32 v[232:233], v[232:233], v[44:45]
	v_pk_add_f32 v[232:233], v[232:233], v[46:47]
	s_waitcnt lgkmcnt(12)
	v_mfma_f32_32x32x16_bf16 v[0:15], v[64:67], v[72:75], v[0:15]
	v_mfma_f32_32x32x16_bf16 v[16:31], v[64:67], v[76:79], v[16:31]
	v_mfma_f32_32x32x16_bf16 v[0:15], v[68:71], v[220:223], v[0:15]
	v_mfma_f32_32x32x16_bf16 v[16:31], v[68:71], v[224:227], v[16:31]
	global_load_dwordx4 v[156:159], v235, s[84:85]
	global_load_dwordx4 v[160:163], v236, s[84:85]
	global_load_dwordx4 v[164:167], v237, s[84:85]
	global_load_dwordx4 v[168:171], v238, s[84:85]
	global_load_dwordx4 v[172:175], v100, s[84:85] offset:768
	global_load_dwordx4 v[176:179], v149, s[84:85] offset:768
	global_load_dwordx4 v[180:183], v100, s[84:85] offset:832
	global_load_dwordx4 v[184:187], v149, s[84:85] offset:832
	s_add_u32 s84, s84, 0x30000
	s_addc_u32 s85, s85, 0
	ds_read2_b32 v[32:33], v115 offset0:170 offset1:171
	ds_read2_b32 v[34:35], v115 offset0:172 offset1:173
	ds_read2_b32 v[36:37], v115 offset0:178 offset1:179
	ds_read2_b32 v[38:39], v115 offset0:180 offset1:181
	ds_read2_b32 v[40:41], v115 offset0:187 offset1:188
	ds_read2_b32 v[42:43], v115 offset0:189 offset1:190
	ds_read2_b32 v[44:45], v115 offset0:195 offset1:196
	ds_read2_b32 v[46:47], v115 offset0:197 offset1:198
	s_waitcnt lgkmcnt(0)
	v_mfma_f32_32x32x16_bf16 v[32:47], v[188:191], v[48:51], v[32:47]
	ds_read_b64_tr_b16 v[72:73], v231
	ds_read_b64_tr_b16 v[74:75], v231 offset:512
	ds_read_b64_tr_b16 v[76:77], v231 offset:2048
	ds_read_b64_tr_b16 v[78:79], v231 offset:2560
	ds_read_b64_tr_b16 v[220:221], v231 offset:1024
	ds_read_b64_tr_b16 v[222:223], v231 offset:1536
	ds_read_b64_tr_b16 v[224:225], v231 offset:3072
	ds_read_b64_tr_b16 v[226:227], v231 offset:3584
	s_waitcnt vmcnt(8)
	ds_write_b128 v247, v[116:119]
	ds_write_b128 v247, v[120:123] offset:1024
	ds_write_b128 v247, v[124:127] offset:2048
	ds_write_b128 v247, v[128:131] offset:3072
	ds_read_b128 v[116:119], v248
	ds_read_b128 v[120:123], v249
	ds_read_b128 v[124:127], v250
	ds_read_b128 v[128:131], v251
	ds_write_b128 v112, v[132:135]
	ds_write_b128 v112, v[136:139] offset:1024
	ds_write_b128 v112, v[140:143] offset:2048
	ds_write_b128 v112, v[144:147] offset:3072
	v_mfma_f32_32x32x16_bf16 v[32:47], v[192:195], v[52:55], v[32:47]
	v_mfma_f32_32x32x16_bf16 v[32:47], v[196:199], v[56:59], v[32:47]
	v_mfma_f32_32x32x16_bf16 v[32:47], v[200:203], v[60:63], v[32:47]
	s_nop 11
	v_exp_f32_e32 v32, v32
	v_exp_f32_e32 v33, v33
	v_exp_f32_e32 v34, v34
	v_exp_f32_e32 v35, v35
	v_exp_f32_e32 v36, v36
	v_exp_f32_e32 v37, v37
	v_exp_f32_e32 v38, v38
	v_exp_f32_e32 v39, v39
	v_exp_f32_e32 v40, v40
	v_exp_f32_e32 v41, v41
	v_exp_f32_e32 v42, v42
	v_exp_f32_e32 v43, v43
	v_exp_f32_e32 v44, v44
	v_exp_f32_e32 v45, v45
	v_exp_f32_e32 v46, v46
	v_exp_f32_e32 v47, v47
	v_cvt_pk_bf16_f32 v64, v32, v33
	v_cvt_pk_bf16_f32 v65, v34, v35
	v_cvt_pk_bf16_f32 v66, v36, v37
	v_cvt_pk_bf16_f32 v67, v38, v39
	v_cvt_pk_bf16_f32 v68, v40, v41
	v_cvt_pk_bf16_f32 v69, v42, v43
	v_cvt_pk_bf16_f32 v70, v44, v45
	v_cvt_pk_bf16_f32 v71, v46, v47
	v_pk_add_f32 v[232:233], v[232:233], v[32:33]
	v_pk_add_f32 v[232:233], v[232:233], v[34:35]
	v_pk_add_f32 v[232:233], v[232:233], v[36:37]
	v_pk_add_f32 v[232:233], v[232:233], v[38:39]
	v_pk_add_f32 v[232:233], v[232:233], v[40:41]
	v_pk_add_f32 v[232:233], v[232:233], v[42:43]
	v_pk_add_f32 v[232:233], v[232:233], v[44:45]
	v_pk_add_f32 v[232:233], v[232:233], v[46:47]
	s_waitcnt lgkmcnt(12)
	v_mfma_f32_32x32x16_bf16 v[0:15], v[64:67], v[72:75], v[0:15]
	v_mfma_f32_32x32x16_bf16 v[16:31], v[64:67], v[76:79], v[16:31]
	v_mfma_f32_32x32x16_bf16 v[0:15], v[68:71], v[220:223], v[0:15]
	v_mfma_f32_32x32x16_bf16 v[16:31], v[68:71], v[224:227], v[16:31]
	global_load_dwordx4 v[188:191], v235, s[84:85]
	global_load_dwordx4 v[192:195], v236, s[84:85]
	global_load_dwordx4 v[196:199], v237, s[84:85]
	global_load_dwordx4 v[200:203], v238, s[84:85]
	global_load_dwordx4 v[204:207], v100, s[84:85] offset:768
	global_load_dwordx4 v[208:211], v149, s[84:85] offset:768
	global_load_dwordx4 v[212:215], v100, s[84:85] offset:832
	global_load_dwordx4 v[216:219], v149, s[84:85] offset:832
	s_add_u32 s84, s84, 0x30000
	s_addc_u32 s85, s85, 0
	ds_read2_b32 v[32:33], v115 offset0:204 offset1:205
	ds_read2_b32 v[34:35], v115 offset0:206 offset1:207
	ds_read2_b32 v[36:37], v115 offset0:212 offset1:213
	ds_read2_b32 v[38:39], v115 offset0:214 offset1:215
	ds_read2_b32 v[40:41], v115 offset0:221 offset1:222
	ds_read2_b32 v[42:43], v115 offset0:223 offset1:224
	ds_read2_b32 v[44:45], v115 offset0:229 offset1:230
	ds_read2_b32 v[46:47], v115 offset0:231 offset1:232
	s_waitcnt lgkmcnt(0)
	v_mfma_f32_32x32x16_bf16 v[32:47], v[116:119], v[48:51], v[32:47]
	ds_read_b64_tr_b16 v[72:73], v231
	ds_read_b64_tr_b16 v[74:75], v231 offset:512
	ds_read_b64_tr_b16 v[76:77], v231 offset:2048
	ds_read_b64_tr_b16 v[78:79], v231 offset:2560
	ds_read_b64_tr_b16 v[220:221], v231 offset:1024
	ds_read_b64_tr_b16 v[222:223], v231 offset:1536
	ds_read_b64_tr_b16 v[224:225], v231 offset:3072
	ds_read_b64_tr_b16 v[226:227], v231 offset:3584
	s_waitcnt vmcnt(8)
	ds_write_b128 v247, v[156:159]
	ds_write_b128 v247, v[160:163] offset:1024
	ds_write_b128 v247, v[164:167] offset:2048
	ds_write_b128 v247, v[168:171] offset:3072
	ds_read_b128 v[156:159], v248
	ds_read_b128 v[160:163], v249
	ds_read_b128 v[164:167], v250
	ds_read_b128 v[168:171], v251
	ds_write_b128 v112, v[172:175]
	ds_write_b128 v112, v[176:179] offset:1024
	ds_write_b128 v112, v[180:183] offset:2048
	ds_write_b128 v112, v[184:187] offset:3072
	v_mfma_f32_32x32x16_bf16 v[32:47], v[120:123], v[52:55], v[32:47]
	v_mfma_f32_32x32x16_bf16 v[32:47], v[124:127], v[56:59], v[32:47]
	v_mfma_f32_32x32x16_bf16 v[32:47], v[128:131], v[60:63], v[32:47]
	s_nop 11
	v_exp_f32_e32 v32, v32
	v_exp_f32_e32 v33, v33
	v_exp_f32_e32 v34, v34
	v_exp_f32_e32 v35, v35
	v_exp_f32_e32 v36, v36
	v_exp_f32_e32 v37, v37
	v_exp_f32_e32 v38, v38
	v_exp_f32_e32 v39, v39
	v_exp_f32_e32 v40, v40
	v_exp_f32_e32 v41, v41
	v_exp_f32_e32 v42, v42
	v_exp_f32_e32 v43, v43
	v_exp_f32_e32 v44, v44
	v_exp_f32_e32 v45, v45
	v_exp_f32_e32 v46, v46
	v_exp_f32_e32 v47, v47
	v_cvt_pk_bf16_f32 v64, v32, v33
	v_cvt_pk_bf16_f32 v65, v34, v35
	v_cvt_pk_bf16_f32 v66, v36, v37
	v_cvt_pk_bf16_f32 v67, v38, v39
	v_cvt_pk_bf16_f32 v68, v40, v41
	v_cvt_pk_bf16_f32 v69, v42, v43
	v_cvt_pk_bf16_f32 v70, v44, v45
	v_cvt_pk_bf16_f32 v71, v46, v47
	v_pk_add_f32 v[232:233], v[232:233], v[32:33]
	v_pk_add_f32 v[232:233], v[232:233], v[34:35]
	v_pk_add_f32 v[232:233], v[232:233], v[36:37]
	v_pk_add_f32 v[232:233], v[232:233], v[38:39]
	v_pk_add_f32 v[232:233], v[232:233], v[40:41]
	v_pk_add_f32 v[232:233], v[232:233], v[42:43]
	v_pk_add_f32 v[232:233], v[232:233], v[44:45]
	v_pk_add_f32 v[232:233], v[232:233], v[46:47]
	s_waitcnt lgkmcnt(12)
	v_mfma_f32_32x32x16_bf16 v[0:15], v[64:67], v[72:75], v[0:15]
	v_mfma_f32_32x32x16_bf16 v[16:31], v[64:67], v[76:79], v[16:31]
	v_mfma_f32_32x32x16_bf16 v[0:15], v[68:71], v[220:223], v[0:15]
	v_mfma_f32_32x32x16_bf16 v[16:31], v[68:71], v[224:227], v[16:31]
	global_load_dwordx4 v[116:119], v235, s[84:85]
	global_load_dwordx4 v[120:123], v236, s[84:85]
	global_load_dwordx4 v[124:127], v237, s[84:85]
	global_load_dwordx4 v[128:131], v238, s[84:85]
	global_load_dwordx4 v[132:135], v100, s[84:85] offset:768
	global_load_dwordx4 v[136:139], v149, s[84:85] offset:768
	global_load_dwordx4 v[140:143], v100, s[84:85] offset:832
	global_load_dwordx4 v[144:147], v149, s[84:85] offset:832
	s_add_u32 s84, s84, 0x30000
	s_addc_u32 s85, s85, 0
	v_add_u32_e32 v115, 952, v115
	ds_read2_b32 v[32:33], v115 offset0:0 offset1:1
	ds_read2_b32 v[34:35], v115 offset0:2 offset1:3
	ds_read2_b32 v[36:37], v115 offset0:8 offset1:9
	ds_read2_b32 v[38:39], v115 offset0:10 offset1:11
	ds_read2_b32 v[40:41], v115 offset0:17 offset1:18
	ds_read2_b32 v[42:43], v115 offset0:19 offset1:20
	ds_read2_b32 v[44:45], v115 offset0:25 offset1:26
	ds_read2_b32 v[46:47], v115 offset0:27 offset1:28
	s_waitcnt lgkmcnt(0)
	v_mfma_f32_32x32x16_bf16 v[32:47], v[156:159], v[48:51], v[32:47]
	ds_read_b64_tr_b16 v[72:73], v231
	ds_read_b64_tr_b16 v[74:75], v231 offset:512
	ds_read_b64_tr_b16 v[76:77], v231 offset:2048
	ds_read_b64_tr_b16 v[78:79], v231 offset:2560
	ds_read_b64_tr_b16 v[220:221], v231 offset:1024
	ds_read_b64_tr_b16 v[222:223], v231 offset:1536
	ds_read_b64_tr_b16 v[224:225], v231 offset:3072
	ds_read_b64_tr_b16 v[226:227], v231 offset:3584
	s_waitcnt vmcnt(8)
	ds_write_b128 v247, v[188:191]
	ds_write_b128 v247, v[192:195] offset:1024
	ds_write_b128 v247, v[196:199] offset:2048
	ds_write_b128 v247, v[200:203] offset:3072
	ds_read_b128 v[188:191], v248
	ds_read_b128 v[192:195], v249
	ds_read_b128 v[196:199], v250
	ds_read_b128 v[200:203], v251
	ds_write_b128 v112, v[204:207]
	ds_write_b128 v112, v[208:211] offset:1024
	ds_write_b128 v112, v[212:215] offset:2048
	ds_write_b128 v112, v[216:219] offset:3072
	v_mfma_f32_32x32x16_bf16 v[32:47], v[160:163], v[52:55], v[32:47]
	v_mfma_f32_32x32x16_bf16 v[32:47], v[164:167], v[56:59], v[32:47]
	v_mfma_f32_32x32x16_bf16 v[32:47], v[168:171], v[60:63], v[32:47]
	s_nop 11
	v_exp_f32_e32 v32, v32
	v_exp_f32_e32 v33, v33
	v_exp_f32_e32 v34, v34
	v_exp_f32_e32 v35, v35
	v_exp_f32_e32 v36, v36
	v_exp_f32_e32 v37, v37
	v_exp_f32_e32 v38, v38
	v_exp_f32_e32 v39, v39
	v_exp_f32_e32 v40, v40
	v_exp_f32_e32 v41, v41
	v_exp_f32_e32 v42, v42
	v_exp_f32_e32 v43, v43
	v_exp_f32_e32 v44, v44
	v_exp_f32_e32 v45, v45
	v_exp_f32_e32 v46, v46
	v_exp_f32_e32 v47, v47
	v_cvt_pk_bf16_f32 v64, v32, v33
	v_cvt_pk_bf16_f32 v65, v34, v35
	v_cvt_pk_bf16_f32 v66, v36, v37
	v_cvt_pk_bf16_f32 v67, v38, v39
	v_cvt_pk_bf16_f32 v68, v40, v41
	v_cvt_pk_bf16_f32 v69, v42, v43
	v_cvt_pk_bf16_f32 v70, v44, v45
	v_cvt_pk_bf16_f32 v71, v46, v47
	v_pk_add_f32 v[232:233], v[232:233], v[32:33]
	v_pk_add_f32 v[232:233], v[232:233], v[34:35]
	v_pk_add_f32 v[232:233], v[232:233], v[36:37]
	v_pk_add_f32 v[232:233], v[232:233], v[38:39]
	v_pk_add_f32 v[232:233], v[232:233], v[40:41]
	v_pk_add_f32 v[232:233], v[232:233], v[42:43]
	v_pk_add_f32 v[232:233], v[232:233], v[44:45]
	v_pk_add_f32 v[232:233], v[232:233], v[46:47]
	s_waitcnt lgkmcnt(12)
	v_mfma_f32_32x32x16_bf16 v[0:15], v[64:67], v[72:75], v[0:15]
	v_mfma_f32_32x32x16_bf16 v[16:31], v[64:67], v[76:79], v[16:31]
	v_mfma_f32_32x32x16_bf16 v[0:15], v[68:71], v[220:223], v[0:15]
	v_mfma_f32_32x32x16_bf16 v[16:31], v[68:71], v[224:227], v[16:31]
	global_load_dwordx4 v[156:159], v235, s[84:85]
	global_load_dwordx4 v[160:163], v236, s[84:85]
	global_load_dwordx4 v[164:167], v237, s[84:85]
	global_load_dwordx4 v[168:171], v238, s[84:85]
	global_load_dwordx4 v[172:175], v100, s[84:85] offset:768
	global_load_dwordx4 v[176:179], v149, s[84:85] offset:768
	global_load_dwordx4 v[180:183], v100, s[84:85] offset:832
	global_load_dwordx4 v[184:187], v149, s[84:85] offset:832
	s_add_u32 s84, s84, 0x30000
	s_addc_u32 s85, s85, 0
	ds_read2_b32 v[32:33], v115 offset0:34 offset1:35
	ds_read2_b32 v[34:35], v115 offset0:36 offset1:37
	ds_read2_b32 v[36:37], v115 offset0:42 offset1:43
	ds_read2_b32 v[38:39], v115 offset0:44 offset1:45
	ds_read2_b32 v[40:41], v115 offset0:51 offset1:52
	ds_read2_b32 v[42:43], v115 offset0:53 offset1:54
	ds_read2_b32 v[44:45], v115 offset0:59 offset1:60
	ds_read2_b32 v[46:47], v115 offset0:61 offset1:62
	s_waitcnt lgkmcnt(0)
	v_mfma_f32_32x32x16_bf16 v[32:47], v[188:191], v[48:51], v[32:47]
	ds_read_b64_tr_b16 v[72:73], v231
	ds_read_b64_tr_b16 v[74:75], v231 offset:512
	ds_read_b64_tr_b16 v[76:77], v231 offset:2048
	ds_read_b64_tr_b16 v[78:79], v231 offset:2560
	ds_read_b64_tr_b16 v[220:221], v231 offset:1024
	ds_read_b64_tr_b16 v[222:223], v231 offset:1536
	ds_read_b64_tr_b16 v[224:225], v231 offset:3072
	ds_read_b64_tr_b16 v[226:227], v231 offset:3584
	s_waitcnt vmcnt(8)
	ds_write_b128 v247, v[116:119]
	ds_write_b128 v247, v[120:123] offset:1024
	ds_write_b128 v247, v[124:127] offset:2048
	ds_write_b128 v247, v[128:131] offset:3072
	ds_read_b128 v[116:119], v248
	ds_read_b128 v[120:123], v249
	ds_read_b128 v[124:127], v250
	ds_read_b128 v[128:131], v251
	ds_write_b128 v112, v[132:135]
	ds_write_b128 v112, v[136:139] offset:1024
	ds_write_b128 v112, v[140:143] offset:2048
	ds_write_b128 v112, v[144:147] offset:3072
	v_mfma_f32_32x32x16_bf16 v[32:47], v[192:195], v[52:55], v[32:47]
	v_mfma_f32_32x32x16_bf16 v[32:47], v[196:199], v[56:59], v[32:47]
	v_mfma_f32_32x32x16_bf16 v[32:47], v[200:203], v[60:63], v[32:47]
	s_nop 11
	v_exp_f32_e32 v32, v32
	v_exp_f32_e32 v33, v33
	v_exp_f32_e32 v34, v34
	v_exp_f32_e32 v35, v35
	v_exp_f32_e32 v36, v36
	v_exp_f32_e32 v37, v37
	v_exp_f32_e32 v38, v38
	v_exp_f32_e32 v39, v39
	v_exp_f32_e32 v40, v40
	v_exp_f32_e32 v41, v41
	v_exp_f32_e32 v42, v42
	v_exp_f32_e32 v43, v43
	v_exp_f32_e32 v44, v44
	v_exp_f32_e32 v45, v45
	v_exp_f32_e32 v46, v46
	v_exp_f32_e32 v47, v47
	v_cvt_pk_bf16_f32 v64, v32, v33
	v_cvt_pk_bf16_f32 v65, v34, v35
	v_cvt_pk_bf16_f32 v66, v36, v37
	v_cvt_pk_bf16_f32 v67, v38, v39
	v_cvt_pk_bf16_f32 v68, v40, v41
	v_cvt_pk_bf16_f32 v69, v42, v43
	v_cvt_pk_bf16_f32 v70, v44, v45
	v_cvt_pk_bf16_f32 v71, v46, v47
	v_pk_add_f32 v[232:233], v[232:233], v[32:33]
	v_pk_add_f32 v[232:233], v[232:233], v[34:35]
	v_pk_add_f32 v[232:233], v[232:233], v[36:37]
	v_pk_add_f32 v[232:233], v[232:233], v[38:39]
	v_pk_add_f32 v[232:233], v[232:233], v[40:41]
	v_pk_add_f32 v[232:233], v[232:233], v[42:43]
	v_pk_add_f32 v[232:233], v[232:233], v[44:45]
	v_pk_add_f32 v[232:233], v[232:233], v[46:47]
	s_waitcnt lgkmcnt(12)
	v_mfma_f32_32x32x16_bf16 v[0:15], v[64:67], v[72:75], v[0:15]
	v_mfma_f32_32x32x16_bf16 v[16:31], v[64:67], v[76:79], v[16:31]
	v_mfma_f32_32x32x16_bf16 v[0:15], v[68:71], v[220:223], v[0:15]
	v_mfma_f32_32x32x16_bf16 v[16:31], v[68:71], v[224:227], v[16:31]
	global_load_dwordx4 v[188:191], v235, s[84:85]
	global_load_dwordx4 v[192:195], v236, s[84:85]
	global_load_dwordx4 v[196:199], v237, s[84:85]
	global_load_dwordx4 v[200:203], v238, s[84:85]
	global_load_dwordx4 v[204:207], v100, s[84:85] offset:768
	global_load_dwordx4 v[208:211], v149, s[84:85] offset:768
	global_load_dwordx4 v[212:215], v100, s[84:85] offset:832
	global_load_dwordx4 v[216:219], v149, s[84:85] offset:832
	s_add_u32 s84, s84, 0x30000
	s_addc_u32 s85, s85, 0
	ds_read2_b32 v[32:33], v115 offset0:68 offset1:69
	ds_read2_b32 v[34:35], v115 offset0:70 offset1:71
	ds_read2_b32 v[36:37], v115 offset0:76 offset1:77
	ds_read2_b32 v[38:39], v115 offset0:78 offset1:79
	ds_read2_b32 v[40:41], v115 offset0:85 offset1:86
	ds_read2_b32 v[42:43], v115 offset0:87 offset1:88
	ds_read2_b32 v[44:45], v115 offset0:93 offset1:94
	ds_read2_b32 v[46:47], v115 offset0:95 offset1:96
	s_waitcnt lgkmcnt(0)
	v_mfma_f32_32x32x16_bf16 v[32:47], v[116:119], v[48:51], v[32:47]
	ds_read_b64_tr_b16 v[72:73], v231
	ds_read_b64_tr_b16 v[74:75], v231 offset:512
	ds_read_b64_tr_b16 v[76:77], v231 offset:2048
	ds_read_b64_tr_b16 v[78:79], v231 offset:2560
	ds_read_b64_tr_b16 v[220:221], v231 offset:1024
	ds_read_b64_tr_b16 v[222:223], v231 offset:1536
	ds_read_b64_tr_b16 v[224:225], v231 offset:3072
	ds_read_b64_tr_b16 v[226:227], v231 offset:3584
	s_waitcnt vmcnt(8)
	ds_write_b128 v247, v[156:159]
	ds_write_b128 v247, v[160:163] offset:1024
	ds_write_b128 v247, v[164:167] offset:2048
	ds_write_b128 v247, v[168:171] offset:3072
	ds_read_b128 v[156:159], v248
	ds_read_b128 v[160:163], v249
	ds_read_b128 v[164:167], v250
	ds_read_b128 v[168:171], v251
	ds_write_b128 v112, v[172:175]
	ds_write_b128 v112, v[176:179] offset:1024
	ds_write_b128 v112, v[180:183] offset:2048
	ds_write_b128 v112, v[184:187] offset:3072
	v_mfma_f32_32x32x16_bf16 v[32:47], v[120:123], v[52:55], v[32:47]
	v_mfma_f32_32x32x16_bf16 v[32:47], v[124:127], v[56:59], v[32:47]
	v_mfma_f32_32x32x16_bf16 v[32:47], v[128:131], v[60:63], v[32:47]
	s_nop 11
	v_exp_f32_e32 v32, v32
	v_exp_f32_e32 v33, v33
	v_exp_f32_e32 v34, v34
	v_exp_f32_e32 v35, v35
	v_exp_f32_e32 v36, v36
	v_exp_f32_e32 v37, v37
	v_exp_f32_e32 v38, v38
	v_exp_f32_e32 v39, v39
	v_exp_f32_e32 v40, v40
	v_exp_f32_e32 v41, v41
	v_exp_f32_e32 v42, v42
	v_exp_f32_e32 v43, v43
	v_exp_f32_e32 v44, v44
	v_exp_f32_e32 v45, v45
	v_exp_f32_e32 v46, v46
	v_exp_f32_e32 v47, v47
	v_cvt_pk_bf16_f32 v64, v32, v33
	v_cvt_pk_bf16_f32 v65, v34, v35
	v_cvt_pk_bf16_f32 v66, v36, v37
	v_cvt_pk_bf16_f32 v67, v38, v39
	v_cvt_pk_bf16_f32 v68, v40, v41
	v_cvt_pk_bf16_f32 v69, v42, v43
	v_cvt_pk_bf16_f32 v70, v44, v45
	v_cvt_pk_bf16_f32 v71, v46, v47
	v_pk_add_f32 v[232:233], v[232:233], v[32:33]
	v_pk_add_f32 v[232:233], v[232:233], v[34:35]
	v_pk_add_f32 v[232:233], v[232:233], v[36:37]
	v_pk_add_f32 v[232:233], v[232:233], v[38:39]
	v_pk_add_f32 v[232:233], v[232:233], v[40:41]
	v_pk_add_f32 v[232:233], v[232:233], v[42:43]
	v_pk_add_f32 v[232:233], v[232:233], v[44:45]
	v_pk_add_f32 v[232:233], v[232:233], v[46:47]
	s_waitcnt lgkmcnt(12)
	v_mfma_f32_32x32x16_bf16 v[0:15], v[64:67], v[72:75], v[0:15]
	v_mfma_f32_32x32x16_bf16 v[16:31], v[64:67], v[76:79], v[16:31]
	v_mfma_f32_32x32x16_bf16 v[0:15], v[68:71], v[220:223], v[0:15]
	v_mfma_f32_32x32x16_bf16 v[16:31], v[68:71], v[224:227], v[16:31]
	global_load_dwordx4 v[116:119], v235, s[84:85]
	global_load_dwordx4 v[120:123], v236, s[84:85]
	global_load_dwordx4 v[124:127], v237, s[84:85]
	global_load_dwordx4 v[128:131], v238, s[84:85]
	global_load_dwordx4 v[132:135], v100, s[84:85] offset:768
	global_load_dwordx4 v[136:139], v149, s[84:85] offset:768
	global_load_dwordx4 v[140:143], v100, s[84:85] offset:832
	global_load_dwordx4 v[144:147], v149, s[84:85] offset:832
	s_add_u32 s84, s84, 0x30000
	s_addc_u32 s85, s85, 0
	ds_read2_b32 v[32:33], v115 offset0:102 offset1:103
	ds_read2_b32 v[34:35], v115 offset0:104 offset1:105
	ds_read2_b32 v[36:37], v115 offset0:110 offset1:111
	ds_read2_b32 v[38:39], v115 offset0:112 offset1:113
	ds_read2_b32 v[40:41], v115 offset0:119 offset1:120
	ds_read2_b32 v[42:43], v115 offset0:121 offset1:122
	ds_read2_b32 v[44:45], v115 offset0:127 offset1:128
	ds_read2_b32 v[46:47], v115 offset0:129 offset1:130
	s_waitcnt lgkmcnt(0)
	v_mfma_f32_32x32x16_bf16 v[32:47], v[156:159], v[48:51], v[32:47]
	ds_read_b64_tr_b16 v[72:73], v231
	ds_read_b64_tr_b16 v[74:75], v231 offset:512
	ds_read_b64_tr_b16 v[76:77], v231 offset:2048
	ds_read_b64_tr_b16 v[78:79], v231 offset:2560
	ds_read_b64_tr_b16 v[220:221], v231 offset:1024
	ds_read_b64_tr_b16 v[222:223], v231 offset:1536
	ds_read_b64_tr_b16 v[224:225], v231 offset:3072
	ds_read_b64_tr_b16 v[226:227], v231 offset:3584
	s_waitcnt vmcnt(8)
	ds_write_b128 v247, v[188:191]
	ds_write_b128 v247, v[192:195] offset:1024
	ds_write_b128 v247, v[196:199] offset:2048
	ds_write_b128 v247, v[200:203] offset:3072
	ds_read_b128 v[188:191], v248
	ds_read_b128 v[192:195], v249
	ds_read_b128 v[196:199], v250
	ds_read_b128 v[200:203], v251
	ds_write_b128 v112, v[204:207]
	ds_write_b128 v112, v[208:211] offset:1024
	ds_write_b128 v112, v[212:215] offset:2048
	ds_write_b128 v112, v[216:219] offset:3072
	v_mfma_f32_32x32x16_bf16 v[32:47], v[160:163], v[52:55], v[32:47]
	v_mfma_f32_32x32x16_bf16 v[32:47], v[164:167], v[56:59], v[32:47]
	v_mfma_f32_32x32x16_bf16 v[32:47], v[168:171], v[60:63], v[32:47]
	s_nop 11
	v_exp_f32_e32 v32, v32
	v_exp_f32_e32 v33, v33
	v_exp_f32_e32 v34, v34
	v_exp_f32_e32 v35, v35
	v_exp_f32_e32 v36, v36
	v_exp_f32_e32 v37, v37
	v_exp_f32_e32 v38, v38
	v_exp_f32_e32 v39, v39
	v_exp_f32_e32 v40, v40
	v_exp_f32_e32 v41, v41
	v_exp_f32_e32 v42, v42
	v_exp_f32_e32 v43, v43
	v_exp_f32_e32 v44, v44
	v_exp_f32_e32 v45, v45
	v_exp_f32_e32 v46, v46
	v_exp_f32_e32 v47, v47
	v_cvt_pk_bf16_f32 v64, v32, v33
	v_cvt_pk_bf16_f32 v65, v34, v35
	v_cvt_pk_bf16_f32 v66, v36, v37
	v_cvt_pk_bf16_f32 v67, v38, v39
	v_cvt_pk_bf16_f32 v68, v40, v41
	v_cvt_pk_bf16_f32 v69, v42, v43
	v_cvt_pk_bf16_f32 v70, v44, v45
	v_cvt_pk_bf16_f32 v71, v46, v47
	v_pk_add_f32 v[232:233], v[232:233], v[32:33]
	v_pk_add_f32 v[232:233], v[232:233], v[34:35]
	v_pk_add_f32 v[232:233], v[232:233], v[36:37]
	v_pk_add_f32 v[232:233], v[232:233], v[38:39]
	v_pk_add_f32 v[232:233], v[232:233], v[40:41]
	v_pk_add_f32 v[232:233], v[232:233], v[42:43]
	v_pk_add_f32 v[232:233], v[232:233], v[44:45]
	v_pk_add_f32 v[232:233], v[232:233], v[46:47]
	s_waitcnt lgkmcnt(12)
	v_mfma_f32_32x32x16_bf16 v[0:15], v[64:67], v[72:75], v[0:15]
	v_mfma_f32_32x32x16_bf16 v[16:31], v[64:67], v[76:79], v[16:31]
	v_mfma_f32_32x32x16_bf16 v[0:15], v[68:71], v[220:223], v[0:15]
	v_mfma_f32_32x32x16_bf16 v[16:31], v[68:71], v[224:227], v[16:31]
	global_load_dwordx4 v[156:159], v235, s[84:85]
	global_load_dwordx4 v[160:163], v236, s[84:85]
	global_load_dwordx4 v[164:167], v237, s[84:85]
	global_load_dwordx4 v[168:171], v238, s[84:85]
	global_load_dwordx4 v[172:175], v100, s[84:85] offset:768
	global_load_dwordx4 v[176:179], v149, s[84:85] offset:768
	global_load_dwordx4 v[180:183], v100, s[84:85] offset:832
	global_load_dwordx4 v[184:187], v149, s[84:85] offset:832
	s_add_u32 s84, s84, 0x30000
	s_addc_u32 s85, s85, 0
	ds_read2_b32 v[32:33], v115 offset0:136 offset1:137
	ds_read2_b32 v[34:35], v115 offset0:138 offset1:139
	ds_read2_b32 v[36:37], v115 offset0:144 offset1:145
	ds_read2_b32 v[38:39], v115 offset0:146 offset1:147
	ds_read2_b32 v[40:41], v115 offset0:153 offset1:154
	ds_read2_b32 v[42:43], v115 offset0:155 offset1:156
	ds_read2_b32 v[44:45], v115 offset0:161 offset1:162
	ds_read2_b32 v[46:47], v115 offset0:163 offset1:164
	s_waitcnt lgkmcnt(0)
	v_mfma_f32_32x32x16_bf16 v[32:47], v[188:191], v[48:51], v[32:47]
	ds_read_b64_tr_b16 v[72:73], v231
	ds_read_b64_tr_b16 v[74:75], v231 offset:512
	ds_read_b64_tr_b16 v[76:77], v231 offset:2048
	ds_read_b64_tr_b16 v[78:79], v231 offset:2560
	ds_read_b64_tr_b16 v[220:221], v231 offset:1024
	ds_read_b64_tr_b16 v[222:223], v231 offset:1536
	ds_read_b64_tr_b16 v[224:225], v231 offset:3072
	ds_read_b64_tr_b16 v[226:227], v231 offset:3584
	s_waitcnt vmcnt(8)
	ds_write_b128 v247, v[116:119]
	ds_write_b128 v247, v[120:123] offset:1024
	ds_write_b128 v247, v[124:127] offset:2048
	ds_write_b128 v247, v[128:131] offset:3072
	ds_read_b128 v[116:119], v248
	ds_read_b128 v[120:123], v249
	ds_read_b128 v[124:127], v250
	ds_read_b128 v[128:131], v251
	ds_write_b128 v112, v[132:135]
	ds_write_b128 v112, v[136:139] offset:1024
	ds_write_b128 v112, v[140:143] offset:2048
	ds_write_b128 v112, v[144:147] offset:3072
	v_mfma_f32_32x32x16_bf16 v[32:47], v[192:195], v[52:55], v[32:47]
	v_mfma_f32_32x32x16_bf16 v[32:47], v[196:199], v[56:59], v[32:47]
	v_mfma_f32_32x32x16_bf16 v[32:47], v[200:203], v[60:63], v[32:47]
	s_nop 11
	v_exp_f32_e32 v32, v32
	v_exp_f32_e32 v33, v33
	v_exp_f32_e32 v34, v34
	v_exp_f32_e32 v35, v35
	v_exp_f32_e32 v36, v36
	v_exp_f32_e32 v37, v37
	v_exp_f32_e32 v38, v38
	v_exp_f32_e32 v39, v39
	v_exp_f32_e32 v40, v40
	v_exp_f32_e32 v41, v41
	v_exp_f32_e32 v42, v42
	v_exp_f32_e32 v43, v43
	v_exp_f32_e32 v44, v44
	v_exp_f32_e32 v45, v45
	v_exp_f32_e32 v46, v46
	v_exp_f32_e32 v47, v47
	v_cvt_pk_bf16_f32 v64, v32, v33
	v_cvt_pk_bf16_f32 v65, v34, v35
	v_cvt_pk_bf16_f32 v66, v36, v37
	v_cvt_pk_bf16_f32 v67, v38, v39
	v_cvt_pk_bf16_f32 v68, v40, v41
	v_cvt_pk_bf16_f32 v69, v42, v43
	v_cvt_pk_bf16_f32 v70, v44, v45
	v_cvt_pk_bf16_f32 v71, v46, v47
	v_pk_add_f32 v[232:233], v[232:233], v[32:33]
	v_pk_add_f32 v[232:233], v[232:233], v[34:35]
	v_pk_add_f32 v[232:233], v[232:233], v[36:37]
	v_pk_add_f32 v[232:233], v[232:233], v[38:39]
	v_pk_add_f32 v[232:233], v[232:233], v[40:41]
	v_pk_add_f32 v[232:233], v[232:233], v[42:43]
	v_pk_add_f32 v[232:233], v[232:233], v[44:45]
	v_pk_add_f32 v[232:233], v[232:233], v[46:47]
	s_waitcnt lgkmcnt(12)
	v_mfma_f32_32x32x16_bf16 v[0:15], v[64:67], v[72:75], v[0:15]
	v_mfma_f32_32x32x16_bf16 v[16:31], v[64:67], v[76:79], v[16:31]
	v_mfma_f32_32x32x16_bf16 v[0:15], v[68:71], v[220:223], v[0:15]
	v_mfma_f32_32x32x16_bf16 v[16:31], v[68:71], v[224:227], v[16:31]
	global_load_dwordx4 v[188:191], v235, s[84:85]
	global_load_dwordx4 v[192:195], v236, s[84:85]
	global_load_dwordx4 v[196:199], v237, s[84:85]
	global_load_dwordx4 v[200:203], v238, s[84:85]
	global_load_dwordx4 v[204:207], v100, s[84:85] offset:768
	global_load_dwordx4 v[208:211], v149, s[84:85] offset:768
	global_load_dwordx4 v[212:215], v100, s[84:85] offset:832
	global_load_dwordx4 v[216:219], v149, s[84:85] offset:832
	s_add_u32 s84, s84, 0x30000
	s_addc_u32 s85, s85, 0
	ds_read2_b32 v[32:33], v115 offset0:170 offset1:171
	ds_read2_b32 v[34:35], v115 offset0:172 offset1:173
	ds_read2_b32 v[36:37], v115 offset0:178 offset1:179
	ds_read2_b32 v[38:39], v115 offset0:180 offset1:181
	ds_read2_b32 v[40:41], v115 offset0:187 offset1:188
	ds_read2_b32 v[42:43], v115 offset0:189 offset1:190
	ds_read2_b32 v[44:45], v115 offset0:195 offset1:196
	ds_read2_b32 v[46:47], v115 offset0:197 offset1:198
	s_waitcnt lgkmcnt(0)
	v_mfma_f32_32x32x16_bf16 v[32:47], v[116:119], v[48:51], v[32:47]
	ds_read_b64_tr_b16 v[72:73], v231
	ds_read_b64_tr_b16 v[74:75], v231 offset:512
	ds_read_b64_tr_b16 v[76:77], v231 offset:2048
	ds_read_b64_tr_b16 v[78:79], v231 offset:2560
	ds_read_b64_tr_b16 v[220:221], v231 offset:1024
	ds_read_b64_tr_b16 v[222:223], v231 offset:1536
	ds_read_b64_tr_b16 v[224:225], v231 offset:3072
	ds_read_b64_tr_b16 v[226:227], v231 offset:3584
	s_waitcnt vmcnt(8)
	ds_write_b128 v247, v[156:159]
	ds_write_b128 v247, v[160:163] offset:1024
	ds_write_b128 v247, v[164:167] offset:2048
	ds_write_b128 v247, v[168:171] offset:3072
	ds_read_b128 v[156:159], v248
	ds_read_b128 v[160:163], v249
	ds_read_b128 v[164:167], v250
	ds_read_b128 v[168:171], v251
	ds_write_b128 v112, v[172:175]
	ds_write_b128 v112, v[176:179] offset:1024
	ds_write_b128 v112, v[180:183] offset:2048
	ds_write_b128 v112, v[184:187] offset:3072
	v_mfma_f32_32x32x16_bf16 v[32:47], v[120:123], v[52:55], v[32:47]
	v_mfma_f32_32x32x16_bf16 v[32:47], v[124:127], v[56:59], v[32:47]
	v_mfma_f32_32x32x16_bf16 v[32:47], v[128:131], v[60:63], v[32:47]
	s_nop 11
	v_exp_f32_e32 v32, v32
	v_exp_f32_e32 v33, v33
	v_exp_f32_e32 v34, v34
	v_exp_f32_e32 v35, v35
	v_exp_f32_e32 v36, v36
	v_exp_f32_e32 v37, v37
	v_exp_f32_e32 v38, v38
	v_exp_f32_e32 v39, v39
	v_exp_f32_e32 v40, v40
	v_exp_f32_e32 v41, v41
	v_exp_f32_e32 v42, v42
	v_exp_f32_e32 v43, v43
	v_exp_f32_e32 v44, v44
	v_exp_f32_e32 v45, v45
	v_exp_f32_e32 v46, v46
	v_exp_f32_e32 v47, v47
	v_cvt_pk_bf16_f32 v64, v32, v33
	v_cvt_pk_bf16_f32 v65, v34, v35
	v_cvt_pk_bf16_f32 v66, v36, v37
	v_cvt_pk_bf16_f32 v67, v38, v39
	v_cvt_pk_bf16_f32 v68, v40, v41
	v_cvt_pk_bf16_f32 v69, v42, v43
	v_cvt_pk_bf16_f32 v70, v44, v45
	v_cvt_pk_bf16_f32 v71, v46, v47
	v_pk_add_f32 v[232:233], v[232:233], v[32:33]
	v_pk_add_f32 v[232:233], v[232:233], v[34:35]
	v_pk_add_f32 v[232:233], v[232:233], v[36:37]
	v_pk_add_f32 v[232:233], v[232:233], v[38:39]
	v_pk_add_f32 v[232:233], v[232:233], v[40:41]
	v_pk_add_f32 v[232:233], v[232:233], v[42:43]
	v_pk_add_f32 v[232:233], v[232:233], v[44:45]
	v_pk_add_f32 v[232:233], v[232:233], v[46:47]
	s_waitcnt lgkmcnt(12)
	v_mfma_f32_32x32x16_bf16 v[0:15], v[64:67], v[72:75], v[0:15]
	v_mfma_f32_32x32x16_bf16 v[16:31], v[64:67], v[76:79], v[16:31]
	v_mfma_f32_32x32x16_bf16 v[0:15], v[68:71], v[220:223], v[0:15]
	v_mfma_f32_32x32x16_bf16 v[16:31], v[68:71], v[224:227], v[16:31]
	global_load_dwordx4 v[116:119], v235, s[84:85]
	global_load_dwordx4 v[120:123], v236, s[84:85]
	global_load_dwordx4 v[124:127], v237, s[84:85]
	global_load_dwordx4 v[128:131], v238, s[84:85]
	global_load_dwordx4 v[132:135], v100, s[84:85] offset:768
	global_load_dwordx4 v[136:139], v149, s[84:85] offset:768
	global_load_dwordx4 v[140:143], v100, s[84:85] offset:832
	global_load_dwordx4 v[144:147], v149, s[84:85] offset:832
	s_add_u32 s84, s84, 0x30000
	s_addc_u32 s85, s85, 0
	ds_read2_b32 v[32:33], v115 offset0:204 offset1:205
	ds_read2_b32 v[34:35], v115 offset0:206 offset1:207
	ds_read2_b32 v[36:37], v115 offset0:212 offset1:213
	ds_read2_b32 v[38:39], v115 offset0:214 offset1:215
	ds_read2_b32 v[40:41], v115 offset0:221 offset1:222
	ds_read2_b32 v[42:43], v115 offset0:223 offset1:224
	ds_read2_b32 v[44:45], v115 offset0:229 offset1:230
	ds_read2_b32 v[46:47], v115 offset0:231 offset1:232
	s_waitcnt lgkmcnt(0)
	v_mfma_f32_32x32x16_bf16 v[32:47], v[156:159], v[48:51], v[32:47]
	ds_read_b64_tr_b16 v[72:73], v231
	ds_read_b64_tr_b16 v[74:75], v231 offset:512
	ds_read_b64_tr_b16 v[76:77], v231 offset:2048
	ds_read_b64_tr_b16 v[78:79], v231 offset:2560
	ds_read_b64_tr_b16 v[220:221], v231 offset:1024
	ds_read_b64_tr_b16 v[222:223], v231 offset:1536
	ds_read_b64_tr_b16 v[224:225], v231 offset:3072
	ds_read_b64_tr_b16 v[226:227], v231 offset:3584
	s_waitcnt vmcnt(8)
	ds_write_b128 v247, v[188:191]
	ds_write_b128 v247, v[192:195] offset:1024
	ds_write_b128 v247, v[196:199] offset:2048
	ds_write_b128 v247, v[200:203] offset:3072
	ds_read_b128 v[188:191], v248
	ds_read_b128 v[192:195], v249
	ds_read_b128 v[196:199], v250
	ds_read_b128 v[200:203], v251
	ds_write_b128 v112, v[204:207]
	ds_write_b128 v112, v[208:211] offset:1024
	ds_write_b128 v112, v[212:215] offset:2048
	ds_write_b128 v112, v[216:219] offset:3072
	v_mfma_f32_32x32x16_bf16 v[32:47], v[160:163], v[52:55], v[32:47]
	v_mfma_f32_32x32x16_bf16 v[32:47], v[164:167], v[56:59], v[32:47]
	v_mfma_f32_32x32x16_bf16 v[32:47], v[168:171], v[60:63], v[32:47]
	s_nop 11
	v_exp_f32_e32 v32, v32
	v_exp_f32_e32 v33, v33
	v_exp_f32_e32 v34, v34
	v_exp_f32_e32 v35, v35
	v_exp_f32_e32 v36, v36
	v_exp_f32_e32 v37, v37
	v_exp_f32_e32 v38, v38
	v_exp_f32_e32 v39, v39
	v_exp_f32_e32 v40, v40
	v_exp_f32_e32 v41, v41
	v_exp_f32_e32 v42, v42
	v_exp_f32_e32 v43, v43
	v_exp_f32_e32 v44, v44
	v_exp_f32_e32 v45, v45
	v_exp_f32_e32 v46, v46
	v_exp_f32_e32 v47, v47
	v_cvt_pk_bf16_f32 v64, v32, v33
	v_cvt_pk_bf16_f32 v65, v34, v35
	v_cvt_pk_bf16_f32 v66, v36, v37
	v_cvt_pk_bf16_f32 v67, v38, v39
	v_cvt_pk_bf16_f32 v68, v40, v41
	v_cvt_pk_bf16_f32 v69, v42, v43
	v_cvt_pk_bf16_f32 v70, v44, v45
	v_cvt_pk_bf16_f32 v71, v46, v47
	v_pk_add_f32 v[232:233], v[232:233], v[32:33]
	v_pk_add_f32 v[232:233], v[232:233], v[34:35]
	v_pk_add_f32 v[232:233], v[232:233], v[36:37]
	v_pk_add_f32 v[232:233], v[232:233], v[38:39]
	v_pk_add_f32 v[232:233], v[232:233], v[40:41]
	v_pk_add_f32 v[232:233], v[232:233], v[42:43]
	v_pk_add_f32 v[232:233], v[232:233], v[44:45]
	v_pk_add_f32 v[232:233], v[232:233], v[46:47]
	s_waitcnt lgkmcnt(12)
	v_mfma_f32_32x32x16_bf16 v[0:15], v[64:67], v[72:75], v[0:15]
	v_mfma_f32_32x32x16_bf16 v[16:31], v[64:67], v[76:79], v[16:31]
	v_mfma_f32_32x32x16_bf16 v[0:15], v[68:71], v[220:223], v[0:15]
	v_mfma_f32_32x32x16_bf16 v[16:31], v[68:71], v[224:227], v[16:31]
	global_load_dwordx4 v[156:159], v235, s[84:85]
	global_load_dwordx4 v[160:163], v236, s[84:85]
	global_load_dwordx4 v[164:167], v237, s[84:85]
	global_load_dwordx4 v[168:171], v238, s[84:85]
	global_load_dwordx4 v[172:175], v100, s[84:85] offset:768
	global_load_dwordx4 v[176:179], v149, s[84:85] offset:768
	global_load_dwordx4 v[180:183], v100, s[84:85] offset:832
	global_load_dwordx4 v[184:187], v149, s[84:85] offset:832
	s_add_u32 s84, s84, 0x30000
	s_addc_u32 s85, s85, 0
	v_add_u32_e32 v115, 952, v115
	ds_read2_b32 v[32:33], v115 offset0:0 offset1:1
	ds_read2_b32 v[34:35], v115 offset0:2 offset1:3
	ds_read2_b32 v[36:37], v115 offset0:8 offset1:9
	ds_read2_b32 v[38:39], v115 offset0:10 offset1:11
	ds_read2_b32 v[40:41], v115 offset0:17 offset1:18
	ds_read2_b32 v[42:43], v115 offset0:19 offset1:20
	ds_read2_b32 v[44:45], v115 offset0:25 offset1:26
	ds_read2_b32 v[46:47], v115 offset0:27 offset1:28
	s_waitcnt lgkmcnt(0)
	v_mfma_f32_32x32x16_bf16 v[32:47], v[188:191], v[48:51], v[32:47]
	ds_read_b64_tr_b16 v[72:73], v231
	ds_read_b64_tr_b16 v[74:75], v231 offset:512
	ds_read_b64_tr_b16 v[76:77], v231 offset:2048
	ds_read_b64_tr_b16 v[78:79], v231 offset:2560
	ds_read_b64_tr_b16 v[220:221], v231 offset:1024
	ds_read_b64_tr_b16 v[222:223], v231 offset:1536
	ds_read_b64_tr_b16 v[224:225], v231 offset:3072
	ds_read_b64_tr_b16 v[226:227], v231 offset:3584
	s_waitcnt vmcnt(8)
	ds_write_b128 v247, v[116:119]
	ds_write_b128 v247, v[120:123] offset:1024
	ds_write_b128 v247, v[124:127] offset:2048
	ds_write_b128 v247, v[128:131] offset:3072
	ds_read_b128 v[116:119], v248
	ds_read_b128 v[120:123], v249
	ds_read_b128 v[124:127], v250
	ds_read_b128 v[128:131], v251
	ds_write_b128 v112, v[132:135]
	ds_write_b128 v112, v[136:139] offset:1024
	ds_write_b128 v112, v[140:143] offset:2048
	ds_write_b128 v112, v[144:147] offset:3072
	v_mfma_f32_32x32x16_bf16 v[32:47], v[192:195], v[52:55], v[32:47]
	v_mfma_f32_32x32x16_bf16 v[32:47], v[196:199], v[56:59], v[32:47]
	v_mfma_f32_32x32x16_bf16 v[32:47], v[200:203], v[60:63], v[32:47]
	s_nop 11
	v_exp_f32_e32 v32, v32
	v_exp_f32_e32 v33, v33
	v_exp_f32_e32 v34, v34
	v_exp_f32_e32 v35, v35
	v_exp_f32_e32 v36, v36
	v_exp_f32_e32 v37, v37
	v_exp_f32_e32 v38, v38
	v_exp_f32_e32 v39, v39
	v_exp_f32_e32 v40, v40
	v_exp_f32_e32 v41, v41
	v_exp_f32_e32 v42, v42
	v_exp_f32_e32 v43, v43
	v_exp_f32_e32 v44, v44
	v_exp_f32_e32 v45, v45
	v_exp_f32_e32 v46, v46
	v_exp_f32_e32 v47, v47
	v_cvt_pk_bf16_f32 v64, v32, v33
	v_cvt_pk_bf16_f32 v65, v34, v35
	v_cvt_pk_bf16_f32 v66, v36, v37
	v_cvt_pk_bf16_f32 v67, v38, v39
	v_cvt_pk_bf16_f32 v68, v40, v41
	v_cvt_pk_bf16_f32 v69, v42, v43
	v_cvt_pk_bf16_f32 v70, v44, v45
	v_cvt_pk_bf16_f32 v71, v46, v47
	v_pk_add_f32 v[232:233], v[232:233], v[32:33]
	v_pk_add_f32 v[232:233], v[232:233], v[34:35]
	v_pk_add_f32 v[232:233], v[232:233], v[36:37]
	v_pk_add_f32 v[232:233], v[232:233], v[38:39]
	v_pk_add_f32 v[232:233], v[232:233], v[40:41]
	v_pk_add_f32 v[232:233], v[232:233], v[42:43]
	v_pk_add_f32 v[232:233], v[232:233], v[44:45]
	v_pk_add_f32 v[232:233], v[232:233], v[46:47]
	s_waitcnt lgkmcnt(12)
	v_mfma_f32_32x32x16_bf16 v[0:15], v[64:67], v[72:75], v[0:15]
	v_mfma_f32_32x32x16_bf16 v[16:31], v[64:67], v[76:79], v[16:31]
	v_mfma_f32_32x32x16_bf16 v[0:15], v[68:71], v[220:223], v[0:15]
	v_mfma_f32_32x32x16_bf16 v[16:31], v[68:71], v[224:227], v[16:31]
	global_load_dwordx4 v[188:191], v235, s[84:85]
	global_load_dwordx4 v[192:195], v236, s[84:85]
	global_load_dwordx4 v[196:199], v237, s[84:85]
	global_load_dwordx4 v[200:203], v238, s[84:85]
	global_load_dwordx4 v[204:207], v100, s[84:85] offset:768
	global_load_dwordx4 v[208:211], v149, s[84:85] offset:768
	global_load_dwordx4 v[212:215], v100, s[84:85] offset:832
	global_load_dwordx4 v[216:219], v149, s[84:85] offset:832
	s_add_u32 s84, s84, 0x30000
	s_addc_u32 s85, s85, 0
	ds_read2_b32 v[32:33], v115 offset0:34 offset1:35
	ds_read2_b32 v[34:35], v115 offset0:36 offset1:37
	ds_read2_b32 v[36:37], v115 offset0:42 offset1:43
	ds_read2_b32 v[38:39], v115 offset0:44 offset1:45
	ds_read2_b32 v[40:41], v115 offset0:51 offset1:52
	ds_read2_b32 v[42:43], v115 offset0:53 offset1:54
	ds_read2_b32 v[44:45], v115 offset0:59 offset1:60
	ds_read2_b32 v[46:47], v115 offset0:61 offset1:62
	s_waitcnt lgkmcnt(0)
	v_mfma_f32_32x32x16_bf16 v[32:47], v[116:119], v[48:51], v[32:47]
	ds_read_b64_tr_b16 v[72:73], v231
	ds_read_b64_tr_b16 v[74:75], v231 offset:512
	ds_read_b64_tr_b16 v[76:77], v231 offset:2048
	ds_read_b64_tr_b16 v[78:79], v231 offset:2560
	ds_read_b64_tr_b16 v[220:221], v231 offset:1024
	ds_read_b64_tr_b16 v[222:223], v231 offset:1536
	ds_read_b64_tr_b16 v[224:225], v231 offset:3072
	ds_read_b64_tr_b16 v[226:227], v231 offset:3584
	s_waitcnt vmcnt(8)
	ds_write_b128 v247, v[156:159]
	ds_write_b128 v247, v[160:163] offset:1024
	ds_write_b128 v247, v[164:167] offset:2048
	ds_write_b128 v247, v[168:171] offset:3072
	ds_read_b128 v[156:159], v248
	ds_read_b128 v[160:163], v249
	ds_read_b128 v[164:167], v250
	ds_read_b128 v[168:171], v251
	ds_write_b128 v112, v[172:175]
	ds_write_b128 v112, v[176:179] offset:1024
	ds_write_b128 v112, v[180:183] offset:2048
	ds_write_b128 v112, v[184:187] offset:3072
	v_mfma_f32_32x32x16_bf16 v[32:47], v[120:123], v[52:55], v[32:47]
	v_mfma_f32_32x32x16_bf16 v[32:47], v[124:127], v[56:59], v[32:47]
	v_mfma_f32_32x32x16_bf16 v[32:47], v[128:131], v[60:63], v[32:47]
	s_nop 11
	v_exp_f32_e32 v32, v32
	v_exp_f32_e32 v33, v33
	v_exp_f32_e32 v34, v34
	v_exp_f32_e32 v35, v35
	v_exp_f32_e32 v36, v36
	v_exp_f32_e32 v37, v37
	v_exp_f32_e32 v38, v38
	v_exp_f32_e32 v39, v39
	v_exp_f32_e32 v40, v40
	v_exp_f32_e32 v41, v41
	v_exp_f32_e32 v42, v42
	v_exp_f32_e32 v43, v43
	v_exp_f32_e32 v44, v44
	v_exp_f32_e32 v45, v45
	v_exp_f32_e32 v46, v46
	v_exp_f32_e32 v47, v47
	v_cvt_pk_bf16_f32 v64, v32, v33
	v_cvt_pk_bf16_f32 v65, v34, v35
	v_cvt_pk_bf16_f32 v66, v36, v37
	v_cvt_pk_bf16_f32 v67, v38, v39
	v_cvt_pk_bf16_f32 v68, v40, v41
	v_cvt_pk_bf16_f32 v69, v42, v43
	v_cvt_pk_bf16_f32 v70, v44, v45
	v_cvt_pk_bf16_f32 v71, v46, v47
	v_pk_add_f32 v[232:233], v[232:233], v[32:33]
	v_pk_add_f32 v[232:233], v[232:233], v[34:35]
	v_pk_add_f32 v[232:233], v[232:233], v[36:37]
	v_pk_add_f32 v[232:233], v[232:233], v[38:39]
	v_pk_add_f32 v[232:233], v[232:233], v[40:41]
	v_pk_add_f32 v[232:233], v[232:233], v[42:43]
	v_pk_add_f32 v[232:233], v[232:233], v[44:45]
	v_pk_add_f32 v[232:233], v[232:233], v[46:47]
	s_waitcnt lgkmcnt(12)
	v_mfma_f32_32x32x16_bf16 v[0:15], v[64:67], v[72:75], v[0:15]
	v_mfma_f32_32x32x16_bf16 v[16:31], v[64:67], v[76:79], v[16:31]
	v_mfma_f32_32x32x16_bf16 v[0:15], v[68:71], v[220:223], v[0:15]
	v_mfma_f32_32x32x16_bf16 v[16:31], v[68:71], v[224:227], v[16:31]
	global_load_dwordx4 v[116:119], v235, s[84:85]
	global_load_dwordx4 v[120:123], v236, s[84:85]
	global_load_dwordx4 v[124:127], v237, s[84:85]
	global_load_dwordx4 v[128:131], v238, s[84:85]
	global_load_dwordx4 v[132:135], v100, s[84:85] offset:768
	global_load_dwordx4 v[136:139], v149, s[84:85] offset:768
	global_load_dwordx4 v[140:143], v100, s[84:85] offset:832
	global_load_dwordx4 v[144:147], v149, s[84:85] offset:832
	s_add_u32 s84, s84, 0x30000
	s_addc_u32 s85, s85, 0
	ds_read2_b32 v[32:33], v115 offset0:68 offset1:69
	ds_read2_b32 v[34:35], v115 offset0:70 offset1:71
	ds_read2_b32 v[36:37], v115 offset0:76 offset1:77
	ds_read2_b32 v[38:39], v115 offset0:78 offset1:79
	ds_read2_b32 v[40:41], v115 offset0:85 offset1:86
	ds_read2_b32 v[42:43], v115 offset0:87 offset1:88
	ds_read2_b32 v[44:45], v115 offset0:93 offset1:94
	ds_read2_b32 v[46:47], v115 offset0:95 offset1:96
	s_waitcnt lgkmcnt(0)
	v_mfma_f32_32x32x16_bf16 v[32:47], v[156:159], v[48:51], v[32:47]
	ds_read_b64_tr_b16 v[72:73], v231
	ds_read_b64_tr_b16 v[74:75], v231 offset:512
	ds_read_b64_tr_b16 v[76:77], v231 offset:2048
	ds_read_b64_tr_b16 v[78:79], v231 offset:2560
	ds_read_b64_tr_b16 v[220:221], v231 offset:1024
	ds_read_b64_tr_b16 v[222:223], v231 offset:1536
	ds_read_b64_tr_b16 v[224:225], v231 offset:3072
	ds_read_b64_tr_b16 v[226:227], v231 offset:3584
	s_waitcnt vmcnt(8)
	ds_write_b128 v247, v[188:191]
	ds_write_b128 v247, v[192:195] offset:1024
	ds_write_b128 v247, v[196:199] offset:2048
	ds_write_b128 v247, v[200:203] offset:3072
	ds_read_b128 v[188:191], v248
	ds_read_b128 v[192:195], v249
	ds_read_b128 v[196:199], v250
	ds_read_b128 v[200:203], v251
	ds_write_b128 v112, v[204:207]
	ds_write_b128 v112, v[208:211] offset:1024
	ds_write_b128 v112, v[212:215] offset:2048
	ds_write_b128 v112, v[216:219] offset:3072
	v_mfma_f32_32x32x16_bf16 v[32:47], v[160:163], v[52:55], v[32:47]
	v_mfma_f32_32x32x16_bf16 v[32:47], v[164:167], v[56:59], v[32:47]
	v_mfma_f32_32x32x16_bf16 v[32:47], v[168:171], v[60:63], v[32:47]
	s_nop 11
	v_exp_f32_e32 v32, v32
	v_exp_f32_e32 v33, v33
	v_exp_f32_e32 v34, v34
	v_exp_f32_e32 v35, v35
	v_exp_f32_e32 v36, v36
	v_exp_f32_e32 v37, v37
	v_exp_f32_e32 v38, v38
	v_exp_f32_e32 v39, v39
	v_exp_f32_e32 v40, v40
	v_exp_f32_e32 v41, v41
	v_exp_f32_e32 v42, v42
	v_exp_f32_e32 v43, v43
	v_exp_f32_e32 v44, v44
	v_exp_f32_e32 v45, v45
	v_exp_f32_e32 v46, v46
	v_exp_f32_e32 v47, v47
	v_cvt_pk_bf16_f32 v64, v32, v33
	v_cvt_pk_bf16_f32 v65, v34, v35
	v_cvt_pk_bf16_f32 v66, v36, v37
	v_cvt_pk_bf16_f32 v67, v38, v39
	v_cvt_pk_bf16_f32 v68, v40, v41
	v_cvt_pk_bf16_f32 v69, v42, v43
	v_cvt_pk_bf16_f32 v70, v44, v45
	v_cvt_pk_bf16_f32 v71, v46, v47
	v_pk_add_f32 v[232:233], v[232:233], v[32:33]
	v_pk_add_f32 v[232:233], v[232:233], v[34:35]
	v_pk_add_f32 v[232:233], v[232:233], v[36:37]
	v_pk_add_f32 v[232:233], v[232:233], v[38:39]
	v_pk_add_f32 v[232:233], v[232:233], v[40:41]
	v_pk_add_f32 v[232:233], v[232:233], v[42:43]
	v_pk_add_f32 v[232:233], v[232:233], v[44:45]
	v_pk_add_f32 v[232:233], v[232:233], v[46:47]
	s_waitcnt lgkmcnt(12)
	v_mfma_f32_32x32x16_bf16 v[0:15], v[64:67], v[72:75], v[0:15]
	v_mfma_f32_32x32x16_bf16 v[16:31], v[64:67], v[76:79], v[16:31]
	v_mfma_f32_32x32x16_bf16 v[0:15], v[68:71], v[220:223], v[0:15]
	v_mfma_f32_32x32x16_bf16 v[16:31], v[68:71], v[224:227], v[16:31]
	global_load_dwordx4 v[156:159], v235, s[84:85]
	global_load_dwordx4 v[160:163], v236, s[84:85]
	global_load_dwordx4 v[164:167], v237, s[84:85]
	global_load_dwordx4 v[168:171], v238, s[84:85]
	global_load_dwordx4 v[172:175], v100, s[84:85] offset:768
	global_load_dwordx4 v[176:179], v149, s[84:85] offset:768
	global_load_dwordx4 v[180:183], v100, s[84:85] offset:832
	global_load_dwordx4 v[184:187], v149, s[84:85] offset:832
	ds_read2_b32 v[32:33], v115 offset0:102 offset1:103
	ds_read2_b32 v[34:35], v115 offset0:104 offset1:105
	ds_read2_b32 v[36:37], v115 offset0:110 offset1:111
	ds_read2_b32 v[38:39], v115 offset0:112 offset1:113
	ds_read2_b32 v[40:41], v115 offset0:119 offset1:120
	ds_read2_b32 v[42:43], v115 offset0:121 offset1:122
	ds_read2_b32 v[44:45], v115 offset0:127 offset1:128
	ds_read2_b32 v[46:47], v115 offset0:129 offset1:130
	s_waitcnt lgkmcnt(0)
	v_mfma_f32_32x32x16_bf16 v[32:47], v[188:191], v[48:51], v[32:47]
	ds_read_b64_tr_b16 v[72:73], v231
	ds_read_b64_tr_b16 v[74:75], v231 offset:512
	ds_read_b64_tr_b16 v[76:77], v231 offset:2048
	ds_read_b64_tr_b16 v[78:79], v231 offset:2560
	ds_read_b64_tr_b16 v[220:221], v231 offset:1024
	ds_read_b64_tr_b16 v[222:223], v231 offset:1536
	ds_read_b64_tr_b16 v[224:225], v231 offset:3072
	ds_read_b64_tr_b16 v[226:227], v231 offset:3584
	s_waitcnt vmcnt(8)
	ds_write_b128 v247, v[116:119]
	ds_write_b128 v247, v[120:123] offset:1024
	ds_write_b128 v247, v[124:127] offset:2048
	ds_write_b128 v247, v[128:131] offset:3072
	ds_read_b128 v[116:119], v248
	ds_read_b128 v[120:123], v249
	ds_read_b128 v[124:127], v250
	ds_read_b128 v[128:131], v251
	ds_write_b128 v112, v[132:135]
	ds_write_b128 v112, v[136:139] offset:1024
	ds_write_b128 v112, v[140:143] offset:2048
	ds_write_b128 v112, v[144:147] offset:3072
	v_mfma_f32_32x32x16_bf16 v[32:47], v[192:195], v[52:55], v[32:47]
	v_mfma_f32_32x32x16_bf16 v[32:47], v[196:199], v[56:59], v[32:47]
	v_mfma_f32_32x32x16_bf16 v[32:47], v[200:203], v[60:63], v[32:47]
	s_nop 11
	v_exp_f32_e32 v32, v32
	v_exp_f32_e32 v33, v33
	v_exp_f32_e32 v34, v34
	v_exp_f32_e32 v35, v35
	v_exp_f32_e32 v36, v36
	v_exp_f32_e32 v37, v37
	v_exp_f32_e32 v38, v38
	v_exp_f32_e32 v39, v39
	v_exp_f32_e32 v40, v40
	v_exp_f32_e32 v41, v41
	v_exp_f32_e32 v42, v42
	v_exp_f32_e32 v43, v43
	v_exp_f32_e32 v44, v44
	v_exp_f32_e32 v45, v45
	v_exp_f32_e32 v46, v46
	v_exp_f32_e32 v47, v47
	v_cvt_pk_bf16_f32 v64, v32, v33
	v_cvt_pk_bf16_f32 v65, v34, v35
	v_cvt_pk_bf16_f32 v66, v36, v37
	v_cvt_pk_bf16_f32 v67, v38, v39
	v_cvt_pk_bf16_f32 v68, v40, v41
	v_cvt_pk_bf16_f32 v69, v42, v43
	v_cvt_pk_bf16_f32 v70, v44, v45
	v_cvt_pk_bf16_f32 v71, v46, v47
	v_pk_add_f32 v[232:233], v[232:233], v[32:33]
	v_pk_add_f32 v[232:233], v[232:233], v[34:35]
	v_pk_add_f32 v[232:233], v[232:233], v[36:37]
	v_pk_add_f32 v[232:233], v[232:233], v[38:39]
	v_pk_add_f32 v[232:233], v[232:233], v[40:41]
	v_pk_add_f32 v[232:233], v[232:233], v[42:43]
	v_pk_add_f32 v[232:233], v[232:233], v[44:45]
	v_pk_add_f32 v[232:233], v[232:233], v[46:47]
	s_waitcnt lgkmcnt(12)
	v_mfma_f32_32x32x16_bf16 v[0:15], v[64:67], v[72:75], v[0:15]
	v_mfma_f32_32x32x16_bf16 v[16:31], v[64:67], v[76:79], v[16:31]
	v_mfma_f32_32x32x16_bf16 v[0:15], v[68:71], v[220:223], v[0:15]
	v_mfma_f32_32x32x16_bf16 v[16:31], v[68:71], v[224:227], v[16:31]
	global_load_dwordx4 v[188:191], v239, s[86:87]
	global_load_dwordx4 v[192:195], v240, s[86:87]
	global_load_dwordx4 v[196:199], v241, s[86:87]
	global_load_dwordx4 v[200:203], v242, s[86:87]
	global_load_dwordx4 v[204:207], v101, s[86:87] offset:768
	global_load_dwordx4 v[208:211], v150, s[86:87] offset:768
	global_load_dwordx4 v[212:215], v101, s[86:87] offset:832
	global_load_dwordx4 v[216:219], v150, s[86:87] offset:832
	s_add_u32 s86, s86, 0xc0000
	s_addc_u32 s87, s87, 0
	ds_read2_b32 v[32:33], v115 offset0:136 offset1:137
	ds_read2_b32 v[34:35], v115 offset0:138 offset1:139
	ds_read2_b32 v[36:37], v115 offset0:144 offset1:145
	ds_read2_b32 v[38:39], v115 offset0:146 offset1:147
	ds_read2_b32 v[40:41], v115 offset0:153 offset1:154
	ds_read2_b32 v[42:43], v115 offset0:155 offset1:156
	ds_read2_b32 v[44:45], v115 offset0:161 offset1:162
	ds_read2_b32 v[46:47], v115 offset0:163 offset1:164
	s_waitcnt lgkmcnt(0)
	v_mfma_f32_32x32x16_bf16 v[32:47], v[116:119], v[48:51], v[32:47]
	ds_read_b64_tr_b16 v[72:73], v231
	ds_read_b64_tr_b16 v[74:75], v231 offset:512
	ds_read_b64_tr_b16 v[76:77], v231 offset:2048
	ds_read_b64_tr_b16 v[78:79], v231 offset:2560
	ds_read_b64_tr_b16 v[220:221], v231 offset:1024
	ds_read_b64_tr_b16 v[222:223], v231 offset:1536
	ds_read_b64_tr_b16 v[224:225], v231 offset:3072
	ds_read_b64_tr_b16 v[226:227], v231 offset:3584
	s_waitcnt vmcnt(8)
	ds_write_b128 v247, v[156:159]
	ds_write_b128 v247, v[160:163] offset:1024
	ds_write_b128 v247, v[164:167] offset:2048
	ds_write_b128 v247, v[168:171] offset:3072
	ds_read_b128 v[156:159], v248
	ds_read_b128 v[160:163], v249
	ds_read_b128 v[164:167], v250
	ds_read_b128 v[168:171], v251
	ds_write_b128 v112, v[172:175]
	ds_write_b128 v112, v[176:179] offset:1024
	ds_write_b128 v112, v[180:183] offset:2048
	ds_write_b128 v112, v[184:187] offset:3072
	v_mfma_f32_32x32x16_bf16 v[32:47], v[120:123], v[52:55], v[32:47]
	v_mfma_f32_32x32x16_bf16 v[32:47], v[124:127], v[56:59], v[32:47]
	v_mfma_f32_32x32x16_bf16 v[32:47], v[128:131], v[60:63], v[32:47]
	s_nop 11
	v_exp_f32_e32 v32, v32
	v_exp_f32_e32 v33, v33
	v_exp_f32_e32 v34, v34
	v_exp_f32_e32 v35, v35
	v_exp_f32_e32 v36, v36
	v_exp_f32_e32 v37, v37
	v_exp_f32_e32 v38, v38
	v_exp_f32_e32 v39, v39
	v_exp_f32_e32 v40, v40
	v_exp_f32_e32 v41, v41
	v_exp_f32_e32 v42, v42
	v_exp_f32_e32 v43, v43
	v_exp_f32_e32 v44, v44
	v_exp_f32_e32 v45, v45
	v_exp_f32_e32 v46, v46
	v_exp_f32_e32 v47, v47
	v_cvt_pk_bf16_f32 v64, v32, v33
	v_cvt_pk_bf16_f32 v65, v34, v35
	v_cvt_pk_bf16_f32 v66, v36, v37
	v_cvt_pk_bf16_f32 v67, v38, v39
	v_cvt_pk_bf16_f32 v68, v40, v41
	v_cvt_pk_bf16_f32 v69, v42, v43
	v_cvt_pk_bf16_f32 v70, v44, v45
	v_cvt_pk_bf16_f32 v71, v46, v47
	v_pk_add_f32 v[232:233], v[232:233], v[32:33]
	v_pk_add_f32 v[232:233], v[232:233], v[34:35]
	v_pk_add_f32 v[232:233], v[232:233], v[36:37]
	v_pk_add_f32 v[232:233], v[232:233], v[38:39]
	v_pk_add_f32 v[232:233], v[232:233], v[40:41]
	v_pk_add_f32 v[232:233], v[232:233], v[42:43]
	v_pk_add_f32 v[232:233], v[232:233], v[44:45]
	v_pk_add_f32 v[232:233], v[232:233], v[46:47]
	s_waitcnt lgkmcnt(12)
	v_mfma_f32_32x32x16_bf16 v[0:15], v[64:67], v[72:75], v[0:15]
	v_mfma_f32_32x32x16_bf16 v[16:31], v[64:67], v[76:79], v[16:31]
	v_mfma_f32_32x32x16_bf16 v[0:15], v[68:71], v[220:223], v[0:15]
	v_mfma_f32_32x32x16_bf16 v[16:31], v[68:71], v[224:227], v[16:31]
	global_load_dwordx4 v[116:119], v239, s[86:87]
	global_load_dwordx4 v[120:123], v240, s[86:87]
	global_load_dwordx4 v[124:127], v241, s[86:87]
	global_load_dwordx4 v[128:131], v242, s[86:87]
	global_load_dwordx4 v[132:135], v101, s[86:87] offset:768
	global_load_dwordx4 v[136:139], v150, s[86:87] offset:768
	global_load_dwordx4 v[140:143], v101, s[86:87] offset:832
	global_load_dwordx4 v[144:147], v150, s[86:87] offset:832
	s_add_u32 s86, s86, 0xc0000
	s_addc_u32 s87, s87, 0
	ds_read2_b32 v[32:33], v115 offset0:170 offset1:171
	ds_read2_b32 v[34:35], v115 offset0:172 offset1:173
	ds_read2_b32 v[36:37], v115 offset0:178 offset1:179
	ds_read2_b32 v[38:39], v115 offset0:180 offset1:181
	ds_read2_b32 v[40:41], v115 offset0:187 offset1:188
	ds_read2_b32 v[42:43], v115 offset0:189 offset1:190
	ds_read2_b32 v[44:45], v115 offset0:195 offset1:196
	ds_read2_b32 v[46:47], v115 offset0:197 offset1:198
	s_waitcnt lgkmcnt(0)
	v_mfma_f32_32x32x16_bf16 v[32:47], v[156:159], v[48:51], v[32:47]
	ds_read_b64_tr_b16 v[72:73], v231
	ds_read_b64_tr_b16 v[74:75], v231 offset:512
	ds_read_b64_tr_b16 v[76:77], v231 offset:2048
	ds_read_b64_tr_b16 v[78:79], v231 offset:2560
	ds_read_b64_tr_b16 v[220:221], v231 offset:1024
	ds_read_b64_tr_b16 v[222:223], v231 offset:1536
	ds_read_b64_tr_b16 v[224:225], v231 offset:3072
	ds_read_b64_tr_b16 v[226:227], v231 offset:3584
	s_waitcnt vmcnt(8)
	ds_write_b128 v247, v[188:191]
	ds_write_b128 v247, v[192:195] offset:1024
	ds_write_b128 v247, v[196:199] offset:2048
	ds_write_b128 v247, v[200:203] offset:3072
	ds_read_b128 v[188:191], v248
	ds_read_b128 v[192:195], v249
	ds_read_b128 v[196:199], v250
	ds_read_b128 v[200:203], v251
	ds_write_b128 v112, v[204:207]
	ds_write_b128 v112, v[208:211] offset:1024
	ds_write_b128 v112, v[212:215] offset:2048
	ds_write_b128 v112, v[216:219] offset:3072
	v_mfma_f32_32x32x16_bf16 v[32:47], v[160:163], v[52:55], v[32:47]
	v_mfma_f32_32x32x16_bf16 v[32:47], v[164:167], v[56:59], v[32:47]
	v_mfma_f32_32x32x16_bf16 v[32:47], v[168:171], v[60:63], v[32:47]
	s_nop 11
	v_exp_f32_e32 v32, v32
	v_exp_f32_e32 v33, v33
	v_exp_f32_e32 v34, v34
	v_exp_f32_e32 v35, v35
	v_exp_f32_e32 v36, v36
	v_exp_f32_e32 v37, v37
	v_exp_f32_e32 v38, v38
	v_exp_f32_e32 v39, v39
	v_exp_f32_e32 v40, v40
	v_exp_f32_e32 v41, v41
	v_exp_f32_e32 v42, v42
	v_exp_f32_e32 v43, v43
	v_exp_f32_e32 v44, v44
	v_exp_f32_e32 v45, v45
	v_exp_f32_e32 v46, v46
	v_exp_f32_e32 v47, v47
	v_cvt_pk_bf16_f32 v64, v32, v33
	v_cvt_pk_bf16_f32 v65, v34, v35
	v_cvt_pk_bf16_f32 v66, v36, v37
	v_cvt_pk_bf16_f32 v67, v38, v39
	v_cvt_pk_bf16_f32 v68, v40, v41
	v_cvt_pk_bf16_f32 v69, v42, v43
	v_cvt_pk_bf16_f32 v70, v44, v45
	v_cvt_pk_bf16_f32 v71, v46, v47
	v_pk_add_f32 v[232:233], v[232:233], v[32:33]
	v_pk_add_f32 v[232:233], v[232:233], v[34:35]
	v_pk_add_f32 v[232:233], v[232:233], v[36:37]
	v_pk_add_f32 v[232:233], v[232:233], v[38:39]
	v_pk_add_f32 v[232:233], v[232:233], v[40:41]
	v_pk_add_f32 v[232:233], v[232:233], v[42:43]
	v_pk_add_f32 v[232:233], v[232:233], v[44:45]
	v_pk_add_f32 v[232:233], v[232:233], v[46:47]
	s_waitcnt lgkmcnt(12)
	v_mfma_f32_32x32x16_bf16 v[0:15], v[64:67], v[72:75], v[0:15]
	v_mfma_f32_32x32x16_bf16 v[16:31], v[64:67], v[76:79], v[16:31]
	v_mfma_f32_32x32x16_bf16 v[0:15], v[68:71], v[220:223], v[0:15]
	v_mfma_f32_32x32x16_bf16 v[16:31], v[68:71], v[224:227], v[16:31]
	global_load_dwordx4 v[156:159], v239, s[86:87]
	global_load_dwordx4 v[160:163], v240, s[86:87]
	global_load_dwordx4 v[164:167], v241, s[86:87]
	global_load_dwordx4 v[168:171], v242, s[86:87]
	global_load_dwordx4 v[172:175], v101, s[86:87] offset:768
	global_load_dwordx4 v[176:179], v150, s[86:87] offset:768
	global_load_dwordx4 v[180:183], v101, s[86:87] offset:832
	global_load_dwordx4 v[184:187], v150, s[86:87] offset:832
	s_add_u32 s86, s86, 0xc0000
	s_addc_u32 s87, s87, 0
	v_mov_b32_e32 v115, v229
	ds_read2_b32 v[32:33], v115 offset0:0 offset1:1
	ds_read2_b32 v[34:35], v115 offset0:2 offset1:3
	ds_read2_b32 v[36:37], v115 offset0:10 offset1:11
	ds_read2_b32 v[38:39], v115 offset0:12 offset1:13
	ds_read2_b32 v[40:41], v115 offset0:20 offset1:21
	ds_read2_b32 v[42:43], v115 offset0:22 offset1:23
	ds_read2_b32 v[44:45], v115 offset0:30 offset1:31
	ds_read2_b32 v[46:47], v115 offset0:32 offset1:33
	s_waitcnt lgkmcnt(0)
	v_mfma_f32_32x32x16_bf16 v[32:47], v[188:191], v[48:51], v[32:47]
	ds_read_b64_tr_b16 v[72:73], v231
	ds_read_b64_tr_b16 v[74:75], v231 offset:512
	ds_read_b64_tr_b16 v[76:77], v231 offset:2048
	ds_read_b64_tr_b16 v[78:79], v231 offset:2560
	ds_read_b64_tr_b16 v[220:221], v231 offset:1024
	ds_read_b64_tr_b16 v[222:223], v231 offset:1536
	ds_read_b64_tr_b16 v[224:225], v231 offset:3072
	ds_read_b64_tr_b16 v[226:227], v231 offset:3584
	s_waitcnt vmcnt(8)
	ds_write_b128 v247, v[116:119]
	ds_write_b128 v247, v[120:123] offset:1024
	ds_write_b128 v247, v[124:127] offset:2048
	ds_write_b128 v247, v[128:131] offset:3072
	ds_read_b128 v[116:119], v248
	ds_read_b128 v[120:123], v249
	ds_read_b128 v[124:127], v250
	ds_read_b128 v[128:131], v251
	ds_write_b128 v112, v[132:135]
	ds_write_b128 v112, v[136:139] offset:1024
	ds_write_b128 v112, v[140:143] offset:2048
	ds_write_b128 v112, v[144:147] offset:3072
	v_mfma_f32_32x32x16_bf16 v[32:47], v[192:195], v[52:55], v[32:47]
	v_mfma_f32_32x32x16_bf16 v[32:47], v[196:199], v[56:59], v[32:47]
	v_mfma_f32_32x32x16_bf16 v[32:47], v[200:203], v[60:63], v[32:47]
	s_nop 11
	v_exp_f32_e32 v32, v32
	v_exp_f32_e32 v33, v33
	v_exp_f32_e32 v34, v34
	v_exp_f32_e32 v35, v35
	v_exp_f32_e32 v36, v36
	v_exp_f32_e32 v37, v37
	v_exp_f32_e32 v38, v38
	v_exp_f32_e32 v39, v39
	v_exp_f32_e32 v40, v40
	v_exp_f32_e32 v41, v41
	v_exp_f32_e32 v42, v42
	v_exp_f32_e32 v43, v43
	v_exp_f32_e32 v44, v44
	v_exp_f32_e32 v45, v45
	v_exp_f32_e32 v46, v46
	v_exp_f32_e32 v47, v47
	v_cvt_pk_bf16_f32 v64, v32, v33
	v_cvt_pk_bf16_f32 v65, v34, v35
	v_cvt_pk_bf16_f32 v66, v36, v37
	v_cvt_pk_bf16_f32 v67, v38, v39
	v_cvt_pk_bf16_f32 v68, v40, v41
	v_cvt_pk_bf16_f32 v69, v42, v43
	v_cvt_pk_bf16_f32 v70, v44, v45
	v_cvt_pk_bf16_f32 v71, v46, v47
	v_pk_add_f32 v[232:233], v[232:233], v[32:33]
	v_pk_add_f32 v[232:233], v[232:233], v[34:35]
	v_pk_add_f32 v[232:233], v[232:233], v[36:37]
	v_pk_add_f32 v[232:233], v[232:233], v[38:39]
	v_pk_add_f32 v[232:233], v[232:233], v[40:41]
	v_pk_add_f32 v[232:233], v[232:233], v[42:43]
	v_pk_add_f32 v[232:233], v[232:233], v[44:45]
	v_pk_add_f32 v[232:233], v[232:233], v[46:47]
	s_waitcnt lgkmcnt(12)
	v_mfma_f32_32x32x16_bf16 v[0:15], v[64:67], v[72:75], v[0:15]
	v_mfma_f32_32x32x16_bf16 v[16:31], v[64:67], v[76:79], v[16:31]
	v_mfma_f32_32x32x16_bf16 v[0:15], v[68:71], v[220:223], v[0:15]
	v_mfma_f32_32x32x16_bf16 v[16:31], v[68:71], v[224:227], v[16:31]
	global_load_dwordx4 v[188:191], v239, s[86:87]
	global_load_dwordx4 v[192:195], v240, s[86:87]
	global_load_dwordx4 v[196:199], v241, s[86:87]
	global_load_dwordx4 v[200:203], v242, s[86:87]
	global_load_dwordx4 v[204:207], v101, s[86:87] offset:768
	global_load_dwordx4 v[208:211], v150, s[86:87] offset:768
	global_load_dwordx4 v[212:215], v101, s[86:87] offset:832
	global_load_dwordx4 v[216:219], v150, s[86:87] offset:832
	s_add_u32 s86, s86, 0xc0000
	s_addc_u32 s87, s87, 0
	ds_read2_b32 v[32:33], v115 offset0:40 offset1:41
	ds_read2_b32 v[34:35], v115 offset0:42 offset1:43
	ds_read2_b32 v[36:37], v115 offset0:50 offset1:51
	ds_read2_b32 v[38:39], v115 offset0:52 offset1:53
	ds_read2_b32 v[40:41], v115 offset0:60 offset1:61
	ds_read2_b32 v[42:43], v115 offset0:62 offset1:63
	ds_read2_b32 v[44:45], v115 offset0:70 offset1:71
	ds_read2_b32 v[46:47], v115 offset0:72 offset1:73
	s_waitcnt lgkmcnt(0)
	v_mfma_f32_32x32x16_bf16 v[32:47], v[116:119], v[48:51], v[32:47]
	ds_read_b64_tr_b16 v[72:73], v231
	ds_read_b64_tr_b16 v[74:75], v231 offset:512
	ds_read_b64_tr_b16 v[76:77], v231 offset:2048
	ds_read_b64_tr_b16 v[78:79], v231 offset:2560
	ds_read_b64_tr_b16 v[220:221], v231 offset:1024
	ds_read_b64_tr_b16 v[222:223], v231 offset:1536
	ds_read_b64_tr_b16 v[224:225], v231 offset:3072
	ds_read_b64_tr_b16 v[226:227], v231 offset:3584
	s_waitcnt vmcnt(8)
	ds_write_b128 v247, v[156:159]
	ds_write_b128 v247, v[160:163] offset:1024
	ds_write_b128 v247, v[164:167] offset:2048
	ds_write_b128 v247, v[168:171] offset:3072
	ds_read_b128 v[156:159], v248
	ds_read_b128 v[160:163], v249
	ds_read_b128 v[164:167], v250
	ds_read_b128 v[168:171], v251
	ds_write_b128 v112, v[172:175]
	ds_write_b128 v112, v[176:179] offset:1024
	ds_write_b128 v112, v[180:183] offset:2048
	ds_write_b128 v112, v[184:187] offset:3072
	v_mfma_f32_32x32x16_bf16 v[32:47], v[120:123], v[52:55], v[32:47]
	v_mfma_f32_32x32x16_bf16 v[32:47], v[124:127], v[56:59], v[32:47]
	v_mfma_f32_32x32x16_bf16 v[32:47], v[128:131], v[60:63], v[32:47]
	s_nop 11
	v_exp_f32_e32 v32, v32
	v_exp_f32_e32 v33, v33
	v_exp_f32_e32 v34, v34
	v_exp_f32_e32 v35, v35
	v_exp_f32_e32 v36, v36
	v_exp_f32_e32 v37, v37
	v_exp_f32_e32 v38, v38
	v_exp_f32_e32 v39, v39
	v_exp_f32_e32 v40, v40
	v_exp_f32_e32 v41, v41
	v_exp_f32_e32 v42, v42
	v_exp_f32_e32 v43, v43
	v_exp_f32_e32 v44, v44
	v_exp_f32_e32 v45, v45
	v_exp_f32_e32 v46, v46
	v_exp_f32_e32 v47, v47
	v_cvt_pk_bf16_f32 v64, v32, v33
	v_cvt_pk_bf16_f32 v65, v34, v35
	v_cvt_pk_bf16_f32 v66, v36, v37
	v_cvt_pk_bf16_f32 v67, v38, v39
	v_cvt_pk_bf16_f32 v68, v40, v41
	v_cvt_pk_bf16_f32 v69, v42, v43
	v_cvt_pk_bf16_f32 v70, v44, v45
	v_cvt_pk_bf16_f32 v71, v46, v47
	v_pk_add_f32 v[232:233], v[232:233], v[32:33]
	v_pk_add_f32 v[232:233], v[232:233], v[34:35]
	v_pk_add_f32 v[232:233], v[232:233], v[36:37]
	v_pk_add_f32 v[232:233], v[232:233], v[38:39]
	v_pk_add_f32 v[232:233], v[232:233], v[40:41]
	v_pk_add_f32 v[232:233], v[232:233], v[42:43]
	v_pk_add_f32 v[232:233], v[232:233], v[44:45]
	v_pk_add_f32 v[232:233], v[232:233], v[46:47]
	s_waitcnt lgkmcnt(12)
	v_mfma_f32_32x32x16_bf16 v[0:15], v[64:67], v[72:75], v[0:15]
	v_mfma_f32_32x32x16_bf16 v[16:31], v[64:67], v[76:79], v[16:31]
	v_mfma_f32_32x32x16_bf16 v[0:15], v[68:71], v[220:223], v[0:15]
	v_mfma_f32_32x32x16_bf16 v[16:31], v[68:71], v[224:227], v[16:31]
	global_load_dwordx4 v[116:119], v239, s[86:87]
	global_load_dwordx4 v[120:123], v240, s[86:87]
	global_load_dwordx4 v[124:127], v241, s[86:87]
	global_load_dwordx4 v[128:131], v242, s[86:87]
	global_load_dwordx4 v[132:135], v101, s[86:87] offset:768
	global_load_dwordx4 v[136:139], v150, s[86:87] offset:768
	global_load_dwordx4 v[140:143], v101, s[86:87] offset:832
	global_load_dwordx4 v[144:147], v150, s[86:87] offset:832
	s_add_u32 s86, s86, 0xc0000
	s_addc_u32 s87, s87, 0
	ds_read2_b32 v[32:33], v115 offset0:80 offset1:81
	ds_read2_b32 v[34:35], v115 offset0:82 offset1:83
	ds_read2_b32 v[36:37], v115 offset0:90 offset1:91
	ds_read2_b32 v[38:39], v115 offset0:92 offset1:93
	ds_read2_b32 v[40:41], v115 offset0:100 offset1:101
	ds_read2_b32 v[42:43], v115 offset0:102 offset1:103
	ds_read2_b32 v[44:45], v115 offset0:110 offset1:111
	ds_read2_b32 v[46:47], v115 offset0:112 offset1:113
	s_waitcnt lgkmcnt(0)
	v_mfma_f32_32x32x16_bf16 v[32:47], v[156:159], v[48:51], v[32:47]
	ds_read_b64_tr_b16 v[72:73], v231
	ds_read_b64_tr_b16 v[74:75], v231 offset:512
	ds_read_b64_tr_b16 v[76:77], v231 offset:2048
	ds_read_b64_tr_b16 v[78:79], v231 offset:2560
	ds_read_b64_tr_b16 v[220:221], v231 offset:1024
	ds_read_b64_tr_b16 v[222:223], v231 offset:1536
	ds_read_b64_tr_b16 v[224:225], v231 offset:3072
	ds_read_b64_tr_b16 v[226:227], v231 offset:3584
	s_waitcnt vmcnt(8)
	ds_write_b128 v247, v[188:191]
	ds_write_b128 v247, v[192:195] offset:1024
	ds_write_b128 v247, v[196:199] offset:2048
	ds_write_b128 v247, v[200:203] offset:3072
	ds_read_b128 v[188:191], v248
	ds_read_b128 v[192:195], v249
	ds_read_b128 v[196:199], v250
	ds_read_b128 v[200:203], v251
	ds_write_b128 v112, v[204:207]
	ds_write_b128 v112, v[208:211] offset:1024
	ds_write_b128 v112, v[212:215] offset:2048
	ds_write_b128 v112, v[216:219] offset:3072
	v_mfma_f32_32x32x16_bf16 v[32:47], v[160:163], v[52:55], v[32:47]
	v_mfma_f32_32x32x16_bf16 v[32:47], v[164:167], v[56:59], v[32:47]
	v_mfma_f32_32x32x16_bf16 v[32:47], v[168:171], v[60:63], v[32:47]
	s_nop 11
	v_exp_f32_e32 v32, v32
	v_exp_f32_e32 v33, v33
	v_exp_f32_e32 v34, v34
	v_exp_f32_e32 v35, v35
	v_exp_f32_e32 v36, v36
	v_exp_f32_e32 v37, v37
	v_exp_f32_e32 v38, v38
	v_exp_f32_e32 v39, v39
	v_exp_f32_e32 v40, v40
	v_exp_f32_e32 v41, v41
	v_exp_f32_e32 v42, v42
	v_exp_f32_e32 v43, v43
	v_exp_f32_e32 v44, v44
	v_exp_f32_e32 v45, v45
	v_exp_f32_e32 v46, v46
	v_exp_f32_e32 v47, v47
	v_cvt_pk_bf16_f32 v64, v32, v33
	v_cvt_pk_bf16_f32 v65, v34, v35
	v_cvt_pk_bf16_f32 v66, v36, v37
	v_cvt_pk_bf16_f32 v67, v38, v39
	v_cvt_pk_bf16_f32 v68, v40, v41
	v_cvt_pk_bf16_f32 v69, v42, v43
	v_cvt_pk_bf16_f32 v70, v44, v45
	v_cvt_pk_bf16_f32 v71, v46, v47
	v_pk_add_f32 v[232:233], v[232:233], v[32:33]
	v_pk_add_f32 v[232:233], v[232:233], v[34:35]
	v_pk_add_f32 v[232:233], v[232:233], v[36:37]
	v_pk_add_f32 v[232:233], v[232:233], v[38:39]
	v_pk_add_f32 v[232:233], v[232:233], v[40:41]
	v_pk_add_f32 v[232:233], v[232:233], v[42:43]
	v_pk_add_f32 v[232:233], v[232:233], v[44:45]
	v_pk_add_f32 v[232:233], v[232:233], v[46:47]
	s_waitcnt lgkmcnt(12)
	v_mfma_f32_32x32x16_bf16 v[0:15], v[64:67], v[72:75], v[0:15]
	v_mfma_f32_32x32x16_bf16 v[16:31], v[64:67], v[76:79], v[16:31]
	v_mfma_f32_32x32x16_bf16 v[0:15], v[68:71], v[220:223], v[0:15]
	v_mfma_f32_32x32x16_bf16 v[16:31], v[68:71], v[224:227], v[16:31]
	global_load_dwordx4 v[156:159], v239, s[86:87]
	global_load_dwordx4 v[160:163], v240, s[86:87]
	global_load_dwordx4 v[164:167], v241, s[86:87]
	global_load_dwordx4 v[168:171], v242, s[86:87]
	global_load_dwordx4 v[172:175], v101, s[86:87] offset:768
	global_load_dwordx4 v[176:179], v150, s[86:87] offset:768
	global_load_dwordx4 v[180:183], v101, s[86:87] offset:832
	global_load_dwordx4 v[184:187], v150, s[86:87] offset:832
	s_add_u32 s86, s86, 0xc0000
	s_addc_u32 s87, s87, 0
	ds_read2_b32 v[32:33], v115 offset0:120 offset1:121
	ds_read2_b32 v[34:35], v115 offset0:122 offset1:123
	ds_read2_b32 v[36:37], v115 offset0:130 offset1:131
	ds_read2_b32 v[38:39], v115 offset0:132 offset1:133
	ds_read2_b32 v[40:41], v115 offset0:140 offset1:141
	ds_read2_b32 v[42:43], v115 offset0:142 offset1:143
	ds_read2_b32 v[44:45], v115 offset0:150 offset1:151
	ds_read2_b32 v[46:47], v115 offset0:152 offset1:153
	s_waitcnt lgkmcnt(0)
	v_mfma_f32_32x32x16_bf16 v[32:47], v[188:191], v[48:51], v[32:47]
	ds_read_b64_tr_b16 v[72:73], v231
	ds_read_b64_tr_b16 v[74:75], v231 offset:512
	ds_read_b64_tr_b16 v[76:77], v231 offset:2048
	ds_read_b64_tr_b16 v[78:79], v231 offset:2560
	ds_read_b64_tr_b16 v[220:221], v231 offset:1024
	ds_read_b64_tr_b16 v[222:223], v231 offset:1536
	ds_read_b64_tr_b16 v[224:225], v231 offset:3072
	ds_read_b64_tr_b16 v[226:227], v231 offset:3584
	s_waitcnt vmcnt(8)
	ds_write_b128 v247, v[116:119]
	ds_write_b128 v247, v[120:123] offset:1024
	ds_write_b128 v247, v[124:127] offset:2048
	ds_write_b128 v247, v[128:131] offset:3072
	ds_read_b128 v[116:119], v248
	ds_read_b128 v[120:123], v249
	ds_read_b128 v[124:127], v250
	ds_read_b128 v[128:131], v251
	ds_write_b128 v112, v[132:135]
	ds_write_b128 v112, v[136:139] offset:1024
	ds_write_b128 v112, v[140:143] offset:2048
	ds_write_b128 v112, v[144:147] offset:3072
	v_mfma_f32_32x32x16_bf16 v[32:47], v[192:195], v[52:55], v[32:47]
	v_mfma_f32_32x32x16_bf16 v[32:47], v[196:199], v[56:59], v[32:47]
	v_mfma_f32_32x32x16_bf16 v[32:47], v[200:203], v[60:63], v[32:47]
	s_nop 11
	v_exp_f32_e32 v32, v32
	v_exp_f32_e32 v33, v33
	v_exp_f32_e32 v34, v34
	v_exp_f32_e32 v35, v35
	v_exp_f32_e32 v36, v36
	v_exp_f32_e32 v37, v37
	v_exp_f32_e32 v38, v38
	v_exp_f32_e32 v39, v39
	v_exp_f32_e32 v40, v40
	v_exp_f32_e32 v41, v41
	v_exp_f32_e32 v42, v42
	v_exp_f32_e32 v43, v43
	v_exp_f32_e32 v44, v44
	v_exp_f32_e32 v45, v45
	v_exp_f32_e32 v46, v46
	v_exp_f32_e32 v47, v47
	v_cvt_pk_bf16_f32 v64, v32, v33
	v_cvt_pk_bf16_f32 v65, v34, v35
	v_cvt_pk_bf16_f32 v66, v36, v37
	v_cvt_pk_bf16_f32 v67, v38, v39
	v_cvt_pk_bf16_f32 v68, v40, v41
	v_cvt_pk_bf16_f32 v69, v42, v43
	v_cvt_pk_bf16_f32 v70, v44, v45
	v_cvt_pk_bf16_f32 v71, v46, v47
	v_pk_add_f32 v[232:233], v[232:233], v[32:33]
	v_pk_add_f32 v[232:233], v[232:233], v[34:35]
	v_pk_add_f32 v[232:233], v[232:233], v[36:37]
	v_pk_add_f32 v[232:233], v[232:233], v[38:39]
	v_pk_add_f32 v[232:233], v[232:233], v[40:41]
	v_pk_add_f32 v[232:233], v[232:233], v[42:43]
	v_pk_add_f32 v[232:233], v[232:233], v[44:45]
	v_pk_add_f32 v[232:233], v[232:233], v[46:47]
	s_waitcnt lgkmcnt(12)
	v_mfma_f32_32x32x16_bf16 v[0:15], v[64:67], v[72:75], v[0:15]
	v_mfma_f32_32x32x16_bf16 v[16:31], v[64:67], v[76:79], v[16:31]
	v_mfma_f32_32x32x16_bf16 v[0:15], v[68:71], v[220:223], v[0:15]
	v_mfma_f32_32x32x16_bf16 v[16:31], v[68:71], v[224:227], v[16:31]
	global_load_dwordx4 v[188:191], v239, s[86:87]
	global_load_dwordx4 v[192:195], v240, s[86:87]
	global_load_dwordx4 v[196:199], v241, s[86:87]
	global_load_dwordx4 v[200:203], v242, s[86:87]
	global_load_dwordx4 v[204:207], v101, s[86:87] offset:768
	global_load_dwordx4 v[208:211], v150, s[86:87] offset:768
	global_load_dwordx4 v[212:215], v101, s[86:87] offset:832
	global_load_dwordx4 v[216:219], v150, s[86:87] offset:832
	s_add_u32 s86, s86, 0xc0000
	s_addc_u32 s87, s87, 0
	v_add_u32_e32 v115, 640, v115
	ds_read2_b32 v[32:33], v115 offset0:0 offset1:1
	ds_read2_b32 v[34:35], v115 offset0:2 offset1:3
	ds_read2_b32 v[36:37], v115 offset0:10 offset1:11
	ds_read2_b32 v[38:39], v115 offset0:12 offset1:13
	ds_read2_b32 v[40:41], v115 offset0:20 offset1:21
	ds_read2_b32 v[42:43], v115 offset0:22 offset1:23
	ds_read2_b32 v[44:45], v115 offset0:30 offset1:31
	ds_read2_b32 v[46:47], v115 offset0:32 offset1:33
	s_waitcnt lgkmcnt(0)
	v_mfma_f32_32x32x16_bf16 v[32:47], v[116:119], v[48:51], v[32:47]
	ds_read_b64_tr_b16 v[72:73], v231
	ds_read_b64_tr_b16 v[74:75], v231 offset:512
	ds_read_b64_tr_b16 v[76:77], v231 offset:2048
	ds_read_b64_tr_b16 v[78:79], v231 offset:2560
	ds_read_b64_tr_b16 v[220:221], v231 offset:1024
	ds_read_b64_tr_b16 v[222:223], v231 offset:1536
	ds_read_b64_tr_b16 v[224:225], v231 offset:3072
	ds_read_b64_tr_b16 v[226:227], v231 offset:3584
	s_waitcnt vmcnt(8)
	ds_write_b128 v247, v[156:159]
	ds_write_b128 v247, v[160:163] offset:1024
	ds_write_b128 v247, v[164:167] offset:2048
	ds_write_b128 v247, v[168:171] offset:3072
	ds_read_b128 v[156:159], v248
	ds_read_b128 v[160:163], v249
	ds_read_b128 v[164:167], v250
	ds_read_b128 v[168:171], v251
	ds_write_b128 v112, v[172:175]
	ds_write_b128 v112, v[176:179] offset:1024
	ds_write_b128 v112, v[180:183] offset:2048
	ds_write_b128 v112, v[184:187] offset:3072
	v_mfma_f32_32x32x16_bf16 v[32:47], v[120:123], v[52:55], v[32:47]
	v_mfma_f32_32x32x16_bf16 v[32:47], v[124:127], v[56:59], v[32:47]
	v_mfma_f32_32x32x16_bf16 v[32:47], v[128:131], v[60:63], v[32:47]
	s_nop 11
	v_exp_f32_e32 v32, v32
	v_exp_f32_e32 v33, v33
	v_exp_f32_e32 v34, v34
	v_exp_f32_e32 v35, v35
	v_exp_f32_e32 v36, v36
	v_exp_f32_e32 v37, v37
	v_exp_f32_e32 v38, v38
	v_exp_f32_e32 v39, v39
	v_exp_f32_e32 v40, v40
	v_exp_f32_e32 v41, v41
	v_exp_f32_e32 v42, v42
	v_exp_f32_e32 v43, v43
	v_exp_f32_e32 v44, v44
	v_exp_f32_e32 v45, v45
	v_exp_f32_e32 v46, v46
	v_exp_f32_e32 v47, v47
	v_cvt_pk_bf16_f32 v64, v32, v33
	v_cvt_pk_bf16_f32 v65, v34, v35
	v_cvt_pk_bf16_f32 v66, v36, v37
	v_cvt_pk_bf16_f32 v67, v38, v39
	v_cvt_pk_bf16_f32 v68, v40, v41
	v_cvt_pk_bf16_f32 v69, v42, v43
	v_cvt_pk_bf16_f32 v70, v44, v45
	v_cvt_pk_bf16_f32 v71, v46, v47
	v_pk_add_f32 v[232:233], v[232:233], v[32:33]
	v_pk_add_f32 v[232:233], v[232:233], v[34:35]
	v_pk_add_f32 v[232:233], v[232:233], v[36:37]
	v_pk_add_f32 v[232:233], v[232:233], v[38:39]
	v_pk_add_f32 v[232:233], v[232:233], v[40:41]
	v_pk_add_f32 v[232:233], v[232:233], v[42:43]
	v_pk_add_f32 v[232:233], v[232:233], v[44:45]
	v_pk_add_f32 v[232:233], v[232:233], v[46:47]
	s_waitcnt lgkmcnt(12)
	v_mfma_f32_32x32x16_bf16 v[0:15], v[64:67], v[72:75], v[0:15]
	v_mfma_f32_32x32x16_bf16 v[16:31], v[64:67], v[76:79], v[16:31]
	v_mfma_f32_32x32x16_bf16 v[0:15], v[68:71], v[220:223], v[0:15]
	v_mfma_f32_32x32x16_bf16 v[16:31], v[68:71], v[224:227], v[16:31]
	global_load_dwordx4 v[116:119], v239, s[86:87]
	global_load_dwordx4 v[120:123], v240, s[86:87]
	global_load_dwordx4 v[124:127], v241, s[86:87]
	global_load_dwordx4 v[128:131], v242, s[86:87]
	global_load_dwordx4 v[132:135], v101, s[86:87] offset:768
	global_load_dwordx4 v[136:139], v150, s[86:87] offset:768
	global_load_dwordx4 v[140:143], v101, s[86:87] offset:832
	global_load_dwordx4 v[144:147], v150, s[86:87] offset:832
	ds_read2_b32 v[32:33], v115 offset0:40 offset1:41
	ds_read2_b32 v[34:35], v115 offset0:42 offset1:43
	ds_read2_b32 v[36:37], v115 offset0:50 offset1:51
	ds_read2_b32 v[38:39], v115 offset0:52 offset1:53
	ds_read2_b32 v[40:41], v115 offset0:60 offset1:61
	ds_read2_b32 v[42:43], v115 offset0:62 offset1:63
	ds_read2_b32 v[44:45], v115 offset0:70 offset1:71
	ds_read2_b32 v[46:47], v115 offset0:72 offset1:73
	s_waitcnt lgkmcnt(0)
	v_mfma_f32_32x32x16_bf16 v[32:47], v[156:159], v[48:51], v[32:47]
	ds_read_b64_tr_b16 v[72:73], v231
	ds_read_b64_tr_b16 v[74:75], v231 offset:512
	ds_read_b64_tr_b16 v[76:77], v231 offset:2048
	ds_read_b64_tr_b16 v[78:79], v231 offset:2560
	ds_read_b64_tr_b16 v[220:221], v231 offset:1024
	ds_read_b64_tr_b16 v[222:223], v231 offset:1536
	ds_read_b64_tr_b16 v[224:225], v231 offset:3072
	ds_read_b64_tr_b16 v[226:227], v231 offset:3584
	s_waitcnt vmcnt(8)
	ds_write_b128 v247, v[188:191]
	ds_write_b128 v247, v[192:195] offset:1024
	ds_write_b128 v247, v[196:199] offset:2048
	ds_write_b128 v247, v[200:203] offset:3072
	ds_read_b128 v[188:191], v248
	ds_read_b128 v[192:195], v249
	ds_read_b128 v[196:199], v250
	ds_read_b128 v[200:203], v251
	ds_write_b128 v112, v[204:207]
	ds_write_b128 v112, v[208:211] offset:1024
	ds_write_b128 v112, v[212:215] offset:2048
	ds_write_b128 v112, v[216:219] offset:3072
	v_mfma_f32_32x32x16_bf16 v[32:47], v[160:163], v[52:55], v[32:47]
	v_mfma_f32_32x32x16_bf16 v[32:47], v[164:167], v[56:59], v[32:47]
	v_mfma_f32_32x32x16_bf16 v[32:47], v[168:171], v[60:63], v[32:47]
	s_nop 11
	v_exp_f32_e32 v32, v32
	v_exp_f32_e32 v33, v33
	v_exp_f32_e32 v34, v34
	v_exp_f32_e32 v35, v35
	v_exp_f32_e32 v36, v36
	v_exp_f32_e32 v37, v37
	v_exp_f32_e32 v38, v38
	v_exp_f32_e32 v39, v39
	v_exp_f32_e32 v40, v40
	v_exp_f32_e32 v41, v41
	v_exp_f32_e32 v42, v42
	v_exp_f32_e32 v43, v43
	v_exp_f32_e32 v44, v44
	v_exp_f32_e32 v45, v45
	v_exp_f32_e32 v46, v46
	v_exp_f32_e32 v47, v47
	v_cvt_pk_bf16_f32 v64, v32, v33
	v_cvt_pk_bf16_f32 v65, v34, v35
	v_cvt_pk_bf16_f32 v66, v36, v37
	v_cvt_pk_bf16_f32 v67, v38, v39
	v_cvt_pk_bf16_f32 v68, v40, v41
	v_cvt_pk_bf16_f32 v69, v42, v43
	v_cvt_pk_bf16_f32 v70, v44, v45
	v_cvt_pk_bf16_f32 v71, v46, v47
	v_pk_add_f32 v[232:233], v[232:233], v[32:33]
	v_pk_add_f32 v[232:233], v[232:233], v[34:35]
	v_pk_add_f32 v[232:233], v[232:233], v[36:37]
	v_pk_add_f32 v[232:233], v[232:233], v[38:39]
	v_pk_add_f32 v[232:233], v[232:233], v[40:41]
	v_pk_add_f32 v[232:233], v[232:233], v[42:43]
	v_pk_add_f32 v[232:233], v[232:233], v[44:45]
	v_pk_add_f32 v[232:233], v[232:233], v[46:47]
	s_waitcnt lgkmcnt(12)
	v_mfma_f32_32x32x16_bf16 v[0:15], v[64:67], v[72:75], v[0:15]
	v_mfma_f32_32x32x16_bf16 v[16:31], v[64:67], v[76:79], v[16:31]
	v_mfma_f32_32x32x16_bf16 v[0:15], v[68:71], v[220:223], v[0:15]
	v_mfma_f32_32x32x16_bf16 v[16:31], v[68:71], v[224:227], v[16:31]
	global_load_dwordx4 v[156:159], v243, s[88:89]
	global_load_dwordx4 v[160:163], v244, s[88:89]
	global_load_dwordx4 v[164:167], v245, s[88:89]
	global_load_dwordx4 v[168:171], v246, s[88:89]
	global_load_dwordx4 v[172:175], v148, s[88:89] offset:768
	global_load_dwordx4 v[176:179], v151, s[88:89] offset:768
	global_load_dwordx4 v[180:183], v148, s[88:89] offset:832
	global_load_dwordx4 v[184:187], v151, s[88:89] offset:832
	s_add_u32 s88, s88, 0x300000
	s_addc_u32 s89, s89, 0
	ds_read2_b32 v[32:33], v115 offset0:80 offset1:81
	ds_read2_b32 v[34:35], v115 offset0:82 offset1:83
	ds_read2_b32 v[36:37], v115 offset0:90 offset1:91
	ds_read2_b32 v[38:39], v115 offset0:92 offset1:93
	ds_read2_b32 v[40:41], v115 offset0:100 offset1:101
	ds_read2_b32 v[42:43], v115 offset0:102 offset1:103
	ds_read2_b32 v[44:45], v115 offset0:110 offset1:111
	ds_read2_b32 v[46:47], v115 offset0:112 offset1:113
	s_waitcnt lgkmcnt(0)
	v_mfma_f32_32x32x16_bf16 v[32:47], v[188:191], v[48:51], v[32:47]
	ds_read_b64_tr_b16 v[72:73], v231
	ds_read_b64_tr_b16 v[74:75], v231 offset:512
	ds_read_b64_tr_b16 v[76:77], v231 offset:2048
	ds_read_b64_tr_b16 v[78:79], v231 offset:2560
	ds_read_b64_tr_b16 v[220:221], v231 offset:1024
	ds_read_b64_tr_b16 v[222:223], v231 offset:1536
	ds_read_b64_tr_b16 v[224:225], v231 offset:3072
	ds_read_b64_tr_b16 v[226:227], v231 offset:3584
	s_waitcnt vmcnt(8)
	ds_write_b128 v247, v[116:119]
	ds_write_b128 v247, v[120:123] offset:1024
	ds_write_b128 v247, v[124:127] offset:2048
	ds_write_b128 v247, v[128:131] offset:3072
	ds_read_b128 v[116:119], v248
	ds_read_b128 v[120:123], v249
	ds_read_b128 v[124:127], v250
	ds_read_b128 v[128:131], v251
	ds_write_b128 v112, v[132:135]
	ds_write_b128 v112, v[136:139] offset:1024
	ds_write_b128 v112, v[140:143] offset:2048
	ds_write_b128 v112, v[144:147] offset:3072
	v_mfma_f32_32x32x16_bf16 v[32:47], v[192:195], v[52:55], v[32:47]
	v_mfma_f32_32x32x16_bf16 v[32:47], v[196:199], v[56:59], v[32:47]
	v_mfma_f32_32x32x16_bf16 v[32:47], v[200:203], v[60:63], v[32:47]
	s_nop 11
	v_exp_f32_e32 v32, v32
	v_exp_f32_e32 v33, v33
	v_exp_f32_e32 v34, v34
	v_exp_f32_e32 v35, v35
	v_exp_f32_e32 v36, v36
	v_exp_f32_e32 v37, v37
	v_exp_f32_e32 v38, v38
	v_exp_f32_e32 v39, v39
	v_exp_f32_e32 v40, v40
	v_exp_f32_e32 v41, v41
	v_exp_f32_e32 v42, v42
	v_exp_f32_e32 v43, v43
	v_exp_f32_e32 v44, v44
	v_exp_f32_e32 v45, v45
	v_exp_f32_e32 v46, v46
	v_exp_f32_e32 v47, v47
	v_cvt_pk_bf16_f32 v64, v32, v33
	v_cvt_pk_bf16_f32 v65, v34, v35
	v_cvt_pk_bf16_f32 v66, v36, v37
	v_cvt_pk_bf16_f32 v67, v38, v39
	v_cvt_pk_bf16_f32 v68, v40, v41
	v_cvt_pk_bf16_f32 v69, v42, v43
	v_cvt_pk_bf16_f32 v70, v44, v45
	v_cvt_pk_bf16_f32 v71, v46, v47
	v_pk_add_f32 v[232:233], v[232:233], v[32:33]
	v_pk_add_f32 v[232:233], v[232:233], v[34:35]
	v_pk_add_f32 v[232:233], v[232:233], v[36:37]
	v_pk_add_f32 v[232:233], v[232:233], v[38:39]
	v_pk_add_f32 v[232:233], v[232:233], v[40:41]
	v_pk_add_f32 v[232:233], v[232:233], v[42:43]
	v_pk_add_f32 v[232:233], v[232:233], v[44:45]
	v_pk_add_f32 v[232:233], v[232:233], v[46:47]
	s_waitcnt lgkmcnt(12)
	v_mfma_f32_32x32x16_bf16 v[0:15], v[64:67], v[72:75], v[0:15]
	v_mfma_f32_32x32x16_bf16 v[16:31], v[64:67], v[76:79], v[16:31]
	v_mfma_f32_32x32x16_bf16 v[0:15], v[68:71], v[220:223], v[0:15]
	v_mfma_f32_32x32x16_bf16 v[16:31], v[68:71], v[224:227], v[16:31]
	global_load_dwordx4 v[188:191], v243, s[88:89]
	global_load_dwordx4 v[192:195], v244, s[88:89]
	global_load_dwordx4 v[196:199], v245, s[88:89]
	global_load_dwordx4 v[200:203], v246, s[88:89]
	global_load_dwordx4 v[204:207], v148, s[88:89] offset:768
	global_load_dwordx4 v[208:211], v151, s[88:89] offset:768
	global_load_dwordx4 v[212:215], v148, s[88:89] offset:832
	global_load_dwordx4 v[216:219], v151, s[88:89] offset:832
	s_add_u32 s88, s88, 0x300000
	s_addc_u32 s89, s89, 0
	ds_read2_b32 v[32:33], v115 offset0:120 offset1:121
	ds_read2_b32 v[34:35], v115 offset0:122 offset1:123
	ds_read2_b32 v[36:37], v115 offset0:130 offset1:131
	ds_read2_b32 v[38:39], v115 offset0:132 offset1:133
	ds_read2_b32 v[40:41], v115 offset0:140 offset1:141
	ds_read2_b32 v[42:43], v115 offset0:142 offset1:143
	ds_read2_b32 v[44:45], v115 offset0:150 offset1:151
	ds_read2_b32 v[46:47], v115 offset0:152 offset1:153
	s_waitcnt lgkmcnt(0)
	v_mfma_f32_32x32x16_bf16 v[32:47], v[116:119], v[48:51], v[32:47]
	ds_read_b64_tr_b16 v[72:73], v231
	ds_read_b64_tr_b16 v[74:75], v231 offset:512
	ds_read_b64_tr_b16 v[76:77], v231 offset:2048
	ds_read_b64_tr_b16 v[78:79], v231 offset:2560
	ds_read_b64_tr_b16 v[220:221], v231 offset:1024
	ds_read_b64_tr_b16 v[222:223], v231 offset:1536
	ds_read_b64_tr_b16 v[224:225], v231 offset:3072
	ds_read_b64_tr_b16 v[226:227], v231 offset:3584
	s_waitcnt vmcnt(8)
	ds_write_b128 v247, v[156:159]
	ds_write_b128 v247, v[160:163] offset:1024
	ds_write_b128 v247, v[164:167] offset:2048
	ds_write_b128 v247, v[168:171] offset:3072
	ds_read_b128 v[156:159], v248
	ds_read_b128 v[160:163], v249
	ds_read_b128 v[164:167], v250
	ds_read_b128 v[168:171], v251
	ds_write_b128 v112, v[172:175]
	ds_write_b128 v112, v[176:179] offset:1024
	ds_write_b128 v112, v[180:183] offset:2048
	ds_write_b128 v112, v[184:187] offset:3072
	v_mfma_f32_32x32x16_bf16 v[32:47], v[120:123], v[52:55], v[32:47]
	v_mfma_f32_32x32x16_bf16 v[32:47], v[124:127], v[56:59], v[32:47]
	v_mfma_f32_32x32x16_bf16 v[32:47], v[128:131], v[60:63], v[32:47]
	s_nop 11
	v_exp_f32_e32 v32, v32
	v_exp_f32_e32 v33, v33
	v_exp_f32_e32 v34, v34
	v_exp_f32_e32 v35, v35
	v_exp_f32_e32 v36, v36
	v_exp_f32_e32 v37, v37
	v_exp_f32_e32 v38, v38
	v_exp_f32_e32 v39, v39
	v_exp_f32_e32 v40, v40
	v_exp_f32_e32 v41, v41
	v_exp_f32_e32 v42, v42
	v_exp_f32_e32 v43, v43
	v_exp_f32_e32 v44, v44
	v_exp_f32_e32 v45, v45
	v_exp_f32_e32 v46, v46
	v_exp_f32_e32 v47, v47
	v_cvt_pk_bf16_f32 v64, v32, v33
	v_cvt_pk_bf16_f32 v65, v34, v35
	v_cvt_pk_bf16_f32 v66, v36, v37
	v_cvt_pk_bf16_f32 v67, v38, v39
	v_cvt_pk_bf16_f32 v68, v40, v41
	v_cvt_pk_bf16_f32 v69, v42, v43
	v_cvt_pk_bf16_f32 v70, v44, v45
	v_cvt_pk_bf16_f32 v71, v46, v47
	v_pk_add_f32 v[232:233], v[232:233], v[32:33]
	v_pk_add_f32 v[232:233], v[232:233], v[34:35]
	v_pk_add_f32 v[232:233], v[232:233], v[36:37]
	v_pk_add_f32 v[232:233], v[232:233], v[38:39]
	v_pk_add_f32 v[232:233], v[232:233], v[40:41]
	v_pk_add_f32 v[232:233], v[232:233], v[42:43]
	v_pk_add_f32 v[232:233], v[232:233], v[44:45]
	v_pk_add_f32 v[232:233], v[232:233], v[46:47]
	s_waitcnt lgkmcnt(12)
	v_mfma_f32_32x32x16_bf16 v[0:15], v[64:67], v[72:75], v[0:15]
	v_mfma_f32_32x32x16_bf16 v[16:31], v[64:67], v[76:79], v[16:31]
	v_mfma_f32_32x32x16_bf16 v[0:15], v[68:71], v[220:223], v[0:15]
	v_mfma_f32_32x32x16_bf16 v[16:31], v[68:71], v[224:227], v[16:31]
	global_load_dwordx4 v[116:119], v243, s[88:89]
	global_load_dwordx4 v[120:123], v244, s[88:89]
	global_load_dwordx4 v[124:127], v245, s[88:89]
	global_load_dwordx4 v[128:131], v246, s[88:89]
	global_load_dwordx4 v[132:135], v148, s[88:89] offset:768
	global_load_dwordx4 v[136:139], v151, s[88:89] offset:768
	global_load_dwordx4 v[140:143], v148, s[88:89] offset:832
	global_load_dwordx4 v[144:147], v151, s[88:89] offset:832
	s_add_u32 s88, s88, 0x300000
	s_addc_u32 s89, s89, 0
	v_mov_b32_e32 v115, v230
	ds_read2_b32 v[32:33], v115 offset0:0 offset1:1
	ds_read2_b32 v[34:35], v115 offset0:2 offset1:3
	ds_read2_b32 v[36:37], v115 offset0:8 offset1:9
	ds_read2_b32 v[38:39], v115 offset0:10 offset1:11
	ds_read2_b32 v[40:41], v115 offset0:16 offset1:17
	ds_read2_b32 v[42:43], v115 offset0:18 offset1:19
	ds_read2_b32 v[44:45], v115 offset0:24 offset1:25
	ds_read2_b32 v[46:47], v115 offset0:26 offset1:27
	s_waitcnt lgkmcnt(0)
	v_mfma_f32_32x32x16_bf16 v[32:47], v[156:159], v[48:51], v[32:47]
	ds_read_b64_tr_b16 v[72:73], v231
	ds_read_b64_tr_b16 v[74:75], v231 offset:512
	ds_read_b64_tr_b16 v[76:77], v231 offset:2048
	ds_read_b64_tr_b16 v[78:79], v231 offset:2560
	ds_read_b64_tr_b16 v[220:221], v231 offset:1024
	ds_read_b64_tr_b16 v[222:223], v231 offset:1536
	ds_read_b64_tr_b16 v[224:225], v231 offset:3072
	ds_read_b64_tr_b16 v[226:227], v231 offset:3584
	s_waitcnt vmcnt(8)
	ds_write_b128 v247, v[188:191]
	ds_write_b128 v247, v[192:195] offset:1024
	ds_write_b128 v247, v[196:199] offset:2048
	ds_write_b128 v247, v[200:203] offset:3072
	ds_read_b128 v[188:191], v248
	ds_read_b128 v[192:195], v249
	ds_read_b128 v[196:199], v250
	ds_read_b128 v[200:203], v251
	ds_write_b128 v112, v[204:207]
	ds_write_b128 v112, v[208:211] offset:1024
	ds_write_b128 v112, v[212:215] offset:2048
	ds_write_b128 v112, v[216:219] offset:3072
	v_mfma_f32_32x32x16_bf16 v[32:47], v[160:163], v[52:55], v[32:47]
	v_mfma_f32_32x32x16_bf16 v[32:47], v[164:167], v[56:59], v[32:47]
	v_mfma_f32_32x32x16_bf16 v[32:47], v[168:171], v[60:63], v[32:47]
	s_nop 11
	v_exp_f32_e32 v32, v32
	v_exp_f32_e32 v33, v33
	v_exp_f32_e32 v34, v34
	v_exp_f32_e32 v35, v35
	v_exp_f32_e32 v36, v36
	v_exp_f32_e32 v37, v37
	v_exp_f32_e32 v38, v38
	v_exp_f32_e32 v39, v39
	v_exp_f32_e32 v40, v40
	v_exp_f32_e32 v41, v41
	v_exp_f32_e32 v42, v42
	v_exp_f32_e32 v43, v43
	v_exp_f32_e32 v44, v44
	v_exp_f32_e32 v45, v45
	v_exp_f32_e32 v46, v46
	v_exp_f32_e32 v47, v47
	v_cvt_pk_bf16_f32 v64, v32, v33
	v_cvt_pk_bf16_f32 v65, v34, v35
	v_cvt_pk_bf16_f32 v66, v36, v37
	v_cvt_pk_bf16_f32 v67, v38, v39
	v_cvt_pk_bf16_f32 v68, v40, v41
	v_cvt_pk_bf16_f32 v69, v42, v43
	v_cvt_pk_bf16_f32 v70, v44, v45
	v_cvt_pk_bf16_f32 v71, v46, v47
	v_pk_add_f32 v[232:233], v[232:233], v[32:33]
	v_pk_add_f32 v[232:233], v[232:233], v[34:35]
	v_pk_add_f32 v[232:233], v[232:233], v[36:37]
	v_pk_add_f32 v[232:233], v[232:233], v[38:39]
	v_pk_add_f32 v[232:233], v[232:233], v[40:41]
	v_pk_add_f32 v[232:233], v[232:233], v[42:43]
	v_pk_add_f32 v[232:233], v[232:233], v[44:45]
	v_pk_add_f32 v[232:233], v[232:233], v[46:47]
	s_waitcnt lgkmcnt(12)
	v_mfma_f32_32x32x16_bf16 v[0:15], v[64:67], v[72:75], v[0:15]
	v_mfma_f32_32x32x16_bf16 v[16:31], v[64:67], v[76:79], v[16:31]
	v_mfma_f32_32x32x16_bf16 v[0:15], v[68:71], v[220:223], v[0:15]
	v_mfma_f32_32x32x16_bf16 v[16:31], v[68:71], v[224:227], v[16:31]
	global_load_dwordx4 v[156:159], v243, s[88:89]
	global_load_dwordx4 v[160:163], v244, s[88:89]
	global_load_dwordx4 v[164:167], v245, s[88:89]
	global_load_dwordx4 v[168:171], v246, s[88:89]
	global_load_dwordx4 v[172:175], v148, s[88:89] offset:768
	global_load_dwordx4 v[176:179], v151, s[88:89] offset:768
	global_load_dwordx4 v[180:183], v148, s[88:89] offset:832
	global_load_dwordx4 v[184:187], v151, s[88:89] offset:832
	s_add_u32 s88, s88, 0x300000
	s_addc_u32 s89, s89, 0
	ds_read2_b32 v[32:33], v115 offset0:32 offset1:33
	ds_read2_b32 v[34:35], v115 offset0:34 offset1:35
	ds_read2_b32 v[36:37], v115 offset0:40 offset1:41
	ds_read2_b32 v[38:39], v115 offset0:42 offset1:43
	ds_read2_b32 v[40:41], v115 offset0:48 offset1:49
	ds_read2_b32 v[42:43], v115 offset0:50 offset1:51
	ds_read2_b32 v[44:45], v115 offset0:56 offset1:57
	ds_read2_b32 v[46:47], v115 offset0:58 offset1:59
	s_waitcnt lgkmcnt(0)
	v_mfma_f32_32x32x16_bf16 v[32:47], v[188:191], v[48:51], v[32:47]
	ds_read_b64_tr_b16 v[72:73], v231
	ds_read_b64_tr_b16 v[74:75], v231 offset:512
	ds_read_b64_tr_b16 v[76:77], v231 offset:2048
	ds_read_b64_tr_b16 v[78:79], v231 offset:2560
	ds_read_b64_tr_b16 v[220:221], v231 offset:1024
	ds_read_b64_tr_b16 v[222:223], v231 offset:1536
	ds_read_b64_tr_b16 v[224:225], v231 offset:3072
	ds_read_b64_tr_b16 v[226:227], v231 offset:3584
	s_waitcnt vmcnt(8)
	ds_write_b128 v247, v[116:119]
	ds_write_b128 v247, v[120:123] offset:1024
	ds_write_b128 v247, v[124:127] offset:2048
	ds_write_b128 v247, v[128:131] offset:3072
	ds_read_b128 v[116:119], v248
	ds_read_b128 v[120:123], v249
	ds_read_b128 v[124:127], v250
	ds_read_b128 v[128:131], v251
	ds_write_b128 v112, v[132:135]
	ds_write_b128 v112, v[136:139] offset:1024
	ds_write_b128 v112, v[140:143] offset:2048
	ds_write_b128 v112, v[144:147] offset:3072
	v_mfma_f32_32x32x16_bf16 v[32:47], v[192:195], v[52:55], v[32:47]
	v_mfma_f32_32x32x16_bf16 v[32:47], v[196:199], v[56:59], v[32:47]
	v_mfma_f32_32x32x16_bf16 v[32:47], v[200:203], v[60:63], v[32:47]
	s_nop 11
	v_exp_f32_e32 v32, v32
	v_exp_f32_e32 v33, v33
	v_exp_f32_e32 v34, v34
	v_exp_f32_e32 v35, v35
	v_exp_f32_e32 v36, v36
	v_exp_f32_e32 v37, v37
	v_exp_f32_e32 v38, v38
	v_exp_f32_e32 v39, v39
	v_exp_f32_e32 v40, v40
	v_exp_f32_e32 v41, v41
	v_exp_f32_e32 v42, v42
	v_exp_f32_e32 v43, v43
	v_exp_f32_e32 v44, v44
	v_exp_f32_e32 v45, v45
	v_exp_f32_e32 v46, v46
	v_exp_f32_e32 v47, v47
	v_cvt_pk_bf16_f32 v64, v32, v33
	v_cvt_pk_bf16_f32 v65, v34, v35
	v_cvt_pk_bf16_f32 v66, v36, v37
	v_cvt_pk_bf16_f32 v67, v38, v39
	v_cvt_pk_bf16_f32 v68, v40, v41
	v_cvt_pk_bf16_f32 v69, v42, v43
	v_cvt_pk_bf16_f32 v70, v44, v45
	v_cvt_pk_bf16_f32 v71, v46, v47
	v_pk_add_f32 v[232:233], v[232:233], v[32:33]
	v_pk_add_f32 v[232:233], v[232:233], v[34:35]
	v_pk_add_f32 v[232:233], v[232:233], v[36:37]
	v_pk_add_f32 v[232:233], v[232:233], v[38:39]
	v_pk_add_f32 v[232:233], v[232:233], v[40:41]
	v_pk_add_f32 v[232:233], v[232:233], v[42:43]
	v_pk_add_f32 v[232:233], v[232:233], v[44:45]
	v_pk_add_f32 v[232:233], v[232:233], v[46:47]
	s_waitcnt lgkmcnt(12)
	v_mfma_f32_32x32x16_bf16 v[0:15], v[64:67], v[72:75], v[0:15]
	v_mfma_f32_32x32x16_bf16 v[16:31], v[64:67], v[76:79], v[16:31]
	v_mfma_f32_32x32x16_bf16 v[0:15], v[68:71], v[220:223], v[0:15]
	v_mfma_f32_32x32x16_bf16 v[16:31], v[68:71], v[224:227], v[16:31]
	global_load_dwordx4 v[188:191], v243, s[88:89]
	global_load_dwordx4 v[192:195], v244, s[88:89]
	global_load_dwordx4 v[196:199], v245, s[88:89]
	global_load_dwordx4 v[200:203], v246, s[88:89]
	global_load_dwordx4 v[204:207], v148, s[88:89] offset:768
	global_load_dwordx4 v[208:211], v151, s[88:89] offset:768
	global_load_dwordx4 v[212:215], v148, s[88:89] offset:832
	global_load_dwordx4 v[216:219], v151, s[88:89] offset:832
	ds_read2_b32 v[32:33], v115 offset0:64 offset1:65
	ds_read2_b32 v[34:35], v115 offset0:66 offset1:67
	ds_read2_b32 v[36:37], v115 offset0:72 offset1:73
	ds_read2_b32 v[38:39], v115 offset0:74 offset1:75
	ds_read2_b32 v[40:41], v115 offset0:80 offset1:81
	ds_read2_b32 v[42:43], v115 offset0:82 offset1:83
	ds_read2_b32 v[44:45], v115 offset0:88 offset1:89
	ds_read2_b32 v[46:47], v115 offset0:90 offset1:91
	s_waitcnt lgkmcnt(0)
	v_mfma_f32_32x32x16_bf16 v[32:47], v[116:119], v[48:51], v[32:47]
	ds_read_b64_tr_b16 v[72:73], v231
	ds_read_b64_tr_b16 v[74:75], v231 offset:512
	ds_read_b64_tr_b16 v[76:77], v231 offset:2048
	ds_read_b64_tr_b16 v[78:79], v231 offset:2560
	ds_read_b64_tr_b16 v[220:221], v231 offset:1024
	ds_read_b64_tr_b16 v[222:223], v231 offset:1536
	ds_read_b64_tr_b16 v[224:225], v231 offset:3072
	ds_read_b64_tr_b16 v[226:227], v231 offset:3584
	s_waitcnt vmcnt(8)
	ds_write_b128 v247, v[156:159]
	ds_write_b128 v247, v[160:163] offset:1024
	ds_write_b128 v247, v[164:167] offset:2048
	ds_write_b128 v247, v[168:171] offset:3072
	ds_read_b128 v[156:159], v248
	ds_read_b128 v[160:163], v249
	ds_read_b128 v[164:167], v250
	ds_read_b128 v[168:171], v251
	ds_write_b128 v112, v[172:175]
	ds_write_b128 v112, v[176:179] offset:1024
	ds_write_b128 v112, v[180:183] offset:2048
	ds_write_b128 v112, v[184:187] offset:3072
	v_mfma_f32_32x32x16_bf16 v[32:47], v[120:123], v[52:55], v[32:47]
	v_mfma_f32_32x32x16_bf16 v[32:47], v[124:127], v[56:59], v[32:47]
	v_mfma_f32_32x32x16_bf16 v[32:47], v[128:131], v[60:63], v[32:47]
	s_nop 11
	v_exp_f32_e32 v32, v32
	v_exp_f32_e32 v33, v33
	v_exp_f32_e32 v34, v34
	v_exp_f32_e32 v35, v35
	v_exp_f32_e32 v36, v36
	v_exp_f32_e32 v37, v37
	v_exp_f32_e32 v38, v38
	v_exp_f32_e32 v39, v39
	v_exp_f32_e32 v40, v40
	v_exp_f32_e32 v41, v41
	v_exp_f32_e32 v42, v42
	v_exp_f32_e32 v43, v43
	v_exp_f32_e32 v44, v44
	v_exp_f32_e32 v45, v45
	v_exp_f32_e32 v46, v46
	v_exp_f32_e32 v47, v47
	v_cvt_pk_bf16_f32 v64, v32, v33
	v_cvt_pk_bf16_f32 v65, v34, v35
	v_cvt_pk_bf16_f32 v66, v36, v37
	v_cvt_pk_bf16_f32 v67, v38, v39
	v_cvt_pk_bf16_f32 v68, v40, v41
	v_cvt_pk_bf16_f32 v69, v42, v43
	v_cvt_pk_bf16_f32 v70, v44, v45
	v_cvt_pk_bf16_f32 v71, v46, v47
	v_pk_add_f32 v[232:233], v[232:233], v[32:33]
	v_pk_add_f32 v[232:233], v[232:233], v[34:35]
	v_pk_add_f32 v[232:233], v[232:233], v[36:37]
	v_pk_add_f32 v[232:233], v[232:233], v[38:39]
	v_pk_add_f32 v[232:233], v[232:233], v[40:41]
	v_pk_add_f32 v[232:233], v[232:233], v[42:43]
	v_pk_add_f32 v[232:233], v[232:233], v[44:45]
	v_pk_add_f32 v[232:233], v[232:233], v[46:47]
	s_waitcnt lgkmcnt(12)
	v_mfma_f32_32x32x16_bf16 v[0:15], v[64:67], v[72:75], v[0:15]
	v_mfma_f32_32x32x16_bf16 v[16:31], v[64:67], v[76:79], v[16:31]
	v_mfma_f32_32x32x16_bf16 v[0:15], v[68:71], v[220:223], v[0:15]
	v_mfma_f32_32x32x16_bf16 v[16:31], v[68:71], v[224:227], v[16:31]
	ds_read2_b32 v[32:33], v115 offset0:96 offset1:97
	ds_read2_b32 v[34:35], v115 offset0:98 offset1:99
	ds_read2_b32 v[36:37], v115 offset0:104 offset1:105
	ds_read2_b32 v[38:39], v115 offset0:106 offset1:107
	ds_read2_b32 v[40:41], v115 offset0:112 offset1:113
	ds_read2_b32 v[42:43], v115 offset0:114 offset1:115
	ds_read2_b32 v[44:45], v115 offset0:120 offset1:121
	ds_read2_b32 v[46:47], v115 offset0:122 offset1:123
	s_waitcnt lgkmcnt(0)
	v_mfma_f32_32x32x16_bf16 v[32:47], v[156:159], v[48:51], v[32:47]
	ds_read_b64_tr_b16 v[72:73], v231
	ds_read_b64_tr_b16 v[74:75], v231 offset:512
	ds_read_b64_tr_b16 v[76:77], v231 offset:2048
	ds_read_b64_tr_b16 v[78:79], v231 offset:2560
	ds_read_b64_tr_b16 v[220:221], v231 offset:1024
	ds_read_b64_tr_b16 v[222:223], v231 offset:1536
	ds_read_b64_tr_b16 v[224:225], v231 offset:3072
	ds_read_b64_tr_b16 v[226:227], v231 offset:3584
	s_waitcnt vmcnt(0)
	ds_write_b128 v247, v[188:191]
	ds_write_b128 v247, v[192:195] offset:1024
	ds_write_b128 v247, v[196:199] offset:2048
	ds_write_b128 v247, v[200:203] offset:3072
	ds_read_b128 v[188:191], v248
	ds_read_b128 v[192:195], v249
	ds_read_b128 v[196:199], v250
	ds_read_b128 v[200:203], v251
	ds_write_b128 v112, v[204:207]
	ds_write_b128 v112, v[208:211] offset:1024
	ds_write_b128 v112, v[212:215] offset:2048
	ds_write_b128 v112, v[216:219] offset:3072
	v_mfma_f32_32x32x16_bf16 v[32:47], v[160:163], v[52:55], v[32:47]
	v_mfma_f32_32x32x16_bf16 v[32:47], v[164:167], v[56:59], v[32:47]
	v_mfma_f32_32x32x16_bf16 v[32:47], v[168:171], v[60:63], v[32:47]
	s_nop 11
	v_exp_f32_e32 v32, v32
	v_exp_f32_e32 v33, v33
	v_exp_f32_e32 v34, v34
	v_exp_f32_e32 v35, v35
	v_exp_f32_e32 v36, v36
	v_exp_f32_e32 v37, v37
	v_exp_f32_e32 v38, v38
	v_exp_f32_e32 v39, v39
	v_exp_f32_e32 v40, v40
	v_exp_f32_e32 v41, v41
	v_exp_f32_e32 v42, v42
	v_exp_f32_e32 v43, v43
	v_exp_f32_e32 v44, v44
	v_exp_f32_e32 v45, v45
	v_exp_f32_e32 v46, v46
	v_exp_f32_e32 v47, v47
	v_cvt_pk_bf16_f32 v64, v32, v33
	v_cvt_pk_bf16_f32 v65, v34, v35
	v_cvt_pk_bf16_f32 v66, v36, v37
	v_cvt_pk_bf16_f32 v67, v38, v39
	v_cvt_pk_bf16_f32 v68, v40, v41
	v_cvt_pk_bf16_f32 v69, v42, v43
	v_cvt_pk_bf16_f32 v70, v44, v45
	v_cvt_pk_bf16_f32 v71, v46, v47
	v_pk_add_f32 v[232:233], v[232:233], v[32:33]
	v_pk_add_f32 v[232:233], v[232:233], v[34:35]
	v_pk_add_f32 v[232:233], v[232:233], v[36:37]
	v_pk_add_f32 v[232:233], v[232:233], v[38:39]
	v_pk_add_f32 v[232:233], v[232:233], v[40:41]
	v_pk_add_f32 v[232:233], v[232:233], v[42:43]
	v_pk_add_f32 v[232:233], v[232:233], v[44:45]
	v_pk_add_f32 v[232:233], v[232:233], v[46:47]
	s_waitcnt lgkmcnt(12)
	v_mfma_f32_32x32x16_bf16 v[0:15], v[64:67], v[72:75], v[0:15]
	v_mfma_f32_32x32x16_bf16 v[16:31], v[64:67], v[76:79], v[16:31]
	v_mfma_f32_32x32x16_bf16 v[0:15], v[68:71], v[220:223], v[0:15]
	v_mfma_f32_32x32x16_bf16 v[16:31], v[68:71], v[224:227], v[16:31]
	ds_read2_b32 v[32:33], v115 offset0:128 offset1:129
	ds_read2_b32 v[34:35], v115 offset0:130 offset1:131
	ds_read2_b32 v[36:37], v115 offset0:136 offset1:137
	ds_read2_b32 v[38:39], v115 offset0:138 offset1:139
	ds_read2_b32 v[40:41], v115 offset0:144 offset1:145
	ds_read2_b32 v[42:43], v115 offset0:146 offset1:147
	ds_read2_b32 v[44:45], v115 offset0:152 offset1:153
	ds_read2_b32 v[46:47], v115 offset0:154 offset1:155
	s_waitcnt lgkmcnt(0)
; #define LAS __attribute__((address_space(3)))
; #define GAS __attribute__((address_space(1)))
; __device__ __forceinline__ int crow(int r, int hi) { return (r & 3) + 8 * (r >> 2) + 4 * hi; }
; __device__ __forceinline__ void dil_unit(LAS unsigned char* lds, bf16_t* proj, int seq, int hd, int T0, int rho) {
;     int tid_ = threadIdx.x; asm volatile("" : "+v"(tid_));
;     const int tid = tid_, lane = tid & 63, r32 = lane & 31, hi = lane >> 5, wid = __builtin_amdgcn_readfirstlane(tid >> 6);
;     bf16_t* base = proj + (size_t)seq * SEQ * NIN;
;     LAS unsigned char* wbuf = lds + wid * 4096;
;     const LAS unsigned char* vp = wbuf + ((lane >> 4) & 1) * 32 + (lane & 3) * 8 + (4 * hi + ((lane & 15) >> 2)) * 64;
;     const int P0 = T0 + rho;
;     bf16x8 qr[4];
; #pragma unroll
;     for (int ks = 0; ks < 4; ++ks) qr[ks] = *(const GAS bf16x8*)(base + (size_t)(P0 + 16 * r32) * NIN + PC_LQ + hd * 64 + 16 * ks + 8 * hi);
;     f32x16 o0 = {}, o1 = {}; float l = 0.f;
;     const bool bound = (T0 < 1024) || (T0 >= 15360);
;     ...
;     if (bound) DIL_LOOP(true); else DIL_LOOP(false);
;     ...
;     LAS bf16_t* stg = (LAS bf16_t*)wbuf;
;     l += __shfl_xor(l, 32);
; #pragma unroll
;     for (int rr = 0; rr < 16; ++rr) {
;         const int j = crow(rr, hi);
;         const float il = __builtin_amdgcn_rcpf(__shfl(l, j));
	v_mfma_f32_32x32x16_bf16 v[32:47], v[188:191], v[48:51], v[32:47]
	ds_read_b64_tr_b16 v[72:73], v231
	ds_read_b64_tr_b16 v[74:75], v231 offset:512
	ds_read_b64_tr_b16 v[76:77], v231 offset:2048
	ds_read_b64_tr_b16 v[78:79], v231 offset:2560
	ds_read_b64_tr_b16 v[220:221], v231 offset:1024
	ds_read_b64_tr_b16 v[222:223], v231 offset:1536
	ds_read_b64_tr_b16 v[224:225], v231 offset:3072
	ds_read_b64_tr_b16 v[226:227], v231 offset:3584
	v_mfma_f32_32x32x16_bf16 v[32:47], v[192:195], v[52:55], v[32:47]
	v_mfma_f32_32x32x16_bf16 v[32:47], v[196:199], v[56:59], v[32:47]
	v_mfma_f32_32x32x16_bf16 v[32:47], v[200:203], v[60:63], v[32:47]
	s_nop 11
	v_exp_f32_e32 v32, v32
	v_exp_f32_e32 v33, v33
	v_exp_f32_e32 v34, v34
	v_exp_f32_e32 v35, v35
	v_exp_f32_e32 v36, v36
	v_exp_f32_e32 v37, v37
	v_exp_f32_e32 v38, v38
	v_exp_f32_e32 v39, v39
	v_exp_f32_e32 v40, v40
	v_exp_f32_e32 v41, v41
	v_exp_f32_e32 v42, v42
	v_exp_f32_e32 v43, v43
	v_exp_f32_e32 v44, v44
	v_exp_f32_e32 v45, v45
	v_exp_f32_e32 v46, v46
	v_exp_f32_e32 v47, v47
	v_cvt_pk_bf16_f32 v64, v32, v33
	v_cvt_pk_bf16_f32 v65, v34, v35
	v_cvt_pk_bf16_f32 v66, v36, v37
	v_cvt_pk_bf16_f32 v67, v38, v39
	v_cvt_pk_bf16_f32 v68, v40, v41
	v_cvt_pk_bf16_f32 v69, v42, v43
	v_cvt_pk_bf16_f32 v70, v44, v45
	v_cvt_pk_bf16_f32 v71, v46, v47
	v_pk_add_f32 v[232:233], v[232:233], v[32:33]
	v_pk_add_f32 v[232:233], v[232:233], v[34:35]
	v_pk_add_f32 v[232:233], v[232:233], v[36:37]
	v_pk_add_f32 v[232:233], v[232:233], v[38:39]
	v_pk_add_f32 v[232:233], v[232:233], v[40:41]
	v_pk_add_f32 v[232:233], v[232:233], v[42:43]
	v_pk_add_f32 v[232:233], v[232:233], v[44:45]
	v_pk_add_f32 v[232:233], v[232:233], v[46:47]
	s_waitcnt lgkmcnt(0)
	v_mfma_f32_32x32x16_bf16 v[0:15], v[64:67], v[72:75], v[0:15]
	v_mfma_f32_32x32x16_bf16 v[16:31], v[64:67], v[76:79], v[16:31]
	v_mfma_f32_32x32x16_bf16 v[0:15], v[68:71], v[220:223], v[0:15]
	v_mfma_f32_32x32x16_bf16 v[16:31], v[68:71], v[224:227], v[16:31]
	v_add_f32_e32 v113, v232, v233
	v_or_b32_e32 v114, 1, v107
	v_or_b32_e32 v97, 2, v107
	v_or_b32_e32 v96, 3, v107
	v_or_b32_e32 v95, 8, v107
	v_or_b32_e32 v94, 9, v107
	v_or_b32_e32 v93, 10, v107
	v_or_b32_e32 v92, 11, v107
	v_or_b32_e32 v91, 16, v107
	v_or_b32_e32 v90, 17, v107
	v_or_b32_e32 v89, 18, v107
	v_or_b32_e32 v88, 19, v107
	v_or_b32_e32 v87, 24, v107
	v_or_b32_e32 v86, 25, v107
	v_or_b32_e32 v85, 26, v107
	v_or_b32_e32 v84, 27, v107
	s_nop 11
	s_branch .LBB0_1265
.LBB0_1270:
	s_movk_i32 s100, 0x1800
	s_add_i32 s101, s8, 0x15c00
	s_lshl_b32 s90, s54, 1
	s_add_u32 s82, s52, s90
	s_addc_u32 s83, s53, 0
	s_add_u32 s82, s82, 0x1200
	s_addc_u32 s83, s83, 0
	s_sub_i32 s90, s67, 64
	s_mul_i32 s90, s90, 0x1800
	s_add_u32 s84, s82, s90
	s_addc_u32 s85, s83, 0
	s_sub_i32 s90, s67, 256
	s_mul_i32 s90, s90, 0x1800
	s_add_u32 s86, s82, s90
	s_addc_u32 s87, s83, 0
	s_sub_i32 s90, s67, 1024
	s_mul_i32 s90, s90, 0x1800
	s_add_u32 s88, s82, s90
	s_addc_u32 s89, s83, 0
	v_lshlrev_b32_e32 v153, 1, v98
	v_mad_u32_u24 v80, v105, s100, v82
	v_mad_u32_u24 v100, v110, s100, v153
	v_add_u32_e32 v149, 0x18000, v100
	v_lshlrev_b32_e32 v83, 2, v105
	v_mad_u32_u24 v83, v83, s100, v82
	v_lshlrev_b32_e32 v101, 2, v110
	v_mad_u32_u24 v101, v101, s100, v153
	v_add_u32_e32 v150, 0x60000, v101
	v_lshlrev_b32_e32 v99, 4, v105
	v_mad_u32_u24 v99, v99, s100, v82
	v_lshlrev_b32_e32 v148, 4, v110
	v_mad_u32_u24 v148, v148, s100, v153
	v_add_u32_e32 v151, 0x180000, v148
	v_lshrrev_b32_e32 v249, 3, v103
	v_and_b32_e32 v250, 7, v103
	v_lshlrev_b32_e32 v250, 4, v250
	v_add_u32_e32 v235, 0, v249
	v_add_u32_e32 v236, 8, v249
	v_add_u32_e32 v237, 16, v249
	v_add_u32_e32 v238, 24, v249
	v_add_u32_e32 v239, 0, v249
	v_lshlrev_b32_e32 v239, 2, v239
	v_add_u32_e32 v240, 8, v249
	v_lshlrev_b32_e32 v240, 2, v240
	v_add_u32_e32 v241, 16, v249
	v_lshlrev_b32_e32 v241, 2, v241
	v_add_u32_e32 v242, 24, v249
	v_lshlrev_b32_e32 v242, 2, v242
	v_add_u32_e32 v243, 0, v249
	v_lshlrev_b32_e32 v243, 4, v243
	v_add_u32_e32 v244, 8, v249
	v_lshlrev_b32_e32 v244, 4, v244
	v_add_u32_e32 v245, 16, v249
	v_lshlrev_b32_e32 v245, 4, v245
	v_add_u32_e32 v246, 24, v249
	v_lshlrev_b32_e32 v246, 4, v246
	v_mov_b32_e32 v252, v250
	v_mov_b32_e32 v100, v110
	v_add_u32_e32 v149, 16, v100
	v_lshlrev_b32_e32 v101, 2, v110
	v_add_u32_e32 v150, 64, v101
	v_lshlrev_b32_e32 v148, 4, v110
	v_add_u32_e32 v151, 256, v148
	s_mov_b32 s98, 0x4000
	s_mov_b32 s99, 0x3fff
	v_and_b32_e32 v247, 7, v249
	v_lshlrev_b32_e32 v247, 4, v247
	v_xor_b32_e32 v247, v247, v112
	v_and_b32_e32 v153, 7, v105
	v_or_b32_e32 v248, 0, v106
	v_xor_b32_e32 v248, v248, v153
	v_lshlrev_b32_e32 v248, 4, v248
	v_lshl_add_u32 v248, v105, 7, v248
	v_add_u32_e32 v248, s69, v248
	v_or_b32_e32 v249, 2, v106
	v_xor_b32_e32 v249, v249, v153
	v_lshlrev_b32_e32 v249, 4, v249
	v_lshl_add_u32 v249, v105, 7, v249
	v_add_u32_e32 v249, s69, v249
	v_or_b32_e32 v250, 4, v106
	v_xor_b32_e32 v250, v250, v153
	v_lshlrev_b32_e32 v250, 4, v250
	v_lshl_add_u32 v250, v105, 7, v250
	v_add_u32_e32 v250, s69, v250
	v_or_b32_e32 v251, 6, v106
	v_xor_b32_e32 v251, v251, v153
	v_lshlrev_b32_e32 v251, 4, v251
	v_lshl_add_u32 v251, v105, 7, v251
	v_add_u32_e32 v251, s69, v251
	v_lshlrev_b32_e32 v153, 1, v98
	v_mul_u32_u24_e32 v228, 17, v105
	v_sub_u32_e32 v228, v107, v228
	s_mul_i32 s90, s54, 153
	s_lshr_b32 s90, s90, 1
	s_add_i32 s90, s90, 34876
	v_lshl_add_u32 v228, v228, 2, s90
	v_mul_u32_u24_e32 v229, 5, v105
	v_sub_u32_e32 v229, v107, v229
	v_add_u32_e32 v229, v229, v106
	s_mul_i32 s90, s54, 30
	s_add_i32 s90, s90, 66156
	v_lshl_add_u32 v229, v229, 2, s90
	v_sub_u32_e32 v230, v107, v105
	s_add_i32 s90, s101, 6364
	v_lshl_add_u32 v230, v230, 2, s90
; __device__ __forceinline__ void dil_unit(LAS unsigned char* lds, bf16_t* proj, int seq, int hd, int T0, int rho) {
;     ...
;     f32x16 o0 = {}, o1 = {}; float l = 0.f;
;     const bool bound = (T0 < 1024) || (T0 >= 15360);
	v_add_u32_e32 v231, v109, v108
	v_mov_b64_e32 v[232:233], 0
	v_mov_b64_e32 v[0:1], 0
	v_mov_b64_e32 v[2:3], 0
	v_mov_b64_e32 v[4:5], 0
	v_mov_b64_e32 v[6:7], 0
	v_mov_b64_e32 v[8:9], 0
	v_mov_b64_e32 v[10:11], 0
	v_mov_b64_e32 v[12:13], 0
	v_mov_b64_e32 v[14:15], 0
	v_mov_b64_e32 v[16:17], 0
	v_mov_b64_e32 v[18:19], 0
	v_mov_b64_e32 v[20:21], 0
	v_mov_b64_e32 v[22:23], 0
	v_mov_b64_e32 v[24:25], 0
	v_mov_b64_e32 v[26:27], 0
	v_mov_b64_e32 v[28:29], 0
	v_mov_b64_e32 v[30:31], 0
	s_add_i32 s90, s67, -64
	v_add_u32_e32 v80, s90, v235
	v_add_u32_e32 v83, s90, v236
	v_add_u32_e32 v99, s90, v237
	v_add_u32_e32 v253, s90, v238
	v_add_u32_e32 v254, s90, v100
	v_add_u32_e32 v255, s90, v149
	v_med3_i32 v80, v80, 0, s99
	v_med3_i32 v83, v83, 0, s99
	v_med3_i32 v99, v99, 0, s99
	v_med3_i32 v253, v253, 0, s99
	v_med3_i32 v254, v254, 0, s99
	v_med3_i32 v255, v255, 0, s99
	v_mad_u32_u24 v80, v80, s100, v252
	v_mad_u32_u24 v83, v83, s100, v252
	v_mad_u32_u24 v99, v99, s100, v252
	v_mad_u32_u24 v253, v253, s100, v252
	v_mad_u32_u24 v254, v254, s100, v153
	v_mad_u32_u24 v255, v255, s100, v153
	global_load_dwordx4 v[116:119], v80, s[82:83]
	global_load_dwordx4 v[120:123], v83, s[82:83]
	global_load_dwordx4 v[124:127], v99, s[82:83]
	global_load_dwordx4 v[128:131], v253, s[82:83]
	global_load_dwordx4 v[132:135], v254, s[82:83] offset:768
	global_load_dwordx4 v[136:139], v255, s[82:83] offset:768
	global_load_dwordx4 v[140:143], v254, s[82:83] offset:832
	global_load_dwordx4 v[144:147], v255, s[82:83] offset:832
	s_add_i32 s90, s67, -32
	v_add_u32_e32 v80, s90, v235
	v_add_u32_e32 v83, s90, v236
	v_add_u32_e32 v99, s90, v237
	v_add_u32_e32 v253, s90, v238
	v_add_u32_e32 v254, s90, v100
	v_add_u32_e32 v255, s90, v149
	v_med3_i32 v80, v80, 0, s99
	v_med3_i32 v83, v83, 0, s99
	v_med3_i32 v99, v99, 0, s99
	v_med3_i32 v253, v253, 0, s99
	v_med3_i32 v254, v254, 0, s99
	v_med3_i32 v255, v255, 0, s99
	v_mad_u32_u24 v80, v80, s100, v252
	v_mad_u32_u24 v83, v83, s100, v252
	v_mad_u32_u24 v99, v99, s100, v252
	v_mad_u32_u24 v253, v253, s100, v252
	v_mad_u32_u24 v254, v254, s100, v153
	v_mad_u32_u24 v255, v255, s100, v153
	global_load_dwordx4 v[156:159], v80, s[82:83]
	global_load_dwordx4 v[160:163], v83, s[82:83]
	global_load_dwordx4 v[164:167], v99, s[82:83]
	global_load_dwordx4 v[168:171], v253, s[82:83]
	global_load_dwordx4 v[172:175], v254, s[82:83] offset:768
	global_load_dwordx4 v[176:179], v255, s[82:83] offset:768
	global_load_dwordx4 v[180:183], v254, s[82:83] offset:832
	global_load_dwordx4 v[184:187], v255, s[82:83] offset:832
	s_add_i32 s90, s67, 0
	v_add_u32_e32 v80, s90, v235
	v_add_u32_e32 v83, s90, v236
	v_add_u32_e32 v99, s90, v237
	v_add_u32_e32 v253, s90, v238
	v_add_u32_e32 v254, s90, v100
	v_add_u32_e32 v255, s90, v149
	v_med3_i32 v80, v80, 0, s99
	v_med3_i32 v83, v83, 0, s99
	v_med3_i32 v99, v99, 0, s99
	v_med3_i32 v253, v253, 0, s99
	v_med3_i32 v254, v254, 0, s99
	v_med3_i32 v255, v255, 0, s99
	v_mad_u32_u24 v80, v80, s100, v252
	v_mad_u32_u24 v83, v83, s100, v252
	v_mad_u32_u24 v99, v99, s100, v252
	v_mad_u32_u24 v253, v253, s100, v252
	v_mad_u32_u24 v254, v254, s100, v153
	v_mad_u32_u24 v255, v255, s100, v153
	global_load_dwordx4 v[188:191], v80, s[82:83]
	global_load_dwordx4 v[192:195], v83, s[82:83]
	global_load_dwordx4 v[196:199], v99, s[82:83]
	global_load_dwordx4 v[200:203], v253, s[82:83]
	global_load_dwordx4 v[204:207], v254, s[82:83] offset:768
	global_load_dwordx4 v[208:211], v255, s[82:83] offset:768
	global_load_dwordx4 v[212:215], v254, s[82:83] offset:832
	global_load_dwordx4 v[216:219], v255, s[82:83] offset:832
	s_waitcnt vmcnt(16)
	ds_write_b128 v247, v[116:119]
	ds_write_b128 v247, v[120:123] offset:1024
	ds_write_b128 v247, v[124:127] offset:2048
	ds_write_b128 v247, v[128:131] offset:3072
	ds_read_b128 v[116:119], v248
	ds_read_b128 v[120:123], v249
	ds_read_b128 v[124:127], v250
	ds_read_b128 v[128:131], v251
	ds_write_b128 v112, v[132:135]
	ds_write_b128 v112, v[136:139] offset:1024
	ds_write_b128 v112, v[140:143] offset:2048
	ds_write_b128 v112, v[144:147] offset:3072
	v_mov_b32_e32 v115, v228
	ds_read2_b32 v[32:33], v115 offset0:0 offset1:1
	ds_read2_b32 v[34:35], v115 offset0:2 offset1:3
	ds_read2_b32 v[36:37], v115 offset0:8 offset1:9
	ds_read2_b32 v[38:39], v115 offset0:10 offset1:11
	ds_read2_b32 v[40:41], v115 offset0:17 offset1:18
	ds_read2_b32 v[42:43], v115 offset0:19 offset1:20
	ds_read2_b32 v[44:45], v115 offset0:25 offset1:26
	ds_read2_b32 v[46:47], v115 offset0:27 offset1:28
	s_waitcnt lgkmcnt(0)
	v_mfma_f32_32x32x16_bf16 v[32:47], v[116:119], v[48:51], v[32:47]
	ds_read_b64_tr_b16 v[72:73], v231
	ds_read_b64_tr_b16 v[74:75], v231 offset:512
	ds_read_b64_tr_b16 v[76:77], v231 offset:2048
	ds_read_b64_tr_b16 v[78:79], v231 offset:2560
	ds_read_b64_tr_b16 v[220:221], v231 offset:1024
	ds_read_b64_tr_b16 v[222:223], v231 offset:1536
	ds_read_b64_tr_b16 v[224:225], v231 offset:3072
	ds_read_b64_tr_b16 v[226:227], v231 offset:3584
	s_waitcnt vmcnt(8)
	ds_write_b128 v247, v[156:159]
	ds_write_b128 v247, v[160:163] offset:1024
	ds_write_b128 v247, v[164:167] offset:2048
	ds_write_b128 v247, v[168:171] offset:3072
	ds_read_b128 v[156:159], v248
	ds_read_b128 v[160:163], v249
	ds_read_b128 v[164:167], v250
	ds_read_b128 v[168:171], v251
	ds_write_b128 v112, v[172:175]
	ds_write_b128 v112, v[176:179] offset:1024
	ds_write_b128 v112, v[180:183] offset:2048
	ds_write_b128 v112, v[184:187] offset:3072
	v_mfma_f32_32x32x16_bf16 v[32:47], v[120:123], v[52:55], v[32:47]
	v_mfma_f32_32x32x16_bf16 v[32:47], v[124:127], v[56:59], v[32:47]
	v_mfma_f32_32x32x16_bf16 v[32:47], v[128:131], v[60:63], v[32:47]
	s_nop 11
	v_exp_f32_e32 v32, v32
	v_exp_f32_e32 v33, v33
	v_exp_f32_e32 v34, v34
	v_exp_f32_e32 v35, v35
	v_exp_f32_e32 v36, v36
	v_exp_f32_e32 v37, v37
	v_exp_f32_e32 v38, v38
	v_exp_f32_e32 v39, v39
	v_exp_f32_e32 v40, v40
	v_exp_f32_e32 v41, v41
	v_exp_f32_e32 v42, v42
	v_exp_f32_e32 v43, v43
	v_exp_f32_e32 v44, v44
	v_exp_f32_e32 v45, v45
	v_exp_f32_e32 v46, v46
	v_exp_f32_e32 v47, v47
	s_add_i32 s90, s67, -64
	v_add_u32_e32 v84, s90, v107
	v_add_u32_e32 v85, 0, v84
	v_add_u32_e32 v86, 1, v84
	v_add_u32_e32 v87, 2, v84
	v_add_u32_e32 v88, 3, v84
	v_cmp_gt_u32_e64 s[30:31], s98, v85
	v_cmp_gt_u32_e64 s[36:37], s98, v86
	v_cmp_gt_u32_e64 s[78:79], s98, v87
	v_cmp_gt_u32_e64 s[50:51], s98, v88
	v_cndmask_b32_e64 v32, 0, v32, s[30:31]
	v_add_u32_e32 v85, 8, v84
	v_cmp_gt_u32_e64 s[30:31], s98, v85
	v_cndmask_b32_e64 v33, 0, v33, s[36:37]
	v_add_u32_e32 v86, 9, v84
	v_cmp_gt_u32_e64 s[36:37], s98, v86
	v_cndmask_b32_e64 v34, 0, v34, s[78:79]
	v_add_u32_e32 v87, 10, v84
	v_cmp_gt_u32_e64 s[78:79], s98, v87
	v_cndmask_b32_e64 v35, 0, v35, s[50:51]
	v_add_u32_e32 v88, 11, v84
	v_cmp_gt_u32_e64 s[50:51], s98, v88
	v_cndmask_b32_e64 v36, 0, v36, s[30:31]
	v_add_u32_e32 v85, 16, v84
	v_cmp_gt_u32_e64 s[30:31], s98, v85
	v_cndmask_b32_e64 v37, 0, v37, s[36:37]
	v_add_u32_e32 v86, 17, v84
	v_cmp_gt_u32_e64 s[36:37], s98, v86
	v_cndmask_b32_e64 v38, 0, v38, s[78:79]
	v_add_u32_e32 v87, 18, v84
	v_cmp_gt_u32_e64 s[78:79], s98, v87
	v_cndmask_b32_e64 v39, 0, v39, s[50:51]
	v_add_u32_e32 v88, 19, v84
	v_cmp_gt_u32_e64 s[50:51], s98, v88
	v_cndmask_b32_e64 v40, 0, v40, s[30:31]
	v_add_u32_e32 v85, 24, v84
	v_cmp_gt_u32_e64 s[30:31], s98, v85
	v_cndmask_b32_e64 v41, 0, v41, s[36:37]
	v_add_u32_e32 v86, 25, v84
	v_cmp_gt_u32_e64 s[36:37], s98, v86
	v_cndmask_b32_e64 v42, 0, v42, s[78:79]
	v_add_u32_e32 v87, 26, v84
	v_cmp_gt_u32_e64 s[78:79], s98, v87
	v_cndmask_b32_e64 v43, 0, v43, s[50:51]
	v_add_u32_e32 v88, 27, v84
	v_cmp_gt_u32_e64 s[50:51], s98, v88
	v_nop
	v_cndmask_b32_e64 v44, 0, v44, s[30:31]
	v_cndmask_b32_e64 v45, 0, v45, s[36:37]
	v_cndmask_b32_e64 v46, 0, v46, s[78:79]
	v_cndmask_b32_e64 v47, 0, v47, s[50:51]
	v_cvt_pk_bf16_f32 v64, v32, v33
	v_cvt_pk_bf16_f32 v65, v34, v35
	v_cvt_pk_bf16_f32 v66, v36, v37
	v_cvt_pk_bf16_f32 v67, v38, v39
	v_cvt_pk_bf16_f32 v68, v40, v41
	v_cvt_pk_bf16_f32 v69, v42, v43
	v_cvt_pk_bf16_f32 v70, v44, v45
	v_cvt_pk_bf16_f32 v71, v46, v47
	v_pk_add_f32 v[232:233], v[232:233], v[32:33]
	v_pk_add_f32 v[232:233], v[232:233], v[34:35]
	v_pk_add_f32 v[232:233], v[232:233], v[36:37]
	v_pk_add_f32 v[232:233], v[232:233], v[38:39]
	v_pk_add_f32 v[232:233], v[232:233], v[40:41]
	v_pk_add_f32 v[232:233], v[232:233], v[42:43]
	v_pk_add_f32 v[232:233], v[232:233], v[44:45]
	v_pk_add_f32 v[232:233], v[232:233], v[46:47]
	s_waitcnt lgkmcnt(12)
	v_mfma_f32_32x32x16_bf16 v[0:15], v[64:67], v[72:75], v[0:15]
	v_mfma_f32_32x32x16_bf16 v[16:31], v[64:67], v[76:79], v[16:31]
	v_mfma_f32_32x32x16_bf16 v[0:15], v[68:71], v[220:223], v[0:15]
	v_mfma_f32_32x32x16_bf16 v[16:31], v[68:71], v[224:227], v[16:31]
	s_add_i32 s90, s67, 32
	v_add_u32_e32 v80, s90, v235
	v_add_u32_e32 v83, s90, v236
	v_add_u32_e32 v99, s90, v237
	v_add_u32_e32 v253, s90, v238
	v_add_u32_e32 v254, s90, v100
	v_add_u32_e32 v255, s90, v149
	v_med3_i32 v80, v80, 0, s99
	v_med3_i32 v83, v83, 0, s99
	v_med3_i32 v99, v99, 0, s99
	v_med3_i32 v253, v253, 0, s99
	v_med3_i32 v254, v254, 0, s99
	v_med3_i32 v255, v255, 0, s99
	v_mad_u32_u24 v80, v80, s100, v252
	v_mad_u32_u24 v83, v83, s100, v252
	v_mad_u32_u24 v99, v99, s100, v252
	v_mad_u32_u24 v253, v253, s100, v252
	v_mad_u32_u24 v254, v254, s100, v153
	v_mad_u32_u24 v255, v255, s100, v153
	global_load_dwordx4 v[116:119], v80, s[82:83]
	global_load_dwordx4 v[120:123], v83, s[82:83]
	global_load_dwordx4 v[124:127], v99, s[82:83]
	global_load_dwordx4 v[128:131], v253, s[82:83]
	global_load_dwordx4 v[132:135], v254, s[82:83] offset:768
	global_load_dwordx4 v[136:139], v255, s[82:83] offset:768
	global_load_dwordx4 v[140:143], v254, s[82:83] offset:832
	global_load_dwordx4 v[144:147], v255, s[82:83] offset:832
	ds_read2_b32 v[32:33], v115 offset0:34 offset1:35
	ds_read2_b32 v[34:35], v115 offset0:36 offset1:37
	ds_read2_b32 v[36:37], v115 offset0:42 offset1:43
	ds_read2_b32 v[38:39], v115 offset0:44 offset1:45
	ds_read2_b32 v[40:41], v115 offset0:51 offset1:52
	ds_read2_b32 v[42:43], v115 offset0:53 offset1:54
	ds_read2_b32 v[44:45], v115 offset0:59 offset1:60
	ds_read2_b32 v[46:47], v115 offset0:61 offset1:62
	s_waitcnt lgkmcnt(0)
	v_mfma_f32_32x32x16_bf16 v[32:47], v[156:159], v[48:51], v[32:47]
	ds_read_b64_tr_b16 v[72:73], v231
	ds_read_b64_tr_b16 v[74:75], v231 offset:512
	ds_read_b64_tr_b16 v[76:77], v231 offset:2048
	ds_read_b64_tr_b16 v[78:79], v231 offset:2560
	ds_read_b64_tr_b16 v[220:221], v231 offset:1024
	ds_read_b64_tr_b16 v[222:223], v231 offset:1536
	ds_read_b64_tr_b16 v[224:225], v231 offset:3072
	ds_read_b64_tr_b16 v[226:227], v231 offset:3584
	s_waitcnt vmcnt(8)
	ds_write_b128 v247, v[188:191]
	ds_write_b128 v247, v[192:195] offset:1024
	ds_write_b128 v247, v[196:199] offset:2048
	ds_write_b128 v247, v[200:203] offset:3072
	ds_read_b128 v[188:191], v248
	ds_read_b128 v[192:195], v249
	ds_read_b128 v[196:199], v250
	ds_read_b128 v[200:203], v251
	ds_write_b128 v112, v[204:207]
	ds_write_b128 v112, v[208:211] offset:1024
	ds_write_b128 v112, v[212:215] offset:2048
	ds_write_b128 v112, v[216:219] offset:3072
	v_mfma_f32_32x32x16_bf16 v[32:47], v[160:163], v[52:55], v[32:47]
	v_mfma_f32_32x32x16_bf16 v[32:47], v[164:167], v[56:59], v[32:47]
	v_mfma_f32_32x32x16_bf16 v[32:47], v[168:171], v[60:63], v[32:47]
	s_nop 11
	v_exp_f32_e32 v32, v32
	v_exp_f32_e32 v33, v33
	v_exp_f32_e32 v34, v34
	v_exp_f32_e32 v35, v35
	v_exp_f32_e32 v36, v36
	v_exp_f32_e32 v37, v37
	v_exp_f32_e32 v38, v38
	v_exp_f32_e32 v39, v39
	v_exp_f32_e32 v40, v40
	v_exp_f32_e32 v41, v41
	v_exp_f32_e32 v42, v42
	v_exp_f32_e32 v43, v43
	v_exp_f32_e32 v44, v44
	v_exp_f32_e32 v45, v45
	v_exp_f32_e32 v46, v46
	v_exp_f32_e32 v47, v47
	s_add_i32 s90, s67, -32
	v_add_u32_e32 v84, s90, v107
	v_add_u32_e32 v85, 0, v84
	v_add_u32_e32 v86, 1, v84
	v_add_u32_e32 v87, 2, v84
	v_add_u32_e32 v88, 3, v84
	v_cmp_gt_u32_e64 s[30:31], s98, v85
	v_cmp_gt_u32_e64 s[36:37], s98, v86
	v_cmp_gt_u32_e64 s[78:79], s98, v87
	v_cmp_gt_u32_e64 s[50:51], s98, v88
	v_cndmask_b32_e64 v32, 0, v32, s[30:31]
	v_add_u32_e32 v85, 8, v84
	v_cmp_gt_u32_e64 s[30:31], s98, v85
	v_cndmask_b32_e64 v33, 0, v33, s[36:37]
	v_add_u32_e32 v86, 9, v84
	v_cmp_gt_u32_e64 s[36:37], s98, v86
	v_cndmask_b32_e64 v34, 0, v34, s[78:79]
	v_add_u32_e32 v87, 10, v84
	v_cmp_gt_u32_e64 s[78:79], s98, v87
	v_cndmask_b32_e64 v35, 0, v35, s[50:51]
	v_add_u32_e32 v88, 11, v84
	v_cmp_gt_u32_e64 s[50:51], s98, v88
	v_cndmask_b32_e64 v36, 0, v36, s[30:31]
	v_add_u32_e32 v85, 16, v84
	v_cmp_gt_u32_e64 s[30:31], s98, v85
	v_cndmask_b32_e64 v37, 0, v37, s[36:37]
	v_add_u32_e32 v86, 17, v84
	v_cmp_gt_u32_e64 s[36:37], s98, v86
	v_cndmask_b32_e64 v38, 0, v38, s[78:79]
	v_add_u32_e32 v87, 18, v84
	v_cmp_gt_u32_e64 s[78:79], s98, v87
	v_cndmask_b32_e64 v39, 0, v39, s[50:51]
	v_add_u32_e32 v88, 19, v84
	v_cmp_gt_u32_e64 s[50:51], s98, v88
	v_cndmask_b32_e64 v40, 0, v40, s[30:31]
	v_add_u32_e32 v85, 24, v84
	v_cmp_gt_u32_e64 s[30:31], s98, v85
	v_cndmask_b32_e64 v41, 0, v41, s[36:37]
	v_add_u32_e32 v86, 25, v84
	v_cmp_gt_u32_e64 s[36:37], s98, v86
	v_cndmask_b32_e64 v42, 0, v42, s[78:79]
	v_add_u32_e32 v87, 26, v84
	v_cmp_gt_u32_e64 s[78:79], s98, v87
	v_cndmask_b32_e64 v43, 0, v43, s[50:51]
	v_add_u32_e32 v88, 27, v84
	v_cmp_gt_u32_e64 s[50:51], s98, v88
	v_nop
	v_cndmask_b32_e64 v44, 0, v44, s[30:31]
	v_cndmask_b32_e64 v45, 0, v45, s[36:37]
	v_cndmask_b32_e64 v46, 0, v46, s[78:79]
	v_cndmask_b32_e64 v47, 0, v47, s[50:51]
	v_cvt_pk_bf16_f32 v64, v32, v33
	v_cvt_pk_bf16_f32 v65, v34, v35
	v_cvt_pk_bf16_f32 v66, v36, v37
	v_cvt_pk_bf16_f32 v67, v38, v39
	v_cvt_pk_bf16_f32 v68, v40, v41
	v_cvt_pk_bf16_f32 v69, v42, v43
	v_cvt_pk_bf16_f32 v70, v44, v45
	v_cvt_pk_bf16_f32 v71, v46, v47
	v_pk_add_f32 v[232:233], v[232:233], v[32:33]
	v_pk_add_f32 v[232:233], v[232:233], v[34:35]
	v_pk_add_f32 v[232:233], v[232:233], v[36:37]
	v_pk_add_f32 v[232:233], v[232:233], v[38:39]
	v_pk_add_f32 v[232:233], v[232:233], v[40:41]
	v_pk_add_f32 v[232:233], v[232:233], v[42:43]
	v_pk_add_f32 v[232:233], v[232:233], v[44:45]
	v_pk_add_f32 v[232:233], v[232:233], v[46:47]
	s_waitcnt lgkmcnt(12)
	v_mfma_f32_32x32x16_bf16 v[0:15], v[64:67], v[72:75], v[0:15]
	v_mfma_f32_32x32x16_bf16 v[16:31], v[64:67], v[76:79], v[16:31]
	v_mfma_f32_32x32x16_bf16 v[0:15], v[68:71], v[220:223], v[0:15]
	v_mfma_f32_32x32x16_bf16 v[16:31], v[68:71], v[224:227], v[16:31]
	s_add_i32 s90, s67, 64
	v_add_u32_e32 v80, s90, v235
	v_add_u32_e32 v83, s90, v236
	v_add_u32_e32 v99, s90, v237
	v_add_u32_e32 v253, s90, v238
	v_add_u32_e32 v254, s90, v100
	v_add_u32_e32 v255, s90, v149
	v_med3_i32 v80, v80, 0, s99
	v_med3_i32 v83, v83, 0, s99
	v_med3_i32 v99, v99, 0, s99
	v_med3_i32 v253, v253, 0, s99
	v_med3_i32 v254, v254, 0, s99
	v_med3_i32 v255, v255, 0, s99
	v_mad_u32_u24 v80, v80, s100, v252
	v_mad_u32_u24 v83, v83, s100, v252
	v_mad_u32_u24 v99, v99, s100, v252
	v_mad_u32_u24 v253, v253, s100, v252
	v_mad_u32_u24 v254, v254, s100, v153
	v_mad_u32_u24 v255, v255, s100, v153
	global_load_dwordx4 v[156:159], v80, s[82:83]
	global_load_dwordx4 v[160:163], v83, s[82:83]
	global_load_dwordx4 v[164:167], v99, s[82:83]
	global_load_dwordx4 v[168:171], v253, s[82:83]
	global_load_dwordx4 v[172:175], v254, s[82:83] offset:768
	global_load_dwordx4 v[176:179], v255, s[82:83] offset:768
	global_load_dwordx4 v[180:183], v254, s[82:83] offset:832
	global_load_dwordx4 v[184:187], v255, s[82:83] offset:832
	ds_read2_b32 v[32:33], v115 offset0:68 offset1:69
	ds_read2_b32 v[34:35], v115 offset0:70 offset1:71
	ds_read2_b32 v[36:37], v115 offset0:76 offset1:77
	ds_read2_b32 v[38:39], v115 offset0:78 offset1:79
	ds_read2_b32 v[40:41], v115 offset0:85 offset1:86
	ds_read2_b32 v[42:43], v115 offset0:87 offset1:88
	ds_read2_b32 v[44:45], v115 offset0:93 offset1:94
	ds_read2_b32 v[46:47], v115 offset0:95 offset1:96
	s_waitcnt lgkmcnt(0)
	v_mfma_f32_32x32x16_bf16 v[32:47], v[188:191], v[48:51], v[32:47]
	ds_read_b64_tr_b16 v[72:73], v231
	ds_read_b64_tr_b16 v[74:75], v231 offset:512
	ds_read_b64_tr_b16 v[76:77], v231 offset:2048
	ds_read_b64_tr_b16 v[78:79], v231 offset:2560
	ds_read_b64_tr_b16 v[220:221], v231 offset:1024
	ds_read_b64_tr_b16 v[222:223], v231 offset:1536
	ds_read_b64_tr_b16 v[224:225], v231 offset:3072
	ds_read_b64_tr_b16 v[226:227], v231 offset:3584
	s_waitcnt vmcnt(8)
	ds_write_b128 v247, v[116:119]
	ds_write_b128 v247, v[120:123] offset:1024
	ds_write_b128 v247, v[124:127] offset:2048
	ds_write_b128 v247, v[128:131] offset:3072
	ds_read_b128 v[116:119], v248
	ds_read_b128 v[120:123], v249
	ds_read_b128 v[124:127], v250
	ds_read_b128 v[128:131], v251
	ds_write_b128 v112, v[132:135]
	ds_write_b128 v112, v[136:139] offset:1024
	ds_write_b128 v112, v[140:143] offset:2048
	ds_write_b128 v112, v[144:147] offset:3072
	v_mfma_f32_32x32x16_bf16 v[32:47], v[192:195], v[52:55], v[32:47]
	v_mfma_f32_32x32x16_bf16 v[32:47], v[196:199], v[56:59], v[32:47]
	v_mfma_f32_32x32x16_bf16 v[32:47], v[200:203], v[60:63], v[32:47]
	s_nop 11
	v_exp_f32_e32 v32, v32
	v_exp_f32_e32 v33, v33
	v_exp_f32_e32 v34, v34
	v_exp_f32_e32 v35, v35
	v_exp_f32_e32 v36, v36
	v_exp_f32_e32 v37, v37
	v_exp_f32_e32 v38, v38
	v_exp_f32_e32 v39, v39
	v_exp_f32_e32 v40, v40
	v_exp_f32_e32 v41, v41
	v_exp_f32_e32 v42, v42
	v_exp_f32_e32 v43, v43
	v_exp_f32_e32 v44, v44
	v_exp_f32_e32 v45, v45
	v_exp_f32_e32 v46, v46
	v_exp_f32_e32 v47, v47
	s_add_i32 s90, s67, 0
	v_add_u32_e32 v84, s90, v107
	v_add_u32_e32 v85, 0, v84
	v_add_u32_e32 v86, 1, v84
	v_add_u32_e32 v87, 2, v84
	v_add_u32_e32 v88, 3, v84
	v_cmp_gt_u32_e64 s[30:31], s98, v85
	v_cmp_gt_u32_e64 s[36:37], s98, v86
	v_cmp_gt_u32_e64 s[78:79], s98, v87
	v_cmp_gt_u32_e64 s[50:51], s98, v88
	v_cndmask_b32_e64 v32, 0, v32, s[30:31]
	v_add_u32_e32 v85, 8, v84
	v_cmp_gt_u32_e64 s[30:31], s98, v85
	v_cndmask_b32_e64 v33, 0, v33, s[36:37]
	v_add_u32_e32 v86, 9, v84
	v_cmp_gt_u32_e64 s[36:37], s98, v86
	v_cndmask_b32_e64 v34, 0, v34, s[78:79]
	v_add_u32_e32 v87, 10, v84
	v_cmp_gt_u32_e64 s[78:79], s98, v87
	v_cndmask_b32_e64 v35, 0, v35, s[50:51]
	v_add_u32_e32 v88, 11, v84
	v_cmp_gt_u32_e64 s[50:51], s98, v88
	v_cndmask_b32_e64 v36, 0, v36, s[30:31]
	v_add_u32_e32 v85, 16, v84
	v_cmp_gt_u32_e64 s[30:31], s98, v85
	v_cndmask_b32_e64 v37, 0, v37, s[36:37]
	v_add_u32_e32 v86, 17, v84
	v_cmp_gt_u32_e64 s[36:37], s98, v86
	v_cndmask_b32_e64 v38, 0, v38, s[78:79]
	v_add_u32_e32 v87, 18, v84
	v_cmp_gt_u32_e64 s[78:79], s98, v87
	v_cndmask_b32_e64 v39, 0, v39, s[50:51]
	v_add_u32_e32 v88, 19, v84
	v_cmp_gt_u32_e64 s[50:51], s98, v88
	v_cndmask_b32_e64 v40, 0, v40, s[30:31]
	v_add_u32_e32 v85, 24, v84
	v_cmp_gt_u32_e64 s[30:31], s98, v85
	v_cndmask_b32_e64 v41, 0, v41, s[36:37]
	v_add_u32_e32 v86, 25, v84
	v_cmp_gt_u32_e64 s[36:37], s98, v86
	v_cndmask_b32_e64 v42, 0, v42, s[78:79]
	v_add_u32_e32 v87, 26, v84
	v_cmp_gt_u32_e64 s[78:79], s98, v87
	v_cndmask_b32_e64 v43, 0, v43, s[50:51]
	v_add_u32_e32 v88, 27, v84
	v_cmp_gt_u32_e64 s[50:51], s98, v88
	v_nop
	v_cndmask_b32_e64 v44, 0, v44, s[30:31]
	v_cndmask_b32_e64 v45, 0, v45, s[36:37]
	v_cndmask_b32_e64 v46, 0, v46, s[78:79]
	v_cndmask_b32_e64 v47, 0, v47, s[50:51]
	v_cvt_pk_bf16_f32 v64, v32, v33
	v_cvt_pk_bf16_f32 v65, v34, v35
	v_cvt_pk_bf16_f32 v66, v36, v37
	v_cvt_pk_bf16_f32 v67, v38, v39
	v_cvt_pk_bf16_f32 v68, v40, v41
	v_cvt_pk_bf16_f32 v69, v42, v43
	v_cvt_pk_bf16_f32 v70, v44, v45
	v_cvt_pk_bf16_f32 v71, v46, v47
	v_pk_add_f32 v[232:233], v[232:233], v[32:33]
	v_pk_add_f32 v[232:233], v[232:233], v[34:35]
	v_pk_add_f32 v[232:233], v[232:233], v[36:37]
	v_pk_add_f32 v[232:233], v[232:233], v[38:39]
	v_pk_add_f32 v[232:233], v[232:233], v[40:41]
	v_pk_add_f32 v[232:233], v[232:233], v[42:43]
	v_pk_add_f32 v[232:233], v[232:233], v[44:45]
	v_pk_add_f32 v[232:233], v[232:233], v[46:47]
	s_waitcnt lgkmcnt(12)
	v_mfma_f32_32x32x16_bf16 v[0:15], v[64:67], v[72:75], v[0:15]
	v_mfma_f32_32x32x16_bf16 v[16:31], v[64:67], v[76:79], v[16:31]
	v_mfma_f32_32x32x16_bf16 v[0:15], v[68:71], v[220:223], v[0:15]
	v_mfma_f32_32x32x16_bf16 v[16:31], v[68:71], v[224:227], v[16:31]
	s_add_i32 s90, s67, 96
	v_add_u32_e32 v80, s90, v235
	v_add_u32_e32 v83, s90, v236
	v_add_u32_e32 v99, s90, v237
	v_add_u32_e32 v253, s90, v238
	v_add_u32_e32 v254, s90, v100
	v_add_u32_e32 v255, s90, v149
	v_med3_i32 v80, v80, 0, s99
	v_med3_i32 v83, v83, 0, s99
	v_med3_i32 v99, v99, 0, s99
	v_med3_i32 v253, v253, 0, s99
	v_med3_i32 v254, v254, 0, s99
	v_med3_i32 v255, v255, 0, s99
	v_mad_u32_u24 v80, v80, s100, v252
	v_mad_u32_u24 v83, v83, s100, v252
	v_mad_u32_u24 v99, v99, s100, v252
	v_mad_u32_u24 v253, v253, s100, v252
	v_mad_u32_u24 v254, v254, s100, v153
	v_mad_u32_u24 v255, v255, s100, v153
	global_load_dwordx4 v[188:191], v80, s[82:83]
	global_load_dwordx4 v[192:195], v83, s[82:83]
	global_load_dwordx4 v[196:199], v99, s[82:83]
	global_load_dwordx4 v[200:203], v253, s[82:83]
	global_load_dwordx4 v[204:207], v254, s[82:83] offset:768
	global_load_dwordx4 v[208:211], v255, s[82:83] offset:768
	global_load_dwordx4 v[212:215], v254, s[82:83] offset:832
	global_load_dwordx4 v[216:219], v255, s[82:83] offset:832
	ds_read2_b32 v[32:33], v115 offset0:102 offset1:103
	ds_read2_b32 v[34:35], v115 offset0:104 offset1:105
	ds_read2_b32 v[36:37], v115 offset0:110 offset1:111
	ds_read2_b32 v[38:39], v115 offset0:112 offset1:113
	ds_read2_b32 v[40:41], v115 offset0:119 offset1:120
	ds_read2_b32 v[42:43], v115 offset0:121 offset1:122
	ds_read2_b32 v[44:45], v115 offset0:127 offset1:128
	ds_read2_b32 v[46:47], v115 offset0:129 offset1:130
	s_waitcnt lgkmcnt(0)
	v_mfma_f32_32x32x16_bf16 v[32:47], v[116:119], v[48:51], v[32:47]
	ds_read_b64_tr_b16 v[72:73], v231
	ds_read_b64_tr_b16 v[74:75], v231 offset:512
	ds_read_b64_tr_b16 v[76:77], v231 offset:2048
	ds_read_b64_tr_b16 v[78:79], v231 offset:2560
	ds_read_b64_tr_b16 v[220:221], v231 offset:1024
	ds_read_b64_tr_b16 v[222:223], v231 offset:1536
	ds_read_b64_tr_b16 v[224:225], v231 offset:3072
	ds_read_b64_tr_b16 v[226:227], v231 offset:3584
	s_waitcnt vmcnt(8)
	ds_write_b128 v247, v[156:159]
	ds_write_b128 v247, v[160:163] offset:1024
	ds_write_b128 v247, v[164:167] offset:2048
	ds_write_b128 v247, v[168:171] offset:3072
	ds_read_b128 v[156:159], v248
	ds_read_b128 v[160:163], v249
	ds_read_b128 v[164:167], v250
	ds_read_b128 v[168:171], v251
	ds_write_b128 v112, v[172:175]
	ds_write_b128 v112, v[176:179] offset:1024
	ds_write_b128 v112, v[180:183] offset:2048
	ds_write_b128 v112, v[184:187] offset:3072
	v_mfma_f32_32x32x16_bf16 v[32:47], v[120:123], v[52:55], v[32:47]
	v_mfma_f32_32x32x16_bf16 v[32:47], v[124:127], v[56:59], v[32:47]
	v_mfma_f32_32x32x16_bf16 v[32:47], v[128:131], v[60:63], v[32:47]
	s_nop 11
	v_exp_f32_e32 v32, v32
	v_exp_f32_e32 v33, v33
	v_exp_f32_e32 v34, v34
	v_exp_f32_e32 v35, v35
	v_exp_f32_e32 v36, v36
	v_exp_f32_e32 v37, v37
	v_exp_f32_e32 v38, v38
	v_exp_f32_e32 v39, v39
	v_exp_f32_e32 v40, v40
	v_exp_f32_e32 v41, v41
	v_exp_f32_e32 v42, v42
	v_exp_f32_e32 v43, v43
	v_exp_f32_e32 v44, v44
	v_exp_f32_e32 v45, v45
	v_exp_f32_e32 v46, v46
	v_exp_f32_e32 v47, v47
	s_add_i32 s90, s67, 32
	v_add_u32_e32 v84, s90, v107
	v_add_u32_e32 v85, 0, v84
	v_add_u32_e32 v86, 1, v84
	v_add_u32_e32 v87, 2, v84
	v_add_u32_e32 v88, 3, v84
	v_cmp_gt_u32_e64 s[30:31], s98, v85
	v_cmp_gt_u32_e64 s[36:37], s98, v86
	v_cmp_gt_u32_e64 s[78:79], s98, v87
	v_cmp_gt_u32_e64 s[50:51], s98, v88
	v_cndmask_b32_e64 v32, 0, v32, s[30:31]
	v_add_u32_e32 v85, 8, v84
	v_cmp_gt_u32_e64 s[30:31], s98, v85
	v_cndmask_b32_e64 v33, 0, v33, s[36:37]
	v_add_u32_e32 v86, 9, v84
	v_cmp_gt_u32_e64 s[36:37], s98, v86
	v_cndmask_b32_e64 v34, 0, v34, s[78:79]
	v_add_u32_e32 v87, 10, v84
	v_cmp_gt_u32_e64 s[78:79], s98, v87
	v_cndmask_b32_e64 v35, 0, v35, s[50:51]
	v_add_u32_e32 v88, 11, v84
	v_cmp_gt_u32_e64 s[50:51], s98, v88
	v_cndmask_b32_e64 v36, 0, v36, s[30:31]
	v_add_u32_e32 v85, 16, v84
	v_cmp_gt_u32_e64 s[30:31], s98, v85
	v_cndmask_b32_e64 v37, 0, v37, s[36:37]
	v_add_u32_e32 v86, 17, v84
	v_cmp_gt_u32_e64 s[36:37], s98, v86
	v_cndmask_b32_e64 v38, 0, v38, s[78:79]
	v_add_u32_e32 v87, 18, v84
	v_cmp_gt_u32_e64 s[78:79], s98, v87
	v_cndmask_b32_e64 v39, 0, v39, s[50:51]
	v_add_u32_e32 v88, 19, v84
	v_cmp_gt_u32_e64 s[50:51], s98, v88
	v_cndmask_b32_e64 v40, 0, v40, s[30:31]
	v_add_u32_e32 v85, 24, v84
	v_cmp_gt_u32_e64 s[30:31], s98, v85
	v_cndmask_b32_e64 v41, 0, v41, s[36:37]
	v_add_u32_e32 v86, 25, v84
	v_cmp_gt_u32_e64 s[36:37], s98, v86
	v_cndmask_b32_e64 v42, 0, v42, s[78:79]
	v_add_u32_e32 v87, 26, v84
	v_cmp_gt_u32_e64 s[78:79], s98, v87
	v_cndmask_b32_e64 v43, 0, v43, s[50:51]
	v_add_u32_e32 v88, 27, v84
	v_cmp_gt_u32_e64 s[50:51], s98, v88
	v_nop
	v_cndmask_b32_e64 v44, 0, v44, s[30:31]
	v_cndmask_b32_e64 v45, 0, v45, s[36:37]
	v_cndmask_b32_e64 v46, 0, v46, s[78:79]
	v_cndmask_b32_e64 v47, 0, v47, s[50:51]
	v_cvt_pk_bf16_f32 v64, v32, v33
	v_cvt_pk_bf16_f32 v65, v34, v35
	v_cvt_pk_bf16_f32 v66, v36, v37
	v_cvt_pk_bf16_f32 v67, v38, v39
	v_cvt_pk_bf16_f32 v68, v40, v41
	v_cvt_pk_bf16_f32 v69, v42, v43
	v_cvt_pk_bf16_f32 v70, v44, v45
	v_cvt_pk_bf16_f32 v71, v46, v47
	v_pk_add_f32 v[232:233], v[232:233], v[32:33]
	v_pk_add_f32 v[232:233], v[232:233], v[34:35]
	v_pk_add_f32 v[232:233], v[232:233], v[36:37]
	v_pk_add_f32 v[232:233], v[232:233], v[38:39]
	v_pk_add_f32 v[232:233], v[232:233], v[40:41]
	v_pk_add_f32 v[232:233], v[232:233], v[42:43]
	v_pk_add_f32 v[232:233], v[232:233], v[44:45]
	v_pk_add_f32 v[232:233], v[232:233], v[46:47]
	s_waitcnt lgkmcnt(12)
	v_mfma_f32_32x32x16_bf16 v[0:15], v[64:67], v[72:75], v[0:15]
	v_mfma_f32_32x32x16_bf16 v[16:31], v[64:67], v[76:79], v[16:31]
	v_mfma_f32_32x32x16_bf16 v[0:15], v[68:71], v[220:223], v[0:15]
	v_mfma_f32_32x32x16_bf16 v[16:31], v[68:71], v[224:227], v[16:31]
	s_add_i32 s90, s67, 128
	v_add_u32_e32 v80, s90, v235
	v_add_u32_e32 v83, s90, v236
	v_add_u32_e32 v99, s90, v237
	v_add_u32_e32 v253, s90, v238
	v_add_u32_e32 v254, s90, v100
	v_add_u32_e32 v255, s90, v149
	v_med3_i32 v80, v80, 0, s99
	v_med3_i32 v83, v83, 0, s99
	v_med3_i32 v99, v99, 0, s99
	v_med3_i32 v253, v253, 0, s99
	v_med3_i32 v254, v254, 0, s99
	v_med3_i32 v255, v255, 0, s99
	v_mad_u32_u24 v80, v80, s100, v252
	v_mad_u32_u24 v83, v83, s100, v252
	v_mad_u32_u24 v99, v99, s100, v252
	v_mad_u32_u24 v253, v253, s100, v252
	v_mad_u32_u24 v254, v254, s100, v153
	v_mad_u32_u24 v255, v255, s100, v153
	global_load_dwordx4 v[116:119], v80, s[82:83]
	global_load_dwordx4 v[120:123], v83, s[82:83]
	global_load_dwordx4 v[124:127], v99, s[82:83]
	global_load_dwordx4 v[128:131], v253, s[82:83]
	global_load_dwordx4 v[132:135], v254, s[82:83] offset:768
	global_load_dwordx4 v[136:139], v255, s[82:83] offset:768
	global_load_dwordx4 v[140:143], v254, s[82:83] offset:832
	global_load_dwordx4 v[144:147], v255, s[82:83] offset:832
	ds_read2_b32 v[32:33], v115 offset0:136 offset1:137
	ds_read2_b32 v[34:35], v115 offset0:138 offset1:139
	ds_read2_b32 v[36:37], v115 offset0:144 offset1:145
	ds_read2_b32 v[38:39], v115 offset0:146 offset1:147
	ds_read2_b32 v[40:41], v115 offset0:153 offset1:154
	ds_read2_b32 v[42:43], v115 offset0:155 offset1:156
	ds_read2_b32 v[44:45], v115 offset0:161 offset1:162
	ds_read2_b32 v[46:47], v115 offset0:163 offset1:164
	s_waitcnt lgkmcnt(0)
	v_mfma_f32_32x32x16_bf16 v[32:47], v[156:159], v[48:51], v[32:47]
	ds_read_b64_tr_b16 v[72:73], v231
	ds_read_b64_tr_b16 v[74:75], v231 offset:512
	ds_read_b64_tr_b16 v[76:77], v231 offset:2048
	ds_read_b64_tr_b16 v[78:79], v231 offset:2560
	ds_read_b64_tr_b16 v[220:221], v231 offset:1024
	ds_read_b64_tr_b16 v[222:223], v231 offset:1536
	ds_read_b64_tr_b16 v[224:225], v231 offset:3072
	ds_read_b64_tr_b16 v[226:227], v231 offset:3584
	s_waitcnt vmcnt(8)
	ds_write_b128 v247, v[188:191]
	ds_write_b128 v247, v[192:195] offset:1024
	ds_write_b128 v247, v[196:199] offset:2048
	ds_write_b128 v247, v[200:203] offset:3072
	ds_read_b128 v[188:191], v248
	ds_read_b128 v[192:195], v249
	ds_read_b128 v[196:199], v250
	ds_read_b128 v[200:203], v251
	ds_write_b128 v112, v[204:207]
	ds_write_b128 v112, v[208:211] offset:1024
	ds_write_b128 v112, v[212:215] offset:2048
	ds_write_b128 v112, v[216:219] offset:3072
	v_mfma_f32_32x32x16_bf16 v[32:47], v[160:163], v[52:55], v[32:47]
	v_mfma_f32_32x32x16_bf16 v[32:47], v[164:167], v[56:59], v[32:47]
	v_mfma_f32_32x32x16_bf16 v[32:47], v[168:171], v[60:63], v[32:47]
	s_nop 11
	v_exp_f32_e32 v32, v32
	v_exp_f32_e32 v33, v33
	v_exp_f32_e32 v34, v34
	v_exp_f32_e32 v35, v35
	v_exp_f32_e32 v36, v36
	v_exp_f32_e32 v37, v37
	v_exp_f32_e32 v38, v38
	v_exp_f32_e32 v39, v39
	v_exp_f32_e32 v40, v40
	v_exp_f32_e32 v41, v41
	v_exp_f32_e32 v42, v42
	v_exp_f32_e32 v43, v43
	v_exp_f32_e32 v44, v44
	v_exp_f32_e32 v45, v45
	v_exp_f32_e32 v46, v46
	v_exp_f32_e32 v47, v47
	s_add_i32 s90, s67, 64
	v_add_u32_e32 v84, s90, v107
	v_add_u32_e32 v85, 0, v84
	v_add_u32_e32 v86, 1, v84
	v_add_u32_e32 v87, 2, v84
	v_add_u32_e32 v88, 3, v84
	v_cmp_gt_u32_e64 s[30:31], s98, v85
	v_cmp_gt_u32_e64 s[36:37], s98, v86
	v_cmp_gt_u32_e64 s[78:79], s98, v87
	v_cmp_gt_u32_e64 s[50:51], s98, v88
	v_cndmask_b32_e64 v32, 0, v32, s[30:31]
	v_add_u32_e32 v85, 8, v84
	v_cmp_gt_u32_e64 s[30:31], s98, v85
	v_cndmask_b32_e64 v33, 0, v33, s[36:37]
	v_add_u32_e32 v86, 9, v84
	v_cmp_gt_u32_e64 s[36:37], s98, v86
	v_cndmask_b32_e64 v34, 0, v34, s[78:79]
	v_add_u32_e32 v87, 10, v84
	v_cmp_gt_u32_e64 s[78:79], s98, v87
	v_cndmask_b32_e64 v35, 0, v35, s[50:51]
	v_add_u32_e32 v88, 11, v84
	v_cmp_gt_u32_e64 s[50:51], s98, v88
	v_cndmask_b32_e64 v36, 0, v36, s[30:31]
	v_add_u32_e32 v85, 16, v84
	v_cmp_gt_u32_e64 s[30:31], s98, v85
	v_cndmask_b32_e64 v37, 0, v37, s[36:37]
	v_add_u32_e32 v86, 17, v84
	v_cmp_gt_u32_e64 s[36:37], s98, v86
	v_cndmask_b32_e64 v38, 0, v38, s[78:79]
	v_add_u32_e32 v87, 18, v84
	v_cmp_gt_u32_e64 s[78:79], s98, v87
	v_cndmask_b32_e64 v39, 0, v39, s[50:51]
	v_add_u32_e32 v88, 19, v84
	v_cmp_gt_u32_e64 s[50:51], s98, v88
	v_cndmask_b32_e64 v40, 0, v40, s[30:31]
	v_add_u32_e32 v85, 24, v84
	v_cmp_gt_u32_e64 s[30:31], s98, v85
	v_cndmask_b32_e64 v41, 0, v41, s[36:37]
	v_add_u32_e32 v86, 25, v84
	v_cmp_gt_u32_e64 s[36:37], s98, v86
	v_cndmask_b32_e64 v42, 0, v42, s[78:79]
	v_add_u32_e32 v87, 26, v84
	v_cmp_gt_u32_e64 s[78:79], s98, v87
	v_cndmask_b32_e64 v43, 0, v43, s[50:51]
	v_add_u32_e32 v88, 27, v84
	v_cmp_gt_u32_e64 s[50:51], s98, v88
	v_nop
	v_cndmask_b32_e64 v44, 0, v44, s[30:31]
	v_cndmask_b32_e64 v45, 0, v45, s[36:37]
	v_cndmask_b32_e64 v46, 0, v46, s[78:79]
	v_cndmask_b32_e64 v47, 0, v47, s[50:51]
	v_cvt_pk_bf16_f32 v64, v32, v33
	v_cvt_pk_bf16_f32 v65, v34, v35
	v_cvt_pk_bf16_f32 v66, v36, v37
	v_cvt_pk_bf16_f32 v67, v38, v39
	v_cvt_pk_bf16_f32 v68, v40, v41
	v_cvt_pk_bf16_f32 v69, v42, v43
	v_cvt_pk_bf16_f32 v70, v44, v45
	v_cvt_pk_bf16_f32 v71, v46, v47
	v_pk_add_f32 v[232:233], v[232:233], v[32:33]
	v_pk_add_f32 v[232:233], v[232:233], v[34:35]
	v_pk_add_f32 v[232:233], v[232:233], v[36:37]
	v_pk_add_f32 v[232:233], v[232:233], v[38:39]
	v_pk_add_f32 v[232:233], v[232:233], v[40:41]
	v_pk_add_f32 v[232:233], v[232:233], v[42:43]
	v_pk_add_f32 v[232:233], v[232:233], v[44:45]
	v_pk_add_f32 v[232:233], v[232:233], v[46:47]
	s_waitcnt lgkmcnt(12)
	v_mfma_f32_32x32x16_bf16 v[0:15], v[64:67], v[72:75], v[0:15]
	v_mfma_f32_32x32x16_bf16 v[16:31], v[64:67], v[76:79], v[16:31]
	v_mfma_f32_32x32x16_bf16 v[0:15], v[68:71], v[220:223], v[0:15]
	v_mfma_f32_32x32x16_bf16 v[16:31], v[68:71], v[224:227], v[16:31]
	s_add_i32 s90, s67, 160
	v_add_u32_e32 v80, s90, v235
	v_add_u32_e32 v83, s90, v236
	v_add_u32_e32 v99, s90, v237
	v_add_u32_e32 v253, s90, v238
	v_add_u32_e32 v254, s90, v100
	v_add_u32_e32 v255, s90, v149
	v_med3_i32 v80, v80, 0, s99
	v_med3_i32 v83, v83, 0, s99
	v_med3_i32 v99, v99, 0, s99
	v_med3_i32 v253, v253, 0, s99
	v_med3_i32 v254, v254, 0, s99
	v_med3_i32 v255, v255, 0, s99
	v_mad_u32_u24 v80, v80, s100, v252
	v_mad_u32_u24 v83, v83, s100, v252
	v_mad_u32_u24 v99, v99, s100, v252
	v_mad_u32_u24 v253, v253, s100, v252
	v_mad_u32_u24 v254, v254, s100, v153
	v_mad_u32_u24 v255, v255, s100, v153
	global_load_dwordx4 v[156:159], v80, s[82:83]
	global_load_dwordx4 v[160:163], v83, s[82:83]
	global_load_dwordx4 v[164:167], v99, s[82:83]
	global_load_dwordx4 v[168:171], v253, s[82:83]
	global_load_dwordx4 v[172:175], v254, s[82:83] offset:768
	global_load_dwordx4 v[176:179], v255, s[82:83] offset:768
	global_load_dwordx4 v[180:183], v254, s[82:83] offset:832
	global_load_dwordx4 v[184:187], v255, s[82:83] offset:832
	ds_read2_b32 v[32:33], v115 offset0:170 offset1:171
	ds_read2_b32 v[34:35], v115 offset0:172 offset1:173
	ds_read2_b32 v[36:37], v115 offset0:178 offset1:179
	ds_read2_b32 v[38:39], v115 offset0:180 offset1:181
	ds_read2_b32 v[40:41], v115 offset0:187 offset1:188
	ds_read2_b32 v[42:43], v115 offset0:189 offset1:190
	ds_read2_b32 v[44:45], v115 offset0:195 offset1:196
	ds_read2_b32 v[46:47], v115 offset0:197 offset1:198
	s_waitcnt lgkmcnt(0)
	v_mfma_f32_32x32x16_bf16 v[32:47], v[188:191], v[48:51], v[32:47]
	ds_read_b64_tr_b16 v[72:73], v231
	ds_read_b64_tr_b16 v[74:75], v231 offset:512
	ds_read_b64_tr_b16 v[76:77], v231 offset:2048
	ds_read_b64_tr_b16 v[78:79], v231 offset:2560
	ds_read_b64_tr_b16 v[220:221], v231 offset:1024
	ds_read_b64_tr_b16 v[222:223], v231 offset:1536
	ds_read_b64_tr_b16 v[224:225], v231 offset:3072
	ds_read_b64_tr_b16 v[226:227], v231 offset:3584
	s_waitcnt vmcnt(8)
	ds_write_b128 v247, v[116:119]
	ds_write_b128 v247, v[120:123] offset:1024
	ds_write_b128 v247, v[124:127] offset:2048
	ds_write_b128 v247, v[128:131] offset:3072
	ds_read_b128 v[116:119], v248
	ds_read_b128 v[120:123], v249
	ds_read_b128 v[124:127], v250
	ds_read_b128 v[128:131], v251
	ds_write_b128 v112, v[132:135]
	ds_write_b128 v112, v[136:139] offset:1024
	ds_write_b128 v112, v[140:143] offset:2048
	ds_write_b128 v112, v[144:147] offset:3072
	v_mfma_f32_32x32x16_bf16 v[32:47], v[192:195], v[52:55], v[32:47]
	v_mfma_f32_32x32x16_bf16 v[32:47], v[196:199], v[56:59], v[32:47]
	v_mfma_f32_32x32x16_bf16 v[32:47], v[200:203], v[60:63], v[32:47]
	s_nop 11
	v_exp_f32_e32 v32, v32
	v_exp_f32_e32 v33, v33
	v_exp_f32_e32 v34, v34
	v_exp_f32_e32 v35, v35
	v_exp_f32_e32 v36, v36
	v_exp_f32_e32 v37, v37
	v_exp_f32_e32 v38, v38
	v_exp_f32_e32 v39, v39
	v_exp_f32_e32 v40, v40
	v_exp_f32_e32 v41, v41
	v_exp_f32_e32 v42, v42
	v_exp_f32_e32 v43, v43
	v_exp_f32_e32 v44, v44
	v_exp_f32_e32 v45, v45
	v_exp_f32_e32 v46, v46
	v_exp_f32_e32 v47, v47
	s_add_i32 s90, s67, 96
	v_add_u32_e32 v84, s90, v107
	v_add_u32_e32 v85, 0, v84
	v_add_u32_e32 v86, 1, v84
	v_add_u32_e32 v87, 2, v84
	v_add_u32_e32 v88, 3, v84
	v_cmp_gt_u32_e64 s[30:31], s98, v85
	v_cmp_gt_u32_e64 s[36:37], s98, v86
	v_cmp_gt_u32_e64 s[78:79], s98, v87
	v_cmp_gt_u32_e64 s[50:51], s98, v88
	v_cndmask_b32_e64 v32, 0, v32, s[30:31]
	v_add_u32_e32 v85, 8, v84
	v_cmp_gt_u32_e64 s[30:31], s98, v85
	v_cndmask_b32_e64 v33, 0, v33, s[36:37]
	v_add_u32_e32 v86, 9, v84
	v_cmp_gt_u32_e64 s[36:37], s98, v86
	v_cndmask_b32_e64 v34, 0, v34, s[78:79]
	v_add_u32_e32 v87, 10, v84
	v_cmp_gt_u32_e64 s[78:79], s98, v87
	v_cndmask_b32_e64 v35, 0, v35, s[50:51]
	v_add_u32_e32 v88, 11, v84
	v_cmp_gt_u32_e64 s[50:51], s98, v88
	v_cndmask_b32_e64 v36, 0, v36, s[30:31]
	v_add_u32_e32 v85, 16, v84
	v_cmp_gt_u32_e64 s[30:31], s98, v85
	v_cndmask_b32_e64 v37, 0, v37, s[36:37]
	v_add_u32_e32 v86, 17, v84
	v_cmp_gt_u32_e64 s[36:37], s98, v86
	v_cndmask_b32_e64 v38, 0, v38, s[78:79]
	v_add_u32_e32 v87, 18, v84
	v_cmp_gt_u32_e64 s[78:79], s98, v87
	v_cndmask_b32_e64 v39, 0, v39, s[50:51]
	v_add_u32_e32 v88, 19, v84
	v_cmp_gt_u32_e64 s[50:51], s98, v88
	v_cndmask_b32_e64 v40, 0, v40, s[30:31]
	v_add_u32_e32 v85, 24, v84
	v_cmp_gt_u32_e64 s[30:31], s98, v85
	v_cndmask_b32_e64 v41, 0, v41, s[36:37]
	v_add_u32_e32 v86, 25, v84
	v_cmp_gt_u32_e64 s[36:37], s98, v86
	v_cndmask_b32_e64 v42, 0, v42, s[78:79]
	v_add_u32_e32 v87, 26, v84
	v_cmp_gt_u32_e64 s[78:79], s98, v87
	v_cndmask_b32_e64 v43, 0, v43, s[50:51]
	v_add_u32_e32 v88, 27, v84
	v_cmp_gt_u32_e64 s[50:51], s98, v88
	v_nop
	v_cndmask_b32_e64 v44, 0, v44, s[30:31]
	v_cndmask_b32_e64 v45, 0, v45, s[36:37]
	v_cndmask_b32_e64 v46, 0, v46, s[78:79]
	v_cndmask_b32_e64 v47, 0, v47, s[50:51]
	v_cvt_pk_bf16_f32 v64, v32, v33
	v_cvt_pk_bf16_f32 v65, v34, v35
	v_cvt_pk_bf16_f32 v66, v36, v37
	v_cvt_pk_bf16_f32 v67, v38, v39
	v_cvt_pk_bf16_f32 v68, v40, v41
	v_cvt_pk_bf16_f32 v69, v42, v43
	v_cvt_pk_bf16_f32 v70, v44, v45
	v_cvt_pk_bf16_f32 v71, v46, v47
	v_pk_add_f32 v[232:233], v[232:233], v[32:33]
	v_pk_add_f32 v[232:233], v[232:233], v[34:35]
	v_pk_add_f32 v[232:233], v[232:233], v[36:37]
	v_pk_add_f32 v[232:233], v[232:233], v[38:39]
	v_pk_add_f32 v[232:233], v[232:233], v[40:41]
	v_pk_add_f32 v[232:233], v[232:233], v[42:43]
	v_pk_add_f32 v[232:233], v[232:233], v[44:45]
	v_pk_add_f32 v[232:233], v[232:233], v[46:47]
	s_waitcnt lgkmcnt(12)
	v_mfma_f32_32x32x16_bf16 v[0:15], v[64:67], v[72:75], v[0:15]
	v_mfma_f32_32x32x16_bf16 v[16:31], v[64:67], v[76:79], v[16:31]
	v_mfma_f32_32x32x16_bf16 v[0:15], v[68:71], v[220:223], v[0:15]
	v_mfma_f32_32x32x16_bf16 v[16:31], v[68:71], v[224:227], v[16:31]
	s_add_i32 s90, s67, 192
	v_add_u32_e32 v80, s90, v235
	v_add_u32_e32 v83, s90, v236
	v_add_u32_e32 v99, s90, v237
	v_add_u32_e32 v253, s90, v238
	v_add_u32_e32 v254, s90, v100
	v_add_u32_e32 v255, s90, v149
	v_med3_i32 v80, v80, 0, s99
	v_med3_i32 v83, v83, 0, s99
	v_med3_i32 v99, v99, 0, s99
	v_med3_i32 v253, v253, 0, s99
	v_med3_i32 v254, v254, 0, s99
	v_med3_i32 v255, v255, 0, s99
	v_mad_u32_u24 v80, v80, s100, v252
	v_mad_u32_u24 v83, v83, s100, v252
	v_mad_u32_u24 v99, v99, s100, v252
	v_mad_u32_u24 v253, v253, s100, v252
	v_mad_u32_u24 v254, v254, s100, v153
	v_mad_u32_u24 v255, v255, s100, v153
	global_load_dwordx4 v[188:191], v80, s[82:83]
	global_load_dwordx4 v[192:195], v83, s[82:83]
	global_load_dwordx4 v[196:199], v99, s[82:83]
	global_load_dwordx4 v[200:203], v253, s[82:83]
	global_load_dwordx4 v[204:207], v254, s[82:83] offset:768
	global_load_dwordx4 v[208:211], v255, s[82:83] offset:768
	global_load_dwordx4 v[212:215], v254, s[82:83] offset:832
	global_load_dwordx4 v[216:219], v255, s[82:83] offset:832
	ds_read2_b32 v[32:33], v115 offset0:204 offset1:205
	ds_read2_b32 v[34:35], v115 offset0:206 offset1:207
	ds_read2_b32 v[36:37], v115 offset0:212 offset1:213
	ds_read2_b32 v[38:39], v115 offset0:214 offset1:215
	ds_read2_b32 v[40:41], v115 offset0:221 offset1:222
	ds_read2_b32 v[42:43], v115 offset0:223 offset1:224
	ds_read2_b32 v[44:45], v115 offset0:229 offset1:230
	ds_read2_b32 v[46:47], v115 offset0:231 offset1:232
	s_waitcnt lgkmcnt(0)
	v_mfma_f32_32x32x16_bf16 v[32:47], v[116:119], v[48:51], v[32:47]
	ds_read_b64_tr_b16 v[72:73], v231
	ds_read_b64_tr_b16 v[74:75], v231 offset:512
	ds_read_b64_tr_b16 v[76:77], v231 offset:2048
	ds_read_b64_tr_b16 v[78:79], v231 offset:2560
	ds_read_b64_tr_b16 v[220:221], v231 offset:1024
	ds_read_b64_tr_b16 v[222:223], v231 offset:1536
	ds_read_b64_tr_b16 v[224:225], v231 offset:3072
	ds_read_b64_tr_b16 v[226:227], v231 offset:3584
	s_waitcnt vmcnt(8)
	ds_write_b128 v247, v[156:159]
	ds_write_b128 v247, v[160:163] offset:1024
	ds_write_b128 v247, v[164:167] offset:2048
	ds_write_b128 v247, v[168:171] offset:3072
	ds_read_b128 v[156:159], v248
	ds_read_b128 v[160:163], v249
	ds_read_b128 v[164:167], v250
	ds_read_b128 v[168:171], v251
	ds_write_b128 v112, v[172:175]
	ds_write_b128 v112, v[176:179] offset:1024
	ds_write_b128 v112, v[180:183] offset:2048
	ds_write_b128 v112, v[184:187] offset:3072
	v_mfma_f32_32x32x16_bf16 v[32:47], v[120:123], v[52:55], v[32:47]
	v_mfma_f32_32x32x16_bf16 v[32:47], v[124:127], v[56:59], v[32:47]
	v_mfma_f32_32x32x16_bf16 v[32:47], v[128:131], v[60:63], v[32:47]
	s_nop 11
	v_exp_f32_e32 v32, v32
	v_exp_f32_e32 v33, v33
	v_exp_f32_e32 v34, v34
	v_exp_f32_e32 v35, v35
	v_exp_f32_e32 v36, v36
	v_exp_f32_e32 v37, v37
	v_exp_f32_e32 v38, v38
	v_exp_f32_e32 v39, v39
	v_exp_f32_e32 v40, v40
	v_exp_f32_e32 v41, v41
	v_exp_f32_e32 v42, v42
	v_exp_f32_e32 v43, v43
	v_exp_f32_e32 v44, v44
	v_exp_f32_e32 v45, v45
	v_exp_f32_e32 v46, v46
	v_exp_f32_e32 v47, v47
	s_add_i32 s90, s67, 128
	v_add_u32_e32 v84, s90, v107
	v_add_u32_e32 v85, 0, v84
	v_add_u32_e32 v86, 1, v84
	v_add_u32_e32 v87, 2, v84
	v_add_u32_e32 v88, 3, v84
	v_cmp_gt_u32_e64 s[30:31], s98, v85
	v_cmp_gt_u32_e64 s[36:37], s98, v86
	v_cmp_gt_u32_e64 s[78:79], s98, v87
	v_cmp_gt_u32_e64 s[50:51], s98, v88
	v_cndmask_b32_e64 v32, 0, v32, s[30:31]
	v_add_u32_e32 v85, 8, v84
	v_cmp_gt_u32_e64 s[30:31], s98, v85
	v_cndmask_b32_e64 v33, 0, v33, s[36:37]
	v_add_u32_e32 v86, 9, v84
	v_cmp_gt_u32_e64 s[36:37], s98, v86
	v_cndmask_b32_e64 v34, 0, v34, s[78:79]
	v_add_u32_e32 v87, 10, v84
	v_cmp_gt_u32_e64 s[78:79], s98, v87
	v_cndmask_b32_e64 v35, 0, v35, s[50:51]
	v_add_u32_e32 v88, 11, v84
	v_cmp_gt_u32_e64 s[50:51], s98, v88
	v_cndmask_b32_e64 v36, 0, v36, s[30:31]
	v_add_u32_e32 v85, 16, v84
	v_cmp_gt_u32_e64 s[30:31], s98, v85
	v_cndmask_b32_e64 v37, 0, v37, s[36:37]
	v_add_u32_e32 v86, 17, v84
	v_cmp_gt_u32_e64 s[36:37], s98, v86
	v_cndmask_b32_e64 v38, 0, v38, s[78:79]
	v_add_u32_e32 v87, 18, v84
	v_cmp_gt_u32_e64 s[78:79], s98, v87
	v_cndmask_b32_e64 v39, 0, v39, s[50:51]
	v_add_u32_e32 v88, 19, v84
	v_cmp_gt_u32_e64 s[50:51], s98, v88
	v_cndmask_b32_e64 v40, 0, v40, s[30:31]
	v_add_u32_e32 v85, 24, v84
	v_cmp_gt_u32_e64 s[30:31], s98, v85
	v_cndmask_b32_e64 v41, 0, v41, s[36:37]
	v_add_u32_e32 v86, 25, v84
	v_cmp_gt_u32_e64 s[36:37], s98, v86
	v_cndmask_b32_e64 v42, 0, v42, s[78:79]
	v_add_u32_e32 v87, 26, v84
	v_cmp_gt_u32_e64 s[78:79], s98, v87
	v_cndmask_b32_e64 v43, 0, v43, s[50:51]
	v_add_u32_e32 v88, 27, v84
	v_cmp_gt_u32_e64 s[50:51], s98, v88
	v_nop
	v_cndmask_b32_e64 v44, 0, v44, s[30:31]
	v_cndmask_b32_e64 v45, 0, v45, s[36:37]
	v_cndmask_b32_e64 v46, 0, v46, s[78:79]
	v_cndmask_b32_e64 v47, 0, v47, s[50:51]
	v_cvt_pk_bf16_f32 v64, v32, v33
	v_cvt_pk_bf16_f32 v65, v34, v35
	v_cvt_pk_bf16_f32 v66, v36, v37
	v_cvt_pk_bf16_f32 v67, v38, v39
	v_cvt_pk_bf16_f32 v68, v40, v41
	v_cvt_pk_bf16_f32 v69, v42, v43
	v_cvt_pk_bf16_f32 v70, v44, v45
	v_cvt_pk_bf16_f32 v71, v46, v47
	v_pk_add_f32 v[232:233], v[232:233], v[32:33]
	v_pk_add_f32 v[232:233], v[232:233], v[34:35]
	v_pk_add_f32 v[232:233], v[232:233], v[36:37]
	v_pk_add_f32 v[232:233], v[232:233], v[38:39]
	v_pk_add_f32 v[232:233], v[232:233], v[40:41]
	v_pk_add_f32 v[232:233], v[232:233], v[42:43]
	v_pk_add_f32 v[232:233], v[232:233], v[44:45]
	v_pk_add_f32 v[232:233], v[232:233], v[46:47]
	s_waitcnt lgkmcnt(12)
	v_mfma_f32_32x32x16_bf16 v[0:15], v[64:67], v[72:75], v[0:15]
	v_mfma_f32_32x32x16_bf16 v[16:31], v[64:67], v[76:79], v[16:31]
	v_mfma_f32_32x32x16_bf16 v[0:15], v[68:71], v[220:223], v[0:15]
	v_mfma_f32_32x32x16_bf16 v[16:31], v[68:71], v[224:227], v[16:31]
	s_add_i32 s90, s67, 224
	v_add_u32_e32 v80, s90, v235
	v_add_u32_e32 v83, s90, v236
	v_add_u32_e32 v99, s90, v237
	v_add_u32_e32 v253, s90, v238
	v_add_u32_e32 v254, s90, v100
	v_add_u32_e32 v255, s90, v149
	v_med3_i32 v80, v80, 0, s99
	v_med3_i32 v83, v83, 0, s99
	v_med3_i32 v99, v99, 0, s99
	v_med3_i32 v253, v253, 0, s99
	v_med3_i32 v254, v254, 0, s99
	v_med3_i32 v255, v255, 0, s99
	v_mad_u32_u24 v80, v80, s100, v252
	v_mad_u32_u24 v83, v83, s100, v252
	v_mad_u32_u24 v99, v99, s100, v252
	v_mad_u32_u24 v253, v253, s100, v252
	v_mad_u32_u24 v254, v254, s100, v153
	v_mad_u32_u24 v255, v255, s100, v153
	global_load_dwordx4 v[116:119], v80, s[82:83]
	global_load_dwordx4 v[120:123], v83, s[82:83]
	global_load_dwordx4 v[124:127], v99, s[82:83]
	global_load_dwordx4 v[128:131], v253, s[82:83]
	global_load_dwordx4 v[132:135], v254, s[82:83] offset:768
	global_load_dwordx4 v[136:139], v255, s[82:83] offset:768
	global_load_dwordx4 v[140:143], v254, s[82:83] offset:832
	global_load_dwordx4 v[144:147], v255, s[82:83] offset:832
	v_add_u32_e32 v115, 952, v115
	ds_read2_b32 v[32:33], v115 offset0:0 offset1:1
	ds_read2_b32 v[34:35], v115 offset0:2 offset1:3
	ds_read2_b32 v[36:37], v115 offset0:8 offset1:9
	ds_read2_b32 v[38:39], v115 offset0:10 offset1:11
	ds_read2_b32 v[40:41], v115 offset0:17 offset1:18
	ds_read2_b32 v[42:43], v115 offset0:19 offset1:20
	ds_read2_b32 v[44:45], v115 offset0:25 offset1:26
	ds_read2_b32 v[46:47], v115 offset0:27 offset1:28
	s_waitcnt lgkmcnt(0)
	v_mfma_f32_32x32x16_bf16 v[32:47], v[156:159], v[48:51], v[32:47]
	ds_read_b64_tr_b16 v[72:73], v231
	ds_read_b64_tr_b16 v[74:75], v231 offset:512
	ds_read_b64_tr_b16 v[76:77], v231 offset:2048
	ds_read_b64_tr_b16 v[78:79], v231 offset:2560
	ds_read_b64_tr_b16 v[220:221], v231 offset:1024
	ds_read_b64_tr_b16 v[222:223], v231 offset:1536
	ds_read_b64_tr_b16 v[224:225], v231 offset:3072
	ds_read_b64_tr_b16 v[226:227], v231 offset:3584
	s_waitcnt vmcnt(8)
	ds_write_b128 v247, v[188:191]
	ds_write_b128 v247, v[192:195] offset:1024
	ds_write_b128 v247, v[196:199] offset:2048
	ds_write_b128 v247, v[200:203] offset:3072
	ds_read_b128 v[188:191], v248
	ds_read_b128 v[192:195], v249
	ds_read_b128 v[196:199], v250
	ds_read_b128 v[200:203], v251
	ds_write_b128 v112, v[204:207]
	ds_write_b128 v112, v[208:211] offset:1024
	ds_write_b128 v112, v[212:215] offset:2048
	ds_write_b128 v112, v[216:219] offset:3072
	v_mfma_f32_32x32x16_bf16 v[32:47], v[160:163], v[52:55], v[32:47]
	v_mfma_f32_32x32x16_bf16 v[32:47], v[164:167], v[56:59], v[32:47]
	v_mfma_f32_32x32x16_bf16 v[32:47], v[168:171], v[60:63], v[32:47]
	s_nop 11
	v_exp_f32_e32 v32, v32
	v_exp_f32_e32 v33, v33
	v_exp_f32_e32 v34, v34
	v_exp_f32_e32 v35, v35
	v_exp_f32_e32 v36, v36
	v_exp_f32_e32 v37, v37
	v_exp_f32_e32 v38, v38
	v_exp_f32_e32 v39, v39
	v_exp_f32_e32 v40, v40
	v_exp_f32_e32 v41, v41
	v_exp_f32_e32 v42, v42
	v_exp_f32_e32 v43, v43
	v_exp_f32_e32 v44, v44
	v_exp_f32_e32 v45, v45
	v_exp_f32_e32 v46, v46
	v_exp_f32_e32 v47, v47
	s_add_i32 s90, s67, 160
	v_add_u32_e32 v84, s90, v107
	v_add_u32_e32 v85, 0, v84
	v_add_u32_e32 v86, 1, v84
	v_add_u32_e32 v87, 2, v84
	v_add_u32_e32 v88, 3, v84
	v_cmp_gt_u32_e64 s[30:31], s98, v85
	v_cmp_gt_u32_e64 s[36:37], s98, v86
	v_cmp_gt_u32_e64 s[78:79], s98, v87
	v_cmp_gt_u32_e64 s[50:51], s98, v88
	v_cndmask_b32_e64 v32, 0, v32, s[30:31]
	v_add_u32_e32 v85, 8, v84
	v_cmp_gt_u32_e64 s[30:31], s98, v85
	v_cndmask_b32_e64 v33, 0, v33, s[36:37]
	v_add_u32_e32 v86, 9, v84
	v_cmp_gt_u32_e64 s[36:37], s98, v86
	v_cndmask_b32_e64 v34, 0, v34, s[78:79]
	v_add_u32_e32 v87, 10, v84
	v_cmp_gt_u32_e64 s[78:79], s98, v87
	v_cndmask_b32_e64 v35, 0, v35, s[50:51]
	v_add_u32_e32 v88, 11, v84
	v_cmp_gt_u32_e64 s[50:51], s98, v88
	v_cndmask_b32_e64 v36, 0, v36, s[30:31]
	v_add_u32_e32 v85, 16, v84
	v_cmp_gt_u32_e64 s[30:31], s98, v85
	v_cndmask_b32_e64 v37, 0, v37, s[36:37]
	v_add_u32_e32 v86, 17, v84
	v_cmp_gt_u32_e64 s[36:37], s98, v86
	v_cndmask_b32_e64 v38, 0, v38, s[78:79]
	v_add_u32_e32 v87, 18, v84
	v_cmp_gt_u32_e64 s[78:79], s98, v87
	v_cndmask_b32_e64 v39, 0, v39, s[50:51]
	v_add_u32_e32 v88, 19, v84
	v_cmp_gt_u32_e64 s[50:51], s98, v88
	v_cndmask_b32_e64 v40, 0, v40, s[30:31]
	v_add_u32_e32 v85, 24, v84
	v_cmp_gt_u32_e64 s[30:31], s98, v85
	v_cndmask_b32_e64 v41, 0, v41, s[36:37]
	v_add_u32_e32 v86, 25, v84
	v_cmp_gt_u32_e64 s[36:37], s98, v86
	v_cndmask_b32_e64 v42, 0, v42, s[78:79]
	v_add_u32_e32 v87, 26, v84
	v_cmp_gt_u32_e64 s[78:79], s98, v87
	v_cndmask_b32_e64 v43, 0, v43, s[50:51]
	v_add_u32_e32 v88, 27, v84
	v_cmp_gt_u32_e64 s[50:51], s98, v88
	v_nop
	v_cndmask_b32_e64 v44, 0, v44, s[30:31]
	v_cndmask_b32_e64 v45, 0, v45, s[36:37]
	v_cndmask_b32_e64 v46, 0, v46, s[78:79]
	v_cndmask_b32_e64 v47, 0, v47, s[50:51]
	v_cvt_pk_bf16_f32 v64, v32, v33
	v_cvt_pk_bf16_f32 v65, v34, v35
	v_cvt_pk_bf16_f32 v66, v36, v37
	v_cvt_pk_bf16_f32 v67, v38, v39
	v_cvt_pk_bf16_f32 v68, v40, v41
	v_cvt_pk_bf16_f32 v69, v42, v43
	v_cvt_pk_bf16_f32 v70, v44, v45
	v_cvt_pk_bf16_f32 v71, v46, v47
	v_pk_add_f32 v[232:233], v[232:233], v[32:33]
	v_pk_add_f32 v[232:233], v[232:233], v[34:35]
	v_pk_add_f32 v[232:233], v[232:233], v[36:37]
	v_pk_add_f32 v[232:233], v[232:233], v[38:39]
	v_pk_add_f32 v[232:233], v[232:233], v[40:41]
	v_pk_add_f32 v[232:233], v[232:233], v[42:43]
	v_pk_add_f32 v[232:233], v[232:233], v[44:45]
	v_pk_add_f32 v[232:233], v[232:233], v[46:47]
	s_waitcnt lgkmcnt(12)
	v_mfma_f32_32x32x16_bf16 v[0:15], v[64:67], v[72:75], v[0:15]
	v_mfma_f32_32x32x16_bf16 v[16:31], v[64:67], v[76:79], v[16:31]
	v_mfma_f32_32x32x16_bf16 v[0:15], v[68:71], v[220:223], v[0:15]
	v_mfma_f32_32x32x16_bf16 v[16:31], v[68:71], v[224:227], v[16:31]
	s_add_i32 s90, s67, 256
	v_add_u32_e32 v80, s90, v235
	v_add_u32_e32 v83, s90, v236
	v_add_u32_e32 v99, s90, v237
	v_add_u32_e32 v253, s90, v238
	v_add_u32_e32 v254, s90, v100
	v_add_u32_e32 v255, s90, v149
	v_med3_i32 v80, v80, 0, s99
	v_med3_i32 v83, v83, 0, s99
	v_med3_i32 v99, v99, 0, s99
	v_med3_i32 v253, v253, 0, s99
	v_med3_i32 v254, v254, 0, s99
	v_med3_i32 v255, v255, 0, s99
	v_mad_u32_u24 v80, v80, s100, v252
	v_mad_u32_u24 v83, v83, s100, v252
	v_mad_u32_u24 v99, v99, s100, v252
	v_mad_u32_u24 v253, v253, s100, v252
	v_mad_u32_u24 v254, v254, s100, v153
	v_mad_u32_u24 v255, v255, s100, v153
	global_load_dwordx4 v[156:159], v80, s[82:83]
	global_load_dwordx4 v[160:163], v83, s[82:83]
	global_load_dwordx4 v[164:167], v99, s[82:83]
	global_load_dwordx4 v[168:171], v253, s[82:83]
	global_load_dwordx4 v[172:175], v254, s[82:83] offset:768
	global_load_dwordx4 v[176:179], v255, s[82:83] offset:768
	global_load_dwordx4 v[180:183], v254, s[82:83] offset:832
	global_load_dwordx4 v[184:187], v255, s[82:83] offset:832
	ds_read2_b32 v[32:33], v115 offset0:34 offset1:35
	ds_read2_b32 v[34:35], v115 offset0:36 offset1:37
	ds_read2_b32 v[36:37], v115 offset0:42 offset1:43
	ds_read2_b32 v[38:39], v115 offset0:44 offset1:45
	ds_read2_b32 v[40:41], v115 offset0:51 offset1:52
	ds_read2_b32 v[42:43], v115 offset0:53 offset1:54
	ds_read2_b32 v[44:45], v115 offset0:59 offset1:60
	ds_read2_b32 v[46:47], v115 offset0:61 offset1:62
	s_waitcnt lgkmcnt(0)
	v_mfma_f32_32x32x16_bf16 v[32:47], v[188:191], v[48:51], v[32:47]
	ds_read_b64_tr_b16 v[72:73], v231
	ds_read_b64_tr_b16 v[74:75], v231 offset:512
	ds_read_b64_tr_b16 v[76:77], v231 offset:2048
	ds_read_b64_tr_b16 v[78:79], v231 offset:2560
	ds_read_b64_tr_b16 v[220:221], v231 offset:1024
	ds_read_b64_tr_b16 v[222:223], v231 offset:1536
	ds_read_b64_tr_b16 v[224:225], v231 offset:3072
	ds_read_b64_tr_b16 v[226:227], v231 offset:3584
	s_waitcnt vmcnt(8)
	ds_write_b128 v247, v[116:119]
	ds_write_b128 v247, v[120:123] offset:1024
	ds_write_b128 v247, v[124:127] offset:2048
	ds_write_b128 v247, v[128:131] offset:3072
	ds_read_b128 v[116:119], v248
	ds_read_b128 v[120:123], v249
	ds_read_b128 v[124:127], v250
	ds_read_b128 v[128:131], v251
	ds_write_b128 v112, v[132:135]
	ds_write_b128 v112, v[136:139] offset:1024
	ds_write_b128 v112, v[140:143] offset:2048
	ds_write_b128 v112, v[144:147] offset:3072
	v_mfma_f32_32x32x16_bf16 v[32:47], v[192:195], v[52:55], v[32:47]
	v_mfma_f32_32x32x16_bf16 v[32:47], v[196:199], v[56:59], v[32:47]
	v_mfma_f32_32x32x16_bf16 v[32:47], v[200:203], v[60:63], v[32:47]
	s_nop 11
	v_exp_f32_e32 v32, v32
	v_exp_f32_e32 v33, v33
	v_exp_f32_e32 v34, v34
	v_exp_f32_e32 v35, v35
	v_exp_f32_e32 v36, v36
	v_exp_f32_e32 v37, v37
	v_exp_f32_e32 v38, v38
	v_exp_f32_e32 v39, v39
	v_exp_f32_e32 v40, v40
	v_exp_f32_e32 v41, v41
	v_exp_f32_e32 v42, v42
	v_exp_f32_e32 v43, v43
	v_exp_f32_e32 v44, v44
	v_exp_f32_e32 v45, v45
	v_exp_f32_e32 v46, v46
	v_exp_f32_e32 v47, v47
	s_add_i32 s90, s67, 192
	v_add_u32_e32 v84, s90, v107
	v_add_u32_e32 v85, 0, v84
	v_add_u32_e32 v86, 1, v84
	v_add_u32_e32 v87, 2, v84
	v_add_u32_e32 v88, 3, v84
	v_cmp_gt_u32_e64 s[30:31], s98, v85
	v_cmp_gt_u32_e64 s[36:37], s98, v86
	v_cmp_gt_u32_e64 s[78:79], s98, v87
	v_cmp_gt_u32_e64 s[50:51], s98, v88
	v_cndmask_b32_e64 v32, 0, v32, s[30:31]
	v_add_u32_e32 v85, 8, v84
	v_cmp_gt_u32_e64 s[30:31], s98, v85
	v_cndmask_b32_e64 v33, 0, v33, s[36:37]
	v_add_u32_e32 v86, 9, v84
	v_cmp_gt_u32_e64 s[36:37], s98, v86
	v_cndmask_b32_e64 v34, 0, v34, s[78:79]
	v_add_u32_e32 v87, 10, v84
	v_cmp_gt_u32_e64 s[78:79], s98, v87
	v_cndmask_b32_e64 v35, 0, v35, s[50:51]
	v_add_u32_e32 v88, 11, v84
	v_cmp_gt_u32_e64 s[50:51], s98, v88
	v_cndmask_b32_e64 v36, 0, v36, s[30:31]
	v_add_u32_e32 v85, 16, v84
	v_cmp_gt_u32_e64 s[30:31], s98, v85
	v_cndmask_b32_e64 v37, 0, v37, s[36:37]
	v_add_u32_e32 v86, 17, v84
	v_cmp_gt_u32_e64 s[36:37], s98, v86
	v_cndmask_b32_e64 v38, 0, v38, s[78:79]
	v_add_u32_e32 v87, 18, v84
	v_cmp_gt_u32_e64 s[78:79], s98, v87
	v_cndmask_b32_e64 v39, 0, v39, s[50:51]
	v_add_u32_e32 v88, 19, v84
	v_cmp_gt_u32_e64 s[50:51], s98, v88
	v_cndmask_b32_e64 v40, 0, v40, s[30:31]
	v_add_u32_e32 v85, 24, v84
	v_cmp_gt_u32_e64 s[30:31], s98, v85
	v_cndmask_b32_e64 v41, 0, v41, s[36:37]
	v_add_u32_e32 v86, 25, v84
	v_cmp_gt_u32_e64 s[36:37], s98, v86
	v_cndmask_b32_e64 v42, 0, v42, s[78:79]
	v_add_u32_e32 v87, 26, v84
	v_cmp_gt_u32_e64 s[78:79], s98, v87
	v_cndmask_b32_e64 v43, 0, v43, s[50:51]
	v_add_u32_e32 v88, 27, v84
	v_cmp_gt_u32_e64 s[50:51], s98, v88
	v_nop
	v_cndmask_b32_e64 v44, 0, v44, s[30:31]
	v_cndmask_b32_e64 v45, 0, v45, s[36:37]
	v_cndmask_b32_e64 v46, 0, v46, s[78:79]
	v_cndmask_b32_e64 v47, 0, v47, s[50:51]
	v_cvt_pk_bf16_f32 v64, v32, v33
	v_cvt_pk_bf16_f32 v65, v34, v35
	v_cvt_pk_bf16_f32 v66, v36, v37
	v_cvt_pk_bf16_f32 v67, v38, v39
	v_cvt_pk_bf16_f32 v68, v40, v41
	v_cvt_pk_bf16_f32 v69, v42, v43
	v_cvt_pk_bf16_f32 v70, v44, v45
	v_cvt_pk_bf16_f32 v71, v46, v47
	v_pk_add_f32 v[232:233], v[232:233], v[32:33]
	v_pk_add_f32 v[232:233], v[232:233], v[34:35]
	v_pk_add_f32 v[232:233], v[232:233], v[36:37]
	v_pk_add_f32 v[232:233], v[232:233], v[38:39]
	v_pk_add_f32 v[232:233], v[232:233], v[40:41]
	v_pk_add_f32 v[232:233], v[232:233], v[42:43]
	v_pk_add_f32 v[232:233], v[232:233], v[44:45]
	v_pk_add_f32 v[232:233], v[232:233], v[46:47]
	s_waitcnt lgkmcnt(12)
	v_mfma_f32_32x32x16_bf16 v[0:15], v[64:67], v[72:75], v[0:15]
	v_mfma_f32_32x32x16_bf16 v[16:31], v[64:67], v[76:79], v[16:31]
	v_mfma_f32_32x32x16_bf16 v[0:15], v[68:71], v[220:223], v[0:15]
	v_mfma_f32_32x32x16_bf16 v[16:31], v[68:71], v[224:227], v[16:31]
	s_add_i32 s90, s67, 288
	v_add_u32_e32 v80, s90, v235
	v_add_u32_e32 v83, s90, v236
	v_add_u32_e32 v99, s90, v237
	v_add_u32_e32 v253, s90, v238
	v_add_u32_e32 v254, s90, v100
	v_add_u32_e32 v255, s90, v149
	v_med3_i32 v80, v80, 0, s99
	v_med3_i32 v83, v83, 0, s99
	v_med3_i32 v99, v99, 0, s99
	v_med3_i32 v253, v253, 0, s99
	v_med3_i32 v254, v254, 0, s99
	v_med3_i32 v255, v255, 0, s99
	v_mad_u32_u24 v80, v80, s100, v252
	v_mad_u32_u24 v83, v83, s100, v252
	v_mad_u32_u24 v99, v99, s100, v252
	v_mad_u32_u24 v253, v253, s100, v252
	v_mad_u32_u24 v254, v254, s100, v153
	v_mad_u32_u24 v255, v255, s100, v153
	global_load_dwordx4 v[188:191], v80, s[82:83]
	global_load_dwordx4 v[192:195], v83, s[82:83]
	global_load_dwordx4 v[196:199], v99, s[82:83]
	global_load_dwordx4 v[200:203], v253, s[82:83]
	global_load_dwordx4 v[204:207], v254, s[82:83] offset:768
	global_load_dwordx4 v[208:211], v255, s[82:83] offset:768
	global_load_dwordx4 v[212:215], v254, s[82:83] offset:832
	global_load_dwordx4 v[216:219], v255, s[82:83] offset:832
	ds_read2_b32 v[32:33], v115 offset0:68 offset1:69
	ds_read2_b32 v[34:35], v115 offset0:70 offset1:71
	ds_read2_b32 v[36:37], v115 offset0:76 offset1:77
	ds_read2_b32 v[38:39], v115 offset0:78 offset1:79
	ds_read2_b32 v[40:41], v115 offset0:85 offset1:86
	ds_read2_b32 v[42:43], v115 offset0:87 offset1:88
	ds_read2_b32 v[44:45], v115 offset0:93 offset1:94
	ds_read2_b32 v[46:47], v115 offset0:95 offset1:96
	s_waitcnt lgkmcnt(0)
	v_mfma_f32_32x32x16_bf16 v[32:47], v[116:119], v[48:51], v[32:47]
	ds_read_b64_tr_b16 v[72:73], v231
	ds_read_b64_tr_b16 v[74:75], v231 offset:512
	ds_read_b64_tr_b16 v[76:77], v231 offset:2048
	ds_read_b64_tr_b16 v[78:79], v231 offset:2560
	ds_read_b64_tr_b16 v[220:221], v231 offset:1024
	ds_read_b64_tr_b16 v[222:223], v231 offset:1536
	ds_read_b64_tr_b16 v[224:225], v231 offset:3072
	ds_read_b64_tr_b16 v[226:227], v231 offset:3584
	s_waitcnt vmcnt(8)
	ds_write_b128 v247, v[156:159]
	ds_write_b128 v247, v[160:163] offset:1024
	ds_write_b128 v247, v[164:167] offset:2048
	ds_write_b128 v247, v[168:171] offset:3072
	ds_read_b128 v[156:159], v248
	ds_read_b128 v[160:163], v249
	ds_read_b128 v[164:167], v250
	ds_read_b128 v[168:171], v251
	ds_write_b128 v112, v[172:175]
	ds_write_b128 v112, v[176:179] offset:1024
	ds_write_b128 v112, v[180:183] offset:2048
	ds_write_b128 v112, v[184:187] offset:3072
	v_mfma_f32_32x32x16_bf16 v[32:47], v[120:123], v[52:55], v[32:47]
	v_mfma_f32_32x32x16_bf16 v[32:47], v[124:127], v[56:59], v[32:47]
	v_mfma_f32_32x32x16_bf16 v[32:47], v[128:131], v[60:63], v[32:47]
	s_nop 11
	v_exp_f32_e32 v32, v32
	v_exp_f32_e32 v33, v33
	v_exp_f32_e32 v34, v34
	v_exp_f32_e32 v35, v35
	v_exp_f32_e32 v36, v36
	v_exp_f32_e32 v37, v37
	v_exp_f32_e32 v38, v38
	v_exp_f32_e32 v39, v39
	v_exp_f32_e32 v40, v40
	v_exp_f32_e32 v41, v41
	v_exp_f32_e32 v42, v42
	v_exp_f32_e32 v43, v43
	v_exp_f32_e32 v44, v44
	v_exp_f32_e32 v45, v45
	v_exp_f32_e32 v46, v46
	v_exp_f32_e32 v47, v47
	s_add_i32 s90, s67, 224
	v_add_u32_e32 v84, s90, v107
	v_add_u32_e32 v85, 0, v84
	v_add_u32_e32 v86, 1, v84
	v_add_u32_e32 v87, 2, v84
	v_add_u32_e32 v88, 3, v84
	v_cmp_gt_u32_e64 s[30:31], s98, v85
	v_cmp_gt_u32_e64 s[36:37], s98, v86
	v_cmp_gt_u32_e64 s[78:79], s98, v87
	v_cmp_gt_u32_e64 s[50:51], s98, v88
	v_cndmask_b32_e64 v32, 0, v32, s[30:31]
	v_add_u32_e32 v85, 8, v84
	v_cmp_gt_u32_e64 s[30:31], s98, v85
	v_cndmask_b32_e64 v33, 0, v33, s[36:37]
	v_add_u32_e32 v86, 9, v84
	v_cmp_gt_u32_e64 s[36:37], s98, v86
	v_cndmask_b32_e64 v34, 0, v34, s[78:79]
	v_add_u32_e32 v87, 10, v84
	v_cmp_gt_u32_e64 s[78:79], s98, v87
	v_cndmask_b32_e64 v35, 0, v35, s[50:51]
	v_add_u32_e32 v88, 11, v84
	v_cmp_gt_u32_e64 s[50:51], s98, v88
	v_cndmask_b32_e64 v36, 0, v36, s[30:31]
	v_add_u32_e32 v85, 16, v84
	v_cmp_gt_u32_e64 s[30:31], s98, v85
	v_cndmask_b32_e64 v37, 0, v37, s[36:37]
	v_add_u32_e32 v86, 17, v84
	v_cmp_gt_u32_e64 s[36:37], s98, v86
	v_cndmask_b32_e64 v38, 0, v38, s[78:79]
	v_add_u32_e32 v87, 18, v84
	v_cmp_gt_u32_e64 s[78:79], s98, v87
	v_cndmask_b32_e64 v39, 0, v39, s[50:51]
	v_add_u32_e32 v88, 19, v84
	v_cmp_gt_u32_e64 s[50:51], s98, v88
	v_cndmask_b32_e64 v40, 0, v40, s[30:31]
	v_add_u32_e32 v85, 24, v84
	v_cmp_gt_u32_e64 s[30:31], s98, v85
	v_cndmask_b32_e64 v41, 0, v41, s[36:37]
	v_add_u32_e32 v86, 25, v84
	v_cmp_gt_u32_e64 s[36:37], s98, v86
	v_cndmask_b32_e64 v42, 0, v42, s[78:79]
	v_add_u32_e32 v87, 26, v84
	v_cmp_gt_u32_e64 s[78:79], s98, v87
	v_cndmask_b32_e64 v43, 0, v43, s[50:51]
	v_add_u32_e32 v88, 27, v84
	v_cmp_gt_u32_e64 s[50:51], s98, v88
	v_nop
	v_cndmask_b32_e64 v44, 0, v44, s[30:31]
	v_cndmask_b32_e64 v45, 0, v45, s[36:37]
	v_cndmask_b32_e64 v46, 0, v46, s[78:79]
	v_cndmask_b32_e64 v47, 0, v47, s[50:51]
	v_cvt_pk_bf16_f32 v64, v32, v33
	v_cvt_pk_bf16_f32 v65, v34, v35
	v_cvt_pk_bf16_f32 v66, v36, v37
	v_cvt_pk_bf16_f32 v67, v38, v39
	v_cvt_pk_bf16_f32 v68, v40, v41
	v_cvt_pk_bf16_f32 v69, v42, v43
	v_cvt_pk_bf16_f32 v70, v44, v45
	v_cvt_pk_bf16_f32 v71, v46, v47
	v_pk_add_f32 v[232:233], v[232:233], v[32:33]
	v_pk_add_f32 v[232:233], v[232:233], v[34:35]
	v_pk_add_f32 v[232:233], v[232:233], v[36:37]
	v_pk_add_f32 v[232:233], v[232:233], v[38:39]
	v_pk_add_f32 v[232:233], v[232:233], v[40:41]
	v_pk_add_f32 v[232:233], v[232:233], v[42:43]
	v_pk_add_f32 v[232:233], v[232:233], v[44:45]
	v_pk_add_f32 v[232:233], v[232:233], v[46:47]
	s_waitcnt lgkmcnt(12)
	v_mfma_f32_32x32x16_bf16 v[0:15], v[64:67], v[72:75], v[0:15]
	v_mfma_f32_32x32x16_bf16 v[16:31], v[64:67], v[76:79], v[16:31]
	v_mfma_f32_32x32x16_bf16 v[0:15], v[68:71], v[220:223], v[0:15]
	v_mfma_f32_32x32x16_bf16 v[16:31], v[68:71], v[224:227], v[16:31]
	s_add_i32 s90, s67, 320
	v_add_u32_e32 v80, s90, v235
	v_add_u32_e32 v83, s90, v236
	v_add_u32_e32 v99, s90, v237
	v_add_u32_e32 v253, s90, v238
	v_add_u32_e32 v254, s90, v100
	v_add_u32_e32 v255, s90, v149
	v_med3_i32 v80, v80, 0, s99
	v_med3_i32 v83, v83, 0, s99
	v_med3_i32 v99, v99, 0, s99
	v_med3_i32 v253, v253, 0, s99
	v_med3_i32 v254, v254, 0, s99
	v_med3_i32 v255, v255, 0, s99
	v_mad_u32_u24 v80, v80, s100, v252
	v_mad_u32_u24 v83, v83, s100, v252
	v_mad_u32_u24 v99, v99, s100, v252
	v_mad_u32_u24 v253, v253, s100, v252
	v_mad_u32_u24 v254, v254, s100, v153
	v_mad_u32_u24 v255, v255, s100, v153
	global_load_dwordx4 v[116:119], v80, s[82:83]
	global_load_dwordx4 v[120:123], v83, s[82:83]
	global_load_dwordx4 v[124:127], v99, s[82:83]
	global_load_dwordx4 v[128:131], v253, s[82:83]
	global_load_dwordx4 v[132:135], v254, s[82:83] offset:768
	global_load_dwordx4 v[136:139], v255, s[82:83] offset:768
	global_load_dwordx4 v[140:143], v254, s[82:83] offset:832
	global_load_dwordx4 v[144:147], v255, s[82:83] offset:832
	ds_read2_b32 v[32:33], v115 offset0:102 offset1:103
	ds_read2_b32 v[34:35], v115 offset0:104 offset1:105
	ds_read2_b32 v[36:37], v115 offset0:110 offset1:111
	ds_read2_b32 v[38:39], v115 offset0:112 offset1:113
	ds_read2_b32 v[40:41], v115 offset0:119 offset1:120
	ds_read2_b32 v[42:43], v115 offset0:121 offset1:122
	ds_read2_b32 v[44:45], v115 offset0:127 offset1:128
	ds_read2_b32 v[46:47], v115 offset0:129 offset1:130
	s_waitcnt lgkmcnt(0)
	v_mfma_f32_32x32x16_bf16 v[32:47], v[156:159], v[48:51], v[32:47]
	ds_read_b64_tr_b16 v[72:73], v231
	ds_read_b64_tr_b16 v[74:75], v231 offset:512
	ds_read_b64_tr_b16 v[76:77], v231 offset:2048
	ds_read_b64_tr_b16 v[78:79], v231 offset:2560
	ds_read_b64_tr_b16 v[220:221], v231 offset:1024
	ds_read_b64_tr_b16 v[222:223], v231 offset:1536
	ds_read_b64_tr_b16 v[224:225], v231 offset:3072
	ds_read_b64_tr_b16 v[226:227], v231 offset:3584
	s_waitcnt vmcnt(8)
	ds_write_b128 v247, v[188:191]
	ds_write_b128 v247, v[192:195] offset:1024
	ds_write_b128 v247, v[196:199] offset:2048
	ds_write_b128 v247, v[200:203] offset:3072
	ds_read_b128 v[188:191], v248
	ds_read_b128 v[192:195], v249
	ds_read_b128 v[196:199], v250
	ds_read_b128 v[200:203], v251
	ds_write_b128 v112, v[204:207]
	ds_write_b128 v112, v[208:211] offset:1024
	ds_write_b128 v112, v[212:215] offset:2048
	ds_write_b128 v112, v[216:219] offset:3072
	v_mfma_f32_32x32x16_bf16 v[32:47], v[160:163], v[52:55], v[32:47]
	v_mfma_f32_32x32x16_bf16 v[32:47], v[164:167], v[56:59], v[32:47]
	v_mfma_f32_32x32x16_bf16 v[32:47], v[168:171], v[60:63], v[32:47]
	s_nop 11
	v_exp_f32_e32 v32, v32
	v_exp_f32_e32 v33, v33
	v_exp_f32_e32 v34, v34
	v_exp_f32_e32 v35, v35
	v_exp_f32_e32 v36, v36
	v_exp_f32_e32 v37, v37
	v_exp_f32_e32 v38, v38
	v_exp_f32_e32 v39, v39
	v_exp_f32_e32 v40, v40
	v_exp_f32_e32 v41, v41
	v_exp_f32_e32 v42, v42
	v_exp_f32_e32 v43, v43
	v_exp_f32_e32 v44, v44
	v_exp_f32_e32 v45, v45
	v_exp_f32_e32 v46, v46
	v_exp_f32_e32 v47, v47
	s_add_i32 s90, s67, 256
	v_add_u32_e32 v84, s90, v107
	v_add_u32_e32 v85, 0, v84
	v_add_u32_e32 v86, 1, v84
	v_add_u32_e32 v87, 2, v84
	v_add_u32_e32 v88, 3, v84
	v_cmp_gt_u32_e64 s[30:31], s98, v85
	v_cmp_gt_u32_e64 s[36:37], s98, v86
	v_cmp_gt_u32_e64 s[78:79], s98, v87
	v_cmp_gt_u32_e64 s[50:51], s98, v88
	v_cndmask_b32_e64 v32, 0, v32, s[30:31]
	v_add_u32_e32 v85, 8, v84
	v_cmp_gt_u32_e64 s[30:31], s98, v85
	v_cndmask_b32_e64 v33, 0, v33, s[36:37]
	v_add_u32_e32 v86, 9, v84
	v_cmp_gt_u32_e64 s[36:37], s98, v86
	v_cndmask_b32_e64 v34, 0, v34, s[78:79]
	v_add_u32_e32 v87, 10, v84
	v_cmp_gt_u32_e64 s[78:79], s98, v87
	v_cndmask_b32_e64 v35, 0, v35, s[50:51]
	v_add_u32_e32 v88, 11, v84
	v_cmp_gt_u32_e64 s[50:51], s98, v88
	v_cndmask_b32_e64 v36, 0, v36, s[30:31]
	v_add_u32_e32 v85, 16, v84
	v_cmp_gt_u32_e64 s[30:31], s98, v85
	v_cndmask_b32_e64 v37, 0, v37, s[36:37]
	v_add_u32_e32 v86, 17, v84
	v_cmp_gt_u32_e64 s[36:37], s98, v86
	v_cndmask_b32_e64 v38, 0, v38, s[78:79]
	v_add_u32_e32 v87, 18, v84
	v_cmp_gt_u32_e64 s[78:79], s98, v87
	v_cndmask_b32_e64 v39, 0, v39, s[50:51]
	v_add_u32_e32 v88, 19, v84
	v_cmp_gt_u32_e64 s[50:51], s98, v88
	v_cndmask_b32_e64 v40, 0, v40, s[30:31]
	v_add_u32_e32 v85, 24, v84
	v_cmp_gt_u32_e64 s[30:31], s98, v85
	v_cndmask_b32_e64 v41, 0, v41, s[36:37]
	v_add_u32_e32 v86, 25, v84
	v_cmp_gt_u32_e64 s[36:37], s98, v86
	v_cndmask_b32_e64 v42, 0, v42, s[78:79]
	v_add_u32_e32 v87, 26, v84
	v_cmp_gt_u32_e64 s[78:79], s98, v87
	v_cndmask_b32_e64 v43, 0, v43, s[50:51]
	v_add_u32_e32 v88, 27, v84
	v_cmp_gt_u32_e64 s[50:51], s98, v88
	v_nop
	v_cndmask_b32_e64 v44, 0, v44, s[30:31]
	v_cndmask_b32_e64 v45, 0, v45, s[36:37]
	v_cndmask_b32_e64 v46, 0, v46, s[78:79]
	v_cndmask_b32_e64 v47, 0, v47, s[50:51]
	v_cvt_pk_bf16_f32 v64, v32, v33
	v_cvt_pk_bf16_f32 v65, v34, v35
	v_cvt_pk_bf16_f32 v66, v36, v37
	v_cvt_pk_bf16_f32 v67, v38, v39
	v_cvt_pk_bf16_f32 v68, v40, v41
	v_cvt_pk_bf16_f32 v69, v42, v43
	v_cvt_pk_bf16_f32 v70, v44, v45
	v_cvt_pk_bf16_f32 v71, v46, v47
	v_pk_add_f32 v[232:233], v[232:233], v[32:33]
	v_pk_add_f32 v[232:233], v[232:233], v[34:35]
	v_pk_add_f32 v[232:233], v[232:233], v[36:37]
	v_pk_add_f32 v[232:233], v[232:233], v[38:39]
	v_pk_add_f32 v[232:233], v[232:233], v[40:41]
	v_pk_add_f32 v[232:233], v[232:233], v[42:43]
	v_pk_add_f32 v[232:233], v[232:233], v[44:45]
	v_pk_add_f32 v[232:233], v[232:233], v[46:47]
	s_waitcnt lgkmcnt(12)
	v_mfma_f32_32x32x16_bf16 v[0:15], v[64:67], v[72:75], v[0:15]
	v_mfma_f32_32x32x16_bf16 v[16:31], v[64:67], v[76:79], v[16:31]
	v_mfma_f32_32x32x16_bf16 v[0:15], v[68:71], v[220:223], v[0:15]
	v_mfma_f32_32x32x16_bf16 v[16:31], v[68:71], v[224:227], v[16:31]
	s_add_i32 s90, s67, 352
	v_add_u32_e32 v80, s90, v235
	v_add_u32_e32 v83, s90, v236
	v_add_u32_e32 v99, s90, v237
	v_add_u32_e32 v253, s90, v238
	v_add_u32_e32 v254, s90, v100
	v_add_u32_e32 v255, s90, v149
	v_med3_i32 v80, v80, 0, s99
	v_med3_i32 v83, v83, 0, s99
	v_med3_i32 v99, v99, 0, s99
	v_med3_i32 v253, v253, 0, s99
	v_med3_i32 v254, v254, 0, s99
	v_med3_i32 v255, v255, 0, s99
	v_mad_u32_u24 v80, v80, s100, v252
	v_mad_u32_u24 v83, v83, s100, v252
	v_mad_u32_u24 v99, v99, s100, v252
	v_mad_u32_u24 v253, v253, s100, v252
	v_mad_u32_u24 v254, v254, s100, v153
	v_mad_u32_u24 v255, v255, s100, v153
	global_load_dwordx4 v[156:159], v80, s[82:83]
	global_load_dwordx4 v[160:163], v83, s[82:83]
	global_load_dwordx4 v[164:167], v99, s[82:83]
	global_load_dwordx4 v[168:171], v253, s[82:83]
	global_load_dwordx4 v[172:175], v254, s[82:83] offset:768
	global_load_dwordx4 v[176:179], v255, s[82:83] offset:768
	global_load_dwordx4 v[180:183], v254, s[82:83] offset:832
	global_load_dwordx4 v[184:187], v255, s[82:83] offset:832
	ds_read2_b32 v[32:33], v115 offset0:136 offset1:137
	ds_read2_b32 v[34:35], v115 offset0:138 offset1:139
	ds_read2_b32 v[36:37], v115 offset0:144 offset1:145
	ds_read2_b32 v[38:39], v115 offset0:146 offset1:147
	ds_read2_b32 v[40:41], v115 offset0:153 offset1:154
	ds_read2_b32 v[42:43], v115 offset0:155 offset1:156
	ds_read2_b32 v[44:45], v115 offset0:161 offset1:162
	ds_read2_b32 v[46:47], v115 offset0:163 offset1:164
	s_waitcnt lgkmcnt(0)
	v_mfma_f32_32x32x16_bf16 v[32:47], v[188:191], v[48:51], v[32:47]
	ds_read_b64_tr_b16 v[72:73], v231
	ds_read_b64_tr_b16 v[74:75], v231 offset:512
	ds_read_b64_tr_b16 v[76:77], v231 offset:2048
	ds_read_b64_tr_b16 v[78:79], v231 offset:2560
	ds_read_b64_tr_b16 v[220:221], v231 offset:1024
	ds_read_b64_tr_b16 v[222:223], v231 offset:1536
	ds_read_b64_tr_b16 v[224:225], v231 offset:3072
	ds_read_b64_tr_b16 v[226:227], v231 offset:3584
	s_waitcnt vmcnt(8)
	ds_write_b128 v247, v[116:119]
	ds_write_b128 v247, v[120:123] offset:1024
	ds_write_b128 v247, v[124:127] offset:2048
	ds_write_b128 v247, v[128:131] offset:3072
	ds_read_b128 v[116:119], v248
	ds_read_b128 v[120:123], v249
	ds_read_b128 v[124:127], v250
	ds_read_b128 v[128:131], v251
	ds_write_b128 v112, v[132:135]
	ds_write_b128 v112, v[136:139] offset:1024
	ds_write_b128 v112, v[140:143] offset:2048
	ds_write_b128 v112, v[144:147] offset:3072
	v_mfma_f32_32x32x16_bf16 v[32:47], v[192:195], v[52:55], v[32:47]
	v_mfma_f32_32x32x16_bf16 v[32:47], v[196:199], v[56:59], v[32:47]
	v_mfma_f32_32x32x16_bf16 v[32:47], v[200:203], v[60:63], v[32:47]
	s_nop 11
	v_exp_f32_e32 v32, v32
	v_exp_f32_e32 v33, v33
	v_exp_f32_e32 v34, v34
	v_exp_f32_e32 v35, v35
	v_exp_f32_e32 v36, v36
	v_exp_f32_e32 v37, v37
	v_exp_f32_e32 v38, v38
	v_exp_f32_e32 v39, v39
	v_exp_f32_e32 v40, v40
	v_exp_f32_e32 v41, v41
	v_exp_f32_e32 v42, v42
	v_exp_f32_e32 v43, v43
	v_exp_f32_e32 v44, v44
	v_exp_f32_e32 v45, v45
	v_exp_f32_e32 v46, v46
	v_exp_f32_e32 v47, v47
	s_add_i32 s90, s67, 288
	v_add_u32_e32 v84, s90, v107
	v_add_u32_e32 v85, 0, v84
	v_add_u32_e32 v86, 1, v84
	v_add_u32_e32 v87, 2, v84
	v_add_u32_e32 v88, 3, v84
	v_cmp_gt_u32_e64 s[30:31], s98, v85
	v_cmp_gt_u32_e64 s[36:37], s98, v86
	v_cmp_gt_u32_e64 s[78:79], s98, v87
	v_cmp_gt_u32_e64 s[50:51], s98, v88
	v_cndmask_b32_e64 v32, 0, v32, s[30:31]
	v_add_u32_e32 v85, 8, v84
	v_cmp_gt_u32_e64 s[30:31], s98, v85
	v_cndmask_b32_e64 v33, 0, v33, s[36:37]
	v_add_u32_e32 v86, 9, v84
	v_cmp_gt_u32_e64 s[36:37], s98, v86
	v_cndmask_b32_e64 v34, 0, v34, s[78:79]
	v_add_u32_e32 v87, 10, v84
	v_cmp_gt_u32_e64 s[78:79], s98, v87
	v_cndmask_b32_e64 v35, 0, v35, s[50:51]
	v_add_u32_e32 v88, 11, v84
	v_cmp_gt_u32_e64 s[50:51], s98, v88
	v_cndmask_b32_e64 v36, 0, v36, s[30:31]
	v_add_u32_e32 v85, 16, v84
	v_cmp_gt_u32_e64 s[30:31], s98, v85
	v_cndmask_b32_e64 v37, 0, v37, s[36:37]
	v_add_u32_e32 v86, 17, v84
	v_cmp_gt_u32_e64 s[36:37], s98, v86
	v_cndmask_b32_e64 v38, 0, v38, s[78:79]
	v_add_u32_e32 v87, 18, v84
	v_cmp_gt_u32_e64 s[78:79], s98, v87
	v_cndmask_b32_e64 v39, 0, v39, s[50:51]
	v_add_u32_e32 v88, 19, v84
	v_cmp_gt_u32_e64 s[50:51], s98, v88
	v_cndmask_b32_e64 v40, 0, v40, s[30:31]
	v_add_u32_e32 v85, 24, v84
	v_cmp_gt_u32_e64 s[30:31], s98, v85
	v_cndmask_b32_e64 v41, 0, v41, s[36:37]
	v_add_u32_e32 v86, 25, v84
	v_cmp_gt_u32_e64 s[36:37], s98, v86
	v_cndmask_b32_e64 v42, 0, v42, s[78:79]
	v_add_u32_e32 v87, 26, v84
	v_cmp_gt_u32_e64 s[78:79], s98, v87
	v_cndmask_b32_e64 v43, 0, v43, s[50:51]
	v_add_u32_e32 v88, 27, v84
	v_cmp_gt_u32_e64 s[50:51], s98, v88
	v_nop
	v_cndmask_b32_e64 v44, 0, v44, s[30:31]
	v_cndmask_b32_e64 v45, 0, v45, s[36:37]
	v_cndmask_b32_e64 v46, 0, v46, s[78:79]
	v_cndmask_b32_e64 v47, 0, v47, s[50:51]
	v_cvt_pk_bf16_f32 v64, v32, v33
	v_cvt_pk_bf16_f32 v65, v34, v35
	v_cvt_pk_bf16_f32 v66, v36, v37
	v_cvt_pk_bf16_f32 v67, v38, v39
	v_cvt_pk_bf16_f32 v68, v40, v41
	v_cvt_pk_bf16_f32 v69, v42, v43
	v_cvt_pk_bf16_f32 v70, v44, v45
	v_cvt_pk_bf16_f32 v71, v46, v47
	v_pk_add_f32 v[232:233], v[232:233], v[32:33]
	v_pk_add_f32 v[232:233], v[232:233], v[34:35]
	v_pk_add_f32 v[232:233], v[232:233], v[36:37]
	v_pk_add_f32 v[232:233], v[232:233], v[38:39]
	v_pk_add_f32 v[232:233], v[232:233], v[40:41]
	v_pk_add_f32 v[232:233], v[232:233], v[42:43]
	v_pk_add_f32 v[232:233], v[232:233], v[44:45]
	v_pk_add_f32 v[232:233], v[232:233], v[46:47]
	s_waitcnt lgkmcnt(12)
	v_mfma_f32_32x32x16_bf16 v[0:15], v[64:67], v[72:75], v[0:15]
	v_mfma_f32_32x32x16_bf16 v[16:31], v[64:67], v[76:79], v[16:31]
	v_mfma_f32_32x32x16_bf16 v[0:15], v[68:71], v[220:223], v[0:15]
	v_mfma_f32_32x32x16_bf16 v[16:31], v[68:71], v[224:227], v[16:31]
	s_add_i32 s90, s67, 384
	v_add_u32_e32 v80, s90, v235
	v_add_u32_e32 v83, s90, v236
	v_add_u32_e32 v99, s90, v237
	v_add_u32_e32 v253, s90, v238
	v_add_u32_e32 v254, s90, v100
	v_add_u32_e32 v255, s90, v149
	v_med3_i32 v80, v80, 0, s99
	v_med3_i32 v83, v83, 0, s99
	v_med3_i32 v99, v99, 0, s99
	v_med3_i32 v253, v253, 0, s99
	v_med3_i32 v254, v254, 0, s99
	v_med3_i32 v255, v255, 0, s99
	v_mad_u32_u24 v80, v80, s100, v252
	v_mad_u32_u24 v83, v83, s100, v252
	v_mad_u32_u24 v99, v99, s100, v252
	v_mad_u32_u24 v253, v253, s100, v252
	v_mad_u32_u24 v254, v254, s100, v153
	v_mad_u32_u24 v255, v255, s100, v153
	global_load_dwordx4 v[188:191], v80, s[82:83]
	global_load_dwordx4 v[192:195], v83, s[82:83]
	global_load_dwordx4 v[196:199], v99, s[82:83]
	global_load_dwordx4 v[200:203], v253, s[82:83]
	global_load_dwordx4 v[204:207], v254, s[82:83] offset:768
	global_load_dwordx4 v[208:211], v255, s[82:83] offset:768
	global_load_dwordx4 v[212:215], v254, s[82:83] offset:832
	global_load_dwordx4 v[216:219], v255, s[82:83] offset:832
	ds_read2_b32 v[32:33], v115 offset0:170 offset1:171
	ds_read2_b32 v[34:35], v115 offset0:172 offset1:173
	ds_read2_b32 v[36:37], v115 offset0:178 offset1:179
	ds_read2_b32 v[38:39], v115 offset0:180 offset1:181
	ds_read2_b32 v[40:41], v115 offset0:187 offset1:188
	ds_read2_b32 v[42:43], v115 offset0:189 offset1:190
	ds_read2_b32 v[44:45], v115 offset0:195 offset1:196
	ds_read2_b32 v[46:47], v115 offset0:197 offset1:198
	s_waitcnt lgkmcnt(0)
	v_mfma_f32_32x32x16_bf16 v[32:47], v[116:119], v[48:51], v[32:47]
	ds_read_b64_tr_b16 v[72:73], v231
	ds_read_b64_tr_b16 v[74:75], v231 offset:512
	ds_read_b64_tr_b16 v[76:77], v231 offset:2048
	ds_read_b64_tr_b16 v[78:79], v231 offset:2560
	ds_read_b64_tr_b16 v[220:221], v231 offset:1024
	ds_read_b64_tr_b16 v[222:223], v231 offset:1536
	ds_read_b64_tr_b16 v[224:225], v231 offset:3072
	ds_read_b64_tr_b16 v[226:227], v231 offset:3584
	s_waitcnt vmcnt(8)
	ds_write_b128 v247, v[156:159]
	ds_write_b128 v247, v[160:163] offset:1024
	ds_write_b128 v247, v[164:167] offset:2048
	ds_write_b128 v247, v[168:171] offset:3072
	ds_read_b128 v[156:159], v248
	ds_read_b128 v[160:163], v249
	ds_read_b128 v[164:167], v250
	ds_read_b128 v[168:171], v251
	ds_write_b128 v112, v[172:175]
	ds_write_b128 v112, v[176:179] offset:1024
	ds_write_b128 v112, v[180:183] offset:2048
	ds_write_b128 v112, v[184:187] offset:3072
	v_mfma_f32_32x32x16_bf16 v[32:47], v[120:123], v[52:55], v[32:47]
	v_mfma_f32_32x32x16_bf16 v[32:47], v[124:127], v[56:59], v[32:47]
	v_mfma_f32_32x32x16_bf16 v[32:47], v[128:131], v[60:63], v[32:47]
	s_nop 11
	v_exp_f32_e32 v32, v32
	v_exp_f32_e32 v33, v33
	v_exp_f32_e32 v34, v34
	v_exp_f32_e32 v35, v35
	v_exp_f32_e32 v36, v36
	v_exp_f32_e32 v37, v37
	v_exp_f32_e32 v38, v38
	v_exp_f32_e32 v39, v39
	v_exp_f32_e32 v40, v40
	v_exp_f32_e32 v41, v41
	v_exp_f32_e32 v42, v42
	v_exp_f32_e32 v43, v43
	v_exp_f32_e32 v44, v44
	v_exp_f32_e32 v45, v45
	v_exp_f32_e32 v46, v46
	v_exp_f32_e32 v47, v47
	s_add_i32 s90, s67, 320
	v_add_u32_e32 v84, s90, v107
	v_add_u32_e32 v85, 0, v84
	v_add_u32_e32 v86, 1, v84
	v_add_u32_e32 v87, 2, v84
	v_add_u32_e32 v88, 3, v84
	v_cmp_gt_u32_e64 s[30:31], s98, v85
	v_cmp_gt_u32_e64 s[36:37], s98, v86
	v_cmp_gt_u32_e64 s[78:79], s98, v87
	v_cmp_gt_u32_e64 s[50:51], s98, v88
	v_cndmask_b32_e64 v32, 0, v32, s[30:31]
	v_add_u32_e32 v85, 8, v84
	v_cmp_gt_u32_e64 s[30:31], s98, v85
	v_cndmask_b32_e64 v33, 0, v33, s[36:37]
	v_add_u32_e32 v86, 9, v84
	v_cmp_gt_u32_e64 s[36:37], s98, v86
	v_cndmask_b32_e64 v34, 0, v34, s[78:79]
	v_add_u32_e32 v87, 10, v84
	v_cmp_gt_u32_e64 s[78:79], s98, v87
	v_cndmask_b32_e64 v35, 0, v35, s[50:51]
	v_add_u32_e32 v88, 11, v84
	v_cmp_gt_u32_e64 s[50:51], s98, v88
	v_cndmask_b32_e64 v36, 0, v36, s[30:31]
	v_add_u32_e32 v85, 16, v84
	v_cmp_gt_u32_e64 s[30:31], s98, v85
	v_cndmask_b32_e64 v37, 0, v37, s[36:37]
	v_add_u32_e32 v86, 17, v84
	v_cmp_gt_u32_e64 s[36:37], s98, v86
	v_cndmask_b32_e64 v38, 0, v38, s[78:79]
	v_add_u32_e32 v87, 18, v84
	v_cmp_gt_u32_e64 s[78:79], s98, v87
	v_cndmask_b32_e64 v39, 0, v39, s[50:51]
	v_add_u32_e32 v88, 19, v84
	v_cmp_gt_u32_e64 s[50:51], s98, v88
	v_cndmask_b32_e64 v40, 0, v40, s[30:31]
	v_add_u32_e32 v85, 24, v84
	v_cmp_gt_u32_e64 s[30:31], s98, v85
	v_cndmask_b32_e64 v41, 0, v41, s[36:37]
	v_add_u32_e32 v86, 25, v84
	v_cmp_gt_u32_e64 s[36:37], s98, v86
	v_cndmask_b32_e64 v42, 0, v42, s[78:79]
	v_add_u32_e32 v87, 26, v84
	v_cmp_gt_u32_e64 s[78:79], s98, v87
	v_cndmask_b32_e64 v43, 0, v43, s[50:51]
	v_add_u32_e32 v88, 27, v84
	v_cmp_gt_u32_e64 s[50:51], s98, v88
	v_nop
	v_cndmask_b32_e64 v44, 0, v44, s[30:31]
	v_cndmask_b32_e64 v45, 0, v45, s[36:37]
	v_cndmask_b32_e64 v46, 0, v46, s[78:79]
	v_cndmask_b32_e64 v47, 0, v47, s[50:51]
	v_cvt_pk_bf16_f32 v64, v32, v33
	v_cvt_pk_bf16_f32 v65, v34, v35
	v_cvt_pk_bf16_f32 v66, v36, v37
	v_cvt_pk_bf16_f32 v67, v38, v39
	v_cvt_pk_bf16_f32 v68, v40, v41
	v_cvt_pk_bf16_f32 v69, v42, v43
	v_cvt_pk_bf16_f32 v70, v44, v45
	v_cvt_pk_bf16_f32 v71, v46, v47
	v_pk_add_f32 v[232:233], v[232:233], v[32:33]
	v_pk_add_f32 v[232:233], v[232:233], v[34:35]
	v_pk_add_f32 v[232:233], v[232:233], v[36:37]
	v_pk_add_f32 v[232:233], v[232:233], v[38:39]
	v_pk_add_f32 v[232:233], v[232:233], v[40:41]
	v_pk_add_f32 v[232:233], v[232:233], v[42:43]
	v_pk_add_f32 v[232:233], v[232:233], v[44:45]
	v_pk_add_f32 v[232:233], v[232:233], v[46:47]
	s_waitcnt lgkmcnt(12)
	v_mfma_f32_32x32x16_bf16 v[0:15], v[64:67], v[72:75], v[0:15]
	v_mfma_f32_32x32x16_bf16 v[16:31], v[64:67], v[76:79], v[16:31]
	v_mfma_f32_32x32x16_bf16 v[0:15], v[68:71], v[220:223], v[0:15]
	v_mfma_f32_32x32x16_bf16 v[16:31], v[68:71], v[224:227], v[16:31]
	s_add_i32 s90, s67, 416
	v_add_u32_e32 v80, s90, v235
	v_add_u32_e32 v83, s90, v236
	v_add_u32_e32 v99, s90, v237
	v_add_u32_e32 v253, s90, v238
	v_add_u32_e32 v254, s90, v100
	v_add_u32_e32 v255, s90, v149
	v_med3_i32 v80, v80, 0, s99
	v_med3_i32 v83, v83, 0, s99
	v_med3_i32 v99, v99, 0, s99
	v_med3_i32 v253, v253, 0, s99
	v_med3_i32 v254, v254, 0, s99
	v_med3_i32 v255, v255, 0, s99
	v_mad_u32_u24 v80, v80, s100, v252
	v_mad_u32_u24 v83, v83, s100, v252
	v_mad_u32_u24 v99, v99, s100, v252
	v_mad_u32_u24 v253, v253, s100, v252
	v_mad_u32_u24 v254, v254, s100, v153
	v_mad_u32_u24 v255, v255, s100, v153
	global_load_dwordx4 v[116:119], v80, s[82:83]
	global_load_dwordx4 v[120:123], v83, s[82:83]
	global_load_dwordx4 v[124:127], v99, s[82:83]
	global_load_dwordx4 v[128:131], v253, s[82:83]
	global_load_dwordx4 v[132:135], v254, s[82:83] offset:768
	global_load_dwordx4 v[136:139], v255, s[82:83] offset:768
	global_load_dwordx4 v[140:143], v254, s[82:83] offset:832
	global_load_dwordx4 v[144:147], v255, s[82:83] offset:832
	ds_read2_b32 v[32:33], v115 offset0:204 offset1:205
	ds_read2_b32 v[34:35], v115 offset0:206 offset1:207
	ds_read2_b32 v[36:37], v115 offset0:212 offset1:213
	ds_read2_b32 v[38:39], v115 offset0:214 offset1:215
	ds_read2_b32 v[40:41], v115 offset0:221 offset1:222
	ds_read2_b32 v[42:43], v115 offset0:223 offset1:224
	ds_read2_b32 v[44:45], v115 offset0:229 offset1:230
	ds_read2_b32 v[46:47], v115 offset0:231 offset1:232
	s_waitcnt lgkmcnt(0)
	v_mfma_f32_32x32x16_bf16 v[32:47], v[156:159], v[48:51], v[32:47]
	ds_read_b64_tr_b16 v[72:73], v231
	ds_read_b64_tr_b16 v[74:75], v231 offset:512
	ds_read_b64_tr_b16 v[76:77], v231 offset:2048
	ds_read_b64_tr_b16 v[78:79], v231 offset:2560
	ds_read_b64_tr_b16 v[220:221], v231 offset:1024
	ds_read_b64_tr_b16 v[222:223], v231 offset:1536
	ds_read_b64_tr_b16 v[224:225], v231 offset:3072
	ds_read_b64_tr_b16 v[226:227], v231 offset:3584
	s_waitcnt vmcnt(8)
	ds_write_b128 v247, v[188:191]
	ds_write_b128 v247, v[192:195] offset:1024
	ds_write_b128 v247, v[196:199] offset:2048
	ds_write_b128 v247, v[200:203] offset:3072
	ds_read_b128 v[188:191], v248
	ds_read_b128 v[192:195], v249
	ds_read_b128 v[196:199], v250
	ds_read_b128 v[200:203], v251
	ds_write_b128 v112, v[204:207]
	ds_write_b128 v112, v[208:211] offset:1024
	ds_write_b128 v112, v[212:215] offset:2048
	ds_write_b128 v112, v[216:219] offset:3072
	v_mfma_f32_32x32x16_bf16 v[32:47], v[160:163], v[52:55], v[32:47]
	v_mfma_f32_32x32x16_bf16 v[32:47], v[164:167], v[56:59], v[32:47]
	v_mfma_f32_32x32x16_bf16 v[32:47], v[168:171], v[60:63], v[32:47]
	s_nop 11
	v_exp_f32_e32 v32, v32
	v_exp_f32_e32 v33, v33
	v_exp_f32_e32 v34, v34
	v_exp_f32_e32 v35, v35
	v_exp_f32_e32 v36, v36
	v_exp_f32_e32 v37, v37
	v_exp_f32_e32 v38, v38
	v_exp_f32_e32 v39, v39
	v_exp_f32_e32 v40, v40
	v_exp_f32_e32 v41, v41
	v_exp_f32_e32 v42, v42
	v_exp_f32_e32 v43, v43
	v_exp_f32_e32 v44, v44
	v_exp_f32_e32 v45, v45
	v_exp_f32_e32 v46, v46
	v_exp_f32_e32 v47, v47
	s_add_i32 s90, s67, 352
	v_add_u32_e32 v84, s90, v107
	v_add_u32_e32 v85, 0, v84
	v_add_u32_e32 v86, 1, v84
	v_add_u32_e32 v87, 2, v84
	v_add_u32_e32 v88, 3, v84
	v_cmp_gt_u32_e64 s[30:31], s98, v85
	v_cmp_gt_u32_e64 s[36:37], s98, v86
	v_cmp_gt_u32_e64 s[78:79], s98, v87
	v_cmp_gt_u32_e64 s[50:51], s98, v88
	v_cndmask_b32_e64 v32, 0, v32, s[30:31]
	v_add_u32_e32 v85, 8, v84
	v_cmp_gt_u32_e64 s[30:31], s98, v85
	v_cndmask_b32_e64 v33, 0, v33, s[36:37]
	v_add_u32_e32 v86, 9, v84
	v_cmp_gt_u32_e64 s[36:37], s98, v86
	v_cndmask_b32_e64 v34, 0, v34, s[78:79]
	v_add_u32_e32 v87, 10, v84
	v_cmp_gt_u32_e64 s[78:79], s98, v87
	v_cndmask_b32_e64 v35, 0, v35, s[50:51]
	v_add_u32_e32 v88, 11, v84
	v_cmp_gt_u32_e64 s[50:51], s98, v88
	v_cndmask_b32_e64 v36, 0, v36, s[30:31]
	v_add_u32_e32 v85, 16, v84
	v_cmp_gt_u32_e64 s[30:31], s98, v85
	v_cndmask_b32_e64 v37, 0, v37, s[36:37]
	v_add_u32_e32 v86, 17, v84
	v_cmp_gt_u32_e64 s[36:37], s98, v86
	v_cndmask_b32_e64 v38, 0, v38, s[78:79]
	v_add_u32_e32 v87, 18, v84
	v_cmp_gt_u32_e64 s[78:79], s98, v87
	v_cndmask_b32_e64 v39, 0, v39, s[50:51]
	v_add_u32_e32 v88, 19, v84
	v_cmp_gt_u32_e64 s[50:51], s98, v88
	v_cndmask_b32_e64 v40, 0, v40, s[30:31]
	v_add_u32_e32 v85, 24, v84
	v_cmp_gt_u32_e64 s[30:31], s98, v85
	v_cndmask_b32_e64 v41, 0, v41, s[36:37]
	v_add_u32_e32 v86, 25, v84
	v_cmp_gt_u32_e64 s[36:37], s98, v86
	v_cndmask_b32_e64 v42, 0, v42, s[78:79]
	v_add_u32_e32 v87, 26, v84
	v_cmp_gt_u32_e64 s[78:79], s98, v87
	v_cndmask_b32_e64 v43, 0, v43, s[50:51]
	v_add_u32_e32 v88, 27, v84
	v_cmp_gt_u32_e64 s[50:51], s98, v88
	v_nop
	v_cndmask_b32_e64 v44, 0, v44, s[30:31]
	v_cndmask_b32_e64 v45, 0, v45, s[36:37]
	v_cndmask_b32_e64 v46, 0, v46, s[78:79]
	v_cndmask_b32_e64 v47, 0, v47, s[50:51]
	v_cvt_pk_bf16_f32 v64, v32, v33
	v_cvt_pk_bf16_f32 v65, v34, v35
	v_cvt_pk_bf16_f32 v66, v36, v37
	v_cvt_pk_bf16_f32 v67, v38, v39
	v_cvt_pk_bf16_f32 v68, v40, v41
	v_cvt_pk_bf16_f32 v69, v42, v43
	v_cvt_pk_bf16_f32 v70, v44, v45
	v_cvt_pk_bf16_f32 v71, v46, v47
	v_pk_add_f32 v[232:233], v[232:233], v[32:33]
	v_pk_add_f32 v[232:233], v[232:233], v[34:35]
	v_pk_add_f32 v[232:233], v[232:233], v[36:37]
	v_pk_add_f32 v[232:233], v[232:233], v[38:39]
	v_pk_add_f32 v[232:233], v[232:233], v[40:41]
	v_pk_add_f32 v[232:233], v[232:233], v[42:43]
	v_pk_add_f32 v[232:233], v[232:233], v[44:45]
	v_pk_add_f32 v[232:233], v[232:233], v[46:47]
	s_waitcnt lgkmcnt(12)
	v_mfma_f32_32x32x16_bf16 v[0:15], v[64:67], v[72:75], v[0:15]
	v_mfma_f32_32x32x16_bf16 v[16:31], v[64:67], v[76:79], v[16:31]
	v_mfma_f32_32x32x16_bf16 v[0:15], v[68:71], v[220:223], v[0:15]
	v_mfma_f32_32x32x16_bf16 v[16:31], v[68:71], v[224:227], v[16:31]
	s_add_i32 s90, s67, 448
	v_add_u32_e32 v80, s90, v235
	v_add_u32_e32 v83, s90, v236
	v_add_u32_e32 v99, s90, v237
	v_add_u32_e32 v253, s90, v238
	v_add_u32_e32 v254, s90, v100
	v_add_u32_e32 v255, s90, v149
	v_med3_i32 v80, v80, 0, s99
	v_med3_i32 v83, v83, 0, s99
	v_med3_i32 v99, v99, 0, s99
	v_med3_i32 v253, v253, 0, s99
	v_med3_i32 v254, v254, 0, s99
	v_med3_i32 v255, v255, 0, s99
	v_mad_u32_u24 v80, v80, s100, v252
	v_mad_u32_u24 v83, v83, s100, v252
	v_mad_u32_u24 v99, v99, s100, v252
	v_mad_u32_u24 v253, v253, s100, v252
	v_mad_u32_u24 v254, v254, s100, v153
	v_mad_u32_u24 v255, v255, s100, v153
	global_load_dwordx4 v[156:159], v80, s[82:83]
	global_load_dwordx4 v[160:163], v83, s[82:83]
	global_load_dwordx4 v[164:167], v99, s[82:83]
	global_load_dwordx4 v[168:171], v253, s[82:83]
	global_load_dwordx4 v[172:175], v254, s[82:83] offset:768
	global_load_dwordx4 v[176:179], v255, s[82:83] offset:768
	global_load_dwordx4 v[180:183], v254, s[82:83] offset:832
	global_load_dwordx4 v[184:187], v255, s[82:83] offset:832
	v_add_u32_e32 v115, 952, v115
	ds_read2_b32 v[32:33], v115 offset0:0 offset1:1
	ds_read2_b32 v[34:35], v115 offset0:2 offset1:3
	ds_read2_b32 v[36:37], v115 offset0:8 offset1:9
	ds_read2_b32 v[38:39], v115 offset0:10 offset1:11
	ds_read2_b32 v[40:41], v115 offset0:17 offset1:18
	ds_read2_b32 v[42:43], v115 offset0:19 offset1:20
	ds_read2_b32 v[44:45], v115 offset0:25 offset1:26
	ds_read2_b32 v[46:47], v115 offset0:27 offset1:28
	s_waitcnt lgkmcnt(0)
	v_mfma_f32_32x32x16_bf16 v[32:47], v[188:191], v[48:51], v[32:47]
	ds_read_b64_tr_b16 v[72:73], v231
	ds_read_b64_tr_b16 v[74:75], v231 offset:512
	ds_read_b64_tr_b16 v[76:77], v231 offset:2048
	ds_read_b64_tr_b16 v[78:79], v231 offset:2560
	ds_read_b64_tr_b16 v[220:221], v231 offset:1024
	ds_read_b64_tr_b16 v[222:223], v231 offset:1536
	ds_read_b64_tr_b16 v[224:225], v231 offset:3072
	ds_read_b64_tr_b16 v[226:227], v231 offset:3584
	s_waitcnt vmcnt(8)
	ds_write_b128 v247, v[116:119]
	ds_write_b128 v247, v[120:123] offset:1024
	ds_write_b128 v247, v[124:127] offset:2048
	ds_write_b128 v247, v[128:131] offset:3072
	ds_read_b128 v[116:119], v248
	ds_read_b128 v[120:123], v249
	ds_read_b128 v[124:127], v250
	ds_read_b128 v[128:131], v251
	ds_write_b128 v112, v[132:135]
	ds_write_b128 v112, v[136:139] offset:1024
	ds_write_b128 v112, v[140:143] offset:2048
	ds_write_b128 v112, v[144:147] offset:3072
	v_mfma_f32_32x32x16_bf16 v[32:47], v[192:195], v[52:55], v[32:47]
	v_mfma_f32_32x32x16_bf16 v[32:47], v[196:199], v[56:59], v[32:47]
	v_mfma_f32_32x32x16_bf16 v[32:47], v[200:203], v[60:63], v[32:47]
	s_nop 11
	v_exp_f32_e32 v32, v32
	v_exp_f32_e32 v33, v33
	v_exp_f32_e32 v34, v34
	v_exp_f32_e32 v35, v35
	v_exp_f32_e32 v36, v36
	v_exp_f32_e32 v37, v37
	v_exp_f32_e32 v38, v38
	v_exp_f32_e32 v39, v39
	v_exp_f32_e32 v40, v40
	v_exp_f32_e32 v41, v41
	v_exp_f32_e32 v42, v42
	v_exp_f32_e32 v43, v43
	v_exp_f32_e32 v44, v44
	v_exp_f32_e32 v45, v45
	v_exp_f32_e32 v46, v46
	v_exp_f32_e32 v47, v47
	s_add_i32 s90, s67, 384
	v_add_u32_e32 v84, s90, v107
	v_add_u32_e32 v85, 0, v84
	v_add_u32_e32 v86, 1, v84
	v_add_u32_e32 v87, 2, v84
	v_add_u32_e32 v88, 3, v84
	v_cmp_gt_u32_e64 s[30:31], s98, v85
	v_cmp_gt_u32_e64 s[36:37], s98, v86
	v_cmp_gt_u32_e64 s[78:79], s98, v87
	v_cmp_gt_u32_e64 s[50:51], s98, v88
	v_cndmask_b32_e64 v32, 0, v32, s[30:31]
	v_add_u32_e32 v85, 8, v84
	v_cmp_gt_u32_e64 s[30:31], s98, v85
	v_cndmask_b32_e64 v33, 0, v33, s[36:37]
	v_add_u32_e32 v86, 9, v84
	v_cmp_gt_u32_e64 s[36:37], s98, v86
	v_cndmask_b32_e64 v34, 0, v34, s[78:79]
	v_add_u32_e32 v87, 10, v84
	v_cmp_gt_u32_e64 s[78:79], s98, v87
	v_cndmask_b32_e64 v35, 0, v35, s[50:51]
	v_add_u32_e32 v88, 11, v84
	v_cmp_gt_u32_e64 s[50:51], s98, v88
	v_cndmask_b32_e64 v36, 0, v36, s[30:31]
	v_add_u32_e32 v85, 16, v84
	v_cmp_gt_u32_e64 s[30:31], s98, v85
	v_cndmask_b32_e64 v37, 0, v37, s[36:37]
	v_add_u32_e32 v86, 17, v84
	v_cmp_gt_u32_e64 s[36:37], s98, v86
	v_cndmask_b32_e64 v38, 0, v38, s[78:79]
	v_add_u32_e32 v87, 18, v84
	v_cmp_gt_u32_e64 s[78:79], s98, v87
	v_cndmask_b32_e64 v39, 0, v39, s[50:51]
	v_add_u32_e32 v88, 19, v84
	v_cmp_gt_u32_e64 s[50:51], s98, v88
	v_cndmask_b32_e64 v40, 0, v40, s[30:31]
	v_add_u32_e32 v85, 24, v84
	v_cmp_gt_u32_e64 s[30:31], s98, v85
	v_cndmask_b32_e64 v41, 0, v41, s[36:37]
	v_add_u32_e32 v86, 25, v84
	v_cmp_gt_u32_e64 s[36:37], s98, v86
	v_cndmask_b32_e64 v42, 0, v42, s[78:79]
	v_add_u32_e32 v87, 26, v84
	v_cmp_gt_u32_e64 s[78:79], s98, v87
	v_cndmask_b32_e64 v43, 0, v43, s[50:51]
	v_add_u32_e32 v88, 27, v84
	v_cmp_gt_u32_e64 s[50:51], s98, v88
	v_nop
	v_cndmask_b32_e64 v44, 0, v44, s[30:31]
	v_cndmask_b32_e64 v45, 0, v45, s[36:37]
	v_cndmask_b32_e64 v46, 0, v46, s[78:79]
	v_cndmask_b32_e64 v47, 0, v47, s[50:51]
	v_cvt_pk_bf16_f32 v64, v32, v33
	v_cvt_pk_bf16_f32 v65, v34, v35
	v_cvt_pk_bf16_f32 v66, v36, v37
	v_cvt_pk_bf16_f32 v67, v38, v39
	v_cvt_pk_bf16_f32 v68, v40, v41
	v_cvt_pk_bf16_f32 v69, v42, v43
	v_cvt_pk_bf16_f32 v70, v44, v45
	v_cvt_pk_bf16_f32 v71, v46, v47
	v_pk_add_f32 v[232:233], v[232:233], v[32:33]
	v_pk_add_f32 v[232:233], v[232:233], v[34:35]
	v_pk_add_f32 v[232:233], v[232:233], v[36:37]
	v_pk_add_f32 v[232:233], v[232:233], v[38:39]
	v_pk_add_f32 v[232:233], v[232:233], v[40:41]
	v_pk_add_f32 v[232:233], v[232:233], v[42:43]
	v_pk_add_f32 v[232:233], v[232:233], v[44:45]
	v_pk_add_f32 v[232:233], v[232:233], v[46:47]
	s_waitcnt lgkmcnt(12)
	v_mfma_f32_32x32x16_bf16 v[0:15], v[64:67], v[72:75], v[0:15]
	v_mfma_f32_32x32x16_bf16 v[16:31], v[64:67], v[76:79], v[16:31]
	v_mfma_f32_32x32x16_bf16 v[0:15], v[68:71], v[220:223], v[0:15]
	v_mfma_f32_32x32x16_bf16 v[16:31], v[68:71], v[224:227], v[16:31]
	s_add_i32 s90, s67, 480
	v_add_u32_e32 v80, s90, v235
	v_add_u32_e32 v83, s90, v236
	v_add_u32_e32 v99, s90, v237
	v_add_u32_e32 v253, s90, v238
	v_add_u32_e32 v254, s90, v100
	v_add_u32_e32 v255, s90, v149
	v_med3_i32 v80, v80, 0, s99
	v_med3_i32 v83, v83, 0, s99
	v_med3_i32 v99, v99, 0, s99
	v_med3_i32 v253, v253, 0, s99
	v_med3_i32 v254, v254, 0, s99
	v_med3_i32 v255, v255, 0, s99
	v_mad_u32_u24 v80, v80, s100, v252
	v_mad_u32_u24 v83, v83, s100, v252
	v_mad_u32_u24 v99, v99, s100, v252
	v_mad_u32_u24 v253, v253, s100, v252
	v_mad_u32_u24 v254, v254, s100, v153
	v_mad_u32_u24 v255, v255, s100, v153
	global_load_dwordx4 v[188:191], v80, s[82:83]
	global_load_dwordx4 v[192:195], v83, s[82:83]
	global_load_dwordx4 v[196:199], v99, s[82:83]
	global_load_dwordx4 v[200:203], v253, s[82:83]
	global_load_dwordx4 v[204:207], v254, s[82:83] offset:768
	global_load_dwordx4 v[208:211], v255, s[82:83] offset:768
	global_load_dwordx4 v[212:215], v254, s[82:83] offset:832
	global_load_dwordx4 v[216:219], v255, s[82:83] offset:832
	ds_read2_b32 v[32:33], v115 offset0:34 offset1:35
	ds_read2_b32 v[34:35], v115 offset0:36 offset1:37
	ds_read2_b32 v[36:37], v115 offset0:42 offset1:43
	ds_read2_b32 v[38:39], v115 offset0:44 offset1:45
	ds_read2_b32 v[40:41], v115 offset0:51 offset1:52
	ds_read2_b32 v[42:43], v115 offset0:53 offset1:54
	ds_read2_b32 v[44:45], v115 offset0:59 offset1:60
	ds_read2_b32 v[46:47], v115 offset0:61 offset1:62
	s_waitcnt lgkmcnt(0)
	v_mfma_f32_32x32x16_bf16 v[32:47], v[116:119], v[48:51], v[32:47]
	ds_read_b64_tr_b16 v[72:73], v231
	ds_read_b64_tr_b16 v[74:75], v231 offset:512
	ds_read_b64_tr_b16 v[76:77], v231 offset:2048
	ds_read_b64_tr_b16 v[78:79], v231 offset:2560
	ds_read_b64_tr_b16 v[220:221], v231 offset:1024
	ds_read_b64_tr_b16 v[222:223], v231 offset:1536
	ds_read_b64_tr_b16 v[224:225], v231 offset:3072
	ds_read_b64_tr_b16 v[226:227], v231 offset:3584
	s_waitcnt vmcnt(8)
	ds_write_b128 v247, v[156:159]
	ds_write_b128 v247, v[160:163] offset:1024
	ds_write_b128 v247, v[164:167] offset:2048
	ds_write_b128 v247, v[168:171] offset:3072
	ds_read_b128 v[156:159], v248
	ds_read_b128 v[160:163], v249
	ds_read_b128 v[164:167], v250
	ds_read_b128 v[168:171], v251
	ds_write_b128 v112, v[172:175]
	ds_write_b128 v112, v[176:179] offset:1024
	ds_write_b128 v112, v[180:183] offset:2048
	ds_write_b128 v112, v[184:187] offset:3072
	v_mfma_f32_32x32x16_bf16 v[32:47], v[120:123], v[52:55], v[32:47]
	v_mfma_f32_32x32x16_bf16 v[32:47], v[124:127], v[56:59], v[32:47]
	v_mfma_f32_32x32x16_bf16 v[32:47], v[128:131], v[60:63], v[32:47]
	s_nop 11
	v_exp_f32_e32 v32, v32
	v_exp_f32_e32 v33, v33
	v_exp_f32_e32 v34, v34
	v_exp_f32_e32 v35, v35
	v_exp_f32_e32 v36, v36
	v_exp_f32_e32 v37, v37
	v_exp_f32_e32 v38, v38
	v_exp_f32_e32 v39, v39
	v_exp_f32_e32 v40, v40
	v_exp_f32_e32 v41, v41
	v_exp_f32_e32 v42, v42
	v_exp_f32_e32 v43, v43
	v_exp_f32_e32 v44, v44
	v_exp_f32_e32 v45, v45
	v_exp_f32_e32 v46, v46
	v_exp_f32_e32 v47, v47
	s_add_i32 s90, s67, 416
	v_add_u32_e32 v84, s90, v107
	v_add_u32_e32 v85, 0, v84
	v_add_u32_e32 v86, 1, v84
	v_add_u32_e32 v87, 2, v84
	v_add_u32_e32 v88, 3, v84
	v_cmp_gt_u32_e64 s[30:31], s98, v85
	v_cmp_gt_u32_e64 s[36:37], s98, v86
	v_cmp_gt_u32_e64 s[78:79], s98, v87
	v_cmp_gt_u32_e64 s[50:51], s98, v88
	v_cndmask_b32_e64 v32, 0, v32, s[30:31]
	v_add_u32_e32 v85, 8, v84
	v_cmp_gt_u32_e64 s[30:31], s98, v85
	v_cndmask_b32_e64 v33, 0, v33, s[36:37]
	v_add_u32_e32 v86, 9, v84
	v_cmp_gt_u32_e64 s[36:37], s98, v86
	v_cndmask_b32_e64 v34, 0, v34, s[78:79]
	v_add_u32_e32 v87, 10, v84
	v_cmp_gt_u32_e64 s[78:79], s98, v87
	v_cndmask_b32_e64 v35, 0, v35, s[50:51]
	v_add_u32_e32 v88, 11, v84
	v_cmp_gt_u32_e64 s[50:51], s98, v88
	v_cndmask_b32_e64 v36, 0, v36, s[30:31]
	v_add_u32_e32 v85, 16, v84
	v_cmp_gt_u32_e64 s[30:31], s98, v85
	v_cndmask_b32_e64 v37, 0, v37, s[36:37]
	v_add_u32_e32 v86, 17, v84
	v_cmp_gt_u32_e64 s[36:37], s98, v86
	v_cndmask_b32_e64 v38, 0, v38, s[78:79]
	v_add_u32_e32 v87, 18, v84
	v_cmp_gt_u32_e64 s[78:79], s98, v87
	v_cndmask_b32_e64 v39, 0, v39, s[50:51]
	v_add_u32_e32 v88, 19, v84
	v_cmp_gt_u32_e64 s[50:51], s98, v88
	v_cndmask_b32_e64 v40, 0, v40, s[30:31]
	v_add_u32_e32 v85, 24, v84
	v_cmp_gt_u32_e64 s[30:31], s98, v85
	v_cndmask_b32_e64 v41, 0, v41, s[36:37]
	v_add_u32_e32 v86, 25, v84
	v_cmp_gt_u32_e64 s[36:37], s98, v86
	v_cndmask_b32_e64 v42, 0, v42, s[78:79]
	v_add_u32_e32 v87, 26, v84
	v_cmp_gt_u32_e64 s[78:79], s98, v87
	v_cndmask_b32_e64 v43, 0, v43, s[50:51]
	v_add_u32_e32 v88, 27, v84
	v_cmp_gt_u32_e64 s[50:51], s98, v88
	v_nop
	v_cndmask_b32_e64 v44, 0, v44, s[30:31]
	v_cndmask_b32_e64 v45, 0, v45, s[36:37]
	v_cndmask_b32_e64 v46, 0, v46, s[78:79]
	v_cndmask_b32_e64 v47, 0, v47, s[50:51]
	v_cvt_pk_bf16_f32 v64, v32, v33
	v_cvt_pk_bf16_f32 v65, v34, v35
	v_cvt_pk_bf16_f32 v66, v36, v37
	v_cvt_pk_bf16_f32 v67, v38, v39
	v_cvt_pk_bf16_f32 v68, v40, v41
	v_cvt_pk_bf16_f32 v69, v42, v43
	v_cvt_pk_bf16_f32 v70, v44, v45
	v_cvt_pk_bf16_f32 v71, v46, v47
	v_pk_add_f32 v[232:233], v[232:233], v[32:33]
	v_pk_add_f32 v[232:233], v[232:233], v[34:35]
	v_pk_add_f32 v[232:233], v[232:233], v[36:37]
	v_pk_add_f32 v[232:233], v[232:233], v[38:39]
	v_pk_add_f32 v[232:233], v[232:233], v[40:41]
	v_pk_add_f32 v[232:233], v[232:233], v[42:43]
	v_pk_add_f32 v[232:233], v[232:233], v[44:45]
	v_pk_add_f32 v[232:233], v[232:233], v[46:47]
	s_waitcnt lgkmcnt(12)
	v_mfma_f32_32x32x16_bf16 v[0:15], v[64:67], v[72:75], v[0:15]
	v_mfma_f32_32x32x16_bf16 v[16:31], v[64:67], v[76:79], v[16:31]
	v_mfma_f32_32x32x16_bf16 v[0:15], v[68:71], v[220:223], v[0:15]
	v_mfma_f32_32x32x16_bf16 v[16:31], v[68:71], v[224:227], v[16:31]
	s_add_i32 s90, s67, 512
	v_add_u32_e32 v80, s90, v235
	v_add_u32_e32 v83, s90, v236
	v_add_u32_e32 v99, s90, v237
	v_add_u32_e32 v253, s90, v238
	v_add_u32_e32 v254, s90, v100
	v_add_u32_e32 v255, s90, v149
	v_med3_i32 v80, v80, 0, s99
	v_med3_i32 v83, v83, 0, s99
	v_med3_i32 v99, v99, 0, s99
	v_med3_i32 v253, v253, 0, s99
	v_med3_i32 v254, v254, 0, s99
	v_med3_i32 v255, v255, 0, s99
	v_mad_u32_u24 v80, v80, s100, v252
	v_mad_u32_u24 v83, v83, s100, v252
	v_mad_u32_u24 v99, v99, s100, v252
	v_mad_u32_u24 v253, v253, s100, v252
	v_mad_u32_u24 v254, v254, s100, v153
	v_mad_u32_u24 v255, v255, s100, v153
	global_load_dwordx4 v[116:119], v80, s[82:83]
	global_load_dwordx4 v[120:123], v83, s[82:83]
	global_load_dwordx4 v[124:127], v99, s[82:83]
	global_load_dwordx4 v[128:131], v253, s[82:83]
	global_load_dwordx4 v[132:135], v254, s[82:83] offset:768
	global_load_dwordx4 v[136:139], v255, s[82:83] offset:768
	global_load_dwordx4 v[140:143], v254, s[82:83] offset:832
	global_load_dwordx4 v[144:147], v255, s[82:83] offset:832
	ds_read2_b32 v[32:33], v115 offset0:68 offset1:69
	ds_read2_b32 v[34:35], v115 offset0:70 offset1:71
	ds_read2_b32 v[36:37], v115 offset0:76 offset1:77
	ds_read2_b32 v[38:39], v115 offset0:78 offset1:79
	ds_read2_b32 v[40:41], v115 offset0:85 offset1:86
	ds_read2_b32 v[42:43], v115 offset0:87 offset1:88
	ds_read2_b32 v[44:45], v115 offset0:93 offset1:94
	ds_read2_b32 v[46:47], v115 offset0:95 offset1:96
	s_waitcnt lgkmcnt(0)
	v_mfma_f32_32x32x16_bf16 v[32:47], v[156:159], v[48:51], v[32:47]
	ds_read_b64_tr_b16 v[72:73], v231
	ds_read_b64_tr_b16 v[74:75], v231 offset:512
	ds_read_b64_tr_b16 v[76:77], v231 offset:2048
	ds_read_b64_tr_b16 v[78:79], v231 offset:2560
	ds_read_b64_tr_b16 v[220:221], v231 offset:1024
	ds_read_b64_tr_b16 v[222:223], v231 offset:1536
	ds_read_b64_tr_b16 v[224:225], v231 offset:3072
	ds_read_b64_tr_b16 v[226:227], v231 offset:3584
	s_waitcnt vmcnt(8)
	ds_write_b128 v247, v[188:191]
	ds_write_b128 v247, v[192:195] offset:1024
	ds_write_b128 v247, v[196:199] offset:2048
	ds_write_b128 v247, v[200:203] offset:3072
	ds_read_b128 v[188:191], v248
	ds_read_b128 v[192:195], v249
	ds_read_b128 v[196:199], v250
	ds_read_b128 v[200:203], v251
	ds_write_b128 v112, v[204:207]
	ds_write_b128 v112, v[208:211] offset:1024
	ds_write_b128 v112, v[212:215] offset:2048
	ds_write_b128 v112, v[216:219] offset:3072
	v_mfma_f32_32x32x16_bf16 v[32:47], v[160:163], v[52:55], v[32:47]
	v_mfma_f32_32x32x16_bf16 v[32:47], v[164:167], v[56:59], v[32:47]
	v_mfma_f32_32x32x16_bf16 v[32:47], v[168:171], v[60:63], v[32:47]
	s_nop 11
	v_exp_f32_e32 v32, v32
	v_exp_f32_e32 v33, v33
	v_exp_f32_e32 v34, v34
	v_exp_f32_e32 v35, v35
	v_exp_f32_e32 v36, v36
	v_exp_f32_e32 v37, v37
	v_exp_f32_e32 v38, v38
	v_exp_f32_e32 v39, v39
	v_exp_f32_e32 v40, v40
	v_exp_f32_e32 v41, v41
	v_exp_f32_e32 v42, v42
	v_exp_f32_e32 v43, v43
	v_exp_f32_e32 v44, v44
	v_exp_f32_e32 v45, v45
	v_exp_f32_e32 v46, v46
	v_exp_f32_e32 v47, v47
	s_add_i32 s90, s67, 448
	v_add_u32_e32 v84, s90, v107
	v_add_u32_e32 v85, 0, v84
	v_add_u32_e32 v86, 1, v84
	v_add_u32_e32 v87, 2, v84
	v_add_u32_e32 v88, 3, v84
	v_cmp_gt_u32_e64 s[30:31], s98, v85
	v_cmp_gt_u32_e64 s[36:37], s98, v86
	v_cmp_gt_u32_e64 s[78:79], s98, v87
	v_cmp_gt_u32_e64 s[50:51], s98, v88
	v_cndmask_b32_e64 v32, 0, v32, s[30:31]
	v_add_u32_e32 v85, 8, v84
	v_cmp_gt_u32_e64 s[30:31], s98, v85
	v_cndmask_b32_e64 v33, 0, v33, s[36:37]
	v_add_u32_e32 v86, 9, v84
	v_cmp_gt_u32_e64 s[36:37], s98, v86
	v_cndmask_b32_e64 v34, 0, v34, s[78:79]
	v_add_u32_e32 v87, 10, v84
	v_cmp_gt_u32_e64 s[78:79], s98, v87
	v_cndmask_b32_e64 v35, 0, v35, s[50:51]
	v_add_u32_e32 v88, 11, v84
	v_cmp_gt_u32_e64 s[50:51], s98, v88
	v_cndmask_b32_e64 v36, 0, v36, s[30:31]
	v_add_u32_e32 v85, 16, v84
	v_cmp_gt_u32_e64 s[30:31], s98, v85
	v_cndmask_b32_e64 v37, 0, v37, s[36:37]
	v_add_u32_e32 v86, 17, v84
	v_cmp_gt_u32_e64 s[36:37], s98, v86
	v_cndmask_b32_e64 v38, 0, v38, s[78:79]
	v_add_u32_e32 v87, 18, v84
	v_cmp_gt_u32_e64 s[78:79], s98, v87
	v_cndmask_b32_e64 v39, 0, v39, s[50:51]
	v_add_u32_e32 v88, 19, v84
	v_cmp_gt_u32_e64 s[50:51], s98, v88
	v_cndmask_b32_e64 v40, 0, v40, s[30:31]
	v_add_u32_e32 v85, 24, v84
	v_cmp_gt_u32_e64 s[30:31], s98, v85
	v_cndmask_b32_e64 v41, 0, v41, s[36:37]
	v_add_u32_e32 v86, 25, v84
	v_cmp_gt_u32_e64 s[36:37], s98, v86
	v_cndmask_b32_e64 v42, 0, v42, s[78:79]
	v_add_u32_e32 v87, 26, v84
	v_cmp_gt_u32_e64 s[78:79], s98, v87
	v_cndmask_b32_e64 v43, 0, v43, s[50:51]
	v_add_u32_e32 v88, 27, v84
	v_cmp_gt_u32_e64 s[50:51], s98, v88
	v_nop
	v_cndmask_b32_e64 v44, 0, v44, s[30:31]
	v_cndmask_b32_e64 v45, 0, v45, s[36:37]
	v_cndmask_b32_e64 v46, 0, v46, s[78:79]
	v_cndmask_b32_e64 v47, 0, v47, s[50:51]
	v_cvt_pk_bf16_f32 v64, v32, v33
	v_cvt_pk_bf16_f32 v65, v34, v35
	v_cvt_pk_bf16_f32 v66, v36, v37
	v_cvt_pk_bf16_f32 v67, v38, v39
	v_cvt_pk_bf16_f32 v68, v40, v41
	v_cvt_pk_bf16_f32 v69, v42, v43
	v_cvt_pk_bf16_f32 v70, v44, v45
	v_cvt_pk_bf16_f32 v71, v46, v47
	v_pk_add_f32 v[232:233], v[232:233], v[32:33]
	v_pk_add_f32 v[232:233], v[232:233], v[34:35]
	v_pk_add_f32 v[232:233], v[232:233], v[36:37]
	v_pk_add_f32 v[232:233], v[232:233], v[38:39]
	v_pk_add_f32 v[232:233], v[232:233], v[40:41]
	v_pk_add_f32 v[232:233], v[232:233], v[42:43]
	v_pk_add_f32 v[232:233], v[232:233], v[44:45]
	v_pk_add_f32 v[232:233], v[232:233], v[46:47]
	s_waitcnt lgkmcnt(12)
	v_mfma_f32_32x32x16_bf16 v[0:15], v[64:67], v[72:75], v[0:15]
	v_mfma_f32_32x32x16_bf16 v[16:31], v[64:67], v[76:79], v[16:31]
	v_mfma_f32_32x32x16_bf16 v[0:15], v[68:71], v[220:223], v[0:15]
	v_mfma_f32_32x32x16_bf16 v[16:31], v[68:71], v[224:227], v[16:31]
	s_add_i32 s90, s67, 544
	v_add_u32_e32 v80, s90, v235
	v_add_u32_e32 v83, s90, v236
	v_add_u32_e32 v99, s90, v237
	v_add_u32_e32 v253, s90, v238
	v_add_u32_e32 v254, s90, v100
	v_add_u32_e32 v255, s90, v149
	v_med3_i32 v80, v80, 0, s99
	v_med3_i32 v83, v83, 0, s99
	v_med3_i32 v99, v99, 0, s99
	v_med3_i32 v253, v253, 0, s99
	v_med3_i32 v254, v254, 0, s99
	v_med3_i32 v255, v255, 0, s99
	v_mad_u32_u24 v80, v80, s100, v252
	v_mad_u32_u24 v83, v83, s100, v252
	v_mad_u32_u24 v99, v99, s100, v252
	v_mad_u32_u24 v253, v253, s100, v252
	v_mad_u32_u24 v254, v254, s100, v153
	v_mad_u32_u24 v255, v255, s100, v153
	global_load_dwordx4 v[156:159], v80, s[82:83]
	global_load_dwordx4 v[160:163], v83, s[82:83]
	global_load_dwordx4 v[164:167], v99, s[82:83]
	global_load_dwordx4 v[168:171], v253, s[82:83]
	global_load_dwordx4 v[172:175], v254, s[82:83] offset:768
	global_load_dwordx4 v[176:179], v255, s[82:83] offset:768
	global_load_dwordx4 v[180:183], v254, s[82:83] offset:832
	global_load_dwordx4 v[184:187], v255, s[82:83] offset:832
	ds_read2_b32 v[32:33], v115 offset0:102 offset1:103
	ds_read2_b32 v[34:35], v115 offset0:104 offset1:105
	ds_read2_b32 v[36:37], v115 offset0:110 offset1:111
	ds_read2_b32 v[38:39], v115 offset0:112 offset1:113
	ds_read2_b32 v[40:41], v115 offset0:119 offset1:120
	ds_read2_b32 v[42:43], v115 offset0:121 offset1:122
	ds_read2_b32 v[44:45], v115 offset0:127 offset1:128
	ds_read2_b32 v[46:47], v115 offset0:129 offset1:130
	s_waitcnt lgkmcnt(0)
	v_mfma_f32_32x32x16_bf16 v[32:47], v[188:191], v[48:51], v[32:47]
	ds_read_b64_tr_b16 v[72:73], v231
	ds_read_b64_tr_b16 v[74:75], v231 offset:512
	ds_read_b64_tr_b16 v[76:77], v231 offset:2048
	ds_read_b64_tr_b16 v[78:79], v231 offset:2560
	ds_read_b64_tr_b16 v[220:221], v231 offset:1024
	ds_read_b64_tr_b16 v[222:223], v231 offset:1536
	ds_read_b64_tr_b16 v[224:225], v231 offset:3072
	ds_read_b64_tr_b16 v[226:227], v231 offset:3584
	s_waitcnt vmcnt(8)
	ds_write_b128 v247, v[116:119]
	ds_write_b128 v247, v[120:123] offset:1024
	ds_write_b128 v247, v[124:127] offset:2048
	ds_write_b128 v247, v[128:131] offset:3072
	ds_read_b128 v[116:119], v248
	ds_read_b128 v[120:123], v249
	ds_read_b128 v[124:127], v250
	ds_read_b128 v[128:131], v251
	ds_write_b128 v112, v[132:135]
	ds_write_b128 v112, v[136:139] offset:1024
	ds_write_b128 v112, v[140:143] offset:2048
	ds_write_b128 v112, v[144:147] offset:3072
	v_mfma_f32_32x32x16_bf16 v[32:47], v[192:195], v[52:55], v[32:47]
	v_mfma_f32_32x32x16_bf16 v[32:47], v[196:199], v[56:59], v[32:47]
	v_mfma_f32_32x32x16_bf16 v[32:47], v[200:203], v[60:63], v[32:47]
	s_nop 11
	v_exp_f32_e32 v32, v32
	v_exp_f32_e32 v33, v33
	v_exp_f32_e32 v34, v34
	v_exp_f32_e32 v35, v35
	v_exp_f32_e32 v36, v36
	v_exp_f32_e32 v37, v37
	v_exp_f32_e32 v38, v38
	v_exp_f32_e32 v39, v39
	v_exp_f32_e32 v40, v40
	v_exp_f32_e32 v41, v41
	v_exp_f32_e32 v42, v42
	v_exp_f32_e32 v43, v43
	v_exp_f32_e32 v44, v44
	v_exp_f32_e32 v45, v45
	v_exp_f32_e32 v46, v46
	v_exp_f32_e32 v47, v47
	s_add_i32 s90, s67, 480
	v_add_u32_e32 v84, s90, v107
	v_add_u32_e32 v85, 0, v84
	v_add_u32_e32 v86, 1, v84
	v_add_u32_e32 v87, 2, v84
	v_add_u32_e32 v88, 3, v84
	v_cmp_gt_u32_e64 s[30:31], s98, v85
	v_cmp_gt_u32_e64 s[36:37], s98, v86
	v_cmp_gt_u32_e64 s[78:79], s98, v87
	v_cmp_gt_u32_e64 s[50:51], s98, v88
	v_cndmask_b32_e64 v32, 0, v32, s[30:31]
	v_add_u32_e32 v85, 8, v84
	v_cmp_gt_u32_e64 s[30:31], s98, v85
	v_cndmask_b32_e64 v33, 0, v33, s[36:37]
	v_add_u32_e32 v86, 9, v84
	v_cmp_gt_u32_e64 s[36:37], s98, v86
	v_cndmask_b32_e64 v34, 0, v34, s[78:79]
	v_add_u32_e32 v87, 10, v84
	v_cmp_gt_u32_e64 s[78:79], s98, v87
	v_cndmask_b32_e64 v35, 0, v35, s[50:51]
	v_add_u32_e32 v88, 11, v84
	v_cmp_gt_u32_e64 s[50:51], s98, v88
	v_cndmask_b32_e64 v36, 0, v36, s[30:31]
	v_add_u32_e32 v85, 16, v84
	v_cmp_gt_u32_e64 s[30:31], s98, v85
	v_cndmask_b32_e64 v37, 0, v37, s[36:37]
	v_add_u32_e32 v86, 17, v84
	v_cmp_gt_u32_e64 s[36:37], s98, v86
	v_cndmask_b32_e64 v38, 0, v38, s[78:79]
	v_add_u32_e32 v87, 18, v84
	v_cmp_gt_u32_e64 s[78:79], s98, v87
	v_cndmask_b32_e64 v39, 0, v39, s[50:51]
	v_add_u32_e32 v88, 19, v84
	v_cmp_gt_u32_e64 s[50:51], s98, v88
	v_cndmask_b32_e64 v40, 0, v40, s[30:31]
	v_add_u32_e32 v85, 24, v84
	v_cmp_gt_u32_e64 s[30:31], s98, v85
	v_cndmask_b32_e64 v41, 0, v41, s[36:37]
	v_add_u32_e32 v86, 25, v84
	v_cmp_gt_u32_e64 s[36:37], s98, v86
	v_cndmask_b32_e64 v42, 0, v42, s[78:79]
	v_add_u32_e32 v87, 26, v84
	v_cmp_gt_u32_e64 s[78:79], s98, v87
	v_cndmask_b32_e64 v43, 0, v43, s[50:51]
	v_add_u32_e32 v88, 27, v84
	v_cmp_gt_u32_e64 s[50:51], s98, v88
	v_nop
	v_cndmask_b32_e64 v44, 0, v44, s[30:31]
	v_cndmask_b32_e64 v45, 0, v45, s[36:37]
	v_cndmask_b32_e64 v46, 0, v46, s[78:79]
	v_cndmask_b32_e64 v47, 0, v47, s[50:51]
	v_cvt_pk_bf16_f32 v64, v32, v33
	v_cvt_pk_bf16_f32 v65, v34, v35
	v_cvt_pk_bf16_f32 v66, v36, v37
	v_cvt_pk_bf16_f32 v67, v38, v39
	v_cvt_pk_bf16_f32 v68, v40, v41
	v_cvt_pk_bf16_f32 v69, v42, v43
	v_cvt_pk_bf16_f32 v70, v44, v45
	v_cvt_pk_bf16_f32 v71, v46, v47
	v_pk_add_f32 v[232:233], v[232:233], v[32:33]
	v_pk_add_f32 v[232:233], v[232:233], v[34:35]
	v_pk_add_f32 v[232:233], v[232:233], v[36:37]
	v_pk_add_f32 v[232:233], v[232:233], v[38:39]
	v_pk_add_f32 v[232:233], v[232:233], v[40:41]
	v_pk_add_f32 v[232:233], v[232:233], v[42:43]
	v_pk_add_f32 v[232:233], v[232:233], v[44:45]
	v_pk_add_f32 v[232:233], v[232:233], v[46:47]
	s_waitcnt lgkmcnt(12)
	v_mfma_f32_32x32x16_bf16 v[0:15], v[64:67], v[72:75], v[0:15]
	v_mfma_f32_32x32x16_bf16 v[16:31], v[64:67], v[76:79], v[16:31]
	v_mfma_f32_32x32x16_bf16 v[0:15], v[68:71], v[220:223], v[0:15]
	v_mfma_f32_32x32x16_bf16 v[16:31], v[68:71], v[224:227], v[16:31]
	s_add_i32 s90, s67, -256
	v_add_u32_e32 v80, s90, v239
	v_add_u32_e32 v83, s90, v240
	v_add_u32_e32 v99, s90, v241
	v_add_u32_e32 v253, s90, v242
	v_add_u32_e32 v254, s90, v101
	v_add_u32_e32 v255, s90, v150
	v_med3_i32 v80, v80, 0, s99
	v_med3_i32 v83, v83, 0, s99
	v_med3_i32 v99, v99, 0, s99
	v_med3_i32 v253, v253, 0, s99
	v_med3_i32 v254, v254, 0, s99
	v_med3_i32 v255, v255, 0, s99
	v_mad_u32_u24 v80, v80, s100, v252
	v_mad_u32_u24 v83, v83, s100, v252
	v_mad_u32_u24 v99, v99, s100, v252
	v_mad_u32_u24 v253, v253, s100, v252
	v_mad_u32_u24 v254, v254, s100, v153
	v_mad_u32_u24 v255, v255, s100, v153
	global_load_dwordx4 v[188:191], v80, s[82:83]
	global_load_dwordx4 v[192:195], v83, s[82:83]
	global_load_dwordx4 v[196:199], v99, s[82:83]
	global_load_dwordx4 v[200:203], v253, s[82:83]
	global_load_dwordx4 v[204:207], v254, s[82:83] offset:768
	global_load_dwordx4 v[208:211], v255, s[82:83] offset:768
	global_load_dwordx4 v[212:215], v254, s[82:83] offset:832
	global_load_dwordx4 v[216:219], v255, s[82:83] offset:832
	ds_read2_b32 v[32:33], v115 offset0:136 offset1:137
	ds_read2_b32 v[34:35], v115 offset0:138 offset1:139
	ds_read2_b32 v[36:37], v115 offset0:144 offset1:145
	ds_read2_b32 v[38:39], v115 offset0:146 offset1:147
	ds_read2_b32 v[40:41], v115 offset0:153 offset1:154
	ds_read2_b32 v[42:43], v115 offset0:155 offset1:156
	ds_read2_b32 v[44:45], v115 offset0:161 offset1:162
	ds_read2_b32 v[46:47], v115 offset0:163 offset1:164
	s_waitcnt lgkmcnt(0)
	v_mfma_f32_32x32x16_bf16 v[32:47], v[116:119], v[48:51], v[32:47]
	ds_read_b64_tr_b16 v[72:73], v231
	ds_read_b64_tr_b16 v[74:75], v231 offset:512
	ds_read_b64_tr_b16 v[76:77], v231 offset:2048
	ds_read_b64_tr_b16 v[78:79], v231 offset:2560
	ds_read_b64_tr_b16 v[220:221], v231 offset:1024
	ds_read_b64_tr_b16 v[222:223], v231 offset:1536
	ds_read_b64_tr_b16 v[224:225], v231 offset:3072
	ds_read_b64_tr_b16 v[226:227], v231 offset:3584
	s_waitcnt vmcnt(8)
	ds_write_b128 v247, v[156:159]
	ds_write_b128 v247, v[160:163] offset:1024
	ds_write_b128 v247, v[164:167] offset:2048
	ds_write_b128 v247, v[168:171] offset:3072
	ds_read_b128 v[156:159], v248
	ds_read_b128 v[160:163], v249
	ds_read_b128 v[164:167], v250
	ds_read_b128 v[168:171], v251
	ds_write_b128 v112, v[172:175]
	ds_write_b128 v112, v[176:179] offset:1024
	ds_write_b128 v112, v[180:183] offset:2048
	ds_write_b128 v112, v[184:187] offset:3072
	v_mfma_f32_32x32x16_bf16 v[32:47], v[120:123], v[52:55], v[32:47]
	v_mfma_f32_32x32x16_bf16 v[32:47], v[124:127], v[56:59], v[32:47]
	v_mfma_f32_32x32x16_bf16 v[32:47], v[128:131], v[60:63], v[32:47]
	s_nop 11
	v_exp_f32_e32 v32, v32
	v_exp_f32_e32 v33, v33
	v_exp_f32_e32 v34, v34
	v_exp_f32_e32 v35, v35
	v_exp_f32_e32 v36, v36
	v_exp_f32_e32 v37, v37
	v_exp_f32_e32 v38, v38
	v_exp_f32_e32 v39, v39
	v_exp_f32_e32 v40, v40
	v_exp_f32_e32 v41, v41
	v_exp_f32_e32 v42, v42
	v_exp_f32_e32 v43, v43
	v_exp_f32_e32 v44, v44
	v_exp_f32_e32 v45, v45
	v_exp_f32_e32 v46, v46
	v_exp_f32_e32 v47, v47
	s_add_i32 s90, s67, 512
	v_add_u32_e32 v84, s90, v107
	v_add_u32_e32 v85, 0, v84
	v_add_u32_e32 v86, 1, v84
	v_add_u32_e32 v87, 2, v84
	v_add_u32_e32 v88, 3, v84
	v_cmp_gt_u32_e64 s[30:31], s98, v85
	v_cmp_gt_u32_e64 s[36:37], s98, v86
	v_cmp_gt_u32_e64 s[78:79], s98, v87
	v_cmp_gt_u32_e64 s[50:51], s98, v88
	v_cndmask_b32_e64 v32, 0, v32, s[30:31]
	v_add_u32_e32 v85, 8, v84
	v_cmp_gt_u32_e64 s[30:31], s98, v85
	v_cndmask_b32_e64 v33, 0, v33, s[36:37]
	v_add_u32_e32 v86, 9, v84
	v_cmp_gt_u32_e64 s[36:37], s98, v86
	v_cndmask_b32_e64 v34, 0, v34, s[78:79]
	v_add_u32_e32 v87, 10, v84
	v_cmp_gt_u32_e64 s[78:79], s98, v87
	v_cndmask_b32_e64 v35, 0, v35, s[50:51]
	v_add_u32_e32 v88, 11, v84
	v_cmp_gt_u32_e64 s[50:51], s98, v88
	v_cndmask_b32_e64 v36, 0, v36, s[30:31]
	v_add_u32_e32 v85, 16, v84
	v_cmp_gt_u32_e64 s[30:31], s98, v85
	v_cndmask_b32_e64 v37, 0, v37, s[36:37]
	v_add_u32_e32 v86, 17, v84
	v_cmp_gt_u32_e64 s[36:37], s98, v86
	v_cndmask_b32_e64 v38, 0, v38, s[78:79]
	v_add_u32_e32 v87, 18, v84
	v_cmp_gt_u32_e64 s[78:79], s98, v87
	v_cndmask_b32_e64 v39, 0, v39, s[50:51]
	v_add_u32_e32 v88, 19, v84
	v_cmp_gt_u32_e64 s[50:51], s98, v88
	v_cndmask_b32_e64 v40, 0, v40, s[30:31]
	v_add_u32_e32 v85, 24, v84
	v_cmp_gt_u32_e64 s[30:31], s98, v85
	v_cndmask_b32_e64 v41, 0, v41, s[36:37]
	v_add_u32_e32 v86, 25, v84
	v_cmp_gt_u32_e64 s[36:37], s98, v86
	v_cndmask_b32_e64 v42, 0, v42, s[78:79]
	v_add_u32_e32 v87, 26, v84
	v_cmp_gt_u32_e64 s[78:79], s98, v87
	v_cndmask_b32_e64 v43, 0, v43, s[50:51]
	v_add_u32_e32 v88, 27, v84
	v_cmp_gt_u32_e64 s[50:51], s98, v88
	v_nop
	v_cndmask_b32_e64 v44, 0, v44, s[30:31]
	v_cndmask_b32_e64 v45, 0, v45, s[36:37]
	v_cndmask_b32_e64 v46, 0, v46, s[78:79]
	v_cndmask_b32_e64 v47, 0, v47, s[50:51]
	v_cvt_pk_bf16_f32 v64, v32, v33
	v_cvt_pk_bf16_f32 v65, v34, v35
	v_cvt_pk_bf16_f32 v66, v36, v37
	v_cvt_pk_bf16_f32 v67, v38, v39
	v_cvt_pk_bf16_f32 v68, v40, v41
	v_cvt_pk_bf16_f32 v69, v42, v43
	v_cvt_pk_bf16_f32 v70, v44, v45
	v_cvt_pk_bf16_f32 v71, v46, v47
	v_pk_add_f32 v[232:233], v[232:233], v[32:33]
	v_pk_add_f32 v[232:233], v[232:233], v[34:35]
	v_pk_add_f32 v[232:233], v[232:233], v[36:37]
	v_pk_add_f32 v[232:233], v[232:233], v[38:39]
	v_pk_add_f32 v[232:233], v[232:233], v[40:41]
	v_pk_add_f32 v[232:233], v[232:233], v[42:43]
	v_pk_add_f32 v[232:233], v[232:233], v[44:45]
	v_pk_add_f32 v[232:233], v[232:233], v[46:47]
	s_waitcnt lgkmcnt(12)
	v_mfma_f32_32x32x16_bf16 v[0:15], v[64:67], v[72:75], v[0:15]
	v_mfma_f32_32x32x16_bf16 v[16:31], v[64:67], v[76:79], v[16:31]
	v_mfma_f32_32x32x16_bf16 v[0:15], v[68:71], v[220:223], v[0:15]
	v_mfma_f32_32x32x16_bf16 v[16:31], v[68:71], v[224:227], v[16:31]
	s_add_i32 s90, s67, -128
	v_add_u32_e32 v80, s90, v239
	v_add_u32_e32 v83, s90, v240
	v_add_u32_e32 v99, s90, v241
	v_add_u32_e32 v253, s90, v242
	v_add_u32_e32 v254, s90, v101
	v_add_u32_e32 v255, s90, v150
	v_med3_i32 v80, v80, 0, s99
	v_med3_i32 v83, v83, 0, s99
	v_med3_i32 v99, v99, 0, s99
	v_med3_i32 v253, v253, 0, s99
	v_med3_i32 v254, v254, 0, s99
	v_med3_i32 v255, v255, 0, s99
	v_mad_u32_u24 v80, v80, s100, v252
	v_mad_u32_u24 v83, v83, s100, v252
	v_mad_u32_u24 v99, v99, s100, v252
	v_mad_u32_u24 v253, v253, s100, v252
	v_mad_u32_u24 v254, v254, s100, v153
	v_mad_u32_u24 v255, v255, s100, v153
	global_load_dwordx4 v[116:119], v80, s[82:83]
	global_load_dwordx4 v[120:123], v83, s[82:83]
	global_load_dwordx4 v[124:127], v99, s[82:83]
	global_load_dwordx4 v[128:131], v253, s[82:83]
	global_load_dwordx4 v[132:135], v254, s[82:83] offset:768
	global_load_dwordx4 v[136:139], v255, s[82:83] offset:768
	global_load_dwordx4 v[140:143], v254, s[82:83] offset:832
	global_load_dwordx4 v[144:147], v255, s[82:83] offset:832
	ds_read2_b32 v[32:33], v115 offset0:170 offset1:171
	ds_read2_b32 v[34:35], v115 offset0:172 offset1:173
	ds_read2_b32 v[36:37], v115 offset0:178 offset1:179
	ds_read2_b32 v[38:39], v115 offset0:180 offset1:181
	ds_read2_b32 v[40:41], v115 offset0:187 offset1:188
	ds_read2_b32 v[42:43], v115 offset0:189 offset1:190
	ds_read2_b32 v[44:45], v115 offset0:195 offset1:196
	ds_read2_b32 v[46:47], v115 offset0:197 offset1:198
	s_waitcnt lgkmcnt(0)
	v_mfma_f32_32x32x16_bf16 v[32:47], v[156:159], v[48:51], v[32:47]
	ds_read_b64_tr_b16 v[72:73], v231
	ds_read_b64_tr_b16 v[74:75], v231 offset:512
	ds_read_b64_tr_b16 v[76:77], v231 offset:2048
	ds_read_b64_tr_b16 v[78:79], v231 offset:2560
	ds_read_b64_tr_b16 v[220:221], v231 offset:1024
	ds_read_b64_tr_b16 v[222:223], v231 offset:1536
	ds_read_b64_tr_b16 v[224:225], v231 offset:3072
	ds_read_b64_tr_b16 v[226:227], v231 offset:3584
	s_waitcnt vmcnt(8)
	ds_write_b128 v247, v[188:191]
	ds_write_b128 v247, v[192:195] offset:1024
	ds_write_b128 v247, v[196:199] offset:2048
	ds_write_b128 v247, v[200:203] offset:3072
	ds_read_b128 v[188:191], v248
	ds_read_b128 v[192:195], v249
	ds_read_b128 v[196:199], v250
	ds_read_b128 v[200:203], v251
	ds_write_b128 v112, v[204:207]
	ds_write_b128 v112, v[208:211] offset:1024
	ds_write_b128 v112, v[212:215] offset:2048
	ds_write_b128 v112, v[216:219] offset:3072
	v_mfma_f32_32x32x16_bf16 v[32:47], v[160:163], v[52:55], v[32:47]
	v_mfma_f32_32x32x16_bf16 v[32:47], v[164:167], v[56:59], v[32:47]
	v_mfma_f32_32x32x16_bf16 v[32:47], v[168:171], v[60:63], v[32:47]
	s_nop 11
	v_exp_f32_e32 v32, v32
	v_exp_f32_e32 v33, v33
	v_exp_f32_e32 v34, v34
	v_exp_f32_e32 v35, v35
	v_exp_f32_e32 v36, v36
	v_exp_f32_e32 v37, v37
	v_exp_f32_e32 v38, v38
	v_exp_f32_e32 v39, v39
	v_exp_f32_e32 v40, v40
	v_exp_f32_e32 v41, v41
	v_exp_f32_e32 v42, v42
	v_exp_f32_e32 v43, v43
	v_exp_f32_e32 v44, v44
	v_exp_f32_e32 v45, v45
	v_exp_f32_e32 v46, v46
	v_exp_f32_e32 v47, v47
	s_add_i32 s90, s67, 544
	v_add_u32_e32 v84, s90, v107
	v_add_u32_e32 v85, 0, v84
	v_add_u32_e32 v86, 1, v84
	v_add_u32_e32 v87, 2, v84
	v_add_u32_e32 v88, 3, v84
	v_cmp_gt_u32_e64 s[30:31], s98, v85
	v_cmp_gt_u32_e64 s[36:37], s98, v86
	v_cmp_gt_u32_e64 s[78:79], s98, v87
	v_cmp_gt_u32_e64 s[50:51], s98, v88
	v_cndmask_b32_e64 v32, 0, v32, s[30:31]
	v_add_u32_e32 v85, 8, v84
	v_cmp_gt_u32_e64 s[30:31], s98, v85
	v_cndmask_b32_e64 v33, 0, v33, s[36:37]
	v_add_u32_e32 v86, 9, v84
	v_cmp_gt_u32_e64 s[36:37], s98, v86
	v_cndmask_b32_e64 v34, 0, v34, s[78:79]
	v_add_u32_e32 v87, 10, v84
	v_cmp_gt_u32_e64 s[78:79], s98, v87
	v_cndmask_b32_e64 v35, 0, v35, s[50:51]
	v_add_u32_e32 v88, 11, v84
	v_cmp_gt_u32_e64 s[50:51], s98, v88
	v_cndmask_b32_e64 v36, 0, v36, s[30:31]
	v_add_u32_e32 v85, 16, v84
	v_cmp_gt_u32_e64 s[30:31], s98, v85
	v_cndmask_b32_e64 v37, 0, v37, s[36:37]
	v_add_u32_e32 v86, 17, v84
	v_cmp_gt_u32_e64 s[36:37], s98, v86
	v_cndmask_b32_e64 v38, 0, v38, s[78:79]
	v_add_u32_e32 v87, 18, v84
	v_cmp_gt_u32_e64 s[78:79], s98, v87
	v_cndmask_b32_e64 v39, 0, v39, s[50:51]
	v_add_u32_e32 v88, 19, v84
	v_cmp_gt_u32_e64 s[50:51], s98, v88
	v_cndmask_b32_e64 v40, 0, v40, s[30:31]
	v_add_u32_e32 v85, 24, v84
	v_cmp_gt_u32_e64 s[30:31], s98, v85
	v_cndmask_b32_e64 v41, 0, v41, s[36:37]
	v_add_u32_e32 v86, 25, v84
	v_cmp_gt_u32_e64 s[36:37], s98, v86
	v_cndmask_b32_e64 v42, 0, v42, s[78:79]
	v_add_u32_e32 v87, 26, v84
	v_cmp_gt_u32_e64 s[78:79], s98, v87
	v_cndmask_b32_e64 v43, 0, v43, s[50:51]
	v_add_u32_e32 v88, 27, v84
	v_cmp_gt_u32_e64 s[50:51], s98, v88
	v_nop
	v_cndmask_b32_e64 v44, 0, v44, s[30:31]
	v_cndmask_b32_e64 v45, 0, v45, s[36:37]
	v_cndmask_b32_e64 v46, 0, v46, s[78:79]
	v_cndmask_b32_e64 v47, 0, v47, s[50:51]
	v_cvt_pk_bf16_f32 v64, v32, v33
	v_cvt_pk_bf16_f32 v65, v34, v35
	v_cvt_pk_bf16_f32 v66, v36, v37
	v_cvt_pk_bf16_f32 v67, v38, v39
	v_cvt_pk_bf16_f32 v68, v40, v41
	v_cvt_pk_bf16_f32 v69, v42, v43
	v_cvt_pk_bf16_f32 v70, v44, v45
	v_cvt_pk_bf16_f32 v71, v46, v47
	v_pk_add_f32 v[232:233], v[232:233], v[32:33]
	v_pk_add_f32 v[232:233], v[232:233], v[34:35]
	v_pk_add_f32 v[232:233], v[232:233], v[36:37]
	v_pk_add_f32 v[232:233], v[232:233], v[38:39]
	v_pk_add_f32 v[232:233], v[232:233], v[40:41]
	v_pk_add_f32 v[232:233], v[232:233], v[42:43]
	v_pk_add_f32 v[232:233], v[232:233], v[44:45]
	v_pk_add_f32 v[232:233], v[232:233], v[46:47]
	s_waitcnt lgkmcnt(12)
	v_mfma_f32_32x32x16_bf16 v[0:15], v[64:67], v[72:75], v[0:15]
	v_mfma_f32_32x32x16_bf16 v[16:31], v[64:67], v[76:79], v[16:31]
	v_mfma_f32_32x32x16_bf16 v[0:15], v[68:71], v[220:223], v[0:15]
	v_mfma_f32_32x32x16_bf16 v[16:31], v[68:71], v[224:227], v[16:31]
	s_add_i32 s90, s67, 0
	v_add_u32_e32 v80, s90, v239
	v_add_u32_e32 v83, s90, v240
	v_add_u32_e32 v99, s90, v241
	v_add_u32_e32 v253, s90, v242
	v_add_u32_e32 v254, s90, v101
	v_add_u32_e32 v255, s90, v150
	v_med3_i32 v80, v80, 0, s99
	v_med3_i32 v83, v83, 0, s99
	v_med3_i32 v99, v99, 0, s99
	v_med3_i32 v253, v253, 0, s99
	v_med3_i32 v254, v254, 0, s99
	v_med3_i32 v255, v255, 0, s99
	v_mad_u32_u24 v80, v80, s100, v252
	v_mad_u32_u24 v83, v83, s100, v252
	v_mad_u32_u24 v99, v99, s100, v252
	v_mad_u32_u24 v253, v253, s100, v252
	v_mad_u32_u24 v254, v254, s100, v153
	v_mad_u32_u24 v255, v255, s100, v153
	global_load_dwordx4 v[156:159], v80, s[82:83]
	global_load_dwordx4 v[160:163], v83, s[82:83]
	global_load_dwordx4 v[164:167], v99, s[82:83]
	global_load_dwordx4 v[168:171], v253, s[82:83]
	global_load_dwordx4 v[172:175], v254, s[82:83] offset:768
	global_load_dwordx4 v[176:179], v255, s[82:83] offset:768
	global_load_dwordx4 v[180:183], v254, s[82:83] offset:832
	global_load_dwordx4 v[184:187], v255, s[82:83] offset:832
	v_mov_b32_e32 v115, v229
	ds_read2_b32 v[32:33], v115 offset0:0 offset1:1
	ds_read2_b32 v[34:35], v115 offset0:2 offset1:3
	ds_read2_b32 v[36:37], v115 offset0:10 offset1:11
	ds_read2_b32 v[38:39], v115 offset0:12 offset1:13
	ds_read2_b32 v[40:41], v115 offset0:20 offset1:21
	ds_read2_b32 v[42:43], v115 offset0:22 offset1:23
	ds_read2_b32 v[44:45], v115 offset0:30 offset1:31
	ds_read2_b32 v[46:47], v115 offset0:32 offset1:33
	s_waitcnt lgkmcnt(0)
	v_mfma_f32_32x32x16_bf16 v[32:47], v[188:191], v[48:51], v[32:47]
	ds_read_b64_tr_b16 v[72:73], v231
	ds_read_b64_tr_b16 v[74:75], v231 offset:512
	ds_read_b64_tr_b16 v[76:77], v231 offset:2048
	ds_read_b64_tr_b16 v[78:79], v231 offset:2560
	ds_read_b64_tr_b16 v[220:221], v231 offset:1024
	ds_read_b64_tr_b16 v[222:223], v231 offset:1536
	ds_read_b64_tr_b16 v[224:225], v231 offset:3072
	ds_read_b64_tr_b16 v[226:227], v231 offset:3584
	s_waitcnt vmcnt(8)
	ds_write_b128 v247, v[116:119]
	ds_write_b128 v247, v[120:123] offset:1024
	ds_write_b128 v247, v[124:127] offset:2048
	ds_write_b128 v247, v[128:131] offset:3072
	ds_read_b128 v[116:119], v248
	ds_read_b128 v[120:123], v249
	ds_read_b128 v[124:127], v250
	ds_read_b128 v[128:131], v251
	ds_write_b128 v112, v[132:135]
	ds_write_b128 v112, v[136:139] offset:1024
	ds_write_b128 v112, v[140:143] offset:2048
	ds_write_b128 v112, v[144:147] offset:3072
	v_mfma_f32_32x32x16_bf16 v[32:47], v[192:195], v[52:55], v[32:47]
	v_mfma_f32_32x32x16_bf16 v[32:47], v[196:199], v[56:59], v[32:47]
	v_mfma_f32_32x32x16_bf16 v[32:47], v[200:203], v[60:63], v[32:47]
	s_nop 11
	v_exp_f32_e32 v32, v32
	v_exp_f32_e32 v33, v33
	v_exp_f32_e32 v34, v34
	v_exp_f32_e32 v35, v35
	v_exp_f32_e32 v36, v36
	v_exp_f32_e32 v37, v37
	v_exp_f32_e32 v38, v38
	v_exp_f32_e32 v39, v39
	v_exp_f32_e32 v40, v40
	v_exp_f32_e32 v41, v41
	v_exp_f32_e32 v42, v42
	v_exp_f32_e32 v43, v43
	v_exp_f32_e32 v44, v44
	v_exp_f32_e32 v45, v45
	v_exp_f32_e32 v46, v46
	v_exp_f32_e32 v47, v47
	s_add_i32 s90, s67, -256
	v_lshlrev_b32_e32 v84, 2, v107
	v_add_u32_e32 v84, s90, v84
	v_add_u32_e32 v85, 0, v84
	v_add_u32_e32 v86, 4, v84
	v_add_u32_e32 v87, 8, v84
	v_add_u32_e32 v88, 12, v84
	v_cmp_gt_u32_e64 s[30:31], s98, v85
	v_cmp_gt_u32_e64 s[36:37], s98, v86
	v_cmp_gt_u32_e64 s[78:79], s98, v87
	v_cmp_gt_u32_e64 s[50:51], s98, v88
	v_cndmask_b32_e64 v32, 0, v32, s[30:31]
	v_add_u32_e32 v85, 32, v84
	v_cmp_gt_u32_e64 s[30:31], s98, v85
	v_cndmask_b32_e64 v33, 0, v33, s[36:37]
	v_add_u32_e32 v86, 36, v84
	v_cmp_gt_u32_e64 s[36:37], s98, v86
	v_cndmask_b32_e64 v34, 0, v34, s[78:79]
	v_add_u32_e32 v87, 40, v84
	v_cmp_gt_u32_e64 s[78:79], s98, v87
	v_cndmask_b32_e64 v35, 0, v35, s[50:51]
	v_add_u32_e32 v88, 44, v84
	v_cmp_gt_u32_e64 s[50:51], s98, v88
	v_cndmask_b32_e64 v36, 0, v36, s[30:31]
	v_add_u32_e32 v85, 64, v84
	v_cmp_gt_u32_e64 s[30:31], s98, v85
	v_cndmask_b32_e64 v37, 0, v37, s[36:37]
	v_add_u32_e32 v86, 68, v84
	v_cmp_gt_u32_e64 s[36:37], s98, v86
	v_cndmask_b32_e64 v38, 0, v38, s[78:79]
	v_add_u32_e32 v87, 72, v84
	v_cmp_gt_u32_e64 s[78:79], s98, v87
	v_cndmask_b32_e64 v39, 0, v39, s[50:51]
	v_add_u32_e32 v88, 76, v84
	v_cmp_gt_u32_e64 s[50:51], s98, v88
	v_cndmask_b32_e64 v40, 0, v40, s[30:31]
	v_add_u32_e32 v85, 96, v84
	v_cmp_gt_u32_e64 s[30:31], s98, v85
	v_cndmask_b32_e64 v41, 0, v41, s[36:37]
	v_add_u32_e32 v86, 100, v84
	v_cmp_gt_u32_e64 s[36:37], s98, v86
	v_cndmask_b32_e64 v42, 0, v42, s[78:79]
	v_add_u32_e32 v87, 104, v84
	v_cmp_gt_u32_e64 s[78:79], s98, v87
	v_cndmask_b32_e64 v43, 0, v43, s[50:51]
	v_add_u32_e32 v88, 108, v84
	v_cmp_gt_u32_e64 s[50:51], s98, v88
	v_nop
	v_cndmask_b32_e64 v44, 0, v44, s[30:31]
	v_cndmask_b32_e64 v45, 0, v45, s[36:37]
	v_cndmask_b32_e64 v46, 0, v46, s[78:79]
	v_cndmask_b32_e64 v47, 0, v47, s[50:51]
	v_cvt_pk_bf16_f32 v64, v32, v33
	v_cvt_pk_bf16_f32 v65, v34, v35
	v_cvt_pk_bf16_f32 v66, v36, v37
	v_cvt_pk_bf16_f32 v67, v38, v39
	v_cvt_pk_bf16_f32 v68, v40, v41
	v_cvt_pk_bf16_f32 v69, v42, v43
	v_cvt_pk_bf16_f32 v70, v44, v45
	v_cvt_pk_bf16_f32 v71, v46, v47
	v_pk_add_f32 v[232:233], v[232:233], v[32:33]
	v_pk_add_f32 v[232:233], v[232:233], v[34:35]
	v_pk_add_f32 v[232:233], v[232:233], v[36:37]
	v_pk_add_f32 v[232:233], v[232:233], v[38:39]
	v_pk_add_f32 v[232:233], v[232:233], v[40:41]
	v_pk_add_f32 v[232:233], v[232:233], v[42:43]
	v_pk_add_f32 v[232:233], v[232:233], v[44:45]
	v_pk_add_f32 v[232:233], v[232:233], v[46:47]
	s_waitcnt lgkmcnt(12)
	v_mfma_f32_32x32x16_bf16 v[0:15], v[64:67], v[72:75], v[0:15]
	v_mfma_f32_32x32x16_bf16 v[16:31], v[64:67], v[76:79], v[16:31]
	v_mfma_f32_32x32x16_bf16 v[0:15], v[68:71], v[220:223], v[0:15]
	v_mfma_f32_32x32x16_bf16 v[16:31], v[68:71], v[224:227], v[16:31]
	s_add_i32 s90, s67, 128
	v_add_u32_e32 v80, s90, v239
	v_add_u32_e32 v83, s90, v240
	v_add_u32_e32 v99, s90, v241
	v_add_u32_e32 v253, s90, v242
	v_add_u32_e32 v254, s90, v101
	v_add_u32_e32 v255, s90, v150
	v_med3_i32 v80, v80, 0, s99
	v_med3_i32 v83, v83, 0, s99
	v_med3_i32 v99, v99, 0, s99
	v_med3_i32 v253, v253, 0, s99
	v_med3_i32 v254, v254, 0, s99
	v_med3_i32 v255, v255, 0, s99
	v_mad_u32_u24 v80, v80, s100, v252
	v_mad_u32_u24 v83, v83, s100, v252
	v_mad_u32_u24 v99, v99, s100, v252
	v_mad_u32_u24 v253, v253, s100, v252
	v_mad_u32_u24 v254, v254, s100, v153
	v_mad_u32_u24 v255, v255, s100, v153
	global_load_dwordx4 v[188:191], v80, s[82:83]
	global_load_dwordx4 v[192:195], v83, s[82:83]
	global_load_dwordx4 v[196:199], v99, s[82:83]
	global_load_dwordx4 v[200:203], v253, s[82:83]
	global_load_dwordx4 v[204:207], v254, s[82:83] offset:768
	global_load_dwordx4 v[208:211], v255, s[82:83] offset:768
	global_load_dwordx4 v[212:215], v254, s[82:83] offset:832
	global_load_dwordx4 v[216:219], v255, s[82:83] offset:832
	ds_read2_b32 v[32:33], v115 offset0:40 offset1:41
	ds_read2_b32 v[34:35], v115 offset0:42 offset1:43
	ds_read2_b32 v[36:37], v115 offset0:50 offset1:51
	ds_read2_b32 v[38:39], v115 offset0:52 offset1:53
	ds_read2_b32 v[40:41], v115 offset0:60 offset1:61
	ds_read2_b32 v[42:43], v115 offset0:62 offset1:63
	ds_read2_b32 v[44:45], v115 offset0:70 offset1:71
	ds_read2_b32 v[46:47], v115 offset0:72 offset1:73
	s_waitcnt lgkmcnt(0)
	v_mfma_f32_32x32x16_bf16 v[32:47], v[116:119], v[48:51], v[32:47]
	ds_read_b64_tr_b16 v[72:73], v231
	ds_read_b64_tr_b16 v[74:75], v231 offset:512
	ds_read_b64_tr_b16 v[76:77], v231 offset:2048
	ds_read_b64_tr_b16 v[78:79], v231 offset:2560
	ds_read_b64_tr_b16 v[220:221], v231 offset:1024
	ds_read_b64_tr_b16 v[222:223], v231 offset:1536
	ds_read_b64_tr_b16 v[224:225], v231 offset:3072
	ds_read_b64_tr_b16 v[226:227], v231 offset:3584
	s_waitcnt vmcnt(8)
	ds_write_b128 v247, v[156:159]
	ds_write_b128 v247, v[160:163] offset:1024
	ds_write_b128 v247, v[164:167] offset:2048
	ds_write_b128 v247, v[168:171] offset:3072
	ds_read_b128 v[156:159], v248
	ds_read_b128 v[160:163], v249
	ds_read_b128 v[164:167], v250
	ds_read_b128 v[168:171], v251
	ds_write_b128 v112, v[172:175]
	ds_write_b128 v112, v[176:179] offset:1024
	ds_write_b128 v112, v[180:183] offset:2048
	ds_write_b128 v112, v[184:187] offset:3072
	v_mfma_f32_32x32x16_bf16 v[32:47], v[120:123], v[52:55], v[32:47]
	v_mfma_f32_32x32x16_bf16 v[32:47], v[124:127], v[56:59], v[32:47]
	v_mfma_f32_32x32x16_bf16 v[32:47], v[128:131], v[60:63], v[32:47]
	s_nop 11
	v_exp_f32_e32 v32, v32
	v_exp_f32_e32 v33, v33
	v_exp_f32_e32 v34, v34
	v_exp_f32_e32 v35, v35
	v_exp_f32_e32 v36, v36
	v_exp_f32_e32 v37, v37
	v_exp_f32_e32 v38, v38
	v_exp_f32_e32 v39, v39
	v_exp_f32_e32 v40, v40
	v_exp_f32_e32 v41, v41
	v_exp_f32_e32 v42, v42
	v_exp_f32_e32 v43, v43
	v_exp_f32_e32 v44, v44
	v_exp_f32_e32 v45, v45
	v_exp_f32_e32 v46, v46
	v_exp_f32_e32 v47, v47
	s_add_i32 s90, s67, -128
	v_lshlrev_b32_e32 v84, 2, v107
	v_add_u32_e32 v84, s90, v84
	v_add_u32_e32 v85, 0, v84
	v_add_u32_e32 v86, 4, v84
	v_add_u32_e32 v87, 8, v84
	v_add_u32_e32 v88, 12, v84
	v_cmp_gt_u32_e64 s[30:31], s98, v85
	v_cmp_gt_u32_e64 s[36:37], s98, v86
	v_cmp_gt_u32_e64 s[78:79], s98, v87
	v_cmp_gt_u32_e64 s[50:51], s98, v88
	v_cndmask_b32_e64 v32, 0, v32, s[30:31]
	v_add_u32_e32 v85, 32, v84
	v_cmp_gt_u32_e64 s[30:31], s98, v85
	v_cndmask_b32_e64 v33, 0, v33, s[36:37]
	v_add_u32_e32 v86, 36, v84
	v_cmp_gt_u32_e64 s[36:37], s98, v86
	v_cndmask_b32_e64 v34, 0, v34, s[78:79]
	v_add_u32_e32 v87, 40, v84
	v_cmp_gt_u32_e64 s[78:79], s98, v87
	v_cndmask_b32_e64 v35, 0, v35, s[50:51]
	v_add_u32_e32 v88, 44, v84
	v_cmp_gt_u32_e64 s[50:51], s98, v88
	v_cndmask_b32_e64 v36, 0, v36, s[30:31]
	v_add_u32_e32 v85, 64, v84
	v_cmp_gt_u32_e64 s[30:31], s98, v85
	v_cndmask_b32_e64 v37, 0, v37, s[36:37]
	v_add_u32_e32 v86, 68, v84
	v_cmp_gt_u32_e64 s[36:37], s98, v86
	v_cndmask_b32_e64 v38, 0, v38, s[78:79]
	v_add_u32_e32 v87, 72, v84
	v_cmp_gt_u32_e64 s[78:79], s98, v87
	v_cndmask_b32_e64 v39, 0, v39, s[50:51]
	v_add_u32_e32 v88, 76, v84
	v_cmp_gt_u32_e64 s[50:51], s98, v88
	v_cndmask_b32_e64 v40, 0, v40, s[30:31]
	v_add_u32_e32 v85, 96, v84
	v_cmp_gt_u32_e64 s[30:31], s98, v85
	v_cndmask_b32_e64 v41, 0, v41, s[36:37]
	v_add_u32_e32 v86, 100, v84
	v_cmp_gt_u32_e64 s[36:37], s98, v86
	v_cndmask_b32_e64 v42, 0, v42, s[78:79]
	v_add_u32_e32 v87, 104, v84
	v_cmp_gt_u32_e64 s[78:79], s98, v87
	v_cndmask_b32_e64 v43, 0, v43, s[50:51]
	v_add_u32_e32 v88, 108, v84
	v_cmp_gt_u32_e64 s[50:51], s98, v88
	v_nop
	v_cndmask_b32_e64 v44, 0, v44, s[30:31]
	v_cndmask_b32_e64 v45, 0, v45, s[36:37]
	v_cndmask_b32_e64 v46, 0, v46, s[78:79]
	v_cndmask_b32_e64 v47, 0, v47, s[50:51]
	v_cvt_pk_bf16_f32 v64, v32, v33
	v_cvt_pk_bf16_f32 v65, v34, v35
	v_cvt_pk_bf16_f32 v66, v36, v37
	v_cvt_pk_bf16_f32 v67, v38, v39
	v_cvt_pk_bf16_f32 v68, v40, v41
	v_cvt_pk_bf16_f32 v69, v42, v43
	v_cvt_pk_bf16_f32 v70, v44, v45
	v_cvt_pk_bf16_f32 v71, v46, v47
	v_pk_add_f32 v[232:233], v[232:233], v[32:33]
	v_pk_add_f32 v[232:233], v[232:233], v[34:35]
	v_pk_add_f32 v[232:233], v[232:233], v[36:37]
	v_pk_add_f32 v[232:233], v[232:233], v[38:39]
	v_pk_add_f32 v[232:233], v[232:233], v[40:41]
	v_pk_add_f32 v[232:233], v[232:233], v[42:43]
	v_pk_add_f32 v[232:233], v[232:233], v[44:45]
	v_pk_add_f32 v[232:233], v[232:233], v[46:47]
	s_waitcnt lgkmcnt(12)
	v_mfma_f32_32x32x16_bf16 v[0:15], v[64:67], v[72:75], v[0:15]
	v_mfma_f32_32x32x16_bf16 v[16:31], v[64:67], v[76:79], v[16:31]
	v_mfma_f32_32x32x16_bf16 v[0:15], v[68:71], v[220:223], v[0:15]
	v_mfma_f32_32x32x16_bf16 v[16:31], v[68:71], v[224:227], v[16:31]
	s_add_i32 s90, s67, 256
	v_add_u32_e32 v80, s90, v239
	v_add_u32_e32 v83, s90, v240
	v_add_u32_e32 v99, s90, v241
	v_add_u32_e32 v253, s90, v242
	v_add_u32_e32 v254, s90, v101
	v_add_u32_e32 v255, s90, v150
	v_med3_i32 v80, v80, 0, s99
	v_med3_i32 v83, v83, 0, s99
	v_med3_i32 v99, v99, 0, s99
	v_med3_i32 v253, v253, 0, s99
	v_med3_i32 v254, v254, 0, s99
	v_med3_i32 v255, v255, 0, s99
	v_mad_u32_u24 v80, v80, s100, v252
	v_mad_u32_u24 v83, v83, s100, v252
	v_mad_u32_u24 v99, v99, s100, v252
	v_mad_u32_u24 v253, v253, s100, v252
	v_mad_u32_u24 v254, v254, s100, v153
	v_mad_u32_u24 v255, v255, s100, v153
	global_load_dwordx4 v[116:119], v80, s[82:83]
	global_load_dwordx4 v[120:123], v83, s[82:83]
	global_load_dwordx4 v[124:127], v99, s[82:83]
	global_load_dwordx4 v[128:131], v253, s[82:83]
	global_load_dwordx4 v[132:135], v254, s[82:83] offset:768
	global_load_dwordx4 v[136:139], v255, s[82:83] offset:768
	global_load_dwordx4 v[140:143], v254, s[82:83] offset:832
	global_load_dwordx4 v[144:147], v255, s[82:83] offset:832
	ds_read2_b32 v[32:33], v115 offset0:80 offset1:81
	ds_read2_b32 v[34:35], v115 offset0:82 offset1:83
	ds_read2_b32 v[36:37], v115 offset0:90 offset1:91
	ds_read2_b32 v[38:39], v115 offset0:92 offset1:93
	ds_read2_b32 v[40:41], v115 offset0:100 offset1:101
	ds_read2_b32 v[42:43], v115 offset0:102 offset1:103
	ds_read2_b32 v[44:45], v115 offset0:110 offset1:111
	ds_read2_b32 v[46:47], v115 offset0:112 offset1:113
	s_waitcnt lgkmcnt(0)
	v_mfma_f32_32x32x16_bf16 v[32:47], v[156:159], v[48:51], v[32:47]
	ds_read_b64_tr_b16 v[72:73], v231
	ds_read_b64_tr_b16 v[74:75], v231 offset:512
	ds_read_b64_tr_b16 v[76:77], v231 offset:2048
	ds_read_b64_tr_b16 v[78:79], v231 offset:2560
	ds_read_b64_tr_b16 v[220:221], v231 offset:1024
	ds_read_b64_tr_b16 v[222:223], v231 offset:1536
	ds_read_b64_tr_b16 v[224:225], v231 offset:3072
	ds_read_b64_tr_b16 v[226:227], v231 offset:3584
	s_waitcnt vmcnt(8)
	ds_write_b128 v247, v[188:191]
	ds_write_b128 v247, v[192:195] offset:1024
	ds_write_b128 v247, v[196:199] offset:2048
	ds_write_b128 v247, v[200:203] offset:3072
	ds_read_b128 v[188:191], v248
	ds_read_b128 v[192:195], v249
	ds_read_b128 v[196:199], v250
	ds_read_b128 v[200:203], v251
	ds_write_b128 v112, v[204:207]
	ds_write_b128 v112, v[208:211] offset:1024
	ds_write_b128 v112, v[212:215] offset:2048
	ds_write_b128 v112, v[216:219] offset:3072
	v_mfma_f32_32x32x16_bf16 v[32:47], v[160:163], v[52:55], v[32:47]
	v_mfma_f32_32x32x16_bf16 v[32:47], v[164:167], v[56:59], v[32:47]
	v_mfma_f32_32x32x16_bf16 v[32:47], v[168:171], v[60:63], v[32:47]
	s_nop 11
	v_exp_f32_e32 v32, v32
	v_exp_f32_e32 v33, v33
	v_exp_f32_e32 v34, v34
	v_exp_f32_e32 v35, v35
	v_exp_f32_e32 v36, v36
	v_exp_f32_e32 v37, v37
	v_exp_f32_e32 v38, v38
	v_exp_f32_e32 v39, v39
	v_exp_f32_e32 v40, v40
	v_exp_f32_e32 v41, v41
	v_exp_f32_e32 v42, v42
	v_exp_f32_e32 v43, v43
	v_exp_f32_e32 v44, v44
	v_exp_f32_e32 v45, v45
	v_exp_f32_e32 v46, v46
	v_exp_f32_e32 v47, v47
	s_add_i32 s90, s67, 0
	v_lshlrev_b32_e32 v84, 2, v107
	v_add_u32_e32 v84, s90, v84
	v_add_u32_e32 v85, 0, v84
	v_add_u32_e32 v86, 4, v84
	v_add_u32_e32 v87, 8, v84
	v_add_u32_e32 v88, 12, v84
	v_cmp_gt_u32_e64 s[30:31], s98, v85
	v_cmp_gt_u32_e64 s[36:37], s98, v86
	v_cmp_gt_u32_e64 s[78:79], s98, v87
	v_cmp_gt_u32_e64 s[50:51], s98, v88
	v_cndmask_b32_e64 v32, 0, v32, s[30:31]
	v_add_u32_e32 v85, 32, v84
	v_cmp_gt_u32_e64 s[30:31], s98, v85
	v_cndmask_b32_e64 v33, 0, v33, s[36:37]
	v_add_u32_e32 v86, 36, v84
	v_cmp_gt_u32_e64 s[36:37], s98, v86
	v_cndmask_b32_e64 v34, 0, v34, s[78:79]
	v_add_u32_e32 v87, 40, v84
	v_cmp_gt_u32_e64 s[78:79], s98, v87
	v_cndmask_b32_e64 v35, 0, v35, s[50:51]
	v_add_u32_e32 v88, 44, v84
	v_cmp_gt_u32_e64 s[50:51], s98, v88
	v_cndmask_b32_e64 v36, 0, v36, s[30:31]
	v_add_u32_e32 v85, 64, v84
	v_cmp_gt_u32_e64 s[30:31], s98, v85
	v_cndmask_b32_e64 v37, 0, v37, s[36:37]
	v_add_u32_e32 v86, 68, v84
	v_cmp_gt_u32_e64 s[36:37], s98, v86
	v_cndmask_b32_e64 v38, 0, v38, s[78:79]
	v_add_u32_e32 v87, 72, v84
	v_cmp_gt_u32_e64 s[78:79], s98, v87
	v_cndmask_b32_e64 v39, 0, v39, s[50:51]
	v_add_u32_e32 v88, 76, v84
	v_cmp_gt_u32_e64 s[50:51], s98, v88
	v_cndmask_b32_e64 v40, 0, v40, s[30:31]
	v_add_u32_e32 v85, 96, v84
	v_cmp_gt_u32_e64 s[30:31], s98, v85
	v_cndmask_b32_e64 v41, 0, v41, s[36:37]
	v_add_u32_e32 v86, 100, v84
	v_cmp_gt_u32_e64 s[36:37], s98, v86
	v_cndmask_b32_e64 v42, 0, v42, s[78:79]
	v_add_u32_e32 v87, 104, v84
	v_cmp_gt_u32_e64 s[78:79], s98, v87
	v_cndmask_b32_e64 v43, 0, v43, s[50:51]
	v_add_u32_e32 v88, 108, v84
	v_cmp_gt_u32_e64 s[50:51], s98, v88
	v_nop
	v_cndmask_b32_e64 v44, 0, v44, s[30:31]
	v_cndmask_b32_e64 v45, 0, v45, s[36:37]
	v_cndmask_b32_e64 v46, 0, v46, s[78:79]
	v_cndmask_b32_e64 v47, 0, v47, s[50:51]
	v_cvt_pk_bf16_f32 v64, v32, v33
	v_cvt_pk_bf16_f32 v65, v34, v35
	v_cvt_pk_bf16_f32 v66, v36, v37
	v_cvt_pk_bf16_f32 v67, v38, v39
	v_cvt_pk_bf16_f32 v68, v40, v41
	v_cvt_pk_bf16_f32 v69, v42, v43
	v_cvt_pk_bf16_f32 v70, v44, v45
	v_cvt_pk_bf16_f32 v71, v46, v47
	v_pk_add_f32 v[232:233], v[232:233], v[32:33]
	v_pk_add_f32 v[232:233], v[232:233], v[34:35]
	v_pk_add_f32 v[232:233], v[232:233], v[36:37]
	v_pk_add_f32 v[232:233], v[232:233], v[38:39]
	v_pk_add_f32 v[232:233], v[232:233], v[40:41]
	v_pk_add_f32 v[232:233], v[232:233], v[42:43]
	v_pk_add_f32 v[232:233], v[232:233], v[44:45]
	v_pk_add_f32 v[232:233], v[232:233], v[46:47]
	s_waitcnt lgkmcnt(12)
	v_mfma_f32_32x32x16_bf16 v[0:15], v[64:67], v[72:75], v[0:15]
	v_mfma_f32_32x32x16_bf16 v[16:31], v[64:67], v[76:79], v[16:31]
	v_mfma_f32_32x32x16_bf16 v[0:15], v[68:71], v[220:223], v[0:15]
	v_mfma_f32_32x32x16_bf16 v[16:31], v[68:71], v[224:227], v[16:31]
	s_add_i32 s90, s67, 384
	v_add_u32_e32 v80, s90, v239
	v_add_u32_e32 v83, s90, v240
	v_add_u32_e32 v99, s90, v241
	v_add_u32_e32 v253, s90, v242
	v_add_u32_e32 v254, s90, v101
	v_add_u32_e32 v255, s90, v150
	v_med3_i32 v80, v80, 0, s99
	v_med3_i32 v83, v83, 0, s99
	v_med3_i32 v99, v99, 0, s99
	v_med3_i32 v253, v253, 0, s99
	v_med3_i32 v254, v254, 0, s99
	v_med3_i32 v255, v255, 0, s99
	v_mad_u32_u24 v80, v80, s100, v252
	v_mad_u32_u24 v83, v83, s100, v252
	v_mad_u32_u24 v99, v99, s100, v252
	v_mad_u32_u24 v253, v253, s100, v252
	v_mad_u32_u24 v254, v254, s100, v153
	v_mad_u32_u24 v255, v255, s100, v153
	global_load_dwordx4 v[156:159], v80, s[82:83]
	global_load_dwordx4 v[160:163], v83, s[82:83]
	global_load_dwordx4 v[164:167], v99, s[82:83]
	global_load_dwordx4 v[168:171], v253, s[82:83]
	global_load_dwordx4 v[172:175], v254, s[82:83] offset:768
	global_load_dwordx4 v[176:179], v255, s[82:83] offset:768
	global_load_dwordx4 v[180:183], v254, s[82:83] offset:832
	global_load_dwordx4 v[184:187], v255, s[82:83] offset:832
	ds_read2_b32 v[32:33], v115 offset0:120 offset1:121
	ds_read2_b32 v[34:35], v115 offset0:122 offset1:123
	ds_read2_b32 v[36:37], v115 offset0:130 offset1:131
	ds_read2_b32 v[38:39], v115 offset0:132 offset1:133
	ds_read2_b32 v[40:41], v115 offset0:140 offset1:141
	ds_read2_b32 v[42:43], v115 offset0:142 offset1:143
	ds_read2_b32 v[44:45], v115 offset0:150 offset1:151
	ds_read2_b32 v[46:47], v115 offset0:152 offset1:153
	s_waitcnt lgkmcnt(0)
	v_mfma_f32_32x32x16_bf16 v[32:47], v[188:191], v[48:51], v[32:47]
	ds_read_b64_tr_b16 v[72:73], v231
	ds_read_b64_tr_b16 v[74:75], v231 offset:512
	ds_read_b64_tr_b16 v[76:77], v231 offset:2048
	ds_read_b64_tr_b16 v[78:79], v231 offset:2560
	ds_read_b64_tr_b16 v[220:221], v231 offset:1024
	ds_read_b64_tr_b16 v[222:223], v231 offset:1536
	ds_read_b64_tr_b16 v[224:225], v231 offset:3072
	ds_read_b64_tr_b16 v[226:227], v231 offset:3584
	s_waitcnt vmcnt(8)
	ds_write_b128 v247, v[116:119]
	ds_write_b128 v247, v[120:123] offset:1024
	ds_write_b128 v247, v[124:127] offset:2048
	ds_write_b128 v247, v[128:131] offset:3072
	ds_read_b128 v[116:119], v248
	ds_read_b128 v[120:123], v249
	ds_read_b128 v[124:127], v250
	ds_read_b128 v[128:131], v251
	ds_write_b128 v112, v[132:135]
	ds_write_b128 v112, v[136:139] offset:1024
	ds_write_b128 v112, v[140:143] offset:2048
	ds_write_b128 v112, v[144:147] offset:3072
	v_mfma_f32_32x32x16_bf16 v[32:47], v[192:195], v[52:55], v[32:47]
	v_mfma_f32_32x32x16_bf16 v[32:47], v[196:199], v[56:59], v[32:47]
	v_mfma_f32_32x32x16_bf16 v[32:47], v[200:203], v[60:63], v[32:47]
	s_nop 11
	v_exp_f32_e32 v32, v32
	v_exp_f32_e32 v33, v33
	v_exp_f32_e32 v34, v34
	v_exp_f32_e32 v35, v35
	v_exp_f32_e32 v36, v36
	v_exp_f32_e32 v37, v37
	v_exp_f32_e32 v38, v38
	v_exp_f32_e32 v39, v39
	v_exp_f32_e32 v40, v40
	v_exp_f32_e32 v41, v41
	v_exp_f32_e32 v42, v42
	v_exp_f32_e32 v43, v43
	v_exp_f32_e32 v44, v44
	v_exp_f32_e32 v45, v45
	v_exp_f32_e32 v46, v46
	v_exp_f32_e32 v47, v47
	s_add_i32 s90, s67, 128
	v_lshlrev_b32_e32 v84, 2, v107
	v_add_u32_e32 v84, s90, v84
	v_add_u32_e32 v85, 0, v84
	v_add_u32_e32 v86, 4, v84
	v_add_u32_e32 v87, 8, v84
	v_add_u32_e32 v88, 12, v84
	v_cmp_gt_u32_e64 s[30:31], s98, v85
	v_cmp_gt_u32_e64 s[36:37], s98, v86
	v_cmp_gt_u32_e64 s[78:79], s98, v87
	v_cmp_gt_u32_e64 s[50:51], s98, v88
	v_cndmask_b32_e64 v32, 0, v32, s[30:31]
	v_add_u32_e32 v85, 32, v84
	v_cmp_gt_u32_e64 s[30:31], s98, v85
	v_cndmask_b32_e64 v33, 0, v33, s[36:37]
	v_add_u32_e32 v86, 36, v84
	v_cmp_gt_u32_e64 s[36:37], s98, v86
	v_cndmask_b32_e64 v34, 0, v34, s[78:79]
	v_add_u32_e32 v87, 40, v84
	v_cmp_gt_u32_e64 s[78:79], s98, v87
	v_cndmask_b32_e64 v35, 0, v35, s[50:51]
	v_add_u32_e32 v88, 44, v84
	v_cmp_gt_u32_e64 s[50:51], s98, v88
	v_cndmask_b32_e64 v36, 0, v36, s[30:31]
	v_add_u32_e32 v85, 64, v84
	v_cmp_gt_u32_e64 s[30:31], s98, v85
	v_cndmask_b32_e64 v37, 0, v37, s[36:37]
	v_add_u32_e32 v86, 68, v84
	v_cmp_gt_u32_e64 s[36:37], s98, v86
	v_cndmask_b32_e64 v38, 0, v38, s[78:79]
	v_add_u32_e32 v87, 72, v84
	v_cmp_gt_u32_e64 s[78:79], s98, v87
	v_cndmask_b32_e64 v39, 0, v39, s[50:51]
	v_add_u32_e32 v88, 76, v84
	v_cmp_gt_u32_e64 s[50:51], s98, v88
	v_cndmask_b32_e64 v40, 0, v40, s[30:31]
	v_add_u32_e32 v85, 96, v84
	v_cmp_gt_u32_e64 s[30:31], s98, v85
	v_cndmask_b32_e64 v41, 0, v41, s[36:37]
	v_add_u32_e32 v86, 100, v84
	v_cmp_gt_u32_e64 s[36:37], s98, v86
	v_cndmask_b32_e64 v42, 0, v42, s[78:79]
	v_add_u32_e32 v87, 104, v84
	v_cmp_gt_u32_e64 s[78:79], s98, v87
	v_cndmask_b32_e64 v43, 0, v43, s[50:51]
	v_add_u32_e32 v88, 108, v84
	v_cmp_gt_u32_e64 s[50:51], s98, v88
	v_nop
	v_cndmask_b32_e64 v44, 0, v44, s[30:31]
	v_cndmask_b32_e64 v45, 0, v45, s[36:37]
	v_cndmask_b32_e64 v46, 0, v46, s[78:79]
	v_cndmask_b32_e64 v47, 0, v47, s[50:51]
	v_cvt_pk_bf16_f32 v64, v32, v33
	v_cvt_pk_bf16_f32 v65, v34, v35
	v_cvt_pk_bf16_f32 v66, v36, v37
	v_cvt_pk_bf16_f32 v67, v38, v39
	v_cvt_pk_bf16_f32 v68, v40, v41
	v_cvt_pk_bf16_f32 v69, v42, v43
	v_cvt_pk_bf16_f32 v70, v44, v45
	v_cvt_pk_bf16_f32 v71, v46, v47
	v_pk_add_f32 v[232:233], v[232:233], v[32:33]
	v_pk_add_f32 v[232:233], v[232:233], v[34:35]
	v_pk_add_f32 v[232:233], v[232:233], v[36:37]
	v_pk_add_f32 v[232:233], v[232:233], v[38:39]
	v_pk_add_f32 v[232:233], v[232:233], v[40:41]
	v_pk_add_f32 v[232:233], v[232:233], v[42:43]
	v_pk_add_f32 v[232:233], v[232:233], v[44:45]
	v_pk_add_f32 v[232:233], v[232:233], v[46:47]
	s_waitcnt lgkmcnt(12)
	v_mfma_f32_32x32x16_bf16 v[0:15], v[64:67], v[72:75], v[0:15]
	v_mfma_f32_32x32x16_bf16 v[16:31], v[64:67], v[76:79], v[16:31]
	v_mfma_f32_32x32x16_bf16 v[0:15], v[68:71], v[220:223], v[0:15]
	v_mfma_f32_32x32x16_bf16 v[16:31], v[68:71], v[224:227], v[16:31]
	s_add_i32 s90, s67, 512
	v_add_u32_e32 v80, s90, v239
	v_add_u32_e32 v83, s90, v240
	v_add_u32_e32 v99, s90, v241
	v_add_u32_e32 v253, s90, v242
	v_add_u32_e32 v254, s90, v101
	v_add_u32_e32 v255, s90, v150
	v_med3_i32 v80, v80, 0, s99
	v_med3_i32 v83, v83, 0, s99
	v_med3_i32 v99, v99, 0, s99
	v_med3_i32 v253, v253, 0, s99
	v_med3_i32 v254, v254, 0, s99
	v_med3_i32 v255, v255, 0, s99
	v_mad_u32_u24 v80, v80, s100, v252
	v_mad_u32_u24 v83, v83, s100, v252
	v_mad_u32_u24 v99, v99, s100, v252
	v_mad_u32_u24 v253, v253, s100, v252
	v_mad_u32_u24 v254, v254, s100, v153
	v_mad_u32_u24 v255, v255, s100, v153
	global_load_dwordx4 v[188:191], v80, s[82:83]
	global_load_dwordx4 v[192:195], v83, s[82:83]
	global_load_dwordx4 v[196:199], v99, s[82:83]
	global_load_dwordx4 v[200:203], v253, s[82:83]
	global_load_dwordx4 v[204:207], v254, s[82:83] offset:768
	global_load_dwordx4 v[208:211], v255, s[82:83] offset:768
	global_load_dwordx4 v[212:215], v254, s[82:83] offset:832
	global_load_dwordx4 v[216:219], v255, s[82:83] offset:832
	v_add_u32_e32 v115, 640, v115
	ds_read2_b32 v[32:33], v115 offset0:0 offset1:1
	ds_read2_b32 v[34:35], v115 offset0:2 offset1:3
	ds_read2_b32 v[36:37], v115 offset0:10 offset1:11
	ds_read2_b32 v[38:39], v115 offset0:12 offset1:13
	ds_read2_b32 v[40:41], v115 offset0:20 offset1:21
	ds_read2_b32 v[42:43], v115 offset0:22 offset1:23
	ds_read2_b32 v[44:45], v115 offset0:30 offset1:31
	ds_read2_b32 v[46:47], v115 offset0:32 offset1:33
	s_waitcnt lgkmcnt(0)
	v_mfma_f32_32x32x16_bf16 v[32:47], v[116:119], v[48:51], v[32:47]
	ds_read_b64_tr_b16 v[72:73], v231
	ds_read_b64_tr_b16 v[74:75], v231 offset:512
	ds_read_b64_tr_b16 v[76:77], v231 offset:2048
	ds_read_b64_tr_b16 v[78:79], v231 offset:2560
	ds_read_b64_tr_b16 v[220:221], v231 offset:1024
	ds_read_b64_tr_b16 v[222:223], v231 offset:1536
	ds_read_b64_tr_b16 v[224:225], v231 offset:3072
	ds_read_b64_tr_b16 v[226:227], v231 offset:3584
	s_waitcnt vmcnt(8)
	ds_write_b128 v247, v[156:159]
	ds_write_b128 v247, v[160:163] offset:1024
	ds_write_b128 v247, v[164:167] offset:2048
	ds_write_b128 v247, v[168:171] offset:3072
	ds_read_b128 v[156:159], v248
	ds_read_b128 v[160:163], v249
	ds_read_b128 v[164:167], v250
	ds_read_b128 v[168:171], v251
	ds_write_b128 v112, v[172:175]
	ds_write_b128 v112, v[176:179] offset:1024
	ds_write_b128 v112, v[180:183] offset:2048
	ds_write_b128 v112, v[184:187] offset:3072
	v_mfma_f32_32x32x16_bf16 v[32:47], v[120:123], v[52:55], v[32:47]
	v_mfma_f32_32x32x16_bf16 v[32:47], v[124:127], v[56:59], v[32:47]
	v_mfma_f32_32x32x16_bf16 v[32:47], v[128:131], v[60:63], v[32:47]
	s_nop 11
	v_exp_f32_e32 v32, v32
	v_exp_f32_e32 v33, v33
	v_exp_f32_e32 v34, v34
	v_exp_f32_e32 v35, v35
	v_exp_f32_e32 v36, v36
	v_exp_f32_e32 v37, v37
	v_exp_f32_e32 v38, v38
	v_exp_f32_e32 v39, v39
	v_exp_f32_e32 v40, v40
	v_exp_f32_e32 v41, v41
	v_exp_f32_e32 v42, v42
	v_exp_f32_e32 v43, v43
	v_exp_f32_e32 v44, v44
	v_exp_f32_e32 v45, v45
	v_exp_f32_e32 v46, v46
	v_exp_f32_e32 v47, v47
	s_add_i32 s90, s67, 256
	v_lshlrev_b32_e32 v84, 2, v107
	v_add_u32_e32 v84, s90, v84
	v_add_u32_e32 v85, 0, v84
	v_add_u32_e32 v86, 4, v84
	v_add_u32_e32 v87, 8, v84
	v_add_u32_e32 v88, 12, v84
	v_cmp_gt_u32_e64 s[30:31], s98, v85
	v_cmp_gt_u32_e64 s[36:37], s98, v86
	v_cmp_gt_u32_e64 s[78:79], s98, v87
	v_cmp_gt_u32_e64 s[50:51], s98, v88
	v_cndmask_b32_e64 v32, 0, v32, s[30:31]
	v_add_u32_e32 v85, 32, v84
	v_cmp_gt_u32_e64 s[30:31], s98, v85
	v_cndmask_b32_e64 v33, 0, v33, s[36:37]
	v_add_u32_e32 v86, 36, v84
	v_cmp_gt_u32_e64 s[36:37], s98, v86
	v_cndmask_b32_e64 v34, 0, v34, s[78:79]
	v_add_u32_e32 v87, 40, v84
	v_cmp_gt_u32_e64 s[78:79], s98, v87
	v_cndmask_b32_e64 v35, 0, v35, s[50:51]
	v_add_u32_e32 v88, 44, v84
	v_cmp_gt_u32_e64 s[50:51], s98, v88
	v_cndmask_b32_e64 v36, 0, v36, s[30:31]
	v_add_u32_e32 v85, 64, v84
	v_cmp_gt_u32_e64 s[30:31], s98, v85
	v_cndmask_b32_e64 v37, 0, v37, s[36:37]
	v_add_u32_e32 v86, 68, v84
	v_cmp_gt_u32_e64 s[36:37], s98, v86
	v_cndmask_b32_e64 v38, 0, v38, s[78:79]
	v_add_u32_e32 v87, 72, v84
	v_cmp_gt_u32_e64 s[78:79], s98, v87
	v_cndmask_b32_e64 v39, 0, v39, s[50:51]
	v_add_u32_e32 v88, 76, v84
	v_cmp_gt_u32_e64 s[50:51], s98, v88
	v_cndmask_b32_e64 v40, 0, v40, s[30:31]
	v_add_u32_e32 v85, 96, v84
	v_cmp_gt_u32_e64 s[30:31], s98, v85
	v_cndmask_b32_e64 v41, 0, v41, s[36:37]
	v_add_u32_e32 v86, 100, v84
	v_cmp_gt_u32_e64 s[36:37], s98, v86
	v_cndmask_b32_e64 v42, 0, v42, s[78:79]
	v_add_u32_e32 v87, 104, v84
	v_cmp_gt_u32_e64 s[78:79], s98, v87
	v_cndmask_b32_e64 v43, 0, v43, s[50:51]
	v_add_u32_e32 v88, 108, v84
	v_cmp_gt_u32_e64 s[50:51], s98, v88
	v_nop
	v_cndmask_b32_e64 v44, 0, v44, s[30:31]
	v_cndmask_b32_e64 v45, 0, v45, s[36:37]
	v_cndmask_b32_e64 v46, 0, v46, s[78:79]
	v_cndmask_b32_e64 v47, 0, v47, s[50:51]
	v_cvt_pk_bf16_f32 v64, v32, v33
	v_cvt_pk_bf16_f32 v65, v34, v35
	v_cvt_pk_bf16_f32 v66, v36, v37
	v_cvt_pk_bf16_f32 v67, v38, v39
	v_cvt_pk_bf16_f32 v68, v40, v41
	v_cvt_pk_bf16_f32 v69, v42, v43
	v_cvt_pk_bf16_f32 v70, v44, v45
	v_cvt_pk_bf16_f32 v71, v46, v47
	v_pk_add_f32 v[232:233], v[232:233], v[32:33]
	v_pk_add_f32 v[232:233], v[232:233], v[34:35]
	v_pk_add_f32 v[232:233], v[232:233], v[36:37]
	v_pk_add_f32 v[232:233], v[232:233], v[38:39]
	v_pk_add_f32 v[232:233], v[232:233], v[40:41]
	v_pk_add_f32 v[232:233], v[232:233], v[42:43]
	v_pk_add_f32 v[232:233], v[232:233], v[44:45]
	v_pk_add_f32 v[232:233], v[232:233], v[46:47]
	s_waitcnt lgkmcnt(12)
	v_mfma_f32_32x32x16_bf16 v[0:15], v[64:67], v[72:75], v[0:15]
	v_mfma_f32_32x32x16_bf16 v[16:31], v[64:67], v[76:79], v[16:31]
	v_mfma_f32_32x32x16_bf16 v[0:15], v[68:71], v[220:223], v[0:15]
	v_mfma_f32_32x32x16_bf16 v[16:31], v[68:71], v[224:227], v[16:31]
	s_add_i32 s90, s67, 640
	v_add_u32_e32 v80, s90, v239
	v_add_u32_e32 v83, s90, v240
	v_add_u32_e32 v99, s90, v241
	v_add_u32_e32 v253, s90, v242
	v_add_u32_e32 v254, s90, v101
	v_add_u32_e32 v255, s90, v150
	v_med3_i32 v80, v80, 0, s99
	v_med3_i32 v83, v83, 0, s99
	v_med3_i32 v99, v99, 0, s99
	v_med3_i32 v253, v253, 0, s99
	v_med3_i32 v254, v254, 0, s99
	v_med3_i32 v255, v255, 0, s99
	v_mad_u32_u24 v80, v80, s100, v252
	v_mad_u32_u24 v83, v83, s100, v252
	v_mad_u32_u24 v99, v99, s100, v252
	v_mad_u32_u24 v253, v253, s100, v252
	v_mad_u32_u24 v254, v254, s100, v153
	v_mad_u32_u24 v255, v255, s100, v153
	global_load_dwordx4 v[116:119], v80, s[82:83]
	global_load_dwordx4 v[120:123], v83, s[82:83]
	global_load_dwordx4 v[124:127], v99, s[82:83]
	global_load_dwordx4 v[128:131], v253, s[82:83]
	global_load_dwordx4 v[132:135], v254, s[82:83] offset:768
	global_load_dwordx4 v[136:139], v255, s[82:83] offset:768
	global_load_dwordx4 v[140:143], v254, s[82:83] offset:832
	global_load_dwordx4 v[144:147], v255, s[82:83] offset:832
	ds_read2_b32 v[32:33], v115 offset0:40 offset1:41
	ds_read2_b32 v[34:35], v115 offset0:42 offset1:43
	ds_read2_b32 v[36:37], v115 offset0:50 offset1:51
	ds_read2_b32 v[38:39], v115 offset0:52 offset1:53
	ds_read2_b32 v[40:41], v115 offset0:60 offset1:61
	ds_read2_b32 v[42:43], v115 offset0:62 offset1:63
	ds_read2_b32 v[44:45], v115 offset0:70 offset1:71
	ds_read2_b32 v[46:47], v115 offset0:72 offset1:73
	s_waitcnt lgkmcnt(0)
	v_mfma_f32_32x32x16_bf16 v[32:47], v[156:159], v[48:51], v[32:47]
	ds_read_b64_tr_b16 v[72:73], v231
	ds_read_b64_tr_b16 v[74:75], v231 offset:512
	ds_read_b64_tr_b16 v[76:77], v231 offset:2048
	ds_read_b64_tr_b16 v[78:79], v231 offset:2560
	ds_read_b64_tr_b16 v[220:221], v231 offset:1024
	ds_read_b64_tr_b16 v[222:223], v231 offset:1536
	ds_read_b64_tr_b16 v[224:225], v231 offset:3072
	ds_read_b64_tr_b16 v[226:227], v231 offset:3584
	s_waitcnt vmcnt(8)
	ds_write_b128 v247, v[188:191]
	ds_write_b128 v247, v[192:195] offset:1024
	ds_write_b128 v247, v[196:199] offset:2048
	ds_write_b128 v247, v[200:203] offset:3072
	ds_read_b128 v[188:191], v248
	ds_read_b128 v[192:195], v249
	ds_read_b128 v[196:199], v250
	ds_read_b128 v[200:203], v251
	ds_write_b128 v112, v[204:207]
	ds_write_b128 v112, v[208:211] offset:1024
	ds_write_b128 v112, v[212:215] offset:2048
	ds_write_b128 v112, v[216:219] offset:3072
	v_mfma_f32_32x32x16_bf16 v[32:47], v[160:163], v[52:55], v[32:47]
	v_mfma_f32_32x32x16_bf16 v[32:47], v[164:167], v[56:59], v[32:47]
	v_mfma_f32_32x32x16_bf16 v[32:47], v[168:171], v[60:63], v[32:47]
	s_nop 11
	v_exp_f32_e32 v32, v32
	v_exp_f32_e32 v33, v33
	v_exp_f32_e32 v34, v34
	v_exp_f32_e32 v35, v35
	v_exp_f32_e32 v36, v36
	v_exp_f32_e32 v37, v37
	v_exp_f32_e32 v38, v38
	v_exp_f32_e32 v39, v39
	v_exp_f32_e32 v40, v40
	v_exp_f32_e32 v41, v41
	v_exp_f32_e32 v42, v42
	v_exp_f32_e32 v43, v43
	v_exp_f32_e32 v44, v44
	v_exp_f32_e32 v45, v45
	v_exp_f32_e32 v46, v46
	v_exp_f32_e32 v47, v47
	s_add_i32 s90, s67, 384
	v_lshlrev_b32_e32 v84, 2, v107
	v_add_u32_e32 v84, s90, v84
	v_add_u32_e32 v85, 0, v84
	v_add_u32_e32 v86, 4, v84
	v_add_u32_e32 v87, 8, v84
	v_add_u32_e32 v88, 12, v84
	v_cmp_gt_u32_e64 s[30:31], s98, v85
	v_cmp_gt_u32_e64 s[36:37], s98, v86
	v_cmp_gt_u32_e64 s[78:79], s98, v87
	v_cmp_gt_u32_e64 s[50:51], s98, v88
	v_cndmask_b32_e64 v32, 0, v32, s[30:31]
	v_add_u32_e32 v85, 32, v84
	v_cmp_gt_u32_e64 s[30:31], s98, v85
	v_cndmask_b32_e64 v33, 0, v33, s[36:37]
	v_add_u32_e32 v86, 36, v84
	v_cmp_gt_u32_e64 s[36:37], s98, v86
	v_cndmask_b32_e64 v34, 0, v34, s[78:79]
	v_add_u32_e32 v87, 40, v84
	v_cmp_gt_u32_e64 s[78:79], s98, v87
	v_cndmask_b32_e64 v35, 0, v35, s[50:51]
	v_add_u32_e32 v88, 44, v84
	v_cmp_gt_u32_e64 s[50:51], s98, v88
	v_cndmask_b32_e64 v36, 0, v36, s[30:31]
	v_add_u32_e32 v85, 64, v84
	v_cmp_gt_u32_e64 s[30:31], s98, v85
	v_cndmask_b32_e64 v37, 0, v37, s[36:37]
	v_add_u32_e32 v86, 68, v84
	v_cmp_gt_u32_e64 s[36:37], s98, v86
	v_cndmask_b32_e64 v38, 0, v38, s[78:79]
	v_add_u32_e32 v87, 72, v84
	v_cmp_gt_u32_e64 s[78:79], s98, v87
	v_cndmask_b32_e64 v39, 0, v39, s[50:51]
	v_add_u32_e32 v88, 76, v84
	v_cmp_gt_u32_e64 s[50:51], s98, v88
	v_cndmask_b32_e64 v40, 0, v40, s[30:31]
	v_add_u32_e32 v85, 96, v84
	v_cmp_gt_u32_e64 s[30:31], s98, v85
	v_cndmask_b32_e64 v41, 0, v41, s[36:37]
	v_add_u32_e32 v86, 100, v84
	v_cmp_gt_u32_e64 s[36:37], s98, v86
	v_cndmask_b32_e64 v42, 0, v42, s[78:79]
	v_add_u32_e32 v87, 104, v84
	v_cmp_gt_u32_e64 s[78:79], s98, v87
	v_cndmask_b32_e64 v43, 0, v43, s[50:51]
	v_add_u32_e32 v88, 108, v84
	v_cmp_gt_u32_e64 s[50:51], s98, v88
	v_nop
	v_cndmask_b32_e64 v44, 0, v44, s[30:31]
	v_cndmask_b32_e64 v45, 0, v45, s[36:37]
	v_cndmask_b32_e64 v46, 0, v46, s[78:79]
	v_cndmask_b32_e64 v47, 0, v47, s[50:51]
	v_cvt_pk_bf16_f32 v64, v32, v33
	v_cvt_pk_bf16_f32 v65, v34, v35
	v_cvt_pk_bf16_f32 v66, v36, v37
	v_cvt_pk_bf16_f32 v67, v38, v39
	v_cvt_pk_bf16_f32 v68, v40, v41
	v_cvt_pk_bf16_f32 v69, v42, v43
	v_cvt_pk_bf16_f32 v70, v44, v45
	v_cvt_pk_bf16_f32 v71, v46, v47
	v_pk_add_f32 v[232:233], v[232:233], v[32:33]
	v_pk_add_f32 v[232:233], v[232:233], v[34:35]
	v_pk_add_f32 v[232:233], v[232:233], v[36:37]
	v_pk_add_f32 v[232:233], v[232:233], v[38:39]
	v_pk_add_f32 v[232:233], v[232:233], v[40:41]
	v_pk_add_f32 v[232:233], v[232:233], v[42:43]
	v_pk_add_f32 v[232:233], v[232:233], v[44:45]
	v_pk_add_f32 v[232:233], v[232:233], v[46:47]
	s_waitcnt lgkmcnt(12)
	v_mfma_f32_32x32x16_bf16 v[0:15], v[64:67], v[72:75], v[0:15]
	v_mfma_f32_32x32x16_bf16 v[16:31], v[64:67], v[76:79], v[16:31]
	v_mfma_f32_32x32x16_bf16 v[0:15], v[68:71], v[220:223], v[0:15]
	v_mfma_f32_32x32x16_bf16 v[16:31], v[68:71], v[224:227], v[16:31]
	s_add_i32 s90, s67, -1024
	v_add_u32_e32 v80, s90, v243
	v_add_u32_e32 v83, s90, v244
	v_add_u32_e32 v99, s90, v245
	v_add_u32_e32 v253, s90, v246
	v_add_u32_e32 v254, s90, v148
	v_add_u32_e32 v255, s90, v151
	v_med3_i32 v80, v80, 0, s99
	v_med3_i32 v83, v83, 0, s99
	v_med3_i32 v99, v99, 0, s99
	v_med3_i32 v253, v253, 0, s99
	v_med3_i32 v254, v254, 0, s99
	v_med3_i32 v255, v255, 0, s99
	v_mad_u32_u24 v80, v80, s100, v252
	v_mad_u32_u24 v83, v83, s100, v252
	v_mad_u32_u24 v99, v99, s100, v252
	v_mad_u32_u24 v253, v253, s100, v252
	v_mad_u32_u24 v254, v254, s100, v153
	v_mad_u32_u24 v255, v255, s100, v153
	global_load_dwordx4 v[156:159], v80, s[82:83]
	global_load_dwordx4 v[160:163], v83, s[82:83]
	global_load_dwordx4 v[164:167], v99, s[82:83]
	global_load_dwordx4 v[168:171], v253, s[82:83]
	global_load_dwordx4 v[172:175], v254, s[82:83] offset:768
	global_load_dwordx4 v[176:179], v255, s[82:83] offset:768
	global_load_dwordx4 v[180:183], v254, s[82:83] offset:832
	global_load_dwordx4 v[184:187], v255, s[82:83] offset:832
	ds_read2_b32 v[32:33], v115 offset0:80 offset1:81
	ds_read2_b32 v[34:35], v115 offset0:82 offset1:83
	ds_read2_b32 v[36:37], v115 offset0:90 offset1:91
	ds_read2_b32 v[38:39], v115 offset0:92 offset1:93
	ds_read2_b32 v[40:41], v115 offset0:100 offset1:101
	ds_read2_b32 v[42:43], v115 offset0:102 offset1:103
	ds_read2_b32 v[44:45], v115 offset0:110 offset1:111
	ds_read2_b32 v[46:47], v115 offset0:112 offset1:113
	s_waitcnt lgkmcnt(0)
	v_mfma_f32_32x32x16_bf16 v[32:47], v[188:191], v[48:51], v[32:47]
	ds_read_b64_tr_b16 v[72:73], v231
	ds_read_b64_tr_b16 v[74:75], v231 offset:512
	ds_read_b64_tr_b16 v[76:77], v231 offset:2048
	ds_read_b64_tr_b16 v[78:79], v231 offset:2560
	ds_read_b64_tr_b16 v[220:221], v231 offset:1024
	ds_read_b64_tr_b16 v[222:223], v231 offset:1536
	ds_read_b64_tr_b16 v[224:225], v231 offset:3072
	ds_read_b64_tr_b16 v[226:227], v231 offset:3584
	s_waitcnt vmcnt(8)
	ds_write_b128 v247, v[116:119]
	ds_write_b128 v247, v[120:123] offset:1024
	ds_write_b128 v247, v[124:127] offset:2048
	ds_write_b128 v247, v[128:131] offset:3072
	ds_read_b128 v[116:119], v248
	ds_read_b128 v[120:123], v249
	ds_read_b128 v[124:127], v250
	ds_read_b128 v[128:131], v251
	ds_write_b128 v112, v[132:135]
	ds_write_b128 v112, v[136:139] offset:1024
	ds_write_b128 v112, v[140:143] offset:2048
	ds_write_b128 v112, v[144:147] offset:3072
	v_mfma_f32_32x32x16_bf16 v[32:47], v[192:195], v[52:55], v[32:47]
	v_mfma_f32_32x32x16_bf16 v[32:47], v[196:199], v[56:59], v[32:47]
	v_mfma_f32_32x32x16_bf16 v[32:47], v[200:203], v[60:63], v[32:47]
	s_nop 11
	v_exp_f32_e32 v32, v32
	v_exp_f32_e32 v33, v33
	v_exp_f32_e32 v34, v34
	v_exp_f32_e32 v35, v35
	v_exp_f32_e32 v36, v36
	v_exp_f32_e32 v37, v37
	v_exp_f32_e32 v38, v38
	v_exp_f32_e32 v39, v39
	v_exp_f32_e32 v40, v40
	v_exp_f32_e32 v41, v41
	v_exp_f32_e32 v42, v42
	v_exp_f32_e32 v43, v43
	v_exp_f32_e32 v44, v44
	v_exp_f32_e32 v45, v45
	v_exp_f32_e32 v46, v46
	v_exp_f32_e32 v47, v47
	s_add_i32 s90, s67, 512
	v_lshlrev_b32_e32 v84, 2, v107
	v_add_u32_e32 v84, s90, v84
	v_add_u32_e32 v85, 0, v84
	v_add_u32_e32 v86, 4, v84
	v_add_u32_e32 v87, 8, v84
	v_add_u32_e32 v88, 12, v84
	v_cmp_gt_u32_e64 s[30:31], s98, v85
	v_cmp_gt_u32_e64 s[36:37], s98, v86
	v_cmp_gt_u32_e64 s[78:79], s98, v87
	v_cmp_gt_u32_e64 s[50:51], s98, v88
	v_cndmask_b32_e64 v32, 0, v32, s[30:31]
	v_add_u32_e32 v85, 32, v84
	v_cmp_gt_u32_e64 s[30:31], s98, v85
	v_cndmask_b32_e64 v33, 0, v33, s[36:37]
	v_add_u32_e32 v86, 36, v84
	v_cmp_gt_u32_e64 s[36:37], s98, v86
	v_cndmask_b32_e64 v34, 0, v34, s[78:79]
	v_add_u32_e32 v87, 40, v84
	v_cmp_gt_u32_e64 s[78:79], s98, v87
	v_cndmask_b32_e64 v35, 0, v35, s[50:51]
	v_add_u32_e32 v88, 44, v84
	v_cmp_gt_u32_e64 s[50:51], s98, v88
	v_cndmask_b32_e64 v36, 0, v36, s[30:31]
	v_add_u32_e32 v85, 64, v84
	v_cmp_gt_u32_e64 s[30:31], s98, v85
	v_cndmask_b32_e64 v37, 0, v37, s[36:37]
	v_add_u32_e32 v86, 68, v84
	v_cmp_gt_u32_e64 s[36:37], s98, v86
	v_cndmask_b32_e64 v38, 0, v38, s[78:79]
	v_add_u32_e32 v87, 72, v84
	v_cmp_gt_u32_e64 s[78:79], s98, v87
	v_cndmask_b32_e64 v39, 0, v39, s[50:51]
	v_add_u32_e32 v88, 76, v84
	v_cmp_gt_u32_e64 s[50:51], s98, v88
	v_cndmask_b32_e64 v40, 0, v40, s[30:31]
	v_add_u32_e32 v85, 96, v84
	v_cmp_gt_u32_e64 s[30:31], s98, v85
	v_cndmask_b32_e64 v41, 0, v41, s[36:37]
	v_add_u32_e32 v86, 100, v84
	v_cmp_gt_u32_e64 s[36:37], s98, v86
	v_cndmask_b32_e64 v42, 0, v42, s[78:79]
	v_add_u32_e32 v87, 104, v84
	v_cmp_gt_u32_e64 s[78:79], s98, v87
	v_cndmask_b32_e64 v43, 0, v43, s[50:51]
	v_add_u32_e32 v88, 108, v84
	v_cmp_gt_u32_e64 s[50:51], s98, v88
	v_nop
	v_cndmask_b32_e64 v44, 0, v44, s[30:31]
	v_cndmask_b32_e64 v45, 0, v45, s[36:37]
	v_cndmask_b32_e64 v46, 0, v46, s[78:79]
	v_cndmask_b32_e64 v47, 0, v47, s[50:51]
	v_cvt_pk_bf16_f32 v64, v32, v33
	v_cvt_pk_bf16_f32 v65, v34, v35
	v_cvt_pk_bf16_f32 v66, v36, v37
	v_cvt_pk_bf16_f32 v67, v38, v39
	v_cvt_pk_bf16_f32 v68, v40, v41
	v_cvt_pk_bf16_f32 v69, v42, v43
	v_cvt_pk_bf16_f32 v70, v44, v45
	v_cvt_pk_bf16_f32 v71, v46, v47
	v_pk_add_f32 v[232:233], v[232:233], v[32:33]
	v_pk_add_f32 v[232:233], v[232:233], v[34:35]
	v_pk_add_f32 v[232:233], v[232:233], v[36:37]
	v_pk_add_f32 v[232:233], v[232:233], v[38:39]
	v_pk_add_f32 v[232:233], v[232:233], v[40:41]
	v_pk_add_f32 v[232:233], v[232:233], v[42:43]
	v_pk_add_f32 v[232:233], v[232:233], v[44:45]
	v_pk_add_f32 v[232:233], v[232:233], v[46:47]
	s_waitcnt lgkmcnt(12)
	v_mfma_f32_32x32x16_bf16 v[0:15], v[64:67], v[72:75], v[0:15]
	v_mfma_f32_32x32x16_bf16 v[16:31], v[64:67], v[76:79], v[16:31]
	v_mfma_f32_32x32x16_bf16 v[0:15], v[68:71], v[220:223], v[0:15]
	v_mfma_f32_32x32x16_bf16 v[16:31], v[68:71], v[224:227], v[16:31]
	s_add_i32 s90, s67, -512
	v_add_u32_e32 v80, s90, v243
	v_add_u32_e32 v83, s90, v244
	v_add_u32_e32 v99, s90, v245
	v_add_u32_e32 v253, s90, v246
	v_add_u32_e32 v254, s90, v148
	v_add_u32_e32 v255, s90, v151
	v_med3_i32 v80, v80, 0, s99
	v_med3_i32 v83, v83, 0, s99
	v_med3_i32 v99, v99, 0, s99
	v_med3_i32 v253, v253, 0, s99
	v_med3_i32 v254, v254, 0, s99
	v_med3_i32 v255, v255, 0, s99
	v_mad_u32_u24 v80, v80, s100, v252
	v_mad_u32_u24 v83, v83, s100, v252
	v_mad_u32_u24 v99, v99, s100, v252
	v_mad_u32_u24 v253, v253, s100, v252
	v_mad_u32_u24 v254, v254, s100, v153
	v_mad_u32_u24 v255, v255, s100, v153
	global_load_dwordx4 v[188:191], v80, s[82:83]
	global_load_dwordx4 v[192:195], v83, s[82:83]
	global_load_dwordx4 v[196:199], v99, s[82:83]
	global_load_dwordx4 v[200:203], v253, s[82:83]
	global_load_dwordx4 v[204:207], v254, s[82:83] offset:768
	global_load_dwordx4 v[208:211], v255, s[82:83] offset:768
	global_load_dwordx4 v[212:215], v254, s[82:83] offset:832
	global_load_dwordx4 v[216:219], v255, s[82:83] offset:832
	ds_read2_b32 v[32:33], v115 offset0:120 offset1:121
	ds_read2_b32 v[34:35], v115 offset0:122 offset1:123
	ds_read2_b32 v[36:37], v115 offset0:130 offset1:131
	ds_read2_b32 v[38:39], v115 offset0:132 offset1:133
	ds_read2_b32 v[40:41], v115 offset0:140 offset1:141
	ds_read2_b32 v[42:43], v115 offset0:142 offset1:143
	ds_read2_b32 v[44:45], v115 offset0:150 offset1:151
	ds_read2_b32 v[46:47], v115 offset0:152 offset1:153
	s_waitcnt lgkmcnt(0)
	v_mfma_f32_32x32x16_bf16 v[32:47], v[116:119], v[48:51], v[32:47]
	ds_read_b64_tr_b16 v[72:73], v231
	ds_read_b64_tr_b16 v[74:75], v231 offset:512
	ds_read_b64_tr_b16 v[76:77], v231 offset:2048
	ds_read_b64_tr_b16 v[78:79], v231 offset:2560
	ds_read_b64_tr_b16 v[220:221], v231 offset:1024
	ds_read_b64_tr_b16 v[222:223], v231 offset:1536
	ds_read_b64_tr_b16 v[224:225], v231 offset:3072
	ds_read_b64_tr_b16 v[226:227], v231 offset:3584
	s_waitcnt vmcnt(8)
	ds_write_b128 v247, v[156:159]
	ds_write_b128 v247, v[160:163] offset:1024
	ds_write_b128 v247, v[164:167] offset:2048
	ds_write_b128 v247, v[168:171] offset:3072
	ds_read_b128 v[156:159], v248
	ds_read_b128 v[160:163], v249
	ds_read_b128 v[164:167], v250
	ds_read_b128 v[168:171], v251
	ds_write_b128 v112, v[172:175]
	ds_write_b128 v112, v[176:179] offset:1024
	ds_write_b128 v112, v[180:183] offset:2048
	ds_write_b128 v112, v[184:187] offset:3072
	v_mfma_f32_32x32x16_bf16 v[32:47], v[120:123], v[52:55], v[32:47]
	v_mfma_f32_32x32x16_bf16 v[32:47], v[124:127], v[56:59], v[32:47]
	v_mfma_f32_32x32x16_bf16 v[32:47], v[128:131], v[60:63], v[32:47]
	s_nop 11
	v_exp_f32_e32 v32, v32
	v_exp_f32_e32 v33, v33
	v_exp_f32_e32 v34, v34
	v_exp_f32_e32 v35, v35
	v_exp_f32_e32 v36, v36
	v_exp_f32_e32 v37, v37
	v_exp_f32_e32 v38, v38
	v_exp_f32_e32 v39, v39
	v_exp_f32_e32 v40, v40
	v_exp_f32_e32 v41, v41
	v_exp_f32_e32 v42, v42
	v_exp_f32_e32 v43, v43
	v_exp_f32_e32 v44, v44
	v_exp_f32_e32 v45, v45
	v_exp_f32_e32 v46, v46
	v_exp_f32_e32 v47, v47
	s_add_i32 s90, s67, 640
	v_lshlrev_b32_e32 v84, 2, v107
	v_add_u32_e32 v84, s90, v84
	v_add_u32_e32 v85, 0, v84
	v_add_u32_e32 v86, 4, v84
	v_add_u32_e32 v87, 8, v84
	v_add_u32_e32 v88, 12, v84
	v_cmp_gt_u32_e64 s[30:31], s98, v85
	v_cmp_gt_u32_e64 s[36:37], s98, v86
	v_cmp_gt_u32_e64 s[78:79], s98, v87
	v_cmp_gt_u32_e64 s[50:51], s98, v88
	v_cndmask_b32_e64 v32, 0, v32, s[30:31]
	v_add_u32_e32 v85, 32, v84
	v_cmp_gt_u32_e64 s[30:31], s98, v85
	v_cndmask_b32_e64 v33, 0, v33, s[36:37]
	v_add_u32_e32 v86, 36, v84
	v_cmp_gt_u32_e64 s[36:37], s98, v86
	v_cndmask_b32_e64 v34, 0, v34, s[78:79]
	v_add_u32_e32 v87, 40, v84
	v_cmp_gt_u32_e64 s[78:79], s98, v87
	v_cndmask_b32_e64 v35, 0, v35, s[50:51]
	v_add_u32_e32 v88, 44, v84
	v_cmp_gt_u32_e64 s[50:51], s98, v88
	v_cndmask_b32_e64 v36, 0, v36, s[30:31]
	v_add_u32_e32 v85, 64, v84
	v_cmp_gt_u32_e64 s[30:31], s98, v85
	v_cndmask_b32_e64 v37, 0, v37, s[36:37]
	v_add_u32_e32 v86, 68, v84
	v_cmp_gt_u32_e64 s[36:37], s98, v86
	v_cndmask_b32_e64 v38, 0, v38, s[78:79]
	v_add_u32_e32 v87, 72, v84
	v_cmp_gt_u32_e64 s[78:79], s98, v87
	v_cndmask_b32_e64 v39, 0, v39, s[50:51]
	v_add_u32_e32 v88, 76, v84
	v_cmp_gt_u32_e64 s[50:51], s98, v88
	v_cndmask_b32_e64 v40, 0, v40, s[30:31]
	v_add_u32_e32 v85, 96, v84
	v_cmp_gt_u32_e64 s[30:31], s98, v85
	v_cndmask_b32_e64 v41, 0, v41, s[36:37]
	v_add_u32_e32 v86, 100, v84
	v_cmp_gt_u32_e64 s[36:37], s98, v86
	v_cndmask_b32_e64 v42, 0, v42, s[78:79]
	v_add_u32_e32 v87, 104, v84
	v_cmp_gt_u32_e64 s[78:79], s98, v87
	v_cndmask_b32_e64 v43, 0, v43, s[50:51]
	v_add_u32_e32 v88, 108, v84
	v_cmp_gt_u32_e64 s[50:51], s98, v88
	v_nop
	v_cndmask_b32_e64 v44, 0, v44, s[30:31]
	v_cndmask_b32_e64 v45, 0, v45, s[36:37]
	v_cndmask_b32_e64 v46, 0, v46, s[78:79]
	v_cndmask_b32_e64 v47, 0, v47, s[50:51]
	v_cvt_pk_bf16_f32 v64, v32, v33
	v_cvt_pk_bf16_f32 v65, v34, v35
	v_cvt_pk_bf16_f32 v66, v36, v37
	v_cvt_pk_bf16_f32 v67, v38, v39
	v_cvt_pk_bf16_f32 v68, v40, v41
	v_cvt_pk_bf16_f32 v69, v42, v43
	v_cvt_pk_bf16_f32 v70, v44, v45
	v_cvt_pk_bf16_f32 v71, v46, v47
	v_pk_add_f32 v[232:233], v[232:233], v[32:33]
	v_pk_add_f32 v[232:233], v[232:233], v[34:35]
	v_pk_add_f32 v[232:233], v[232:233], v[36:37]
	v_pk_add_f32 v[232:233], v[232:233], v[38:39]
	v_pk_add_f32 v[232:233], v[232:233], v[40:41]
	v_pk_add_f32 v[232:233], v[232:233], v[42:43]
	v_pk_add_f32 v[232:233], v[232:233], v[44:45]
	v_pk_add_f32 v[232:233], v[232:233], v[46:47]
	s_waitcnt lgkmcnt(12)
	v_mfma_f32_32x32x16_bf16 v[0:15], v[64:67], v[72:75], v[0:15]
	v_mfma_f32_32x32x16_bf16 v[16:31], v[64:67], v[76:79], v[16:31]
	v_mfma_f32_32x32x16_bf16 v[0:15], v[68:71], v[220:223], v[0:15]
	v_mfma_f32_32x32x16_bf16 v[16:31], v[68:71], v[224:227], v[16:31]
	s_add_i32 s90, s67, 0
	v_add_u32_e32 v80, s90, v243
	v_add_u32_e32 v83, s90, v244
	v_add_u32_e32 v99, s90, v245
	v_add_u32_e32 v253, s90, v246
	v_add_u32_e32 v254, s90, v148
	v_add_u32_e32 v255, s90, v151
	v_med3_i32 v80, v80, 0, s99
	v_med3_i32 v83, v83, 0, s99
	v_med3_i32 v99, v99, 0, s99
	v_med3_i32 v253, v253, 0, s99
	v_med3_i32 v254, v254, 0, s99
	v_med3_i32 v255, v255, 0, s99
	v_mad_u32_u24 v80, v80, s100, v252
	v_mad_u32_u24 v83, v83, s100, v252
	v_mad_u32_u24 v99, v99, s100, v252
	v_mad_u32_u24 v253, v253, s100, v252
	v_mad_u32_u24 v254, v254, s100, v153
	v_mad_u32_u24 v255, v255, s100, v153
	global_load_dwordx4 v[116:119], v80, s[82:83]
	global_load_dwordx4 v[120:123], v83, s[82:83]
	global_load_dwordx4 v[124:127], v99, s[82:83]
	global_load_dwordx4 v[128:131], v253, s[82:83]
	global_load_dwordx4 v[132:135], v254, s[82:83] offset:768
	global_load_dwordx4 v[136:139], v255, s[82:83] offset:768
	global_load_dwordx4 v[140:143], v254, s[82:83] offset:832
	global_load_dwordx4 v[144:147], v255, s[82:83] offset:832
	v_mov_b32_e32 v115, v230
	ds_read2_b32 v[32:33], v115 offset0:0 offset1:1
	ds_read2_b32 v[34:35], v115 offset0:2 offset1:3
	ds_read2_b32 v[36:37], v115 offset0:8 offset1:9
	ds_read2_b32 v[38:39], v115 offset0:10 offset1:11
	ds_read2_b32 v[40:41], v115 offset0:16 offset1:17
	ds_read2_b32 v[42:43], v115 offset0:18 offset1:19
	ds_read2_b32 v[44:45], v115 offset0:24 offset1:25
	ds_read2_b32 v[46:47], v115 offset0:26 offset1:27
	s_waitcnt lgkmcnt(0)
	v_mfma_f32_32x32x16_bf16 v[32:47], v[156:159], v[48:51], v[32:47]
	ds_read_b64_tr_b16 v[72:73], v231
	ds_read_b64_tr_b16 v[74:75], v231 offset:512
	ds_read_b64_tr_b16 v[76:77], v231 offset:2048
	ds_read_b64_tr_b16 v[78:79], v231 offset:2560
	ds_read_b64_tr_b16 v[220:221], v231 offset:1024
	ds_read_b64_tr_b16 v[222:223], v231 offset:1536
	ds_read_b64_tr_b16 v[224:225], v231 offset:3072
	ds_read_b64_tr_b16 v[226:227], v231 offset:3584
	s_waitcnt vmcnt(8)
	ds_write_b128 v247, v[188:191]
	ds_write_b128 v247, v[192:195] offset:1024
	ds_write_b128 v247, v[196:199] offset:2048
	ds_write_b128 v247, v[200:203] offset:3072
	ds_read_b128 v[188:191], v248
	ds_read_b128 v[192:195], v249
	ds_read_b128 v[196:199], v250
	ds_read_b128 v[200:203], v251
	ds_write_b128 v112, v[204:207]
	ds_write_b128 v112, v[208:211] offset:1024
	ds_write_b128 v112, v[212:215] offset:2048
	ds_write_b128 v112, v[216:219] offset:3072
	v_mfma_f32_32x32x16_bf16 v[32:47], v[160:163], v[52:55], v[32:47]
	v_mfma_f32_32x32x16_bf16 v[32:47], v[164:167], v[56:59], v[32:47]
	v_mfma_f32_32x32x16_bf16 v[32:47], v[168:171], v[60:63], v[32:47]
	s_nop 11
	v_exp_f32_e32 v32, v32
	v_exp_f32_e32 v33, v33
	v_exp_f32_e32 v34, v34
	v_exp_f32_e32 v35, v35
	v_exp_f32_e32 v36, v36
	v_exp_f32_e32 v37, v37
	v_exp_f32_e32 v38, v38
	v_exp_f32_e32 v39, v39
	v_exp_f32_e32 v40, v40
	v_exp_f32_e32 v41, v41
	v_exp_f32_e32 v42, v42
	v_exp_f32_e32 v43, v43
	v_exp_f32_e32 v44, v44
	v_exp_f32_e32 v45, v45
	v_exp_f32_e32 v46, v46
	v_exp_f32_e32 v47, v47
	s_add_i32 s90, s67, -1024
	v_lshlrev_b32_e32 v84, 4, v107
	v_add_u32_e32 v84, s90, v84
	v_add_u32_e32 v85, 0, v84
	v_add_u32_e32 v86, 16, v84
	v_add_u32_e32 v87, 32, v84
	v_add_u32_e32 v88, 48, v84
	v_cmp_gt_u32_e64 s[30:31], s98, v85
	v_cmp_gt_u32_e64 s[36:37], s98, v86
	v_cmp_gt_u32_e64 s[78:79], s98, v87
	v_cmp_gt_u32_e64 s[50:51], s98, v88
	v_cndmask_b32_e64 v32, 0, v32, s[30:31]
	v_add_u32_e32 v85, 128, v84
	v_cmp_gt_u32_e64 s[30:31], s98, v85
	v_cndmask_b32_e64 v33, 0, v33, s[36:37]
	v_add_u32_e32 v86, 144, v84
	v_cmp_gt_u32_e64 s[36:37], s98, v86
	v_cndmask_b32_e64 v34, 0, v34, s[78:79]
	v_add_u32_e32 v87, 160, v84
	v_cmp_gt_u32_e64 s[78:79], s98, v87
	v_cndmask_b32_e64 v35, 0, v35, s[50:51]
	v_add_u32_e32 v88, 176, v84
	v_cmp_gt_u32_e64 s[50:51], s98, v88
	v_cndmask_b32_e64 v36, 0, v36, s[30:31]
	v_add_u32_e32 v85, 256, v84
	v_cmp_gt_u32_e64 s[30:31], s98, v85
	v_cndmask_b32_e64 v37, 0, v37, s[36:37]
	v_add_u32_e32 v86, 272, v84
	v_cmp_gt_u32_e64 s[36:37], s98, v86
	v_cndmask_b32_e64 v38, 0, v38, s[78:79]
	v_add_u32_e32 v87, 288, v84
	v_cmp_gt_u32_e64 s[78:79], s98, v87
	v_cndmask_b32_e64 v39, 0, v39, s[50:51]
	v_add_u32_e32 v88, 304, v84
	v_cmp_gt_u32_e64 s[50:51], s98, v88
	v_cndmask_b32_e64 v40, 0, v40, s[30:31]
	v_add_u32_e32 v85, 384, v84
	v_cmp_gt_u32_e64 s[30:31], s98, v85
	v_cndmask_b32_e64 v41, 0, v41, s[36:37]
	v_add_u32_e32 v86, 400, v84
	v_cmp_gt_u32_e64 s[36:37], s98, v86
	v_cndmask_b32_e64 v42, 0, v42, s[78:79]
	v_add_u32_e32 v87, 416, v84
	v_cmp_gt_u32_e64 s[78:79], s98, v87
	v_cndmask_b32_e64 v43, 0, v43, s[50:51]
	v_add_u32_e32 v88, 432, v84
	v_cmp_gt_u32_e64 s[50:51], s98, v88
	v_nop
	v_cndmask_b32_e64 v44, 0, v44, s[30:31]
	v_cndmask_b32_e64 v45, 0, v45, s[36:37]
	v_cndmask_b32_e64 v46, 0, v46, s[78:79]
	v_cndmask_b32_e64 v47, 0, v47, s[50:51]
	v_cvt_pk_bf16_f32 v64, v32, v33
	v_cvt_pk_bf16_f32 v65, v34, v35
	v_cvt_pk_bf16_f32 v66, v36, v37
	v_cvt_pk_bf16_f32 v67, v38, v39
	v_cvt_pk_bf16_f32 v68, v40, v41
	v_cvt_pk_bf16_f32 v69, v42, v43
	v_cvt_pk_bf16_f32 v70, v44, v45
	v_cvt_pk_bf16_f32 v71, v46, v47
	v_pk_add_f32 v[232:233], v[232:233], v[32:33]
	v_pk_add_f32 v[232:233], v[232:233], v[34:35]
	v_pk_add_f32 v[232:233], v[232:233], v[36:37]
	v_pk_add_f32 v[232:233], v[232:233], v[38:39]
	v_pk_add_f32 v[232:233], v[232:233], v[40:41]
	v_pk_add_f32 v[232:233], v[232:233], v[42:43]
	v_pk_add_f32 v[232:233], v[232:233], v[44:45]
	v_pk_add_f32 v[232:233], v[232:233], v[46:47]
	s_waitcnt lgkmcnt(12)
	v_mfma_f32_32x32x16_bf16 v[0:15], v[64:67], v[72:75], v[0:15]
	v_mfma_f32_32x32x16_bf16 v[16:31], v[64:67], v[76:79], v[16:31]
	v_mfma_f32_32x32x16_bf16 v[0:15], v[68:71], v[220:223], v[0:15]
	v_mfma_f32_32x32x16_bf16 v[16:31], v[68:71], v[224:227], v[16:31]
	s_add_i32 s90, s67, 512
	v_add_u32_e32 v80, s90, v243
	v_add_u32_e32 v83, s90, v244
	v_add_u32_e32 v99, s90, v245
	v_add_u32_e32 v253, s90, v246
	v_add_u32_e32 v254, s90, v148
	v_add_u32_e32 v255, s90, v151
	v_med3_i32 v80, v80, 0, s99
	v_med3_i32 v83, v83, 0, s99
	v_med3_i32 v99, v99, 0, s99
	v_med3_i32 v253, v253, 0, s99
	v_med3_i32 v254, v254, 0, s99
	v_med3_i32 v255, v255, 0, s99
	v_mad_u32_u24 v80, v80, s100, v252
	v_mad_u32_u24 v83, v83, s100, v252
	v_mad_u32_u24 v99, v99, s100, v252
	v_mad_u32_u24 v253, v253, s100, v252
	v_mad_u32_u24 v254, v254, s100, v153
	v_mad_u32_u24 v255, v255, s100, v153
	global_load_dwordx4 v[156:159], v80, s[82:83]
	global_load_dwordx4 v[160:163], v83, s[82:83]
	global_load_dwordx4 v[164:167], v99, s[82:83]
	global_load_dwordx4 v[168:171], v253, s[82:83]
	global_load_dwordx4 v[172:175], v254, s[82:83] offset:768
	global_load_dwordx4 v[176:179], v255, s[82:83] offset:768
	global_load_dwordx4 v[180:183], v254, s[82:83] offset:832
	global_load_dwordx4 v[184:187], v255, s[82:83] offset:832
	ds_read2_b32 v[32:33], v115 offset0:32 offset1:33
	ds_read2_b32 v[34:35], v115 offset0:34 offset1:35
	ds_read2_b32 v[36:37], v115 offset0:40 offset1:41
	ds_read2_b32 v[38:39], v115 offset0:42 offset1:43
	ds_read2_b32 v[40:41], v115 offset0:48 offset1:49
	ds_read2_b32 v[42:43], v115 offset0:50 offset1:51
	ds_read2_b32 v[44:45], v115 offset0:56 offset1:57
	ds_read2_b32 v[46:47], v115 offset0:58 offset1:59
	s_waitcnt lgkmcnt(0)
	v_mfma_f32_32x32x16_bf16 v[32:47], v[188:191], v[48:51], v[32:47]
	ds_read_b64_tr_b16 v[72:73], v231
	ds_read_b64_tr_b16 v[74:75], v231 offset:512
	ds_read_b64_tr_b16 v[76:77], v231 offset:2048
	ds_read_b64_tr_b16 v[78:79], v231 offset:2560
	ds_read_b64_tr_b16 v[220:221], v231 offset:1024
	ds_read_b64_tr_b16 v[222:223], v231 offset:1536
	ds_read_b64_tr_b16 v[224:225], v231 offset:3072
	ds_read_b64_tr_b16 v[226:227], v231 offset:3584
	s_waitcnt vmcnt(8)
	ds_write_b128 v247, v[116:119]
	ds_write_b128 v247, v[120:123] offset:1024
	ds_write_b128 v247, v[124:127] offset:2048
	ds_write_b128 v247, v[128:131] offset:3072
	ds_read_b128 v[116:119], v248
	ds_read_b128 v[120:123], v249
	ds_read_b128 v[124:127], v250
	ds_read_b128 v[128:131], v251
	ds_write_b128 v112, v[132:135]
	ds_write_b128 v112, v[136:139] offset:1024
	ds_write_b128 v112, v[140:143] offset:2048
	ds_write_b128 v112, v[144:147] offset:3072
	v_mfma_f32_32x32x16_bf16 v[32:47], v[192:195], v[52:55], v[32:47]
	v_mfma_f32_32x32x16_bf16 v[32:47], v[196:199], v[56:59], v[32:47]
	v_mfma_f32_32x32x16_bf16 v[32:47], v[200:203], v[60:63], v[32:47]
	s_nop 11
	v_exp_f32_e32 v32, v32
	v_exp_f32_e32 v33, v33
	v_exp_f32_e32 v34, v34
	v_exp_f32_e32 v35, v35
	v_exp_f32_e32 v36, v36
	v_exp_f32_e32 v37, v37
	v_exp_f32_e32 v38, v38
	v_exp_f32_e32 v39, v39
	v_exp_f32_e32 v40, v40
	v_exp_f32_e32 v41, v41
	v_exp_f32_e32 v42, v42
	v_exp_f32_e32 v43, v43
	v_exp_f32_e32 v44, v44
	v_exp_f32_e32 v45, v45
	v_exp_f32_e32 v46, v46
	v_exp_f32_e32 v47, v47
	s_add_i32 s90, s67, -512
	v_lshlrev_b32_e32 v84, 4, v107
	v_add_u32_e32 v84, s90, v84
	v_add_u32_e32 v85, 0, v84
	v_add_u32_e32 v86, 16, v84
	v_add_u32_e32 v87, 32, v84
	v_add_u32_e32 v88, 48, v84
	v_cmp_gt_u32_e64 s[30:31], s98, v85
	v_cmp_gt_u32_e64 s[36:37], s98, v86
	v_cmp_gt_u32_e64 s[78:79], s98, v87
	v_cmp_gt_u32_e64 s[50:51], s98, v88
	v_cndmask_b32_e64 v32, 0, v32, s[30:31]
	v_add_u32_e32 v85, 128, v84
	v_cmp_gt_u32_e64 s[30:31], s98, v85
	v_cndmask_b32_e64 v33, 0, v33, s[36:37]
	v_add_u32_e32 v86, 144, v84
	v_cmp_gt_u32_e64 s[36:37], s98, v86
	v_cndmask_b32_e64 v34, 0, v34, s[78:79]
	v_add_u32_e32 v87, 160, v84
	v_cmp_gt_u32_e64 s[78:79], s98, v87
	v_cndmask_b32_e64 v35, 0, v35, s[50:51]
	v_add_u32_e32 v88, 176, v84
	v_cmp_gt_u32_e64 s[50:51], s98, v88
	v_cndmask_b32_e64 v36, 0, v36, s[30:31]
	v_add_u32_e32 v85, 256, v84
	v_cmp_gt_u32_e64 s[30:31], s98, v85
	v_cndmask_b32_e64 v37, 0, v37, s[36:37]
	v_add_u32_e32 v86, 272, v84
	v_cmp_gt_u32_e64 s[36:37], s98, v86
	v_cndmask_b32_e64 v38, 0, v38, s[78:79]
	v_add_u32_e32 v87, 288, v84
	v_cmp_gt_u32_e64 s[78:79], s98, v87
	v_cndmask_b32_e64 v39, 0, v39, s[50:51]
	v_add_u32_e32 v88, 304, v84
	v_cmp_gt_u32_e64 s[50:51], s98, v88
	v_cndmask_b32_e64 v40, 0, v40, s[30:31]
	v_add_u32_e32 v85, 384, v84
	v_cmp_gt_u32_e64 s[30:31], s98, v85
	v_cndmask_b32_e64 v41, 0, v41, s[36:37]
	v_add_u32_e32 v86, 400, v84
	v_cmp_gt_u32_e64 s[36:37], s98, v86
	v_cndmask_b32_e64 v42, 0, v42, s[78:79]
	v_add_u32_e32 v87, 416, v84
	v_cmp_gt_u32_e64 s[78:79], s98, v87
	v_cndmask_b32_e64 v43, 0, v43, s[50:51]
	v_add_u32_e32 v88, 432, v84
	v_cmp_gt_u32_e64 s[50:51], s98, v88
	v_nop
	v_cndmask_b32_e64 v44, 0, v44, s[30:31]
	v_cndmask_b32_e64 v45, 0, v45, s[36:37]
	v_cndmask_b32_e64 v46, 0, v46, s[78:79]
	v_cndmask_b32_e64 v47, 0, v47, s[50:51]
	v_cvt_pk_bf16_f32 v64, v32, v33
	v_cvt_pk_bf16_f32 v65, v34, v35
	v_cvt_pk_bf16_f32 v66, v36, v37
	v_cvt_pk_bf16_f32 v67, v38, v39
	v_cvt_pk_bf16_f32 v68, v40, v41
	v_cvt_pk_bf16_f32 v69, v42, v43
	v_cvt_pk_bf16_f32 v70, v44, v45
	v_cvt_pk_bf16_f32 v71, v46, v47
	v_pk_add_f32 v[232:233], v[232:233], v[32:33]
	v_pk_add_f32 v[232:233], v[232:233], v[34:35]
	v_pk_add_f32 v[232:233], v[232:233], v[36:37]
	v_pk_add_f32 v[232:233], v[232:233], v[38:39]
	v_pk_add_f32 v[232:233], v[232:233], v[40:41]
	v_pk_add_f32 v[232:233], v[232:233], v[42:43]
	v_pk_add_f32 v[232:233], v[232:233], v[44:45]
	v_pk_add_f32 v[232:233], v[232:233], v[46:47]
	s_waitcnt lgkmcnt(12)
	v_mfma_f32_32x32x16_bf16 v[0:15], v[64:67], v[72:75], v[0:15]
	v_mfma_f32_32x32x16_bf16 v[16:31], v[64:67], v[76:79], v[16:31]
	v_mfma_f32_32x32x16_bf16 v[0:15], v[68:71], v[220:223], v[0:15]
	v_mfma_f32_32x32x16_bf16 v[16:31], v[68:71], v[224:227], v[16:31]
	s_add_i32 s90, s67, 1024
	v_add_u32_e32 v80, s90, v243
	v_add_u32_e32 v83, s90, v244
	v_add_u32_e32 v99, s90, v245
	v_add_u32_e32 v253, s90, v246
	v_add_u32_e32 v254, s90, v148
	v_add_u32_e32 v255, s90, v151
	v_med3_i32 v80, v80, 0, s99
	v_med3_i32 v83, v83, 0, s99
	v_med3_i32 v99, v99, 0, s99
	v_med3_i32 v253, v253, 0, s99
	v_med3_i32 v254, v254, 0, s99
	v_med3_i32 v255, v255, 0, s99
	v_mad_u32_u24 v80, v80, s100, v252
	v_mad_u32_u24 v83, v83, s100, v252
	v_mad_u32_u24 v99, v99, s100, v252
	v_mad_u32_u24 v253, v253, s100, v252
	v_mad_u32_u24 v254, v254, s100, v153
	v_mad_u32_u24 v255, v255, s100, v153
	global_load_dwordx4 v[188:191], v80, s[82:83]
	global_load_dwordx4 v[192:195], v83, s[82:83]
	global_load_dwordx4 v[196:199], v99, s[82:83]
	global_load_dwordx4 v[200:203], v253, s[82:83]
	global_load_dwordx4 v[204:207], v254, s[82:83] offset:768
	global_load_dwordx4 v[208:211], v255, s[82:83] offset:768
	global_load_dwordx4 v[212:215], v254, s[82:83] offset:832
	global_load_dwordx4 v[216:219], v255, s[82:83] offset:832
	ds_read2_b32 v[32:33], v115 offset0:64 offset1:65
	ds_read2_b32 v[34:35], v115 offset0:66 offset1:67
	ds_read2_b32 v[36:37], v115 offset0:72 offset1:73
	ds_read2_b32 v[38:39], v115 offset0:74 offset1:75
	ds_read2_b32 v[40:41], v115 offset0:80 offset1:81
	ds_read2_b32 v[42:43], v115 offset0:82 offset1:83
	ds_read2_b32 v[44:45], v115 offset0:88 offset1:89
	ds_read2_b32 v[46:47], v115 offset0:90 offset1:91
	s_waitcnt lgkmcnt(0)
	v_mfma_f32_32x32x16_bf16 v[32:47], v[116:119], v[48:51], v[32:47]
	ds_read_b64_tr_b16 v[72:73], v231
	ds_read_b64_tr_b16 v[74:75], v231 offset:512
	ds_read_b64_tr_b16 v[76:77], v231 offset:2048
	ds_read_b64_tr_b16 v[78:79], v231 offset:2560
	ds_read_b64_tr_b16 v[220:221], v231 offset:1024
	ds_read_b64_tr_b16 v[222:223], v231 offset:1536
	ds_read_b64_tr_b16 v[224:225], v231 offset:3072
	ds_read_b64_tr_b16 v[226:227], v231 offset:3584
	s_waitcnt vmcnt(8)
	ds_write_b128 v247, v[156:159]
	ds_write_b128 v247, v[160:163] offset:1024
	ds_write_b128 v247, v[164:167] offset:2048
	ds_write_b128 v247, v[168:171] offset:3072
	ds_read_b128 v[156:159], v248
	ds_read_b128 v[160:163], v249
	ds_read_b128 v[164:167], v250
	ds_read_b128 v[168:171], v251
	ds_write_b128 v112, v[172:175]
	ds_write_b128 v112, v[176:179] offset:1024
	ds_write_b128 v112, v[180:183] offset:2048
	ds_write_b128 v112, v[184:187] offset:3072
	v_mfma_f32_32x32x16_bf16 v[32:47], v[120:123], v[52:55], v[32:47]
	v_mfma_f32_32x32x16_bf16 v[32:47], v[124:127], v[56:59], v[32:47]
	v_mfma_f32_32x32x16_bf16 v[32:47], v[128:131], v[60:63], v[32:47]
	s_nop 11
	v_exp_f32_e32 v32, v32
	v_exp_f32_e32 v33, v33
	v_exp_f32_e32 v34, v34
	v_exp_f32_e32 v35, v35
	v_exp_f32_e32 v36, v36
	v_exp_f32_e32 v37, v37
	v_exp_f32_e32 v38, v38
	v_exp_f32_e32 v39, v39
	v_exp_f32_e32 v40, v40
	v_exp_f32_e32 v41, v41
	v_exp_f32_e32 v42, v42
	v_exp_f32_e32 v43, v43
	v_exp_f32_e32 v44, v44
	v_exp_f32_e32 v45, v45
	v_exp_f32_e32 v46, v46
	v_exp_f32_e32 v47, v47
	s_add_i32 s90, s67, 0
	v_lshlrev_b32_e32 v84, 4, v107
	v_add_u32_e32 v84, s90, v84
	v_add_u32_e32 v85, 0, v84
	v_add_u32_e32 v86, 16, v84
	v_add_u32_e32 v87, 32, v84
	v_add_u32_e32 v88, 48, v84
	v_cmp_gt_u32_e64 s[30:31], s98, v85
	v_cmp_gt_u32_e64 s[36:37], s98, v86
	v_cmp_gt_u32_e64 s[78:79], s98, v87
	v_cmp_gt_u32_e64 s[50:51], s98, v88
	v_cndmask_b32_e64 v32, 0, v32, s[30:31]
	v_add_u32_e32 v85, 128, v84
	v_cmp_gt_u32_e64 s[30:31], s98, v85
	v_cndmask_b32_e64 v33, 0, v33, s[36:37]
	v_add_u32_e32 v86, 144, v84
	v_cmp_gt_u32_e64 s[36:37], s98, v86
	v_cndmask_b32_e64 v34, 0, v34, s[78:79]
	v_add_u32_e32 v87, 160, v84
	v_cmp_gt_u32_e64 s[78:79], s98, v87
	v_cndmask_b32_e64 v35, 0, v35, s[50:51]
	v_add_u32_e32 v88, 176, v84
	v_cmp_gt_u32_e64 s[50:51], s98, v88
	v_cndmask_b32_e64 v36, 0, v36, s[30:31]
	v_add_u32_e32 v85, 256, v84
	v_cmp_gt_u32_e64 s[30:31], s98, v85
	v_cndmask_b32_e64 v37, 0, v37, s[36:37]
	v_add_u32_e32 v86, 272, v84
	v_cmp_gt_u32_e64 s[36:37], s98, v86
	v_cndmask_b32_e64 v38, 0, v38, s[78:79]
	v_add_u32_e32 v87, 288, v84
	v_cmp_gt_u32_e64 s[78:79], s98, v87
	v_cndmask_b32_e64 v39, 0, v39, s[50:51]
	v_add_u32_e32 v88, 304, v84
	v_cmp_gt_u32_e64 s[50:51], s98, v88
	v_cndmask_b32_e64 v40, 0, v40, s[30:31]
	v_add_u32_e32 v85, 384, v84
	v_cmp_gt_u32_e64 s[30:31], s98, v85
	v_cndmask_b32_e64 v41, 0, v41, s[36:37]
	v_add_u32_e32 v86, 400, v84
	v_cmp_gt_u32_e64 s[36:37], s98, v86
	v_cndmask_b32_e64 v42, 0, v42, s[78:79]
	v_add_u32_e32 v87, 416, v84
	v_cmp_gt_u32_e64 s[78:79], s98, v87
	v_cndmask_b32_e64 v43, 0, v43, s[50:51]
	v_add_u32_e32 v88, 432, v84
	v_cmp_gt_u32_e64 s[50:51], s98, v88
	v_nop
	v_cndmask_b32_e64 v44, 0, v44, s[30:31]
	v_cndmask_b32_e64 v45, 0, v45, s[36:37]
	v_cndmask_b32_e64 v46, 0, v46, s[78:79]
	v_cndmask_b32_e64 v47, 0, v47, s[50:51]
	v_cvt_pk_bf16_f32 v64, v32, v33
	v_cvt_pk_bf16_f32 v65, v34, v35
	v_cvt_pk_bf16_f32 v66, v36, v37
	v_cvt_pk_bf16_f32 v67, v38, v39
	v_cvt_pk_bf16_f32 v68, v40, v41
	v_cvt_pk_bf16_f32 v69, v42, v43
	v_cvt_pk_bf16_f32 v70, v44, v45
	v_cvt_pk_bf16_f32 v71, v46, v47
	v_pk_add_f32 v[232:233], v[232:233], v[32:33]
	v_pk_add_f32 v[232:233], v[232:233], v[34:35]
	v_pk_add_f32 v[232:233], v[232:233], v[36:37]
	v_pk_add_f32 v[232:233], v[232:233], v[38:39]
	v_pk_add_f32 v[232:233], v[232:233], v[40:41]
	v_pk_add_f32 v[232:233], v[232:233], v[42:43]
	v_pk_add_f32 v[232:233], v[232:233], v[44:45]
	v_pk_add_f32 v[232:233], v[232:233], v[46:47]
	s_waitcnt lgkmcnt(12)
	v_mfma_f32_32x32x16_bf16 v[0:15], v[64:67], v[72:75], v[0:15]
	v_mfma_f32_32x32x16_bf16 v[16:31], v[64:67], v[76:79], v[16:31]
	v_mfma_f32_32x32x16_bf16 v[0:15], v[68:71], v[220:223], v[0:15]
	v_mfma_f32_32x32x16_bf16 v[16:31], v[68:71], v[224:227], v[16:31]
	ds_read2_b32 v[32:33], v115 offset0:96 offset1:97
	ds_read2_b32 v[34:35], v115 offset0:98 offset1:99
	ds_read2_b32 v[36:37], v115 offset0:104 offset1:105
	ds_read2_b32 v[38:39], v115 offset0:106 offset1:107
	ds_read2_b32 v[40:41], v115 offset0:112 offset1:113
	ds_read2_b32 v[42:43], v115 offset0:114 offset1:115
	ds_read2_b32 v[44:45], v115 offset0:120 offset1:121
	ds_read2_b32 v[46:47], v115 offset0:122 offset1:123
	s_waitcnt lgkmcnt(0)
	v_mfma_f32_32x32x16_bf16 v[32:47], v[156:159], v[48:51], v[32:47]
	ds_read_b64_tr_b16 v[72:73], v231
	ds_read_b64_tr_b16 v[74:75], v231 offset:512
	ds_read_b64_tr_b16 v[76:77], v231 offset:2048
	ds_read_b64_tr_b16 v[78:79], v231 offset:2560
	ds_read_b64_tr_b16 v[220:221], v231 offset:1024
	ds_read_b64_tr_b16 v[222:223], v231 offset:1536
	ds_read_b64_tr_b16 v[224:225], v231 offset:3072
	ds_read_b64_tr_b16 v[226:227], v231 offset:3584
	s_waitcnt vmcnt(0)
	ds_write_b128 v247, v[188:191]
	ds_write_b128 v247, v[192:195] offset:1024
	ds_write_b128 v247, v[196:199] offset:2048
	ds_write_b128 v247, v[200:203] offset:3072
	ds_read_b128 v[188:191], v248
	ds_read_b128 v[192:195], v249
	ds_read_b128 v[196:199], v250
	ds_read_b128 v[200:203], v251
	ds_write_b128 v112, v[204:207]
	ds_write_b128 v112, v[208:211] offset:1024
	ds_write_b128 v112, v[212:215] offset:2048
	ds_write_b128 v112, v[216:219] offset:3072
	v_mfma_f32_32x32x16_bf16 v[32:47], v[160:163], v[52:55], v[32:47]
	v_mfma_f32_32x32x16_bf16 v[32:47], v[164:167], v[56:59], v[32:47]
	v_mfma_f32_32x32x16_bf16 v[32:47], v[168:171], v[60:63], v[32:47]
	s_nop 11
	v_exp_f32_e32 v32, v32
	v_exp_f32_e32 v33, v33
	v_exp_f32_e32 v34, v34
	v_exp_f32_e32 v35, v35
	v_exp_f32_e32 v36, v36
	v_exp_f32_e32 v37, v37
	v_exp_f32_e32 v38, v38
	v_exp_f32_e32 v39, v39
	v_exp_f32_e32 v40, v40
	v_exp_f32_e32 v41, v41
	v_exp_f32_e32 v42, v42
	v_exp_f32_e32 v43, v43
	v_exp_f32_e32 v44, v44
	v_exp_f32_e32 v45, v45
	v_exp_f32_e32 v46, v46
	v_exp_f32_e32 v47, v47
	s_add_i32 s90, s67, 512
	v_lshlrev_b32_e32 v84, 4, v107
	v_add_u32_e32 v84, s90, v84
	v_add_u32_e32 v85, 0, v84
	v_add_u32_e32 v86, 16, v84
	v_add_u32_e32 v87, 32, v84
	v_add_u32_e32 v88, 48, v84
	v_cmp_gt_u32_e64 s[30:31], s98, v85
	v_cmp_gt_u32_e64 s[36:37], s98, v86
	v_cmp_gt_u32_e64 s[78:79], s98, v87
	v_cmp_gt_u32_e64 s[50:51], s98, v88
	v_cndmask_b32_e64 v32, 0, v32, s[30:31]
	v_add_u32_e32 v85, 128, v84
	v_cmp_gt_u32_e64 s[30:31], s98, v85
	v_cndmask_b32_e64 v33, 0, v33, s[36:37]
	v_add_u32_e32 v86, 144, v84
	v_cmp_gt_u32_e64 s[36:37], s98, v86
	v_cndmask_b32_e64 v34, 0, v34, s[78:79]
	v_add_u32_e32 v87, 160, v84
	v_cmp_gt_u32_e64 s[78:79], s98, v87
	v_cndmask_b32_e64 v35, 0, v35, s[50:51]
	v_add_u32_e32 v88, 176, v84
	v_cmp_gt_u32_e64 s[50:51], s98, v88
	v_cndmask_b32_e64 v36, 0, v36, s[30:31]
	v_add_u32_e32 v85, 256, v84
	v_cmp_gt_u32_e64 s[30:31], s98, v85
	v_cndmask_b32_e64 v37, 0, v37, s[36:37]
	v_add_u32_e32 v86, 272, v84
	v_cmp_gt_u32_e64 s[36:37], s98, v86
	v_cndmask_b32_e64 v38, 0, v38, s[78:79]
	v_add_u32_e32 v87, 288, v84
	v_cmp_gt_u32_e64 s[78:79], s98, v87
	v_cndmask_b32_e64 v39, 0, v39, s[50:51]
	v_add_u32_e32 v88, 304, v84
	v_cmp_gt_u32_e64 s[50:51], s98, v88
	v_cndmask_b32_e64 v40, 0, v40, s[30:31]
	v_add_u32_e32 v85, 384, v84
	v_cmp_gt_u32_e64 s[30:31], s98, v85
	v_cndmask_b32_e64 v41, 0, v41, s[36:37]
	v_add_u32_e32 v86, 400, v84
	v_cmp_gt_u32_e64 s[36:37], s98, v86
	v_cndmask_b32_e64 v42, 0, v42, s[78:79]
	v_add_u32_e32 v87, 416, v84
	v_cmp_gt_u32_e64 s[78:79], s98, v87
	v_cndmask_b32_e64 v43, 0, v43, s[50:51]
	v_add_u32_e32 v88, 432, v84
	v_cmp_gt_u32_e64 s[50:51], s98, v88
	v_nop
	v_cndmask_b32_e64 v44, 0, v44, s[30:31]
	v_cndmask_b32_e64 v45, 0, v45, s[36:37]
	v_cndmask_b32_e64 v46, 0, v46, s[78:79]
	v_cndmask_b32_e64 v47, 0, v47, s[50:51]
	v_cvt_pk_bf16_f32 v64, v32, v33
	v_cvt_pk_bf16_f32 v65, v34, v35
	v_cvt_pk_bf16_f32 v66, v36, v37
	v_cvt_pk_bf16_f32 v67, v38, v39
	v_cvt_pk_bf16_f32 v68, v40, v41
	v_cvt_pk_bf16_f32 v69, v42, v43
	v_cvt_pk_bf16_f32 v70, v44, v45
	v_cvt_pk_bf16_f32 v71, v46, v47
	v_pk_add_f32 v[232:233], v[232:233], v[32:33]
	v_pk_add_f32 v[232:233], v[232:233], v[34:35]
	v_pk_add_f32 v[232:233], v[232:233], v[36:37]
	v_pk_add_f32 v[232:233], v[232:233], v[38:39]
	v_pk_add_f32 v[232:233], v[232:233], v[40:41]
	v_pk_add_f32 v[232:233], v[232:233], v[42:43]
	v_pk_add_f32 v[232:233], v[232:233], v[44:45]
	v_pk_add_f32 v[232:233], v[232:233], v[46:47]
	s_waitcnt lgkmcnt(12)
	v_mfma_f32_32x32x16_bf16 v[0:15], v[64:67], v[72:75], v[0:15]
	v_mfma_f32_32x32x16_bf16 v[16:31], v[64:67], v[76:79], v[16:31]
	v_mfma_f32_32x32x16_bf16 v[0:15], v[68:71], v[220:223], v[0:15]
	v_mfma_f32_32x32x16_bf16 v[16:31], v[68:71], v[224:227], v[16:31]
	ds_read2_b32 v[32:33], v115 offset0:128 offset1:129
	ds_read2_b32 v[34:35], v115 offset0:130 offset1:131
	ds_read2_b32 v[36:37], v115 offset0:136 offset1:137
	ds_read2_b32 v[38:39], v115 offset0:138 offset1:139
	ds_read2_b32 v[40:41], v115 offset0:144 offset1:145
	ds_read2_b32 v[42:43], v115 offset0:146 offset1:147
	ds_read2_b32 v[44:45], v115 offset0:152 offset1:153
	ds_read2_b32 v[46:47], v115 offset0:154 offset1:155
	s_waitcnt lgkmcnt(0)
; #define LAS __attribute__((address_space(3)))
; __device__ __forceinline__ int crow(int r, int hi) { return (r & 3) + 8 * (r >> 2) + 4 * hi; }
; __device__ __forceinline__ void dil_unit(LAS unsigned char* lds, bf16_t* proj, int seq, int hd, int T0, int rho) {
;     ...
;     if (bound) DIL_LOOP(true); else DIL_LOOP(false);
;     ...
;     LAS bf16_t* stg = (LAS bf16_t*)wbuf;
;     l += __shfl_xor(l, 32);
; #pragma unroll
;     for (int rr = 0; rr < 16; ++rr) {
;         const int j = crow(rr, hi);
;         const float il = __builtin_amdgcn_rcpf(__shfl(l, j));
	v_mfma_f32_32x32x16_bf16 v[32:47], v[188:191], v[48:51], v[32:47]
	ds_read_b64_tr_b16 v[72:73], v231
	ds_read_b64_tr_b16 v[74:75], v231 offset:512
	ds_read_b64_tr_b16 v[76:77], v231 offset:2048
	ds_read_b64_tr_b16 v[78:79], v231 offset:2560
	ds_read_b64_tr_b16 v[220:221], v231 offset:1024
	ds_read_b64_tr_b16 v[222:223], v231 offset:1536
	ds_read_b64_tr_b16 v[224:225], v231 offset:3072
	ds_read_b64_tr_b16 v[226:227], v231 offset:3584
	v_mfma_f32_32x32x16_bf16 v[32:47], v[192:195], v[52:55], v[32:47]
	v_mfma_f32_32x32x16_bf16 v[32:47], v[196:199], v[56:59], v[32:47]
	v_mfma_f32_32x32x16_bf16 v[32:47], v[200:203], v[60:63], v[32:47]
	s_nop 11
	v_exp_f32_e32 v32, v32
	v_exp_f32_e32 v33, v33
	v_exp_f32_e32 v34, v34
	v_exp_f32_e32 v35, v35
	v_exp_f32_e32 v36, v36
	v_exp_f32_e32 v37, v37
	v_exp_f32_e32 v38, v38
	v_exp_f32_e32 v39, v39
	v_exp_f32_e32 v40, v40
	v_exp_f32_e32 v41, v41
	v_exp_f32_e32 v42, v42
	v_exp_f32_e32 v43, v43
	v_exp_f32_e32 v44, v44
	v_exp_f32_e32 v45, v45
	v_exp_f32_e32 v46, v46
	v_exp_f32_e32 v47, v47
	s_add_i32 s90, s67, 1024
	v_lshlrev_b32_e32 v84, 4, v107
	v_add_u32_e32 v84, s90, v84
	v_add_u32_e32 v85, 0, v84
	v_add_u32_e32 v86, 16, v84
	v_add_u32_e32 v87, 32, v84
	v_add_u32_e32 v88, 48, v84
	v_cmp_gt_u32_e64 s[30:31], s98, v85
	v_cmp_gt_u32_e64 s[36:37], s98, v86
	v_cmp_gt_u32_e64 s[78:79], s98, v87
	v_cmp_gt_u32_e64 s[50:51], s98, v88
	v_cndmask_b32_e64 v32, 0, v32, s[30:31]
	v_add_u32_e32 v85, 128, v84
	v_cmp_gt_u32_e64 s[30:31], s98, v85
	v_cndmask_b32_e64 v33, 0, v33, s[36:37]
	v_add_u32_e32 v86, 144, v84
	v_cmp_gt_u32_e64 s[36:37], s98, v86
	v_cndmask_b32_e64 v34, 0, v34, s[78:79]
	v_add_u32_e32 v87, 160, v84
	v_cmp_gt_u32_e64 s[78:79], s98, v87
	v_cndmask_b32_e64 v35, 0, v35, s[50:51]
	v_add_u32_e32 v88, 176, v84
	v_cmp_gt_u32_e64 s[50:51], s98, v88
	v_cndmask_b32_e64 v36, 0, v36, s[30:31]
	v_add_u32_e32 v85, 256, v84
	v_cmp_gt_u32_e64 s[30:31], s98, v85
	v_cndmask_b32_e64 v37, 0, v37, s[36:37]
	v_add_u32_e32 v86, 272, v84
	v_cmp_gt_u32_e64 s[36:37], s98, v86
	v_cndmask_b32_e64 v38, 0, v38, s[78:79]
	v_add_u32_e32 v87, 288, v84
	v_cmp_gt_u32_e64 s[78:79], s98, v87
	v_cndmask_b32_e64 v39, 0, v39, s[50:51]
	v_add_u32_e32 v88, 304, v84
	v_cmp_gt_u32_e64 s[50:51], s98, v88
	v_cndmask_b32_e64 v40, 0, v40, s[30:31]
	v_add_u32_e32 v85, 384, v84
	v_cmp_gt_u32_e64 s[30:31], s98, v85
	v_cndmask_b32_e64 v41, 0, v41, s[36:37]
	v_add_u32_e32 v86, 400, v84
	v_cmp_gt_u32_e64 s[36:37], s98, v86
	v_cndmask_b32_e64 v42, 0, v42, s[78:79]
	v_add_u32_e32 v87, 416, v84
	v_cmp_gt_u32_e64 s[78:79], s98, v87
	v_cndmask_b32_e64 v43, 0, v43, s[50:51]
	v_add_u32_e32 v88, 432, v84
	v_cmp_gt_u32_e64 s[50:51], s98, v88
	v_nop
	v_cndmask_b32_e64 v44, 0, v44, s[30:31]
	v_cndmask_b32_e64 v45, 0, v45, s[36:37]
	v_cndmask_b32_e64 v46, 0, v46, s[78:79]
	v_cndmask_b32_e64 v47, 0, v47, s[50:51]
	v_cvt_pk_bf16_f32 v64, v32, v33
	v_cvt_pk_bf16_f32 v65, v34, v35
	v_cvt_pk_bf16_f32 v66, v36, v37
	v_cvt_pk_bf16_f32 v67, v38, v39
	v_cvt_pk_bf16_f32 v68, v40, v41
	v_cvt_pk_bf16_f32 v69, v42, v43
	v_cvt_pk_bf16_f32 v70, v44, v45
	v_cvt_pk_bf16_f32 v71, v46, v47
	v_pk_add_f32 v[232:233], v[232:233], v[32:33]
	v_pk_add_f32 v[232:233], v[232:233], v[34:35]
	v_pk_add_f32 v[232:233], v[232:233], v[36:37]
	v_pk_add_f32 v[232:233], v[232:233], v[38:39]
	v_pk_add_f32 v[232:233], v[232:233], v[40:41]
	v_pk_add_f32 v[232:233], v[232:233], v[42:43]
	v_pk_add_f32 v[232:233], v[232:233], v[44:45]
	v_pk_add_f32 v[232:233], v[232:233], v[46:47]
	s_waitcnt lgkmcnt(0)
	v_mfma_f32_32x32x16_bf16 v[0:15], v[64:67], v[72:75], v[0:15]
	v_mfma_f32_32x32x16_bf16 v[16:31], v[64:67], v[76:79], v[16:31]
	v_mfma_f32_32x32x16_bf16 v[0:15], v[68:71], v[220:223], v[0:15]
	v_mfma_f32_32x32x16_bf16 v[16:31], v[68:71], v[224:227], v[16:31]
	v_add_f32_e32 v113, v232, v233
	v_or_b32_e32 v114, 1, v107
	v_or_b32_e32 v97, 2, v107
	v_or_b32_e32 v96, 3, v107
	v_or_b32_e32 v95, 8, v107
	v_or_b32_e32 v94, 9, v107
	v_or_b32_e32 v93, 10, v107
	v_or_b32_e32 v92, 11, v107
	v_or_b32_e32 v91, 16, v107
	v_or_b32_e32 v90, 17, v107
	v_or_b32_e32 v89, 18, v107
	v_or_b32_e32 v88, 19, v107
	v_or_b32_e32 v87, 24, v107
	v_or_b32_e32 v86, 25, v107
	v_or_b32_e32 v85, 26, v107
	v_or_b32_e32 v84, 27, v107
	s_nop 11
	s_branch .LBB0_1265
